# v26 + nt hint on the wide / 16-bit loads of the gMLP + GLA-update phase (activation tiles read once)
# baseline (speedup 1.0000x reference)
; __device__ __forceinline__ float ss_val(u64 v) { return (float)v * (1.0f / 1099511627776.0f); }
; __device__ __forceinline__ unsigned pk2(float lo, float hi) { return f2bf(lo) | (f2bf(hi) << 16); }
; __device__ __forceinline__ void gmlp_unit(LAS unsigned char* wl, const bf16* PROJ, const u64* rowss_v, const bf16* wsb, const float* norm_v, const float* b_s, bf16* Y, int nb, int g, int lane) {
;     ...
;     const int tok0 = nb * 128, sp = lane >> 3, cc = lane & 7;
; #pragma unroll 4
;     for (int it = 0; it < 8; ++it) {
;         const int s0 = it * 16 + 2 * sp;
;         const float r0 = __builtin_amdgcn_rsqf(ss_val(rowss_v[tok0 + s0]) * (1.f / 512.f) + EPS), r1 = __builtin_amdgcn_rsqf(ss_val(rowss_v[tok0 + s0 + 1]) * (1.f / 512.f) + EPS);
;         const u32x4 va = *(const u32x4*)(PROJ + (size_t)(tok0 + s0) * NPROJ + 512 + g * 64 + 8 * cc);
;         const u32x4 vb = *(const u32x4*)(PROJ + (size_t)(tok0 + s0 + 1) * NPROJ + 512 + g * 64 + 8 * cc);
; #pragma unroll
;         for (int i = 0; i < 4; ++i) {
;             VT32[(8 * cc + 2 * i) * (VS / 2) + (s0 >> 1)] = pk2(bf_lo(va[i]) * r0, bf_lo(vb[i]) * r1);
;             VT32[(8 * cc + 2 * i + 1) * (VS / 2) + (s0 >> 1)] = pk2(bf_hi(va[i]) * r0, bf_hi(vb[i]) * r1);
;         }
.LBB0_418:
	v_add_u32_e32 v0, s21, v2
	v_ashrrev_i32_e32 v1, 31, v0
	v_add_u32_e32 v8, 1, v0
	v_add_u32_e32 v40, 16, v0
	v_add_u32_e32 v9, 17, v0
	v_add_u32_e32 v42, 32, v0
	v_add_u32_e32 v10, 33, v0
	v_add_u32_e32 v44, 48, v0
	v_add_u32_e32 v11, 49, v0
	v_mad_i64_i32 v[12:13], s[28:29], v0, s4, v[126:127]
	v_lshl_add_u64 v[0:1], v[0:1], 3, s[0:1]
	v_mad_i64_i32 v[16:17], s[28:29], v8, s4, v[126:127]
	v_ashrrev_i32_e32 v41, 31, v40
	v_mad_i64_i32 v[20:21], s[28:29], v40, s4, v[126:127]
	v_mad_i64_i32 v[24:25], s[28:29], v9, s4, v[126:127]
	v_ashrrev_i32_e32 v43, 31, v42
	v_mad_i64_i32 v[28:29], s[28:29], v10, s4, v[126:127]
	v_ashrrev_i32_e32 v45, 31, v44
	v_mad_i64_i32 v[32:33], s[28:29], v44, s4, v[126:127]
	v_mad_i64_i32 v[36:37], s[28:29], v11, s4, v[126:127]
	v_mad_i64_i32 v[48:49], s[28:29], v42, s4, v[126:127]
	global_load_dwordx4 v[8:11], v[0:1], off nt
	s_nop 0
	global_load_dwordx4 v[12:15], v[12:13], off offset:1024 nt
	s_nop 0
	global_load_dwordx4 v[16:19], v[16:17], off offset:1024 nt
	s_nop 0
	global_load_dwordx4 v[20:23], v[20:21], off offset:1024 nt
	s_nop 0
	global_load_dwordx4 v[24:27], v[24:25], off offset:1024 nt
	s_nop 0
	global_load_dwordx4 v[28:31], v[28:29], off offset:1024 nt
	s_nop 0
	global_load_dwordx4 v[32:35], v[32:33], off offset:1024 nt
	s_nop 0
	global_load_dwordx4 v[36:39], v[36:37], off offset:1024 nt
	v_lshl_add_u64 v[0:1], v[40:41], 3, s[0:1]
	v_lshl_add_u64 v[46:47], v[42:43], 3, s[0:1]
	v_lshl_add_u64 v[52:53], v[44:45], 3, s[0:1]
	global_load_dwordx4 v[40:43], v[0:1], off nt
	s_nop 0
	global_load_dwordx4 v[44:47], v[46:47], off nt
	s_nop 0
	global_load_dwordx4 v[48:51], v[48:49], off offset:1024 nt
	s_nop 0
	global_load_dwordx4 v[52:55], v[52:53], off nt
	v_add_u32_e32 v4, v3, v142
	s_add_i32 s21, s21, 64
	v_add_u32_e32 v5, v3, v141
	v_add_u32_e32 v6, v3, v140
	v_add_u32_e32 v7, v3, v139
	v_add_u32_e32 v3, 0x80, v3
	v_add_u32_e32 v56, 0x400, v4
	s_cmpk_lg_i32 s21, 0x80
	v_add_u32_e32 v57, 0x400, v5
	v_add_u32_e32 v58, 0x400, v6
	v_add_u32_e32 v59, 0x400, v7
	s_waitcnt vmcnt(11)
	v_ffbh_u32_e32 v0, v9
	v_ffbh_u32_e32 v1, v11
	s_waitcnt vmcnt(10)
	v_lshlrev_b32_e32 v60, 16, v12
	v_and_b32_e32 v62, 0xffff0000, v12
	v_lshlrev_b32_e32 v145, 16, v13
	v_and_b32_e32 v147, 0xffff0000, v13
	v_lshlrev_b32_e32 v149, 16, v14
	v_and_b32_e32 v151, 0xffff0000, v14
	v_min_u32_e32 v12, 32, v0
	v_min_u32_e32 v13, 32, v1
	s_waitcnt vmcnt(3)
	v_ffbh_u32_e32 v14, v41
	v_lshlrev_b32_e32 v61, 16, v16
	v_and_b32_e32 v63, 0xffff0000, v16
	v_lshlrev_b32_e32 v146, 16, v17
	v_and_b32_e32 v148, 0xffff0000, v17
	v_lshlrev_b32_e32 v150, 16, v18
	v_and_b32_e32 v152, 0xffff0000, v18
	v_lshlrev_b32_e32 v153, 16, v15
	v_and_b32_e32 v155, 0xffff0000, v15
	v_ffbh_u32_e32 v15, v43
	s_waitcnt vmcnt(2)
	v_ffbh_u32_e32 v16, v45
	v_ffbh_u32_e32 v17, v47
	s_waitcnt vmcnt(0)
	v_ffbh_u32_e32 v18, v53
	v_lshlrev_b64 v[0:1], v12, v[8:9]
	v_sub_u32_e32 v183, 32, v12
	v_lshlrev_b64 v[8:9], v13, v[10:11]
	v_min_u32_e32 v12, 32, v14
	v_lshlrev_b32_e32 v154, 16, v19
	v_and_b32_e32 v156, 0xffff0000, v19
	v_lshlrev_b32_e32 v157, 16, v20
	v_and_b32_e32 v159, 0xffff0000, v20
	v_lshlrev_b32_e32 v160, 16, v21
	v_and_b32_e32 v162, 0xffff0000, v21
	v_min_u32_e32 v14, 32, v15
	v_min_u32_e32 v16, 32, v16
	v_min_u32_e32 v20, 32, v17
	v_min_u32_e32 v21, 32, v18
	v_min_u32_e32 v0, 1, v0
	v_min_u32_e32 v8, 1, v8
	v_lshlrev_b64 v[10:11], v12, v[40:41]
	v_sub_u32_e32 v184, 32, v13
	v_sub_u32_e32 v40, 32, v12
	v_lshlrev_b64 v[12:13], v14, v[42:43]
	v_sub_u32_e32 v41, 32, v14
	v_lshlrev_b64 v[14:15], v16, v[44:45]
	v_sub_u32_e32 v42, 32, v16
	v_lshlrev_b64 v[16:17], v20, v[46:47]
	v_lshlrev_b64 v[18:19], v21, v[52:53]
	v_or_b32_e32 v0, v1, v0
	v_or_b32_e32 v1, v9, v8
	v_min_u32_e32 v8, 1, v10
	v_sub_u32_e32 v43, 32, v20
	v_sub_u32_e32 v44, 32, v21
	v_min_u32_e32 v9, 1, v12
	v_min_u32_e32 v10, 1, v14
	v_min_u32_e32 v12, 1, v16
	v_min_u32_e32 v14, 1, v18
	v_cvt_f32_u32_e32 v0, v0
	v_or_b32_e32 v8, v11, v8
	v_cvt_f32_u32_e32 v1, v1
	v_or_b32_e32 v9, v13, v9
	v_or_b32_e32 v10, v15, v10
	v_or_b32_e32 v11, v17, v12
	v_or_b32_e32 v12, v19, v14
	v_cvt_f32_u32_e32 v8, v8
	v_cvt_f32_u32_e32 v9, v9
	v_cvt_f32_u32_e32 v10, v10
	v_cvt_f32_u32_e32 v11, v11
	v_cvt_f32_u32_e32 v12, v12
	v_ldexp_f32 v0, v0, v183
	v_ldexp_f32 v1, v1, v184
	v_mul_f32_e32 v0, 0x2b800000, v0
	v_ldexp_f32 v8, v8, v40
	v_mul_f32_e32 v1, 0x2b800000, v1
	v_ldexp_f32 v9, v9, v41
	v_ldexp_f32 v10, v10, v42
	v_ldexp_f32 v11, v11, v43
	v_ldexp_f32 v12, v12, v44
	v_fmamk_f32 v0, v0, 0x3b000000, v143
	v_mul_f32_e32 v8, 0x2b800000, v8
	v_fmamk_f32 v1, v1, 0x3b000000, v143
	v_mul_f32_e32 v9, 0x2b800000, v9
	v_mul_f32_e32 v10, 0x2b800000, v10
	v_mul_f32_e32 v11, 0x2b800000, v11
	v_mul_f32_e32 v12, 0x2b800000, v12
	v_rsq_f32_e32 v0, v0
	v_fmamk_f32 v8, v8, 0x3b000000, v143
	v_rsq_f32_e32 v1, v1
	v_fmamk_f32 v9, v9, 0x3b000000, v143
	v_fmamk_f32 v10, v10, 0x3b000000, v143
	v_fmamk_f32 v11, v11, 0x3b000000, v143
	v_fmamk_f32 v12, v12, 0x3b000000, v143
	v_rsq_f32_e32 v8, v8
	v_cvt_f32_u32_e32 v54, v54
	v_cvt_f32_u32_e32 v55, v55
	v_fmamk_f32 v54, v55, 0x4f800000, v54
	v_fmamk_f32 v13, v54, 0x27000000, v143
	v_rsq_f32_e32 v9, v9
	v_rsq_f32_e32 v10, v10
	v_rsq_f32_e32 v11, v11
	v_rsq_f32_e32 v12, v12
	v_rsq_f32_e32 v13, v13
	v_mul_f32_e32 v14, v0, v60
	v_mul_f32_e32 v16, v0, v62
	v_mul_f32_e32 v18, v0, v145
	v_mul_f32_e32 v20, v0, v147
	v_mul_f32_e32 v40, v0, v149
	v_mul_f32_e32 v42, v0, v151
	v_mul_f32_e32 v44, v0, v153
	v_mul_f32_e32 v0, v0, v155
	v_lshlrev_b32_e32 v158, 16, v24
	v_and_b32_e32 v24, 0xffff0000, v24
	v_lshlrev_b32_e32 v161, 16, v25
	v_and_b32_e32 v25, 0xffff0000, v25
	v_lshlrev_b32_e32 v163, 16, v22
; __device__ __forceinline__ float ss_val(u64 v) { return (float)v * (1.0f / 1099511627776.0f); }
; __device__ __forceinline__ unsigned pk2(float lo, float hi) { return f2bf(lo) | (f2bf(hi) << 16); }
; __device__ __forceinline__ void gmlp_unit(LAS unsigned char* wl, const bf16* PROJ, const u64* rowss_v, const bf16* wsb, const float* norm_v, const float* b_s, bf16* Y, int nb, int g, int lane) {
;     ...
;         const float r0 = __builtin_amdgcn_rsqf(ss_val(rowss_v[tok0 + s0]) * (1.f / 512.f) + EPS), r1 = __builtin_amdgcn_rsqf(ss_val(rowss_v[tok0 + s0 + 1]) * (1.f / 512.f) + EPS);
;         const u32x4 va = *(const u32x4*)(PROJ + (size_t)(tok0 + s0) * NPROJ + 512 + g * 64 + 8 * cc);
;         const u32x4 vb = *(const u32x4*)(PROJ + (size_t)(tok0 + s0 + 1) * NPROJ + 512 + g * 64 + 8 * cc);
; #pragma unroll
;         for (int i = 0; i < 4; ++i) {
;             VT32[(8 * cc + 2 * i) * (VS / 2) + (s0 >> 1)] = pk2(bf_lo(va[i]) * r0, bf_lo(vb[i]) * r1);
;             VT32[(8 * cc + 2 * i + 1) * (VS / 2) + (s0 >> 1)] = pk2(bf_hi(va[i]) * r0, bf_hi(vb[i]) * r1);
;         }
	v_lshlrev_b32_e32 v164, 16, v26
	v_and_b32_e32 v22, 0xffff0000, v22
	v_and_b32_e32 v26, 0xffff0000, v26
	v_lshlrev_b32_e32 v165, 16, v23
	v_lshlrev_b32_e32 v166, 16, v27
	v_and_b32_e32 v23, 0xffff0000, v23
	v_and_b32_e32 v27, 0xffff0000, v27
	v_lshlrev_b32_e32 v167, 16, v28
	v_and_b32_e32 v28, 0xffff0000, v28
	v_lshlrev_b32_e32 v168, 16, v29
	v_and_b32_e32 v29, 0xffff0000, v29
	v_lshlrev_b32_e32 v169, 16, v30
	v_and_b32_e32 v30, 0xffff0000, v30
	v_lshlrev_b32_e32 v170, 16, v31
	v_and_b32_e32 v31, 0xffff0000, v31
	v_lshlrev_b32_e32 v171, 16, v32
	v_and_b32_e32 v32, 0xffff0000, v32
	v_lshlrev_b32_e32 v173, 16, v33
	v_and_b32_e32 v33, 0xffff0000, v33
	v_lshlrev_b32_e32 v175, 16, v34
	v_and_b32_e32 v34, 0xffff0000, v34
	v_lshlrev_b32_e32 v177, 16, v35
	v_and_b32_e32 v35, 0xffff0000, v35
	v_lshlrev_b32_e32 v179, 16, v48
	v_and_b32_e32 v48, 0xffff0000, v48
	v_lshlrev_b32_e32 v180, 16, v49
	v_and_b32_e32 v49, 0xffff0000, v49
	v_lshlrev_b32_e32 v181, 16, v50
	v_and_b32_e32 v50, 0xffff0000, v50
	v_lshlrev_b32_e32 v182, 16, v51
	v_and_b32_e32 v51, 0xffff0000, v51
	v_mul_f32_e32 v15, v1, v61
	v_mul_f32_e32 v17, v1, v63
	v_mul_f32_e32 v19, v1, v146
	v_mul_f32_e32 v21, v1, v148
	v_mul_f32_e32 v41, v1, v150
	v_mul_f32_e32 v43, v1, v152
	v_mul_f32_e32 v45, v1, v154
	v_mul_f32_e32 v1, v1, v156
	v_bfe_u32 v46, v14, 16, 1
	v_bfe_u32 v52, v16, 16, 1
	v_bfe_u32 v60, v20, 16, 1
	v_bfe_u32 v62, v40, 16, 1
	v_bfe_u32 v145, v42, 16, 1
	v_bfe_u32 v147, v44, 16, 1
	v_bfe_u32 v149, v0, 16, 1
	v_mul_f32_e32 v151, v8, v157
	v_mul_f32_e32 v153, v8, v159
	v_lshlrev_b32_e32 v172, 16, v36
	v_and_b32_e32 v36, 0xffff0000, v36
	v_lshlrev_b32_e32 v174, 16, v37
	v_and_b32_e32 v37, 0xffff0000, v37
	v_lshlrev_b32_e32 v176, 16, v38
	v_and_b32_e32 v38, 0xffff0000, v38
	v_lshlrev_b32_e32 v178, 16, v39
	v_and_b32_e32 v39, 0xffff0000, v39
	v_bfe_u32 v47, v15, 16, 1
	v_bfe_u32 v53, v17, 16, 1
	v_bfe_u32 v54, v18, 16, 1
	v_bfe_u32 v61, v21, 16, 1
	v_bfe_u32 v63, v41, 16, 1
	v_bfe_u32 v146, v43, 16, 1
	v_bfe_u32 v148, v45, 16, 1
	v_bfe_u32 v150, v1, 16, 1
	v_mul_f32_e32 v152, v9, v158
	v_mul_f32_e32 v24, v9, v24
	v_mul_f32_e32 v154, v8, v160
	v_mul_f32_e32 v155, v9, v161
	v_mul_f32_e32 v156, v8, v162
	v_mul_f32_e32 v25, v9, v25
	v_mul_f32_e32 v157, v8, v163
	v_mul_f32_e32 v158, v9, v164
	v_mul_f32_e32 v22, v8, v22
	v_mul_f32_e32 v26, v9, v26
	v_mul_f32_e32 v159, v8, v165
	v_mul_f32_e32 v160, v9, v166
	v_mul_f32_e32 v8, v8, v23
	v_mul_f32_e32 v9, v9, v27
	v_mul_f32_e32 v23, v10, v179
	v_mul_f32_e32 v27, v11, v167
	v_mul_f32_e32 v48, v10, v48
	v_mul_f32_e32 v28, v11, v28
	v_mul_f32_e32 v161, v10, v180
	v_mul_f32_e32 v162, v11, v168
	v_mul_f32_e32 v49, v10, v49
	v_mul_f32_e32 v29, v11, v29
	v_mul_f32_e32 v163, v10, v181
	v_mul_f32_e32 v164, v11, v169
	v_mul_f32_e32 v50, v10, v50
	v_mul_f32_e32 v30, v11, v30
	v_mul_f32_e32 v165, v10, v182
	v_mul_f32_e32 v166, v11, v170
	v_mul_f32_e32 v10, v10, v51
	v_mul_f32_e32 v11, v11, v31
	v_mul_f32_e32 v31, v12, v171
	v_mul_f32_e32 v32, v12, v32
	v_mul_f32_e32 v167, v12, v173
	v_mul_f32_e32 v33, v12, v33
	v_mul_f32_e32 v169, v12, v175
	v_mul_f32_e32 v34, v12, v34
	v_mul_f32_e32 v171, v12, v177
	v_mul_f32_e32 v12, v12, v35
	v_add3_u32 v14, v14, v46, s5
	v_add3_u32 v16, v16, v52, s5
	v_add3_u32 v20, v20, v60, s5
	v_add3_u32 v35, v40, v62, s5
	v_add3_u32 v40, v42, v145, s5
	v_add3_u32 v42, v44, v147, s5
	v_add3_u32 v0, v0, v149, s5
	v_bfe_u32 v44, v151, 16, 1
	v_bfe_u32 v46, v153, 16, 1
	v_bfe_u32 v55, v19, 16, 1
	v_mul_f32_e32 v51, v13, v172
	v_mul_f32_e32 v36, v13, v36
	v_mul_f32_e32 v168, v13, v174
	v_mul_f32_e32 v37, v13, v37
	v_mul_f32_e32 v170, v13, v176
	v_mul_f32_e32 v38, v13, v38
	v_mul_f32_e32 v172, v13, v178
	v_mul_f32_e32 v13, v13, v39
	v_add3_u32 v15, v15, v47, s5
	v_add3_u32 v17, v17, v53, s5
	v_add3_u32 v18, v18, v54, s5
	v_add3_u32 v21, v21, v61, s5
	v_add3_u32 v39, v41, v63, s5
	v_add3_u32 v41, v43, v146, s5
	v_add3_u32 v43, v45, v148, s5
	v_add3_u32 v1, v1, v150, s5
	v_bfe_u32 v45, v152, 16, 1
	v_bfe_u32 v47, v24, 16, 1
	v_bfe_u32 v52, v154, 16, 1
	v_bfe_u32 v53, v155, 16, 1
	v_bfe_u32 v54, v156, 16, 1
	v_bfe_u32 v60, v157, 16, 1
	v_bfe_u32 v62, v22, 16, 1
	v_bfe_u32 v145, v159, 16, 1
	v_bfe_u32 v147, v8, 16, 1
	v_bfe_u32 v149, v23, 16, 1
	v_bfe_u32 v173, v48, 16, 1
	v_bfe_u32 v175, v161, 16, 1
	v_bfe_u32 v177, v49, 16, 1
	v_bfe_u32 v179, v163, 16, 1
	v_bfe_u32 v181, v50, 16, 1
	v_bfe_u32 v183, v165, 16, 1
	v_bfe_u32 v185, v10, 16, 1
	v_bfe_u32 v187, v31, 16, 1
	v_bfe_u32 v189, v32, 16, 1
	v_bfe_u32 v191, v167, 16, 1
	v_bfe_u32 v193, v33, 16, 1
	v_bfe_u32 v195, v169, 16, 1
	v_bfe_u32 v197, v34, 16, 1
	v_bfe_u32 v199, v171, 16, 1
	v_bfe_u32 v203, v12, 16, 1
	v_lshrrev_b32_e32 v14, 16, v14
	v_lshrrev_b32_e32 v16, 16, v16
	v_lshrrev_b32_e32 v20, 16, v20
	v_lshrrev_b32_e32 v0, 16, v0
	v_add3_u32 v44, v151, v44, s5
	v_add3_u32 v46, v153, v46, s5
	v_add3_u32 v19, v19, v55, s5
	v_bfe_u32 v55, v25, 16, 1
	v_bfe_u32 v61, v158, 16, 1
	v_bfe_u32 v63, v26, 16, 1
	v_bfe_u32 v146, v160, 16, 1
	v_bfe_u32 v148, v9, 16, 1
	v_bfe_u32 v150, v27, 16, 1
	v_bfe_u32 v174, v28, 16, 1
	v_bfe_u32 v176, v162, 16, 1
	v_bfe_u32 v178, v29, 16, 1
	v_bfe_u32 v180, v164, 16, 1
	v_bfe_u32 v182, v30, 16, 1
	v_bfe_u32 v184, v166, 16, 1
	v_bfe_u32 v186, v11, 16, 1
	v_bfe_u32 v188, v51, 16, 1
	v_bfe_u32 v190, v36, 16, 1
	v_bfe_u32 v192, v168, 16, 1
	v_bfe_u32 v194, v37, 16, 1
	v_bfe_u32 v196, v170, 16, 1
	v_bfe_u32 v198, v38, 16, 1
	v_bfe_u32 v202, v172, 16, 1
	v_bfe_u32 v204, v13, 16, 1
	v_lshrrev_b32_e32 v18, 16, v18
	v_lshrrev_b32_e32 v35, 16, v35
	v_lshrrev_b32_e32 v40, 16, v40
	v_lshrrev_b32_e32 v42, 16, v42
	v_add3_u32 v45, v152, v45, s5
	v_add3_u32 v24, v24, v47, s5
; #define LAS __attribute__((address_space(3)))
; #define LDS_WAIT() asm volatile("s_waitcnt lgkmcnt(0)" ::: "memory")
; __device__ __forceinline__ unsigned pk2(float lo, float hi) { return f2bf(lo) | (f2bf(hi) << 16); }
; template <int HF>
; __device__ __forceinline__ void gmlp_half(LAS unsigned char* wl, const bf16* PROJ, const bf16* wsg, const float* norm_v, const float* b_s, bf16* Y, int tok0, int g, int fr, int fq) {
;     ...
; #pragma unroll
;     for (int ki = 0; ki < NK; ++ki)
; #pragma unroll
;         for (int nt = 0; nt < 4; ++nt) bw[ki][nt] = *(const bf16x8*)(wsg + (size_t)(64 * HF + 16 * nt + fr) * 128 + 32 * ki + 8 * fq);
;     f32x4 acc[4][4];
; #pragma unroll
;     for (int i = 0; i < 4; ++i)
; #pragma unroll
;         for (int j = 0; j < 4; ++j) acc[i][j] = (f32x4){0.f, 0.f, 0.f, 0.f};
; #pragma unroll
;     for (int ki = 0; ki < NK; ++ki) {
;         bf16x8 av[4];
; #pragma unroll
;         for (int mi = 0; mi < 4; ++mi) av[mi] = *(const LAS bf16x8*)(wl + ((32 * (mi >> 1) + 8 * (fr >> 2) + 4 * (mi & 1) + (fr & 3)) * VS + 32 * ki + 8 * fq) * 2);
; #pragma unroll
;         for (int nt = 0; nt < 4; ++nt)
; #pragma unroll
;             for (int mi = 0; mi < 4; ++mi) acc[mi][nt] = __builtin_amdgcn_mfma_f32_16x16x32_bf16(av[mi], bw[ki][nt], acc[mi][nt], 0, 0, 0);
; __device__ __forceinline__ void gmlp_unit(LAS unsigned char* wl, const bf16* PROJ, const u64* rowss_v, const bf16* wsb, const float* norm_v, const float* b_s, bf16* Y, int nb, int g, int lane) {
;     ...
;         for (int i = 0; i < 4; ++i) {
;             VT32[(8 * cc + 2 * i) * (VS / 2) + (s0 >> 1)] = pk2(bf_lo(va[i]) * r0, bf_lo(vb[i]) * r1);
;             VT32[(8 * cc + 2 * i + 1) * (VS / 2) + (s0 >> 1)] = pk2(bf_hi(va[i]) * r0, bf_hi(vb[i]) * r1);
;         }
;     }
;     LDS_WAIT(); asm volatile("" ::: "memory");
	v_add3_u32 v47, v154, v52, s5
	v_add3_u32 v52, v155, v53, s5
	v_add3_u32 v53, v156, v54, s5
	v_add3_u32 v54, v157, v60, s5
	v_add3_u32 v22, v22, v62, s5
	v_add3_u32 v60, v159, v145, s5
	v_add3_u32 v8, v8, v147, s5
	v_add3_u32 v23, v23, v149, s5
	v_add3_u32 v48, v48, v173, s5
	v_add3_u32 v62, v161, v175, s5
	v_add3_u32 v49, v49, v177, s5
	v_add3_u32 v145, v163, v179, s5
	v_add3_u32 v50, v50, v181, s5
	v_add3_u32 v147, v165, v183, s5
	v_add3_u32 v10, v10, v185, s5
	v_add3_u32 v31, v31, v187, s5
	v_add3_u32 v32, v32, v189, s5
	v_add3_u32 v149, v167, v191, s5
	v_add3_u32 v33, v33, v193, s5
	v_add3_u32 v151, v169, v195, s5
	v_add3_u32 v34, v34, v197, s5
	v_add3_u32 v153, v171, v199, s5
	v_add3_u32 v12, v12, v203, s5
	v_and_or_b32 v14, v15, s11, v14
	v_and_or_b32 v15, v17, s11, v16
	v_and_or_b32 v17, v21, s11, v20
	v_and_or_b32 v0, v1, s11, v0
	v_lshrrev_b32_e32 v1, 16, v44
	v_lshrrev_b32_e32 v21, 16, v46
	v_add3_u32 v25, v25, v55, s5
	v_add3_u32 v55, v158, v61, s5
	v_add3_u32 v26, v26, v63, s5
	v_add3_u32 v61, v160, v146, s5
	v_add3_u32 v9, v9, v148, s5
	v_add3_u32 v27, v27, v150, s5
	v_add3_u32 v28, v28, v174, s5
	v_add3_u32 v63, v162, v176, s5
	v_add3_u32 v29, v29, v178, s5
	v_add3_u32 v146, v164, v180, s5
	v_add3_u32 v30, v30, v182, s5
	v_add3_u32 v148, v166, v184, s5
	v_add3_u32 v11, v11, v186, s5
	v_add3_u32 v51, v51, v188, s5
	v_add3_u32 v36, v36, v190, s5
	v_add3_u32 v150, v168, v192, s5
	v_add3_u32 v37, v37, v194, s5
	v_add3_u32 v152, v170, v196, s5
	v_add3_u32 v38, v38, v198, s5
	v_add3_u32 v154, v172, v202, s5
	v_add3_u32 v13, v13, v204, s5
	v_and_or_b32 v16, v19, s11, v18
	v_and_or_b32 v18, v39, s11, v35
	v_and_or_b32 v19, v41, s11, v40
	v_and_or_b32 v20, v43, s11, v42
	v_lshrrev_b32_e32 v35, 16, v47
	v_lshrrev_b32_e32 v39, 16, v53
	v_lshrrev_b32_e32 v40, 16, v54
	v_lshrrev_b32_e32 v22, 16, v22
	v_lshrrev_b32_e32 v41, 16, v60
	v_lshrrev_b32_e32 v8, 16, v8
	v_lshrrev_b32_e32 v23, 16, v23
	v_lshrrev_b32_e32 v42, 16, v48
	v_lshrrev_b32_e32 v43, 16, v62
	v_lshrrev_b32_e32 v44, 16, v49
	v_lshrrev_b32_e32 v46, 16, v145
	v_lshrrev_b32_e32 v47, 16, v50
	v_lshrrev_b32_e32 v48, 16, v147
	v_lshrrev_b32_e32 v10, 16, v10
	v_lshrrev_b32_e32 v31, 16, v31
	v_lshrrev_b32_e32 v32, 16, v32
	v_lshrrev_b32_e32 v49, 16, v149
	v_lshrrev_b32_e32 v33, 16, v33
	v_lshrrev_b32_e32 v50, 16, v151
	v_lshrrev_b32_e32 v34, 16, v34
	v_lshrrev_b32_e32 v53, 16, v153
	v_lshrrev_b32_e32 v12, 16, v12
	ds_write2_b32 v4, v14, v15 offset1:68
	ds_write2_b32 v4, v16, v17 offset0:136 offset1:204
	ds_write2_b32 v56, v18, v19 offset0:16 offset1:84
	ds_write2_b32 v56, v20, v0 offset0:152 offset1:220
	v_and_or_b32 v0, v45, s11, v1
	v_and_or_b32 v1, v24, s11, v21
	v_and_or_b32 v4, v52, s11, v35
	v_and_or_b32 v14, v25, s11, v39
	v_and_or_b32 v15, v55, s11, v40
	v_and_or_b32 v16, v26, s11, v22
	v_and_or_b32 v17, v61, s11, v41
	v_and_or_b32 v8, v9, s11, v8
	v_and_or_b32 v9, v27, s11, v23
	v_and_or_b32 v18, v28, s11, v42
	v_and_or_b32 v19, v63, s11, v43
	v_and_or_b32 v20, v29, s11, v44
	v_and_or_b32 v21, v146, s11, v46
	v_and_or_b32 v22, v30, s11, v47
	v_and_or_b32 v23, v148, s11, v48
	v_and_or_b32 v10, v11, s11, v10
	v_and_or_b32 v11, v51, s11, v31
	v_and_or_b32 v24, v36, s11, v32
	v_and_or_b32 v25, v150, s11, v49
	v_and_or_b32 v26, v37, s11, v33
	v_and_or_b32 v27, v152, s11, v50
	v_and_or_b32 v28, v38, s11, v34
	v_and_or_b32 v29, v154, s11, v53
	v_and_or_b32 v12, v13, s11, v12
	ds_write2_b32 v5, v0, v1 offset1:68
	ds_write2_b32 v5, v4, v14 offset0:136 offset1:204
	ds_write2_b32 v57, v15, v16 offset0:16 offset1:84
	ds_write2_b32 v57, v17, v8 offset0:152 offset1:220
	ds_write2_b32 v6, v9, v18 offset1:68
	ds_write2_b32 v6, v19, v20 offset0:136 offset1:204
	ds_write2_b32 v58, v21, v22 offset0:16 offset1:84
	ds_write2_b32 v58, v23, v10 offset0:152 offset1:220
	ds_write2_b32 v7, v11, v24 offset1:68
	ds_write2_b32 v7, v25, v26 offset0:136 offset1:204
	ds_write2_b32 v59, v27, v28 offset0:16 offset1:84
	ds_write2_b32 v59, v29, v12 offset0:152 offset1:220
	s_cbranch_scc1 .LBB0_418
	s_waitcnt lgkmcnt(0)
	global_load_dwordx4 v[4:7], v[68:69], off nt
	ds_read_b128 v[20:23], v144
	ds_read_b128 v[28:31], v144 offset:1088
	global_load_dwordx4 v[146:149], v[68:69], off offset:64 nt
	ds_read_b128 v[48:51], v144 offset:64
	ds_read_b128 v[12:15], v144 offset:8704
	ds_read_b128 v[32:35], v144 offset:1152
	global_load_dwordx4 v[24:27], v[70:71], off nt
	ds_read_b128 v[8:11], v144 offset:8768
	ds_read_b128 v[16:19], v144 offset:9792
	ds_read_b128 v[0:3], v144 offset:9856
	s_lshl_b32 s21, s20, 4
	s_and_b32 s28, s21, 0xffffff80
	v_or_b32_e32 v198, s28, v129
	global_load_dwordx4 v[190:193], v[76:77], off nt
	v_ashrrev_i32_e32 v199, 31, v198
	s_add_i32 s20, s20, s36
	s_add_i32 s2, s2, s3
	s_cmpk_gt_i32 s20, 0xff
	s_waitcnt vmcnt(3) lgkmcnt(7)
	v_mfma_f32_16x16x32_bf16 v[36:39], v[20:23], v[4:7], 0
	s_waitcnt lgkmcnt(6)
	v_mfma_f32_16x16x32_bf16 v[150:153], v[28:31], v[4:7], 0
	s_waitcnt lgkmcnt(4)
	v_mfma_f32_16x16x32_bf16 v[154:157], v[12:15], v[4:7], 0
	s_waitcnt lgkmcnt(1)
	v_mfma_f32_16x16x32_bf16 v[158:161], v[16:19], v[4:7], 0
	global_load_dwordx4 v[4:7], v[72:73], off nt
	s_waitcnt vmcnt(2)
	v_mfma_f32_16x16x32_bf16 v[162:165], v[20:23], v[24:27], 0
	v_mfma_f32_16x16x32_bf16 v[166:169], v[28:31], v[24:27], 0
	v_mfma_f32_16x16x32_bf16 v[170:173], v[12:15], v[24:27], 0
	v_mfma_f32_16x16x32_bf16 v[174:177], v[16:19], v[24:27], 0
	global_load_dwordx4 v[24:27], v[74:75], off nt
	v_mfma_f32_16x16x32_bf16 v[194:197], v[48:51], v[146:149], v[36:39]
	v_mfma_f32_16x16x32_bf16 v[150:153], v[32:35], v[146:149], v[150:153]
	v_mfma_f32_16x16x32_bf16 v[154:157], v[8:11], v[146:149], v[154:157]
	s_waitcnt lgkmcnt(0)
; __device__ __forceinline__ unsigned pk2(float lo, float hi) { return f2bf(lo) | (f2bf(hi) << 16); }
; template <int HF>
; __device__ __forceinline__ void gmlp_half(LAS unsigned char* wl, const bf16* PROJ, const bf16* wsg, const float* norm_v, const float* b_s, bf16* Y, int tok0, int g, int fr, int fq) {
;     ...
;         for (int nt = 0; nt < 4; ++nt)
; #pragma unroll
;             for (int mi = 0; mi < 4; ++mi) acc[mi][nt] = __builtin_amdgcn_mfma_f32_16x16x32_bf16(av[mi], bw[ki][nt], acc[mi][nt], 0, 0, 0);
;     }
;     asm volatile("" ::: "memory");
;     f32x4 nv[2][2];
; #pragma unroll
;     for (int p = 0; p < 2; ++p) { nv[p][0] = *(const f32x4*)(norm_v + g * 64 + 32 * p + 8 * fq); nv[p][1] = *(const f32x4*)(norm_v + g * 64 + 32 * p + 8 * fq + 4); }
; #pragma unroll
;     for (int nt = 0; nt < 4; ++nt) {
;         const int t = 64 * HF + 16 * nt + fr; const size_t tok = (size_t)(tok0 + t); const float bs = b_s[g * 128 + t];
;         u32x4 uu[2];
; #pragma unroll
;         for (int p = 0; p < 2; ++p) uu[p] = *(const u32x4*)(PROJ + tok * NPROJ + g * 64 + 32 * p + 8 * fq);
; #pragma unroll
;         for (int p = 0; p < 2; ++p) {
;             u32x4 w;
; #pragma unroll
;             for (int e2 = 0; e2 < 2; ++e2) {
;                 const f32x4 z = nv[p][e2] * acc[2 * p + e2][nt] + bs;
;                 const unsigned u0 = uu[p][2 * e2], u1 = uu[p][2 * e2 + 1];
;                 w[2 * e2] = pk2(bf_lo(u0) * z[0], bf_hi(u0) * z[1]); w[2 * e2 + 1] = pk2(bf_lo(u1) * z[2], bf_hi(u1) * z[3]);
;             }
;             *(u32x4*)(Y + tok * D + g * 64 + 32 * p + 8 * fq) = w;
	v_mfma_f32_16x16x32_bf16 v[146:149], v[0:3], v[146:149], v[158:161]
	s_waitcnt vmcnt(2)
	v_mfma_f32_16x16x32_bf16 v[158:161], v[48:51], v[190:193], v[162:165]
	v_mfma_f32_16x16x32_bf16 v[162:165], v[32:35], v[190:193], v[166:169]
	v_mfma_f32_16x16x32_bf16 v[166:169], v[8:11], v[190:193], v[170:173]
	v_mfma_f32_16x16x32_bf16 v[170:173], v[0:3], v[190:193], v[174:177]
	s_waitcnt vmcnt(1)
	v_mfma_f32_16x16x32_bf16 v[178:181], v[20:23], v[4:7], 0
	v_mfma_f32_16x16x32_bf16 v[182:185], v[28:31], v[4:7], 0
	v_mfma_f32_16x16x32_bf16 v[186:189], v[12:15], v[4:7], 0
	v_mfma_f32_16x16x32_bf16 v[52:55], v[16:19], v[4:7], 0
	global_load_dwordx4 v[60:63], v[78:79], off nt
	global_load_dwordx4 v[4:7], v[80:81], off nt
	s_waitcnt vmcnt(2)
	v_mfma_f32_16x16x32_bf16 v[56:59], v[20:23], v[24:27], 0
	v_mad_i64_i32 v[20:21], s[30:31], v198, s4, v[82:83]
	global_load_dwordx4 v[202:205], v[20:21], off nt
	global_load_dwordx4 v[44:47], v[118:119], off nt
	global_load_dword v210, v[120:121], off
	v_mfma_f32_16x16x32_bf16 v[40:43], v[28:31], v[24:27], 0
	global_load_dwordx4 v[36:39], v[118:119], off offset:16 nt
	global_load_dwordx4 v[28:31], v[118:119], off offset:128 nt
	global_load_dwordx4 v[206:209], v[20:21], off offset:64 nt
	v_lshlrev_b64 v[198:199], 11, v[198:199]
	global_load_dwordx4 v[20:23], v[118:119], off offset:144 nt
	v_lshl_add_u64 v[198:199], v[84:85], 0, v[198:199]
	v_mfma_f32_16x16x32_bf16 v[12:15], v[12:15], v[24:27], 0
	s_waitcnt vmcnt(6)
	v_lshlrev_b32_e32 v213, 16, v203
	v_lshlrev_b32_e32 v212, 16, v202
	s_waitcnt vmcnt(4)
	v_pk_fma_f32 v[174:175], v[196:197], v[46:47], v[210:211] op_sel_hi:[1,1,0]
	v_pk_fma_f32 v[176:177], v[194:195], v[44:45], v[210:211] op_sel_hi:[1,1,0]
	s_waitcnt vmcnt(3)
	v_pk_fma_f32 v[152:153], v[152:153], v[38:39], v[210:211] op_sel_hi:[1,1,0]
	v_pk_fma_f32 v[150:151], v[150:151], v[36:37], v[210:211] op_sel_hi:[1,1,0]
	v_lshlrev_b32_e32 v215, 16, v205
	v_lshlrev_b32_e32 v214, 16, v204
	v_and_b32_e32 v205, 0xffff0000, v205
	v_and_b32_e32 v204, 0xffff0000, v204
	v_mov_b32_e32 v190, v176
	v_mov_b32_e32 v191, v174
	v_mov_b32_e32 v174, v177
	v_mov_b32_e32 v176, v150
	v_mov_b32_e32 v177, v152
	v_mov_b32_e32 v152, v151
	v_and_b32_e32 v203, 0xffff0000, v203
	v_and_b32_e32 v202, 0xffff0000, v202
	v_pk_mul_f32 v[150:151], v[190:191], v[212:213]
	v_pk_mul_f32 v[176:177], v[176:177], v[214:215]
	v_pk_mul_f32 v[152:153], v[152:153], v[204:205]
	v_pk_mul_f32 v[174:175], v[174:175], v[202:203]
	v_bfe_u32 v145, v153, 16, 1
	v_bfe_u32 v193, v150, 16, 1
	v_bfe_u32 v194, v151, 16, 1
	v_bfe_u32 v195, v176, 16, 1
	v_bfe_u32 v196, v177, 16, 1
	v_bfe_u32 v190, v152, 16, 1
	v_bfe_u32 v191, v175, 16, 1
	v_bfe_u32 v192, v174, 16, 1
	v_add3_u32 v145, v153, v145, s5
	v_add3_u32 v153, v177, v196, s5
	v_add3_u32 v176, v176, v195, s5
	v_add3_u32 v151, v151, v194, s5
	v_add3_u32 v150, v150, v193, s5
	v_add3_u32 v174, v174, v192, s5
	v_add3_u32 v175, v175, v191, s5
	v_add3_u32 v152, v152, v190, s5
	v_lshrrev_b32_e32 v150, 16, v150
	v_lshrrev_b32_e32 v151, 16, v151
	v_lshrrev_b32_e32 v176, 16, v176
	v_lshrrev_b32_e32 v153, 16, v153
	v_and_or_b32 v153, v145, s11, v153
	v_and_or_b32 v152, v152, s11, v176
	v_and_or_b32 v151, v175, s11, v151
	v_and_or_b32 v150, v174, s11, v150
	global_store_dwordx4 v[198:199], v[150:153], off
	s_waitcnt vmcnt(1)
	v_pk_fma_f32 v[148:149], v[148:149], v[22:23], v[210:211] op_sel_hi:[1,1,0]
	v_pk_fma_f32 v[146:147], v[146:147], v[20:21], v[210:211] op_sel_hi:[1,1,0]
	v_pk_fma_f32 v[150:151], v[156:157], v[30:31], v[210:211] op_sel_hi:[1,1,0]
	v_pk_fma_f32 v[152:153], v[154:155], v[28:29], v[210:211] op_sel_hi:[1,1,0]
	v_lshlrev_b32_e32 v155, 16, v207
	v_lshlrev_b32_e32 v154, 16, v206
	v_mov_b32_e32 v156, v152
	v_mov_b32_e32 v157, v150
	v_pk_mul_f32 v[154:155], v[156:157], v[154:155]
	v_and_b32_e32 v157, 0xffff0000, v207
	v_and_b32_e32 v156, 0xffff0000, v206
	v_mov_b32_e32 v150, v153
	v_pk_mul_f32 v[150:151], v[150:151], v[156:157]
	v_lshlrev_b32_e32 v153, 16, v209
	v_lshlrev_b32_e32 v152, 16, v208
	v_mov_b32_e32 v156, v146
	v_mov_b32_e32 v157, v148
	v_pk_mul_f32 v[152:153], v[156:157], v[152:153]
	v_and_b32_e32 v157, 0xffff0000, v209
	v_and_b32_e32 v156, 0xffff0000, v208
	v_mov_b32_e32 v148, v147
	v_pk_mul_f32 v[146:147], v[148:149], v[156:157]
	v_bfe_u32 v149, v151, 16, 1
	v_bfe_u32 v145, v147, 16, 1
	v_bfe_u32 v148, v146, 16, 1
	v_bfe_u32 v156, v150, 16, 1
	v_add3_u32 v150, v150, v156, s5
	v_add3_u32 v151, v151, v149, s5
	v_add3_u32 v146, v146, v148, s5
	v_add3_u32 v145, v147, v145, s5
	v_bfe_u32 v147, v154, 16, 1
	v_bfe_u32 v148, v155, 16, 1
	v_bfe_u32 v149, v152, 16, 1
	v_bfe_u32 v156, v153, 16, 1
	v_add3_u32 v153, v153, v156, s5
	v_add3_u32 v149, v152, v149, s5
	v_add3_u32 v148, v155, v148, s5
	v_add3_u32 v147, v154, v147, s5
	v_lshrrev_b32_e32 v152, 16, v147
	v_lshrrev_b32_e32 v147, 16, v148
	v_lshrrev_b32_e32 v148, 16, v149
	v_lshrrev_b32_e32 v149, 16, v153
	v_and_or_b32 v149, v145, s11, v149
	v_and_or_b32 v148, v146, s11, v148
	v_and_or_b32 v147, v151, s11, v147
	v_and_or_b32 v146, v150, s11, v152
	global_store_dwordx4 v[198:199], v[146:149], off offset:64
	v_or_b32_e32 v190, s28, v133
	global_load_dword v192, v[120:121], off offset:64
	v_mad_i64_i32 v[154:155], s[30:31], v190, s4, v[82:83]
	global_load_dwordx4 v[146:149], v[154:155], off nt
	v_ashrrev_i32_e32 v191, 31, v190
	global_load_dwordx4 v[154:157], v[154:155], off offset:64 nt
	v_mfma_f32_16x16x32_bf16 v[150:153], v[48:51], v[60:63], v[178:181]
	v_or_b32_e32 v198, s28, v135
	v_ashrrev_i32_e32 v199, 31, v198
	s_waitcnt vmcnt(2)
; __device__ __forceinline__ unsigned pk2(float lo, float hi) { return f2bf(lo) | (f2bf(hi) << 16); }
; template <int HF>
; __device__ __forceinline__ void gmlp_half(LAS unsigned char* wl, const bf16* PROJ, const bf16* wsg, const float* norm_v, const float* b_s, bf16* Y, int tok0, int g, int fr, int fq) {
;     ...
;     for (int nt = 0; nt < 4; ++nt) {
;         const int t = 64 * HF + 16 * nt + fr; const size_t tok = (size_t)(tok0 + t); const float bs = b_s[g * 128 + t];
;         u32x4 uu[2];
; #pragma unroll
;         for (int p = 0; p < 2; ++p) uu[p] = *(const u32x4*)(PROJ + tok * NPROJ + g * 64 + 32 * p + 8 * fq);
; #pragma unroll
;         for (int p = 0; p < 2; ++p) {
;             u32x4 w;
; #pragma unroll
;             for (int e2 = 0; e2 < 2; ++e2) {
;                 const f32x4 z = nv[p][e2] * acc[2 * p + e2][nt] + bs;
;                 const unsigned u0 = uu[p][2 * e2], u1 = uu[p][2 * e2 + 1];
;                 w[2 * e2] = pk2(bf_lo(u0) * z[0], bf_hi(u0) * z[1]); w[2 * e2 + 1] = pk2(bf_lo(u1) * z[2], bf_hi(u1) * z[3]);
;             }
;             *(u32x4*)(Y + tok * D + g * 64 + 32 * p + 8 * fq) = w;
	v_pk_fma_f32 v[160:161], v[160:161], v[46:47], v[192:193] op_sel_hi:[1,1,0]
	v_lshlrev_b64 v[178:179], 11, v[190:191]
	v_pk_fma_f32 v[158:159], v[158:159], v[44:45], v[192:193] op_sel_hi:[1,1,0]
	v_pk_fma_f32 v[164:165], v[164:165], v[38:39], v[192:193] op_sel_hi:[1,1,0]
	v_pk_fma_f32 v[162:163], v[162:163], v[36:37], v[192:193] op_sel_hi:[1,1,0]
	v_mfma_f32_16x16x32_bf16 v[174:177], v[32:35], v[60:63], v[182:185]
	s_nop 2
	v_lshl_add_u64 v[182:183], v[84:85], 0, v[178:179]
	v_mfma_f32_16x16x32_bf16 v[178:181], v[8:11], v[60:63], v[186:189]
	s_waitcnt vmcnt(1)
	v_lshlrev_b32_e32 v185, 16, v147
	v_lshlrev_b32_e32 v184, 16, v146
	v_and_b32_e32 v147, 0xffff0000, v147
	v_and_b32_e32 v146, 0xffff0000, v146
	v_lshlrev_b32_e32 v187, 16, v149
	v_lshlrev_b32_e32 v186, 16, v148
	v_and_b32_e32 v149, 0xffff0000, v149
	v_mov_b32_e32 v189, v160
	v_mov_b32_e32 v160, v159
	v_mov_b32_e32 v159, v164
	v_and_b32_e32 v148, 0xffff0000, v148
	v_mov_b32_e32 v164, v163
	v_mov_b32_e32 v188, v158
	v_mov_b32_e32 v158, v162
	v_pk_mul_f32 v[146:147], v[160:161], v[146:147]
	v_pk_mul_f32 v[148:149], v[164:165], v[148:149]
	v_pk_mul_f32 v[184:185], v[188:189], v[184:185]
	v_pk_mul_f32 v[158:159], v[158:159], v[186:187]
	v_bfe_u32 v145, v149, 16, 1
	v_bfe_u32 v160, v148, 16, 1
	v_bfe_u32 v161, v147, 16, 1
	v_bfe_u32 v162, v146, 16, 1
	v_add3_u32 v146, v146, v162, s5
	v_add3_u32 v147, v147, v161, s5
	v_add3_u32 v148, v148, v160, s5
	v_add3_u32 v145, v149, v145, s5
	v_bfe_u32 v149, v184, 16, 1
	v_bfe_u32 v160, v185, 16, 1
	v_bfe_u32 v161, v158, 16, 1
	v_bfe_u32 v162, v159, 16, 1
	v_add3_u32 v159, v159, v162, s5
	v_add3_u32 v158, v158, v161, s5
	v_add3_u32 v160, v185, v160, s5
	v_add3_u32 v149, v184, v149, s5
	v_lshrrev_b32_e32 v161, 16, v149
	v_lshrrev_b32_e32 v160, 16, v160
	v_lshrrev_b32_e32 v158, 16, v158
	v_lshrrev_b32_e32 v149, 16, v159
	v_and_or_b32 v149, v145, s11, v149
	v_and_or_b32 v148, v148, s11, v158
	v_and_or_b32 v147, v147, s11, v160
	v_and_or_b32 v146, v146, s11, v161
	global_store_dwordx4 v[182:183], v[146:149], off
	s_waitcnt vmcnt(1)
	v_lshlrev_b32_e32 v159, 16, v155
	v_lshlrev_b32_e32 v158, 16, v154
	v_pk_fma_f32 v[146:147], v[168:169], v[30:31], v[192:193] op_sel_hi:[1,1,0]
	v_pk_fma_f32 v[148:149], v[166:167], v[28:29], v[192:193] op_sel_hi:[1,1,0]
	v_mov_b32_e32 v161, v146
	v_and_b32_e32 v155, 0xffff0000, v155
	v_and_b32_e32 v154, 0xffff0000, v154
	v_mov_b32_e32 v146, v149
	v_mov_b32_e32 v160, v148
	v_pk_mul_f32 v[146:147], v[146:147], v[154:155]
	v_pk_fma_f32 v[148:149], v[172:173], v[22:23], v[192:193] op_sel_hi:[1,1,0]
	v_pk_fma_f32 v[154:155], v[170:171], v[20:21], v[192:193] op_sel_hi:[1,1,0]
	v_pk_mul_f32 v[158:159], v[160:161], v[158:159]
	v_lshlrev_b32_e32 v161, 16, v157
	v_lshlrev_b32_e32 v160, 16, v156
	v_mov_b32_e32 v163, v148
	v_and_b32_e32 v157, 0xffff0000, v157
	v_and_b32_e32 v156, 0xffff0000, v156
	v_mov_b32_e32 v148, v155
	v_mov_b32_e32 v162, v154
	v_pk_mul_f32 v[148:149], v[148:149], v[156:157]
	v_pk_mul_f32 v[160:161], v[162:163], v[160:161]
	v_bfe_u32 v145, v149, 16, 1
	v_bfe_u32 v154, v148, 16, 1
	v_bfe_u32 v155, v147, 16, 1
	v_bfe_u32 v156, v146, 16, 1
	v_add3_u32 v146, v146, v156, s5
	v_add3_u32 v147, v147, v155, s5
	v_add3_u32 v148, v148, v154, s5
	v_add3_u32 v145, v149, v145, s5
	v_bfe_u32 v149, v158, 16, 1
	v_bfe_u32 v154, v159, 16, 1
	v_bfe_u32 v155, v160, 16, 1
	v_bfe_u32 v156, v161, 16, 1
	v_add3_u32 v156, v161, v156, s5
	v_add3_u32 v155, v160, v155, s5
	v_add3_u32 v154, v159, v154, s5
	v_add3_u32 v149, v158, v149, s5
	v_lshrrev_b32_e32 v157, 16, v149
	v_lshrrev_b32_e32 v154, 16, v154
	v_lshrrev_b32_e32 v155, 16, v155
	v_lshrrev_b32_e32 v149, 16, v156
	v_and_or_b32 v149, v145, s11, v149
	v_and_or_b32 v148, v148, s11, v155
	v_and_or_b32 v147, v147, s11, v154
	v_and_or_b32 v146, v146, s11, v157
	global_store_dwordx4 v[182:183], v[146:149], off offset:64
	v_or_b32_e32 v154, s28, v134
	global_load_dword v156, v[120:121], off offset:128
	v_mad_i64_i32 v[158:159], s[30:31], v154, s4, v[82:83]
	global_load_dwordx4 v[146:149], v[158:159], off nt
	v_mfma_f32_16x16x32_bf16 v[52:55], v[0:3], v[60:63], v[52:55]
	global_load_dwordx4 v[60:63], v[158:159], off offset:64 nt
	v_ashrrev_i32_e32 v155, 31, v154
	v_mfma_f32_16x16x32_bf16 v[48:51], v[48:51], v[4:7], v[56:59]
	s_nop 2
	v_lshlrev_b64 v[56:57], 11, v[154:155]
	v_lshl_add_u64 v[154:155], v[84:85], 0, v[56:57]
	v_mfma_f32_16x16x32_bf16 v[32:35], v[32:35], v[4:7], v[40:43]
	s_waitcnt vmcnt(2)
	v_pk_fma_f32 v[56:57], v[152:153], v[46:47], v[156:157] op_sel_hi:[1,1,0]
	v_pk_fma_f32 v[58:59], v[150:151], v[44:45], v[156:157] op_sel_hi:[1,1,0]
	v_mov_b32_e32 v153, v56
	s_waitcnt vmcnt(1)
	v_lshlrev_b32_e32 v151, 16, v147
	v_lshlrev_b32_e32 v150, 16, v146
	v_and_b32_e32 v147, 0xffff0000, v147
	v_and_b32_e32 v146, 0xffff0000, v146
	v_mov_b32_e32 v56, v59
	v_mov_b32_e32 v152, v58
	v_pk_mul_f32 v[56:57], v[56:57], v[146:147]
	v_pk_fma_f32 v[58:59], v[176:177], v[38:39], v[156:157] op_sel_hi:[1,1,0]
	v_pk_fma_f32 v[146:147], v[174:175], v[36:37], v[156:157] op_sel_hi:[1,1,0]
	v_pk_mul_f32 v[150:151], v[152:153], v[150:151]
	v_lshlrev_b32_e32 v153, 16, v149
	v_lshlrev_b32_e32 v152, 16, v148
	v_mov_b32_e32 v159, v58
	v_and_b32_e32 v149, 0xffff0000, v149
	v_and_b32_e32 v148, 0xffff0000, v148
	v_mov_b32_e32 v58, v147
	v_mov_b32_e32 v158, v146
	v_pk_mul_f32 v[58:59], v[58:59], v[148:149]
	v_pk_mul_f32 v[152:153], v[158:159], v[152:153]
	v_bfe_u32 v145, v59, 16, 1
	v_bfe_u32 v146, v58, 16, 1
	v_bfe_u32 v147, v57, 16, 1
	v_bfe_u32 v148, v56, 16, 1
	v_add3_u32 v56, v56, v148, s5
	v_add3_u32 v57, v57, v147, s5
	v_add3_u32 v58, v58, v146, s5
	v_add3_u32 v59, v59, v145, s5
	v_bfe_u32 v145, v150, 16, 1
	v_bfe_u32 v146, v151, 16, 1
	v_bfe_u32 v147, v152, 16, 1
	v_bfe_u32 v148, v153, 16, 1
	v_add3_u32 v148, v153, v148, s5
	v_add3_u32 v147, v152, v147, s5
	v_add3_u32 v146, v151, v146, s5
	v_add3_u32 v145, v150, v145, s5
	v_lshrrev_b32_e32 v145, 16, v145
	v_lshrrev_b32_e32 v146, 16, v146
	v_lshrrev_b32_e32 v147, 16, v147
	v_lshrrev_b32_e32 v148, 16, v148
	v_and_or_b32 v59, v59, s11, v148
	v_and_or_b32 v58, v58, s11, v147
	v_and_or_b32 v57, v57, s11, v146
	v_and_or_b32 v56, v56, s11, v145
	global_store_dwordx4 v[154:155], v[56:59], off
	s_waitcnt vmcnt(1)
; #define LAS __attribute__((address_space(3)))
; __device__ __forceinline__ unsigned pk2(float lo, float hi) { return f2bf(lo) | (f2bf(hi) << 16); }
; template <int HF>
; __device__ __forceinline__ void gmlp_half(LAS unsigned char* wl, const bf16* PROJ, const bf16* wsg, const float* norm_v, const float* b_s, bf16* Y, int tok0, int g, int fr, int fq) {
;     ...
; #pragma unroll
;     for (int ki = 0; ki < NK; ++ki)
; #pragma unroll
;         for (int nt = 0; nt < 4; ++nt) bw[ki][nt] = *(const bf16x8*)(wsg + (size_t)(64 * HF + 16 * nt + fr) * 128 + 32 * ki + 8 * fq);
;     f32x4 acc[4][4];
; #pragma unroll
;     for (int i = 0; i < 4; ++i)
; #pragma unroll
;         for (int j = 0; j < 4; ++j) acc[i][j] = (f32x4){0.f, 0.f, 0.f, 0.f};
; #pragma unroll
;     for (int ki = 0; ki < NK; ++ki) {
;         bf16x8 av[4];
; #pragma unroll
;         for (int mi = 0; mi < 4; ++mi) av[mi] = *(const LAS bf16x8*)(wl + ((32 * (mi >> 1) + 8 * (fr >> 2) + 4 * (mi & 1) + (fr & 3)) * VS + 32 * ki + 8 * fq) * 2);
; #pragma unroll
;         for (int nt = 0; nt < 4; ++nt)
; #pragma unroll
;             for (int mi = 0; mi < 4; ++mi) acc[mi][nt] = __builtin_amdgcn_mfma_f32_16x16x32_bf16(av[mi], bw[ki][nt], acc[mi][nt], 0, 0, 0);
;     ...
;     for (int nt = 0; nt < 4; ++nt) {
;         const int t = 64 * HF + 16 * nt + fr; const size_t tok = (size_t)(tok0 + t); const float bs = b_s[g * 128 + t];
;         u32x4 uu[2];
; #pragma unroll
;         for (int p = 0; p < 2; ++p) uu[p] = *(const u32x4*)(PROJ + tok * NPROJ + g * 64 + 32 * p + 8 * fq);
; #pragma unroll
;         for (int p = 0; p < 2; ++p) {
;             u32x4 w;
; #pragma unroll
;             for (int e2 = 0; e2 < 2; ++e2) {
;                 const f32x4 z = nv[p][e2] * acc[2 * p + e2][nt] + bs;
;                 const unsigned u0 = uu[p][2 * e2], u1 = uu[p][2 * e2 + 1];
;                 w[2 * e2] = pk2(bf_lo(u0) * z[0], bf_hi(u0) * z[1]); w[2 * e2 + 1] = pk2(bf_lo(u1) * z[2], bf_hi(u1) * z[3]);
;             }
;             *(u32x4*)(Y + tok * D + g * 64 + 32 * p + 8 * fq) = w;
	v_lshlrev_b32_e32 v147, 16, v61
	v_lshlrev_b32_e32 v146, 16, v60
	v_pk_fma_f32 v[56:57], v[180:181], v[30:31], v[156:157] op_sel_hi:[1,1,0]
	v_pk_fma_f32 v[58:59], v[178:179], v[28:29], v[156:157] op_sel_hi:[1,1,0]
	v_mov_b32_e32 v149, v56
	v_and_b32_e32 v61, 0xffff0000, v61
	v_and_b32_e32 v60, 0xffff0000, v60
	v_mov_b32_e32 v56, v59
	v_pk_fma_f32 v[54:55], v[54:55], v[22:23], v[156:157] op_sel_hi:[1,1,0]
	v_pk_fma_f32 v[52:53], v[52:53], v[20:21], v[156:157] op_sel_hi:[1,1,0]
	v_mov_b32_e32 v148, v58
	v_pk_mul_f32 v[56:57], v[56:57], v[60:61]
	v_lshlrev_b32_e32 v59, 16, v63
	v_lshlrev_b32_e32 v58, 16, v62
	v_mov_b32_e32 v60, v52
	v_mov_b32_e32 v61, v54
	v_pk_mul_f32 v[58:59], v[60:61], v[58:59]
	v_and_b32_e32 v61, 0xffff0000, v63
	v_and_b32_e32 v60, 0xffff0000, v62
	v_mov_b32_e32 v54, v53
	v_pk_mul_f32 v[52:53], v[54:55], v[60:61]
	v_pk_mul_f32 v[146:147], v[148:149], v[146:147]
	v_bfe_u32 v54, v53, 16, 1
	v_bfe_u32 v55, v52, 16, 1
	v_bfe_u32 v60, v57, 16, 1
	v_bfe_u32 v61, v56, 16, 1
	v_add3_u32 v56, v56, v61, s5
	v_add3_u32 v57, v57, v60, s5
	v_add3_u32 v52, v52, v55, s5
	v_add3_u32 v53, v53, v54, s5
	v_bfe_u32 v54, v146, 16, 1
	v_bfe_u32 v55, v147, 16, 1
	v_bfe_u32 v60, v58, 16, 1
	v_bfe_u32 v61, v59, 16, 1
	v_add3_u32 v59, v59, v61, s5
	v_add3_u32 v58, v58, v60, s5
	v_add3_u32 v55, v147, v55, s5
	v_add3_u32 v54, v146, v54, s5
	v_lshrrev_b32_e32 v60, 16, v54
	v_lshrrev_b32_e32 v61, 16, v55
	v_lshrrev_b32_e32 v54, 16, v58
	v_lshrrev_b32_e32 v55, 16, v59
	v_and_or_b32 v55, v53, s11, v55
	v_and_or_b32 v54, v52, s11, v54
	v_and_or_b32 v53, v57, s11, v61
	v_and_or_b32 v52, v56, s11, v60
	global_store_dwordx4 v[154:155], v[52:55], off offset:64
	v_or_b32_e32 v56, s28, v131
	global_load_dword v150, v[122:123], off
	v_mad_i64_i32 v[58:59], s[30:31], v56, s4, v[82:83]
	global_load_dwordx4 v[52:55], v[58:59], off nt
	global_load_dwordx4 v[40:43], v[58:59], off offset:64 nt
	v_ashrrev_i32_e32 v57, 31, v56
	v_lshlrev_b64 v[56:57], 11, v[56:57]
	v_lshl_add_u64 v[170:171], v[84:85], 0, v[56:57]
	v_mfma_f32_16x16x32_bf16 v[16:19], v[16:19], v[24:27], 0
	s_waitcnt vmcnt(2)
	v_pk_fma_f32 v[46:47], v[50:51], v[46:47], v[150:151] op_sel_hi:[1,1,0]
	v_pk_fma_f32 v[44:45], v[48:49], v[44:45], v[150:151] op_sel_hi:[1,1,0]
	v_pk_fma_f32 v[34:35], v[34:35], v[38:39], v[150:151] op_sel_hi:[1,1,0]
	v_pk_fma_f32 v[32:33], v[32:33], v[36:37], v[150:151] op_sel_hi:[1,1,0]
	s_waitcnt vmcnt(1)
	v_lshlrev_b32_e32 v49, 16, v53
	v_lshlrev_b32_e32 v48, 16, v52
	v_mov_b32_e32 v50, v44
	v_mov_b32_e32 v51, v46
	v_lshlrev_b32_e32 v37, 16, v55
	v_lshlrev_b32_e32 v36, 16, v54
	v_mov_b32_e32 v38, v32
	v_mov_b32_e32 v39, v34
	v_pk_mul_f32 v[48:49], v[50:51], v[48:49]
	v_and_b32_e32 v51, 0xffff0000, v53
	v_and_b32_e32 v50, 0xffff0000, v52
	v_mov_b32_e32 v46, v45
	v_pk_mul_f32 v[36:37], v[38:39], v[36:37]
	v_and_b32_e32 v39, 0xffff0000, v55
	v_and_b32_e32 v38, 0xffff0000, v54
	v_mov_b32_e32 v34, v33
	v_pk_mul_f32 v[44:45], v[46:47], v[50:51]
	v_pk_mul_f32 v[32:33], v[34:35], v[38:39]
	v_bfe_u32 v38, v45, 16, 1
	v_bfe_u32 v34, v33, 16, 1
	v_bfe_u32 v35, v32, 16, 1
	v_bfe_u32 v39, v44, 16, 1
	v_add3_u32 v39, v44, v39, s5
	v_add3_u32 v38, v45, v38, s5
	v_add3_u32 v32, v32, v35, s5
	v_add3_u32 v33, v33, v34, s5
	v_bfe_u32 v34, v48, 16, 1
	v_bfe_u32 v35, v49, 16, 1
	v_bfe_u32 v44, v36, 16, 1
	v_bfe_u32 v45, v37, 16, 1
	v_add3_u32 v37, v37, v45, s5
	v_add3_u32 v36, v36, v44, s5
	v_add3_u32 v35, v49, v35, s5
	v_add3_u32 v34, v48, v34, s5
	v_lshrrev_b32_e32 v44, 16, v34
	v_lshrrev_b32_e32 v45, 16, v35
	v_lshrrev_b32_e32 v34, 16, v36
	v_lshrrev_b32_e32 v35, 16, v37
	v_and_or_b32 v35, v33, s11, v35
	v_and_or_b32 v34, v32, s11, v34
	v_and_or_b32 v33, v38, s11, v45
	v_and_or_b32 v32, v39, s11, v44
	global_store_dwordx4 v[170:171], v[32:35], off
	global_load_dwordx4 v[32:35], v[86:87], off nt
	s_nop 0
	global_load_dwordx4 v[36:39], v[88:89], off nt
	global_load_dwordx4 v[44:47], v[90:91], off nt
	global_load_dwordx4 v[24:27], v[92:93], off nt
	v_mfma_f32_16x16x32_bf16 v[8:11], v[8:11], v[4:7], v[12:15]
	ds_read_b128 v[48:51], v144 offset:8704
	ds_read_b128 v[52:55], v144 offset:9792
	s_nop 0
	ds_read_b128 v[12:15], v144
	ds_read_b128 v[56:59], v144 offset:64
	ds_read_b128 v[60:63], v144 offset:1088
	ds_read_b128 v[146:149], v144 offset:1152
	s_nop 0
	v_pk_fma_f32 v[8:9], v[8:9], v[28:29], v[150:151] op_sel_hi:[1,1,0]
	v_mfma_f32_16x16x32_bf16 v[0:3], v[0:3], v[4:7], v[16:19]
	v_mov_b32_e32 v28, v8
	s_nop 1
	v_pk_fma_f32 v[16:17], v[10:11], v[30:31], v[150:151] op_sel_hi:[1,1,0]
	s_waitcnt vmcnt(5)
	v_lshlrev_b32_e32 v11, 16, v41
	s_nop 1
	v_pk_fma_f32 v[152:153], v[2:3], v[22:23], v[150:151] op_sel_hi:[1,1,0]
	v_pk_fma_f32 v[150:151], v[0:1], v[20:21], v[150:151] op_sel_hi:[1,1,0]
	v_lshlrev_b32_e32 v10, 16, v40
	v_and_b32_e32 v19, 0xffff0000, v41
	v_and_b32_e32 v18, 0xffff0000, v40
	v_mov_b32_e32 v29, v16
	v_lshlrev_b32_e32 v41, 16, v43
	v_lshlrev_b32_e32 v40, 16, v42
	v_mov_b32_e32 v156, v150
	v_mov_b32_e32 v157, v152
	v_mov_b32_e32 v16, v9
	v_pk_mul_f32 v[166:167], v[28:29], v[10:11]
	v_pk_mul_f32 v[168:169], v[156:157], v[40:41]
	v_and_b32_e32 v157, 0xffff0000, v43
	v_and_b32_e32 v156, 0xffff0000, v42
	v_mov_b32_e32 v152, v151
	v_pk_mul_f32 v[154:155], v[16:17], v[18:19]
	v_pk_mul_f32 v[158:159], v[152:153], v[156:157]
	v_bfe_u32 v175, v166, 16, 1
	v_bfe_u32 v176, v167, 16, 1
	v_bfe_u32 v177, v168, 16, 1
	v_bfe_u32 v162, v169, 16, 1
	v_bfe_u32 v145, v159, 16, 1
	v_bfe_u32 v156, v158, 16, 1
	v_bfe_u32 v157, v155, 16, 1
	v_bfe_u32 v160, v154, 16, 1
	v_add3_u32 v169, v169, v162, s5
	v_add3_u32 v168, v168, v177, s5
	v_add3_u32 v167, v167, v176, s5
	v_add3_u32 v166, v166, v175, s5
	v_add3_u32 v172, v154, v160, s5
	v_add3_u32 v173, v155, v157, s5
	v_add3_u32 v174, v158, v156, s5
	v_add3_u32 v145, v159, v145, s5
	v_lshrrev_b32_e32 v166, 16, v166
	v_lshrrev_b32_e32 v167, 16, v167
	v_lshrrev_b32_e32 v168, 16, v168
	v_lshrrev_b32_e32 v169, 16, v169
	v_and_or_b32 v169, v145, s11, v169
	v_and_or_b32 v168, v174, s11, v168
	v_and_or_b32 v167, v173, s11, v167
	v_and_or_b32 v166, v172, s11, v166
	global_store_dwordx4 v[170:171], v[166:169], off offset:64
	s_waitcnt vmcnt(4) lgkmcnt(3)
; #define LAS __attribute__((address_space(3)))
; template <int HF>
; __device__ __forceinline__ void gmlp_half(LAS unsigned char* wl, const bf16* PROJ, const bf16* wsg, const float* norm_v, const float* b_s, bf16* Y, int tok0, int g, int fr, int fq) {
;     ...
; #pragma unroll
;     for (int ki = 0; ki < NK; ++ki)
; #pragma unroll
;         for (int nt = 0; nt < 4; ++nt) bw[ki][nt] = *(const bf16x8*)(wsg + (size_t)(64 * HF + 16 * nt + fr) * 128 + 32 * ki + 8 * fq);
;     f32x4 acc[4][4];
; #pragma unroll
;     for (int i = 0; i < 4; ++i)
; #pragma unroll
;         for (int j = 0; j < 4; ++j) acc[i][j] = (f32x4){0.f, 0.f, 0.f, 0.f};
; #pragma unroll
;     for (int ki = 0; ki < NK; ++ki) {
;         bf16x8 av[4];
; #pragma unroll
;         for (int mi = 0; mi < 4; ++mi) av[mi] = *(const LAS bf16x8*)(wl + ((32 * (mi >> 1) + 8 * (fr >> 2) + 4 * (mi & 1) + (fr & 3)) * VS + 32 * ki + 8 * fq) * 2);
; #pragma unroll
;         for (int nt = 0; nt < 4; ++nt)
; #pragma unroll
;             for (int mi = 0; mi < 4; ++mi) acc[mi][nt] = __builtin_amdgcn_mfma_f32_16x16x32_bf16(av[mi], bw[ki][nt], acc[mi][nt], 0, 0, 0);
;     }
;     asm volatile("" ::: "memory");
;     f32x4 nv[2][2];
; #pragma unroll
;     for (int p = 0; p < 2; ++p) { nv[p][0] = *(const f32x4*)(norm_v + g * 64 + 32 * p + 8 * fq); nv[p][1] = *(const f32x4*)(norm_v + g * 64 + 32 * p + 8 * fq + 4); }
; #pragma unroll
;     for (int nt = 0; nt < 4; ++nt) {
;         const int t = 64 * HF + 16 * nt + fr; const size_t tok = (size_t)(tok0 + t); const float bs = b_s[g * 128 + t];
;         u32x4 uu[2];
; #pragma unroll
;         for (int p = 0; p < 2; ++p) uu[p] = *(const u32x4*)(PROJ + tok * NPROJ + g * 64 + 32 * p + 8 * fq);
	v_mfma_f32_16x16x32_bf16 v[4:7], v[12:15], v[32:35], 0
	global_load_dwordx4 v[166:169], v[94:95], off nt
	ds_read_b128 v[16:19], v144 offset:8768
	ds_read_b128 v[0:3], v144 offset:9856
	s_waitcnt lgkmcnt(3)
	v_mfma_f32_16x16x32_bf16 v[8:11], v[60:63], v[32:35], 0
	v_mfma_f32_16x16x32_bf16 v[28:31], v[48:51], v[32:35], 0
	v_mfma_f32_16x16x32_bf16 v[20:23], v[52:55], v[32:35], 0
	s_waitcnt vmcnt(4)
	v_mfma_f32_16x16x32_bf16 v[32:35], v[12:15], v[36:39], 0
	v_mfma_f32_16x16x32_bf16 v[40:43], v[60:63], v[36:39], 0
	v_mfma_f32_16x16x32_bf16 v[150:153], v[48:51], v[36:39], 0
	v_mfma_f32_16x16x32_bf16 v[36:39], v[52:55], v[36:39], 0
	s_waitcnt vmcnt(3)
	v_mfma_f32_16x16x32_bf16 v[154:157], v[12:15], v[44:47], 0
	v_mfma_f32_16x16x32_bf16 v[158:161], v[60:63], v[44:47], 0
	v_mfma_f32_16x16x32_bf16 v[162:165], v[48:51], v[44:47], 0
	v_mfma_f32_16x16x32_bf16 v[44:47], v[52:55], v[44:47], 0
	s_waitcnt vmcnt(2)
	v_mfma_f32_16x16x32_bf16 v[12:15], v[12:15], v[24:27], 0
	v_mfma_f32_16x16x32_bf16 v[60:63], v[60:63], v[24:27], 0
	v_mfma_f32_16x16x32_bf16 v[48:51], v[48:51], v[24:27], 0
	v_mfma_f32_16x16x32_bf16 v[24:27], v[52:55], v[24:27], 0
	global_load_dwordx4 v[52:55], v[96:97], off nt
	s_waitcnt vmcnt(1)
	v_mfma_f32_16x16x32_bf16 v[4:7], v[56:59], v[166:169], v[4:7]
	s_waitcnt lgkmcnt(2)
	v_mfma_f32_16x16x32_bf16 v[8:11], v[146:149], v[166:169], v[8:11]
	s_waitcnt lgkmcnt(1)
	v_mfma_f32_16x16x32_bf16 v[28:31], v[16:19], v[166:169], v[28:31]
	s_waitcnt lgkmcnt(0)
	v_mfma_f32_16x16x32_bf16 v[20:23], v[0:3], v[166:169], v[20:23]
	s_waitcnt vmcnt(0)
	v_mfma_f32_16x16x32_bf16 v[32:35], v[56:59], v[52:55], v[32:35]
	v_mfma_f32_16x16x32_bf16 v[166:169], v[146:149], v[52:55], v[40:43]
	v_mfma_f32_16x16x32_bf16 v[150:153], v[16:19], v[52:55], v[150:153]
	s_nop 1
	global_load_dwordx4 v[40:43], v[98:99], off nt
	v_mfma_f32_16x16x32_bf16 v[52:55], v[0:3], v[52:55], v[36:39]
	s_nop 2
	global_load_dwordx4 v[36:39], v[100:101], off nt
	s_waitcnt vmcnt(1)
	v_mfma_f32_16x16x32_bf16 v[158:161], v[146:149], v[40:43], v[158:161]
	s_waitcnt vmcnt(0)
	v_mfma_f32_16x16x32_bf16 v[60:63], v[146:149], v[36:39], v[60:63]
	global_load_dwordx4 v[146:149], v[102:103], off nt
	v_mfma_f32_16x16x32_bf16 v[154:157], v[56:59], v[40:43], v[154:157]
	v_mfma_f32_16x16x32_bf16 v[162:165], v[16:19], v[40:43], v[162:165]
	v_mfma_f32_16x16x32_bf16 v[44:47], v[0:3], v[40:43], v[44:47]
	v_mfma_f32_16x16x32_bf16 v[56:59], v[56:59], v[36:39], v[12:15]
	v_mfma_f32_16x16x32_bf16 v[16:19], v[16:19], v[36:39], v[48:51]
	s_nop 2
	global_load_dwordx4 v[48:51], v[104:105], off nt
	v_mfma_f32_16x16x32_bf16 v[0:3], v[0:3], v[36:39], v[24:27]
	s_nop 2
	ds_read_b128 v[24:27], v144 offset:128
	ds_read_b128 v[36:39], v144 offset:192
	ds_read_b128 v[170:173], v144 offset:1216
	ds_read_b128 v[40:43], v144 offset:1280
	s_waitcnt vmcnt(1) lgkmcnt(1)
	v_mfma_f32_16x16x32_bf16 v[174:177], v[170:173], v[146:149], v[8:11]
	ds_read_b128 v[178:181], v144 offset:8832
	s_nop 1
	ds_read_b128 v[8:11], v144 offset:8896
	ds_read_b128 v[182:185], v144 offset:9920
	ds_read_b128 v[12:15], v144 offset:9984
	global_load_dwordx4 v[186:189], v[108:109], off nt
	v_mfma_f32_16x16x32_bf16 v[4:7], v[24:27], v[146:149], v[4:7]
	s_waitcnt lgkmcnt(3)
	v_mfma_f32_16x16x32_bf16 v[28:31], v[178:181], v[146:149], v[28:31]
	s_waitcnt lgkmcnt(1)
	v_mfma_f32_16x16x32_bf16 v[146:149], v[182:185], v[146:149], v[20:23]
	s_nop 2
	global_load_dwordx4 v[20:23], v[106:107], off nt
	s_waitcnt vmcnt(2)
	v_mfma_f32_16x16x32_bf16 v[32:35], v[24:27], v[48:51], v[32:35]
	v_mfma_f32_16x16x32_bf16 v[166:169], v[170:173], v[48:51], v[166:169]
	v_mfma_f32_16x16x32_bf16 v[150:153], v[178:181], v[48:51], v[150:153]
	v_mfma_f32_16x16x32_bf16 v[52:55], v[182:185], v[48:51], v[52:55]
	s_waitcnt vmcnt(0)
	v_mfma_f32_16x16x32_bf16 v[154:157], v[24:27], v[20:23], v[154:157]
	v_mfma_f32_16x16x32_bf16 v[48:51], v[24:27], v[186:189], v[56:59]
	global_load_dwordx4 v[24:27], v[110:111], off nt
	v_mfma_f32_16x16x32_bf16 v[158:161], v[170:173], v[20:23], v[158:161]
	s_nop 0
	v_mad_i64_i32 v[56:57], s[30:31], v198, s4, v[82:83]
	v_mfma_f32_16x16x32_bf16 v[162:165], v[178:181], v[20:23], v[162:165]
	v_mfma_f32_16x16x32_bf16 v[190:193], v[182:185], v[20:23], v[44:47]
	v_mfma_f32_16x16x32_bf16 v[20:23], v[182:185], v[186:189], v[0:3]
	s_nop 2
	global_load_dwordx4 v[0:3], v[112:113], off nt
	v_mfma_f32_16x16x32_bf16 v[44:47], v[170:173], v[186:189], v[60:63]
	v_mfma_f32_16x16x32_bf16 v[16:19], v[178:181], v[186:189], v[16:19]
	s_waitcnt vmcnt(1)
	v_mfma_f32_16x16x32_bf16 v[178:181], v[8:11], v[24:27], v[28:31]
	global_load_dwordx4 v[186:189], v[114:115], off nt
	s_nop 1
	global_load_dwordx4 v[28:31], v[116:117], off nt
	global_load_dword v206, v[120:121], off offset:256
	s_waitcnt vmcnt(3)
	v_mfma_f32_16x16x32_bf16 v[182:185], v[36:39], v[0:3], v[32:35]
	s_nop 2
	global_load_dwordx4 v[32:35], v[118:119], off nt
	global_load_dwordx4 v[194:197], v[56:57], off nt
	v_mfma_f32_16x16x32_bf16 v[170:173], v[36:39], v[24:27], v[4:7]
	v_mfma_f32_16x16x32_bf16 v[174:177], v[40:43], v[24:27], v[174:177]
	s_waitcnt lgkmcnt(0)
	v_mfma_f32_16x16x32_bf16 v[146:149], v[12:15], v[24:27], v[146:149]
	global_load_dwordx4 v[24:27], v[118:119], off offset:16 nt
	global_load_dwordx4 v[4:7], v[118:119], off offset:128 nt
	global_load_dwordx4 v[202:205], v[56:57], off offset:64 nt
	v_mfma_f32_16x16x32_bf16 v[166:169], v[40:43], v[0:3], v[166:169]
	v_mfma_f32_16x16x32_bf16 v[150:153], v[8:11], v[0:3], v[150:153]
	v_mfma_f32_16x16x32_bf16 v[60:63], v[12:15], v[0:3], v[52:55]
	global_load_dwordx4 v[0:3], v[118:119], off offset:144 nt
	s_waitcnt vmcnt(0)
; __device__ __forceinline__ unsigned pk2(float lo, float hi) { return f2bf(lo) | (f2bf(hi) << 16); }
; template <int HF>
; __device__ __forceinline__ void gmlp_half(LAS unsigned char* wl, const bf16* PROJ, const bf16* wsg, const float* norm_v, const float* b_s, bf16* Y, int tok0, int g, int fr, int fq) {
;     ...
;     for (int nt = 0; nt < 4; ++nt) {
;         const int t = 64 * HF + 16 * nt + fr; const size_t tok = (size_t)(tok0 + t); const float bs = b_s[g * 128 + t];
;         u32x4 uu[2];
; #pragma unroll
;         for (int p = 0; p < 2; ++p) uu[p] = *(const u32x4*)(PROJ + tok * NPROJ + g * 64 + 32 * p + 8 * fq);
; #pragma unroll
;         for (int p = 0; p < 2; ++p) {
;             u32x4 w;
; #pragma unroll
;             for (int e2 = 0; e2 < 2; ++e2) {
;                 const f32x4 z = nv[p][e2] * acc[2 * p + e2][nt] + bs;
;                 const unsigned u0 = uu[p][2 * e2], u1 = uu[p][2 * e2 + 1];
;                 w[2 * e2] = pk2(bf_lo(u0) * z[0], bf_hi(u0) * z[1]); w[2 * e2 + 1] = pk2(bf_lo(u1) * z[2], bf_hi(u1) * z[3]);
;             }
;             *(u32x4*)(Y + tok * D + g * 64 + 32 * p + 8 * fq) = w;
	v_pk_fma_f32 v[148:149], v[148:149], v[2:3], v[206:207] op_sel_hi:[1,1,0]
	v_mfma_f32_16x16x32_bf16 v[56:59], v[36:39], v[186:189], v[154:157]
	v_fma_f32 v146, v146, v0, v206
	v_fma_f32 v147, v147, v1, v206
	s_nop 0
	v_lshlrev_b64 v[154:155], 11, v[198:199]
	v_mfma_f32_16x16x32_bf16 v[52:55], v[40:43], v[186:189], v[158:161]
	v_fma_f32 v156, v170, v32, v206
	v_fma_f32 v157, v171, v33, v206
	v_mov_b32_e32 v170, v156
	v_lshl_add_u64 v[158:159], v[84:85], 0, v[154:155]
	v_pk_fma_f32 v[154:155], v[172:173], v[34:35], v[206:207] op_sel_hi:[1,1,0]
	v_lshlrev_b32_e32 v161, 16, v195
	v_lshlrev_b32_e32 v160, 16, v194
	v_mov_b32_e32 v171, v154
	v_pk_mul_f32 v[160:161], v[170:171], v[160:161]
	v_and_b32_e32 v171, 0xffff0000, v195
	v_and_b32_e32 v170, 0xffff0000, v194
	v_mov_b32_e32 v154, v157
	v_pk_mul_f32 v[154:155], v[154:155], v[170:171]
	v_pk_fma_f32 v[156:157], v[176:177], v[26:27], v[206:207] op_sel_hi:[1,1,0]
	v_pk_fma_f32 v[170:171], v[174:175], v[24:25], v[206:207] op_sel_hi:[1,1,0]
	v_lshlrev_b32_e32 v173, 16, v197
	v_lshlrev_b32_e32 v172, 16, v196
	v_mov_b32_e32 v174, v170
	v_mov_b32_e32 v175, v156
	v_pk_mul_f32 v[172:173], v[174:175], v[172:173]
	v_and_b32_e32 v175, 0xffff0000, v197
	v_and_b32_e32 v174, 0xffff0000, v196
	v_mov_b32_e32 v156, v171
	v_pk_mul_f32 v[156:157], v[156:157], v[174:175]
	v_bfe_u32 v171, v155, 16, 1
	v_bfe_u32 v145, v157, 16, 1
	v_bfe_u32 v170, v156, 16, 1
	v_bfe_u32 v174, v154, 16, 1
	v_add3_u32 v154, v154, v174, s5
	v_add3_u32 v155, v155, v171, s5
	v_add3_u32 v156, v156, v170, s5
	v_add3_u32 v145, v157, v145, s5
	v_bfe_u32 v157, v160, 16, 1
	v_bfe_u32 v170, v161, 16, 1
	v_bfe_u32 v171, v172, 16, 1
	v_bfe_u32 v174, v173, 16, 1
	v_add3_u32 v173, v173, v174, s5
	v_add3_u32 v171, v172, v171, s5
	v_add3_u32 v161, v161, v170, s5
	v_add3_u32 v157, v160, v157, s5
	v_lshrrev_b32_e32 v160, 16, v157
	v_lshrrev_b32_e32 v161, 16, v161
	v_lshrrev_b32_e32 v170, 16, v171
	v_lshrrev_b32_e32 v157, 16, v173
	v_and_or_b32 v157, v145, s11, v157
	v_and_or_b32 v156, v156, s11, v170
	v_and_or_b32 v155, v155, s11, v161
	v_and_or_b32 v154, v154, s11, v160
	global_store_dwordx4 v[158:159], v[154:157], off
	v_lshlrev_b32_e32 v161, 16, v203
	v_lshlrev_b32_e32 v160, 16, v202
	v_pk_fma_f32 v[154:155], v[180:181], v[6:7], v[206:207] op_sel_hi:[1,1,0]
	v_pk_fma_f32 v[156:157], v[178:179], v[4:5], v[206:207] op_sel_hi:[1,1,0]
	v_mov_b32_e32 v171, v154
	v_mov_b32_e32 v170, v156
	v_pk_mul_f32 v[160:161], v[170:171], v[160:161]
	v_and_b32_e32 v171, 0xffff0000, v203
	v_and_b32_e32 v170, 0xffff0000, v202
	v_mov_b32_e32 v154, v157
	v_pk_mul_f32 v[154:155], v[154:155], v[170:171]
	v_lshlrev_b32_e32 v157, 16, v205
	v_lshlrev_b32_e32 v156, 16, v204
	v_mov_b32_e32 v170, v146
	v_mov_b32_e32 v171, v148
	v_pk_mul_f32 v[156:157], v[170:171], v[156:157]
	v_and_b32_e32 v171, 0xffff0000, v205
	v_and_b32_e32 v170, 0xffff0000, v204
	v_mov_b32_e32 v148, v147
	v_pk_mul_f32 v[146:147], v[148:149], v[170:171]
	v_bfe_u32 v149, v155, 16, 1
	v_bfe_u32 v145, v147, 16, 1
	v_bfe_u32 v148, v146, 16, 1
	v_bfe_u32 v170, v154, 16, 1
	v_add3_u32 v154, v154, v170, s5
	v_add3_u32 v155, v155, v149, s5
	v_add3_u32 v146, v146, v148, s5
	v_add3_u32 v145, v147, v145, s5
	v_bfe_u32 v147, v160, 16, 1
	v_bfe_u32 v148, v161, 16, 1
	v_bfe_u32 v149, v156, 16, 1
	v_bfe_u32 v170, v157, 16, 1
	v_add3_u32 v157, v157, v170, s5
	v_add3_u32 v149, v156, v149, s5
	v_add3_u32 v148, v161, v148, s5
	v_add3_u32 v147, v160, v147, s5
	v_lshrrev_b32_e32 v156, 16, v147
	v_lshrrev_b32_e32 v147, 16, v148
	v_lshrrev_b32_e32 v148, 16, v149
	v_lshrrev_b32_e32 v149, 16, v157
	v_and_or_b32 v149, v145, s11, v149
	v_and_or_b32 v148, v146, s11, v148
	v_and_or_b32 v147, v155, s11, v147
	v_and_or_b32 v146, v154, s11, v156
	global_store_dwordx4 v[158:159], v[146:149], off offset:64
	v_or_b32_e32 v170, s28, v136
	global_load_dword v172, v[120:121], off offset:320
	v_mad_i64_i32 v[158:159], s[30:31], v170, s4, v[82:83]
	global_load_dwordx4 v[146:149], v[158:159], off nt
	v_ashrrev_i32_e32 v171, 31, v170
	global_load_dwordx4 v[158:161], v[158:159], off offset:64 nt
	v_lshlrev_b64 v[170:171], 11, v[170:171]
	v_lshl_add_u64 v[170:171], v[84:85], 0, v[170:171]
	v_mfma_f32_16x16x32_bf16 v[36:39], v[36:39], v[28:31], v[48:51]
	s_waitcnt vmcnt(2)
	v_pk_fma_f32 v[174:175], v[184:185], v[34:35], v[172:173] op_sel_hi:[1,1,0]
	v_pk_fma_f32 v[176:177], v[182:183], v[32:33], v[172:173] op_sel_hi:[1,1,0]
	v_mov_b32_e32 v181, v174
	s_waitcnt vmcnt(1)
	v_lshlrev_b32_e32 v179, 16, v147
	v_lshlrev_b32_e32 v178, 16, v146
	v_and_b32_e32 v147, 0xffff0000, v147
	v_and_b32_e32 v146, 0xffff0000, v146
	v_mov_b32_e32 v174, v177
	v_pk_fma_f32 v[168:169], v[168:169], v[26:27], v[172:173] op_sel_hi:[1,1,0]
	v_pk_fma_f32 v[166:167], v[166:167], v[24:25], v[172:173] op_sel_hi:[1,1,0]
	v_pk_mul_f32 v[146:147], v[174:175], v[146:147]
	v_lshlrev_b32_e32 v175, 16, v149
	v_lshlrev_b32_e32 v174, 16, v148
	v_mov_b32_e32 v177, v168
	v_and_b32_e32 v149, 0xffff0000, v149
	v_and_b32_e32 v148, 0xffff0000, v148
	v_mov_b32_e32 v168, v167
	v_mov_b32_e32 v180, v176
	v_mov_b32_e32 v176, v166
	v_pk_mul_f32 v[148:149], v[168:169], v[148:149]
	v_pk_mul_f32 v[178:179], v[180:181], v[178:179]
	v_pk_mul_f32 v[174:175], v[176:177], v[174:175]
	v_bfe_u32 v145, v149, 16, 1
	v_bfe_u32 v166, v148, 16, 1
	v_bfe_u32 v167, v147, 16, 1
	v_bfe_u32 v168, v146, 16, 1
	v_add3_u32 v146, v146, v168, s5
	v_add3_u32 v147, v147, v167, s5
	v_add3_u32 v148, v148, v166, s5
	v_add3_u32 v145, v149, v145, s5
	v_bfe_u32 v149, v178, 16, 1
	v_bfe_u32 v166, v179, 16, 1
	v_bfe_u32 v167, v174, 16, 1
	v_bfe_u32 v168, v175, 16, 1
	v_add3_u32 v168, v175, v168, s5
	v_add3_u32 v167, v174, v167, s5
	v_add3_u32 v166, v179, v166, s5
	v_add3_u32 v149, v178, v149, s5
	v_lshrrev_b32_e32 v169, 16, v149
	v_lshrrev_b32_e32 v166, 16, v166
	v_lshrrev_b32_e32 v167, 16, v167
	v_lshrrev_b32_e32 v149, 16, v168
	v_and_or_b32 v149, v145, s11, v149
	v_and_or_b32 v148, v148, s11, v167
	v_and_or_b32 v147, v147, s11, v166
	v_and_or_b32 v146, v146, s11, v169
	global_store_dwordx4 v[170:171], v[146:149], off
	v_pk_fma_f32 v[62:63], v[62:63], v[2:3], v[172:173] op_sel_hi:[1,1,0]
	v_pk_fma_f32 v[60:61], v[60:61], v[0:1], v[172:173] op_sel_hi:[1,1,0]
	v_pk_fma_f32 v[146:147], v[152:153], v[6:7], v[172:173] op_sel_hi:[1,1,0]
	v_pk_fma_f32 v[148:149], v[150:151], v[4:5], v[172:173] op_sel_hi:[1,1,0]
	s_waitcnt vmcnt(1)
; __device__ __forceinline__ unsigned pk2(float lo, float hi) { return f2bf(lo) | (f2bf(hi) << 16); }
; template <int HF>
; __device__ __forceinline__ void gmlp_half(LAS unsigned char* wl, const bf16* PROJ, const bf16* wsg, const float* norm_v, const float* b_s, bf16* Y, int tok0, int g, int fr, int fq) {
;     ...
;     for (int nt = 0; nt < 4; ++nt) {
;         const int t = 64 * HF + 16 * nt + fr; const size_t tok = (size_t)(tok0 + t); const float bs = b_s[g * 128 + t];
;         u32x4 uu[2];
; #pragma unroll
;         for (int p = 0; p < 2; ++p) uu[p] = *(const u32x4*)(PROJ + tok * NPROJ + g * 64 + 32 * p + 8 * fq);
; #pragma unroll
;         for (int p = 0; p < 2; ++p) {
;             u32x4 w;
; #pragma unroll
;             for (int e2 = 0; e2 < 2; ++e2) {
;                 const f32x4 z = nv[p][e2] * acc[2 * p + e2][nt] + bs;
;                 const unsigned u0 = uu[p][2 * e2], u1 = uu[p][2 * e2 + 1];
;                 w[2 * e2] = pk2(bf_lo(u0) * z[0], bf_hi(u0) * z[1]); w[2 * e2 + 1] = pk2(bf_lo(u1) * z[2], bf_hi(u1) * z[3]);
;             }
;             *(u32x4*)(Y + tok * D + g * 64 + 32 * p + 8 * fq) = w;
	v_lshlrev_b32_e32 v151, 16, v159
	v_lshlrev_b32_e32 v150, 16, v158
	v_mov_b32_e32 v152, v148
	v_mov_b32_e32 v153, v146
	v_pk_mul_f32 v[150:151], v[152:153], v[150:151]
	v_and_b32_e32 v153, 0xffff0000, v159
	v_and_b32_e32 v152, 0xffff0000, v158
	v_mov_b32_e32 v146, v149
	v_pk_mul_f32 v[146:147], v[146:147], v[152:153]
	v_lshlrev_b32_e32 v149, 16, v161
	v_lshlrev_b32_e32 v148, 16, v160
	v_mov_b32_e32 v152, v60
	v_mov_b32_e32 v153, v62
	v_pk_mul_f32 v[148:149], v[152:153], v[148:149]
	v_and_b32_e32 v153, 0xffff0000, v161
	v_and_b32_e32 v152, 0xffff0000, v160
	v_mov_b32_e32 v62, v61
	v_pk_mul_f32 v[60:61], v[62:63], v[152:153]
	v_bfe_u32 v145, v147, 16, 1
	v_bfe_u32 v62, v61, 16, 1
	v_bfe_u32 v63, v60, 16, 1
	v_bfe_u32 v152, v146, 16, 1
	v_add3_u32 v146, v146, v152, s5
	v_add3_u32 v145, v147, v145, s5
	v_add3_u32 v60, v60, v63, s5
	v_add3_u32 v61, v61, v62, s5
	v_bfe_u32 v62, v150, 16, 1
	v_bfe_u32 v63, v151, 16, 1
	v_bfe_u32 v147, v148, 16, 1
	v_bfe_u32 v152, v149, 16, 1
	v_add3_u32 v149, v149, v152, s5
	v_add3_u32 v147, v148, v147, s5
	v_add3_u32 v63, v151, v63, s5
	v_add3_u32 v62, v150, v62, s5
	v_lshrrev_b32_e32 v148, 16, v62
	v_lshrrev_b32_e32 v150, 16, v63
	v_lshrrev_b32_e32 v62, 16, v147
	v_lshrrev_b32_e32 v63, 16, v149
	v_and_or_b32 v63, v61, s11, v63
	v_and_or_b32 v62, v60, s11, v62
	v_and_or_b32 v61, v145, s11, v150
	v_and_or_b32 v60, v146, s11, v148
	global_store_dwordx4 v[170:171], v[60:63], off offset:64
	v_or_b32_e32 v146, s28, v137
	global_load_dword v148, v[120:121], off offset:384
	v_mad_i64_i32 v[150:151], s[28:29], v146, s4, v[82:83]
	global_load_dwordx4 v[60:63], v[150:151], off nt
	global_load_dwordx4 v[48:51], v[150:151], off offset:64 nt
	v_ashrrev_i32_e32 v147, 31, v146
	v_mfma_f32_16x16x32_bf16 v[40:43], v[40:43], v[28:31], v[44:47]
	s_waitcnt vmcnt(2)
	v_pk_fma_f32 v[52:53], v[52:53], v[24:25], v[148:149] op_sel_hi:[1,1,0]
	s_nop 0
	v_lshlrev_b64 v[44:45], 11, v[146:147]
	v_lshl_add_u64 v[146:147], v[84:85], 0, v[44:45]
	v_pk_fma_f32 v[44:45], v[58:59], v[34:35], v[148:149] op_sel_hi:[1,1,0]
	v_pk_fma_f32 v[46:47], v[56:57], v[32:33], v[148:149] op_sel_hi:[1,1,0]
	s_waitcnt vmcnt(1)
	v_lshlrev_b32_e32 v57, 16, v61
	v_lshlrev_b32_e32 v56, 16, v60
	v_mov_b32_e32 v58, v46
	v_mov_b32_e32 v59, v44
	v_pk_mul_f32 v[56:57], v[58:59], v[56:57]
	v_and_b32_e32 v59, 0xffff0000, v61
	v_and_b32_e32 v58, 0xffff0000, v60
	v_mov_b32_e32 v44, v47
	v_pk_fma_f32 v[46:47], v[54:55], v[26:27], v[148:149] op_sel_hi:[1,1,0]
	v_pk_mul_f32 v[44:45], v[44:45], v[58:59]
	v_lshlrev_b32_e32 v55, 16, v63
	v_lshlrev_b32_e32 v54, 16, v62
	v_mov_b32_e32 v58, v52
	v_mov_b32_e32 v59, v46
	v_pk_mul_f32 v[54:55], v[58:59], v[54:55]
	v_and_b32_e32 v59, 0xffff0000, v63
	v_and_b32_e32 v58, 0xffff0000, v62
	v_mov_b32_e32 v46, v53
	v_pk_mul_f32 v[46:47], v[46:47], v[58:59]
	v_bfe_u32 v58, v45, 16, 1
	v_bfe_u32 v52, v47, 16, 1
	v_bfe_u32 v53, v46, 16, 1
	v_bfe_u32 v59, v44, 16, 1
	v_mfma_f32_16x16x32_bf16 v[154:157], v[8:11], v[186:189], v[162:165]
	v_add3_u32 v44, v44, v59, s5
	v_add3_u32 v45, v45, v58, s5
	v_add3_u32 v46, v46, v53, s5
	v_add3_u32 v47, v47, v52, s5
	v_bfe_u32 v52, v56, 16, 1
	v_bfe_u32 v53, v57, 16, 1
	v_bfe_u32 v58, v54, 16, 1
	v_bfe_u32 v59, v55, 16, 1
	v_add3_u32 v55, v55, v59, s5
	v_add3_u32 v54, v54, v58, s5
	v_add3_u32 v53, v57, v53, s5
	v_add3_u32 v52, v56, v52, s5
	v_mfma_f32_16x16x32_bf16 v[162:165], v[12:15], v[186:189], v[190:193]
	v_lshrrev_b32_e32 v52, 16, v52
	v_lshrrev_b32_e32 v53, 16, v53
	v_lshrrev_b32_e32 v54, 16, v54
	v_lshrrev_b32_e32 v55, 16, v55
	v_and_or_b32 v47, v47, s11, v55
	v_and_or_b32 v46, v46, s11, v54
	v_and_or_b32 v45, v45, s11, v53
	v_and_or_b32 v44, v44, s11, v52
	global_store_dwordx4 v[146:147], v[44:47], off
	s_waitcnt vmcnt(1)
	v_lshlrev_b32_e32 v53, 16, v49
	v_lshlrev_b32_e32 v52, 16, v48
	v_pk_fma_f32 v[44:45], v[156:157], v[6:7], v[148:149] op_sel_hi:[1,1,0]
	v_pk_fma_f32 v[46:47], v[154:155], v[4:5], v[148:149] op_sel_hi:[1,1,0]
	v_mov_b32_e32 v55, v44
	v_and_b32_e32 v49, 0xffff0000, v49
	v_and_b32_e32 v48, 0xffff0000, v48
	v_mov_b32_e32 v44, v47
	v_mov_b32_e32 v54, v46
	v_pk_mul_f32 v[44:45], v[44:45], v[48:49]
	v_pk_fma_f32 v[46:47], v[164:165], v[2:3], v[148:149] op_sel_hi:[1,1,0]
	v_pk_fma_f32 v[48:49], v[162:163], v[0:1], v[148:149] op_sel_hi:[1,1,0]
	v_pk_mul_f32 v[52:53], v[54:55], v[52:53]
	v_lshlrev_b32_e32 v55, 16, v51
	v_lshlrev_b32_e32 v54, 16, v50
	v_mov_b32_e32 v57, v46
	v_and_b32_e32 v51, 0xffff0000, v51
	v_and_b32_e32 v50, 0xffff0000, v50
	v_mov_b32_e32 v46, v49
	v_mov_b32_e32 v56, v48
	v_pk_mul_f32 v[46:47], v[46:47], v[50:51]
	v_pk_mul_f32 v[54:55], v[56:57], v[54:55]
	v_bfe_u32 v48, v47, 16, 1
	v_bfe_u32 v49, v46, 16, 1
	v_bfe_u32 v50, v45, 16, 1
	v_bfe_u32 v51, v44, 16, 1
	v_add3_u32 v44, v44, v51, s5
	v_add3_u32 v45, v45, v50, s5
	v_add3_u32 v46, v46, v49, s5
	v_add3_u32 v47, v47, v48, s5
	v_bfe_u32 v48, v52, 16, 1
	v_bfe_u32 v49, v53, 16, 1
	v_bfe_u32 v50, v54, 16, 1
	v_bfe_u32 v51, v55, 16, 1
	v_add3_u32 v51, v55, v51, s5
	v_add3_u32 v50, v54, v50, s5
	v_add3_u32 v49, v53, v49, s5
	v_add3_u32 v48, v52, v48, s5
	v_lshrrev_b32_e32 v48, 16, v48
	v_lshrrev_b32_e32 v49, 16, v49
	v_lshrrev_b32_e32 v50, 16, v50
	v_lshrrev_b32_e32 v51, 16, v51
	v_and_or_b32 v47, v47, s11, v51
	v_and_or_b32 v46, v46, s11, v50
	v_and_or_b32 v45, v45, s11, v49
	v_and_or_b32 v44, v44, s11, v48
	global_store_dwordx4 v[146:147], v[44:47], off offset:64
	v_or_b32_e32 v48, s21, v138
	global_load_dword v50, v[124:125], off
	v_mad_i64_i32 v[52:53], s[28:29], v48, s4, v[82:83]
	global_load_dwordx4 v[44:47], v[52:53], off nt
	v_mfma_f32_16x16x32_bf16 v[8:11], v[8:11], v[28:31], v[16:19]
	v_ashrrev_i32_e32 v49, 31, v48
	s_waitcnt vmcnt(1)
; #define LAS __attribute__((address_space(3)))
; __device__ __forceinline__ unsigned pk2(float lo, float hi) { return f2bf(lo) | (f2bf(hi) << 16); }
; template <int HF>
; __device__ __forceinline__ void gmlp_half(LAS unsigned char* wl, const bf16* PROJ, const bf16* wsg, const float* norm_v, const float* b_s, bf16* Y, int tok0, int g, int fr, int fq) {
;     ...
;     for (int nt = 0; nt < 4; ++nt) {
;         const int t = 64 * HF + 16 * nt + fr; const size_t tok = (size_t)(tok0 + t); const float bs = b_s[g * 128 + t];
;         u32x4 uu[2];
; #pragma unroll
;         for (int p = 0; p < 2; ++p) uu[p] = *(const u32x4*)(PROJ + tok * NPROJ + g * 64 + 32 * p + 8 * fq);
; #pragma unroll
;         for (int p = 0; p < 2; ++p) {
;             u32x4 w;
; #pragma unroll
;             for (int e2 = 0; e2 < 2; ++e2) {
;                 const f32x4 z = nv[p][e2] * acc[2 * p + e2][nt] + bs;
;                 const unsigned u0 = uu[p][2 * e2], u1 = uu[p][2 * e2 + 1];
;                 w[2 * e2] = pk2(bf_lo(u0) * z[0], bf_hi(u0) * z[1]); w[2 * e2 + 1] = pk2(bf_lo(u1) * z[2], bf_hi(u1) * z[3]);
;             }
;             *(u32x4*)(Y + tok * D + g * 64 + 32 * p + 8 * fq) = w;
; __device__ __forceinline__ void gla_upd_unit(LAS unsigned char* wl, const bf16* PROJ, const float* R, const float* w_gk2, const float* b_gk, float* UPD, float* DEC, int unit, int lane) {
;     constexpr int KS = 72;
;     LAS unsigned* KD32 = (LAS unsigned*)wl; LAS unsigned* VB32 = (LAS unsigned*)(wl + 9216);
;     const int h = unit & 3, tok0 = (unit >> 2) * 64, kk = lane;
;     { const f32x4* rp = (const f32x4*)(R + (size_t)(tok0 + lane) * 16); LAS f32x4* rl = (LAS f32x4*)(wl + 9216) + lane * 4;
;       const f32x4 r0 = rp[0], r1 = rp[1], r2 = rp[2], r3 = rp[3]; rl[0] = r0; rl[1] = r1; rl[2] = r2; rl[3] = r3; }
;     const bf16* kp = PROJ + (size_t)tok0 * NPROJ + 1280 + h * 64 + kk;
;     unsigned short kv0[32], kv1[32];
; #pragma unroll
;     for (int t = 0; t < 32; ++t) kv0[t] = kp[(size_t)t * NPROJ];
;     float w[16];
; #pragma unroll
;     for (int j = 0; j < 16; ++j) w[j] = w_gk2[j * 256 + h * 64 + kk];
;     const float bias = b_gk[h * 64 + kk];
	v_pk_fma_f32 v[24:25], v[40:41], v[24:25], v[50:51] op_sel_hi:[1,1,0]
	global_load_dwordx4 v[16:19], v[52:53], off offset:64 nt
	v_mfma_f32_16x16x32_bf16 v[12:15], v[12:15], v[28:31], v[20:23]
	s_nop 2
	v_fma_f32 v6, v10, v6, v50
	v_fma_f32 v7, v11, v7, v50
	v_pk_fma_f32 v[4:5], v[8:9], v[4:5], v[50:51] op_sel_hi:[1,1,0]
	s_waitcnt vmcnt(1)
	v_lshlrev_b32_e32 v31, 16, v45
	v_lshlrev_b64 v[20:21], 11, v[48:49]
	v_lshl_add_u64 v[28:29], v[84:85], 0, v[20:21]
	v_pk_fma_f32 v[20:21], v[38:39], v[34:35], v[50:51] op_sel_hi:[1,1,0]
	v_pk_fma_f32 v[22:23], v[36:37], v[32:33], v[50:51] op_sel_hi:[1,1,0]
	v_lshlrev_b32_e32 v30, 16, v44
	v_mov_b32_e32 v32, v22
	v_mov_b32_e32 v33, v20
	v_mov_b32_e32 v10, v4
	v_mov_b32_e32 v11, v6
	v_pk_mul_f32 v[30:31], v[32:33], v[30:31]
	v_and_b32_e32 v33, 0xffff0000, v45
	v_and_b32_e32 v32, 0xffff0000, v44
	v_mov_b32_e32 v20, v23
	v_pk_fma_f32 v[22:23], v[42:43], v[26:27], v[50:51] op_sel_hi:[1,1,0]
	v_mov_b32_e32 v6, v5
	v_pk_fma_f32 v[2:3], v[14:15], v[2:3], v[50:51] op_sel_hi:[1,1,0]
	v_pk_fma_f32 v[0:1], v[12:13], v[0:1], v[50:51] op_sel_hi:[1,1,0]
	v_pk_mul_f32 v[20:21], v[20:21], v[32:33]
	v_lshlrev_b32_e32 v27, 16, v47
	v_lshlrev_b32_e32 v26, 16, v46
	v_mov_b32_e32 v32, v24
	v_mov_b32_e32 v33, v22
	v_pk_mul_f32 v[26:27], v[32:33], v[26:27]
	v_and_b32_e32 v33, 0xffff0000, v47
	v_and_b32_e32 v32, 0xffff0000, v46
	v_mov_b32_e32 v22, v25
	v_pk_mul_f32 v[22:23], v[22:23], v[32:33]
	v_bfe_u32 v32, v21, 16, 1
	v_bfe_u32 v24, v23, 16, 1
	v_bfe_u32 v25, v22, 16, 1
	v_bfe_u32 v33, v20, 16, 1
	v_add3_u32 v20, v20, v33, s5
	v_add3_u32 v21, v21, v32, s5
	v_add3_u32 v22, v22, v25, s5
	v_add3_u32 v23, v23, v24, s5
	v_bfe_u32 v24, v30, 16, 1
	v_bfe_u32 v25, v31, 16, 1
	v_bfe_u32 v32, v26, 16, 1
	v_bfe_u32 v33, v27, 16, 1
	v_add3_u32 v27, v27, v33, s5
	v_add3_u32 v26, v26, v32, s5
	v_add3_u32 v25, v31, v25, s5
	v_add3_u32 v24, v30, v24, s5
	v_lshrrev_b32_e32 v24, 16, v24
	v_lshrrev_b32_e32 v25, 16, v25
	v_lshrrev_b32_e32 v26, 16, v26
	v_lshrrev_b32_e32 v27, 16, v27
	v_and_or_b32 v23, v23, s11, v27
	v_and_or_b32 v22, v22, s11, v26
	v_and_or_b32 v21, v21, s11, v25
	v_and_or_b32 v20, v20, s11, v24
	global_store_dwordx4 v[28:29], v[20:23], off
	s_waitcnt vmcnt(1)
	v_lshlrev_b32_e32 v9, 16, v17
	v_lshlrev_b32_e32 v8, 16, v16
	v_pk_mul_f32 v[8:9], v[10:11], v[8:9]
	v_and_b32_e32 v11, 0xffff0000, v17
	v_and_b32_e32 v10, 0xffff0000, v16
	v_pk_mul_f32 v[4:5], v[6:7], v[10:11]
	v_lshlrev_b32_e32 v7, 16, v19
	v_lshlrev_b32_e32 v6, 16, v18
	v_mov_b32_e32 v10, v0
	v_mov_b32_e32 v11, v2
	v_pk_mul_f32 v[6:7], v[10:11], v[6:7]
	v_and_b32_e32 v11, 0xffff0000, v19
	v_and_b32_e32 v10, 0xffff0000, v18
	v_mov_b32_e32 v2, v1
	v_pk_mul_f32 v[0:1], v[2:3], v[10:11]
	v_bfe_u32 v10, v5, 16, 1
	v_bfe_u32 v2, v1, 16, 1
	v_bfe_u32 v3, v0, 16, 1
	v_bfe_u32 v11, v4, 16, 1
	v_add3_u32 v4, v4, v11, s5
	v_add3_u32 v5, v5, v10, s5
	v_add3_u32 v0, v0, v3, s5
	v_add3_u32 v1, v1, v2, s5
	v_bfe_u32 v2, v8, 16, 1
	v_bfe_u32 v3, v9, 16, 1
	v_bfe_u32 v10, v6, 16, 1
	v_bfe_u32 v11, v7, 16, 1
	v_add3_u32 v7, v7, v11, s5
	v_add3_u32 v6, v6, v10, s5
	v_add3_u32 v3, v9, v3, s5
	v_add3_u32 v2, v8, v2, s5
	v_lshrrev_b32_e32 v8, 16, v2
	v_lshrrev_b32_e32 v9, 16, v3
	v_lshrrev_b32_e32 v2, 16, v6
	v_lshrrev_b32_e32 v3, 16, v7
	v_and_or_b32 v3, v1, s11, v3
	v_and_or_b32 v2, v0, s11, v2
	v_and_or_b32 v1, v5, s11, v9
	v_and_or_b32 v0, v4, s11, v8
	global_store_dwordx4 v[28:29], v[0:3], off offset:64
	s_waitcnt lgkmcnt(0)
	s_cbranch_scc0 .LBB0_417
	v_readlane_b32 s0, v230, 10
	v_lshlrev_b32_e32 v0, 2, v200
	v_mov_b32_e32 v1, 0
	v_readlane_b32 s1, v230, 11
	v_and_b32_e32 v2, 12, v130
	v_readlane_b32 s2, v230, 8
	v_lshl_add_u64 v[24:25], s[0:1], 0, v[0:1]
	s_movk_i32 s0, 0x90
	v_mov_b32_e32 v6, s37
	v_lshlrev_b32_e32 v2, 2, v2
	v_mov_b32_e32 v3, v1
	v_readlane_b32 s3, v230, 9
	v_mad_u32_u24 v6, v64, s0, v6
	v_readlane_b32 s0, v230, 4
	v_lshl_add_u64 v[2:3], s[2:3], 0, v[2:3]
	s_bfe_u32 s2, s0, 0x20006
	s_lshl_b32 s3, s2, 8
	v_or_b32_e32 v0, s3, v0
	v_lshl_add_u64 v[28:29], s[14:15], 0, v[0:1]
	s_mov_b64 s[0:1], 0x1000
	v_lshl_add_u64 v[30:31], v[28:29], 0, s[0:1]
	s_mov_b64 s[0:1], 0x1400
	v_lshl_add_u64 v[32:33], v[28:29], 0, s[0:1]
	s_mov_b64 s[0:1], 0x1800
	v_lshl_add_u64 v[34:35], v[28:29], 0, s[0:1]
	s_mov_b64 s[0:1], 0x1c00
	v_lshl_add_u64 v[36:37], v[28:29], 0, s[0:1]
	s_mov_b64 s[0:1], 0x2000
	v_lshl_add_u64 v[38:39], v[28:29], 0, s[0:1]
	s_mov_b64 s[0:1], 0x2400
	v_lshl_add_u64 v[40:41], v[28:29], 0, s[0:1]
	s_mov_b64 s[0:1], 0x2800
	v_lshl_add_u64 v[42:43], v[28:29], 0, s[0:1]
	s_mov_b64 s[0:1], 0x2c00
	v_lshl_add_u64 v[44:45], v[28:29], 0, s[0:1]
	s_mov_b64 s[0:1], 0x3000
	v_lshl_add_u64 v[46:47], v[28:29], 0, s[0:1]
	s_mov_b64 s[0:1], 0x3400
	v_lshl_add_u64 v[48:49], v[28:29], 0, s[0:1]
	s_mov_b64 s[0:1], 0x3800
	v_lshl_add_u64 v[50:51], v[28:29], 0, s[0:1]
	s_mov_b64 s[0:1], 0x3c00
	v_lshl_add_u64 v[52:53], v[28:29], 0, s[0:1]
	s_lshl_b32 s0, s2, 7
	s_add_u32 s0, s24, s0
	v_lshl_add_u64 v[54:55], s[16:17], 0, v[0:1]
	s_addc_u32 s1, s25, 0
	v_lshlrev_b32_e32 v0, 1, v200
	v_or_b32_e32 v78, 16, v128
	v_or_b32_e32 v79, 32, v128
	v_or_b32_e32 v80, 48, v128
	v_lshl_add_u64 v[56:57], s[0:1], 0, v[0:1]
	s_add_u32 s0, s24, s3
	v_lshlrev_b32_e32 v4, 6, v200
	v_mul_u32_u24_e32 v5, 0x90, v200
	v_lshl_add_u32 v81, v67, 2, v6
	v_lshl_add_u32 v82, v78, 1, v6
	v_lshl_add_u32 v83, v79, 1, v6
	v_lshl_add_u32 v84, v80, 1, v6
	v_mul_u32_u24_e32 v6, 0x90, v129
	v_mul_u32_u24_e32 v7, 0x90, v131
	v_mov_b32_e32 v67, v1
	s_addc_u32 s1, s25, 0
	v_lshlrev_b32_e32 v0, 1, v64
	v_lshl_add_u64 v[26:27], v[2:3], 0, v[66:67]
	v_lshl_add_u64 v[58:59], s[0:1], 0, v[0:1]
	v_add_u32_e32 v85, s37, v4
	s_movk_i32 s39, 0x1600
	s_mov_b32 s68, 0xbfb8aa3b
	s_mov_b32 s69, 0x800000
	s_mov_b32 s70, 0x3f317217
	s_mov_b32 s71, 0x7f800000
	s_movk_i32 s72, 0x7fff
	s_mov_b32 s73, 0xffff0000
	v_add_u32_e32 v86, s37, v5
	s_mov_b32 s74, 0x3a000
	s_mov_b32 s75, 0x39000
	s_mov_b32 s76, 0x3b000
	s_mov_b32 s77, 0x3d000
	s_mov_b32 s78, 0x3f000
	s_mov_b32 s79, 0x3e000
	s_mov_b32 s80, 0x41000
	s_mov_b32 s81, 0x42000
	s_mov_b32 s82, 0x45000
	s_mov_b32 s83, 0x44000
	s_mov_b32 s84, 0x46000
	s_mov_b32 s85, 0x48000
	s_mov_b32 s86, 0x4a000
	s_mov_b32 s87, 0x49000
	s_mov_b32 s88, 0x4c000
	s_mov_b32 s89, 0x4d000
	s_mov_b32 s90, 0x50000
	s_mov_b32 s91, 0x4f000
	s_mov_b32 s20, 0x51000
	s_mov_b32 s21, 0x53000
	s_mov_b32 s28, 0x55000
	v_add_u32_e32 v87, v65, v6
	v_add_u32_e32 v88, v65, v7
	v_mov_b32_e32 v89, 0x1600
	v_mov_b32_e32 v90, 0x41b17218
	v_mov_b32_e32 v91, 1
	s_mov_b32 s29, 0x54000
	s_mov_b32 s30, 0x57000
	s_mov_b32 s63, 0
	s_mov_b32 s64, s38
; #define LAS __attribute__((address_space(3)))
; __device__ __forceinline__ void gla_upd_unit(LAS unsigned char* wl, const bf16* PROJ, const float* R, const float* w_gk2, const float* b_gk, float* UPD, float* DEC, int unit, int lane) {
;     ...
;     const int h = unit & 3, tok0 = (unit >> 2) * 64, kk = lane;
;     { const f32x4* rp = (const f32x4*)(R + (size_t)(tok0 + lane) * 16); LAS f32x4* rl = (LAS f32x4*)(wl + 9216) + lane * 4;
;       const f32x4 r0 = rp[0], r1 = rp[1], r2 = rp[2], r3 = rp[3]; rl[0] = r0; rl[1] = r1; rl[2] = r2; rl[3] = r3; }
;     const bf16* kp = PROJ + (size_t)tok0 * NPROJ + 1280 + h * 64 + kk;
;     unsigned short kv0[32], kv1[32];
; #pragma unroll
;     for (int t = 0; t < 32; ++t) kv0[t] = kp[(size_t)t * NPROJ];
;     float w[16];
; #pragma unroll
;     for (int j = 0; j < 16; ++j) w[j] = w_gk2[j * 256 + h * 64 + kk];
;     const float bias = b_gk[h * 64 + kk];
.LBB0_421:
	s_lshl_b32 s2, s64, 4
	s_and_b32 s3, s2, 0xffffffc0
	v_or_b32_e32 v0, s3, v200
	v_ashrrev_i32_e32 v1, 31, v0
	v_lshlrev_b64 v[0:1], 6, v[0:1]
	v_lshl_add_u64 v[12:13], s[46:47], 0, v[0:1]
	global_load_dwordx4 v[0:3], v[12:13], off offset:48 nt
	global_load_dwordx4 v[4:7], v[12:13], off offset:32 nt
	global_load_dwordx4 v[8:11], v[12:13], off offset:16 nt
	s_nop 0
	global_load_dwordx4 v[12:15], v[12:13], off nt
	s_ashr_i32 s65, s64, 31
	s_mov_b64 s[66:67], -1
	s_waitcnt vmcnt(0)
	ds_write_b128 v85, v[12:15] offset:9216
	ds_write_b128 v85, v[8:11] offset:9232
	ds_write_b128 v85, v[4:7] offset:9248
	ds_write_b128 v85, v[0:3] offset:9264
	global_load_dword v14, v[28:29], off
	global_load_dword v16, v[28:29], off offset:1024
	global_load_dword v12, v[28:29], off offset:2048
	global_load_dword v10, v[28:29], off offset:3072
	global_load_dword v15, v[30:31], off
	global_load_dword v17, v[32:33], off
	global_load_dword v13, v[34:35], off
	global_load_dword v11, v[36:37], off
	global_load_dword v6, v[38:39], off
	global_load_dword v8, v[40:41], off
	global_load_dword v2, v[42:43], off
	global_load_dword v0, v[44:45], off
	global_load_dword v7, v[46:47], off
	global_load_dword v9, v[48:49], off
	global_load_dword v3, v[50:51], off
	global_load_dword v1, v[52:53], off
	global_load_dword v100, v[54:55], off
	v_mad_i64_i32 v[4:5], s[0:1], s3, v89, v[56:57]
	s_movk_i32 s0, 0x3000
	s_nop 0
	v_add_co_u32_e32 v18, vcc, s0, v4
	s_movk_i32 s0, 0x2000
	s_nop 0
	v_addc_co_u32_e32 v19, vcc, 0, v5, vcc
	global_load_ushort v92, v[18:19], off offset:1536 nt
	global_load_ushort v93, v[4:5], off offset:2560 nt
	v_add_co_u32_e32 v18, vcc, s0, v4
	s_movk_i32 s0, 0x4000
	s_nop 0
	v_addc_co_u32_e32 v19, vcc, 0, v5, vcc
	global_load_ushort v95, v[18:19], off nt
	v_add_co_u32_e32 v18, vcc, s0, v4
	s_movk_i32 s0, 0x6000
	s_nop 0
	v_addc_co_u32_e32 v19, vcc, 0, v5, vcc
	global_load_ushort v97, v[18:19], off offset:3072 nt
	v_add_co_u32_e32 v18, vcc, s0, v4
	s_mov_b32 s0, 0x8000
	s_nop 0
	v_addc_co_u32_e32 v19, vcc, 0, v5, vcc
	global_load_ushort v94, v[18:19], off offset:512 nt
	v_add_co_u32_e32 v18, vcc, s0, v4
	s_movk_i32 s0, 0x7000
	s_nop 0
	v_addc_co_u32_e32 v19, vcc, 0, v5, vcc
	global_load_ushort v96, v[18:19], off offset:3584 nt
	v_add_co_u32_e32 v18, vcc, s0, v4
	s_mov_b32 s0, 0xa000
	s_nop 0
	v_addc_co_u32_e32 v19, vcc, 0, v5, vcc
	global_load_ushort v98, v[18:19], off offset:2048 nt
	v_add_co_u32_e32 v18, vcc, s0, v4
	s_mov_b32 s0, 0xb000
	s_nop 0
	v_addc_co_u32_e32 v19, vcc, 0, v5, vcc
	global_load_ushort v99, v[18:19], off offset:1024 nt
	v_add_co_u32_e32 v18, vcc, s0, v4
	s_mov_b32 s0, 0xe000
	s_nop 0
	v_addc_co_u32_e32 v19, vcc, 0, v5, vcc
	v_add_co_u32_e32 v20, vcc, s0, v4
	s_mov_b32 s0, 0xd000
	s_nop 0
	v_addc_co_u32_e32 v21, vcc, 0, v5, vcc
	global_load_ushort v18, v[18:19], off offset:2560 nt
	s_waitcnt vmcnt(0)
	v_lshlrev_b32_e32 v18, 16, v18
	global_load_ushort v19, v[20:21], off offset:1536 nt
	v_add_co_u32_e32 v20, vcc, s0, v4
	s_mov_b32 s0, 0xf000
	s_nop 0
	v_addc_co_u32_e32 v21, vcc, 0, v5, vcc
	v_add_co_u32_e32 v22, vcc, s0, v4
	s_mov_b32 s0, 0x11000
	s_nop 0
	v_addc_co_u32_e32 v23, vcc, 0, v5, vcc
	global_load_ushort v20, v[20:21], off nt
	s_waitcnt vmcnt(1)
	v_lshlrev_b32_e32 v19, 16, v19
	global_load_ushort v21, v[22:23], off offset:3072 nt
	v_add_co_u32_e32 v22, vcc, s0, v4
	s_mov_b32 s0, 0x13000
	s_nop 0
	v_addc_co_u32_e32 v23, vcc, 0, v5, vcc
	v_add_co_u32_e32 v60, vcc, s0, v4
	s_mov_b32 s0, 0x12000
	s_nop 0
	v_addc_co_u32_e32 v61, vcc, 0, v5, vcc
	v_add_co_u32_e32 v62, vcc, s0, v4
	s_mov_b32 s0, 0x15000
	s_nop 0
	v_addc_co_u32_e32 v63, vcc, 0, v5, vcc
	global_load_ushort v22, v[22:23], off offset:512 nt
	s_nop 0
	global_load_ushort v60, v[60:61], off offset:3584 nt
	s_nop 0
	global_load_ushort v61, v[62:63], off offset:2048 nt
	v_add_co_u32_e32 v62, vcc, s0, v4
	s_mov_b32 s0, 0x16000
	s_nop 0
	v_addc_co_u32_e32 v63, vcc, 0, v5, vcc
	global_load_ushort v75, v[62:63], off offset:1024 nt
	v_add_co_u32_e32 v62, vcc, s0, v4
	s_mov_b32 s0, 0x19000
	s_nop 0
	v_addc_co_u32_e32 v63, vcc, 0, v5, vcc
	v_add_co_u32_e32 v64, vcc, s0, v4
	s_mov_b32 s0, 0x18000
	s_nop 0
	v_addc_co_u32_e32 v65, vcc, 0, v5, vcc
	global_load_ushort v67, v[64:65], off offset:1536 nt
	v_add_co_u32_e32 v64, vcc, s0, v4
	s_mov_b32 s0, 0x1a000
	s_nop 0
	v_addc_co_u32_e32 v65, vcc, 0, v5, vcc
	global_load_ushort v62, v[62:63], off offset:2560 nt
	s_nop 0
	global_load_ushort v68, v[64:65], off nt
	v_add_co_u32_e32 v64, vcc, s0, v4
	s_mov_b32 s0, 0x1c000
	s_nop 0
	v_addc_co_u32_e32 v65, vcc, 0, v5, vcc
	global_load_ushort v73, v[64:65], off offset:3072 nt
	v_add_co_u32_e32 v64, vcc, s0, v4
	s_mov_b32 s0, 0x1e000
	s_nop 0
	v_addc_co_u32_e32 v65, vcc, 0, v5, vcc
	global_load_ushort v23, v[64:65], off offset:512 nt
	v_add_co_u32_e32 v64, vcc, s0, v4
	s_mov_b32 s0, 0x1d000
	s_nop 0
	v_addc_co_u32_e32 v65, vcc, 0, v5, vcc
	v_add_co_u32_e32 v70, vcc, s0, v4
	s_mov_b32 s0, 0x20000
	s_nop 0
	v_addc_co_u32_e32 v71, vcc, 0, v5, vcc
	global_load_ushort v64, v[64:65], off offset:3584 nt
	s_nop 0
	global_load_ushort v65, v[70:71], off offset:2048 nt
	v_add_co_u32_e32 v70, vcc, s0, v4
	s_mov_b32 s0, 0x21000
	s_nop 0
	v_addc_co_u32_e32 v71, vcc, 0, v5, vcc
	global_load_ushort v76, v[70:71], off offset:1024 nt
	v_add_co_u32_e32 v70, vcc, s0, v4
	s_mov_b32 s0, 0x24000
	s_nop 0
	v_addc_co_u32_e32 v71, vcc, 0, v5, vcc
	global_load_ushort v66, v[70:71], off offset:2560 nt
	v_add_co_u32_e32 v70, vcc, s0, v4
	s_mov_b32 s0, 0x23000
	s_nop 0
	v_addc_co_u32_e32 v71, vcc, 0, v5, vcc
	v_add_co_u32_e32 v102, vcc, s0, v4
	s_mov_b32 s0, 0x25000
	s_nop 0
	v_addc_co_u32_e32 v103, vcc, 0, v5, vcc
	global_load_ushort v71, v[70:71], off offset:1536 nt
	s_nop 0
	global_load_ushort v72, v[102:103], off nt
	v_add_co_u32_e32 v102, vcc, s0, v4
	s_mov_b32 s0, 0x27000
	s_nop 0
	v_addc_co_u32_e32 v103, vcc, 0, v5, vcc
	global_load_ushort v74, v[102:103], off offset:3072 nt
	v_add_co_u32_e32 v102, vcc, s0, v4
	s_mov_b32 s0, 0x29000
	s_nop 0
	v_addc_co_u32_e32 v103, vcc, 0, v5, vcc
	global_load_ushort v63, v[102:103], off offset:512 nt
	v_add_co_u32_e32 v102, vcc, s0, v4
	s_mov_b32 s0, 0x28000
	s_nop 0
	v_addc_co_u32_e32 v103, vcc, 0, v5, vcc
	global_load_ushort v69, v[102:103], off offset:3584 nt
	v_add_co_u32_e32 v102, vcc, s0, v4
	s_mov_b32 s0, 0x2b000
	s_nop 0
	v_addc_co_u32_e32 v103, vcc, 0, v5, vcc
	global_load_ushort v70, v[102:103], off offset:2048 nt
	v_add_co_u32_e32 v102, vcc, s0, v4
	s_nop 1
	v_addc_co_u32_e32 v103, vcc, 0, v5, vcc
	global_load_ushort v77, v[102:103], off offset:1024 nt
	s_waitcnt lgkmcnt(0)
; #define LAS __attribute__((address_space(3)))
; __device__ __forceinline__ void gla_upd_unit(LAS unsigned char* wl, const bf16* PROJ, const float* R, const float* w_gk2, const float* b_gk, float* UPD, float* DEC, int unit, int lane) {
;     ...
;     float la[64]; float tot = 0.f;
; #pragma unroll
;     for (int t = 0; t < 64; ++t) {
;         const LAS f32x4* rr = (const LAS f32x4*)(wl + 9216) + t * 4;
;         float z = bias;
; #pragma unroll
;         for (int q = 0; q < 4; ++q) { const f32x4 rv = rr[q]; z += rv[0] * w[4 * q] + rv[1] * w[4 * q + 1] + rv[2] * w[4 * q + 2] + rv[3] * w[4 * q + 3]; }
;         la[t] = (fminf(z, 0.f) - __logf(1.0f + __expf(-fabsf(z)))) * (1.0f / 16.0f);
;         tot += la[t];
;     }
	v_mov_b32_e32 v102, s37
	ds_read_b128 v[104:107], v102 offset:9216
	ds_read_b128 v[108:111], v102 offset:9232
	ds_read_b128 v[112:115], v102 offset:9248
	ds_read_b128 v[116:119], v102 offset:9264
	s_waitcnt lgkmcnt(3)
	v_mov_b32_e32 v120, v104
	s_waitcnt lgkmcnt(2)
	v_mov_b32_e32 v121, v108
	v_mov_b32_e32 v108, v105
	v_pk_mul_f32 v[104:105], v[16:17], v[108:109]
	v_mov_b32_e32 v108, v106
	v_pk_fma_f32 v[104:105], v[14:15], v[120:121], v[104:105]
	v_mov_b32_e32 v109, v110
	v_pk_fma_f32 v[104:105], v[12:13], v[108:109], v[104:105]
	v_mov_b32_e32 v110, v107
	v_pk_fma_f32 v[104:105], v[10:11], v[110:111], v[104:105]
	s_nop 0
	v_add_f32_e32 v101, v100, v104
	v_add_f32_e32 v101, v101, v105
	s_waitcnt lgkmcnt(0)
	v_mov_b32_e32 v105, v116
	v_mov_b32_e32 v116, v113
	v_mov_b32_e32 v104, v112
	v_pk_mul_f32 v[106:107], v[8:9], v[116:117]
	s_nop 0
	v_pk_fma_f32 v[104:105], v[6:7], v[104:105], v[106:107]
	v_mov_b32_e32 v106, v114
	v_mov_b32_e32 v107, v118
	v_pk_fma_f32 v[104:105], v[2:3], v[106:107], v[104:105]
	v_mov_b32_e32 v118, v115
	v_pk_fma_f32 v[104:105], v[0:1], v[118:119], v[104:105]
	s_nop 0
	v_add_f32_e32 v101, v101, v104
	v_add_f32_e32 v101, v101, v105
	v_min_f32_e32 v103, 0, v101
	v_mul_f32_e64 v101, |v101|, s68
	v_exp_f32_e32 v101, v101
	s_nop 0
	v_add_f32_e32 v101, 1.0, v101
	v_cmp_gt_f32_e32 vcc, s69, v101
	s_nop 1
	v_cndmask_b32_e64 v104, 0, 32, vcc
	v_ldexp_f32 v101, v101, v104
	v_log_f32_e32 v101, v101
	s_nop 0
	v_mul_f32_e32 v104, 0x3f317217, v101
	v_fma_f32 v104, v101, s70, -v104
	v_fmac_f32_e32 v104, 0x3377d1cf, v101
	v_fmac_f32_e32 v104, 0x3f317217, v101
	v_cmp_lt_f32_e64 s[0:1], |v101|, s71
	s_nop 1
	v_cndmask_b32_e64 v101, v101, v104, s[0:1]
	v_cndmask_b32_e32 v104, 0, v90, vcc
	v_sub_f32_e32 v101, v101, v104
	ds_read_b128 v[104:107], v102 offset:9280
	ds_read_b128 v[108:111], v102 offset:9296
	v_sub_f32_e32 v101, v103, v101
	s_mov_b32 s0, 0x3d800000
	v_fma_f32 v101, v101, s0, 0
	s_waitcnt lgkmcnt(1)
	v_mov_b32_e32 v112, v104
	s_waitcnt lgkmcnt(0)
	v_mov_b32_e32 v113, v108
	v_mov_b32_e32 v108, v105
	v_pk_mul_f32 v[104:105], v[16:17], v[108:109]
	v_mov_b32_e32 v108, v106
	v_pk_fma_f32 v[104:105], v[14:15], v[112:113], v[104:105]
	v_mov_b32_e32 v109, v110
	v_pk_fma_f32 v[104:105], v[12:13], v[108:109], v[104:105]
	v_mov_b32_e32 v110, v107
	v_pk_fma_f32 v[104:105], v[10:11], v[110:111], v[104:105]
	s_nop 0
	v_add_f32_e32 v103, v100, v104
	v_add_f32_e32 v103, v103, v105
	ds_read_b128 v[104:107], v102 offset:9312
	ds_read_b128 v[108:111], v102 offset:9328
	s_waitcnt lgkmcnt(1)
	v_mov_b32_e32 v112, v104
	s_waitcnt lgkmcnt(0)
	v_mov_b32_e32 v113, v108
	v_mov_b32_e32 v108, v105
	v_pk_mul_f32 v[104:105], v[8:9], v[108:109]
	v_mov_b32_e32 v108, v106
	v_pk_fma_f32 v[104:105], v[6:7], v[112:113], v[104:105]
	v_mov_b32_e32 v109, v110
	v_pk_fma_f32 v[104:105], v[2:3], v[108:109], v[104:105]
	v_mov_b32_e32 v110, v107
	v_pk_fma_f32 v[104:105], v[0:1], v[110:111], v[104:105]
	s_nop 0
	v_add_f32_e32 v103, v103, v104
	v_add_f32_e32 v103, v103, v105
	v_min_f32_e32 v104, 0, v103
	v_mul_f32_e64 v103, |v103|, s68
	v_exp_f32_e32 v103, v103
	s_nop 0
	v_add_f32_e32 v103, 1.0, v103
	v_cmp_gt_f32_e32 vcc, s69, v103
	s_nop 1
	v_cndmask_b32_e64 v105, 0, 32, vcc
	v_ldexp_f32 v103, v103, v105
	v_log_f32_e32 v103, v103
	s_nop 0
	v_mul_f32_e32 v105, 0x3f317217, v103
	v_fma_f32 v105, v103, s70, -v105
	v_fmac_f32_e32 v105, 0x3377d1cf, v103
	v_fmac_f32_e32 v105, 0x3f317217, v103
	v_cmp_lt_f32_e64 s[0:1], |v103|, s71
	s_nop 1
	v_cndmask_b32_e64 v103, v103, v105, s[0:1]
	v_cndmask_b32_e32 v105, 0, v90, vcc
	v_sub_f32_e32 v103, v103, v105
	v_sub_f32_e32 v103, v104, v103
	ds_read_b128 v[104:107], v102 offset:9344
	ds_read_b128 v[108:111], v102 offset:9360
	v_fmamk_f32 v103, v103, 0x3d800000, v101
	s_waitcnt lgkmcnt(1)
	v_mov_b32_e32 v112, v104
	s_waitcnt lgkmcnt(0)
	v_mov_b32_e32 v113, v108
	v_mov_b32_e32 v108, v105
	v_pk_mul_f32 v[104:105], v[16:17], v[108:109]
	v_mov_b32_e32 v108, v106
	v_pk_fma_f32 v[104:105], v[14:15], v[112:113], v[104:105]
	v_mov_b32_e32 v109, v110
	v_pk_fma_f32 v[104:105], v[12:13], v[108:109], v[104:105]
	v_mov_b32_e32 v110, v107
	v_pk_fma_f32 v[104:105], v[10:11], v[110:111], v[104:105]
	s_nop 0
	v_add_f32_e32 v104, v100, v104
	v_add_f32_e32 v114, v104, v105
	ds_read_b128 v[104:107], v102 offset:9376
	ds_read_b128 v[108:111], v102 offset:9392
	s_waitcnt lgkmcnt(1)
	v_mov_b32_e32 v112, v104
	s_waitcnt lgkmcnt(0)
	v_mov_b32_e32 v113, v108
	v_mov_b32_e32 v108, v105
	v_pk_mul_f32 v[104:105], v[8:9], v[108:109]
	v_mov_b32_e32 v108, v106
	v_pk_fma_f32 v[104:105], v[6:7], v[112:113], v[104:105]
	v_mov_b32_e32 v109, v110
	v_pk_fma_f32 v[104:105], v[2:3], v[108:109], v[104:105]
	v_mov_b32_e32 v110, v107
	v_pk_fma_f32 v[104:105], v[0:1], v[110:111], v[104:105]
	s_nop 0
	v_add_f32_e32 v104, v114, v104
	v_add_f32_e32 v104, v104, v105
	v_min_f32_e32 v105, 0, v104
	v_mul_f32_e64 v104, |v104|, s68
	v_exp_f32_e32 v104, v104
	s_nop 0
	v_add_f32_e32 v104, 1.0, v104
	v_cmp_gt_f32_e32 vcc, s69, v104
	s_nop 1
	v_cndmask_b32_e64 v106, 0, 32, vcc
	v_ldexp_f32 v104, v104, v106
	v_log_f32_e32 v104, v104
	s_nop 0
	v_mul_f32_e32 v106, 0x3f317217, v104
	v_fma_f32 v106, v104, s70, -v106
	v_fmac_f32_e32 v106, 0x3377d1cf, v104
	v_fmac_f32_e32 v106, 0x3f317217, v104
	v_cmp_lt_f32_e64 s[0:1], |v104|, s71
	s_nop 1
	v_cndmask_b32_e64 v104, v104, v106, s[0:1]
	v_cndmask_b32_e32 v106, 0, v90, vcc
	v_sub_f32_e32 v104, v104, v106
	ds_read_b128 v[106:109], v102 offset:9408
	ds_read_b128 v[110:113], v102 offset:9424
	v_sub_f32_e32 v104, v105, v104
	v_fmamk_f32 v104, v104, 0x3d800000, v103
	s_waitcnt lgkmcnt(1)
	v_mov_b32_e32 v114, v106
	s_waitcnt lgkmcnt(0)
; #define LAS __attribute__((address_space(3)))
; __device__ __forceinline__ void gla_upd_unit(LAS unsigned char* wl, const bf16* PROJ, const float* R, const float* w_gk2, const float* b_gk, float* UPD, float* DEC, int unit, int lane) {
;     ...
;     float la[64]; float tot = 0.f;
; #pragma unroll
;     for (int t = 0; t < 64; ++t) {
;         const LAS f32x4* rr = (const LAS f32x4*)(wl + 9216) + t * 4;
;         float z = bias;
; #pragma unroll
;         for (int q = 0; q < 4; ++q) { const f32x4 rv = rr[q]; z += rv[0] * w[4 * q] + rv[1] * w[4 * q + 1] + rv[2] * w[4 * q + 2] + rv[3] * w[4 * q + 3]; }
;         la[t] = (fminf(z, 0.f) - __logf(1.0f + __expf(-fabsf(z)))) * (1.0f / 16.0f);
;         tot += la[t];
;     }
	v_mov_b32_e32 v115, v110
	v_mov_b32_e32 v110, v107
	v_pk_mul_f32 v[106:107], v[16:17], v[110:111]
	v_mov_b32_e32 v110, v108
	v_pk_fma_f32 v[106:107], v[14:15], v[114:115], v[106:107]
	v_mov_b32_e32 v111, v112
	v_pk_fma_f32 v[106:107], v[12:13], v[110:111], v[106:107]
	v_mov_b32_e32 v112, v109
	v_pk_fma_f32 v[106:107], v[10:11], v[112:113], v[106:107]
	s_nop 0
	v_add_f32_e32 v105, v100, v106
	v_add_f32_e32 v105, v105, v107
	ds_read_b128 v[106:109], v102 offset:9440
	ds_read_b128 v[110:113], v102 offset:9456
	s_waitcnt lgkmcnt(1)
	v_mov_b32_e32 v114, v106
	s_waitcnt lgkmcnt(0)
	v_mov_b32_e32 v115, v110
	v_mov_b32_e32 v110, v107
	v_pk_mul_f32 v[106:107], v[8:9], v[110:111]
	v_mov_b32_e32 v110, v108
	v_pk_fma_f32 v[106:107], v[6:7], v[114:115], v[106:107]
	v_mov_b32_e32 v111, v112
	v_pk_fma_f32 v[106:107], v[2:3], v[110:111], v[106:107]
	v_mov_b32_e32 v112, v109
	v_pk_fma_f32 v[106:107], v[0:1], v[112:113], v[106:107]
	s_nop 0
	v_add_f32_e32 v105, v105, v106
	v_add_f32_e32 v105, v105, v107
	v_min_f32_e32 v106, 0, v105
	v_mul_f32_e64 v105, |v105|, s68
	v_exp_f32_e32 v105, v105
	s_nop 0
	v_add_f32_e32 v105, 1.0, v105
	v_cmp_gt_f32_e32 vcc, s69, v105
	s_nop 1
	v_cndmask_b32_e64 v107, 0, 32, vcc
	v_ldexp_f32 v105, v105, v107
	v_log_f32_e32 v105, v105
	s_nop 0
	v_mul_f32_e32 v107, 0x3f317217, v105
	v_fma_f32 v107, v105, s70, -v107
	v_fmac_f32_e32 v107, 0x3377d1cf, v105
	v_fmac_f32_e32 v107, 0x3f317217, v105
	v_cmp_lt_f32_e64 s[0:1], |v105|, s71
	s_nop 1
	v_cndmask_b32_e64 v105, v105, v107, s[0:1]
	v_cndmask_b32_e32 v107, 0, v90, vcc
	v_sub_f32_e32 v105, v105, v107
	v_sub_f32_e32 v105, v106, v105
	ds_read_b128 v[106:109], v102 offset:9472
	ds_read_b128 v[110:113], v102 offset:9488
	v_fmamk_f32 v105, v105, 0x3d800000, v104
	s_waitcnt lgkmcnt(1)
	v_mov_b32_e32 v114, v106
	s_waitcnt lgkmcnt(0)
	v_mov_b32_e32 v115, v110
	v_mov_b32_e32 v110, v107
	v_pk_mul_f32 v[106:107], v[16:17], v[110:111]
	v_mov_b32_e32 v110, v108
	v_pk_fma_f32 v[106:107], v[14:15], v[114:115], v[106:107]
	v_mov_b32_e32 v111, v112
	v_pk_fma_f32 v[106:107], v[12:13], v[110:111], v[106:107]
	v_mov_b32_e32 v112, v109
	v_pk_fma_f32 v[106:107], v[10:11], v[112:113], v[106:107]
	s_nop 0
	v_add_f32_e32 v106, v100, v106
	v_add_f32_e32 v116, v106, v107
	ds_read_b128 v[106:109], v102 offset:9504
	ds_read_b128 v[110:113], v102 offset:9520
	s_waitcnt lgkmcnt(1)
	v_mov_b32_e32 v114, v106
	s_waitcnt lgkmcnt(0)
	v_mov_b32_e32 v115, v110
	v_mov_b32_e32 v110, v107
	v_pk_mul_f32 v[106:107], v[8:9], v[110:111]
	v_mov_b32_e32 v110, v108
	v_pk_fma_f32 v[106:107], v[6:7], v[114:115], v[106:107]
	v_mov_b32_e32 v111, v112
	v_pk_fma_f32 v[106:107], v[2:3], v[110:111], v[106:107]
	v_mov_b32_e32 v112, v109
	v_pk_fma_f32 v[106:107], v[0:1], v[112:113], v[106:107]
	s_nop 0
	v_add_f32_e32 v106, v116, v106
	v_add_f32_e32 v106, v106, v107
	v_min_f32_e32 v107, 0, v106
	v_mul_f32_e64 v106, |v106|, s68
	v_exp_f32_e32 v106, v106
	s_nop 0
	v_add_f32_e32 v106, 1.0, v106
	v_cmp_gt_f32_e32 vcc, s69, v106
	s_nop 1
	v_cndmask_b32_e64 v108, 0, 32, vcc
	v_ldexp_f32 v106, v106, v108
	v_log_f32_e32 v106, v106
	s_nop 0
	v_mul_f32_e32 v108, 0x3f317217, v106
	v_fma_f32 v108, v106, s70, -v108
	v_fmac_f32_e32 v108, 0x3377d1cf, v106
	v_fmac_f32_e32 v108, 0x3f317217, v106
	v_cmp_lt_f32_e64 s[0:1], |v106|, s71
	s_nop 1
	v_cndmask_b32_e64 v106, v106, v108, s[0:1]
	v_cndmask_b32_e32 v108, 0, v90, vcc
	v_sub_f32_e32 v106, v106, v108
	ds_read_b128 v[108:111], v102 offset:9536
	ds_read_b128 v[112:115], v102 offset:9552
	v_sub_f32_e32 v106, v107, v106
	v_fmamk_f32 v106, v106, 0x3d800000, v105
	s_waitcnt lgkmcnt(1)
	v_mov_b32_e32 v116, v108
	s_waitcnt lgkmcnt(0)
	v_mov_b32_e32 v117, v112
	v_mov_b32_e32 v112, v109
	v_pk_mul_f32 v[108:109], v[16:17], v[112:113]
	v_mov_b32_e32 v112, v110
	v_pk_fma_f32 v[108:109], v[14:15], v[116:117], v[108:109]
	v_mov_b32_e32 v113, v114
	v_pk_fma_f32 v[108:109], v[12:13], v[112:113], v[108:109]
	v_mov_b32_e32 v114, v111
	v_pk_fma_f32 v[108:109], v[10:11], v[114:115], v[108:109]
	s_nop 0
	v_add_f32_e32 v107, v100, v108
	v_add_f32_e32 v107, v107, v109
	ds_read_b128 v[108:111], v102 offset:9568
	ds_read_b128 v[112:115], v102 offset:9584
	s_waitcnt lgkmcnt(1)
	v_mov_b32_e32 v116, v108
	s_waitcnt lgkmcnt(0)
	v_mov_b32_e32 v117, v112
	v_mov_b32_e32 v112, v109
	v_pk_mul_f32 v[108:109], v[8:9], v[112:113]
	v_mov_b32_e32 v112, v110
	v_pk_fma_f32 v[108:109], v[6:7], v[116:117], v[108:109]
	v_mov_b32_e32 v113, v114
	v_pk_fma_f32 v[108:109], v[2:3], v[112:113], v[108:109]
	v_mov_b32_e32 v114, v111
	v_pk_fma_f32 v[108:109], v[0:1], v[114:115], v[108:109]
	s_nop 0
	v_add_f32_e32 v107, v107, v108
	v_add_f32_e32 v107, v107, v109
	v_min_f32_e32 v108, 0, v107
	v_mul_f32_e64 v107, |v107|, s68
	v_exp_f32_e32 v107, v107
	s_nop 0
	v_add_f32_e32 v107, 1.0, v107
	v_cmp_gt_f32_e32 vcc, s69, v107
	s_nop 1
	v_cndmask_b32_e64 v109, 0, 32, vcc
	v_ldexp_f32 v107, v107, v109
	v_log_f32_e32 v107, v107
	s_nop 0
	v_mul_f32_e32 v109, 0x3f317217, v107
	v_fma_f32 v109, v107, s70, -v109
	v_fmac_f32_e32 v109, 0x3377d1cf, v107
	v_fmac_f32_e32 v109, 0x3f317217, v107
	v_cmp_lt_f32_e64 s[0:1], |v107|, s71
	s_nop 1
	v_cndmask_b32_e64 v107, v107, v109, s[0:1]
	v_cndmask_b32_e32 v109, 0, v90, vcc
	v_sub_f32_e32 v107, v107, v109
	v_sub_f32_e32 v107, v108, v107
	ds_read_b128 v[108:111], v102 offset:9600
	ds_read_b128 v[112:115], v102 offset:9616
	v_fmamk_f32 v107, v107, 0x3d800000, v106
	s_waitcnt lgkmcnt(1)
	v_mov_b32_e32 v116, v108
	s_waitcnt lgkmcnt(0)
; #define LAS __attribute__((address_space(3)))
; __device__ __forceinline__ void gla_upd_unit(LAS unsigned char* wl, const bf16* PROJ, const float* R, const float* w_gk2, const float* b_gk, float* UPD, float* DEC, int unit, int lane) {
;     ...
;     float la[64]; float tot = 0.f;
; #pragma unroll
;     for (int t = 0; t < 64; ++t) {
;         const LAS f32x4* rr = (const LAS f32x4*)(wl + 9216) + t * 4;
;         float z = bias;
; #pragma unroll
;         for (int q = 0; q < 4; ++q) { const f32x4 rv = rr[q]; z += rv[0] * w[4 * q] + rv[1] * w[4 * q + 1] + rv[2] * w[4 * q + 2] + rv[3] * w[4 * q + 3]; }
;         la[t] = (fminf(z, 0.f) - __logf(1.0f + __expf(-fabsf(z)))) * (1.0f / 16.0f);
;         tot += la[t];
;     }
	v_mov_b32_e32 v117, v112
	v_mov_b32_e32 v112, v109
	v_pk_mul_f32 v[108:109], v[16:17], v[112:113]
	v_mov_b32_e32 v112, v110
	v_pk_fma_f32 v[108:109], v[14:15], v[116:117], v[108:109]
	v_mov_b32_e32 v113, v114
	v_pk_fma_f32 v[108:109], v[12:13], v[112:113], v[108:109]
	v_mov_b32_e32 v114, v111
	v_pk_fma_f32 v[108:109], v[10:11], v[114:115], v[108:109]
	s_nop 0
	v_add_f32_e32 v108, v100, v108
	v_add_f32_e32 v118, v108, v109
	ds_read_b128 v[108:111], v102 offset:9632
	ds_read_b128 v[112:115], v102 offset:9648
	s_waitcnt lgkmcnt(1)
	v_mov_b32_e32 v116, v108
	s_waitcnt lgkmcnt(0)
	v_mov_b32_e32 v117, v112
	v_mov_b32_e32 v112, v109
	v_pk_mul_f32 v[108:109], v[8:9], v[112:113]
	v_mov_b32_e32 v112, v110
	v_pk_fma_f32 v[108:109], v[6:7], v[116:117], v[108:109]
	v_mov_b32_e32 v113, v114
	v_pk_fma_f32 v[108:109], v[2:3], v[112:113], v[108:109]
	v_mov_b32_e32 v114, v111
	v_pk_fma_f32 v[108:109], v[0:1], v[114:115], v[108:109]
	s_nop 0
	v_add_f32_e32 v108, v118, v108
	v_add_f32_e32 v108, v108, v109
	v_min_f32_e32 v109, 0, v108
	v_mul_f32_e64 v108, |v108|, s68
	v_exp_f32_e32 v108, v108
	s_nop 0
	v_add_f32_e32 v108, 1.0, v108
	v_cmp_gt_f32_e32 vcc, s69, v108
	s_nop 1
	v_cndmask_b32_e64 v110, 0, 32, vcc
	v_ldexp_f32 v108, v108, v110
	v_log_f32_e32 v108, v108
	s_nop 0
	v_mul_f32_e32 v110, 0x3f317217, v108
	v_fma_f32 v110, v108, s70, -v110
	v_fmac_f32_e32 v110, 0x3377d1cf, v108
	v_fmac_f32_e32 v110, 0x3f317217, v108
	v_cmp_lt_f32_e64 s[0:1], |v108|, s71
	s_nop 1
	v_cndmask_b32_e64 v108, v108, v110, s[0:1]
	v_cndmask_b32_e32 v110, 0, v90, vcc
	v_sub_f32_e32 v108, v108, v110
	ds_read_b128 v[110:113], v102 offset:9664
	ds_read_b128 v[114:117], v102 offset:9680
	v_sub_f32_e32 v108, v109, v108
	v_fmamk_f32 v109, v108, 0x3d800000, v107
	s_waitcnt lgkmcnt(1)
	v_mov_b32_e32 v118, v110
	s_waitcnt lgkmcnt(0)
	v_mov_b32_e32 v119, v114
	v_mov_b32_e32 v114, v111
	v_pk_mul_f32 v[110:111], v[16:17], v[114:115]
	v_mov_b32_e32 v114, v112
	v_pk_fma_f32 v[110:111], v[14:15], v[118:119], v[110:111]
	v_mov_b32_e32 v115, v116
	v_pk_fma_f32 v[110:111], v[12:13], v[114:115], v[110:111]
	v_mov_b32_e32 v116, v113
	v_pk_fma_f32 v[110:111], v[10:11], v[116:117], v[110:111]
	s_nop 0
	v_add_f32_e32 v108, v100, v110
	v_add_f32_e32 v108, v108, v111
	ds_read_b128 v[110:113], v102 offset:9696
	ds_read_b128 v[114:117], v102 offset:9712
	s_waitcnt lgkmcnt(1)
	v_mov_b32_e32 v118, v110
	s_waitcnt lgkmcnt(0)
	v_mov_b32_e32 v119, v114
	v_mov_b32_e32 v114, v111
	v_pk_mul_f32 v[110:111], v[8:9], v[114:115]
	v_mov_b32_e32 v114, v112
	v_pk_fma_f32 v[110:111], v[6:7], v[118:119], v[110:111]
	v_mov_b32_e32 v115, v116
	v_pk_fma_f32 v[110:111], v[2:3], v[114:115], v[110:111]
	v_mov_b32_e32 v116, v113
	v_pk_fma_f32 v[110:111], v[0:1], v[116:117], v[110:111]
	ds_read_b128 v[112:115], v102 offset:9728
	ds_read_b128 v[116:119], v102 offset:9744
	v_add_f32_e32 v108, v108, v110
	v_add_f32_e32 v108, v108, v111
	v_min_f32_e32 v110, 0, v108
	v_mul_f32_e64 v108, |v108|, s68
	v_exp_f32_e32 v108, v108
	s_waitcnt lgkmcnt(0)
	v_mov_b32_e32 v121, v116
	v_mov_b32_e32 v116, v113
	v_mov_b32_e32 v120, v112
	v_add_f32_e32 v108, 1.0, v108
	v_cmp_gt_f32_e32 vcc, s69, v108
	v_pk_mul_f32 v[112:113], v[16:17], v[116:117]
	v_mov_b32_e32 v116, v114
	v_cndmask_b32_e64 v111, 0, 32, vcc
	v_ldexp_f32 v108, v108, v111
	v_log_f32_e32 v108, v108
	v_pk_fma_f32 v[112:113], v[14:15], v[120:121], v[112:113]
	v_mov_b32_e32 v117, v118
	v_pk_fma_f32 v[112:113], v[12:13], v[116:117], v[112:113]
	v_mul_f32_e32 v111, 0x3f317217, v108
	v_fma_f32 v111, v108, s70, -v111
	v_fmac_f32_e32 v111, 0x3377d1cf, v108
	v_fmac_f32_e32 v111, 0x3f317217, v108
	v_cmp_lt_f32_e64 s[0:1], |v108|, s71
	v_mov_b32_e32 v118, v115
	v_pk_fma_f32 v[112:113], v[10:11], v[118:119], v[112:113]
	v_cndmask_b32_e64 v108, v108, v111, s[0:1]
	v_cndmask_b32_e32 v111, 0, v90, vcc
	v_sub_f32_e32 v108, v108, v111
	v_sub_f32_e32 v108, v110, v108
	v_fmamk_f32 v111, v108, 0x3d800000, v109
	v_add_f32_e32 v108, v100, v112
	v_add_f32_e32 v108, v108, v113
	ds_read_b128 v[112:115], v102 offset:9760
	ds_read_b128 v[116:119], v102 offset:9776
	s_waitcnt lgkmcnt(1)
	v_mov_b32_e32 v120, v112
	s_waitcnt lgkmcnt(0)
	v_mov_b32_e32 v121, v116
	v_mov_b32_e32 v116, v113
	v_pk_mul_f32 v[112:113], v[8:9], v[116:117]
	v_mov_b32_e32 v116, v114
	v_pk_fma_f32 v[112:113], v[6:7], v[120:121], v[112:113]
	v_mov_b32_e32 v117, v118
	v_pk_fma_f32 v[112:113], v[2:3], v[116:117], v[112:113]
	v_mov_b32_e32 v118, v115
	v_pk_fma_f32 v[112:113], v[0:1], v[118:119], v[112:113]
	s_nop 0
	v_add_f32_e32 v108, v108, v112
	v_add_f32_e32 v108, v108, v113
	v_min_f32_e32 v110, 0, v108
	v_mul_f32_e64 v108, |v108|, s68
	v_exp_f32_e32 v108, v108
	s_nop 0
	v_add_f32_e32 v108, 1.0, v108
	v_cmp_gt_f32_e32 vcc, s69, v108
	s_nop 1
	v_cndmask_b32_e64 v112, 0, 32, vcc
	v_ldexp_f32 v108, v108, v112
	v_log_f32_e32 v108, v108
	s_nop 0
	v_mul_f32_e32 v112, 0x3f317217, v108
	v_fma_f32 v112, v108, s70, -v112
	v_fmac_f32_e32 v112, 0x3377d1cf, v108
	v_fmac_f32_e32 v112, 0x3f317217, v108
	v_cmp_lt_f32_e64 s[0:1], |v108|, s71
	s_nop 1
	v_cndmask_b32_e64 v108, v108, v112, s[0:1]
	v_cndmask_b32_e32 v112, 0, v90, vcc
	v_sub_f32_e32 v108, v108, v112
	ds_read_b128 v[112:115], v102 offset:9792
	ds_read_b128 v[116:119], v102 offset:9808
	v_sub_f32_e32 v108, v110, v108
	v_fmamk_f32 v108, v108, 0x3d800000, v111
	s_waitcnt lgkmcnt(1)
	v_mov_b32_e32 v120, v112
	s_waitcnt lgkmcnt(0)
	v_mov_b32_e32 v121, v116
	v_mov_b32_e32 v116, v113
	v_pk_mul_f32 v[112:113], v[16:17], v[116:117]
	v_mov_b32_e32 v116, v114
	v_pk_fma_f32 v[112:113], v[14:15], v[120:121], v[112:113]
	v_mov_b32_e32 v117, v118
	v_pk_fma_f32 v[112:113], v[12:13], v[116:117], v[112:113]
	v_mov_b32_e32 v118, v115
	v_pk_fma_f32 v[112:113], v[10:11], v[118:119], v[112:113]
	s_nop 0
	v_add_f32_e32 v110, v100, v112
	v_add_f32_e32 v110, v110, v113
	ds_read_b128 v[112:115], v102 offset:9824
	ds_read_b128 v[116:119], v102 offset:9840
	s_waitcnt lgkmcnt(1)
; #define LAS __attribute__((address_space(3)))
; __device__ __forceinline__ void gla_upd_unit(LAS unsigned char* wl, const bf16* PROJ, const float* R, const float* w_gk2, const float* b_gk, float* UPD, float* DEC, int unit, int lane) {
;     ...
;     float la[64]; float tot = 0.f;
; #pragma unroll
;     for (int t = 0; t < 64; ++t) {
;         const LAS f32x4* rr = (const LAS f32x4*)(wl + 9216) + t * 4;
;         float z = bias;
; #pragma unroll
;         for (int q = 0; q < 4; ++q) { const f32x4 rv = rr[q]; z += rv[0] * w[4 * q] + rv[1] * w[4 * q + 1] + rv[2] * w[4 * q + 2] + rv[3] * w[4 * q + 3]; }
;         la[t] = (fminf(z, 0.f) - __logf(1.0f + __expf(-fabsf(z)))) * (1.0f / 16.0f);
;         tot += la[t];
;     }
	v_mov_b32_e32 v120, v112
	s_waitcnt lgkmcnt(0)
	v_mov_b32_e32 v121, v116
	v_mov_b32_e32 v116, v113
	v_pk_mul_f32 v[112:113], v[8:9], v[116:117]
	v_mov_b32_e32 v116, v114
	v_pk_fma_f32 v[112:113], v[6:7], v[120:121], v[112:113]
	v_mov_b32_e32 v117, v118
	v_pk_fma_f32 v[112:113], v[2:3], v[116:117], v[112:113]
	v_mov_b32_e32 v118, v115
	v_pk_fma_f32 v[112:113], v[0:1], v[118:119], v[112:113]
	s_nop 0
	v_add_f32_e32 v110, v110, v112
	v_add_f32_e32 v110, v110, v113
	v_min_f32_e32 v112, 0, v110
	v_mul_f32_e64 v110, |v110|, s68
	v_exp_f32_e32 v110, v110
	s_nop 0
	v_add_f32_e32 v110, 1.0, v110
	v_cmp_gt_f32_e32 vcc, s69, v110
	s_nop 1
	v_cndmask_b32_e64 v113, 0, 32, vcc
	v_ldexp_f32 v110, v110, v113
	v_log_f32_e32 v110, v110
	s_nop 0
	v_mul_f32_e32 v113, 0x3f317217, v110
	v_fma_f32 v113, v110, s70, -v113
	v_fmac_f32_e32 v113, 0x3377d1cf, v110
	v_fmac_f32_e32 v113, 0x3f317217, v110
	v_cmp_lt_f32_e64 s[0:1], |v110|, s71
	s_nop 1
	v_cndmask_b32_e64 v110, v110, v113, s[0:1]
	v_cndmask_b32_e32 v113, 0, v90, vcc
	v_sub_f32_e32 v110, v110, v113
	v_sub_f32_e32 v110, v112, v110
	ds_read_b128 v[112:115], v102 offset:9856
	ds_read_b128 v[116:119], v102 offset:9872
	v_fmamk_f32 v110, v110, 0x3d800000, v108
	s_waitcnt lgkmcnt(1)
	v_mov_b32_e32 v120, v112
	s_waitcnt lgkmcnt(0)
	v_mov_b32_e32 v121, v116
	v_mov_b32_e32 v116, v113
	v_pk_mul_f32 v[112:113], v[16:17], v[116:117]
	v_mov_b32_e32 v116, v114
	v_pk_fma_f32 v[112:113], v[14:15], v[120:121], v[112:113]
	v_mov_b32_e32 v117, v118
	v_pk_fma_f32 v[112:113], v[12:13], v[116:117], v[112:113]
	v_mov_b32_e32 v118, v115
	v_pk_fma_f32 v[112:113], v[10:11], v[118:119], v[112:113]
	s_nop 0
	v_add_f32_e32 v112, v100, v112
	v_add_f32_e32 v122, v112, v113
	ds_read_b128 v[112:115], v102 offset:9888
	ds_read_b128 v[116:119], v102 offset:9904
	s_waitcnt lgkmcnt(1)
	v_mov_b32_e32 v120, v112
	s_waitcnt lgkmcnt(0)
	v_mov_b32_e32 v121, v116
	v_mov_b32_e32 v116, v113
	v_pk_mul_f32 v[112:113], v[8:9], v[116:117]
	v_mov_b32_e32 v116, v114
	v_pk_fma_f32 v[112:113], v[6:7], v[120:121], v[112:113]
	v_mov_b32_e32 v117, v118
	v_pk_fma_f32 v[112:113], v[2:3], v[116:117], v[112:113]
	v_mov_b32_e32 v118, v115
	v_pk_fma_f32 v[112:113], v[0:1], v[118:119], v[112:113]
	s_nop 0
	v_add_f32_e32 v112, v122, v112
	v_add_f32_e32 v112, v112, v113
	v_min_f32_e32 v113, 0, v112
	v_mul_f32_e64 v112, |v112|, s68
	v_exp_f32_e32 v112, v112
	s_nop 0
	v_add_f32_e32 v112, 1.0, v112
	v_cmp_gt_f32_e32 vcc, s69, v112
	s_nop 1
	v_cndmask_b32_e64 v114, 0, 32, vcc
	v_ldexp_f32 v112, v112, v114
	v_log_f32_e32 v112, v112
	s_nop 0
	v_mul_f32_e32 v114, 0x3f317217, v112
	v_fma_f32 v114, v112, s70, -v114
	v_fmac_f32_e32 v114, 0x3377d1cf, v112
	v_fmac_f32_e32 v114, 0x3f317217, v112
	v_cmp_lt_f32_e64 s[0:1], |v112|, s71
	s_nop 1
	v_cndmask_b32_e64 v112, v112, v114, s[0:1]
	v_cndmask_b32_e32 v114, 0, v90, vcc
	v_sub_f32_e32 v112, v112, v114
	ds_read_b128 v[114:117], v102 offset:9920
	ds_read_b128 v[118:121], v102 offset:9936
	v_sub_f32_e32 v112, v113, v112
	v_fmamk_f32 v112, v112, 0x3d800000, v110
	s_waitcnt lgkmcnt(1)
	v_mov_b32_e32 v122, v114
	s_waitcnt lgkmcnt(0)
	v_mov_b32_e32 v123, v118
	v_mov_b32_e32 v118, v115
	v_pk_mul_f32 v[114:115], v[16:17], v[118:119]
	v_mov_b32_e32 v118, v116
	v_pk_fma_f32 v[114:115], v[14:15], v[122:123], v[114:115]
	v_mov_b32_e32 v119, v120
	v_pk_fma_f32 v[114:115], v[12:13], v[118:119], v[114:115]
	v_mov_b32_e32 v120, v117
	v_pk_fma_f32 v[114:115], v[10:11], v[120:121], v[114:115]
	s_nop 0
	v_add_f32_e32 v113, v100, v114
	v_add_f32_e32 v113, v113, v115
	ds_read_b128 v[114:117], v102 offset:9952
	ds_read_b128 v[118:121], v102 offset:9968
	s_waitcnt lgkmcnt(1)
	v_mov_b32_e32 v122, v114
	s_waitcnt lgkmcnt(0)
	v_mov_b32_e32 v123, v118
	v_mov_b32_e32 v118, v115
	v_pk_mul_f32 v[114:115], v[8:9], v[118:119]
	v_mov_b32_e32 v118, v116
	v_pk_fma_f32 v[114:115], v[6:7], v[122:123], v[114:115]
	v_mov_b32_e32 v119, v120
	v_pk_fma_f32 v[114:115], v[2:3], v[118:119], v[114:115]
	v_mov_b32_e32 v120, v117
	v_pk_fma_f32 v[114:115], v[0:1], v[120:121], v[114:115]
	s_nop 0
	v_add_f32_e32 v113, v113, v114
	v_add_f32_e32 v113, v113, v115
	v_min_f32_e32 v114, 0, v113
	v_mul_f32_e64 v113, |v113|, s68
	v_exp_f32_e32 v113, v113
	s_nop 0
	v_add_f32_e32 v113, 1.0, v113
	v_cmp_gt_f32_e32 vcc, s69, v113
	s_nop 1
	v_cndmask_b32_e64 v115, 0, 32, vcc
	v_ldexp_f32 v113, v113, v115
	v_log_f32_e32 v113, v113
	s_nop 0
	v_mul_f32_e32 v115, 0x3f317217, v113
	v_fma_f32 v115, v113, s70, -v115
	v_fmac_f32_e32 v115, 0x3377d1cf, v113
	v_fmac_f32_e32 v115, 0x3f317217, v113
	v_cmp_lt_f32_e64 s[0:1], |v113|, s71
	s_nop 1
	v_cndmask_b32_e64 v113, v113, v115, s[0:1]
	v_cndmask_b32_e32 v115, 0, v90, vcc
	v_sub_f32_e32 v113, v113, v115
	v_sub_f32_e32 v113, v114, v113
	ds_read_b128 v[114:117], v102 offset:9984
	ds_read_b128 v[118:121], v102 offset:10000
	v_fmamk_f32 v113, v113, 0x3d800000, v112
	s_waitcnt lgkmcnt(1)
	v_mov_b32_e32 v122, v114
	s_waitcnt lgkmcnt(0)
	v_mov_b32_e32 v123, v118
	v_mov_b32_e32 v118, v115
	v_pk_mul_f32 v[114:115], v[16:17], v[118:119]
	v_mov_b32_e32 v118, v116
	v_pk_fma_f32 v[114:115], v[14:15], v[122:123], v[114:115]
	v_mov_b32_e32 v119, v120
	v_pk_fma_f32 v[114:115], v[12:13], v[118:119], v[114:115]
	v_mov_b32_e32 v120, v117
	v_pk_fma_f32 v[114:115], v[10:11], v[120:121], v[114:115]
	s_nop 0
	v_add_f32_e32 v114, v100, v114
	v_add_f32_e32 v124, v114, v115
	ds_read_b128 v[114:117], v102 offset:10016
	ds_read_b128 v[118:121], v102 offset:10032
	s_waitcnt lgkmcnt(1)
	v_mov_b32_e32 v122, v114
	s_waitcnt lgkmcnt(0)
; #define LAS __attribute__((address_space(3)))
; __device__ __forceinline__ void gla_upd_unit(LAS unsigned char* wl, const bf16* PROJ, const float* R, const float* w_gk2, const float* b_gk, float* UPD, float* DEC, int unit, int lane) {
;     ...
;     float la[64]; float tot = 0.f;
; #pragma unroll
;     for (int t = 0; t < 64; ++t) {
;         const LAS f32x4* rr = (const LAS f32x4*)(wl + 9216) + t * 4;
;         float z = bias;
; #pragma unroll
;         for (int q = 0; q < 4; ++q) { const f32x4 rv = rr[q]; z += rv[0] * w[4 * q] + rv[1] * w[4 * q + 1] + rv[2] * w[4 * q + 2] + rv[3] * w[4 * q + 3]; }
;         la[t] = (fminf(z, 0.f) - __logf(1.0f + __expf(-fabsf(z)))) * (1.0f / 16.0f);
;         tot += la[t];
;     }
	v_mov_b32_e32 v123, v118
	v_mov_b32_e32 v118, v115
	v_pk_mul_f32 v[114:115], v[8:9], v[118:119]
	v_mov_b32_e32 v118, v116
	v_pk_fma_f32 v[114:115], v[6:7], v[122:123], v[114:115]
	v_mov_b32_e32 v119, v120
	v_pk_fma_f32 v[114:115], v[2:3], v[118:119], v[114:115]
	v_mov_b32_e32 v120, v117
	v_pk_fma_f32 v[114:115], v[0:1], v[120:121], v[114:115]
	s_nop 0
	v_add_f32_e32 v114, v124, v114
	v_add_f32_e32 v114, v114, v115
	v_min_f32_e32 v115, 0, v114
	v_mul_f32_e64 v114, |v114|, s68
	v_exp_f32_e32 v114, v114
	s_nop 0
	v_add_f32_e32 v114, 1.0, v114
	v_cmp_gt_f32_e32 vcc, s69, v114
	s_nop 1
	v_cndmask_b32_e64 v116, 0, 32, vcc
	v_ldexp_f32 v114, v114, v116
	v_log_f32_e32 v114, v114
	s_nop 0
	v_mul_f32_e32 v116, 0x3f317217, v114
	v_fma_f32 v116, v114, s70, -v116
	v_fmac_f32_e32 v116, 0x3377d1cf, v114
	v_fmac_f32_e32 v116, 0x3f317217, v114
	v_cmp_lt_f32_e64 s[0:1], |v114|, s71
	s_nop 1
	v_cndmask_b32_e64 v114, v114, v116, s[0:1]
	v_cndmask_b32_e32 v116, 0, v90, vcc
	v_sub_f32_e32 v114, v114, v116
	ds_read_b128 v[116:119], v102 offset:10048
	ds_read_b128 v[120:123], v102 offset:10064
	v_sub_f32_e32 v114, v115, v114
	v_fmamk_f32 v114, v114, 0x3d800000, v113
	s_waitcnt lgkmcnt(1)
	v_mov_b32_e32 v124, v116
	s_waitcnt lgkmcnt(0)
	v_mov_b32_e32 v125, v120
	v_mov_b32_e32 v120, v117
	v_pk_mul_f32 v[116:117], v[16:17], v[120:121]
	v_mov_b32_e32 v120, v118
	v_pk_fma_f32 v[116:117], v[14:15], v[124:125], v[116:117]
	v_mov_b32_e32 v121, v122
	v_pk_fma_f32 v[116:117], v[12:13], v[120:121], v[116:117]
	v_mov_b32_e32 v122, v119
	v_pk_fma_f32 v[116:117], v[10:11], v[122:123], v[116:117]
	s_nop 0
	v_add_f32_e32 v115, v100, v116
	v_add_f32_e32 v115, v115, v117
	ds_read_b128 v[116:119], v102 offset:10080
	ds_read_b128 v[120:123], v102 offset:10096
	s_waitcnt lgkmcnt(1)
	v_mov_b32_e32 v124, v116
	s_waitcnt lgkmcnt(0)
	v_mov_b32_e32 v125, v120
	v_mov_b32_e32 v120, v117
	v_pk_mul_f32 v[116:117], v[8:9], v[120:121]
	v_mov_b32_e32 v120, v118
	v_pk_fma_f32 v[116:117], v[6:7], v[124:125], v[116:117]
	v_mov_b32_e32 v121, v122
	v_pk_fma_f32 v[116:117], v[2:3], v[120:121], v[116:117]
	v_mov_b32_e32 v122, v119
	v_pk_fma_f32 v[116:117], v[0:1], v[122:123], v[116:117]
	s_nop 0
	v_add_f32_e32 v115, v115, v116
	v_add_f32_e32 v115, v115, v117
	v_min_f32_e32 v116, 0, v115
	v_mul_f32_e64 v115, |v115|, s68
	v_exp_f32_e32 v115, v115
	s_nop 0
	v_add_f32_e32 v115, 1.0, v115
	v_cmp_gt_f32_e32 vcc, s69, v115
	s_nop 1
	v_cndmask_b32_e64 v117, 0, 32, vcc
	v_ldexp_f32 v115, v115, v117
	v_log_f32_e32 v115, v115
	s_nop 0
	v_mul_f32_e32 v117, 0x3f317217, v115
	v_fma_f32 v117, v115, s70, -v117
	v_fmac_f32_e32 v117, 0x3377d1cf, v115
	v_fmac_f32_e32 v117, 0x3f317217, v115
	v_cmp_lt_f32_e64 s[0:1], |v115|, s71
	s_nop 1
	v_cndmask_b32_e64 v115, v115, v117, s[0:1]
	v_cndmask_b32_e32 v117, 0, v90, vcc
	v_sub_f32_e32 v115, v115, v117
	v_sub_f32_e32 v115, v116, v115
	ds_read_b128 v[116:119], v102 offset:10112
	ds_read_b128 v[120:123], v102 offset:10128
	v_fmamk_f32 v115, v115, 0x3d800000, v114
	s_waitcnt lgkmcnt(1)
	v_mov_b32_e32 v124, v116
	s_waitcnt lgkmcnt(0)
	v_mov_b32_e32 v125, v120
	v_mov_b32_e32 v120, v117
	v_pk_mul_f32 v[116:117], v[16:17], v[120:121]
	v_mov_b32_e32 v120, v118
	v_pk_fma_f32 v[116:117], v[14:15], v[124:125], v[116:117]
	v_mov_b32_e32 v121, v122
	v_pk_fma_f32 v[116:117], v[12:13], v[120:121], v[116:117]
	v_mov_b32_e32 v122, v119
	v_pk_fma_f32 v[116:117], v[10:11], v[122:123], v[116:117]
	s_nop 0
	v_add_f32_e32 v116, v100, v116
	v_add_f32_e32 v126, v116, v117
	ds_read_b128 v[116:119], v102 offset:10144
	ds_read_b128 v[120:123], v102 offset:10160
	s_waitcnt lgkmcnt(1)
	v_mov_b32_e32 v124, v116
	s_waitcnt lgkmcnt(0)
	v_mov_b32_e32 v125, v120
	v_mov_b32_e32 v120, v117
	v_pk_mul_f32 v[116:117], v[8:9], v[120:121]
	v_mov_b32_e32 v120, v118
	v_pk_fma_f32 v[116:117], v[6:7], v[124:125], v[116:117]
	v_mov_b32_e32 v121, v122
	v_pk_fma_f32 v[116:117], v[2:3], v[120:121], v[116:117]
	v_mov_b32_e32 v122, v119
	v_pk_fma_f32 v[116:117], v[0:1], v[122:123], v[116:117]
	s_nop 0
	v_add_f32_e32 v116, v126, v116
	v_add_f32_e32 v116, v116, v117
	v_min_f32_e32 v117, 0, v116
	v_mul_f32_e64 v116, |v116|, s68
	v_exp_f32_e32 v116, v116
	s_nop 0
	v_add_f32_e32 v116, 1.0, v116
	v_cmp_gt_f32_e32 vcc, s69, v116
	s_nop 1
	v_cndmask_b32_e64 v118, 0, 32, vcc
	v_ldexp_f32 v116, v116, v118
	v_log_f32_e32 v116, v116
	s_nop 0
	v_mul_f32_e32 v118, 0x3f317217, v116
	v_fma_f32 v118, v116, s70, -v118
	v_fmac_f32_e32 v118, 0x3377d1cf, v116
	v_fmac_f32_e32 v118, 0x3f317217, v116
	v_cmp_lt_f32_e64 s[0:1], |v116|, s71
	s_nop 1
	v_cndmask_b32_e64 v116, v116, v118, s[0:1]
	v_cndmask_b32_e32 v118, 0, v90, vcc
	v_sub_f32_e32 v116, v116, v118
	ds_read_b128 v[118:121], v102 offset:10176
	ds_read_b128 v[122:125], v102 offset:10192
	v_sub_f32_e32 v116, v117, v116
	v_fmamk_f32 v116, v116, 0x3d800000, v115
	s_waitcnt lgkmcnt(1)
	v_mov_b32_e32 v126, v118
	s_waitcnt lgkmcnt(0)
	v_mov_b32_e32 v127, v122
	v_mov_b32_e32 v122, v119
	v_pk_mul_f32 v[118:119], v[16:17], v[122:123]
	v_mov_b32_e32 v122, v120
	v_pk_fma_f32 v[118:119], v[14:15], v[126:127], v[118:119]
	v_mov_b32_e32 v123, v124
	v_pk_fma_f32 v[118:119], v[12:13], v[122:123], v[118:119]
	v_mov_b32_e32 v124, v121
	v_pk_fma_f32 v[118:119], v[10:11], v[124:125], v[118:119]
	s_nop 0
	v_add_f32_e32 v117, v100, v118
	v_add_f32_e32 v117, v117, v119
	ds_read_b128 v[118:121], v102 offset:10208
	ds_read_b128 v[122:125], v102 offset:10224
	s_waitcnt lgkmcnt(1)
	v_mov_b32_e32 v126, v118
	s_waitcnt lgkmcnt(0)
; #define LAS __attribute__((address_space(3)))
; __device__ __forceinline__ void gla_upd_unit(LAS unsigned char* wl, const bf16* PROJ, const float* R, const float* w_gk2, const float* b_gk, float* UPD, float* DEC, int unit, int lane) {
;     ...
;     float la[64]; float tot = 0.f;
; #pragma unroll
;     for (int t = 0; t < 64; ++t) {
;         const LAS f32x4* rr = (const LAS f32x4*)(wl + 9216) + t * 4;
;         float z = bias;
; #pragma unroll
;         for (int q = 0; q < 4; ++q) { const f32x4 rv = rr[q]; z += rv[0] * w[4 * q] + rv[1] * w[4 * q + 1] + rv[2] * w[4 * q + 2] + rv[3] * w[4 * q + 3]; }
;         la[t] = (fminf(z, 0.f) - __logf(1.0f + __expf(-fabsf(z)))) * (1.0f / 16.0f);
;         tot += la[t];
;     }
	v_mov_b32_e32 v127, v122
	v_mov_b32_e32 v122, v119
	v_pk_mul_f32 v[118:119], v[8:9], v[122:123]
	v_mov_b32_e32 v122, v120
	v_pk_fma_f32 v[118:119], v[6:7], v[126:127], v[118:119]
	v_mov_b32_e32 v123, v124
	v_pk_fma_f32 v[118:119], v[2:3], v[122:123], v[118:119]
	v_mov_b32_e32 v124, v121
	v_pk_fma_f32 v[118:119], v[0:1], v[124:125], v[118:119]
	s_nop 0
	v_add_f32_e32 v117, v117, v118
	v_add_f32_e32 v117, v117, v119
	v_min_f32_e32 v118, 0, v117
	v_mul_f32_e64 v117, |v117|, s68
	v_exp_f32_e32 v117, v117
	s_nop 0
	v_add_f32_e32 v117, 1.0, v117
	v_cmp_gt_f32_e32 vcc, s69, v117
	s_nop 1
	v_cndmask_b32_e64 v119, 0, 32, vcc
	v_ldexp_f32 v117, v117, v119
	v_log_f32_e32 v117, v117
	s_nop 0
	v_mul_f32_e32 v119, 0x3f317217, v117
	v_fma_f32 v119, v117, s70, -v119
	v_fmac_f32_e32 v119, 0x3377d1cf, v117
	v_fmac_f32_e32 v119, 0x3f317217, v117
	v_cmp_lt_f32_e64 s[0:1], |v117|, s71
	s_nop 1
	v_cndmask_b32_e64 v117, v117, v119, s[0:1]
	v_cndmask_b32_e32 v119, 0, v90, vcc
	v_sub_f32_e32 v117, v117, v119
	v_sub_f32_e32 v117, v118, v117
	ds_read_b128 v[118:121], v102 offset:10240
	ds_read_b128 v[122:125], v102 offset:10256
	v_fmamk_f32 v117, v117, 0x3d800000, v116
	s_waitcnt lgkmcnt(1)
	v_mov_b32_e32 v126, v118
	s_waitcnt lgkmcnt(0)
	v_mov_b32_e32 v127, v122
	v_mov_b32_e32 v122, v119
	v_pk_mul_f32 v[118:119], v[16:17], v[122:123]
	v_mov_b32_e32 v122, v120
	v_pk_fma_f32 v[118:119], v[14:15], v[126:127], v[118:119]
	v_mov_b32_e32 v123, v124
	v_pk_fma_f32 v[118:119], v[12:13], v[122:123], v[118:119]
	v_mov_b32_e32 v124, v121
	v_pk_fma_f32 v[118:119], v[10:11], v[124:125], v[118:119]
	s_nop 0
	v_add_f32_e32 v118, v100, v118
	v_add_f32_e32 v129, v118, v119
	ds_read_b128 v[118:121], v102 offset:10272
	ds_read_b128 v[122:125], v102 offset:10288
	s_waitcnt lgkmcnt(1)
	v_mov_b32_e32 v126, v118
	s_waitcnt lgkmcnt(0)
	v_mov_b32_e32 v127, v122
	v_mov_b32_e32 v122, v119
	v_pk_mul_f32 v[118:119], v[8:9], v[122:123]
	v_mov_b32_e32 v122, v120
	v_pk_fma_f32 v[118:119], v[6:7], v[126:127], v[118:119]
	v_mov_b32_e32 v123, v124
	v_pk_fma_f32 v[118:119], v[2:3], v[122:123], v[118:119]
	v_mov_b32_e32 v124, v121
	v_pk_fma_f32 v[118:119], v[0:1], v[124:125], v[118:119]
	s_nop 0
	v_add_f32_e32 v118, v129, v118
	v_add_f32_e32 v118, v118, v119
	v_min_f32_e32 v119, 0, v118
	v_mul_f32_e64 v118, |v118|, s68
	v_exp_f32_e32 v118, v118
	s_nop 0
	v_add_f32_e32 v118, 1.0, v118
	v_cmp_gt_f32_e32 vcc, s69, v118
	s_nop 1
	v_cndmask_b32_e64 v120, 0, 32, vcc
	v_ldexp_f32 v118, v118, v120
	v_log_f32_e32 v118, v118
	s_nop 0
	v_mul_f32_e32 v120, 0x3f317217, v118
	v_fma_f32 v120, v118, s70, -v120
	v_fmac_f32_e32 v120, 0x3377d1cf, v118
	v_fmac_f32_e32 v120, 0x3f317217, v118
	v_cmp_lt_f32_e64 s[0:1], |v118|, s71
	s_nop 1
	v_cndmask_b32_e64 v118, v118, v120, s[0:1]
	v_cndmask_b32_e32 v120, 0, v90, vcc
	v_sub_f32_e32 v118, v118, v120
	ds_read_b128 v[120:123], v102 offset:10304
	ds_read_b128 v[124:127], v102 offset:10320
	v_sub_f32_e32 v118, v119, v118
	v_fmamk_f32 v118, v118, 0x3d800000, v117
	s_waitcnt lgkmcnt(1)
	v_mov_b32_e32 v130, v120
	s_waitcnt lgkmcnt(0)
	v_mov_b32_e32 v131, v124
	v_mov_b32_e32 v124, v121
	v_pk_mul_f32 v[120:121], v[16:17], v[124:125]
	v_mov_b32_e32 v124, v122
	v_pk_fma_f32 v[120:121], v[14:15], v[130:131], v[120:121]
	v_mov_b32_e32 v125, v126
	v_pk_fma_f32 v[120:121], v[12:13], v[124:125], v[120:121]
	v_mov_b32_e32 v126, v123
	v_pk_fma_f32 v[120:121], v[10:11], v[126:127], v[120:121]
	s_nop 0
	v_add_f32_e32 v119, v100, v120
	v_add_f32_e32 v119, v119, v121
	ds_read_b128 v[120:123], v102 offset:10336
	ds_read_b128 v[124:127], v102 offset:10352
	s_waitcnt lgkmcnt(1)
	v_mov_b32_e32 v130, v120
	s_waitcnt lgkmcnt(0)
	v_mov_b32_e32 v131, v124
	v_mov_b32_e32 v124, v121
	v_pk_mul_f32 v[120:121], v[8:9], v[124:125]
	v_mov_b32_e32 v124, v122
	v_pk_fma_f32 v[120:121], v[6:7], v[130:131], v[120:121]
	v_mov_b32_e32 v125, v126
	v_pk_fma_f32 v[120:121], v[2:3], v[124:125], v[120:121]
	v_mov_b32_e32 v126, v123
	v_pk_fma_f32 v[120:121], v[0:1], v[126:127], v[120:121]
	s_nop 0
	v_add_f32_e32 v119, v119, v120
	v_add_f32_e32 v119, v119, v121
	v_min_f32_e32 v120, 0, v119
	v_mul_f32_e64 v119, |v119|, s68
	v_exp_f32_e32 v119, v119
	s_nop 0
	v_add_f32_e32 v119, 1.0, v119
	v_cmp_gt_f32_e32 vcc, s69, v119
	s_nop 1
	v_cndmask_b32_e64 v121, 0, 32, vcc
	v_ldexp_f32 v119, v119, v121
	v_log_f32_e32 v119, v119
	s_nop 0
	v_mul_f32_e32 v121, 0x3f317217, v119
	v_fma_f32 v121, v119, s70, -v121
	v_fmac_f32_e32 v121, 0x3377d1cf, v119
	v_fmac_f32_e32 v121, 0x3f317217, v119
	v_cmp_lt_f32_e64 s[0:1], |v119|, s71
	s_nop 1
	v_cndmask_b32_e64 v119, v119, v121, s[0:1]
	v_cndmask_b32_e32 v121, 0, v90, vcc
	v_sub_f32_e32 v119, v119, v121
	v_sub_f32_e32 v119, v120, v119
	ds_read_b128 v[120:123], v102 offset:10368
	ds_read_b128 v[124:127], v102 offset:10384
	v_fmamk_f32 v119, v119, 0x3d800000, v118
	s_waitcnt lgkmcnt(1)
	v_mov_b32_e32 v130, v120
	s_waitcnt lgkmcnt(0)
	v_mov_b32_e32 v131, v124
	v_mov_b32_e32 v124, v121
	v_pk_mul_f32 v[120:121], v[16:17], v[124:125]
	v_mov_b32_e32 v124, v122
	v_pk_fma_f32 v[120:121], v[14:15], v[130:131], v[120:121]
	v_mov_b32_e32 v125, v126
	v_pk_fma_f32 v[120:121], v[12:13], v[124:125], v[120:121]
	v_mov_b32_e32 v126, v123
	v_pk_fma_f32 v[120:121], v[10:11], v[126:127], v[120:121]
	s_nop 0
	v_add_f32_e32 v120, v100, v120
	v_add_f32_e32 v129, v120, v121
	ds_read_b128 v[120:123], v102 offset:10400
	ds_read_b128 v[124:127], v102 offset:10416
	s_waitcnt lgkmcnt(1)
	v_mov_b32_e32 v130, v120
	s_waitcnt lgkmcnt(0)
; #define LAS __attribute__((address_space(3)))
; __device__ __forceinline__ void gla_upd_unit(LAS unsigned char* wl, const bf16* PROJ, const float* R, const float* w_gk2, const float* b_gk, float* UPD, float* DEC, int unit, int lane) {
;     ...
;     float la[64]; float tot = 0.f;
; #pragma unroll
;     for (int t = 0; t < 64; ++t) {
;         const LAS f32x4* rr = (const LAS f32x4*)(wl + 9216) + t * 4;
;         float z = bias;
; #pragma unroll
;         for (int q = 0; q < 4; ++q) { const f32x4 rv = rr[q]; z += rv[0] * w[4 * q] + rv[1] * w[4 * q + 1] + rv[2] * w[4 * q + 2] + rv[3] * w[4 * q + 3]; }
;         la[t] = (fminf(z, 0.f) - __logf(1.0f + __expf(-fabsf(z)))) * (1.0f / 16.0f);
;         tot += la[t];
;     }
	v_mov_b32_e32 v131, v124
	v_mov_b32_e32 v124, v121
	v_pk_mul_f32 v[120:121], v[8:9], v[124:125]
	v_mov_b32_e32 v124, v122
	v_pk_fma_f32 v[120:121], v[6:7], v[130:131], v[120:121]
	v_mov_b32_e32 v125, v126
	v_pk_fma_f32 v[120:121], v[2:3], v[124:125], v[120:121]
	v_mov_b32_e32 v126, v123
	v_pk_fma_f32 v[120:121], v[0:1], v[126:127], v[120:121]
	s_nop 0
	v_add_f32_e32 v120, v129, v120
	v_add_f32_e32 v120, v120, v121
	v_min_f32_e32 v121, 0, v120
	v_mul_f32_e64 v120, |v120|, s68
	v_exp_f32_e32 v120, v120
	s_nop 0
	v_add_f32_e32 v120, 1.0, v120
	v_cmp_gt_f32_e32 vcc, s69, v120
	s_nop 1
	v_cndmask_b32_e64 v122, 0, 32, vcc
	v_ldexp_f32 v120, v120, v122
	v_log_f32_e32 v120, v120
	s_nop 0
	v_mul_f32_e32 v122, 0x3f317217, v120
	v_fma_f32 v122, v120, s70, -v122
	v_fmac_f32_e32 v122, 0x3377d1cf, v120
	v_fmac_f32_e32 v122, 0x3f317217, v120
	v_cmp_lt_f32_e64 s[0:1], |v120|, s71
	s_nop 1
	v_cndmask_b32_e64 v120, v120, v122, s[0:1]
	v_cndmask_b32_e32 v122, 0, v90, vcc
	v_sub_f32_e32 v120, v120, v122
	ds_read_b128 v[122:125], v102 offset:10432
	ds_read_b128 v[130:133], v102 offset:10448
	v_sub_f32_e32 v120, v121, v120
	v_fmamk_f32 v120, v120, 0x3d800000, v119
	s_waitcnt lgkmcnt(1)
	v_mov_b32_e32 v126, v122
	s_waitcnt lgkmcnt(0)
	v_mov_b32_e32 v127, v130
	v_mov_b32_e32 v130, v123
	v_pk_mul_f32 v[122:123], v[16:17], v[130:131]
	s_nop 0
	v_pk_fma_f32 v[122:123], v[14:15], v[126:127], v[122:123]
	v_mov_b32_e32 v126, v124
	v_mov_b32_e32 v127, v132
	v_pk_fma_f32 v[122:123], v[12:13], v[126:127], v[122:123]
	v_mov_b32_e32 v132, v125
	v_pk_fma_f32 v[122:123], v[10:11], v[132:133], v[122:123]
	s_nop 0
	v_add_f32_e32 v121, v100, v122
	v_add_f32_e32 v121, v121, v123
	ds_read_b128 v[122:125], v102 offset:10464
	ds_read_b128 v[130:133], v102 offset:10480
	s_waitcnt lgkmcnt(1)
	v_mov_b32_e32 v126, v122
	s_waitcnt lgkmcnt(0)
	v_mov_b32_e32 v127, v130
	v_mov_b32_e32 v130, v123
	v_pk_mul_f32 v[122:123], v[8:9], v[130:131]
	s_nop 0
	v_pk_fma_f32 v[122:123], v[6:7], v[126:127], v[122:123]
	v_mov_b32_e32 v126, v124
	v_mov_b32_e32 v127, v132
	v_pk_fma_f32 v[122:123], v[2:3], v[126:127], v[122:123]
	v_mov_b32_e32 v132, v125
	v_pk_fma_f32 v[122:123], v[0:1], v[132:133], v[122:123]
	s_nop 0
	v_add_f32_e32 v121, v121, v122
	v_add_f32_e32 v121, v121, v123
	v_min_f32_e32 v122, 0, v121
	v_mul_f32_e64 v121, |v121|, s68
	v_exp_f32_e32 v121, v121
	s_nop 0
	v_add_f32_e32 v121, 1.0, v121
	v_cmp_gt_f32_e32 vcc, s69, v121
	s_nop 1
	v_cndmask_b32_e64 v123, 0, 32, vcc
	v_ldexp_f32 v121, v121, v123
	v_log_f32_e32 v121, v121
	s_nop 0
	v_mul_f32_e32 v123, 0x3f317217, v121
	v_fma_f32 v123, v121, s70, -v123
	v_fmac_f32_e32 v123, 0x3377d1cf, v121
	v_fmac_f32_e32 v123, 0x3f317217, v121
	v_cmp_lt_f32_e64 s[0:1], |v121|, s71
	s_nop 1
	v_cndmask_b32_e64 v121, v121, v123, s[0:1]
	v_cndmask_b32_e32 v123, 0, v90, vcc
	v_sub_f32_e32 v121, v121, v123
	v_sub_f32_e32 v121, v122, v121
	ds_read_b128 v[122:125], v102 offset:10496
	ds_read_b128 v[130:133], v102 offset:10512
	v_fmamk_f32 v121, v121, 0x3d800000, v120
	s_waitcnt lgkmcnt(1)
	v_mov_b32_e32 v126, v122
	s_waitcnt lgkmcnt(0)
	v_mov_b32_e32 v127, v130
	v_mov_b32_e32 v130, v123
	v_pk_mul_f32 v[122:123], v[16:17], v[130:131]
	s_nop 0
	v_pk_fma_f32 v[122:123], v[14:15], v[126:127], v[122:123]
	v_mov_b32_e32 v126, v124
	v_mov_b32_e32 v127, v132
	v_pk_fma_f32 v[122:123], v[12:13], v[126:127], v[122:123]
	v_mov_b32_e32 v132, v125
	v_pk_fma_f32 v[122:123], v[10:11], v[132:133], v[122:123]
	s_nop 0
	v_add_f32_e32 v122, v100, v122
	v_add_f32_e32 v129, v122, v123
	ds_read_b128 v[122:125], v102 offset:10528
	ds_read_b128 v[130:133], v102 offset:10544
	s_waitcnt lgkmcnt(1)
	v_mov_b32_e32 v126, v122
	s_waitcnt lgkmcnt(0)
	v_mov_b32_e32 v127, v130
	v_mov_b32_e32 v130, v123
	v_pk_mul_f32 v[122:123], v[8:9], v[130:131]
	s_nop 0
	v_pk_fma_f32 v[122:123], v[6:7], v[126:127], v[122:123]
	v_mov_b32_e32 v126, v124
	v_mov_b32_e32 v127, v132
	v_pk_fma_f32 v[122:123], v[2:3], v[126:127], v[122:123]
	v_mov_b32_e32 v132, v125
	v_pk_fma_f32 v[122:123], v[0:1], v[132:133], v[122:123]
	s_nop 0
	v_add_f32_e32 v122, v129, v122
	v_add_f32_e32 v122, v122, v123
	v_min_f32_e32 v123, 0, v122
	v_mul_f32_e64 v122, |v122|, s68
	v_exp_f32_e32 v122, v122
	s_nop 0
	v_add_f32_e32 v122, 1.0, v122
	v_cmp_gt_f32_e32 vcc, s69, v122
	s_nop 1
	v_cndmask_b32_e64 v124, 0, 32, vcc
	v_ldexp_f32 v122, v122, v124
	v_log_f32_e32 v122, v122
	s_nop 0
	v_mul_f32_e32 v124, 0x3f317217, v122
	v_fma_f32 v124, v122, s70, -v124
	v_fmac_f32_e32 v124, 0x3377d1cf, v122
	v_fmac_f32_e32 v124, 0x3f317217, v122
	v_cmp_lt_f32_e64 s[0:1], |v122|, s71
	s_nop 1
	v_cndmask_b32_e64 v122, v122, v124, s[0:1]
	v_cndmask_b32_e32 v124, 0, v90, vcc
	v_sub_f32_e32 v122, v122, v124
	ds_read_b128 v[124:127], v102 offset:10560
	ds_read_b128 v[130:133], v102 offset:10576
	v_sub_f32_e32 v122, v123, v122
	v_fmamk_f32 v122, v122, 0x3d800000, v121
	s_waitcnt lgkmcnt(1)
	v_mov_b32_e32 v134, v124
	s_waitcnt lgkmcnt(0)
	v_mov_b32_e32 v135, v130
	v_mov_b32_e32 v130, v125
	v_pk_mul_f32 v[124:125], v[16:17], v[130:131]
	v_mov_b32_e32 v130, v126
	v_pk_fma_f32 v[124:125], v[14:15], v[134:135], v[124:125]
	v_mov_b32_e32 v131, v132
	v_pk_fma_f32 v[124:125], v[12:13], v[130:131], v[124:125]
	v_mov_b32_e32 v132, v127
	v_pk_fma_f32 v[124:125], v[10:11], v[132:133], v[124:125]
	s_nop 0
	v_add_f32_e32 v123, v100, v124
	v_add_f32_e32 v123, v123, v125
	ds_read_b128 v[124:127], v102 offset:10592
	ds_read_b128 v[130:133], v102 offset:10608
	s_waitcnt lgkmcnt(1)
	v_mov_b32_e32 v134, v124
	s_waitcnt lgkmcnt(0)
; #define LAS __attribute__((address_space(3)))
; __device__ __forceinline__ void gla_upd_unit(LAS unsigned char* wl, const bf16* PROJ, const float* R, const float* w_gk2, const float* b_gk, float* UPD, float* DEC, int unit, int lane) {
;     ...
;     float la[64]; float tot = 0.f;
; #pragma unroll
;     for (int t = 0; t < 64; ++t) {
;         const LAS f32x4* rr = (const LAS f32x4*)(wl + 9216) + t * 4;
;         float z = bias;
; #pragma unroll
;         for (int q = 0; q < 4; ++q) { const f32x4 rv = rr[q]; z += rv[0] * w[4 * q] + rv[1] * w[4 * q + 1] + rv[2] * w[4 * q + 2] + rv[3] * w[4 * q + 3]; }
;         la[t] = (fminf(z, 0.f) - __logf(1.0f + __expf(-fabsf(z)))) * (1.0f / 16.0f);
;         tot += la[t];
;     }
	v_mov_b32_e32 v135, v130
	v_mov_b32_e32 v130, v125
	v_pk_mul_f32 v[124:125], v[8:9], v[130:131]
	v_mov_b32_e32 v130, v126
	v_pk_fma_f32 v[124:125], v[6:7], v[134:135], v[124:125]
	v_mov_b32_e32 v131, v132
	v_pk_fma_f32 v[124:125], v[2:3], v[130:131], v[124:125]
	v_mov_b32_e32 v132, v127
	v_pk_fma_f32 v[124:125], v[0:1], v[132:133], v[124:125]
	s_nop 0
	v_add_f32_e32 v123, v123, v124
	v_add_f32_e32 v123, v123, v125
	v_min_f32_e32 v124, 0, v123
	v_mul_f32_e64 v123, |v123|, s68
	v_exp_f32_e32 v123, v123
	s_nop 0
	v_add_f32_e32 v123, 1.0, v123
	v_cmp_gt_f32_e32 vcc, s69, v123
	s_nop 1
	v_cndmask_b32_e64 v125, 0, 32, vcc
	v_ldexp_f32 v123, v123, v125
	v_log_f32_e32 v123, v123
	s_nop 0
	v_mul_f32_e32 v125, 0x3f317217, v123
	v_fma_f32 v125, v123, s70, -v125
	v_fmac_f32_e32 v125, 0x3377d1cf, v123
	v_fmac_f32_e32 v125, 0x3f317217, v123
	v_cmp_lt_f32_e64 s[0:1], |v123|, s71
	s_nop 1
	v_cndmask_b32_e64 v123, v123, v125, s[0:1]
	v_cndmask_b32_e32 v125, 0, v90, vcc
	v_sub_f32_e32 v123, v123, v125
	v_sub_f32_e32 v123, v124, v123
	ds_read_b128 v[124:127], v102 offset:10624
	ds_read_b128 v[130:133], v102 offset:10640
	v_fmamk_f32 v123, v123, 0x3d800000, v122
	s_waitcnt lgkmcnt(1)
	v_mov_b32_e32 v134, v124
	s_waitcnt lgkmcnt(0)
	v_mov_b32_e32 v135, v130
	v_mov_b32_e32 v130, v125
	v_pk_mul_f32 v[124:125], v[16:17], v[130:131]
	v_mov_b32_e32 v130, v126
	v_pk_fma_f32 v[124:125], v[14:15], v[134:135], v[124:125]
	v_mov_b32_e32 v131, v132
	v_pk_fma_f32 v[124:125], v[12:13], v[130:131], v[124:125]
	v_mov_b32_e32 v132, v127
	v_pk_fma_f32 v[124:125], v[10:11], v[132:133], v[124:125]
	s_nop 0
	v_add_f32_e32 v124, v100, v124
	v_add_f32_e32 v129, v124, v125
	ds_read_b128 v[124:127], v102 offset:10656
	ds_read_b128 v[130:133], v102 offset:10672
	s_waitcnt lgkmcnt(1)
	v_mov_b32_e32 v134, v124
	s_waitcnt lgkmcnt(0)
	v_mov_b32_e32 v135, v130
	v_mov_b32_e32 v130, v125
	v_pk_mul_f32 v[124:125], v[8:9], v[130:131]
	v_mov_b32_e32 v130, v126
	v_pk_fma_f32 v[124:125], v[6:7], v[134:135], v[124:125]
	v_mov_b32_e32 v131, v132
	v_pk_fma_f32 v[124:125], v[2:3], v[130:131], v[124:125]
	v_mov_b32_e32 v132, v127
	v_pk_fma_f32 v[124:125], v[0:1], v[132:133], v[124:125]
	ds_read_b128 v[130:133], v102 offset:10688
	ds_read_b128 v[134:137], v102 offset:10704
	v_add_f32_e32 v124, v129, v124
	v_add_f32_e32 v124, v124, v125
	v_min_f32_e32 v125, 0, v124
	v_mul_f32_e64 v124, |v124|, s68
	v_exp_f32_e32 v124, v124
	s_waitcnt lgkmcnt(0)
	v_mov_b32_e32 v127, v134
	v_mov_b32_e32 v134, v131
	v_add_f32_e32 v124, 1.0, v124
	v_cmp_gt_f32_e32 vcc, s69, v124
	s_nop 1
	v_cndmask_b32_e64 v126, 0, 32, vcc
	v_ldexp_f32 v124, v124, v126
	v_log_f32_e32 v124, v124
	s_nop 0
	v_mul_f32_e32 v126, 0x3f317217, v124
	v_fma_f32 v126, v124, s70, -v126
	v_fmac_f32_e32 v126, 0x3377d1cf, v124
	v_fmac_f32_e32 v126, 0x3f317217, v124
	v_cmp_lt_f32_e64 s[0:1], |v124|, s71
	s_nop 1
	v_cndmask_b32_e64 v124, v124, v126, s[0:1]
	v_cndmask_b32_e32 v126, 0, v90, vcc
	v_sub_f32_e32 v124, v124, v126
	v_mov_b32_e32 v126, v130
	v_pk_mul_f32 v[130:131], v[16:17], v[134:135]
	v_sub_f32_e32 v124, v125, v124
	v_pk_fma_f32 v[126:127], v[14:15], v[126:127], v[130:131]
	v_mov_b32_e32 v130, v132
	v_mov_b32_e32 v131, v136
	v_pk_fma_f32 v[126:127], v[12:13], v[130:131], v[126:127]
	v_mov_b32_e32 v136, v133
	v_pk_fma_f32 v[126:127], v[10:11], v[136:137], v[126:127]
	ds_read_b128 v[130:133], v102 offset:10720
	ds_read_b128 v[134:137], v102 offset:10736
	v_add_f32_e32 v125, v100, v126
	v_add_f32_e32 v125, v125, v127
	v_fmamk_f32 v124, v124, 0x3d800000, v123
	s_waitcnt lgkmcnt(1)
	v_mov_b32_e32 v126, v130
	s_waitcnt lgkmcnt(0)
	v_mov_b32_e32 v127, v134
	v_mov_b32_e32 v134, v131
	v_pk_mul_f32 v[130:131], v[8:9], v[134:135]
	s_nop 0
	v_pk_fma_f32 v[126:127], v[6:7], v[126:127], v[130:131]
	v_mov_b32_e32 v130, v132
	v_mov_b32_e32 v131, v136
	v_pk_fma_f32 v[126:127], v[2:3], v[130:131], v[126:127]
	v_mov_b32_e32 v136, v133
	v_pk_fma_f32 v[126:127], v[0:1], v[136:137], v[126:127]
	ds_read_b128 v[130:133], v102 offset:10752
	ds_read_b128 v[134:137], v102 offset:10768
	v_add_f32_e32 v125, v125, v126
	v_add_f32_e32 v125, v125, v127
	v_min_f32_e32 v126, 0, v125
	v_mul_f32_e64 v125, |v125|, s68
	v_exp_f32_e32 v125, v125
	s_nop 0
	v_add_f32_e32 v125, 1.0, v125
	v_cmp_gt_f32_e32 vcc, s69, v125
	s_nop 1
	v_cndmask_b32_e64 v127, 0, 32, vcc
	v_ldexp_f32 v125, v125, v127
	v_log_f32_e32 v125, v125
	s_nop 0
	v_mul_f32_e32 v127, 0x3f317217, v125
	v_fma_f32 v127, v125, s70, -v127
	v_fmac_f32_e32 v127, 0x3377d1cf, v125
	v_fmac_f32_e32 v127, 0x3f317217, v125
	v_cmp_lt_f32_e64 s[0:1], |v125|, s71
	s_nop 1
	v_cndmask_b32_e64 v125, v125, v127, s[0:1]
	v_cndmask_b32_e32 v127, 0, v90, vcc
	v_sub_f32_e32 v125, v125, v127
	s_waitcnt lgkmcnt(0)
	v_mov_b32_e32 v127, v134
	v_mov_b32_e32 v134, v131
	v_sub_f32_e32 v125, v126, v125
	v_mov_b32_e32 v126, v130
	v_pk_mul_f32 v[130:131], v[16:17], v[134:135]
	v_fmamk_f32 v125, v125, 0x3d800000, v124
	v_pk_fma_f32 v[126:127], v[14:15], v[126:127], v[130:131]
	v_mov_b32_e32 v130, v132
	v_mov_b32_e32 v131, v136
	v_pk_fma_f32 v[126:127], v[12:13], v[130:131], v[126:127]
	v_mov_b32_e32 v136, v133
	v_pk_fma_f32 v[126:127], v[10:11], v[136:137], v[126:127]
	ds_read_b128 v[130:133], v102 offset:10784
	ds_read_b128 v[134:137], v102 offset:10800
	v_add_f32_e32 v126, v100, v126
	v_add_f32_e32 v129, v126, v127
	s_waitcnt lgkmcnt(1)
	v_mov_b32_e32 v126, v130
	s_waitcnt lgkmcnt(0)
; #define LAS __attribute__((address_space(3)))
; __device__ __forceinline__ void gla_upd_unit(LAS unsigned char* wl, const bf16* PROJ, const float* R, const float* w_gk2, const float* b_gk, float* UPD, float* DEC, int unit, int lane) {
;     ...
;     float la[64]; float tot = 0.f;
; #pragma unroll
;     for (int t = 0; t < 64; ++t) {
;         const LAS f32x4* rr = (const LAS f32x4*)(wl + 9216) + t * 4;
;         float z = bias;
; #pragma unroll
;         for (int q = 0; q < 4; ++q) { const f32x4 rv = rr[q]; z += rv[0] * w[4 * q] + rv[1] * w[4 * q + 1] + rv[2] * w[4 * q + 2] + rv[3] * w[4 * q + 3]; }
;         la[t] = (fminf(z, 0.f) - __logf(1.0f + __expf(-fabsf(z)))) * (1.0f / 16.0f);
;         tot += la[t];
;     }
	v_mov_b32_e32 v127, v134
	v_mov_b32_e32 v134, v131
	v_pk_mul_f32 v[130:131], v[8:9], v[134:135]
	s_nop 0
	v_pk_fma_f32 v[126:127], v[6:7], v[126:127], v[130:131]
	v_mov_b32_e32 v130, v132
	v_mov_b32_e32 v131, v136
	v_pk_fma_f32 v[126:127], v[2:3], v[130:131], v[126:127]
	v_mov_b32_e32 v136, v133
	v_pk_fma_f32 v[126:127], v[0:1], v[136:137], v[126:127]
	ds_read_b128 v[130:133], v102 offset:10816
	ds_read_b128 v[134:137], v102 offset:10832
	v_add_f32_e32 v126, v129, v126
	v_add_f32_e32 v126, v126, v127
	v_min_f32_e32 v127, 0, v126
	v_mul_f32_e64 v126, |v126|, s68
	v_exp_f32_e32 v126, v126
	s_waitcnt lgkmcnt(0)
	v_mov_b32_e32 v139, v134
	v_mov_b32_e32 v134, v131
	v_mov_b32_e32 v138, v130
	v_add_f32_e32 v126, 1.0, v126
	v_cmp_gt_f32_e32 vcc, s69, v126
	v_pk_mul_f32 v[130:131], v[16:17], v[134:135]
	v_mov_b32_e32 v134, v132
	v_cndmask_b32_e64 v129, 0, 32, vcc
	v_ldexp_f32 v126, v126, v129
	v_log_f32_e32 v126, v126
	v_pk_fma_f32 v[130:131], v[14:15], v[138:139], v[130:131]
	v_mov_b32_e32 v135, v136
	v_pk_fma_f32 v[130:131], v[12:13], v[134:135], v[130:131]
	v_mul_f32_e32 v129, 0x3f317217, v126
	v_fma_f32 v129, v126, s70, -v129
	v_fmac_f32_e32 v129, 0x3377d1cf, v126
	v_fmac_f32_e32 v129, 0x3f317217, v126
	v_cmp_lt_f32_e64 s[0:1], |v126|, s71
	v_mov_b32_e32 v136, v133
	v_pk_fma_f32 v[130:131], v[10:11], v[136:137], v[130:131]
	v_cndmask_b32_e64 v126, v126, v129, s[0:1]
	v_cndmask_b32_e32 v129, 0, v90, vcc
	v_sub_f32_e32 v126, v126, v129
	v_sub_f32_e32 v126, v127, v126
	v_add_f32_e32 v127, v100, v130
	v_add_f32_e32 v127, v127, v131
	ds_read_b128 v[130:133], v102 offset:10848
	ds_read_b128 v[134:137], v102 offset:10864
	v_fmamk_f32 v126, v126, 0x3d800000, v125
	s_waitcnt lgkmcnt(1)
	v_mov_b32_e32 v138, v130
	s_waitcnt lgkmcnt(0)
	v_mov_b32_e32 v139, v134
	v_mov_b32_e32 v134, v131
	v_pk_mul_f32 v[130:131], v[8:9], v[134:135]
	v_mov_b32_e32 v134, v132
	v_pk_fma_f32 v[130:131], v[6:7], v[138:139], v[130:131]
	v_mov_b32_e32 v135, v136
	v_pk_fma_f32 v[130:131], v[2:3], v[134:135], v[130:131]
	v_mov_b32_e32 v136, v133
	v_pk_fma_f32 v[130:131], v[0:1], v[136:137], v[130:131]
	s_nop 0
	v_add_f32_e32 v127, v127, v130
	v_add_f32_e32 v127, v127, v131
	v_min_f32_e32 v129, 0, v127
	v_mul_f32_e64 v127, |v127|, s68
	v_exp_f32_e32 v127, v127
	s_nop 0
	v_add_f32_e32 v127, 1.0, v127
	v_cmp_gt_f32_e32 vcc, s69, v127
	s_nop 1
	v_cndmask_b32_e64 v130, 0, 32, vcc
	v_ldexp_f32 v127, v127, v130
	v_log_f32_e32 v127, v127
	s_nop 0
	v_mul_f32_e32 v130, 0x3f317217, v127
	v_fma_f32 v130, v127, s70, -v130
	v_fmac_f32_e32 v130, 0x3377d1cf, v127
	v_fmac_f32_e32 v130, 0x3f317217, v127
	v_cmp_lt_f32_e64 s[0:1], |v127|, s71
	s_nop 1
	v_cndmask_b32_e64 v127, v127, v130, s[0:1]
	v_cndmask_b32_e32 v130, 0, v90, vcc
	v_sub_f32_e32 v127, v127, v130
	ds_read_b128 v[130:133], v102 offset:10880
	ds_read_b128 v[134:137], v102 offset:10896
	v_sub_f32_e32 v127, v129, v127
	v_fmamk_f32 v127, v127, 0x3d800000, v126
	s_waitcnt lgkmcnt(1)
	v_mov_b32_e32 v138, v130
	s_waitcnt lgkmcnt(0)
	v_mov_b32_e32 v139, v134
	v_mov_b32_e32 v134, v131
	v_pk_mul_f32 v[130:131], v[16:17], v[134:135]
	v_mov_b32_e32 v134, v132
	v_pk_fma_f32 v[130:131], v[14:15], v[138:139], v[130:131]
	v_mov_b32_e32 v135, v136
	v_pk_fma_f32 v[130:131], v[12:13], v[134:135], v[130:131]
	v_mov_b32_e32 v136, v133
	v_pk_fma_f32 v[130:131], v[10:11], v[136:137], v[130:131]
	s_nop 0
	v_add_f32_e32 v129, v100, v130
	v_add_f32_e32 v129, v129, v131
	ds_read_b128 v[130:133], v102 offset:10912
	ds_read_b128 v[134:137], v102 offset:10928
	s_waitcnt lgkmcnt(1)
	v_mov_b32_e32 v138, v130
	s_waitcnt lgkmcnt(0)
	v_mov_b32_e32 v139, v134
	v_mov_b32_e32 v134, v131
	v_pk_mul_f32 v[130:131], v[8:9], v[134:135]
	v_mov_b32_e32 v134, v132
	v_pk_fma_f32 v[130:131], v[6:7], v[138:139], v[130:131]
	v_mov_b32_e32 v135, v136
	v_pk_fma_f32 v[130:131], v[2:3], v[134:135], v[130:131]
	v_mov_b32_e32 v136, v133
	v_pk_fma_f32 v[130:131], v[0:1], v[136:137], v[130:131]
	s_nop 0
	v_add_f32_e32 v129, v129, v130
	v_add_f32_e32 v129, v129, v131
	v_min_f32_e32 v130, 0, v129
	v_mul_f32_e64 v129, |v129|, s68
	v_exp_f32_e32 v129, v129
	s_nop 0
	v_add_f32_e32 v129, 1.0, v129
	v_cmp_gt_f32_e32 vcc, s69, v129
	s_nop 1
	v_cndmask_b32_e64 v131, 0, 32, vcc
	v_ldexp_f32 v129, v129, v131
	v_log_f32_e32 v129, v129
	s_nop 0
	v_mul_f32_e32 v131, 0x3f317217, v129
	v_fma_f32 v131, v129, s70, -v131
	v_fmac_f32_e32 v131, 0x3377d1cf, v129
	v_fmac_f32_e32 v131, 0x3f317217, v129
	v_cmp_lt_f32_e64 s[0:1], |v129|, s71
	s_nop 1
	v_cndmask_b32_e64 v129, v129, v131, s[0:1]
	v_cndmask_b32_e32 v131, 0, v90, vcc
	v_sub_f32_e32 v129, v129, v131
	v_sub_f32_e32 v129, v130, v129
	ds_read_b128 v[130:133], v102 offset:10944
	ds_read_b128 v[134:137], v102 offset:10960
	v_fmamk_f32 v129, v129, 0x3d800000, v127
	s_waitcnt lgkmcnt(1)
	v_mov_b32_e32 v138, v130
	s_waitcnt lgkmcnt(0)
	v_mov_b32_e32 v139, v134
	v_mov_b32_e32 v134, v131
	v_pk_mul_f32 v[130:131], v[16:17], v[134:135]
	v_mov_b32_e32 v134, v132
	v_pk_fma_f32 v[130:131], v[14:15], v[138:139], v[130:131]
	v_mov_b32_e32 v135, v136
	v_pk_fma_f32 v[130:131], v[12:13], v[134:135], v[130:131]
	v_mov_b32_e32 v136, v133
	v_pk_fma_f32 v[130:131], v[10:11], v[136:137], v[130:131]
	s_nop 0
	v_add_f32_e32 v130, v100, v130
	v_add_f32_e32 v140, v130, v131
	ds_read_b128 v[130:133], v102 offset:10976
	ds_read_b128 v[134:137], v102 offset:10992
	s_waitcnt lgkmcnt(1)
	v_mov_b32_e32 v138, v130
	s_waitcnt lgkmcnt(0)
; #define LAS __attribute__((address_space(3)))
; __device__ __forceinline__ void gla_upd_unit(LAS unsigned char* wl, const bf16* PROJ, const float* R, const float* w_gk2, const float* b_gk, float* UPD, float* DEC, int unit, int lane) {
;     ...
;     float la[64]; float tot = 0.f;
; #pragma unroll
;     for (int t = 0; t < 64; ++t) {
;         const LAS f32x4* rr = (const LAS f32x4*)(wl + 9216) + t * 4;
;         float z = bias;
; #pragma unroll
;         for (int q = 0; q < 4; ++q) { const f32x4 rv = rr[q]; z += rv[0] * w[4 * q] + rv[1] * w[4 * q + 1] + rv[2] * w[4 * q + 2] + rv[3] * w[4 * q + 3]; }
;         la[t] = (fminf(z, 0.f) - __logf(1.0f + __expf(-fabsf(z)))) * (1.0f / 16.0f);
;         tot += la[t];
;     }
	v_mov_b32_e32 v139, v134
	v_mov_b32_e32 v134, v131
	v_pk_mul_f32 v[130:131], v[8:9], v[134:135]
	v_mov_b32_e32 v134, v132
	v_pk_fma_f32 v[130:131], v[6:7], v[138:139], v[130:131]
	v_mov_b32_e32 v135, v136
	v_pk_fma_f32 v[130:131], v[2:3], v[134:135], v[130:131]
	v_mov_b32_e32 v136, v133
	v_pk_fma_f32 v[130:131], v[0:1], v[136:137], v[130:131]
	s_nop 0
	v_add_f32_e32 v130, v140, v130
	v_add_f32_e32 v130, v130, v131
	v_min_f32_e32 v131, 0, v130
	v_mul_f32_e64 v130, |v130|, s68
	v_exp_f32_e32 v130, v130
	s_nop 0
	v_add_f32_e32 v130, 1.0, v130
	v_cmp_gt_f32_e32 vcc, s69, v130
	s_nop 1
	v_cndmask_b32_e64 v132, 0, 32, vcc
	v_ldexp_f32 v130, v130, v132
	v_log_f32_e32 v130, v130
	s_nop 0
	v_mul_f32_e32 v132, 0x3f317217, v130
	v_fma_f32 v132, v130, s70, -v132
	v_fmac_f32_e32 v132, 0x3377d1cf, v130
	v_fmac_f32_e32 v132, 0x3f317217, v130
	v_cmp_lt_f32_e64 s[0:1], |v130|, s71
	s_nop 1
	v_cndmask_b32_e64 v130, v130, v132, s[0:1]
	v_cndmask_b32_e32 v132, 0, v90, vcc
	v_sub_f32_e32 v130, v130, v132
	ds_read_b128 v[132:135], v102 offset:11008
	ds_read_b128 v[136:139], v102 offset:11024
	v_sub_f32_e32 v130, v131, v130
	v_fmamk_f32 v130, v130, 0x3d800000, v129
	s_waitcnt lgkmcnt(1)
	v_mov_b32_e32 v140, v132
	s_waitcnt lgkmcnt(0)
	v_mov_b32_e32 v141, v136
	v_mov_b32_e32 v136, v133
	v_pk_mul_f32 v[132:133], v[16:17], v[136:137]
	v_mov_b32_e32 v136, v134
	v_pk_fma_f32 v[132:133], v[14:15], v[140:141], v[132:133]
	v_mov_b32_e32 v137, v138
	v_pk_fma_f32 v[132:133], v[12:13], v[136:137], v[132:133]
	v_mov_b32_e32 v138, v135
	v_pk_fma_f32 v[132:133], v[10:11], v[138:139], v[132:133]
	s_nop 0
	v_add_f32_e32 v131, v100, v132
	v_add_f32_e32 v131, v131, v133
	ds_read_b128 v[132:135], v102 offset:11040
	ds_read_b128 v[136:139], v102 offset:11056
	s_waitcnt lgkmcnt(1)
	v_mov_b32_e32 v140, v132
	s_waitcnt lgkmcnt(0)
	v_mov_b32_e32 v141, v136
	v_mov_b32_e32 v136, v133
	v_pk_mul_f32 v[132:133], v[8:9], v[136:137]
	v_mov_b32_e32 v136, v134
	v_pk_fma_f32 v[132:133], v[6:7], v[140:141], v[132:133]
	v_mov_b32_e32 v137, v138
	v_pk_fma_f32 v[132:133], v[2:3], v[136:137], v[132:133]
	v_mov_b32_e32 v138, v135
	v_pk_fma_f32 v[132:133], v[0:1], v[138:139], v[132:133]
	s_nop 0
	v_add_f32_e32 v131, v131, v132
	v_add_f32_e32 v131, v131, v133
	v_min_f32_e32 v132, 0, v131
	v_mul_f32_e64 v131, |v131|, s68
	v_exp_f32_e32 v131, v131
	s_nop 0
	v_add_f32_e32 v131, 1.0, v131
	v_cmp_gt_f32_e32 vcc, s69, v131
	s_nop 1
	v_cndmask_b32_e64 v133, 0, 32, vcc
	v_ldexp_f32 v131, v131, v133
	v_log_f32_e32 v131, v131
	s_nop 0
	v_mul_f32_e32 v133, 0x3f317217, v131
	v_fma_f32 v133, v131, s70, -v133
	v_fmac_f32_e32 v133, 0x3377d1cf, v131
	v_fmac_f32_e32 v133, 0x3f317217, v131
	v_cmp_lt_f32_e64 s[0:1], |v131|, s71
	s_nop 1
	v_cndmask_b32_e64 v131, v131, v133, s[0:1]
	v_cndmask_b32_e32 v133, 0, v90, vcc
	v_sub_f32_e32 v131, v131, v133
	v_sub_f32_e32 v131, v132, v131
	ds_read_b128 v[132:135], v102 offset:11072
	ds_read_b128 v[136:139], v102 offset:11088
	v_fmamk_f32 v131, v131, 0x3d800000, v130
	s_waitcnt lgkmcnt(1)
	v_mov_b32_e32 v140, v132
	s_waitcnt lgkmcnt(0)
	v_mov_b32_e32 v141, v136
	v_mov_b32_e32 v136, v133
	v_pk_mul_f32 v[132:133], v[16:17], v[136:137]
	v_mov_b32_e32 v136, v134
	v_pk_fma_f32 v[132:133], v[14:15], v[140:141], v[132:133]
	v_mov_b32_e32 v137, v138
	v_pk_fma_f32 v[132:133], v[12:13], v[136:137], v[132:133]
	v_mov_b32_e32 v138, v135
	v_pk_fma_f32 v[132:133], v[10:11], v[138:139], v[132:133]
	s_nop 0
	v_add_f32_e32 v132, v100, v132
	v_add_f32_e32 v142, v132, v133
	ds_read_b128 v[132:135], v102 offset:11104
	ds_read_b128 v[136:139], v102 offset:11120
	s_waitcnt lgkmcnt(1)
	v_mov_b32_e32 v140, v132
	s_waitcnt lgkmcnt(0)
	v_mov_b32_e32 v141, v136
	v_mov_b32_e32 v136, v133
	v_pk_mul_f32 v[132:133], v[8:9], v[136:137]
	v_mov_b32_e32 v136, v134
	v_pk_fma_f32 v[132:133], v[6:7], v[140:141], v[132:133]
	v_mov_b32_e32 v137, v138
	v_pk_fma_f32 v[132:133], v[2:3], v[136:137], v[132:133]
	v_mov_b32_e32 v138, v135
	v_pk_fma_f32 v[132:133], v[0:1], v[138:139], v[132:133]
	s_nop 0
	v_add_f32_e32 v132, v142, v132
	v_add_f32_e32 v132, v132, v133
	v_min_f32_e32 v133, 0, v132
	v_mul_f32_e64 v132, |v132|, s68
	v_exp_f32_e32 v132, v132
	s_nop 0
	v_add_f32_e32 v132, 1.0, v132
	v_cmp_gt_f32_e32 vcc, s69, v132
	s_nop 1
	v_cndmask_b32_e64 v134, 0, 32, vcc
	v_ldexp_f32 v132, v132, v134
	v_log_f32_e32 v132, v132
	s_nop 0
	v_mul_f32_e32 v134, 0x3f317217, v132
	v_fma_f32 v134, v132, s70, -v134
	v_fmac_f32_e32 v134, 0x3377d1cf, v132
	v_fmac_f32_e32 v134, 0x3f317217, v132
	v_cmp_lt_f32_e64 s[0:1], |v132|, s71
	s_nop 1
	v_cndmask_b32_e64 v132, v132, v134, s[0:1]
	v_cndmask_b32_e32 v134, 0, v90, vcc
	v_sub_f32_e32 v132, v132, v134
	ds_read_b128 v[134:137], v102 offset:11136
	ds_read_b128 v[138:141], v102 offset:11152
	v_sub_f32_e32 v132, v133, v132
	v_fmamk_f32 v132, v132, 0x3d800000, v131
	s_waitcnt lgkmcnt(1)
	v_mov_b32_e32 v142, v134
	s_waitcnt lgkmcnt(0)
	v_mov_b32_e32 v143, v138
	v_mov_b32_e32 v138, v135
	v_pk_mul_f32 v[134:135], v[16:17], v[138:139]
	v_mov_b32_e32 v138, v136
	v_pk_fma_f32 v[134:135], v[14:15], v[142:143], v[134:135]
	v_mov_b32_e32 v139, v140
	v_pk_fma_f32 v[134:135], v[12:13], v[138:139], v[134:135]
	v_mov_b32_e32 v140, v137
	v_pk_fma_f32 v[134:135], v[10:11], v[140:141], v[134:135]
	s_nop 0
	v_add_f32_e32 v133, v100, v134
	v_add_f32_e32 v133, v133, v135
	ds_read_b128 v[134:137], v102 offset:11168
	ds_read_b128 v[138:141], v102 offset:11184
	s_waitcnt lgkmcnt(1)
	v_mov_b32_e32 v142, v134
	s_waitcnt lgkmcnt(0)
; #define LAS __attribute__((address_space(3)))
; __device__ __forceinline__ void gla_upd_unit(LAS unsigned char* wl, const bf16* PROJ, const float* R, const float* w_gk2, const float* b_gk, float* UPD, float* DEC, int unit, int lane) {
;     ...
;     float la[64]; float tot = 0.f;
; #pragma unroll
;     for (int t = 0; t < 64; ++t) {
;         const LAS f32x4* rr = (const LAS f32x4*)(wl + 9216) + t * 4;
;         float z = bias;
; #pragma unroll
;         for (int q = 0; q < 4; ++q) { const f32x4 rv = rr[q]; z += rv[0] * w[4 * q] + rv[1] * w[4 * q + 1] + rv[2] * w[4 * q + 2] + rv[3] * w[4 * q + 3]; }
;         la[t] = (fminf(z, 0.f) - __logf(1.0f + __expf(-fabsf(z)))) * (1.0f / 16.0f);
;         tot += la[t];
;     }
	v_mov_b32_e32 v143, v138
	v_mov_b32_e32 v138, v135
	v_pk_mul_f32 v[134:135], v[8:9], v[138:139]
	v_mov_b32_e32 v138, v136
	v_pk_fma_f32 v[134:135], v[6:7], v[142:143], v[134:135]
	v_mov_b32_e32 v139, v140
	v_pk_fma_f32 v[134:135], v[2:3], v[138:139], v[134:135]
	v_mov_b32_e32 v140, v137
	v_pk_fma_f32 v[134:135], v[0:1], v[140:141], v[134:135]
	s_nop 0
	v_add_f32_e32 v133, v133, v134
	v_add_f32_e32 v133, v133, v135
	v_min_f32_e32 v134, 0, v133
	v_mul_f32_e64 v133, |v133|, s68
	v_exp_f32_e32 v133, v133
	s_nop 0
	v_add_f32_e32 v133, 1.0, v133
	v_cmp_gt_f32_e32 vcc, s69, v133
	s_nop 1
	v_cndmask_b32_e64 v135, 0, 32, vcc
	v_ldexp_f32 v133, v133, v135
	v_log_f32_e32 v133, v133
	s_nop 0
	v_mul_f32_e32 v135, 0x3f317217, v133
	v_fma_f32 v135, v133, s70, -v135
	v_fmac_f32_e32 v135, 0x3377d1cf, v133
	v_fmac_f32_e32 v135, 0x3f317217, v133
	v_cmp_lt_f32_e64 s[0:1], |v133|, s71
	s_nop 1
	v_cndmask_b32_e64 v133, v133, v135, s[0:1]
	v_cndmask_b32_e32 v135, 0, v90, vcc
	v_sub_f32_e32 v133, v133, v135
	v_sub_f32_e32 v133, v134, v133
	ds_read_b128 v[134:137], v102 offset:11200
	ds_read_b128 v[138:141], v102 offset:11216
	v_fmamk_f32 v133, v133, 0x3d800000, v132
	s_waitcnt lgkmcnt(1)
	v_mov_b32_e32 v142, v134
	s_waitcnt lgkmcnt(0)
	v_mov_b32_e32 v143, v138
	v_mov_b32_e32 v138, v135
	v_pk_mul_f32 v[134:135], v[16:17], v[138:139]
	v_mov_b32_e32 v138, v136
	v_pk_fma_f32 v[134:135], v[14:15], v[142:143], v[134:135]
	v_mov_b32_e32 v139, v140
	v_pk_fma_f32 v[134:135], v[12:13], v[138:139], v[134:135]
	v_mov_b32_e32 v140, v137
	v_pk_fma_f32 v[134:135], v[10:11], v[140:141], v[134:135]
	s_nop 0
	v_add_f32_e32 v134, v100, v134
	v_add_f32_e32 v144, v134, v135
	ds_read_b128 v[134:137], v102 offset:11232
	ds_read_b128 v[138:141], v102 offset:11248
	s_waitcnt lgkmcnt(1)
	v_mov_b32_e32 v142, v134
	s_waitcnt lgkmcnt(0)
	v_mov_b32_e32 v143, v138
	v_mov_b32_e32 v138, v135
	v_pk_mul_f32 v[134:135], v[8:9], v[138:139]
	v_mov_b32_e32 v138, v136
	v_pk_fma_f32 v[134:135], v[6:7], v[142:143], v[134:135]
	v_mov_b32_e32 v139, v140
	v_pk_fma_f32 v[134:135], v[2:3], v[138:139], v[134:135]
	v_mov_b32_e32 v140, v137
	v_pk_fma_f32 v[134:135], v[0:1], v[140:141], v[134:135]
	s_nop 0
	v_add_f32_e32 v134, v144, v134
	v_add_f32_e32 v134, v134, v135
	v_min_f32_e32 v135, 0, v134
	v_mul_f32_e64 v134, |v134|, s68
	v_exp_f32_e32 v134, v134
	s_nop 0
	v_add_f32_e32 v134, 1.0, v134
	v_cmp_gt_f32_e32 vcc, s69, v134
	s_nop 1
	v_cndmask_b32_e64 v136, 0, 32, vcc
	v_ldexp_f32 v134, v134, v136
	v_log_f32_e32 v134, v134
	s_nop 0
	v_mul_f32_e32 v136, 0x3f317217, v134
	v_fma_f32 v136, v134, s70, -v136
	v_fmac_f32_e32 v136, 0x3377d1cf, v134
	v_fmac_f32_e32 v136, 0x3f317217, v134
	v_cmp_lt_f32_e64 s[0:1], |v134|, s71
	s_nop 1
	v_cndmask_b32_e64 v134, v134, v136, s[0:1]
	v_cndmask_b32_e32 v136, 0, v90, vcc
	v_sub_f32_e32 v134, v134, v136
	ds_read_b128 v[136:139], v102 offset:11264
	ds_read_b128 v[140:143], v102 offset:11280
	v_sub_f32_e32 v134, v135, v134
	v_fmamk_f32 v134, v134, 0x3d800000, v133
	s_waitcnt lgkmcnt(1)
	v_mov_b32_e32 v144, v136
	s_waitcnt lgkmcnt(0)
	v_mov_b32_e32 v145, v140
	v_mov_b32_e32 v140, v137
	v_pk_mul_f32 v[136:137], v[16:17], v[140:141]
	v_mov_b32_e32 v140, v138
	v_pk_fma_f32 v[136:137], v[14:15], v[144:145], v[136:137]
	v_mov_b32_e32 v141, v142
	v_pk_fma_f32 v[136:137], v[12:13], v[140:141], v[136:137]
	v_mov_b32_e32 v142, v139
	v_pk_fma_f32 v[136:137], v[10:11], v[142:143], v[136:137]
	s_nop 0
	v_add_f32_e32 v135, v100, v136
	v_add_f32_e32 v135, v135, v137
	ds_read_b128 v[136:139], v102 offset:11296
	ds_read_b128 v[140:143], v102 offset:11312
	s_waitcnt lgkmcnt(1)
	v_mov_b32_e32 v144, v136
	s_waitcnt lgkmcnt(0)
	v_mov_b32_e32 v145, v140
	v_mov_b32_e32 v140, v137
	v_pk_mul_f32 v[136:137], v[8:9], v[140:141]
	v_mov_b32_e32 v140, v138
	v_pk_fma_f32 v[136:137], v[6:7], v[144:145], v[136:137]
	v_mov_b32_e32 v141, v142
	v_pk_fma_f32 v[136:137], v[2:3], v[140:141], v[136:137]
	v_mov_b32_e32 v142, v139
	v_pk_fma_f32 v[136:137], v[0:1], v[142:143], v[136:137]
	s_nop 0
	v_add_f32_e32 v135, v135, v136
	v_add_f32_e32 v135, v135, v137
	v_min_f32_e32 v136, 0, v135
	v_mul_f32_e64 v135, |v135|, s68
	v_exp_f32_e32 v135, v135
	s_nop 0
	v_add_f32_e32 v135, 1.0, v135
	v_cmp_gt_f32_e32 vcc, s69, v135
	s_nop 1
	v_cndmask_b32_e64 v137, 0, 32, vcc
	v_ldexp_f32 v135, v135, v137
	v_log_f32_e32 v135, v135
	s_nop 0
	v_mul_f32_e32 v137, 0x3f317217, v135
	v_fma_f32 v137, v135, s70, -v137
	v_fmac_f32_e32 v137, 0x3377d1cf, v135
	v_fmac_f32_e32 v137, 0x3f317217, v135
	v_cmp_lt_f32_e64 s[0:1], |v135|, s71
	s_nop 1
	v_cndmask_b32_e64 v135, v135, v137, s[0:1]
	v_cndmask_b32_e32 v137, 0, v90, vcc
	v_sub_f32_e32 v135, v135, v137
	v_sub_f32_e32 v135, v136, v135
	ds_read_b128 v[136:139], v102 offset:11328
	ds_read_b128 v[140:143], v102 offset:11344
	v_fmamk_f32 v135, v135, 0x3d800000, v134
	s_waitcnt lgkmcnt(1)
	v_mov_b32_e32 v144, v136
	s_waitcnt lgkmcnt(0)
	v_mov_b32_e32 v145, v140
	v_mov_b32_e32 v140, v137
	v_pk_mul_f32 v[136:137], v[16:17], v[140:141]
	v_mov_b32_e32 v140, v138
	v_pk_fma_f32 v[136:137], v[14:15], v[144:145], v[136:137]
	v_mov_b32_e32 v141, v142
	v_pk_fma_f32 v[136:137], v[12:13], v[140:141], v[136:137]
	v_mov_b32_e32 v142, v139
	v_pk_fma_f32 v[136:137], v[10:11], v[142:143], v[136:137]
	s_nop 0
	v_add_f32_e32 v136, v100, v136
	v_add_f32_e32 v146, v136, v137
	ds_read_b128 v[136:139], v102 offset:11360
	ds_read_b128 v[140:143], v102 offset:11376
	s_waitcnt lgkmcnt(1)
	v_mov_b32_e32 v144, v136
	s_waitcnt lgkmcnt(0)
; #define LAS __attribute__((address_space(3)))
; __device__ __forceinline__ void gla_upd_unit(LAS unsigned char* wl, const bf16* PROJ, const float* R, const float* w_gk2, const float* b_gk, float* UPD, float* DEC, int unit, int lane) {
;     ...
;     float la[64]; float tot = 0.f;
; #pragma unroll
;     for (int t = 0; t < 64; ++t) {
;         const LAS f32x4* rr = (const LAS f32x4*)(wl + 9216) + t * 4;
;         float z = bias;
; #pragma unroll
;         for (int q = 0; q < 4; ++q) { const f32x4 rv = rr[q]; z += rv[0] * w[4 * q] + rv[1] * w[4 * q + 1] + rv[2] * w[4 * q + 2] + rv[3] * w[4 * q + 3]; }
;         la[t] = (fminf(z, 0.f) - __logf(1.0f + __expf(-fabsf(z)))) * (1.0f / 16.0f);
;         tot += la[t];
;     }
	v_mov_b32_e32 v145, v140
	v_mov_b32_e32 v140, v137
	v_pk_mul_f32 v[136:137], v[8:9], v[140:141]
	v_mov_b32_e32 v140, v138
	v_pk_fma_f32 v[136:137], v[6:7], v[144:145], v[136:137]
	v_mov_b32_e32 v141, v142
	v_pk_fma_f32 v[136:137], v[2:3], v[140:141], v[136:137]
	v_mov_b32_e32 v142, v139
	v_pk_fma_f32 v[136:137], v[0:1], v[142:143], v[136:137]
	s_nop 0
	v_add_f32_e32 v136, v146, v136
	v_add_f32_e32 v136, v136, v137
	v_min_f32_e32 v137, 0, v136
	v_mul_f32_e64 v136, |v136|, s68
	v_exp_f32_e32 v136, v136
	s_nop 0
	v_add_f32_e32 v136, 1.0, v136
	v_cmp_gt_f32_e32 vcc, s69, v136
	s_nop 1
	v_cndmask_b32_e64 v138, 0, 32, vcc
	v_ldexp_f32 v136, v136, v138
	v_log_f32_e32 v136, v136
	s_nop 0
	v_mul_f32_e32 v138, 0x3f317217, v136
	v_fma_f32 v138, v136, s70, -v138
	v_fmac_f32_e32 v138, 0x3377d1cf, v136
	v_fmac_f32_e32 v138, 0x3f317217, v136
	v_cmp_lt_f32_e64 s[0:1], |v136|, s71
	s_nop 1
	v_cndmask_b32_e64 v136, v136, v138, s[0:1]
	v_cndmask_b32_e32 v138, 0, v90, vcc
	v_sub_f32_e32 v136, v136, v138
	ds_read_b128 v[138:141], v102 offset:11392
	ds_read_b128 v[142:145], v102 offset:11408
	v_sub_f32_e32 v136, v137, v136
	v_fmamk_f32 v136, v136, 0x3d800000, v135
	s_waitcnt lgkmcnt(1)
	v_mov_b32_e32 v146, v138
	s_waitcnt lgkmcnt(0)
	v_mov_b32_e32 v147, v142
	v_mov_b32_e32 v142, v139
	v_pk_mul_f32 v[138:139], v[16:17], v[142:143]
	v_mov_b32_e32 v142, v140
	v_pk_fma_f32 v[138:139], v[14:15], v[146:147], v[138:139]
	v_mov_b32_e32 v143, v144
	v_pk_fma_f32 v[138:139], v[12:13], v[142:143], v[138:139]
	v_mov_b32_e32 v144, v141
	v_pk_fma_f32 v[138:139], v[10:11], v[144:145], v[138:139]
	s_nop 0
	v_add_f32_e32 v137, v100, v138
	v_add_f32_e32 v137, v137, v139
	ds_read_b128 v[138:141], v102 offset:11424
	ds_read_b128 v[142:145], v102 offset:11440
	s_waitcnt lgkmcnt(1)
	v_mov_b32_e32 v146, v138
	s_waitcnt lgkmcnt(0)
	v_mov_b32_e32 v147, v142
	v_mov_b32_e32 v142, v139
	v_pk_mul_f32 v[138:139], v[8:9], v[142:143]
	v_mov_b32_e32 v142, v140
	v_pk_fma_f32 v[138:139], v[6:7], v[146:147], v[138:139]
	v_mov_b32_e32 v143, v144
	v_pk_fma_f32 v[138:139], v[2:3], v[142:143], v[138:139]
	v_mov_b32_e32 v144, v141
	v_pk_fma_f32 v[138:139], v[0:1], v[144:145], v[138:139]
	s_nop 0
	v_add_f32_e32 v137, v137, v138
	v_add_f32_e32 v137, v137, v139
	v_min_f32_e32 v138, 0, v137
	v_mul_f32_e64 v137, |v137|, s68
	v_exp_f32_e32 v137, v137
	s_nop 0
	v_add_f32_e32 v137, 1.0, v137
	v_cmp_gt_f32_e32 vcc, s69, v137
	s_nop 1
	v_cndmask_b32_e64 v139, 0, 32, vcc
	v_ldexp_f32 v137, v137, v139
	v_log_f32_e32 v137, v137
	s_nop 0
	v_mul_f32_e32 v139, 0x3f317217, v137
	v_fma_f32 v139, v137, s70, -v139
	v_fmac_f32_e32 v139, 0x3377d1cf, v137
	v_fmac_f32_e32 v139, 0x3f317217, v137
	v_cmp_lt_f32_e64 s[0:1], |v137|, s71
	s_nop 1
	v_cndmask_b32_e64 v137, v137, v139, s[0:1]
	v_cndmask_b32_e32 v139, 0, v90, vcc
	v_sub_f32_e32 v137, v137, v139
	v_sub_f32_e32 v137, v138, v137
	ds_read_b128 v[138:141], v102 offset:11456
	ds_read_b128 v[142:145], v102 offset:11472
	v_fmamk_f32 v137, v137, 0x3d800000, v136
	s_waitcnt lgkmcnt(1)
	v_mov_b32_e32 v146, v138
	s_waitcnt lgkmcnt(0)
	v_mov_b32_e32 v147, v142
	v_mov_b32_e32 v142, v139
	v_pk_mul_f32 v[138:139], v[16:17], v[142:143]
	v_mov_b32_e32 v142, v140
	v_pk_fma_f32 v[138:139], v[14:15], v[146:147], v[138:139]
	v_mov_b32_e32 v143, v144
	v_pk_fma_f32 v[138:139], v[12:13], v[142:143], v[138:139]
	v_mov_b32_e32 v144, v141
	v_pk_fma_f32 v[138:139], v[10:11], v[144:145], v[138:139]
	s_nop 0
	v_add_f32_e32 v138, v100, v138
	v_add_f32_e32 v148, v138, v139
	ds_read_b128 v[138:141], v102 offset:11488
	ds_read_b128 v[142:145], v102 offset:11504
	s_waitcnt lgkmcnt(1)
	v_mov_b32_e32 v146, v138
	s_waitcnt lgkmcnt(0)
	v_mov_b32_e32 v147, v142
	v_mov_b32_e32 v142, v139
	v_pk_mul_f32 v[138:139], v[8:9], v[142:143]
	v_mov_b32_e32 v142, v140
	v_pk_fma_f32 v[138:139], v[6:7], v[146:147], v[138:139]
	v_mov_b32_e32 v143, v144
	v_pk_fma_f32 v[138:139], v[2:3], v[142:143], v[138:139]
	v_mov_b32_e32 v144, v141
	v_pk_fma_f32 v[138:139], v[0:1], v[144:145], v[138:139]
	s_nop 0
	v_add_f32_e32 v138, v148, v138
	v_add_f32_e32 v138, v138, v139
	v_min_f32_e32 v139, 0, v138
	v_mul_f32_e64 v138, |v138|, s68
	v_exp_f32_e32 v138, v138
	s_nop 0
	v_add_f32_e32 v138, 1.0, v138
	v_cmp_gt_f32_e32 vcc, s69, v138
	s_nop 1
	v_cndmask_b32_e64 v140, 0, 32, vcc
	v_ldexp_f32 v138, v138, v140
	v_log_f32_e32 v138, v138
	s_nop 0
	v_mul_f32_e32 v140, 0x3f317217, v138
	v_fma_f32 v140, v138, s70, -v140
	v_fmac_f32_e32 v140, 0x3377d1cf, v138
	v_fmac_f32_e32 v140, 0x3f317217, v138
	v_cmp_lt_f32_e64 s[0:1], |v138|, s71
	s_nop 1
	v_cndmask_b32_e64 v138, v138, v140, s[0:1]
	v_cndmask_b32_e32 v140, 0, v90, vcc
	v_sub_f32_e32 v138, v138, v140
	ds_read_b128 v[140:143], v102 offset:11520
	ds_read_b128 v[144:147], v102 offset:11536
	v_sub_f32_e32 v138, v139, v138
	v_fmamk_f32 v138, v138, 0x3d800000, v137
	s_waitcnt lgkmcnt(1)
	v_mov_b32_e32 v148, v140
	s_waitcnt lgkmcnt(0)
	v_mov_b32_e32 v149, v144
	v_mov_b32_e32 v144, v141
	v_pk_mul_f32 v[140:141], v[16:17], v[144:145]
	v_mov_b32_e32 v144, v142
	v_pk_fma_f32 v[140:141], v[14:15], v[148:149], v[140:141]
	v_mov_b32_e32 v145, v146
	v_pk_fma_f32 v[140:141], v[12:13], v[144:145], v[140:141]
	v_mov_b32_e32 v146, v143
	v_pk_fma_f32 v[140:141], v[10:11], v[146:147], v[140:141]
	s_nop 0
	v_add_f32_e32 v139, v100, v140
	v_add_f32_e32 v139, v139, v141
	ds_read_b128 v[140:143], v102 offset:11552
	ds_read_b128 v[144:147], v102 offset:11568
	s_waitcnt lgkmcnt(1)
	v_mov_b32_e32 v148, v140
	s_waitcnt lgkmcnt(0)
; #define LAS __attribute__((address_space(3)))
; __device__ __forceinline__ void gla_upd_unit(LAS unsigned char* wl, const bf16* PROJ, const float* R, const float* w_gk2, const float* b_gk, float* UPD, float* DEC, int unit, int lane) {
;     ...
;     float la[64]; float tot = 0.f;
; #pragma unroll
;     for (int t = 0; t < 64; ++t) {
;         const LAS f32x4* rr = (const LAS f32x4*)(wl + 9216) + t * 4;
;         float z = bias;
; #pragma unroll
;         for (int q = 0; q < 4; ++q) { const f32x4 rv = rr[q]; z += rv[0] * w[4 * q] + rv[1] * w[4 * q + 1] + rv[2] * w[4 * q + 2] + rv[3] * w[4 * q + 3]; }
;         la[t] = (fminf(z, 0.f) - __logf(1.0f + __expf(-fabsf(z)))) * (1.0f / 16.0f);
;         tot += la[t];
;     }
	v_mov_b32_e32 v149, v144
	v_mov_b32_e32 v144, v141
	v_pk_mul_f32 v[140:141], v[8:9], v[144:145]
	v_mov_b32_e32 v144, v142
	v_pk_fma_f32 v[140:141], v[6:7], v[148:149], v[140:141]
	v_mov_b32_e32 v145, v146
	v_pk_fma_f32 v[140:141], v[2:3], v[144:145], v[140:141]
	v_mov_b32_e32 v146, v143
	v_pk_fma_f32 v[140:141], v[0:1], v[146:147], v[140:141]
	s_nop 0
	v_add_f32_e32 v139, v139, v140
	v_add_f32_e32 v139, v139, v141
	v_min_f32_e32 v140, 0, v139
	v_mul_f32_e64 v139, |v139|, s68
	v_exp_f32_e32 v139, v139
	s_nop 0
	v_add_f32_e32 v139, 1.0, v139
	v_cmp_gt_f32_e32 vcc, s69, v139
	s_nop 1
	v_cndmask_b32_e64 v141, 0, 32, vcc
	v_ldexp_f32 v139, v139, v141
	v_log_f32_e32 v139, v139
	s_nop 0
	v_mul_f32_e32 v141, 0x3f317217, v139
	v_fma_f32 v141, v139, s70, -v141
	v_fmac_f32_e32 v141, 0x3377d1cf, v139
	v_fmac_f32_e32 v141, 0x3f317217, v139
	v_cmp_lt_f32_e64 s[0:1], |v139|, s71
	s_nop 1
	v_cndmask_b32_e64 v139, v139, v141, s[0:1]
	v_cndmask_b32_e32 v141, 0, v90, vcc
	v_sub_f32_e32 v139, v139, v141
	v_sub_f32_e32 v139, v140, v139
	ds_read_b128 v[140:143], v102 offset:11584
	ds_read_b128 v[144:147], v102 offset:11600
	v_fmamk_f32 v139, v139, 0x3d800000, v138
	s_waitcnt lgkmcnt(1)
	v_mov_b32_e32 v148, v140
	s_waitcnt lgkmcnt(0)
	v_mov_b32_e32 v149, v144
	v_mov_b32_e32 v144, v141
	v_pk_mul_f32 v[140:141], v[16:17], v[144:145]
	v_mov_b32_e32 v144, v142
	v_pk_fma_f32 v[140:141], v[14:15], v[148:149], v[140:141]
	v_mov_b32_e32 v145, v146
	v_pk_fma_f32 v[140:141], v[12:13], v[144:145], v[140:141]
	v_mov_b32_e32 v146, v143
	v_pk_fma_f32 v[140:141], v[10:11], v[146:147], v[140:141]
	s_nop 0
	v_add_f32_e32 v140, v100, v140
	v_add_f32_e32 v150, v140, v141
	ds_read_b128 v[140:143], v102 offset:11616
	ds_read_b128 v[144:147], v102 offset:11632
	s_waitcnt lgkmcnt(1)
	v_mov_b32_e32 v148, v140
	s_waitcnt lgkmcnt(0)
	v_mov_b32_e32 v149, v144
	v_mov_b32_e32 v144, v141
	v_pk_mul_f32 v[140:141], v[8:9], v[144:145]
	v_mov_b32_e32 v144, v142
	v_pk_fma_f32 v[140:141], v[6:7], v[148:149], v[140:141]
	v_mov_b32_e32 v145, v146
	v_pk_fma_f32 v[140:141], v[2:3], v[144:145], v[140:141]
	v_mov_b32_e32 v146, v143
	v_pk_fma_f32 v[140:141], v[0:1], v[146:147], v[140:141]
	s_nop 0
	v_add_f32_e32 v140, v150, v140
	v_add_f32_e32 v140, v140, v141
	v_min_f32_e32 v141, 0, v140
	v_mul_f32_e64 v140, |v140|, s68
	v_exp_f32_e32 v140, v140
	s_nop 0
	v_add_f32_e32 v140, 1.0, v140
	v_cmp_gt_f32_e32 vcc, s69, v140
	s_nop 1
	v_cndmask_b32_e64 v142, 0, 32, vcc
	v_ldexp_f32 v140, v140, v142
	v_log_f32_e32 v140, v140
	s_nop 0
	v_mul_f32_e32 v142, 0x3f317217, v140
	v_fma_f32 v142, v140, s70, -v142
	v_fmac_f32_e32 v142, 0x3377d1cf, v140
	v_fmac_f32_e32 v142, 0x3f317217, v140
	v_cmp_lt_f32_e64 s[0:1], |v140|, s71
	s_nop 1
	v_cndmask_b32_e64 v140, v140, v142, s[0:1]
	v_cndmask_b32_e32 v142, 0, v90, vcc
	v_sub_f32_e32 v140, v140, v142
	ds_read_b128 v[142:145], v102 offset:11648
	ds_read_b128 v[146:149], v102 offset:11664
	v_sub_f32_e32 v140, v141, v140
	v_fmamk_f32 v140, v140, 0x3d800000, v139
	s_waitcnt lgkmcnt(1)
	v_mov_b32_e32 v150, v142
	s_waitcnt lgkmcnt(0)
	v_mov_b32_e32 v151, v146
	v_mov_b32_e32 v146, v143
	v_pk_mul_f32 v[142:143], v[16:17], v[146:147]
	v_mov_b32_e32 v146, v144
	v_pk_fma_f32 v[142:143], v[14:15], v[150:151], v[142:143]
	v_mov_b32_e32 v147, v148
	v_pk_fma_f32 v[142:143], v[12:13], v[146:147], v[142:143]
	v_mov_b32_e32 v148, v145
	v_pk_fma_f32 v[142:143], v[10:11], v[148:149], v[142:143]
	s_nop 0
	v_add_f32_e32 v141, v100, v142
	v_add_f32_e32 v141, v141, v143
	ds_read_b128 v[142:145], v102 offset:11680
	ds_read_b128 v[146:149], v102 offset:11696
	s_waitcnt lgkmcnt(1)
	v_mov_b32_e32 v150, v142
	s_waitcnt lgkmcnt(0)
	v_mov_b32_e32 v151, v146
	v_mov_b32_e32 v146, v143
	v_pk_mul_f32 v[142:143], v[8:9], v[146:147]
	v_mov_b32_e32 v146, v144
	v_pk_fma_f32 v[142:143], v[6:7], v[150:151], v[142:143]
	v_mov_b32_e32 v147, v148
	v_pk_fma_f32 v[142:143], v[2:3], v[146:147], v[142:143]
	v_mov_b32_e32 v148, v145
	v_pk_fma_f32 v[142:143], v[0:1], v[148:149], v[142:143]
	s_nop 0
	v_add_f32_e32 v141, v141, v142
	v_add_f32_e32 v141, v141, v143
	v_min_f32_e32 v142, 0, v141
	v_mul_f32_e64 v141, |v141|, s68
	v_exp_f32_e32 v141, v141
	s_nop 0
	v_add_f32_e32 v141, 1.0, v141
	v_cmp_gt_f32_e32 vcc, s69, v141
	s_nop 1
	v_cndmask_b32_e64 v143, 0, 32, vcc
	v_ldexp_f32 v141, v141, v143
	v_log_f32_e32 v141, v141
	s_nop 0
	v_mul_f32_e32 v143, 0x3f317217, v141
	v_fma_f32 v143, v141, s70, -v143
	v_fmac_f32_e32 v143, 0x3377d1cf, v141
	v_fmac_f32_e32 v143, 0x3f317217, v141
	v_cmp_lt_f32_e64 s[0:1], |v141|, s71
	s_nop 1
	v_cndmask_b32_e64 v141, v141, v143, s[0:1]
	v_cndmask_b32_e32 v143, 0, v90, vcc
	v_sub_f32_e32 v141, v141, v143
	v_sub_f32_e32 v141, v142, v141
	ds_read_b128 v[142:145], v102 offset:11712
	ds_read_b128 v[146:149], v102 offset:11728
	v_fmamk_f32 v141, v141, 0x3d800000, v140
	s_waitcnt lgkmcnt(1)
	v_mov_b32_e32 v150, v142
	s_waitcnt lgkmcnt(0)
	v_mov_b32_e32 v151, v146
	v_mov_b32_e32 v146, v143
	v_pk_mul_f32 v[142:143], v[16:17], v[146:147]
	v_mov_b32_e32 v146, v144
	v_pk_fma_f32 v[142:143], v[14:15], v[150:151], v[142:143]
	v_mov_b32_e32 v147, v148
	v_pk_fma_f32 v[142:143], v[12:13], v[146:147], v[142:143]
	v_mov_b32_e32 v148, v145
	v_pk_fma_f32 v[142:143], v[10:11], v[148:149], v[142:143]
	s_nop 0
	v_add_f32_e32 v142, v100, v142
	v_add_f32_e32 v152, v142, v143
	ds_read_b128 v[142:145], v102 offset:11744
	ds_read_b128 v[146:149], v102 offset:11760
	s_waitcnt lgkmcnt(1)
	v_mov_b32_e32 v150, v142
	s_waitcnt lgkmcnt(0)
; #define LAS __attribute__((address_space(3)))
; __device__ __forceinline__ void gla_upd_unit(LAS unsigned char* wl, const bf16* PROJ, const float* R, const float* w_gk2, const float* b_gk, float* UPD, float* DEC, int unit, int lane) {
;     ...
;     float la[64]; float tot = 0.f;
; #pragma unroll
;     for (int t = 0; t < 64; ++t) {
;         const LAS f32x4* rr = (const LAS f32x4*)(wl + 9216) + t * 4;
;         float z = bias;
; #pragma unroll
;         for (int q = 0; q < 4; ++q) { const f32x4 rv = rr[q]; z += rv[0] * w[4 * q] + rv[1] * w[4 * q + 1] + rv[2] * w[4 * q + 2] + rv[3] * w[4 * q + 3]; }
;         la[t] = (fminf(z, 0.f) - __logf(1.0f + __expf(-fabsf(z)))) * (1.0f / 16.0f);
;         tot += la[t];
;     }
	v_mov_b32_e32 v151, v146
	v_mov_b32_e32 v146, v143
	v_pk_mul_f32 v[142:143], v[8:9], v[146:147]
	v_mov_b32_e32 v146, v144
	v_pk_fma_f32 v[142:143], v[6:7], v[150:151], v[142:143]
	v_mov_b32_e32 v147, v148
	v_pk_fma_f32 v[142:143], v[2:3], v[146:147], v[142:143]
	v_mov_b32_e32 v148, v145
	v_pk_fma_f32 v[142:143], v[0:1], v[148:149], v[142:143]
	s_nop 0
	v_add_f32_e32 v142, v152, v142
	v_add_f32_e32 v142, v142, v143
	v_min_f32_e32 v143, 0, v142
	v_mul_f32_e64 v142, |v142|, s68
	v_exp_f32_e32 v142, v142
	s_nop 0
	v_add_f32_e32 v142, 1.0, v142
	v_cmp_gt_f32_e32 vcc, s69, v142
	s_nop 1
	v_cndmask_b32_e64 v144, 0, 32, vcc
	v_ldexp_f32 v142, v142, v144
	v_log_f32_e32 v142, v142
	s_nop 0
	v_mul_f32_e32 v144, 0x3f317217, v142
	v_fma_f32 v144, v142, s70, -v144
	v_fmac_f32_e32 v144, 0x3377d1cf, v142
	v_fmac_f32_e32 v144, 0x3f317217, v142
	v_cmp_lt_f32_e64 s[0:1], |v142|, s71
	s_nop 1
	v_cndmask_b32_e64 v142, v142, v144, s[0:1]
	v_cndmask_b32_e32 v144, 0, v90, vcc
	v_sub_f32_e32 v142, v142, v144
	ds_read_b128 v[144:147], v102 offset:11776
	ds_read_b128 v[148:151], v102 offset:11792
	v_sub_f32_e32 v142, v143, v142
	v_fmamk_f32 v142, v142, 0x3d800000, v141
	s_waitcnt lgkmcnt(1)
	v_mov_b32_e32 v152, v144
	s_waitcnt lgkmcnt(0)
	v_mov_b32_e32 v153, v148
	v_mov_b32_e32 v148, v145
	v_pk_mul_f32 v[144:145], v[16:17], v[148:149]
	v_mov_b32_e32 v148, v146
	v_pk_fma_f32 v[144:145], v[14:15], v[152:153], v[144:145]
	v_mov_b32_e32 v149, v150
	v_pk_fma_f32 v[144:145], v[12:13], v[148:149], v[144:145]
	v_mov_b32_e32 v150, v147
	v_pk_fma_f32 v[144:145], v[10:11], v[150:151], v[144:145]
	s_nop 0
	v_add_f32_e32 v143, v100, v144
	v_add_f32_e32 v143, v143, v145
	ds_read_b128 v[144:147], v102 offset:11808
	ds_read_b128 v[148:151], v102 offset:11824
	s_waitcnt lgkmcnt(1)
	v_mov_b32_e32 v152, v144
	s_waitcnt lgkmcnt(0)
	v_mov_b32_e32 v153, v148
	v_mov_b32_e32 v148, v145
	v_pk_mul_f32 v[144:145], v[8:9], v[148:149]
	v_mov_b32_e32 v148, v146
	v_pk_fma_f32 v[144:145], v[6:7], v[152:153], v[144:145]
	v_mov_b32_e32 v149, v150
	v_pk_fma_f32 v[144:145], v[2:3], v[148:149], v[144:145]
	v_mov_b32_e32 v150, v147
	v_pk_fma_f32 v[144:145], v[0:1], v[150:151], v[144:145]
	s_nop 0
	v_add_f32_e32 v143, v143, v144
	v_add_f32_e32 v143, v143, v145
	v_min_f32_e32 v144, 0, v143
	v_mul_f32_e64 v143, |v143|, s68
	v_exp_f32_e32 v143, v143
	s_nop 0
	v_add_f32_e32 v143, 1.0, v143
	v_cmp_gt_f32_e32 vcc, s69, v143
	s_nop 1
	v_cndmask_b32_e64 v145, 0, 32, vcc
	v_ldexp_f32 v143, v143, v145
	v_log_f32_e32 v143, v143
	s_nop 0
	v_mul_f32_e32 v145, 0x3f317217, v143
	v_fma_f32 v145, v143, s70, -v145
	v_fmac_f32_e32 v145, 0x3377d1cf, v143
	v_fmac_f32_e32 v145, 0x3f317217, v143
	v_cmp_lt_f32_e64 s[0:1], |v143|, s71
	s_nop 1
	v_cndmask_b32_e64 v143, v143, v145, s[0:1]
	v_cndmask_b32_e32 v145, 0, v90, vcc
	v_sub_f32_e32 v143, v143, v145
	v_sub_f32_e32 v143, v144, v143
	ds_read_b128 v[144:147], v102 offset:11840
	ds_read_b128 v[148:151], v102 offset:11856
	v_fmamk_f32 v143, v143, 0x3d800000, v142
	s_waitcnt lgkmcnt(1)
	v_mov_b32_e32 v152, v144
	s_waitcnt lgkmcnt(0)
	v_mov_b32_e32 v153, v148
	v_mov_b32_e32 v148, v145
	v_pk_mul_f32 v[144:145], v[16:17], v[148:149]
	v_mov_b32_e32 v148, v146
	v_pk_fma_f32 v[144:145], v[14:15], v[152:153], v[144:145]
	v_mov_b32_e32 v149, v150
	v_pk_fma_f32 v[144:145], v[12:13], v[148:149], v[144:145]
	v_mov_b32_e32 v150, v147
	v_pk_fma_f32 v[144:145], v[10:11], v[150:151], v[144:145]
	s_nop 0
	v_add_f32_e32 v144, v100, v144
	v_add_f32_e32 v154, v144, v145
	ds_read_b128 v[144:147], v102 offset:11872
	ds_read_b128 v[148:151], v102 offset:11888
	s_waitcnt lgkmcnt(1)
	v_mov_b32_e32 v152, v144
	s_waitcnt lgkmcnt(0)
	v_mov_b32_e32 v153, v148
	v_mov_b32_e32 v148, v145
	v_pk_mul_f32 v[144:145], v[8:9], v[148:149]
	v_mov_b32_e32 v148, v146
	v_pk_fma_f32 v[144:145], v[6:7], v[152:153], v[144:145]
	v_mov_b32_e32 v149, v150
	v_pk_fma_f32 v[144:145], v[2:3], v[148:149], v[144:145]
	v_mov_b32_e32 v150, v147
	v_pk_fma_f32 v[144:145], v[0:1], v[150:151], v[144:145]
	s_nop 0
	v_add_f32_e32 v144, v154, v144
	v_add_f32_e32 v144, v144, v145
	v_min_f32_e32 v145, 0, v144
	v_mul_f32_e64 v144, |v144|, s68
	v_exp_f32_e32 v144, v144
	s_nop 0
	v_add_f32_e32 v144, 1.0, v144
	v_cmp_gt_f32_e32 vcc, s69, v144
	s_nop 1
	v_cndmask_b32_e64 v146, 0, 32, vcc
	v_ldexp_f32 v144, v144, v146
	v_log_f32_e32 v144, v144
	s_nop 0
	v_mul_f32_e32 v146, 0x3f317217, v144
	v_fma_f32 v146, v144, s70, -v146
	v_fmac_f32_e32 v146, 0x3377d1cf, v144
	v_fmac_f32_e32 v146, 0x3f317217, v144
	v_cmp_lt_f32_e64 s[0:1], |v144|, s71
	s_nop 1
	v_cndmask_b32_e64 v144, v144, v146, s[0:1]
	v_cndmask_b32_e32 v146, 0, v90, vcc
	v_sub_f32_e32 v144, v144, v146
	ds_read_b128 v[146:149], v102 offset:11904
	ds_read_b128 v[150:153], v102 offset:11920
	v_sub_f32_e32 v144, v145, v144
	v_fmamk_f32 v144, v144, 0x3d800000, v143
	s_waitcnt lgkmcnt(1)
	v_mov_b32_e32 v154, v146
	s_waitcnt lgkmcnt(0)
	v_mov_b32_e32 v155, v150
	v_mov_b32_e32 v150, v147
	v_pk_mul_f32 v[146:147], v[16:17], v[150:151]
	v_mov_b32_e32 v150, v148
	v_pk_fma_f32 v[146:147], v[14:15], v[154:155], v[146:147]
	v_mov_b32_e32 v151, v152
	v_pk_fma_f32 v[146:147], v[12:13], v[150:151], v[146:147]
	v_mov_b32_e32 v152, v149
	v_pk_fma_f32 v[146:147], v[10:11], v[152:153], v[146:147]
	s_nop 0
	v_add_f32_e32 v145, v100, v146
	v_add_f32_e32 v145, v145, v147
	ds_read_b128 v[146:149], v102 offset:11936
	ds_read_b128 v[150:153], v102 offset:11952
	s_waitcnt lgkmcnt(1)
	v_mov_b32_e32 v154, v146
	s_waitcnt lgkmcnt(0)
; #define LAS __attribute__((address_space(3)))
; __device__ __forceinline__ void gla_upd_unit(LAS unsigned char* wl, const bf16* PROJ, const float* R, const float* w_gk2, const float* b_gk, float* UPD, float* DEC, int unit, int lane) {
;     ...
;     float la[64]; float tot = 0.f;
; #pragma unroll
;     for (int t = 0; t < 64; ++t) {
;         const LAS f32x4* rr = (const LAS f32x4*)(wl + 9216) + t * 4;
;         float z = bias;
; #pragma unroll
;         for (int q = 0; q < 4; ++q) { const f32x4 rv = rr[q]; z += rv[0] * w[4 * q] + rv[1] * w[4 * q + 1] + rv[2] * w[4 * q + 2] + rv[3] * w[4 * q + 3]; }
;         la[t] = (fminf(z, 0.f) - __logf(1.0f + __expf(-fabsf(z)))) * (1.0f / 16.0f);
;         tot += la[t];
;     }
	v_mov_b32_e32 v155, v150
	v_mov_b32_e32 v150, v147
	v_pk_mul_f32 v[146:147], v[8:9], v[150:151]
	v_mov_b32_e32 v150, v148
	v_pk_fma_f32 v[146:147], v[6:7], v[154:155], v[146:147]
	v_mov_b32_e32 v151, v152
	v_pk_fma_f32 v[146:147], v[2:3], v[150:151], v[146:147]
	v_mov_b32_e32 v152, v149
	v_pk_fma_f32 v[146:147], v[0:1], v[152:153], v[146:147]
	s_nop 0
	v_add_f32_e32 v145, v145, v146
	v_add_f32_e32 v145, v145, v147
	v_min_f32_e32 v146, 0, v145
	v_mul_f32_e64 v145, |v145|, s68
	v_exp_f32_e32 v145, v145
	s_nop 0
	v_add_f32_e32 v145, 1.0, v145
	v_cmp_gt_f32_e32 vcc, s69, v145
	s_nop 1
	v_cndmask_b32_e64 v147, 0, 32, vcc
	v_ldexp_f32 v145, v145, v147
	v_log_f32_e32 v145, v145
	s_nop 0
	v_mul_f32_e32 v147, 0x3f317217, v145
	v_fma_f32 v147, v145, s70, -v147
	v_fmac_f32_e32 v147, 0x3377d1cf, v145
	v_fmac_f32_e32 v147, 0x3f317217, v145
	v_cmp_lt_f32_e64 s[0:1], |v145|, s71
	s_nop 1
	v_cndmask_b32_e64 v145, v145, v147, s[0:1]
	v_cndmask_b32_e32 v147, 0, v90, vcc
	v_sub_f32_e32 v145, v145, v147
	v_sub_f32_e32 v145, v146, v145
	ds_read_b128 v[146:149], v102 offset:11968
	ds_read_b128 v[150:153], v102 offset:11984
	v_fmamk_f32 v145, v145, 0x3d800000, v144
	s_waitcnt lgkmcnt(1)
	v_mov_b32_e32 v154, v146
	s_waitcnt lgkmcnt(0)
	v_mov_b32_e32 v155, v150
	v_mov_b32_e32 v150, v147
	v_pk_mul_f32 v[146:147], v[16:17], v[150:151]
	v_mov_b32_e32 v150, v148
	v_pk_fma_f32 v[146:147], v[14:15], v[154:155], v[146:147]
	v_mov_b32_e32 v151, v152
	v_pk_fma_f32 v[146:147], v[12:13], v[150:151], v[146:147]
	v_mov_b32_e32 v152, v149
	v_pk_fma_f32 v[146:147], v[10:11], v[152:153], v[146:147]
	s_nop 0
	v_add_f32_e32 v146, v100, v146
	v_add_f32_e32 v156, v146, v147
	ds_read_b128 v[146:149], v102 offset:12000
	ds_read_b128 v[150:153], v102 offset:12016
	s_waitcnt lgkmcnt(1)
	v_mov_b32_e32 v154, v146
	s_waitcnt lgkmcnt(0)
	v_mov_b32_e32 v155, v150
	v_mov_b32_e32 v150, v147
	v_pk_mul_f32 v[146:147], v[8:9], v[150:151]
	v_mov_b32_e32 v150, v148
	v_pk_fma_f32 v[146:147], v[6:7], v[154:155], v[146:147]
	v_mov_b32_e32 v151, v152
	v_pk_fma_f32 v[146:147], v[2:3], v[150:151], v[146:147]
	v_mov_b32_e32 v152, v149
	v_pk_fma_f32 v[146:147], v[0:1], v[152:153], v[146:147]
	s_nop 0
	v_add_f32_e32 v146, v156, v146
	v_add_f32_e32 v146, v146, v147
	v_min_f32_e32 v147, 0, v146
	v_mul_f32_e64 v146, |v146|, s68
	v_exp_f32_e32 v146, v146
	s_nop 0
	v_add_f32_e32 v146, 1.0, v146
	v_cmp_gt_f32_e32 vcc, s69, v146
	s_nop 1
	v_cndmask_b32_e64 v148, 0, 32, vcc
	v_ldexp_f32 v146, v146, v148
	v_log_f32_e32 v146, v146
	s_nop 0
	v_mul_f32_e32 v148, 0x3f317217, v146
	v_fma_f32 v148, v146, s70, -v148
	v_fmac_f32_e32 v148, 0x3377d1cf, v146
	v_fmac_f32_e32 v148, 0x3f317217, v146
	v_cmp_lt_f32_e64 s[0:1], |v146|, s71
	s_nop 1
	v_cndmask_b32_e64 v146, v146, v148, s[0:1]
	v_cndmask_b32_e32 v148, 0, v90, vcc
	v_sub_f32_e32 v146, v146, v148
	ds_read_b128 v[148:151], v102 offset:12032
	ds_read_b128 v[152:155], v102 offset:12048
	v_sub_f32_e32 v146, v147, v146
	v_fmamk_f32 v146, v146, 0x3d800000, v145
	s_waitcnt lgkmcnt(1)
	v_mov_b32_e32 v156, v148
	s_waitcnt lgkmcnt(0)
	v_mov_b32_e32 v157, v152
	v_mov_b32_e32 v152, v149
	v_pk_mul_f32 v[148:149], v[16:17], v[152:153]
	v_mov_b32_e32 v152, v150
	v_pk_fma_f32 v[148:149], v[14:15], v[156:157], v[148:149]
	v_mov_b32_e32 v153, v154
	v_pk_fma_f32 v[148:149], v[12:13], v[152:153], v[148:149]
	v_mov_b32_e32 v154, v151
	v_pk_fma_f32 v[148:149], v[10:11], v[154:155], v[148:149]
	s_nop 0
	v_add_f32_e32 v147, v100, v148
	v_add_f32_e32 v147, v147, v149
	ds_read_b128 v[148:151], v102 offset:12064
	ds_read_b128 v[152:155], v102 offset:12080
	s_waitcnt lgkmcnt(1)
	v_mov_b32_e32 v156, v148
	s_waitcnt lgkmcnt(0)
	v_mov_b32_e32 v157, v152
	v_mov_b32_e32 v152, v149
	v_pk_mul_f32 v[148:149], v[8:9], v[152:153]
	v_mov_b32_e32 v152, v150
	v_pk_fma_f32 v[148:149], v[6:7], v[156:157], v[148:149]
	v_mov_b32_e32 v153, v154
	v_pk_fma_f32 v[148:149], v[2:3], v[152:153], v[148:149]
	v_mov_b32_e32 v154, v151
	v_pk_fma_f32 v[148:149], v[0:1], v[154:155], v[148:149]
	s_nop 0
	v_add_f32_e32 v147, v147, v148
	v_add_f32_e32 v147, v147, v149
	v_min_f32_e32 v148, 0, v147
	v_mul_f32_e64 v147, |v147|, s68
	v_exp_f32_e32 v147, v147
	s_nop 0
	v_add_f32_e32 v147, 1.0, v147
	v_cmp_gt_f32_e32 vcc, s69, v147
	s_nop 1
	v_cndmask_b32_e64 v149, 0, 32, vcc
	v_ldexp_f32 v147, v147, v149
	v_log_f32_e32 v147, v147
	s_nop 0
	v_mul_f32_e32 v149, 0x3f317217, v147
	v_fma_f32 v149, v147, s70, -v149
	v_fmac_f32_e32 v149, 0x3377d1cf, v147
	v_fmac_f32_e32 v149, 0x3f317217, v147
	v_cmp_lt_f32_e64 s[0:1], |v147|, s71
	s_nop 1
	v_cndmask_b32_e64 v147, v147, v149, s[0:1]
	v_cndmask_b32_e32 v149, 0, v90, vcc
	v_sub_f32_e32 v147, v147, v149
	v_sub_f32_e32 v147, v148, v147
	ds_read_b128 v[148:151], v102 offset:12096
	ds_read_b128 v[152:155], v102 offset:12112
	v_fmamk_f32 v147, v147, 0x3d800000, v146
	s_waitcnt lgkmcnt(1)
	v_mov_b32_e32 v156, v148
	s_waitcnt lgkmcnt(0)
	v_mov_b32_e32 v157, v152
	v_mov_b32_e32 v152, v149
	v_pk_mul_f32 v[148:149], v[16:17], v[152:153]
	v_mov_b32_e32 v152, v150
	v_pk_fma_f32 v[148:149], v[14:15], v[156:157], v[148:149]
	v_mov_b32_e32 v153, v154
	v_pk_fma_f32 v[148:149], v[12:13], v[152:153], v[148:149]
	v_mov_b32_e32 v154, v151
	v_pk_fma_f32 v[148:149], v[10:11], v[154:155], v[148:149]
	s_nop 0
	v_add_f32_e32 v148, v100, v148
	v_add_f32_e32 v158, v148, v149
	ds_read_b128 v[148:151], v102 offset:12128
	ds_read_b128 v[152:155], v102 offset:12144
	s_waitcnt lgkmcnt(1)
	v_mov_b32_e32 v156, v148
	s_waitcnt lgkmcnt(0)
; #define LAS __attribute__((address_space(3)))
; __device__ __forceinline__ void gla_upd_unit(LAS unsigned char* wl, const bf16* PROJ, const float* R, const float* w_gk2, const float* b_gk, float* UPD, float* DEC, int unit, int lane) {
;     ...
;     float la[64]; float tot = 0.f;
; #pragma unroll
;     for (int t = 0; t < 64; ++t) {
;         const LAS f32x4* rr = (const LAS f32x4*)(wl + 9216) + t * 4;
;         float z = bias;
; #pragma unroll
;         for (int q = 0; q < 4; ++q) { const f32x4 rv = rr[q]; z += rv[0] * w[4 * q] + rv[1] * w[4 * q + 1] + rv[2] * w[4 * q + 2] + rv[3] * w[4 * q + 3]; }
;         la[t] = (fminf(z, 0.f) - __logf(1.0f + __expf(-fabsf(z)))) * (1.0f / 16.0f);
;         tot += la[t];
;     }
	v_mov_b32_e32 v157, v152
	v_mov_b32_e32 v152, v149
	v_pk_mul_f32 v[148:149], v[8:9], v[152:153]
	v_mov_b32_e32 v152, v150
	v_pk_fma_f32 v[148:149], v[6:7], v[156:157], v[148:149]
	v_mov_b32_e32 v153, v154
	v_pk_fma_f32 v[148:149], v[2:3], v[152:153], v[148:149]
	v_mov_b32_e32 v154, v151
	v_pk_fma_f32 v[148:149], v[0:1], v[154:155], v[148:149]
	s_nop 0
	v_add_f32_e32 v148, v158, v148
	v_add_f32_e32 v148, v148, v149
	v_min_f32_e32 v149, 0, v148
	v_mul_f32_e64 v148, |v148|, s68
	v_exp_f32_e32 v148, v148
	s_nop 0
	v_add_f32_e32 v148, 1.0, v148
	v_cmp_gt_f32_e32 vcc, s69, v148
	s_nop 1
	v_cndmask_b32_e64 v150, 0, 32, vcc
	v_ldexp_f32 v148, v148, v150
	v_log_f32_e32 v148, v148
	s_nop 0
	v_mul_f32_e32 v150, 0x3f317217, v148
	v_fma_f32 v150, v148, s70, -v150
	v_fmac_f32_e32 v150, 0x3377d1cf, v148
	v_fmac_f32_e32 v150, 0x3f317217, v148
	v_cmp_lt_f32_e64 s[0:1], |v148|, s71
	s_nop 1
	v_cndmask_b32_e64 v148, v148, v150, s[0:1]
	v_cndmask_b32_e32 v150, 0, v90, vcc
	v_sub_f32_e32 v148, v148, v150
	ds_read_b128 v[150:153], v102 offset:12160
	ds_read_b128 v[154:157], v102 offset:12176
	v_sub_f32_e32 v148, v149, v148
	v_fmamk_f32 v148, v148, 0x3d800000, v147
	s_waitcnt lgkmcnt(1)
	v_mov_b32_e32 v158, v150
	s_waitcnt lgkmcnt(0)
	v_mov_b32_e32 v159, v154
	v_mov_b32_e32 v154, v151
	v_pk_mul_f32 v[150:151], v[16:17], v[154:155]
	v_mov_b32_e32 v154, v152
	v_pk_fma_f32 v[150:151], v[14:15], v[158:159], v[150:151]
	v_mov_b32_e32 v155, v156
	v_pk_fma_f32 v[150:151], v[12:13], v[154:155], v[150:151]
	v_mov_b32_e32 v156, v153
	v_pk_fma_f32 v[150:151], v[10:11], v[156:157], v[150:151]
	s_nop 0
	v_add_f32_e32 v149, v100, v150
	v_add_f32_e32 v149, v149, v151
	ds_read_b128 v[150:153], v102 offset:12192
	ds_read_b128 v[154:157], v102 offset:12208
	s_waitcnt lgkmcnt(1)
	v_mov_b32_e32 v158, v150
	s_waitcnt lgkmcnt(0)
	v_mov_b32_e32 v159, v154
	v_mov_b32_e32 v154, v151
	v_pk_mul_f32 v[150:151], v[8:9], v[154:155]
	v_mov_b32_e32 v154, v152
	v_pk_fma_f32 v[150:151], v[6:7], v[158:159], v[150:151]
	v_mov_b32_e32 v155, v156
	v_pk_fma_f32 v[150:151], v[2:3], v[154:155], v[150:151]
	v_mov_b32_e32 v156, v153
	v_pk_fma_f32 v[150:151], v[0:1], v[156:157], v[150:151]
	s_nop 0
	v_add_f32_e32 v149, v149, v150
	v_add_f32_e32 v149, v149, v151
	v_min_f32_e32 v150, 0, v149
	v_mul_f32_e64 v149, |v149|, s68
	v_exp_f32_e32 v149, v149
	s_nop 0
	v_add_f32_e32 v149, 1.0, v149
	v_cmp_gt_f32_e32 vcc, s69, v149
	s_nop 1
	v_cndmask_b32_e64 v151, 0, 32, vcc
	v_ldexp_f32 v149, v149, v151
	v_log_f32_e32 v149, v149
	s_nop 0
	v_mul_f32_e32 v151, 0x3f317217, v149
	v_fma_f32 v151, v149, s70, -v151
	v_fmac_f32_e32 v151, 0x3377d1cf, v149
	v_fmac_f32_e32 v151, 0x3f317217, v149
	v_cmp_lt_f32_e64 s[0:1], |v149|, s71
	s_nop 1
	v_cndmask_b32_e64 v149, v149, v151, s[0:1]
	v_cndmask_b32_e32 v151, 0, v90, vcc
	v_sub_f32_e32 v149, v149, v151
	v_sub_f32_e32 v149, v150, v149
	ds_read_b128 v[150:153], v102 offset:12224
	ds_read_b128 v[154:157], v102 offset:12240
	v_fmamk_f32 v149, v149, 0x3d800000, v148
	s_waitcnt lgkmcnt(1)
	v_mov_b32_e32 v158, v150
	s_waitcnt lgkmcnt(0)
	v_mov_b32_e32 v159, v154
	v_mov_b32_e32 v154, v151
	v_pk_mul_f32 v[150:151], v[16:17], v[154:155]
	v_mov_b32_e32 v154, v152
	v_pk_fma_f32 v[150:151], v[14:15], v[158:159], v[150:151]
	v_mov_b32_e32 v155, v156
	v_pk_fma_f32 v[150:151], v[12:13], v[154:155], v[150:151]
	v_mov_b32_e32 v156, v153
	v_pk_fma_f32 v[150:151], v[10:11], v[156:157], v[150:151]
	s_nop 0
	v_add_f32_e32 v150, v100, v150
	v_add_f32_e32 v160, v150, v151
	ds_read_b128 v[150:153], v102 offset:12256
	ds_read_b128 v[154:157], v102 offset:12272
	s_waitcnt lgkmcnt(1)
	v_mov_b32_e32 v158, v150
	s_waitcnt lgkmcnt(0)
	v_mov_b32_e32 v159, v154
	v_mov_b32_e32 v154, v151
	v_pk_mul_f32 v[150:151], v[8:9], v[154:155]
	v_mov_b32_e32 v154, v152
	v_pk_fma_f32 v[150:151], v[6:7], v[158:159], v[150:151]
	v_mov_b32_e32 v155, v156
	v_pk_fma_f32 v[150:151], v[2:3], v[154:155], v[150:151]
	v_mov_b32_e32 v156, v153
	v_pk_fma_f32 v[150:151], v[0:1], v[156:157], v[150:151]
	s_nop 0
	v_add_f32_e32 v150, v160, v150
	v_add_f32_e32 v150, v150, v151
	v_min_f32_e32 v151, 0, v150
	v_mul_f32_e64 v150, |v150|, s68
	v_exp_f32_e32 v150, v150
	s_nop 0
	v_add_f32_e32 v150, 1.0, v150
	v_cmp_gt_f32_e32 vcc, s69, v150
	s_nop 1
	v_cndmask_b32_e64 v152, 0, 32, vcc
	v_ldexp_f32 v150, v150, v152
	v_log_f32_e32 v150, v150
	s_nop 0
	v_mul_f32_e32 v152, 0x3f317217, v150
	v_fma_f32 v152, v150, s70, -v152
	v_fmac_f32_e32 v152, 0x3377d1cf, v150
	v_fmac_f32_e32 v152, 0x3f317217, v150
	v_cmp_lt_f32_e64 s[0:1], |v150|, s71
	s_nop 1
	v_cndmask_b32_e64 v150, v150, v152, s[0:1]
	v_cndmask_b32_e32 v152, 0, v90, vcc
	v_sub_f32_e32 v150, v150, v152
	ds_read_b128 v[152:155], v102 offset:12288
	ds_read_b128 v[156:159], v102 offset:12304
	v_sub_f32_e32 v150, v151, v150
	v_fmamk_f32 v150, v150, 0x3d800000, v149
	s_waitcnt lgkmcnt(1)
	v_mov_b32_e32 v160, v152
	s_waitcnt lgkmcnt(0)
	v_mov_b32_e32 v161, v156
	v_mov_b32_e32 v156, v153
	v_pk_mul_f32 v[152:153], v[16:17], v[156:157]
	v_mov_b32_e32 v156, v154
	v_pk_fma_f32 v[152:153], v[14:15], v[160:161], v[152:153]
	v_mov_b32_e32 v157, v158
	v_pk_fma_f32 v[152:153], v[12:13], v[156:157], v[152:153]
	v_mov_b32_e32 v158, v155
	v_pk_fma_f32 v[152:153], v[10:11], v[158:159], v[152:153]
	s_nop 0
	v_add_f32_e32 v151, v100, v152
	v_add_f32_e32 v151, v151, v153
	ds_read_b128 v[152:155], v102 offset:12320
	ds_read_b128 v[156:159], v102 offset:12336
	s_waitcnt lgkmcnt(1)
	v_mov_b32_e32 v160, v152
	s_waitcnt lgkmcnt(0)
; #define LAS __attribute__((address_space(3)))
; __device__ __forceinline__ void gla_upd_unit(LAS unsigned char* wl, const bf16* PROJ, const float* R, const float* w_gk2, const float* b_gk, float* UPD, float* DEC, int unit, int lane) {
;     ...
;     float la[64]; float tot = 0.f;
; #pragma unroll
;     for (int t = 0; t < 64; ++t) {
;         const LAS f32x4* rr = (const LAS f32x4*)(wl + 9216) + t * 4;
;         float z = bias;
; #pragma unroll
;         for (int q = 0; q < 4; ++q) { const f32x4 rv = rr[q]; z += rv[0] * w[4 * q] + rv[1] * w[4 * q + 1] + rv[2] * w[4 * q + 2] + rv[3] * w[4 * q + 3]; }
;         la[t] = (fminf(z, 0.f) - __logf(1.0f + __expf(-fabsf(z)))) * (1.0f / 16.0f);
;         tot += la[t];
;     }
	v_mov_b32_e32 v161, v156
	v_mov_b32_e32 v156, v153
	v_pk_mul_f32 v[152:153], v[8:9], v[156:157]
	v_mov_b32_e32 v156, v154
	v_pk_fma_f32 v[152:153], v[6:7], v[160:161], v[152:153]
	v_mov_b32_e32 v157, v158
	v_pk_fma_f32 v[152:153], v[2:3], v[156:157], v[152:153]
	v_mov_b32_e32 v158, v155
	v_pk_fma_f32 v[152:153], v[0:1], v[158:159], v[152:153]
	s_nop 0
	v_add_f32_e32 v151, v151, v152
	v_add_f32_e32 v151, v151, v153
	v_min_f32_e32 v152, 0, v151
	v_mul_f32_e64 v151, |v151|, s68
	v_exp_f32_e32 v151, v151
	s_nop 0
	v_add_f32_e32 v151, 1.0, v151
	v_cmp_gt_f32_e32 vcc, s69, v151
	s_nop 1
	v_cndmask_b32_e64 v153, 0, 32, vcc
	v_ldexp_f32 v151, v151, v153
	v_log_f32_e32 v151, v151
	s_nop 0
	v_mul_f32_e32 v153, 0x3f317217, v151
	v_fma_f32 v153, v151, s70, -v153
	v_fmac_f32_e32 v153, 0x3377d1cf, v151
	v_fmac_f32_e32 v153, 0x3f317217, v151
	v_cmp_lt_f32_e64 s[0:1], |v151|, s71
	s_nop 1
	v_cndmask_b32_e64 v151, v151, v153, s[0:1]
	v_cndmask_b32_e32 v153, 0, v90, vcc
	v_sub_f32_e32 v151, v151, v153
	v_sub_f32_e32 v151, v152, v151
	ds_read_b128 v[152:155], v102 offset:12352
	ds_read_b128 v[156:159], v102 offset:12368
	v_fmamk_f32 v151, v151, 0x3d800000, v150
	s_waitcnt lgkmcnt(1)
	v_mov_b32_e32 v160, v152
	s_waitcnt lgkmcnt(0)
	v_mov_b32_e32 v161, v156
	v_mov_b32_e32 v156, v153
	v_pk_mul_f32 v[152:153], v[16:17], v[156:157]
	v_mov_b32_e32 v156, v154
	v_pk_fma_f32 v[152:153], v[14:15], v[160:161], v[152:153]
	v_mov_b32_e32 v157, v158
	v_pk_fma_f32 v[152:153], v[12:13], v[156:157], v[152:153]
	v_mov_b32_e32 v158, v155
	v_pk_fma_f32 v[152:153], v[10:11], v[158:159], v[152:153]
	s_nop 0
	v_add_f32_e32 v152, v100, v152
	v_add_f32_e32 v162, v152, v153
	ds_read_b128 v[152:155], v102 offset:12384
	ds_read_b128 v[156:159], v102 offset:12400
	s_waitcnt lgkmcnt(1)
	v_mov_b32_e32 v160, v152
	s_waitcnt lgkmcnt(0)
	v_mov_b32_e32 v161, v156
	v_mov_b32_e32 v156, v153
	v_pk_mul_f32 v[152:153], v[8:9], v[156:157]
	v_mov_b32_e32 v156, v154
	v_pk_fma_f32 v[152:153], v[6:7], v[160:161], v[152:153]
	v_mov_b32_e32 v157, v158
	v_pk_fma_f32 v[152:153], v[2:3], v[156:157], v[152:153]
	v_mov_b32_e32 v158, v155
	v_pk_fma_f32 v[152:153], v[0:1], v[158:159], v[152:153]
	s_nop 0
	v_add_f32_e32 v152, v162, v152
	v_add_f32_e32 v152, v152, v153
	v_min_f32_e32 v153, 0, v152
	v_mul_f32_e64 v152, |v152|, s68
	v_exp_f32_e32 v152, v152
	s_nop 0
	v_add_f32_e32 v152, 1.0, v152
	v_cmp_gt_f32_e32 vcc, s69, v152
	s_nop 1
	v_cndmask_b32_e64 v154, 0, 32, vcc
	v_ldexp_f32 v152, v152, v154
	v_log_f32_e32 v152, v152
	s_nop 0
	v_mul_f32_e32 v154, 0x3f317217, v152
	v_fma_f32 v154, v152, s70, -v154
	v_fmac_f32_e32 v154, 0x3377d1cf, v152
	v_fmac_f32_e32 v154, 0x3f317217, v152
	v_cmp_lt_f32_e64 s[0:1], |v152|, s71
	s_nop 1
	v_cndmask_b32_e64 v152, v152, v154, s[0:1]
	v_cndmask_b32_e32 v154, 0, v90, vcc
	v_sub_f32_e32 v152, v152, v154
	ds_read_b128 v[154:157], v102 offset:12416
	ds_read_b128 v[158:161], v102 offset:12432
	v_sub_f32_e32 v152, v153, v152
	v_fmamk_f32 v152, v152, 0x3d800000, v151
	s_waitcnt lgkmcnt(1)
	v_mov_b32_e32 v162, v154
	s_waitcnt lgkmcnt(0)
	v_mov_b32_e32 v163, v158
	v_mov_b32_e32 v158, v155
	v_pk_mul_f32 v[154:155], v[16:17], v[158:159]
	v_mov_b32_e32 v158, v156
	v_pk_fma_f32 v[154:155], v[14:15], v[162:163], v[154:155]
	v_mov_b32_e32 v159, v160
	v_pk_fma_f32 v[154:155], v[12:13], v[158:159], v[154:155]
	v_mov_b32_e32 v160, v157
	v_pk_fma_f32 v[154:155], v[10:11], v[160:161], v[154:155]
	s_nop 0
	v_add_f32_e32 v153, v100, v154
	v_add_f32_e32 v153, v153, v155
	ds_read_b128 v[154:157], v102 offset:12448
	ds_read_b128 v[158:161], v102 offset:12464
	s_waitcnt lgkmcnt(1)
	v_mov_b32_e32 v162, v154
	s_waitcnt lgkmcnt(0)
	v_mov_b32_e32 v163, v158
	v_mov_b32_e32 v158, v155
	v_pk_mul_f32 v[154:155], v[8:9], v[158:159]
	v_mov_b32_e32 v158, v156
	v_pk_fma_f32 v[154:155], v[6:7], v[162:163], v[154:155]
	v_mov_b32_e32 v159, v160
	v_pk_fma_f32 v[154:155], v[2:3], v[158:159], v[154:155]
	v_mov_b32_e32 v160, v157
	v_pk_fma_f32 v[154:155], v[0:1], v[160:161], v[154:155]
	s_nop 0
	v_add_f32_e32 v153, v153, v154
	v_add_f32_e32 v153, v153, v155
	v_min_f32_e32 v154, 0, v153
	v_mul_f32_e64 v153, |v153|, s68
	v_exp_f32_e32 v153, v153
	s_nop 0
	v_add_f32_e32 v153, 1.0, v153
	v_cmp_gt_f32_e32 vcc, s69, v153
	s_nop 1
	v_cndmask_b32_e64 v155, 0, 32, vcc
	v_ldexp_f32 v153, v153, v155
	v_log_f32_e32 v153, v153
	s_nop 0
	v_mul_f32_e32 v155, 0x3f317217, v153
	v_fma_f32 v155, v153, s70, -v155
	v_fmac_f32_e32 v155, 0x3377d1cf, v153
	v_fmac_f32_e32 v155, 0x3f317217, v153
	v_cmp_lt_f32_e64 s[0:1], |v153|, s71
	s_nop 1
	v_cndmask_b32_e64 v153, v153, v155, s[0:1]
	v_cndmask_b32_e32 v155, 0, v90, vcc
	v_sub_f32_e32 v153, v153, v155
	v_sub_f32_e32 v153, v154, v153
	ds_read_b128 v[154:157], v102 offset:12480
	ds_read_b128 v[158:161], v102 offset:12496
	v_fmamk_f32 v153, v153, 0x3d800000, v152
	s_waitcnt lgkmcnt(1)
	v_mov_b32_e32 v162, v154
	s_waitcnt lgkmcnt(0)
	v_mov_b32_e32 v163, v158
	v_mov_b32_e32 v158, v155
	v_pk_mul_f32 v[154:155], v[16:17], v[158:159]
	v_mov_b32_e32 v158, v156
	v_pk_fma_f32 v[154:155], v[14:15], v[162:163], v[154:155]
	v_mov_b32_e32 v159, v160
	v_pk_fma_f32 v[154:155], v[12:13], v[158:159], v[154:155]
	v_mov_b32_e32 v160, v157
	v_pk_fma_f32 v[154:155], v[10:11], v[160:161], v[154:155]
	s_nop 0
	v_add_f32_e32 v154, v100, v154
	v_add_f32_e32 v164, v154, v155
	ds_read_b128 v[154:157], v102 offset:12512
	ds_read_b128 v[158:161], v102 offset:12528
	s_waitcnt lgkmcnt(1)
	v_mov_b32_e32 v162, v154
	s_waitcnt lgkmcnt(0)
; #define LAS __attribute__((address_space(3)))
; __device__ __forceinline__ void gla_upd_unit(LAS unsigned char* wl, const bf16* PROJ, const float* R, const float* w_gk2, const float* b_gk, float* UPD, float* DEC, int unit, int lane) {
;     ...
;     float la[64]; float tot = 0.f;
; #pragma unroll
;     for (int t = 0; t < 64; ++t) {
;         const LAS f32x4* rr = (const LAS f32x4*)(wl + 9216) + t * 4;
;         float z = bias;
; #pragma unroll
;         for (int q = 0; q < 4; ++q) { const f32x4 rv = rr[q]; z += rv[0] * w[4 * q] + rv[1] * w[4 * q + 1] + rv[2] * w[4 * q + 2] + rv[3] * w[4 * q + 3]; }
;         la[t] = (fminf(z, 0.f) - __logf(1.0f + __expf(-fabsf(z)))) * (1.0f / 16.0f);
;         tot += la[t];
;     }
	v_mov_b32_e32 v163, v158
	v_mov_b32_e32 v158, v155
	v_pk_mul_f32 v[154:155], v[8:9], v[158:159]
	v_mov_b32_e32 v158, v156
	v_pk_fma_f32 v[154:155], v[6:7], v[162:163], v[154:155]
	v_mov_b32_e32 v159, v160
	v_pk_fma_f32 v[154:155], v[2:3], v[158:159], v[154:155]
	v_mov_b32_e32 v160, v157
	v_pk_fma_f32 v[154:155], v[0:1], v[160:161], v[154:155]
	s_nop 0
	v_add_f32_e32 v154, v164, v154
	v_add_f32_e32 v154, v154, v155
	v_min_f32_e32 v155, 0, v154
	v_mul_f32_e64 v154, |v154|, s68
	v_exp_f32_e32 v154, v154
	s_nop 0
	v_add_f32_e32 v154, 1.0, v154
	v_cmp_gt_f32_e32 vcc, s69, v154
	s_nop 1
	v_cndmask_b32_e64 v156, 0, 32, vcc
	v_ldexp_f32 v154, v154, v156
	v_log_f32_e32 v154, v154
	s_nop 0
	v_mul_f32_e32 v156, 0x3f317217, v154
	v_fma_f32 v156, v154, s70, -v156
	v_fmac_f32_e32 v156, 0x3377d1cf, v154
	v_fmac_f32_e32 v156, 0x3f317217, v154
	v_cmp_lt_f32_e64 s[0:1], |v154|, s71
	s_nop 1
	v_cndmask_b32_e64 v154, v154, v156, s[0:1]
	v_cndmask_b32_e32 v156, 0, v90, vcc
	v_sub_f32_e32 v154, v154, v156
	ds_read_b128 v[156:159], v102 offset:12544
	ds_read_b128 v[160:163], v102 offset:12560
	v_sub_f32_e32 v154, v155, v154
	v_fmamk_f32 v154, v154, 0x3d800000, v153
	s_waitcnt lgkmcnt(1)
	v_mov_b32_e32 v164, v156
	s_waitcnt lgkmcnt(0)
	v_mov_b32_e32 v165, v160
	v_mov_b32_e32 v160, v157
	v_pk_mul_f32 v[156:157], v[16:17], v[160:161]
	v_mov_b32_e32 v160, v158
	v_pk_fma_f32 v[156:157], v[14:15], v[164:165], v[156:157]
	v_mov_b32_e32 v161, v162
	v_pk_fma_f32 v[156:157], v[12:13], v[160:161], v[156:157]
	v_mov_b32_e32 v162, v159
	v_pk_fma_f32 v[156:157], v[10:11], v[162:163], v[156:157]
	s_nop 0
	v_add_f32_e32 v155, v100, v156
	v_add_f32_e32 v155, v155, v157
	ds_read_b128 v[156:159], v102 offset:12576
	ds_read_b128 v[160:163], v102 offset:12592
	s_waitcnt lgkmcnt(1)
	v_mov_b32_e32 v164, v156
	s_waitcnt lgkmcnt(0)
	v_mov_b32_e32 v165, v160
	v_mov_b32_e32 v160, v157
	v_pk_mul_f32 v[156:157], v[8:9], v[160:161]
	v_mov_b32_e32 v160, v158
	v_pk_fma_f32 v[156:157], v[6:7], v[164:165], v[156:157]
	v_mov_b32_e32 v161, v162
	v_pk_fma_f32 v[156:157], v[2:3], v[160:161], v[156:157]
	v_mov_b32_e32 v162, v159
	v_pk_fma_f32 v[156:157], v[0:1], v[162:163], v[156:157]
	s_nop 0
	v_add_f32_e32 v155, v155, v156
	v_add_f32_e32 v155, v155, v157
	v_min_f32_e32 v156, 0, v155
	v_mul_f32_e64 v155, |v155|, s68
	v_exp_f32_e32 v155, v155
	s_nop 0
	v_add_f32_e32 v155, 1.0, v155
	v_cmp_gt_f32_e32 vcc, s69, v155
	s_nop 1
	v_cndmask_b32_e64 v157, 0, 32, vcc
	v_ldexp_f32 v155, v155, v157
	v_log_f32_e32 v155, v155
	s_nop 0
	v_mul_f32_e32 v157, 0x3f317217, v155
	v_fma_f32 v157, v155, s70, -v157
	v_fmac_f32_e32 v157, 0x3377d1cf, v155
	v_fmac_f32_e32 v157, 0x3f317217, v155
	v_cmp_lt_f32_e64 s[0:1], |v155|, s71
	s_nop 1
	v_cndmask_b32_e64 v155, v155, v157, s[0:1]
	v_cndmask_b32_e32 v157, 0, v90, vcc
	v_sub_f32_e32 v155, v155, v157
	v_sub_f32_e32 v155, v156, v155
	ds_read_b128 v[156:159], v102 offset:12608
	ds_read_b128 v[160:163], v102 offset:12624
	v_fmamk_f32 v155, v155, 0x3d800000, v154
	s_waitcnt lgkmcnt(1)
	v_mov_b32_e32 v164, v156
	s_waitcnt lgkmcnt(0)
	v_mov_b32_e32 v165, v160
	v_mov_b32_e32 v160, v157
	v_pk_mul_f32 v[156:157], v[16:17], v[160:161]
	v_mov_b32_e32 v160, v158
	v_pk_fma_f32 v[156:157], v[14:15], v[164:165], v[156:157]
	v_mov_b32_e32 v161, v162
	v_pk_fma_f32 v[156:157], v[12:13], v[160:161], v[156:157]
	v_mov_b32_e32 v162, v159
	v_pk_fma_f32 v[156:157], v[10:11], v[162:163], v[156:157]
	s_nop 0
	v_add_f32_e32 v156, v100, v156
	v_add_f32_e32 v166, v156, v157
	ds_read_b128 v[156:159], v102 offset:12640
	ds_read_b128 v[160:163], v102 offset:12656
	s_waitcnt lgkmcnt(1)
	v_mov_b32_e32 v164, v156
	s_waitcnt lgkmcnt(0)
	v_mov_b32_e32 v165, v160
	v_mov_b32_e32 v160, v157
	v_pk_mul_f32 v[156:157], v[8:9], v[160:161]
	v_mov_b32_e32 v160, v158
	v_pk_fma_f32 v[156:157], v[6:7], v[164:165], v[156:157]
	v_mov_b32_e32 v161, v162
	v_pk_fma_f32 v[156:157], v[2:3], v[160:161], v[156:157]
	v_mov_b32_e32 v162, v159
	v_pk_fma_f32 v[156:157], v[0:1], v[162:163], v[156:157]
	s_nop 0
	v_add_f32_e32 v156, v166, v156
	v_add_f32_e32 v156, v156, v157
	v_min_f32_e32 v157, 0, v156
	v_mul_f32_e64 v156, |v156|, s68
	v_exp_f32_e32 v156, v156
	s_nop 0
	v_add_f32_e32 v156, 1.0, v156
	v_cmp_gt_f32_e32 vcc, s69, v156
	s_nop 1
	v_cndmask_b32_e64 v158, 0, 32, vcc
	v_ldexp_f32 v156, v156, v158
	v_log_f32_e32 v156, v156
	s_nop 0
	v_mul_f32_e32 v158, 0x3f317217, v156
	v_fma_f32 v158, v156, s70, -v158
	v_fmac_f32_e32 v158, 0x3377d1cf, v156
	v_fmac_f32_e32 v158, 0x3f317217, v156
	v_cmp_lt_f32_e64 s[0:1], |v156|, s71
	s_nop 1
	v_cndmask_b32_e64 v156, v156, v158, s[0:1]
	v_cndmask_b32_e32 v158, 0, v90, vcc
	v_sub_f32_e32 v156, v156, v158
	ds_read_b128 v[158:161], v102 offset:12672
	ds_read_b128 v[162:165], v102 offset:12688
	v_sub_f32_e32 v156, v157, v156
	v_fmamk_f32 v156, v156, 0x3d800000, v155
	s_waitcnt lgkmcnt(1)
	v_mov_b32_e32 v166, v158
	s_waitcnt lgkmcnt(0)
	v_mov_b32_e32 v167, v162
	v_mov_b32_e32 v162, v159
	v_pk_mul_f32 v[158:159], v[16:17], v[162:163]
	v_mov_b32_e32 v162, v160
	v_pk_fma_f32 v[158:159], v[14:15], v[166:167], v[158:159]
	v_mov_b32_e32 v163, v164
	v_pk_fma_f32 v[158:159], v[12:13], v[162:163], v[158:159]
	v_mov_b32_e32 v164, v161
	v_pk_fma_f32 v[158:159], v[10:11], v[164:165], v[158:159]
	s_nop 0
	v_add_f32_e32 v157, v100, v158
	v_add_f32_e32 v157, v157, v159
	ds_read_b128 v[158:161], v102 offset:12704
	ds_read_b128 v[162:165], v102 offset:12720
	s_waitcnt lgkmcnt(1)
	v_mov_b32_e32 v166, v158
	s_waitcnt lgkmcnt(0)
; #define LAS __attribute__((address_space(3)))
; __device__ __forceinline__ void gla_upd_unit(LAS unsigned char* wl, const bf16* PROJ, const float* R, const float* w_gk2, const float* b_gk, float* UPD, float* DEC, int unit, int lane) {
;     ...
;     float la[64]; float tot = 0.f;
; #pragma unroll
;     for (int t = 0; t < 64; ++t) {
;         const LAS f32x4* rr = (const LAS f32x4*)(wl + 9216) + t * 4;
;         float z = bias;
; #pragma unroll
;         for (int q = 0; q < 4; ++q) { const f32x4 rv = rr[q]; z += rv[0] * w[4 * q] + rv[1] * w[4 * q + 1] + rv[2] * w[4 * q + 2] + rv[3] * w[4 * q + 3]; }
;         la[t] = (fminf(z, 0.f) - __logf(1.0f + __expf(-fabsf(z)))) * (1.0f / 16.0f);
;         tot += la[t];
;     }
	v_mov_b32_e32 v167, v162
	v_mov_b32_e32 v162, v159
	v_pk_mul_f32 v[158:159], v[8:9], v[162:163]
	v_mov_b32_e32 v162, v160
	v_pk_fma_f32 v[158:159], v[6:7], v[166:167], v[158:159]
	v_mov_b32_e32 v163, v164
	v_pk_fma_f32 v[158:159], v[2:3], v[162:163], v[158:159]
	v_mov_b32_e32 v164, v161
	v_pk_fma_f32 v[158:159], v[0:1], v[164:165], v[158:159]
	s_nop 0
	v_add_f32_e32 v157, v157, v158
	v_add_f32_e32 v157, v157, v159
	v_min_f32_e32 v158, 0, v157
	v_mul_f32_e64 v157, |v157|, s68
	v_exp_f32_e32 v157, v157
	s_nop 0
	v_add_f32_e32 v157, 1.0, v157
	v_cmp_gt_f32_e32 vcc, s69, v157
	s_nop 1
	v_cndmask_b32_e64 v159, 0, 32, vcc
	v_ldexp_f32 v157, v157, v159
	v_log_f32_e32 v157, v157
	s_nop 0
	v_mul_f32_e32 v159, 0x3f317217, v157
	v_fma_f32 v159, v157, s70, -v159
	v_fmac_f32_e32 v159, 0x3377d1cf, v157
	v_fmac_f32_e32 v159, 0x3f317217, v157
	v_cmp_lt_f32_e64 s[0:1], |v157|, s71
	s_nop 1
	v_cndmask_b32_e64 v157, v157, v159, s[0:1]
	v_cndmask_b32_e32 v159, 0, v90, vcc
	v_sub_f32_e32 v157, v157, v159
	v_sub_f32_e32 v157, v158, v157
	ds_read_b128 v[158:161], v102 offset:12736
	ds_read_b128 v[162:165], v102 offset:12752
	v_fmamk_f32 v157, v157, 0x3d800000, v156
	s_waitcnt lgkmcnt(1)
	v_mov_b32_e32 v166, v158
	s_waitcnt lgkmcnt(0)
	v_mov_b32_e32 v167, v162
	v_mov_b32_e32 v162, v159
	v_pk_mul_f32 v[158:159], v[16:17], v[162:163]
	v_mov_b32_e32 v162, v160
	v_pk_fma_f32 v[158:159], v[14:15], v[166:167], v[158:159]
	v_mov_b32_e32 v163, v164
	v_pk_fma_f32 v[158:159], v[12:13], v[162:163], v[158:159]
	v_mov_b32_e32 v164, v161
	v_pk_fma_f32 v[158:159], v[10:11], v[164:165], v[158:159]
	s_nop 0
	v_add_f32_e32 v158, v100, v158
	v_add_f32_e32 v168, v158, v159
	ds_read_b128 v[158:161], v102 offset:12768
	ds_read_b128 v[162:165], v102 offset:12784
	s_waitcnt lgkmcnt(1)
	v_mov_b32_e32 v166, v158
	s_waitcnt lgkmcnt(0)
	v_mov_b32_e32 v167, v162
	v_mov_b32_e32 v162, v159
	v_pk_mul_f32 v[158:159], v[8:9], v[162:163]
	v_mov_b32_e32 v162, v160
	v_pk_fma_f32 v[158:159], v[6:7], v[166:167], v[158:159]
	v_mov_b32_e32 v163, v164
	v_pk_fma_f32 v[158:159], v[2:3], v[162:163], v[158:159]
	v_mov_b32_e32 v164, v161
	v_pk_fma_f32 v[158:159], v[0:1], v[164:165], v[158:159]
	s_nop 0
	v_add_f32_e32 v158, v168, v158
	v_add_f32_e32 v158, v158, v159
	v_min_f32_e32 v159, 0, v158
	v_mul_f32_e64 v158, |v158|, s68
	v_exp_f32_e32 v158, v158
	s_nop 0
	v_add_f32_e32 v158, 1.0, v158
	v_cmp_gt_f32_e32 vcc, s69, v158
	s_nop 1
	v_cndmask_b32_e64 v160, 0, 32, vcc
	v_ldexp_f32 v158, v158, v160
	v_log_f32_e32 v158, v158
	s_nop 0
	v_mul_f32_e32 v160, 0x3f317217, v158
	v_fma_f32 v160, v158, s70, -v160
	v_fmac_f32_e32 v160, 0x3377d1cf, v158
	v_fmac_f32_e32 v160, 0x3f317217, v158
	v_cmp_lt_f32_e64 s[0:1], |v158|, s71
	s_nop 1
	v_cndmask_b32_e64 v158, v158, v160, s[0:1]
	v_cndmask_b32_e32 v160, 0, v90, vcc
	v_sub_f32_e32 v158, v158, v160
	ds_read_b128 v[160:163], v102 offset:12800
	ds_read_b128 v[164:167], v102 offset:12816
	v_sub_f32_e32 v158, v159, v158
	v_fmamk_f32 v158, v158, 0x3d800000, v157
	s_waitcnt lgkmcnt(1)
	v_mov_b32_e32 v168, v160
	s_waitcnt lgkmcnt(0)
	v_mov_b32_e32 v169, v164
	v_mov_b32_e32 v164, v161
	v_pk_mul_f32 v[160:161], v[16:17], v[164:165]
	v_mov_b32_e32 v164, v162
	v_pk_fma_f32 v[160:161], v[14:15], v[168:169], v[160:161]
	v_mov_b32_e32 v165, v166
	v_pk_fma_f32 v[160:161], v[12:13], v[164:165], v[160:161]
	v_mov_b32_e32 v166, v163
	v_pk_fma_f32 v[160:161], v[10:11], v[166:167], v[160:161]
	s_nop 0
	v_add_f32_e32 v159, v100, v160
	v_add_f32_e32 v159, v159, v161
	ds_read_b128 v[160:163], v102 offset:12832
	ds_read_b128 v[164:167], v102 offset:12848
	s_waitcnt lgkmcnt(1)
	v_mov_b32_e32 v168, v160
	s_waitcnt lgkmcnt(0)
	v_mov_b32_e32 v169, v164
	v_mov_b32_e32 v164, v161
	v_pk_mul_f32 v[160:161], v[8:9], v[164:165]
	v_mov_b32_e32 v164, v162
	v_pk_fma_f32 v[160:161], v[6:7], v[168:169], v[160:161]
	v_mov_b32_e32 v165, v166
	v_pk_fma_f32 v[160:161], v[2:3], v[164:165], v[160:161]
	v_mov_b32_e32 v166, v163
	v_pk_fma_f32 v[160:161], v[0:1], v[166:167], v[160:161]
	s_nop 0
	v_add_f32_e32 v159, v159, v160
	v_add_f32_e32 v159, v159, v161
	v_min_f32_e32 v160, 0, v159
	v_mul_f32_e64 v159, |v159|, s68
	v_exp_f32_e32 v159, v159
	s_nop 0
	v_add_f32_e32 v159, 1.0, v159
	v_cmp_gt_f32_e32 vcc, s69, v159
	s_nop 1
	v_cndmask_b32_e64 v161, 0, 32, vcc
	v_ldexp_f32 v159, v159, v161
	v_log_f32_e32 v159, v159
	s_nop 0
	v_mul_f32_e32 v161, 0x3f317217, v159
	v_fma_f32 v161, v159, s70, -v161
	v_fmac_f32_e32 v161, 0x3377d1cf, v159
	v_fmac_f32_e32 v161, 0x3f317217, v159
	v_cmp_lt_f32_e64 s[0:1], |v159|, s71
	s_nop 1
	v_cndmask_b32_e64 v159, v159, v161, s[0:1]
	v_cndmask_b32_e32 v161, 0, v90, vcc
	v_sub_f32_e32 v159, v159, v161
	v_sub_f32_e32 v159, v160, v159
	ds_read_b128 v[160:163], v102 offset:12864
	ds_read_b128 v[164:167], v102 offset:12880
	v_fmamk_f32 v159, v159, 0x3d800000, v158
	s_waitcnt lgkmcnt(1)
	v_mov_b32_e32 v168, v160
	s_waitcnt lgkmcnt(0)
	v_mov_b32_e32 v169, v164
	v_mov_b32_e32 v164, v161
	v_pk_mul_f32 v[160:161], v[16:17], v[164:165]
	v_mov_b32_e32 v164, v162
	v_pk_fma_f32 v[160:161], v[14:15], v[168:169], v[160:161]
	v_mov_b32_e32 v165, v166
	v_pk_fma_f32 v[160:161], v[12:13], v[164:165], v[160:161]
	v_mov_b32_e32 v166, v163
	v_pk_fma_f32 v[160:161], v[10:11], v[166:167], v[160:161]
	s_nop 0
	v_add_f32_e32 v160, v100, v160
	v_add_f32_e32 v170, v160, v161
	ds_read_b128 v[160:163], v102 offset:12896
	ds_read_b128 v[164:167], v102 offset:12912
	s_waitcnt lgkmcnt(1)
	v_mov_b32_e32 v168, v160
	s_waitcnt lgkmcnt(0)
; #define LAS __attribute__((address_space(3)))
; __device__ __forceinline__ void gla_upd_unit(LAS unsigned char* wl, const bf16* PROJ, const float* R, const float* w_gk2, const float* b_gk, float* UPD, float* DEC, int unit, int lane) {
;     ...
;     float la[64]; float tot = 0.f;
; #pragma unroll
;     for (int t = 0; t < 64; ++t) {
;         const LAS f32x4* rr = (const LAS f32x4*)(wl + 9216) + t * 4;
;         float z = bias;
; #pragma unroll
;         for (int q = 0; q < 4; ++q) { const f32x4 rv = rr[q]; z += rv[0] * w[4 * q] + rv[1] * w[4 * q + 1] + rv[2] * w[4 * q + 2] + rv[3] * w[4 * q + 3]; }
;         la[t] = (fminf(z, 0.f) - __logf(1.0f + __expf(-fabsf(z)))) * (1.0f / 16.0f);
;         tot += la[t];
;     }
	v_mov_b32_e32 v169, v164
	v_mov_b32_e32 v164, v161
	v_pk_mul_f32 v[160:161], v[8:9], v[164:165]
	v_mov_b32_e32 v164, v162
	v_pk_fma_f32 v[160:161], v[6:7], v[168:169], v[160:161]
	v_mov_b32_e32 v165, v166
	v_pk_fma_f32 v[160:161], v[2:3], v[164:165], v[160:161]
	v_mov_b32_e32 v166, v163
	v_pk_fma_f32 v[160:161], v[0:1], v[166:167], v[160:161]
	s_nop 0
	v_add_f32_e32 v160, v170, v160
	v_add_f32_e32 v160, v160, v161
	v_min_f32_e32 v161, 0, v160
	v_mul_f32_e64 v160, |v160|, s68
	v_exp_f32_e32 v160, v160
	s_nop 0
	v_add_f32_e32 v160, 1.0, v160
	v_cmp_gt_f32_e32 vcc, s69, v160
	s_nop 1
	v_cndmask_b32_e64 v162, 0, 32, vcc
	v_ldexp_f32 v160, v160, v162
	v_log_f32_e32 v160, v160
	s_nop 0
	v_mul_f32_e32 v162, 0x3f317217, v160
	v_fma_f32 v162, v160, s70, -v162
	v_fmac_f32_e32 v162, 0x3377d1cf, v160
	v_fmac_f32_e32 v162, 0x3f317217, v160
	v_cmp_lt_f32_e64 s[0:1], |v160|, s71
	s_nop 1
	v_cndmask_b32_e64 v160, v160, v162, s[0:1]
	v_cndmask_b32_e32 v162, 0, v90, vcc
	v_sub_f32_e32 v160, v160, v162
	ds_read_b128 v[162:165], v102 offset:12928
	ds_read_b128 v[166:169], v102 offset:12944
	v_sub_f32_e32 v160, v161, v160
	v_fmamk_f32 v160, v160, 0x3d800000, v159
	s_waitcnt lgkmcnt(1)
	v_mov_b32_e32 v170, v162
	s_waitcnt lgkmcnt(0)
	v_mov_b32_e32 v171, v166
	v_mov_b32_e32 v166, v163
	v_pk_mul_f32 v[162:163], v[16:17], v[166:167]
	v_mov_b32_e32 v166, v164
	v_pk_fma_f32 v[162:163], v[14:15], v[170:171], v[162:163]
	v_mov_b32_e32 v167, v168
	v_pk_fma_f32 v[162:163], v[12:13], v[166:167], v[162:163]
	v_mov_b32_e32 v168, v165
	v_pk_fma_f32 v[162:163], v[10:11], v[168:169], v[162:163]
	s_nop 0
	v_add_f32_e32 v161, v100, v162
	v_add_f32_e32 v161, v161, v163
	ds_read_b128 v[162:165], v102 offset:12960
	ds_read_b128 v[166:169], v102 offset:12976
	s_waitcnt lgkmcnt(1)
	v_mov_b32_e32 v170, v162
	s_waitcnt lgkmcnt(0)
	v_mov_b32_e32 v171, v166
	v_mov_b32_e32 v166, v163
	v_pk_mul_f32 v[162:163], v[8:9], v[166:167]
	v_mov_b32_e32 v166, v164
	v_pk_fma_f32 v[162:163], v[6:7], v[170:171], v[162:163]
	v_mov_b32_e32 v167, v168
	v_pk_fma_f32 v[162:163], v[2:3], v[166:167], v[162:163]
	v_mov_b32_e32 v168, v165
	v_pk_fma_f32 v[162:163], v[0:1], v[168:169], v[162:163]
	s_nop 0
	v_add_f32_e32 v161, v161, v162
	v_add_f32_e32 v161, v161, v163
	v_min_f32_e32 v162, 0, v161
	v_mul_f32_e64 v161, |v161|, s68
	v_exp_f32_e32 v161, v161
	s_nop 0
	v_add_f32_e32 v161, 1.0, v161
	v_cmp_gt_f32_e32 vcc, s69, v161
	s_nop 1
	v_cndmask_b32_e64 v163, 0, 32, vcc
	v_ldexp_f32 v161, v161, v163
	v_log_f32_e32 v161, v161
	s_nop 0
	v_mul_f32_e32 v163, 0x3f317217, v161
	v_fma_f32 v163, v161, s70, -v163
	v_fmac_f32_e32 v163, 0x3377d1cf, v161
	v_fmac_f32_e32 v163, 0x3f317217, v161
	v_cmp_lt_f32_e64 s[0:1], |v161|, s71
	s_nop 1
	v_cndmask_b32_e64 v161, v161, v163, s[0:1]
	v_cndmask_b32_e32 v163, 0, v90, vcc
	v_sub_f32_e32 v161, v161, v163
	v_sub_f32_e32 v161, v162, v161
	ds_read_b128 v[162:165], v102 offset:12992
	ds_read_b128 v[166:169], v102 offset:13008
	v_fmamk_f32 v161, v161, 0x3d800000, v160
	s_waitcnt lgkmcnt(1)
	v_mov_b32_e32 v170, v162
	s_waitcnt lgkmcnt(0)
	v_mov_b32_e32 v171, v166
	v_mov_b32_e32 v166, v163
	v_pk_mul_f32 v[162:163], v[16:17], v[166:167]
	v_mov_b32_e32 v166, v164
	v_pk_fma_f32 v[162:163], v[14:15], v[170:171], v[162:163]
	v_mov_b32_e32 v167, v168
	v_pk_fma_f32 v[162:163], v[12:13], v[166:167], v[162:163]
	v_mov_b32_e32 v168, v165
	v_pk_fma_f32 v[162:163], v[10:11], v[168:169], v[162:163]
	s_nop 0
	v_add_f32_e32 v162, v100, v162
	v_add_f32_e32 v172, v162, v163
	ds_read_b128 v[162:165], v102 offset:13024
	ds_read_b128 v[166:169], v102 offset:13040
	s_waitcnt lgkmcnt(1)
	v_mov_b32_e32 v170, v162
	s_waitcnt lgkmcnt(0)
	v_mov_b32_e32 v171, v166
	v_mov_b32_e32 v166, v163
	v_pk_mul_f32 v[162:163], v[8:9], v[166:167]
	v_mov_b32_e32 v166, v164
	v_pk_fma_f32 v[162:163], v[6:7], v[170:171], v[162:163]
	v_mov_b32_e32 v167, v168
	v_pk_fma_f32 v[162:163], v[2:3], v[166:167], v[162:163]
	v_mov_b32_e32 v168, v165
	v_pk_fma_f32 v[162:163], v[0:1], v[168:169], v[162:163]
	s_nop 0
	v_add_f32_e32 v162, v172, v162
	v_add_f32_e32 v162, v162, v163
	v_min_f32_e32 v163, 0, v162
	v_mul_f32_e64 v162, |v162|, s68
	v_exp_f32_e32 v162, v162
	s_nop 0
	v_add_f32_e32 v162, 1.0, v162
	v_cmp_gt_f32_e32 vcc, s69, v162
	s_nop 1
	v_cndmask_b32_e64 v164, 0, 32, vcc
	v_ldexp_f32 v162, v162, v164
	v_log_f32_e32 v162, v162
	s_nop 0
	v_mul_f32_e32 v164, 0x3f317217, v162
	v_fma_f32 v164, v162, s70, -v164
	v_fmac_f32_e32 v164, 0x3377d1cf, v162
	v_fmac_f32_e32 v164, 0x3f317217, v162
	v_cmp_lt_f32_e64 s[0:1], |v162|, s71
	s_nop 1
	v_cndmask_b32_e64 v162, v162, v164, s[0:1]
	v_cndmask_b32_e32 v164, 0, v90, vcc
	v_sub_f32_e32 v162, v162, v164
	ds_read_b128 v[164:167], v102 offset:13056
	ds_read_b128 v[168:171], v102 offset:13072
	v_sub_f32_e32 v162, v163, v162
	v_fmamk_f32 v162, v162, 0x3d800000, v161
	s_waitcnt lgkmcnt(1)
	v_mov_b32_e32 v172, v164
	s_waitcnt lgkmcnt(0)
	v_mov_b32_e32 v173, v168
	v_mov_b32_e32 v168, v165
	v_pk_mul_f32 v[164:165], v[16:17], v[168:169]
	v_mov_b32_e32 v168, v166
	v_pk_fma_f32 v[164:165], v[14:15], v[172:173], v[164:165]
	v_mov_b32_e32 v169, v170
	v_pk_fma_f32 v[164:165], v[12:13], v[168:169], v[164:165]
	v_mov_b32_e32 v170, v167
	v_pk_fma_f32 v[164:165], v[10:11], v[170:171], v[164:165]
	s_nop 0
	v_add_f32_e32 v163, v100, v164
	v_add_f32_e32 v163, v163, v165
	ds_read_b128 v[164:167], v102 offset:13088
	ds_read_b128 v[168:171], v102 offset:13104
	s_waitcnt lgkmcnt(1)
	v_mov_b32_e32 v172, v164
	s_waitcnt lgkmcnt(0)
; #define LAS __attribute__((address_space(3)))
; __device__ __forceinline__ void gla_upd_unit(LAS unsigned char* wl, const bf16* PROJ, const float* R, const float* w_gk2, const float* b_gk, float* UPD, float* DEC, int unit, int lane) {
;     ...
;     float la[64]; float tot = 0.f;
; #pragma unroll
;     for (int t = 0; t < 64; ++t) {
;         const LAS f32x4* rr = (const LAS f32x4*)(wl + 9216) + t * 4;
;         float z = bias;
; #pragma unroll
;         for (int q = 0; q < 4; ++q) { const f32x4 rv = rr[q]; z += rv[0] * w[4 * q] + rv[1] * w[4 * q + 1] + rv[2] * w[4 * q + 2] + rv[3] * w[4 * q + 3]; }
;         la[t] = (fminf(z, 0.f) - __logf(1.0f + __expf(-fabsf(z)))) * (1.0f / 16.0f);
;         tot += la[t];
;     }
	v_mov_b32_e32 v173, v168
	v_mov_b32_e32 v168, v165
	v_pk_mul_f32 v[164:165], v[8:9], v[168:169]
	v_mov_b32_e32 v168, v166
	v_pk_fma_f32 v[164:165], v[6:7], v[172:173], v[164:165]
	v_mov_b32_e32 v169, v170
	v_pk_fma_f32 v[164:165], v[2:3], v[168:169], v[164:165]
	v_mov_b32_e32 v170, v167
	v_pk_fma_f32 v[164:165], v[0:1], v[170:171], v[164:165]
	s_nop 0
	v_add_f32_e32 v163, v163, v164
	v_add_f32_e32 v163, v163, v165
	v_min_f32_e32 v164, 0, v163
	v_mul_f32_e64 v163, |v163|, s68
	v_exp_f32_e32 v163, v163
	s_nop 0
	v_add_f32_e32 v163, 1.0, v163
	v_cmp_gt_f32_e32 vcc, s69, v163
	s_nop 1
	v_cndmask_b32_e64 v165, 0, 32, vcc
	v_ldexp_f32 v163, v163, v165
	v_log_f32_e32 v163, v163
	s_nop 0
	v_mul_f32_e32 v165, 0x3f317217, v163
	v_fma_f32 v165, v163, s70, -v165
	v_fmac_f32_e32 v165, 0x3377d1cf, v163
	v_fmac_f32_e32 v165, 0x3f317217, v163
	v_cmp_lt_f32_e64 s[0:1], |v163|, s71
	s_nop 1
	v_cndmask_b32_e64 v163, v163, v165, s[0:1]
	v_cndmask_b32_e32 v165, 0, v90, vcc
	v_sub_f32_e32 v163, v163, v165
	v_sub_f32_e32 v163, v164, v163
	ds_read_b128 v[164:167], v102 offset:13120
	ds_read_b128 v[168:171], v102 offset:13136
	v_fmamk_f32 v163, v163, 0x3d800000, v162
	s_waitcnt lgkmcnt(1)
	v_mov_b32_e32 v172, v164
	s_waitcnt lgkmcnt(0)
	v_mov_b32_e32 v173, v168
	v_mov_b32_e32 v168, v165
	v_pk_mul_f32 v[164:165], v[16:17], v[168:169]
	v_mov_b32_e32 v168, v166
	v_pk_fma_f32 v[164:165], v[14:15], v[172:173], v[164:165]
	v_mov_b32_e32 v169, v170
	v_pk_fma_f32 v[164:165], v[12:13], v[168:169], v[164:165]
	v_mov_b32_e32 v170, v167
	v_pk_fma_f32 v[164:165], v[10:11], v[170:171], v[164:165]
	s_nop 0
	v_add_f32_e32 v164, v100, v164
	v_add_f32_e32 v174, v164, v165
	ds_read_b128 v[164:167], v102 offset:13152
	ds_read_b128 v[168:171], v102 offset:13168
	s_waitcnt lgkmcnt(1)
	v_mov_b32_e32 v172, v164
	s_waitcnt lgkmcnt(0)
	v_mov_b32_e32 v173, v168
	v_mov_b32_e32 v168, v165
	v_pk_mul_f32 v[164:165], v[8:9], v[168:169]
	v_mov_b32_e32 v168, v166
	v_pk_fma_f32 v[164:165], v[6:7], v[172:173], v[164:165]
	v_mov_b32_e32 v169, v170
	v_pk_fma_f32 v[164:165], v[2:3], v[168:169], v[164:165]
	v_mov_b32_e32 v170, v167
	v_pk_fma_f32 v[164:165], v[0:1], v[170:171], v[164:165]
	s_nop 0
	v_add_f32_e32 v164, v174, v164
	v_add_f32_e32 v164, v164, v165
	v_min_f32_e32 v165, 0, v164
	v_mul_f32_e64 v164, |v164|, s68
	v_exp_f32_e32 v164, v164
	s_nop 0
	v_add_f32_e32 v164, 1.0, v164
	v_cmp_gt_f32_e32 vcc, s69, v164
	s_nop 1
	v_cndmask_b32_e64 v166, 0, 32, vcc
	v_ldexp_f32 v164, v164, v166
	v_log_f32_e32 v164, v164
	s_nop 0
	v_mul_f32_e32 v166, 0x3f317217, v164
	v_fma_f32 v166, v164, s70, -v166
	v_fmac_f32_e32 v166, 0x3377d1cf, v164
	v_fmac_f32_e32 v166, 0x3f317217, v164
	v_cmp_lt_f32_e64 s[0:1], |v164|, s71
	s_nop 1
	v_cndmask_b32_e64 v164, v164, v166, s[0:1]
	v_cndmask_b32_e32 v166, 0, v90, vcc
	v_sub_f32_e32 v164, v164, v166
	ds_read_b128 v[166:169], v102 offset:13184
	ds_read_b128 v[170:173], v102 offset:13200
	v_sub_f32_e32 v164, v165, v164
	v_fmamk_f32 v164, v164, 0x3d800000, v163
	s_waitcnt lgkmcnt(1)
	v_mov_b32_e32 v174, v166
	s_waitcnt lgkmcnt(0)
	v_mov_b32_e32 v175, v170
	v_mov_b32_e32 v170, v167
	v_pk_mul_f32 v[166:167], v[16:17], v[170:171]
	v_mov_b32_e32 v170, v168
	v_pk_fma_f32 v[166:167], v[14:15], v[174:175], v[166:167]
	v_mov_b32_e32 v171, v172
	v_pk_fma_f32 v[166:167], v[12:13], v[170:171], v[166:167]
	v_mov_b32_e32 v172, v169
	v_pk_fma_f32 v[166:167], v[10:11], v[172:173], v[166:167]
	s_nop 0
	v_add_f32_e32 v165, v100, v166
	v_add_f32_e32 v165, v165, v167
	ds_read_b128 v[166:169], v102 offset:13216
	ds_read_b128 v[170:173], v102 offset:13232
	s_waitcnt lgkmcnt(1)
	v_mov_b32_e32 v174, v166
	s_waitcnt lgkmcnt(0)
	v_mov_b32_e32 v175, v170
	v_mov_b32_e32 v170, v167
	v_pk_mul_f32 v[166:167], v[8:9], v[170:171]
	v_mov_b32_e32 v170, v168
	v_pk_fma_f32 v[166:167], v[6:7], v[174:175], v[166:167]
	v_mov_b32_e32 v171, v172
	v_pk_fma_f32 v[166:167], v[2:3], v[170:171], v[166:167]
	v_mov_b32_e32 v172, v169
	v_pk_fma_f32 v[166:167], v[0:1], v[172:173], v[166:167]
	s_nop 0
	v_add_f32_e32 v165, v165, v166
	v_add_f32_e32 v165, v165, v167
	v_min_f32_e32 v166, 0, v165
	v_mul_f32_e64 v165, |v165|, s68
	v_exp_f32_e32 v165, v165
	s_nop 0
	v_add_f32_e32 v165, 1.0, v165
	v_cmp_gt_f32_e32 vcc, s69, v165
	s_nop 1
	v_cndmask_b32_e64 v167, 0, 32, vcc
	v_ldexp_f32 v165, v165, v167
	v_log_f32_e32 v165, v165
	s_nop 0
	v_mul_f32_e32 v167, 0x3f317217, v165
	v_fma_f32 v167, v165, s70, -v167
	v_fmac_f32_e32 v167, 0x3377d1cf, v165
	v_fmac_f32_e32 v167, 0x3f317217, v165
	v_cmp_lt_f32_e64 s[0:1], |v165|, s71
	s_nop 1
	v_cndmask_b32_e64 v165, v165, v167, s[0:1]
	v_cndmask_b32_e32 v167, 0, v90, vcc
	v_sub_f32_e32 v165, v165, v167
	v_sub_f32_e32 v165, v166, v165
	ds_read_b128 v[166:169], v102 offset:13248
	ds_read_b128 v[170:173], v102 offset:13264
	v_fmamk_f32 v165, v165, 0x3d800000, v164
	s_waitcnt lgkmcnt(1)
	v_mov_b32_e32 v174, v166
	s_waitcnt lgkmcnt(0)
	v_mov_b32_e32 v175, v170
	v_mov_b32_e32 v170, v167
	v_pk_mul_f32 v[16:17], v[16:17], v[170:171]
	s_nop 0
	v_pk_fma_f32 v[14:15], v[14:15], v[174:175], v[16:17]
	v_mov_b32_e32 v16, v168
	v_mov_b32_e32 v17, v172
	v_pk_fma_f32 v[12:13], v[12:13], v[16:17], v[14:15]
	v_mov_b32_e32 v172, v169
	v_pk_fma_f32 v[10:11], v[10:11], v[172:173], v[12:13]
	s_nop 0
	v_add_f32_e32 v10, v100, v10
	v_add_f32_e32 v100, v10, v11
	ds_read_b128 v[10:13], v102 offset:13280
	ds_read_b128 v[14:17], v102 offset:13296
	s_waitcnt lgkmcnt(1)
	v_mov_b32_e32 v166, v10
	s_waitcnt lgkmcnt(0)
; #define LAS __attribute__((address_space(3)))
; __device__ __forceinline__ unsigned pk2(float lo, float hi) { return f2bf(lo) | (f2bf(hi) << 16); }
; __device__ __forceinline__ void gla_upd_unit(LAS unsigned char* wl, const bf16* PROJ, const float* R, const float* w_gk2, const float* b_gk, float* UPD, float* DEC, int unit, int lane) {
;     ...
;     for (int t = 0; t < 64; ++t) {
;         const LAS f32x4* rr = (const LAS f32x4*)(wl + 9216) + t * 4;
;         float z = bias;
; #pragma unroll
;         for (int q = 0; q < 4; ++q) { const f32x4 rv = rr[q]; z += rv[0] * w[4 * q] + rv[1] * w[4 * q + 1] + rv[2] * w[4 * q + 2] + rv[3] * w[4 * q + 3]; }
;         la[t] = (fminf(z, 0.f) - __logf(1.0f + __expf(-fabsf(z)))) * (1.0f / 16.0f);
;         tot += la[t];
;     }
;     DEC[(size_t)unit * 64 + kk] = __expf(tot);
; #pragma unroll
;     for (int t = 0; t < 32; ++t) kv1[t] = kp[(size_t)(t + 32) * NPROJ];
;     float run = 0.f;
; #pragma unroll
;     for (int t = 0; t < 32; t += 2) {
;         run += la[t]; const float d0 = bf2f(kv0[t]) * __expf(tot - run);
;         run += la[t + 1]; const float d1 = bf2f(kv0[t + 1]) * __expf(tot - run);
;         KD32[kk * (KS / 2) + (t >> 1)] = pk2(d0, d1);
;     }
; #pragma unroll
;     for (int t = 0; t < 32; t += 2) {
;         run += la[32 + t]; const float d0 = bf2f(kv1[t]) * __expf(tot - run);
;         run += la[33 + t]; const float d1 = bf2f(kv1[t + 1]) * __expf(tot - run);
;         KD32[kk * (KS / 2) + 16 + (t >> 1)] = pk2(d0, d1);
;     }
	v_mov_b32_e32 v167, v14
	v_mov_b32_e32 v14, v11
	v_pk_mul_f32 v[8:9], v[8:9], v[14:15]
	v_lshlrev_b32_e32 v11, 16, v96
	v_pk_fma_f32 v[6:7], v[6:7], v[166:167], v[8:9]
	v_mov_b32_e32 v8, v12
	v_mov_b32_e32 v9, v16
	v_pk_fma_f32 v[2:3], v[2:3], v[8:9], v[6:7]
	v_mov_b32_e32 v16, v13
	v_pk_fma_f32 v[0:1], v[0:1], v[16:17], v[2:3]
	v_lshlrev_b32_e32 v9, 16, v92
	v_add_f32_e32 v0, v100, v0
	v_add_f32_e32 v0, v0, v1
	v_min_f32_e32 v1, 0, v0
	v_mul_f32_e64 v0, |v0|, s68
	v_exp_f32_e32 v0, v0
	v_lshlrev_b32_e32 v8, 16, v93
	v_lshlrev_b32_e32 v10, 16, v94
	v_add_f32_e32 v0, 1.0, v0
	v_cmp_gt_f32_e32 vcc, s69, v0
	s_nop 1
	v_cndmask_b32_e64 v2, 0, 32, vcc
	v_ldexp_f32 v0, v0, v2
	v_log_f32_e32 v0, v0
	s_nop 0
	v_mul_f32_e32 v2, 0x3f317217, v0
	v_fma_f32 v2, v0, s70, -v2
	v_fmac_f32_e32 v2, 0x3377d1cf, v0
	v_fmac_f32_e32 v2, 0x3f317217, v0
	v_cmp_lt_f32_e64 s[0:1], |v0|, s71
	s_nop 1
	v_cndmask_b32_e64 v0, v0, v2, s[0:1]
	v_cndmask_b32_e32 v2, 0, v90, vcc
	v_sub_f32_e32 v0, v0, v2
	v_sub_f32_e32 v0, v1, v0
	v_fmamk_f32 v6, v0, 0x3d800000, v165
	v_mul_f32_e32 v0, 0x3fb8aa3b, v6
	v_exp_f32_e32 v2, v0
	s_lshl_b64 s[0:1], s[64:65], 8
	v_lshl_add_u64 v[0:1], v[24:25], 0, s[0:1]
	v_sub_f32_e32 v3, v6, v105
	global_store_dword v[0:1], v2, off
	v_sub_f32_e32 v1, v6, v103
	v_mul_f32_e32 v1, 0x3fb8aa3b, v1
	v_sub_f32_e32 v0, v6, v101
	v_exp_f32_e32 v2, v1
	v_sub_f32_e32 v1, v6, v104
	v_mul_f32_e32 v0, 0x3fb8aa3b, v0
	v_mul_f32_e32 v1, 0x3fb8aa3b, v1
	v_exp_f32_e32 v0, v0
	v_exp_f32_e32 v1, v1
	v_mul_f32_e32 v3, 0x3fb8aa3b, v3
	v_exp_f32_e32 v3, v3
	s_mov_b32 s0, 0x2c000
	v_pk_mul_f32 v[0:1], v[0:1], v[8:9]
	v_lshlrev_b32_e32 v9, 16, v97
	v_lshlrev_b32_e32 v8, 16, v95
	v_pk_mul_f32 v[2:3], v[2:3], v[8:9]
	v_and_b32_sdwa v7, v1, v91 dst_sel:DWORD dst_unused:UNUSED_PAD src0_sel:WORD_1 src1_sel:DWORD
	v_add3_u32 v1, v1, v7, s72
	v_and_b32_sdwa v7, v3, v91 dst_sel:DWORD dst_unused:UNUSED_PAD src0_sel:WORD_1 src1_sel:DWORD
	v_and_b32_sdwa v8, v0, v91 dst_sel:DWORD dst_unused:UNUSED_PAD src0_sel:WORD_1 src1_sel:DWORD
	v_add3_u32 v3, v3, v7, s72
	v_add3_u32 v0, v0, v8, s72
	v_and_b32_sdwa v8, v2, v91 dst_sel:DWORD dst_unused:UNUSED_PAD src0_sel:WORD_1 src1_sel:DWORD
	v_and_b32_e32 v3, 0xffff0000, v3
	v_add3_u32 v2, v2, v8, s72
	v_or_b32_sdwa v1, v3, v1 dst_sel:DWORD dst_unused:UNUSED_PAD src0_sel:DWORD src1_sel:WORD_1
	v_sub_f32_e32 v3, v6, v107
	v_and_b32_e32 v2, 0xffff0000, v2
	v_mul_f32_e32 v3, 0x3fb8aa3b, v3
	v_or_b32_sdwa v0, v2, v0 dst_sel:DWORD dst_unused:UNUSED_PAD src0_sel:DWORD src1_sel:WORD_1
	v_sub_f32_e32 v2, v6, v106
	v_exp_f32_e32 v8, v3
	v_sub_f32_e32 v3, v6, v109
	v_mul_f32_e32 v2, 0x3fb8aa3b, v2
	v_mul_f32_e32 v3, 0x3fb8aa3b, v3
	v_sub_f32_e32 v7, v6, v111
	v_exp_f32_e32 v2, v2
	v_exp_f32_e32 v3, v3
	v_mul_f32_e32 v7, 0x3fb8aa3b, v7
	v_exp_f32_e32 v9, v7
	v_pk_mul_f32 v[2:3], v[2:3], v[10:11]
	v_lshlrev_b32_e32 v11, 16, v99
	v_lshlrev_b32_e32 v10, 16, v98
	v_pk_mul_f32 v[8:9], v[8:9], v[10:11]
	v_and_b32_sdwa v10, v2, v91 dst_sel:DWORD dst_unused:UNUSED_PAD src0_sel:WORD_1 src1_sel:DWORD
	v_add3_u32 v2, v2, v10, s72
	v_and_b32_sdwa v10, v8, v91 dst_sel:DWORD dst_unused:UNUSED_PAD src0_sel:WORD_1 src1_sel:DWORD
	v_add3_u32 v8, v8, v10, s72
	v_and_b32_sdwa v7, v3, v91 dst_sel:DWORD dst_unused:UNUSED_PAD src0_sel:WORD_1 src1_sel:DWORD
	v_and_b32_e32 v8, 0xffff0000, v8
	v_add3_u32 v3, v3, v7, s72
	v_and_b32_sdwa v7, v9, v91 dst_sel:DWORD dst_unused:UNUSED_PAD src0_sel:WORD_1 src1_sel:DWORD
	v_or_b32_sdwa v2, v8, v2 dst_sel:DWORD dst_unused:UNUSED_PAD src0_sel:DWORD src1_sel:WORD_1
	v_add_co_u32_e32 v8, vcc, s0, v4
	v_add3_u32 v7, v9, v7, s72
	s_nop 0
	v_addc_co_u32_e32 v9, vcc, 0, v5, vcc
	s_mov_b32 s0, 0x2f000
	v_add_co_u32_e32 v10, vcc, s0, v4
	s_mov_b32 s0, 0x2e000
	s_nop 0
	v_addc_co_u32_e32 v11, vcc, 0, v5, vcc
	global_load_ushort v15, v[10:11], off offset:1536 nt
	v_add_co_u32_e32 v10, vcc, s0, v4
	s_mov_b32 s0, 0x30000
	s_nop 0
	v_addc_co_u32_e32 v11, vcc, 0, v5, vcc
	global_load_ushort v8, v[8:9], off offset:2560 nt
	v_and_b32_e32 v7, 0xffff0000, v7
	global_load_ushort v17, v[10:11], off nt
	v_add_co_u32_e32 v10, vcc, s0, v4
	s_mov_b32 s0, 0x32000
	s_nop 0
	v_addc_co_u32_e32 v11, vcc, 0, v5, vcc
	global_load_ushort v105, v[10:11], off offset:3072 nt
	v_add_co_u32_e32 v10, vcc, s0, v4
	s_mov_b32 s0, 0x34000
	s_nop 0
	v_addc_co_u32_e32 v11, vcc, 0, v5, vcc
	v_or_b32_sdwa v3, v7, v3 dst_sel:DWORD dst_unused:UNUSED_PAD src0_sel:DWORD src1_sel:WORD_1
	global_load_ushort v7, v[10:11], off offset:512 nt
	v_add_co_u32_e32 v10, vcc, s0, v4
	s_mov_b32 s0, 0x33000
	s_nop 0
	v_addc_co_u32_e32 v11, vcc, 0, v5, vcc
	global_load_ushort v12, v[10:11], off offset:3584 nt
	v_add_co_u32_e32 v10, vcc, s0, v4
	s_mov_b32 s0, 0x36000
	s_nop 0
	v_addc_co_u32_e32 v11, vcc, 0, v5, vcc
	global_load_ushort v13, v[10:11], off offset:2048 nt
	v_add_co_u32_e32 v10, vcc, s0, v4
	s_mov_b32 s0, 0x37000
	s_nop 0
	v_addc_co_u32_e32 v11, vcc, 0, v5, vcc
	global_load_ushort v111, v[10:11], off offset:1024 nt
	v_add_co_u32_e32 v10, vcc, s0, v4
	ds_write_b128 v86, v[0:3]
	s_nop 0
	v_addc_co_u32_e32 v11, vcc, 0, v5, vcc
	global_load_ushort v14, v[10:11], off offset:2560 nt
	v_add_co_u32_e32 v10, vcc, s74, v4
	v_sub_f32_e32 v1, v6, v110
	s_nop 0
	v_addc_co_u32_e32 v11, vcc, 0, v5, vcc
	global_load_ushort v99, v[10:11], off offset:1536 nt
	v_add_co_u32_e32 v10, vcc, s75, v4
	v_mul_f32_e32 v1, 0x3fb8aa3b, v1
	s_nop 0
	v_addc_co_u32_e32 v11, vcc, 0, v5, vcc
	global_load_ushort v100, v[10:11], off nt
	v_add_co_u32_e32 v10, vcc, s76, v4
	v_sub_f32_e32 v0, v6, v108
	s_nop 0
	v_addc_co_u32_e32 v11, vcc, 0, v5, vcc
	global_load_ushort v106, v[10:11], off offset:3072 nt
	v_add_co_u32_e32 v10, vcc, s77, v4
; __device__ __forceinline__ unsigned pk2(float lo, float hi) { return f2bf(lo) | (f2bf(hi) << 16); }
; __device__ __forceinline__ void gla_upd_unit(LAS unsigned char* wl, const bf16* PROJ, const float* R, const float* w_gk2, const float* b_gk, float* UPD, float* DEC, int unit, int lane) {
;     ...
;     for (int t = 0; t < 32; ++t) kv1[t] = kp[(size_t)(t + 32) * NPROJ];
;     float run = 0.f;
; #pragma unroll
;     for (int t = 0; t < 32; t += 2) {
;         run += la[t]; const float d0 = bf2f(kv0[t]) * __expf(tot - run);
;         run += la[t + 1]; const float d1 = bf2f(kv0[t + 1]) * __expf(tot - run);
;         KD32[kk * (KS / 2) + (t >> 1)] = pk2(d0, d1);
;     }
; #pragma unroll
;     for (int t = 0; t < 32; t += 2) {
;         run += la[32 + t]; const float d0 = bf2f(kv1[t]) * __expf(tot - run);
;         run += la[33 + t]; const float d1 = bf2f(kv1[t + 1]) * __expf(tot - run);
;         KD32[kk * (KS / 2) + 16 + (t >> 1)] = pk2(d0, d1);
;     }
	v_exp_f32_e32 v2, v1
	s_nop 0
	v_addc_co_u32_e32 v11, vcc, 0, v5, vcc
	global_load_ushort v9, v[10:11], off offset:512 nt
	v_add_co_u32_e32 v10, vcc, s78, v4
	v_sub_f32_e32 v1, v6, v112
	s_nop 0
	v_addc_co_u32_e32 v11, vcc, 0, v5, vcc
	global_load_ushort v93, v[10:11], off offset:3584 nt
	v_add_co_u32_e32 v10, vcc, s79, v4
	v_mul_f32_e32 v0, 0x3fb8aa3b, v0
	s_nop 0
	v_addc_co_u32_e32 v11, vcc, 0, v5, vcc
	global_load_ushort v94, v[10:11], off offset:2048 nt
	v_add_co_u32_e32 v10, vcc, s80, v4
	v_mul_f32_e32 v1, 0x3fb8aa3b, v1
	s_nop 0
	v_addc_co_u32_e32 v11, vcc, 0, v5, vcc
	global_load_ushort v166, v[10:11], off offset:1024 nt
	v_add_co_u32_e32 v10, vcc, s81, v4
	v_sub_f32_e32 v3, v6, v113
	s_nop 0
	v_addc_co_u32_e32 v11, vcc, 0, v5, vcc
	global_load_ushort v16, v[10:11], off offset:2560 nt
	v_add_co_u32_e32 v10, vcc, s82, v4
	v_exp_f32_e32 v0, v0
	s_nop 0
	v_addc_co_u32_e32 v11, vcc, 0, v5, vcc
	global_load_ushort v101, v[10:11], off offset:1536 nt
	v_add_co_u32_e32 v10, vcc, s83, v4
	v_exp_f32_e32 v1, v1
	s_nop 0
	v_addc_co_u32_e32 v11, vcc, 0, v5, vcc
	global_load_ushort v102, v[10:11], off nt
	v_add_co_u32_e32 v10, vcc, s84, v4
	v_mul_f32_e32 v3, 0x3fb8aa3b, v3
	s_nop 0
	v_addc_co_u32_e32 v11, vcc, 0, v5, vcc
	global_load_ushort v107, v[10:11], off offset:3072 nt
	v_add_co_u32_e32 v10, vcc, s85, v4
	v_exp_f32_e32 v3, v3
	s_nop 0
	v_addc_co_u32_e32 v11, vcc, 0, v5, vcc
	v_add_co_u32_e32 v96, vcc, s86, v4
	global_load_ushort v10, v[10:11], off offset:512 nt
	s_nop 0
	v_addc_co_u32_e32 v97, vcc, 0, v5, vcc
	global_load_ushort v95, v[96:97], off offset:3584 nt
	v_add_co_u32_e32 v96, vcc, s87, v4
	v_pk_mul_f32 v[0:1], v[0:1], v[18:19]
	s_nop 0
	v_addc_co_u32_e32 v97, vcc, 0, v5, vcc
	v_add_co_u32_e32 v168, vcc, s88, v4
	global_load_ushort v96, v[96:97], off offset:2048 nt
	s_nop 0
	v_addc_co_u32_e32 v169, vcc, 0, v5, vcc
	global_load_ushort v167, v[168:169], off offset:1024 nt
	v_add_co_u32_e32 v168, vcc, s89, v4
	s_waitcnt vmcnt(45)
	v_lshlrev_b32_e32 v19, 16, v21
	v_addc_co_u32_e32 v169, vcc, 0, v5, vcc
	global_load_ushort v92, v[168:169], off offset:2560 nt
	v_add_co_u32_e32 v168, vcc, s90, v4
	v_lshlrev_b32_e32 v18, 16, v20
	s_nop 0
	v_addc_co_u32_e32 v169, vcc, 0, v5, vcc
	global_load_ushort v103, v[168:169], off offset:1536 nt
	v_add_co_u32_e32 v168, vcc, s91, v4
	v_pk_mul_f32 v[2:3], v[2:3], v[18:19]
	s_nop 0
	v_addc_co_u32_e32 v169, vcc, 0, v5, vcc
	global_load_ushort v104, v[168:169], off nt
	v_add_co_u32_e32 v168, vcc, s20, v4
	v_and_b32_sdwa v18, v0, v91 dst_sel:DWORD dst_unused:UNUSED_PAD src0_sel:WORD_1 src1_sel:DWORD
	s_nop 0
	v_addc_co_u32_e32 v169, vcc, 0, v5, vcc
	global_load_ushort v109, v[168:169], off offset:3072 nt
	v_add_co_u32_e32 v168, vcc, s21, v4
	v_add3_u32 v0, v0, v18, s72
	s_nop 0
	v_addc_co_u32_e32 v169, vcc, 0, v5, vcc
	global_load_ushort v11, v[168:169], off offset:512 nt
	v_add_co_u32_e32 v168, vcc, s28, v4
	v_and_b32_sdwa v18, v2, v91 dst_sel:DWORD dst_unused:UNUSED_PAD src0_sel:WORD_1 src1_sel:DWORD
	s_nop 0
	v_addc_co_u32_e32 v169, vcc, 0, v5, vcc
	global_load_ushort v97, v[168:169], off offset:3584 nt
	v_add_co_u32_e32 v168, vcc, s29, v4
	v_add3_u32 v2, v2, v18, s72
	s_nop 0
	v_addc_co_u32_e32 v169, vcc, 0, v5, vcc
	v_add_co_u32_e32 v4, vcc, s30, v4
	global_load_ushort v98, v[168:169], off offset:2048 nt
	s_nop 0
	v_addc_co_u32_e32 v5, vcc, 0, v5, vcc
	global_load_ushort v4, v[4:5], off offset:1024 nt
	v_and_b32_sdwa v5, v1, v91 dst_sel:DWORD dst_unused:UNUSED_PAD src0_sel:WORD_1 src1_sel:DWORD
	v_add3_u32 v1, v1, v5, s72
	v_and_b32_sdwa v5, v3, v91 dst_sel:DWORD dst_unused:UNUSED_PAD src0_sel:WORD_1 src1_sel:DWORD
	v_add3_u32 v3, v3, v5, s72
	v_and_b32_e32 v3, 0xffff0000, v3
	v_or_b32_sdwa v1, v3, v1 dst_sel:DWORD dst_unused:UNUSED_PAD src0_sel:DWORD src1_sel:WORD_1
	v_sub_f32_e32 v3, v6, v115
	v_and_b32_e32 v2, 0xffff0000, v2
	v_mul_f32_e32 v3, 0x3fb8aa3b, v3
	v_or_b32_sdwa v0, v2, v0 dst_sel:DWORD dst_unused:UNUSED_PAD src0_sel:DWORD src1_sel:WORD_1
	v_sub_f32_e32 v2, v6, v114
	v_exp_f32_e32 v18, v3
	v_sub_f32_e32 v3, v6, v116
	v_mul_f32_e32 v2, 0x3fb8aa3b, v2
	v_mul_f32_e32 v3, 0x3fb8aa3b, v3
	v_sub_f32_e32 v5, v6, v117
	v_exp_f32_e32 v2, v2
	v_exp_f32_e32 v3, v3
	v_mul_f32_e32 v5, 0x3fb8aa3b, v5
	v_exp_f32_e32 v19, v5
	s_waitcnt vmcnt(51)
	v_lshlrev_b32_e32 v21, 16, v60
	v_lshlrev_b32_e32 v20, 16, v22
	v_pk_mul_f32 v[2:3], v[2:3], v[20:21]
	s_waitcnt vmcnt(49)
	v_lshlrev_b32_e32 v21, 16, v75
	v_lshlrev_b32_e32 v20, 16, v61
	v_pk_mul_f32 v[18:19], v[18:19], v[20:21]
	v_and_b32_sdwa v5, v3, v91 dst_sel:DWORD dst_unused:UNUSED_PAD src0_sel:WORD_1 src1_sel:DWORD
	v_and_b32_sdwa v20, v2, v91 dst_sel:DWORD dst_unused:UNUSED_PAD src0_sel:WORD_1 src1_sel:DWORD
	v_add3_u32 v2, v2, v20, s72
	v_add3_u32 v3, v3, v5, s72
	v_and_b32_sdwa v5, v19, v91 dst_sel:DWORD dst_unused:UNUSED_PAD src0_sel:WORD_1 src1_sel:DWORD
	v_and_b32_sdwa v20, v18, v91 dst_sel:DWORD dst_unused:UNUSED_PAD src0_sel:WORD_1 src1_sel:DWORD
	v_add3_u32 v5, v19, v5, s72
	v_add3_u32 v18, v18, v20, s72
	v_and_b32_e32 v5, 0xffff0000, v5
	v_and_b32_e32 v18, 0xffff0000, v18
	v_or_b32_sdwa v3, v5, v3 dst_sel:DWORD dst_unused:UNUSED_PAD src0_sel:DWORD src1_sel:WORD_1
	v_or_b32_sdwa v2, v18, v2 dst_sel:DWORD dst_unused:UNUSED_PAD src0_sel:DWORD src1_sel:WORD_1
	ds_write_b128 v86, v[0:3] offset:16
	v_sub_f32_e32 v1, v6, v119
	v_mul_f32_e32 v1, 0x3fb8aa3b, v1
	v_sub_f32_e32 v0, v6, v118
	v_exp_f32_e32 v2, v1
	v_sub_f32_e32 v1, v6, v120
	v_mul_f32_e32 v0, 0x3fb8aa3b, v0
	v_mul_f32_e32 v1, 0x3fb8aa3b, v1
	v_sub_f32_e32 v3, v6, v121
	v_exp_f32_e32 v0, v0
	v_exp_f32_e32 v1, v1
	v_mul_f32_e32 v3, 0x3fb8aa3b, v3
	v_exp_f32_e32 v3, v3
	s_waitcnt vmcnt(48)
; __device__ __forceinline__ unsigned pk2(float lo, float hi) { return f2bf(lo) | (f2bf(hi) << 16); }
; __device__ __forceinline__ void gla_upd_unit(LAS unsigned char* wl, const bf16* PROJ, const float* R, const float* w_gk2, const float* b_gk, float* UPD, float* DEC, int unit, int lane) {
;     ...
;     for (int t = 0; t < 32; t += 2) {
;         run += la[t]; const float d0 = bf2f(kv0[t]) * __expf(tot - run);
;         run += la[t + 1]; const float d1 = bf2f(kv0[t + 1]) * __expf(tot - run);
;         KD32[kk * (KS / 2) + (t >> 1)] = pk2(d0, d1);
;     }
; #pragma unroll
;     for (int t = 0; t < 32; t += 2) {
;         run += la[32 + t]; const float d0 = bf2f(kv1[t]) * __expf(tot - run);
;         run += la[33 + t]; const float d1 = bf2f(kv1[t + 1]) * __expf(tot - run);
;         KD32[kk * (KS / 2) + 16 + (t >> 1)] = pk2(d0, d1);
;     }
	v_lshlrev_b32_e32 v19, 16, v67
	s_waitcnt vmcnt(47)
	v_lshlrev_b32_e32 v18, 16, v62
	v_pk_mul_f32 v[0:1], v[0:1], v[18:19]
	s_waitcnt vmcnt(45)
	v_lshlrev_b32_e32 v19, 16, v73
	v_lshlrev_b32_e32 v18, 16, v68
	v_pk_mul_f32 v[2:3], v[2:3], v[18:19]
	v_and_b32_sdwa v5, v1, v91 dst_sel:DWORD dst_unused:UNUSED_PAD src0_sel:WORD_1 src1_sel:DWORD
	v_add3_u32 v1, v1, v5, s72
	v_and_b32_sdwa v5, v3, v91 dst_sel:DWORD dst_unused:UNUSED_PAD src0_sel:WORD_1 src1_sel:DWORD
	v_and_b32_sdwa v18, v0, v91 dst_sel:DWORD dst_unused:UNUSED_PAD src0_sel:WORD_1 src1_sel:DWORD
	v_add3_u32 v3, v3, v5, s72
	v_add3_u32 v0, v0, v18, s72
	v_and_b32_sdwa v18, v2, v91 dst_sel:DWORD dst_unused:UNUSED_PAD src0_sel:WORD_1 src1_sel:DWORD
	v_and_b32_e32 v3, 0xffff0000, v3
	v_add3_u32 v2, v2, v18, s72
	v_or_b32_sdwa v1, v3, v1 dst_sel:DWORD dst_unused:UNUSED_PAD src0_sel:DWORD src1_sel:WORD_1
	v_sub_f32_e32 v3, v6, v123
	v_and_b32_e32 v2, 0xffff0000, v2
	v_mul_f32_e32 v3, 0x3fb8aa3b, v3
	v_or_b32_sdwa v0, v2, v0 dst_sel:DWORD dst_unused:UNUSED_PAD src0_sel:DWORD src1_sel:WORD_1
	v_sub_f32_e32 v2, v6, v122
	v_exp_f32_e32 v18, v3
	v_sub_f32_e32 v3, v6, v124
	v_mul_f32_e32 v2, 0x3fb8aa3b, v2
	v_mul_f32_e32 v3, 0x3fb8aa3b, v3
	v_sub_f32_e32 v5, v6, v125
	v_exp_f32_e32 v2, v2
	v_exp_f32_e32 v3, v3
	v_mul_f32_e32 v5, 0x3fb8aa3b, v5
	v_exp_f32_e32 v19, v5
	s_waitcnt vmcnt(43)
	v_lshlrev_b32_e32 v21, 16, v64
	v_lshlrev_b32_e32 v20, 16, v23
	v_pk_mul_f32 v[2:3], v[2:3], v[20:21]
	s_waitcnt vmcnt(41)
	v_lshlrev_b32_e32 v21, 16, v76
	v_lshlrev_b32_e32 v20, 16, v65
	v_pk_mul_f32 v[18:19], v[18:19], v[20:21]
	v_and_b32_sdwa v5, v3, v91 dst_sel:DWORD dst_unused:UNUSED_PAD src0_sel:WORD_1 src1_sel:DWORD
	v_and_b32_sdwa v20, v2, v91 dst_sel:DWORD dst_unused:UNUSED_PAD src0_sel:WORD_1 src1_sel:DWORD
	v_add3_u32 v2, v2, v20, s72
	v_add3_u32 v3, v3, v5, s72
	v_and_b32_sdwa v5, v19, v91 dst_sel:DWORD dst_unused:UNUSED_PAD src0_sel:WORD_1 src1_sel:DWORD
	v_and_b32_sdwa v20, v18, v91 dst_sel:DWORD dst_unused:UNUSED_PAD src0_sel:WORD_1 src1_sel:DWORD
	v_add3_u32 v5, v19, v5, s72
	v_add3_u32 v18, v18, v20, s72
	v_and_b32_e32 v5, 0xffff0000, v5
	v_and_b32_e32 v18, 0xffff0000, v18
	v_or_b32_sdwa v3, v5, v3 dst_sel:DWORD dst_unused:UNUSED_PAD src0_sel:DWORD src1_sel:WORD_1
	v_or_b32_sdwa v2, v18, v2 dst_sel:DWORD dst_unused:UNUSED_PAD src0_sel:DWORD src1_sel:WORD_1
	ds_write_b128 v86, v[0:3] offset:32
	v_sub_f32_e32 v1, v6, v127
	v_mul_f32_e32 v1, 0x3fb8aa3b, v1
	v_sub_f32_e32 v0, v6, v126
	v_exp_f32_e32 v2, v1
	v_sub_f32_e32 v1, v6, v129
	v_mul_f32_e32 v0, 0x3fb8aa3b, v0
	v_mul_f32_e32 v1, 0x3fb8aa3b, v1
	v_sub_f32_e32 v3, v6, v130
	v_exp_f32_e32 v0, v0
	v_exp_f32_e32 v1, v1
	v_mul_f32_e32 v3, 0x3fb8aa3b, v3
	v_exp_f32_e32 v3, v3
	s_waitcnt vmcnt(39)
	v_lshlrev_b32_e32 v19, 16, v71
	v_lshlrev_b32_e32 v18, 16, v66
	v_pk_mul_f32 v[0:1], v[0:1], v[18:19]
	s_waitcnt vmcnt(37)
	v_lshlrev_b32_e32 v19, 16, v74
	v_lshlrev_b32_e32 v18, 16, v72
	v_pk_mul_f32 v[2:3], v[2:3], v[18:19]
	v_and_b32_sdwa v5, v1, v91 dst_sel:DWORD dst_unused:UNUSED_PAD src0_sel:WORD_1 src1_sel:DWORD
	v_add3_u32 v1, v1, v5, s72
	v_and_b32_sdwa v5, v3, v91 dst_sel:DWORD dst_unused:UNUSED_PAD src0_sel:WORD_1 src1_sel:DWORD
	v_and_b32_sdwa v18, v0, v91 dst_sel:DWORD dst_unused:UNUSED_PAD src0_sel:WORD_1 src1_sel:DWORD
	v_add3_u32 v3, v3, v5, s72
	v_add3_u32 v0, v0, v18, s72
	v_and_b32_sdwa v18, v2, v91 dst_sel:DWORD dst_unused:UNUSED_PAD src0_sel:WORD_1 src1_sel:DWORD
	v_and_b32_e32 v3, 0xffff0000, v3
	v_add3_u32 v2, v2, v18, s72
	v_or_b32_sdwa v1, v3, v1 dst_sel:DWORD dst_unused:UNUSED_PAD src0_sel:DWORD src1_sel:WORD_1
	v_sub_f32_e32 v3, v6, v132
	v_and_b32_e32 v2, 0xffff0000, v2
	v_mul_f32_e32 v3, 0x3fb8aa3b, v3
	v_or_b32_sdwa v0, v2, v0 dst_sel:DWORD dst_unused:UNUSED_PAD src0_sel:DWORD src1_sel:WORD_1
	v_sub_f32_e32 v2, v6, v131
	v_exp_f32_e32 v18, v3
	v_sub_f32_e32 v3, v6, v133
	v_mul_f32_e32 v2, 0x3fb8aa3b, v2
	v_mul_f32_e32 v3, 0x3fb8aa3b, v3
	v_sub_f32_e32 v5, v6, v134
	v_exp_f32_e32 v2, v2
	v_exp_f32_e32 v3, v3
	v_mul_f32_e32 v5, 0x3fb8aa3b, v5
	v_exp_f32_e32 v19, v5
	s_waitcnt vmcnt(35)
	v_lshlrev_b32_e32 v21, 16, v69
	v_lshlrev_b32_e32 v20, 16, v63
	v_pk_mul_f32 v[2:3], v[2:3], v[20:21]
	s_waitcnt vmcnt(33)
	v_lshlrev_b32_e32 v21, 16, v77
	v_lshlrev_b32_e32 v20, 16, v70
	v_pk_mul_f32 v[18:19], v[18:19], v[20:21]
	v_and_b32_sdwa v5, v3, v91 dst_sel:DWORD dst_unused:UNUSED_PAD src0_sel:WORD_1 src1_sel:DWORD
	v_and_b32_sdwa v20, v2, v91 dst_sel:DWORD dst_unused:UNUSED_PAD src0_sel:WORD_1 src1_sel:DWORD
	v_add3_u32 v2, v2, v20, s72
	v_add3_u32 v3, v3, v5, s72
	v_and_b32_sdwa v5, v19, v91 dst_sel:DWORD dst_unused:UNUSED_PAD src0_sel:WORD_1 src1_sel:DWORD
	v_and_b32_sdwa v20, v18, v91 dst_sel:DWORD dst_unused:UNUSED_PAD src0_sel:WORD_1 src1_sel:DWORD
	v_add3_u32 v5, v19, v5, s72
	v_add3_u32 v18, v18, v20, s72
	v_and_b32_e32 v5, 0xffff0000, v5
	v_and_b32_e32 v18, 0xffff0000, v18
	v_or_b32_sdwa v3, v5, v3 dst_sel:DWORD dst_unused:UNUSED_PAD src0_sel:DWORD src1_sel:WORD_1
	v_or_b32_sdwa v2, v18, v2 dst_sel:DWORD dst_unused:UNUSED_PAD src0_sel:DWORD src1_sel:WORD_1
	ds_write_b128 v86, v[0:3] offset:48
	v_sub_f32_e32 v1, v6, v136
	v_mul_f32_e32 v1, 0x3fb8aa3b, v1
	v_sub_f32_e32 v0, v6, v135
	v_exp_f32_e32 v2, v1
	v_sub_f32_e32 v1, v6, v137
	v_mul_f32_e32 v0, 0x3fb8aa3b, v0
	v_mul_f32_e32 v1, 0x3fb8aa3b, v1
	v_sub_f32_e32 v3, v6, v138
	v_exp_f32_e32 v0, v0
	v_exp_f32_e32 v1, v1
	v_mul_f32_e32 v3, 0x3fb8aa3b, v3
	v_exp_f32_e32 v3, v3
	s_waitcnt vmcnt(31)
	v_lshlrev_b32_e32 v19, 16, v15
	s_waitcnt vmcnt(30)
	v_lshlrev_b32_e32 v18, 16, v8
	v_pk_mul_f32 v[0:1], v[0:1], v[18:19]
	s_waitcnt vmcnt(28)
; __device__ __forceinline__ unsigned pk2(float lo, float hi) { return f2bf(lo) | (f2bf(hi) << 16); }
; __device__ __forceinline__ void gla_upd_unit(LAS unsigned char* wl, const bf16* PROJ, const float* R, const float* w_gk2, const float* b_gk, float* UPD, float* DEC, int unit, int lane) {
;     ...
;     for (int t = 0; t < 32; t += 2) {
;         run += la[32 + t]; const float d0 = bf2f(kv1[t]) * __expf(tot - run);
;         run += la[33 + t]; const float d1 = bf2f(kv1[t + 1]) * __expf(tot - run);
;         KD32[kk * (KS / 2) + 16 + (t >> 1)] = pk2(d0, d1);
;     }
	v_lshlrev_b32_e32 v19, 16, v105
	v_lshlrev_b32_e32 v18, 16, v17
	v_pk_mul_f32 v[2:3], v[2:3], v[18:19]
	v_and_b32_sdwa v5, v1, v91 dst_sel:DWORD dst_unused:UNUSED_PAD src0_sel:WORD_1 src1_sel:DWORD
	v_add3_u32 v1, v1, v5, s72
	v_and_b32_sdwa v5, v3, v91 dst_sel:DWORD dst_unused:UNUSED_PAD src0_sel:WORD_1 src1_sel:DWORD
	v_and_b32_sdwa v8, v0, v91 dst_sel:DWORD dst_unused:UNUSED_PAD src0_sel:WORD_1 src1_sel:DWORD
	v_add3_u32 v3, v3, v5, s72
	v_add3_u32 v0, v0, v8, s72
	v_and_b32_sdwa v8, v2, v91 dst_sel:DWORD dst_unused:UNUSED_PAD src0_sel:WORD_1 src1_sel:DWORD
	v_and_b32_e32 v3, 0xffff0000, v3
	v_add3_u32 v2, v2, v8, s72
	v_or_b32_sdwa v1, v3, v1 dst_sel:DWORD dst_unused:UNUSED_PAD src0_sel:DWORD src1_sel:WORD_1
	v_sub_f32_e32 v3, v6, v140
	v_and_b32_e32 v2, 0xffff0000, v2
	v_mul_f32_e32 v3, 0x3fb8aa3b, v3
	v_or_b32_sdwa v0, v2, v0 dst_sel:DWORD dst_unused:UNUSED_PAD src0_sel:DWORD src1_sel:WORD_1
	v_sub_f32_e32 v2, v6, v139
	v_exp_f32_e32 v18, v3
	v_sub_f32_e32 v3, v6, v141
	v_mul_f32_e32 v2, 0x3fb8aa3b, v2
	v_mul_f32_e32 v3, 0x3fb8aa3b, v3
	v_sub_f32_e32 v5, v6, v142
	v_exp_f32_e32 v2, v2
	v_exp_f32_e32 v3, v3
	v_mul_f32_e32 v5, 0x3fb8aa3b, v5
	v_exp_f32_e32 v19, v5
	s_waitcnt vmcnt(26)
	v_lshlrev_b32_e32 v21, 16, v12
	v_lshlrev_b32_e32 v20, 16, v7
	v_pk_mul_f32 v[2:3], v[2:3], v[20:21]
	s_waitcnt vmcnt(24)
	v_lshlrev_b32_e32 v21, 16, v111
	v_lshlrev_b32_e32 v20, 16, v13
	v_pk_mul_f32 v[12:13], v[18:19], v[20:21]
	v_and_b32_sdwa v5, v3, v91 dst_sel:DWORD dst_unused:UNUSED_PAD src0_sel:WORD_1 src1_sel:DWORD
	v_and_b32_sdwa v7, v2, v91 dst_sel:DWORD dst_unused:UNUSED_PAD src0_sel:WORD_1 src1_sel:DWORD
	v_add3_u32 v2, v2, v7, s72
	v_add3_u32 v3, v3, v5, s72
	v_and_b32_sdwa v5, v13, v91 dst_sel:DWORD dst_unused:UNUSED_PAD src0_sel:WORD_1 src1_sel:DWORD
	v_and_b32_sdwa v7, v12, v91 dst_sel:DWORD dst_unused:UNUSED_PAD src0_sel:WORD_1 src1_sel:DWORD
	v_add3_u32 v5, v13, v5, s72
	v_add3_u32 v7, v12, v7, s72
	v_and_b32_e32 v5, 0xffff0000, v5
	v_and_b32_e32 v7, 0xffff0000, v7
	v_or_b32_sdwa v3, v5, v3 dst_sel:DWORD dst_unused:UNUSED_PAD src0_sel:DWORD src1_sel:WORD_1
	v_or_b32_sdwa v2, v7, v2 dst_sel:DWORD dst_unused:UNUSED_PAD src0_sel:DWORD src1_sel:WORD_1
	ds_write_b128 v86, v[0:3] offset:64
	v_sub_f32_e32 v1, v6, v144
	v_mul_f32_e32 v1, 0x3fb8aa3b, v1
	v_sub_f32_e32 v0, v6, v143
	v_exp_f32_e32 v2, v1
	v_sub_f32_e32 v1, v6, v145
	v_mul_f32_e32 v0, 0x3fb8aa3b, v0
	v_mul_f32_e32 v1, 0x3fb8aa3b, v1
	v_sub_f32_e32 v3, v6, v146
	v_exp_f32_e32 v0, v0
	v_exp_f32_e32 v1, v1
	v_mul_f32_e32 v3, 0x3fb8aa3b, v3
	v_exp_f32_e32 v3, v3
	s_waitcnt vmcnt(22)
	v_lshlrev_b32_e32 v13, 16, v99
	v_lshlrev_b32_e32 v12, 16, v14
	v_pk_mul_f32 v[0:1], v[0:1], v[12:13]
	s_waitcnt vmcnt(20)
	v_lshlrev_b32_e32 v13, 16, v106
	v_lshlrev_b32_e32 v12, 16, v100
	v_pk_mul_f32 v[2:3], v[2:3], v[12:13]
	v_and_b32_sdwa v5, v1, v91 dst_sel:DWORD dst_unused:UNUSED_PAD src0_sel:WORD_1 src1_sel:DWORD
	v_add3_u32 v1, v1, v5, s72
	v_and_b32_sdwa v5, v3, v91 dst_sel:DWORD dst_unused:UNUSED_PAD src0_sel:WORD_1 src1_sel:DWORD
	v_and_b32_sdwa v7, v0, v91 dst_sel:DWORD dst_unused:UNUSED_PAD src0_sel:WORD_1 src1_sel:DWORD
	v_add3_u32 v3, v3, v5, s72
	v_add3_u32 v0, v0, v7, s72
	v_and_b32_sdwa v7, v2, v91 dst_sel:DWORD dst_unused:UNUSED_PAD src0_sel:WORD_1 src1_sel:DWORD
	v_and_b32_e32 v3, 0xffff0000, v3
	v_add3_u32 v2, v2, v7, s72
	v_or_b32_sdwa v1, v3, v1 dst_sel:DWORD dst_unused:UNUSED_PAD src0_sel:DWORD src1_sel:WORD_1
	v_sub_f32_e32 v3, v6, v148
	v_and_b32_e32 v2, 0xffff0000, v2
	v_mul_f32_e32 v3, 0x3fb8aa3b, v3
	v_or_b32_sdwa v0, v2, v0 dst_sel:DWORD dst_unused:UNUSED_PAD src0_sel:DWORD src1_sel:WORD_1
	v_sub_f32_e32 v2, v6, v147
	v_exp_f32_e32 v12, v3
	v_sub_f32_e32 v3, v6, v149
	v_mul_f32_e32 v2, 0x3fb8aa3b, v2
	v_mul_f32_e32 v3, 0x3fb8aa3b, v3
	v_sub_f32_e32 v5, v6, v150
	v_exp_f32_e32 v2, v2
	v_exp_f32_e32 v3, v3
	v_mul_f32_e32 v5, 0x3fb8aa3b, v5
	v_exp_f32_e32 v13, v5
	s_waitcnt vmcnt(18)
	v_lshlrev_b32_e32 v15, 16, v93
	v_lshlrev_b32_e32 v14, 16, v9
	v_pk_mul_f32 v[2:3], v[2:3], v[14:15]
	s_waitcnt vmcnt(16)
	v_lshlrev_b32_e32 v9, 16, v166
	v_lshlrev_b32_e32 v8, 16, v94
	v_pk_mul_f32 v[8:9], v[12:13], v[8:9]
	v_and_b32_sdwa v5, v3, v91 dst_sel:DWORD dst_unused:UNUSED_PAD src0_sel:WORD_1 src1_sel:DWORD
	v_and_b32_sdwa v7, v2, v91 dst_sel:DWORD dst_unused:UNUSED_PAD src0_sel:WORD_1 src1_sel:DWORD
	v_add3_u32 v2, v2, v7, s72
	v_add3_u32 v3, v3, v5, s72
	v_and_b32_sdwa v5, v9, v91 dst_sel:DWORD dst_unused:UNUSED_PAD src0_sel:WORD_1 src1_sel:DWORD
	v_and_b32_sdwa v7, v8, v91 dst_sel:DWORD dst_unused:UNUSED_PAD src0_sel:WORD_1 src1_sel:DWORD
	v_add3_u32 v5, v9, v5, s72
	v_add3_u32 v7, v8, v7, s72
	v_and_b32_e32 v5, 0xffff0000, v5
	v_and_b32_e32 v7, 0xffff0000, v7
	v_or_b32_sdwa v3, v5, v3 dst_sel:DWORD dst_unused:UNUSED_PAD src0_sel:DWORD src1_sel:WORD_1
	v_or_b32_sdwa v2, v7, v2 dst_sel:DWORD dst_unused:UNUSED_PAD src0_sel:DWORD src1_sel:WORD_1
	ds_write_b128 v86, v[0:3] offset:80
	v_sub_f32_e32 v1, v6, v152
	v_mul_f32_e32 v1, 0x3fb8aa3b, v1
	v_sub_f32_e32 v0, v6, v151
	v_exp_f32_e32 v2, v1
	v_sub_f32_e32 v1, v6, v153
	v_mul_f32_e32 v0, 0x3fb8aa3b, v0
	v_mul_f32_e32 v1, 0x3fb8aa3b, v1
	v_sub_f32_e32 v3, v6, v154
	v_exp_f32_e32 v0, v0
	v_exp_f32_e32 v1, v1
	v_mul_f32_e32 v3, 0x3fb8aa3b, v3
	v_exp_f32_e32 v3, v3
	s_waitcnt vmcnt(14)
	v_lshlrev_b32_e32 v9, 16, v101
	v_lshlrev_b32_e32 v8, 16, v16
	v_pk_mul_f32 v[0:1], v[0:1], v[8:9]
	s_waitcnt vmcnt(12)
; #define LDS_WAIT() asm volatile("s_waitcnt lgkmcnt(0)" ::: "memory")
; __device__ __forceinline__ unsigned pk2(float lo, float hi) { return f2bf(lo) | (f2bf(hi) << 16); }
; __device__ __forceinline__ void gla_upd_unit(LAS unsigned char* wl, const bf16* PROJ, const float* R, const float* w_gk2, const float* b_gk, float* UPD, float* DEC, int unit, int lane) {
;     ...
;     for (int t = 0; t < 32; t += 2) {
;         run += la[32 + t]; const float d0 = bf2f(kv1[t]) * __expf(tot - run);
;         run += la[33 + t]; const float d1 = bf2f(kv1[t + 1]) * __expf(tot - run);
;         KD32[kk * (KS / 2) + 16 + (t >> 1)] = pk2(d0, d1);
;     }
;     LDS_WAIT(); asm volatile("" ::: "memory");
;     const int fr = lane & 15, fq = lane >> 4, sp = lane >> 3, cc = lane & 7;
; #pragma unroll 1
;     for (int vh = 0; vh < 2; ++vh) {
; #pragma unroll
;         for (int it = 0; it < 4; ++it) {
;             const int t0 = it * 16 + 2 * sp;
;             const u32x4 va = *(const u32x4*)(PROJ + (size_t)(tok0 + t0) * NPROJ + 1536 + h * 128 + vh * 64 + 8 * cc);
;             const u32x4 vb = *(const u32x4*)(PROJ + (size_t)(tok0 + t0 + 1) * NPROJ + 1536 + h * 128 + vh * 64 + 8 * cc);
	v_lshlrev_b32_e32 v9, 16, v107
	v_lshlrev_b32_e32 v8, 16, v102
	v_pk_mul_f32 v[2:3], v[2:3], v[8:9]
	v_and_b32_sdwa v5, v1, v91 dst_sel:DWORD dst_unused:UNUSED_PAD src0_sel:WORD_1 src1_sel:DWORD
	v_add3_u32 v1, v1, v5, s72
	v_and_b32_sdwa v5, v3, v91 dst_sel:DWORD dst_unused:UNUSED_PAD src0_sel:WORD_1 src1_sel:DWORD
	v_and_b32_sdwa v7, v0, v91 dst_sel:DWORD dst_unused:UNUSED_PAD src0_sel:WORD_1 src1_sel:DWORD
	v_add3_u32 v3, v3, v5, s72
	v_add3_u32 v0, v0, v7, s72
	v_and_b32_sdwa v7, v2, v91 dst_sel:DWORD dst_unused:UNUSED_PAD src0_sel:WORD_1 src1_sel:DWORD
	v_and_b32_e32 v3, 0xffff0000, v3
	v_add3_u32 v2, v2, v7, s72
	v_or_b32_sdwa v1, v3, v1 dst_sel:DWORD dst_unused:UNUSED_PAD src0_sel:DWORD src1_sel:WORD_1
	v_sub_f32_e32 v3, v6, v156
	v_and_b32_e32 v2, 0xffff0000, v2
	v_mul_f32_e32 v3, 0x3fb8aa3b, v3
	v_or_b32_sdwa v0, v2, v0 dst_sel:DWORD dst_unused:UNUSED_PAD src0_sel:DWORD src1_sel:WORD_1
	v_sub_f32_e32 v2, v6, v155
	v_exp_f32_e32 v8, v3
	v_sub_f32_e32 v3, v6, v157
	v_mul_f32_e32 v2, 0x3fb8aa3b, v2
	v_mul_f32_e32 v3, 0x3fb8aa3b, v3
	v_sub_f32_e32 v5, v6, v158
	v_exp_f32_e32 v2, v2
	v_exp_f32_e32 v3, v3
	v_mul_f32_e32 v5, 0x3fb8aa3b, v5
	v_exp_f32_e32 v9, v5
	s_waitcnt vmcnt(10)
	v_lshlrev_b32_e32 v13, 16, v95
	v_lshlrev_b32_e32 v12, 16, v10
	v_pk_mul_f32 v[2:3], v[2:3], v[12:13]
	s_waitcnt vmcnt(8)
	v_lshlrev_b32_e32 v13, 16, v167
	v_lshlrev_b32_e32 v12, 16, v96
	v_pk_mul_f32 v[8:9], v[8:9], v[12:13]
	v_and_b32_sdwa v5, v3, v91 dst_sel:DWORD dst_unused:UNUSED_PAD src0_sel:WORD_1 src1_sel:DWORD
	v_and_b32_sdwa v7, v2, v91 dst_sel:DWORD dst_unused:UNUSED_PAD src0_sel:WORD_1 src1_sel:DWORD
	v_add3_u32 v2, v2, v7, s72
	v_add3_u32 v3, v3, v5, s72
	v_and_b32_sdwa v5, v9, v91 dst_sel:DWORD dst_unused:UNUSED_PAD src0_sel:WORD_1 src1_sel:DWORD
	v_and_b32_sdwa v7, v8, v91 dst_sel:DWORD dst_unused:UNUSED_PAD src0_sel:WORD_1 src1_sel:DWORD
	v_add3_u32 v5, v9, v5, s72
	v_add3_u32 v7, v8, v7, s72
	v_and_b32_e32 v5, 0xffff0000, v5
	v_and_b32_e32 v7, 0xffff0000, v7
	v_or_b32_sdwa v3, v5, v3 dst_sel:DWORD dst_unused:UNUSED_PAD src0_sel:DWORD src1_sel:WORD_1
	v_or_b32_sdwa v2, v7, v2 dst_sel:DWORD dst_unused:UNUSED_PAD src0_sel:DWORD src1_sel:WORD_1
	ds_write_b128 v86, v[0:3] offset:96
	v_sub_f32_e32 v1, v6, v160
	v_mul_f32_e32 v1, 0x3fb8aa3b, v1
	v_sub_f32_e32 v0, v6, v159
	v_exp_f32_e32 v2, v1
	v_sub_f32_e32 v1, v6, v161
	v_mul_f32_e32 v0, 0x3fb8aa3b, v0
	v_mul_f32_e32 v1, 0x3fb8aa3b, v1
	v_sub_f32_e32 v3, v6, v162
	v_exp_f32_e32 v0, v0
	v_exp_f32_e32 v1, v1
	v_mul_f32_e32 v3, 0x3fb8aa3b, v3
	v_exp_f32_e32 v3, v3
	s_waitcnt vmcnt(6)
	v_lshlrev_b32_e32 v9, 16, v103
	v_lshlrev_b32_e32 v8, 16, v92
	v_pk_mul_f32 v[0:1], v[0:1], v[8:9]
	s_waitcnt vmcnt(4)
	v_lshlrev_b32_e32 v9, 16, v109
	v_lshlrev_b32_e32 v8, 16, v104
	v_pk_mul_f32 v[2:3], v[2:3], v[8:9]
	v_and_b32_sdwa v5, v1, v91 dst_sel:DWORD dst_unused:UNUSED_PAD src0_sel:WORD_1 src1_sel:DWORD
	v_add3_u32 v1, v1, v5, s72
	v_and_b32_sdwa v5, v3, v91 dst_sel:DWORD dst_unused:UNUSED_PAD src0_sel:WORD_1 src1_sel:DWORD
	v_and_b32_sdwa v7, v0, v91 dst_sel:DWORD dst_unused:UNUSED_PAD src0_sel:WORD_1 src1_sel:DWORD
	v_add3_u32 v3, v3, v5, s72
	v_add3_u32 v0, v0, v7, s72
	v_and_b32_sdwa v7, v2, v91 dst_sel:DWORD dst_unused:UNUSED_PAD src0_sel:WORD_1 src1_sel:DWORD
	v_and_b32_e32 v3, 0xffff0000, v3
	v_add3_u32 v2, v2, v7, s72
	v_or_b32_sdwa v1, v3, v1 dst_sel:DWORD dst_unused:UNUSED_PAD src0_sel:DWORD src1_sel:WORD_1
	v_sub_f32_e32 v3, v6, v164
	v_and_b32_e32 v2, 0xffff0000, v2
	v_mul_f32_e32 v3, 0x3fb8aa3b, v3
	v_or_b32_sdwa v0, v2, v0 dst_sel:DWORD dst_unused:UNUSED_PAD src0_sel:DWORD src1_sel:WORD_1
	v_sub_f32_e32 v2, v6, v163
	v_exp_f32_e32 v8, v3
	v_sub_f32_e32 v3, v6, v165
	v_mul_f32_e32 v2, 0x3fb8aa3b, v2
	v_mul_f32_e32 v3, 0x3fb8aa3b, v3
	v_sub_f32_e32 v5, v6, v6
	v_exp_f32_e32 v2, v2
	v_exp_f32_e32 v3, v3
	v_mul_f32_e32 v5, 0x3fb8aa3b, v5
	v_exp_f32_e32 v9, v5
	s_waitcnt vmcnt(2)
	v_lshlrev_b32_e32 v7, 16, v97
	v_lshlrev_b32_e32 v6, 16, v11
	v_pk_mul_f32 v[2:3], v[2:3], v[6:7]
	s_waitcnt vmcnt(0)
	v_lshlrev_b32_e32 v5, 16, v4
	v_lshlrev_b32_e32 v4, 16, v98
	v_pk_mul_f32 v[4:5], v[8:9], v[4:5]
	v_and_b32_sdwa v6, v3, v91 dst_sel:DWORD dst_unused:UNUSED_PAD src0_sel:WORD_1 src1_sel:DWORD
	v_and_b32_sdwa v7, v2, v91 dst_sel:DWORD dst_unused:UNUSED_PAD src0_sel:WORD_1 src1_sel:DWORD
	v_add3_u32 v2, v2, v7, s72
	v_add3_u32 v3, v3, v6, s72
	v_and_b32_sdwa v6, v5, v91 dst_sel:DWORD dst_unused:UNUSED_PAD src0_sel:WORD_1 src1_sel:DWORD
	v_and_b32_sdwa v7, v4, v91 dst_sel:DWORD dst_unused:UNUSED_PAD src0_sel:WORD_1 src1_sel:DWORD
	v_add3_u32 v5, v5, v6, s72
	v_add3_u32 v4, v4, v7, s72
	v_and_b32_e32 v5, 0xffff0000, v5
	v_and_b32_e32 v4, 0xffff0000, v4
	v_or_b32_sdwa v3, v5, v3 dst_sel:DWORD dst_unused:UNUSED_PAD src0_sel:DWORD src1_sel:WORD_1
	v_or_b32_sdwa v2, v4, v2 dst_sel:DWORD dst_unused:UNUSED_PAD src0_sel:DWORD src1_sel:WORD_1
	ds_write_b128 v86, v[0:3] offset:112
	v_or_b32_e32 v0, s3, v128
	v_mad_i64_i32 v[60:61], s[4:5], v0, s39, v[58:59]
	v_or_b32_e32 v0, 1, v0
	v_mad_i64_i32 v[62:63], s[4:5], v0, s39, v[58:59]
	v_or_b32_e32 v0, s3, v78
	v_mad_i64_i32 v[64:65], s[4:5], v0, s39, v[58:59]
	v_or_b32_e32 v0, 1, v0
	v_mad_i64_i32 v[66:67], s[4:5], v0, s39, v[58:59]
	v_or_b32_e32 v0, s3, v79
	s_waitcnt lgkmcnt(0)
	v_mad_i64_i32 v[68:69], s[4:5], v0, s39, v[58:59]
	v_or_b32_e32 v0, 1, v0
	v_mad_i64_i32 v[70:71], s[4:5], v0, s39, v[58:59]
	v_or_b32_e32 v0, s2, v80
	s_lshl_b64 s[0:1], s[64:65], 15
	v_mad_i64_i32 v[72:73], s[2:3], v0, s39, v[58:59]
	v_or_b32_e32 v0, 1, v0
	v_mad_i64_i32 v[74:75], s[2:3], v0, s39, v[58:59]
	v_lshl_add_u64 v[76:77], v[26:27], 0, s[0:1]
	s_mov_b32 s0, s63
; #define LDS_WAIT() asm volatile("s_waitcnt lgkmcnt(0)" ::: "memory")
; __device__ __forceinline__ void gla_upd_unit(LAS unsigned char* wl, const bf16* PROJ, const float* R, const float* w_gk2, const float* b_gk, float* UPD, float* DEC, int unit, int lane) {
;     ...
;     for (int vh = 0; vh < 2; ++vh) {
; #pragma unroll
;         for (int it = 0; it < 4; ++it) {
;             const int t0 = it * 16 + 2 * sp;
;             const u32x4 va = *(const u32x4*)(PROJ + (size_t)(tok0 + t0) * NPROJ + 1536 + h * 128 + vh * 64 + 8 * cc);
;             const u32x4 vb = *(const u32x4*)(PROJ + (size_t)(tok0 + t0 + 1) * NPROJ + 1536 + h * 128 + vh * 64 + 8 * cc);
; #pragma unroll
;             for (int i = 0; i < 4; ++i) {
;                 VB32[(8 * cc + 2 * i) * (KS / 2) + (t0 >> 1)] = (va[i] & 0xffffu) | (vb[i] << 16);
;                 VB32[(8 * cc + 2 * i + 1) * (KS / 2) + (t0 >> 1)] = (va[i] >> 16) | (vb[i] & 0xffff0000u);
;             }
;         }
;         LDS_WAIT(); asm volatile("" ::: "memory");
.LBB0_422:
	s_lshl_b32 s62, s0, 7
	v_lshl_add_u64 v[0:1], v[60:61], 0, s[62:63]
	v_lshl_add_u64 v[16:17], v[62:63], 0, s[62:63]
	v_lshl_add_u64 v[4:5], v[64:65], 0, s[62:63]
	v_lshl_add_u64 v[20:21], v[66:67], 0, s[62:63]
	v_lshl_add_u64 v[8:9], v[68:69], 0, s[62:63]
	v_lshl_add_u64 v[92:93], v[70:71], 0, s[62:63]
	v_lshl_add_u64 v[12:13], v[72:73], 0, s[62:63]
	v_lshl_add_u64 v[96:97], v[74:75], 0, s[62:63]
	global_load_dwordx4 v[0:3], v[0:1], off offset:3072 nt
	s_nop 0
	global_load_dwordx4 v[4:7], v[4:5], off offset:3072 nt
	s_nop 0
	global_load_dwordx4 v[8:11], v[8:9], off offset:3072 nt
	s_nop 0
	global_load_dwordx4 v[12:15], v[12:13], off offset:3072 nt
	s_nop 0
	global_load_dwordx4 v[16:19], v[16:17], off offset:3072 nt
	s_nop 0
	global_load_dwordx4 v[20:23], v[20:21], off offset:3072 nt
	s_nop 0
	global_load_dwordx4 v[92:95], v[92:93], off offset:3072 nt
	s_nop 0
	global_load_dwordx4 v[96:99], v[96:97], off offset:3072 nt
	v_add_u32_e32 v100, 0x2400, v81
	v_add_u32_e32 v101, 0x2400, v82
	v_add_u32_e32 v102, 0x2400, v83
	v_add_u32_e32 v103, 0x2400, v84
	s_lshl_b32 s62, s0, 12
	v_lshl_add_u64 v[154:155], s[62:63], 2, v[76:77]
	v_add_co_u32_e32 v156, vcc, 0x1000, v154
	s_mov_b64 s[4:5], vcc
	s_and_b64 s[2:3], exec, s[66:67]
	s_mov_b64 s[66:67], 0
	s_waitcnt vmcnt(7)
	v_and_b32_e32 v104, 0xffff, v0
	v_lshrrev_b32_e32 v0, 16, v0
	v_and_b32_e32 v105, 0xffff, v1
	v_lshrrev_b32_e32 v1, 16, v1
	v_and_b32_e32 v106, 0xffff, v2
	v_lshrrev_b32_e32 v2, 16, v2
	v_and_b32_e32 v107, 0xffff, v3
	v_lshrrev_b32_e32 v3, 16, v3
	s_waitcnt vmcnt(6)
	v_and_b32_e32 v108, 0xffff, v4
	v_lshrrev_b32_e32 v4, 16, v4
	v_and_b32_e32 v109, 0xffff, v5
	v_lshrrev_b32_e32 v5, 16, v5
	v_and_b32_e32 v110, 0xffff, v6
	v_lshrrev_b32_e32 v6, 16, v6
	v_and_b32_e32 v111, 0xffff, v7
	v_lshrrev_b32_e32 v7, 16, v7
	s_waitcnt vmcnt(5)
	v_and_b32_e32 v112, 0xffff, v8
	v_lshrrev_b32_e32 v8, 16, v8
	v_and_b32_e32 v113, 0xffff, v9
	v_lshrrev_b32_e32 v9, 16, v9
	v_and_b32_e32 v114, 0xffff, v10
	v_lshrrev_b32_e32 v10, 16, v10
	v_and_b32_e32 v115, 0xffff, v11
	v_lshrrev_b32_e32 v11, 16, v11
	s_waitcnt vmcnt(4)
	v_and_b32_e32 v116, 0xffff, v12
	v_lshrrev_b32_e32 v12, 16, v12
	v_and_b32_e32 v117, 0xffff, v13
	v_lshrrev_b32_e32 v13, 16, v13
	v_and_b32_e32 v118, 0xffff, v14
	v_lshrrev_b32_e32 v14, 16, v14
	v_and_b32_e32 v119, 0xffff, v15
	v_lshrrev_b32_e32 v15, 16, v15
	s_waitcnt vmcnt(3)
	v_lshl_or_b32 v104, v16, 16, v104
	v_and_or_b32 v0, v16, s73, v0
	v_lshl_or_b32 v16, v17, 16, v105
	v_and_or_b32 v1, v17, s73, v1
	v_lshl_or_b32 v17, v18, 16, v106
	v_and_or_b32 v2, v18, s73, v2
	v_lshl_or_b32 v18, v19, 16, v107
	v_and_or_b32 v3, v19, s73, v3
	s_waitcnt vmcnt(2)
	v_lshl_or_b32 v19, v20, 16, v108
	v_and_or_b32 v4, v20, s73, v4
	v_lshl_or_b32 v20, v21, 16, v109
	v_and_or_b32 v5, v21, s73, v5
	v_lshl_or_b32 v21, v22, 16, v110
	v_and_or_b32 v6, v22, s73, v6
	v_lshl_or_b32 v22, v23, 16, v111
	v_and_or_b32 v7, v23, s73, v7
	s_waitcnt vmcnt(1)
	v_lshl_or_b32 v23, v92, 16, v112
	v_and_or_b32 v8, v92, s73, v8
	v_lshl_or_b32 v92, v93, 16, v113
	v_and_or_b32 v9, v93, s73, v9
	v_lshl_or_b32 v93, v94, 16, v114
	v_and_or_b32 v10, v94, s73, v10
	v_lshl_or_b32 v94, v95, 16, v115
	v_and_or_b32 v11, v95, s73, v11
	s_waitcnt vmcnt(0)
	v_lshl_or_b32 v95, v96, 16, v116
	v_and_or_b32 v12, v96, s73, v12
	v_lshl_or_b32 v96, v97, 16, v117
	v_and_or_b32 v13, v97, s73, v13
	v_lshl_or_b32 v97, v98, 16, v118
	v_and_or_b32 v14, v98, s73, v14
	v_lshl_or_b32 v98, v99, 16, v119
	v_and_or_b32 v15, v99, s73, v15
	ds_write2_b32 v100, v104, v0 offset1:36
	ds_write2_b32 v100, v16, v1 offset0:72 offset1:108
	ds_write2_b32 v100, v17, v2 offset0:144 offset1:180
	ds_write2_b32 v100, v18, v3 offset0:216 offset1:252
	ds_write2_b32 v101, v19, v4 offset1:36
	ds_write2_b32 v101, v20, v5 offset0:72 offset1:108
	ds_write2_b32 v101, v21, v6 offset0:144 offset1:180
	ds_write2_b32 v101, v22, v7 offset0:216 offset1:252
	ds_write2_b32 v102, v23, v8 offset1:36
	ds_write2_b32 v102, v92, v9 offset0:72 offset1:108
	ds_write2_b32 v102, v93, v10 offset0:144 offset1:180
	ds_write2_b32 v102, v94, v11 offset0:216 offset1:252
	ds_write2_b32 v103, v95, v12 offset1:36
	ds_write2_b32 v103, v96, v13 offset0:72 offset1:108
	ds_write2_b32 v103, v97, v14 offset0:144 offset1:180
	ds_write2_b32 v103, v98, v15 offset0:216 offset1:252
	s_waitcnt lgkmcnt(0)
; #define LAS __attribute__((address_space(3)))
; #define LDS_WAIT() asm volatile("s_waitcnt lgkmcnt(0)" ::: "memory")
; __device__ __forceinline__ void gla_upd_unit(LAS unsigned char* wl, const bf16* PROJ, const float* R, const float* w_gk2, const float* b_gk, float* UPD, float* DEC, int unit, int lane) {
;     ...
;         f32x4 acc[4][4];
; #pragma unroll
;         for (int i = 0; i < 4; ++i)
; #pragma unroll
;             for (int j = 0; j < 4; ++j) acc[i][j] = (f32x4){0.f, 0.f, 0.f, 0.f};
; #pragma unroll
;         for (int ki = 0; ki < 2; ++ki) {
;             bf16x8 av[4], bk[4];
; #pragma unroll
;             for (int mi = 0; mi < 4; ++mi) av[mi] = *(const LAS bf16x8*)(wl + 9216 + ((16 * mi + fr) * KS + 32 * ki + 8 * fq) * 2);
; #pragma unroll
;             for (int ni = 0; ni < 4; ++ni) bk[ni] = *(const LAS bf16x8*)(wl + ((16 * ni + fr) * KS + 32 * ki + 8 * fq) * 2);
; #pragma unroll
;             for (int mi = 0; mi < 4; ++mi)
; #pragma unroll
;                 for (int ni = 0; ni < 4; ++ni) acc[mi][ni] = __builtin_amdgcn_mfma_f32_16x16x32_bf16(bk[ni], av[mi], acc[mi][ni], 0, 0, 0);
;         }
;         float* up = UPD + (size_t)unit * 8192 + (size_t)(vh * 64) * 64;
; #pragma unroll
;         for (int mi = 0; mi < 4; ++mi)
; #pragma unroll
;             for (int ni = 0; ni < 4; ++ni) *(f32x4*)(up + (16 * mi + fr) * 64 + 16 * ni + 4 * fq) = acc[mi][ni];
;         LDS_WAIT(); asm volatile("" ::: "memory");
;     }
	ds_read_b128 v[0:3], v87
	ds_read_b128 v[4:7], v87 offset:9216
	ds_read_b128 v[12:15], v87 offset:2304
	ds_read_b128 v[20:23], v87 offset:4608
	ds_read_b128 v[100:103], v88
	s_waitcnt lgkmcnt(3)
	v_mfma_f32_16x16x32_bf16 v[16:19], v[0:3], v[4:7], 0
	ds_read_b128 v[142:145], v88 offset:9216
	ds_read_b128 v[150:153], v88 offset:64
	ds_read_b128 v[146:149], v87 offset:4672
	s_waitcnt lgkmcnt(5)
	v_mfma_f32_16x16x32_bf16 v[92:95], v[12:15], v[4:7], 0
	s_waitcnt lgkmcnt(4)
	v_mfma_f32_16x16x32_bf16 v[96:99], v[20:23], v[4:7], 0
	s_waitcnt lgkmcnt(3)
	v_mfma_f32_16x16x32_bf16 v[104:107], v[100:103], v[4:7], 0
	ds_read_b128 v[4:7], v87 offset:11520
	s_waitcnt lgkmcnt(0)
	v_mfma_f32_16x16x32_bf16 v[108:111], v[0:3], v[4:7], 0
	v_mfma_f32_16x16x32_bf16 v[112:115], v[12:15], v[4:7], 0
	v_mfma_f32_16x16x32_bf16 v[116:119], v[20:23], v[4:7], 0
	v_mfma_f32_16x16x32_bf16 v[120:123], v[100:103], v[4:7], 0
	ds_read_b128 v[4:7], v87 offset:13824
	s_waitcnt lgkmcnt(0)
	v_mfma_f32_16x16x32_bf16 v[124:127], v[0:3], v[4:7], 0
	v_mfma_f32_16x16x32_bf16 v[130:133], v[12:15], v[4:7], 0
	v_mfma_f32_16x16x32_bf16 v[134:137], v[20:23], v[4:7], 0
	v_mfma_f32_16x16x32_bf16 v[138:141], v[100:103], v[4:7], 0
	v_mfma_f32_16x16x32_bf16 v[8:11], v[0:3], v[142:145], 0
	v_mfma_f32_16x16x32_bf16 v[4:7], v[12:15], v[142:145], 0
	v_mfma_f32_16x16x32_bf16 v[0:3], v[20:23], v[142:145], 0
	ds_read_b128 v[20:23], v87 offset:64
	v_mfma_f32_16x16x32_bf16 v[12:15], v[100:103], v[142:145], 0
	ds_read_b128 v[100:103], v87 offset:9280
	ds_read_b128 v[142:145], v87 offset:2368
	s_waitcnt lgkmcnt(1)
	v_mfma_f32_16x16x32_bf16 v[16:19], v[20:23], v[100:103], v[16:19]
	s_waitcnt lgkmcnt(0)
	v_mfma_f32_16x16x32_bf16 v[92:95], v[142:145], v[100:103], v[92:95]
	v_mfma_f32_16x16x32_bf16 v[96:99], v[146:149], v[100:103], v[96:99]
	v_mfma_f32_16x16x32_bf16 v[100:103], v[150:153], v[100:103], v[104:107]
	s_nop 2
	ds_read_b128 v[104:107], v87 offset:11584
	s_waitcnt lgkmcnt(0)
	v_mfma_f32_16x16x32_bf16 v[108:111], v[20:23], v[104:107], v[108:111]
	v_mfma_f32_16x16x32_bf16 v[112:115], v[142:145], v[104:107], v[112:115]
	v_mfma_f32_16x16x32_bf16 v[116:119], v[146:149], v[104:107], v[116:119]
	v_mfma_f32_16x16x32_bf16 v[104:107], v[150:153], v[104:107], v[120:123]
	s_nop 2
	ds_read_b128 v[120:123], v87 offset:13888
	s_waitcnt lgkmcnt(0)
	v_mfma_f32_16x16x32_bf16 v[124:127], v[20:23], v[120:123], v[124:127]
	v_mfma_f32_16x16x32_bf16 v[130:133], v[142:145], v[120:123], v[130:133]
	v_mfma_f32_16x16x32_bf16 v[134:137], v[146:149], v[120:123], v[134:137]
	v_mfma_f32_16x16x32_bf16 v[120:123], v[150:153], v[120:123], v[138:141]
	s_nop 2
	ds_read_b128 v[138:141], v88 offset:9280
	s_waitcnt lgkmcnt(0)
	v_mfma_f32_16x16x32_bf16 v[8:11], v[20:23], v[138:141], v[8:11]
	v_add_co_u32_e32 v20, vcc, 0x2000, v154
	s_mov_b64 s[0:1], vcc
	v_addc_co_u32_e64 v157, vcc, 0, v155, s[4:5]
	v_add_co_u32_e32 v22, vcc, 0x3000, v154
	v_mfma_f32_16x16x32_bf16 v[4:7], v[142:145], v[138:141], v[4:7]
	v_addc_co_u32_e64 v21, s[0:1], 0, v155, s[0:1]
	v_addc_co_u32_e32 v23, vcc, 0, v155, vcc
	v_mfma_f32_16x16x32_bf16 v[0:3], v[146:149], v[138:141], v[0:3]
	s_mov_b32 s0, 1
	s_mov_b64 vcc, s[2:3]
	v_mfma_f32_16x16x32_bf16 v[12:15], v[150:153], v[138:141], v[12:15]
	global_store_dwordx4 v[154:155], v[16:19], off
	global_store_dwordx4 v[154:155], v[92:95], off offset:64
	global_store_dwordx4 v[154:155], v[96:99], off offset:128
	global_store_dwordx4 v[154:155], v[100:103], off offset:192
	global_store_dwordx4 v[156:157], v[108:111], off
	global_store_dwordx4 v[156:157], v[112:115], off offset:64
	global_store_dwordx4 v[156:157], v[116:119], off offset:128
	global_store_dwordx4 v[156:157], v[104:107], off offset:192
	global_store_dwordx4 v[20:21], v[124:127], off
	global_store_dwordx4 v[20:21], v[130:133], off offset:64
	global_store_dwordx4 v[20:21], v[134:137], off offset:128
	global_store_dwordx4 v[20:21], v[120:123], off offset:192
	global_store_dwordx4 v[22:23], v[8:11], off
	global_store_dwordx4 v[22:23], v[4:7], off offset:64
	global_store_dwordx4 v[22:23], v[0:3], off offset:128
	global_store_dwordx4 v[22:23], v[12:15], off offset:192
	s_waitcnt lgkmcnt(0)
	s_cbranch_vccnz .LBB0_422
	s_add_i32 s64, s64, s36
	s_cmpk_lt_i32 s64, 0x100
	s_cbranch_scc1 .LBB0_421

; __device__ __forceinline__ float ss_val(u64 v) { return (float)v * (1.0f / 1099511627776.0f); }
; __device__ __forceinline__ unsigned pk2(float lo, float hi) { return f2bf(lo) | (f2bf(hi) << 16); }
; __device__ __forceinline__ void gmlp_unit(LAS unsigned char* wl, const bf16* PROJ, const u64* rowss_v, const bf16* wsb, const float* norm_v, const float* b_s, bf16* Y, int nb, int g, int lane) {
;     ...
; #pragma unroll 4
;     for (int it = 0; it < 8; ++it) {
;         const int s0 = it * 16 + 2 * sp;
;         const float r0 = __builtin_amdgcn_rsqf(ss_val(rowss_v[tok0 + s0]) * (1.f / 512.f) + EPS), r1 = __builtin_amdgcn_rsqf(ss_val(rowss_v[tok0 + s0 + 1]) * (1.f / 512.f) + EPS);
;         const u32x4 va = *(const u32x4*)(PROJ + (size_t)(tok0 + s0) * NPROJ + 512 + g * 64 + 8 * cc);
;         const u32x4 vb = *(const u32x4*)(PROJ + (size_t)(tok0 + s0 + 1) * NPROJ + 512 + g * 64 + 8 * cc);
; #pragma unroll
;         for (int i = 0; i < 4; ++i) {
;             VT32[(8 * cc + 2 * i) * (VS / 2) + (s0 >> 1)] = pk2(bf_lo(va[i]) * r0, bf_lo(vb[i]) * r1);
.LBB0_1051:
	v_add_u32_e32 v0, s11, v2
	v_ashrrev_i32_e32 v1, 31, v0
	v_add_u32_e32 v8, 1, v0
	v_add_u32_e32 v40, 16, v0
	v_add_u32_e32 v9, 17, v0
	v_add_u32_e32 v42, 32, v0
	v_add_u32_e32 v10, 33, v0
	v_add_u32_e32 v44, 48, v0
	v_add_u32_e32 v11, 49, v0
	v_mad_i64_i32 v[12:13], s[12:13], v0, s4, v[136:137]
	v_lshl_add_u64 v[0:1], v[0:1], 3, s[0:1]
	v_mad_i64_i32 v[16:17], s[12:13], v8, s4, v[136:137]
	v_ashrrev_i32_e32 v41, 31, v40
	v_mad_i64_i32 v[20:21], s[12:13], v40, s4, v[136:137]
	v_mad_i64_i32 v[24:25], s[12:13], v9, s4, v[136:137]
	v_ashrrev_i32_e32 v43, 31, v42
	v_mad_i64_i32 v[28:29], s[12:13], v10, s4, v[136:137]
	v_ashrrev_i32_e32 v45, 31, v44
	v_mad_i64_i32 v[32:33], s[12:13], v44, s4, v[136:137]
	v_mad_i64_i32 v[36:37], s[12:13], v11, s4, v[136:137]
	v_mad_i64_i32 v[48:49], s[12:13], v42, s4, v[136:137]
	global_load_dwordx4 v[8:11], v[0:1], off nt
	s_nop 0
	global_load_dwordx4 v[12:15], v[12:13], off offset:1024 nt
	s_nop 0
	global_load_dwordx4 v[16:19], v[16:17], off offset:1024 nt
	s_nop 0
	global_load_dwordx4 v[20:23], v[20:21], off offset:1024 nt
	s_nop 0
	global_load_dwordx4 v[24:27], v[24:25], off offset:1024 nt
	s_nop 0
	global_load_dwordx4 v[28:31], v[28:29], off offset:1024 nt
	s_nop 0
	global_load_dwordx4 v[32:35], v[32:33], off offset:1024 nt
	s_nop 0
	global_load_dwordx4 v[36:39], v[36:37], off offset:1024 nt
	v_lshl_add_u64 v[0:1], v[40:41], 3, s[0:1]
	v_lshl_add_u64 v[46:47], v[42:43], 3, s[0:1]
	v_lshl_add_u64 v[52:53], v[44:45], 3, s[0:1]
	global_load_dwordx4 v[40:43], v[0:1], off nt
	s_nop 0
	global_load_dwordx4 v[44:47], v[46:47], off nt
	s_nop 0
	global_load_dwordx4 v[48:51], v[48:49], off offset:1024 nt
	s_nop 0
	global_load_dwordx4 v[52:55], v[52:53], off nt
	v_add_u32_e32 v4, v3, v152
	s_add_i32 s11, s11, 64
	v_add_u32_e32 v5, v3, v151
	v_add_u32_e32 v6, v3, v150
	v_add_u32_e32 v7, v3, v149
	v_add_u32_e32 v3, 0x80, v3
	v_add_u32_e32 v56, 0x400, v4
	s_cmpk_lg_i32 s11, 0x80
	v_add_u32_e32 v57, 0x400, v5
	v_add_u32_e32 v58, 0x400, v6
	v_add_u32_e32 v59, 0x400, v7
	s_waitcnt vmcnt(11)
	v_ffbh_u32_e32 v0, v9
	v_ffbh_u32_e32 v1, v11
	s_waitcnt vmcnt(10)
	v_lshlrev_b32_e32 v60, 16, v12
	v_and_b32_e32 v62, 0xffff0000, v12
	v_lshlrev_b32_e32 v155, 16, v13
	v_and_b32_e32 v157, 0xffff0000, v13
	v_lshlrev_b32_e32 v159, 16, v14
	v_and_b32_e32 v161, 0xffff0000, v14
	v_min_u32_e32 v12, 32, v0
	v_min_u32_e32 v13, 32, v1
	s_waitcnt vmcnt(3)
	v_ffbh_u32_e32 v14, v41
	v_lshlrev_b32_e32 v61, 16, v16
	v_and_b32_e32 v63, 0xffff0000, v16
	v_lshlrev_b32_e32 v156, 16, v17
	v_and_b32_e32 v158, 0xffff0000, v17
	v_lshlrev_b32_e32 v160, 16, v18
	v_and_b32_e32 v162, 0xffff0000, v18
	v_lshlrev_b32_e32 v163, 16, v15
	v_and_b32_e32 v165, 0xffff0000, v15
	v_ffbh_u32_e32 v15, v43
	s_waitcnt vmcnt(2)
	v_ffbh_u32_e32 v16, v45
	v_ffbh_u32_e32 v17, v47
	s_waitcnt vmcnt(0)
	v_ffbh_u32_e32 v18, v53
	v_lshlrev_b64 v[0:1], v12, v[8:9]
	v_sub_u32_e32 v193, 32, v12
	v_lshlrev_b64 v[8:9], v13, v[10:11]
	v_min_u32_e32 v12, 32, v14
	v_lshlrev_b32_e32 v164, 16, v19
	v_and_b32_e32 v166, 0xffff0000, v19
	v_lshlrev_b32_e32 v167, 16, v20
	v_and_b32_e32 v169, 0xffff0000, v20
	v_lshlrev_b32_e32 v170, 16, v21
	v_and_b32_e32 v172, 0xffff0000, v21
	v_min_u32_e32 v14, 32, v15
	v_min_u32_e32 v16, 32, v16
	v_min_u32_e32 v20, 32, v17
	v_min_u32_e32 v21, 32, v18
	v_min_u32_e32 v0, 1, v0
	v_min_u32_e32 v8, 1, v8
	v_lshlrev_b64 v[10:11], v12, v[40:41]
	v_sub_u32_e32 v194, 32, v13
	v_sub_u32_e32 v40, 32, v12
	v_lshlrev_b64 v[12:13], v14, v[42:43]
	v_sub_u32_e32 v41, 32, v14
	v_lshlrev_b64 v[14:15], v16, v[44:45]
	v_sub_u32_e32 v42, 32, v16
	v_lshlrev_b64 v[16:17], v20, v[46:47]
	v_lshlrev_b64 v[18:19], v21, v[52:53]
	v_or_b32_e32 v0, v1, v0
	v_or_b32_e32 v1, v9, v8
	v_min_u32_e32 v8, 1, v10
	v_sub_u32_e32 v43, 32, v20
	v_sub_u32_e32 v44, 32, v21
	v_min_u32_e32 v9, 1, v12
	v_min_u32_e32 v10, 1, v14
	v_min_u32_e32 v12, 1, v16
	v_min_u32_e32 v14, 1, v18
	v_cvt_f32_u32_e32 v0, v0
	v_or_b32_e32 v8, v11, v8
	v_cvt_f32_u32_e32 v1, v1
	v_or_b32_e32 v9, v13, v9
	v_or_b32_e32 v10, v15, v10
	v_or_b32_e32 v11, v17, v12
	v_or_b32_e32 v12, v19, v14
	v_cvt_f32_u32_e32 v8, v8
	v_cvt_f32_u32_e32 v9, v9
	v_cvt_f32_u32_e32 v10, v10
	v_cvt_f32_u32_e32 v11, v11
	v_cvt_f32_u32_e32 v12, v12
	v_ldexp_f32 v0, v0, v193
	v_ldexp_f32 v1, v1, v194
	v_mul_f32_e32 v0, 0x2b800000, v0
	v_ldexp_f32 v8, v8, v40
	v_mul_f32_e32 v1, 0x2b800000, v1
	v_ldexp_f32 v9, v9, v41
	v_ldexp_f32 v10, v10, v42
	v_ldexp_f32 v11, v11, v43
	v_ldexp_f32 v12, v12, v44
	v_fmamk_f32 v0, v0, 0x3b000000, v153
	v_mul_f32_e32 v8, 0x2b800000, v8
	v_fmamk_f32 v1, v1, 0x3b000000, v153
	v_mul_f32_e32 v9, 0x2b800000, v9
	v_mul_f32_e32 v10, 0x2b800000, v10
	v_mul_f32_e32 v11, 0x2b800000, v11
	v_mul_f32_e32 v12, 0x2b800000, v12
	v_rsq_f32_e32 v0, v0
	v_fmamk_f32 v8, v8, 0x3b000000, v153
	v_rsq_f32_e32 v1, v1
	v_fmamk_f32 v9, v9, 0x3b000000, v153
	v_fmamk_f32 v10, v10, 0x3b000000, v153
	v_fmamk_f32 v11, v11, 0x3b000000, v153
	v_fmamk_f32 v12, v12, 0x3b000000, v153
	v_rsq_f32_e32 v8, v8
	v_cvt_f32_u32_e32 v54, v54
	v_cvt_f32_u32_e32 v55, v55
	v_fmamk_f32 v54, v55, 0x4f800000, v54
	v_fmamk_f32 v13, v54, 0x27000000, v153
	v_rsq_f32_e32 v9, v9
	v_rsq_f32_e32 v10, v10
	v_rsq_f32_e32 v11, v11
	v_rsq_f32_e32 v12, v12
	v_rsq_f32_e32 v13, v13
	v_mul_f32_e32 v14, v0, v60
	v_mul_f32_e32 v16, v0, v62
	v_mul_f32_e32 v18, v0, v155
	v_mul_f32_e32 v20, v0, v157
	v_mul_f32_e32 v40, v0, v159
	v_mul_f32_e32 v42, v0, v161
	v_mul_f32_e32 v44, v0, v163
	v_mul_f32_e32 v0, v0, v165
	v_lshlrev_b32_e32 v168, 16, v24
	v_and_b32_e32 v24, 0xffff0000, v24
	v_lshlrev_b32_e32 v171, 16, v25
	v_and_b32_e32 v25, 0xffff0000, v25
	v_lshlrev_b32_e32 v173, 16, v22
; __device__ __forceinline__ float ss_val(u64 v) { return (float)v * (1.0f / 1099511627776.0f); }
; __device__ __forceinline__ unsigned pk2(float lo, float hi) { return f2bf(lo) | (f2bf(hi) << 16); }
; __device__ __forceinline__ void gmlp_unit(LAS unsigned char* wl, const bf16* PROJ, const u64* rowss_v, const bf16* wsb, const float* norm_v, const float* b_s, bf16* Y, int nb, int g, int lane) {
;     ...
;         const int s0 = it * 16 + 2 * sp;
;         const float r0 = __builtin_amdgcn_rsqf(ss_val(rowss_v[tok0 + s0]) * (1.f / 512.f) + EPS), r1 = __builtin_amdgcn_rsqf(ss_val(rowss_v[tok0 + s0 + 1]) * (1.f / 512.f) + EPS);
;         const u32x4 va = *(const u32x4*)(PROJ + (size_t)(tok0 + s0) * NPROJ + 512 + g * 64 + 8 * cc);
;         const u32x4 vb = *(const u32x4*)(PROJ + (size_t)(tok0 + s0 + 1) * NPROJ + 512 + g * 64 + 8 * cc);
; #pragma unroll
;         for (int i = 0; i < 4; ++i) {
;             VT32[(8 * cc + 2 * i) * (VS / 2) + (s0 >> 1)] = pk2(bf_lo(va[i]) * r0, bf_lo(vb[i]) * r1);
;             VT32[(8 * cc + 2 * i + 1) * (VS / 2) + (s0 >> 1)] = pk2(bf_hi(va[i]) * r0, bf_hi(vb[i]) * r1);
;         }
	v_lshlrev_b32_e32 v174, 16, v26
	v_and_b32_e32 v22, 0xffff0000, v22
	v_and_b32_e32 v26, 0xffff0000, v26
	v_lshlrev_b32_e32 v175, 16, v23
	v_lshlrev_b32_e32 v176, 16, v27
	v_and_b32_e32 v23, 0xffff0000, v23
	v_and_b32_e32 v27, 0xffff0000, v27
	v_lshlrev_b32_e32 v177, 16, v28
	v_and_b32_e32 v28, 0xffff0000, v28
	v_lshlrev_b32_e32 v178, 16, v29
	v_and_b32_e32 v29, 0xffff0000, v29
	v_lshlrev_b32_e32 v179, 16, v30
	v_and_b32_e32 v30, 0xffff0000, v30
	v_lshlrev_b32_e32 v180, 16, v31
	v_and_b32_e32 v31, 0xffff0000, v31
	v_lshlrev_b32_e32 v181, 16, v32
	v_and_b32_e32 v32, 0xffff0000, v32
	v_lshlrev_b32_e32 v183, 16, v33
	v_and_b32_e32 v33, 0xffff0000, v33
	v_lshlrev_b32_e32 v185, 16, v34
	v_and_b32_e32 v34, 0xffff0000, v34
	v_lshlrev_b32_e32 v187, 16, v35
	v_and_b32_e32 v35, 0xffff0000, v35
	v_lshlrev_b32_e32 v189, 16, v48
	v_and_b32_e32 v48, 0xffff0000, v48
	v_lshlrev_b32_e32 v190, 16, v49
	v_and_b32_e32 v49, 0xffff0000, v49
	v_lshlrev_b32_e32 v191, 16, v50
	v_and_b32_e32 v50, 0xffff0000, v50
	v_lshlrev_b32_e32 v192, 16, v51
	v_and_b32_e32 v51, 0xffff0000, v51
	v_mul_f32_e32 v15, v1, v61
	v_mul_f32_e32 v17, v1, v63
	v_mul_f32_e32 v19, v1, v156
	v_mul_f32_e32 v21, v1, v158
	v_mul_f32_e32 v41, v1, v160
	v_mul_f32_e32 v43, v1, v162
	v_mul_f32_e32 v45, v1, v164
	v_mul_f32_e32 v1, v1, v166
	v_bfe_u32 v46, v14, 16, 1
	v_bfe_u32 v52, v16, 16, 1
	v_bfe_u32 v60, v20, 16, 1
	v_bfe_u32 v62, v40, 16, 1
	v_bfe_u32 v155, v42, 16, 1
	v_bfe_u32 v157, v44, 16, 1
	v_bfe_u32 v159, v0, 16, 1
	v_mul_f32_e32 v161, v8, v167
	v_mul_f32_e32 v163, v8, v169
	v_lshlrev_b32_e32 v182, 16, v36
	v_and_b32_e32 v36, 0xffff0000, v36
	v_lshlrev_b32_e32 v184, 16, v37
	v_and_b32_e32 v37, 0xffff0000, v37
	v_lshlrev_b32_e32 v186, 16, v38
	v_and_b32_e32 v38, 0xffff0000, v38
	v_lshlrev_b32_e32 v188, 16, v39
	v_and_b32_e32 v39, 0xffff0000, v39
	v_bfe_u32 v47, v15, 16, 1
	v_bfe_u32 v53, v17, 16, 1
	v_bfe_u32 v54, v18, 16, 1
	v_bfe_u32 v61, v21, 16, 1
	v_bfe_u32 v63, v41, 16, 1
	v_bfe_u32 v156, v43, 16, 1
	v_bfe_u32 v158, v45, 16, 1
	v_bfe_u32 v160, v1, 16, 1
	v_mul_f32_e32 v162, v9, v168
	v_mul_f32_e32 v24, v9, v24
	v_mul_f32_e32 v164, v8, v170
	v_mul_f32_e32 v165, v9, v171
	v_mul_f32_e32 v166, v8, v172
	v_mul_f32_e32 v25, v9, v25
	v_mul_f32_e32 v167, v8, v173
	v_mul_f32_e32 v168, v9, v174
	v_mul_f32_e32 v22, v8, v22
	v_mul_f32_e32 v26, v9, v26
	v_mul_f32_e32 v169, v8, v175
	v_mul_f32_e32 v170, v9, v176
	v_mul_f32_e32 v8, v8, v23
	v_mul_f32_e32 v9, v9, v27
	v_mul_f32_e32 v23, v10, v189
	v_mul_f32_e32 v27, v11, v177
	v_mul_f32_e32 v48, v10, v48
	v_mul_f32_e32 v28, v11, v28
	v_mul_f32_e32 v171, v10, v190
	v_mul_f32_e32 v172, v11, v178
	v_mul_f32_e32 v49, v10, v49
	v_mul_f32_e32 v29, v11, v29
	v_mul_f32_e32 v173, v10, v191
	v_mul_f32_e32 v174, v11, v179
	v_mul_f32_e32 v50, v10, v50
	v_mul_f32_e32 v30, v11, v30
	v_mul_f32_e32 v175, v10, v192
	v_mul_f32_e32 v176, v11, v180
	v_mul_f32_e32 v10, v10, v51
	v_mul_f32_e32 v11, v11, v31
	v_mul_f32_e32 v31, v12, v181
	v_mul_f32_e32 v32, v12, v32
	v_mul_f32_e32 v177, v12, v183
	v_mul_f32_e32 v33, v12, v33
	v_mul_f32_e32 v179, v12, v185
	v_mul_f32_e32 v34, v12, v34
	v_mul_f32_e32 v181, v12, v187
	v_mul_f32_e32 v12, v12, v35
	v_add3_u32 v14, v14, v46, s5
	v_add3_u32 v16, v16, v52, s5
	v_add3_u32 v20, v20, v60, s5
	v_add3_u32 v35, v40, v62, s5
	v_add3_u32 v40, v42, v155, s5
	v_add3_u32 v42, v44, v157, s5
	v_add3_u32 v0, v0, v159, s5
	v_bfe_u32 v44, v161, 16, 1
	v_bfe_u32 v46, v163, 16, 1
	v_bfe_u32 v55, v19, 16, 1
	v_mul_f32_e32 v51, v13, v182
	v_mul_f32_e32 v36, v13, v36
	v_mul_f32_e32 v178, v13, v184
	v_mul_f32_e32 v37, v13, v37
	v_mul_f32_e32 v180, v13, v186
	v_mul_f32_e32 v38, v13, v38
	v_mul_f32_e32 v182, v13, v188
	v_mul_f32_e32 v13, v13, v39
	v_add3_u32 v15, v15, v47, s5
	v_add3_u32 v17, v17, v53, s5
	v_add3_u32 v18, v18, v54, s5
	v_add3_u32 v21, v21, v61, s5
	v_add3_u32 v39, v41, v63, s5
	v_add3_u32 v41, v43, v156, s5
	v_add3_u32 v43, v45, v158, s5
	v_add3_u32 v1, v1, v160, s5
	v_bfe_u32 v45, v162, 16, 1
	v_bfe_u32 v47, v24, 16, 1
	v_bfe_u32 v52, v164, 16, 1
	v_bfe_u32 v53, v165, 16, 1
	v_bfe_u32 v54, v166, 16, 1
	v_bfe_u32 v60, v167, 16, 1
	v_bfe_u32 v62, v22, 16, 1
	v_bfe_u32 v155, v169, 16, 1
	v_bfe_u32 v157, v8, 16, 1
	v_bfe_u32 v159, v23, 16, 1
	v_bfe_u32 v183, v48, 16, 1
	v_bfe_u32 v185, v171, 16, 1
	v_bfe_u32 v187, v49, 16, 1
	v_bfe_u32 v189, v173, 16, 1
	v_bfe_u32 v191, v50, 16, 1
	v_bfe_u32 v193, v175, 16, 1
	v_bfe_u32 v195, v10, 16, 1
	v_bfe_u32 v197, v31, 16, 1
	v_bfe_u32 v199, v32, 16, 1
	v_bfe_u32 v206, v177, 16, 1
	v_bfe_u32 v208, v33, 16, 1
	v_bfe_u32 v210, v179, 16, 1
	v_bfe_u32 v212, v34, 16, 1
	v_bfe_u32 v214, v181, 16, 1
	v_bfe_u32 v216, v12, 16, 1
	v_lshrrev_b32_e32 v14, 16, v14
	v_lshrrev_b32_e32 v16, 16, v16
	v_lshrrev_b32_e32 v20, 16, v20
	v_lshrrev_b32_e32 v0, 16, v0
	v_add3_u32 v44, v161, v44, s5
	v_add3_u32 v46, v163, v46, s5
	v_add3_u32 v19, v19, v55, s5
	v_bfe_u32 v55, v25, 16, 1
	v_bfe_u32 v61, v168, 16, 1
	v_bfe_u32 v63, v26, 16, 1
	v_bfe_u32 v156, v170, 16, 1
	v_bfe_u32 v158, v9, 16, 1
	v_bfe_u32 v160, v27, 16, 1
	v_bfe_u32 v184, v28, 16, 1
	v_bfe_u32 v186, v172, 16, 1
	v_bfe_u32 v188, v29, 16, 1
	v_bfe_u32 v190, v174, 16, 1
	v_bfe_u32 v192, v30, 16, 1
	v_bfe_u32 v194, v176, 16, 1
	v_bfe_u32 v196, v11, 16, 1
	v_bfe_u32 v198, v51, 16, 1
	v_bfe_u32 v205, v36, 16, 1
	v_bfe_u32 v207, v178, 16, 1
	v_bfe_u32 v209, v37, 16, 1
	v_bfe_u32 v211, v180, 16, 1
	v_bfe_u32 v213, v38, 16, 1
	v_bfe_u32 v215, v182, 16, 1
	v_bfe_u32 v217, v13, 16, 1
	v_lshrrev_b32_e32 v18, 16, v18
	v_lshrrev_b32_e32 v35, 16, v35
	v_lshrrev_b32_e32 v40, 16, v40
	v_lshrrev_b32_e32 v42, 16, v42
	v_add3_u32 v45, v162, v45, s5
	v_add3_u32 v24, v24, v47, s5
; #define LAS __attribute__((address_space(3)))
; #define LDS_WAIT() asm volatile("s_waitcnt lgkmcnt(0)" ::: "memory")
; __device__ __forceinline__ unsigned pk2(float lo, float hi) { return f2bf(lo) | (f2bf(hi) << 16); }
; template <int HF>
; __device__ __forceinline__ void gmlp_half(LAS unsigned char* wl, const bf16* PROJ, const bf16* wsg, const float* norm_v, const float* b_s, bf16* Y, int tok0, int g, int fr, int fq) {
;     ...
;         for (int nt = 0; nt < 4; ++nt) bw[ki][nt] = *(const bf16x8*)(wsg + (size_t)(64 * HF + 16 * nt + fr) * 128 + 32 * ki + 8 * fq);
;     f32x4 acc[4][4];
; #pragma unroll
;     for (int i = 0; i < 4; ++i)
; #pragma unroll
;         for (int j = 0; j < 4; ++j) acc[i][j] = (f32x4){0.f, 0.f, 0.f, 0.f};
; #pragma unroll
;     for (int ki = 0; ki < NK; ++ki) {
;         bf16x8 av[4];
; #pragma unroll
;         for (int mi = 0; mi < 4; ++mi) av[mi] = *(const LAS bf16x8*)(wl + ((32 * (mi >> 1) + 8 * (fr >> 2) + 4 * (mi & 1) + (fr & 3)) * VS + 32 * ki + 8 * fq) * 2);
; #pragma unroll
;         for (int nt = 0; nt < 4; ++nt)
; #pragma unroll
;             for (int mi = 0; mi < 4; ++mi) acc[mi][nt] = __builtin_amdgcn_mfma_f32_16x16x32_bf16(av[mi], bw[ki][nt], acc[mi][nt], 0, 0, 0);
; __device__ __forceinline__ void gmlp_unit(LAS unsigned char* wl, const bf16* PROJ, const u64* rowss_v, const bf16* wsb, const float* norm_v, const float* b_s, bf16* Y, int nb, int g, int lane) {
;     ...
;             VT32[(8 * cc + 2 * i) * (VS / 2) + (s0 >> 1)] = pk2(bf_lo(va[i]) * r0, bf_lo(vb[i]) * r1);
;             VT32[(8 * cc + 2 * i + 1) * (VS / 2) + (s0 >> 1)] = pk2(bf_hi(va[i]) * r0, bf_hi(vb[i]) * r1);
;         }
;     }
;     LDS_WAIT(); asm volatile("" ::: "memory");
	v_add3_u32 v47, v164, v52, s5
	v_add3_u32 v52, v165, v53, s5
	v_add3_u32 v53, v166, v54, s5
	v_add3_u32 v54, v167, v60, s5
	v_add3_u32 v22, v22, v62, s5
	v_add3_u32 v60, v169, v155, s5
	v_add3_u32 v8, v8, v157, s5
	v_add3_u32 v23, v23, v159, s5
	v_add3_u32 v48, v48, v183, s5
	v_add3_u32 v62, v171, v185, s5
	v_add3_u32 v49, v49, v187, s5
	v_add3_u32 v155, v173, v189, s5
	v_add3_u32 v50, v50, v191, s5
	v_add3_u32 v157, v175, v193, s5
	v_add3_u32 v10, v10, v195, s5
	v_add3_u32 v31, v31, v197, s5
	v_add3_u32 v32, v32, v199, s5
	v_add3_u32 v159, v177, v206, s5
	v_add3_u32 v33, v33, v208, s5
	v_add3_u32 v161, v179, v210, s5
	v_add3_u32 v34, v34, v212, s5
	v_add3_u32 v163, v181, v214, s5
	v_add3_u32 v12, v12, v216, s5
	v_and_or_b32 v14, v15, s6, v14
	v_and_or_b32 v15, v17, s6, v16
	v_and_or_b32 v17, v21, s6, v20
	v_and_or_b32 v0, v1, s6, v0
	v_lshrrev_b32_e32 v1, 16, v44
	v_lshrrev_b32_e32 v21, 16, v46
	v_add3_u32 v25, v25, v55, s5
	v_add3_u32 v55, v168, v61, s5
	v_add3_u32 v26, v26, v63, s5
	v_add3_u32 v61, v170, v156, s5
	v_add3_u32 v9, v9, v158, s5
	v_add3_u32 v27, v27, v160, s5
	v_add3_u32 v28, v28, v184, s5
	v_add3_u32 v63, v172, v186, s5
	v_add3_u32 v29, v29, v188, s5
	v_add3_u32 v156, v174, v190, s5
	v_add3_u32 v30, v30, v192, s5
	v_add3_u32 v158, v176, v194, s5
	v_add3_u32 v11, v11, v196, s5
	v_add3_u32 v51, v51, v198, s5
	v_add3_u32 v36, v36, v205, s5
	v_add3_u32 v160, v178, v207, s5
	v_add3_u32 v37, v37, v209, s5
	v_add3_u32 v162, v180, v211, s5
	v_add3_u32 v38, v38, v213, s5
	v_add3_u32 v164, v182, v215, s5
	v_add3_u32 v13, v13, v217, s5
	v_and_or_b32 v16, v19, s6, v18
	v_and_or_b32 v18, v39, s6, v35
	v_and_or_b32 v19, v41, s6, v40
	v_and_or_b32 v20, v43, s6, v42
	v_lshrrev_b32_e32 v35, 16, v47
	v_lshrrev_b32_e32 v39, 16, v53
	v_lshrrev_b32_e32 v40, 16, v54
	v_lshrrev_b32_e32 v22, 16, v22
	v_lshrrev_b32_e32 v41, 16, v60
	v_lshrrev_b32_e32 v8, 16, v8
	v_lshrrev_b32_e32 v23, 16, v23
	v_lshrrev_b32_e32 v42, 16, v48
	v_lshrrev_b32_e32 v43, 16, v62
	v_lshrrev_b32_e32 v44, 16, v49
	v_lshrrev_b32_e32 v46, 16, v155
	v_lshrrev_b32_e32 v47, 16, v50
	v_lshrrev_b32_e32 v48, 16, v157
	v_lshrrev_b32_e32 v10, 16, v10
	v_lshrrev_b32_e32 v31, 16, v31
	v_lshrrev_b32_e32 v32, 16, v32
	v_lshrrev_b32_e32 v49, 16, v159
	v_lshrrev_b32_e32 v33, 16, v33
	v_lshrrev_b32_e32 v50, 16, v161
	v_lshrrev_b32_e32 v34, 16, v34
	v_lshrrev_b32_e32 v53, 16, v163
	v_lshrrev_b32_e32 v12, 16, v12
	ds_write2_b32 v4, v14, v15 offset1:68
	ds_write2_b32 v4, v16, v17 offset0:136 offset1:204
	ds_write2_b32 v56, v18, v19 offset0:16 offset1:84
	ds_write2_b32 v56, v20, v0 offset0:152 offset1:220
	v_and_or_b32 v0, v45, s6, v1
	v_and_or_b32 v1, v24, s6, v21
	v_and_or_b32 v4, v52, s6, v35
	v_and_or_b32 v14, v25, s6, v39
	v_and_or_b32 v15, v55, s6, v40
	v_and_or_b32 v16, v26, s6, v22
	v_and_or_b32 v17, v61, s6, v41
	v_and_or_b32 v8, v9, s6, v8
	v_and_or_b32 v9, v27, s6, v23
	v_and_or_b32 v18, v28, s6, v42
	v_and_or_b32 v19, v63, s6, v43
	v_and_or_b32 v20, v29, s6, v44
	v_and_or_b32 v21, v156, s6, v46
	v_and_or_b32 v22, v30, s6, v47
	v_and_or_b32 v23, v158, s6, v48
	v_and_or_b32 v10, v11, s6, v10
	v_and_or_b32 v11, v51, s6, v31
	v_and_or_b32 v24, v36, s6, v32
	v_and_or_b32 v25, v160, s6, v49
	v_and_or_b32 v26, v37, s6, v33
	v_and_or_b32 v27, v162, s6, v50
	v_and_or_b32 v28, v38, s6, v34
	v_and_or_b32 v29, v164, s6, v53
	v_and_or_b32 v12, v13, s6, v12
	ds_write2_b32 v5, v0, v1 offset1:68
	ds_write2_b32 v5, v4, v14 offset0:136 offset1:204
	ds_write2_b32 v57, v15, v16 offset0:16 offset1:84
	ds_write2_b32 v57, v17, v8 offset0:152 offset1:220
	ds_write2_b32 v6, v9, v18 offset1:68
	ds_write2_b32 v6, v19, v20 offset0:136 offset1:204
	ds_write2_b32 v58, v21, v22 offset0:16 offset1:84
	ds_write2_b32 v58, v23, v10 offset0:152 offset1:220
	ds_write2_b32 v7, v11, v24 offset1:68
	ds_write2_b32 v7, v25, v26 offset0:136 offset1:204
	ds_write2_b32 v59, v27, v28 offset0:16 offset1:84
	ds_write2_b32 v59, v29, v12 offset0:152 offset1:220
	s_cbranch_scc1 .LBB0_1051
	s_waitcnt lgkmcnt(0)
	global_load_dwordx4 v[4:7], v[68:69], off nt
	ds_read_b128 v[20:23], v154
	ds_read_b128 v[28:31], v154 offset:1088
	global_load_dwordx4 v[156:159], v[68:69], off offset:64 nt
	ds_read_b128 v[48:51], v154 offset:64
	ds_read_b128 v[12:15], v154 offset:8704
	ds_read_b128 v[32:35], v154 offset:1152
	global_load_dwordx4 v[24:27], v[70:71], off nt
	ds_read_b128 v[8:11], v154 offset:8768
	ds_read_b128 v[16:19], v154 offset:9792
	ds_read_b128 v[0:3], v154 offset:9856
	s_lshl_b32 s11, s7, 4
	s_and_b32 s12, s11, 0xffffff80
	v_or_b32_e32 v222, s12, v139
	global_load_dwordx4 v[206:209], v[76:77], off nt
	v_ashrrev_i32_e32 v223, 31, v222
	s_add_i32 s7, s7, s36
	s_add_i32 s2, s2, s3
	s_cmpk_gt_i32 s7, 0xff
	s_waitcnt vmcnt(3) lgkmcnt(7)
	v_mfma_f32_16x16x32_bf16 v[36:39], v[20:23], v[4:7], 0
	s_waitcnt lgkmcnt(6)
	v_mfma_f32_16x16x32_bf16 v[160:163], v[28:31], v[4:7], 0
	s_waitcnt lgkmcnt(4)
	v_mfma_f32_16x16x32_bf16 v[164:167], v[12:15], v[4:7], 0
	s_waitcnt lgkmcnt(1)
	v_mfma_f32_16x16x32_bf16 v[168:171], v[16:19], v[4:7], 0
	global_load_dwordx4 v[4:7], v[72:73], off nt
	s_waitcnt vmcnt(2)
	v_mfma_f32_16x16x32_bf16 v[172:175], v[20:23], v[24:27], 0
	v_mfma_f32_16x16x32_bf16 v[176:179], v[28:31], v[24:27], 0
	v_mfma_f32_16x16x32_bf16 v[180:183], v[12:15], v[24:27], 0
	v_mfma_f32_16x16x32_bf16 v[184:187], v[16:19], v[24:27], 0
	global_load_dwordx4 v[24:27], v[74:75], off nt
	v_mfma_f32_16x16x32_bf16 v[210:213], v[48:51], v[156:159], v[36:39]
	v_mfma_f32_16x16x32_bf16 v[160:163], v[32:35], v[156:159], v[160:163]
	v_mfma_f32_16x16x32_bf16 v[164:167], v[8:11], v[156:159], v[164:167]
	s_waitcnt lgkmcnt(0)
; __device__ __forceinline__ unsigned pk2(float lo, float hi) { return f2bf(lo) | (f2bf(hi) << 16); }
; template <int HF>
; __device__ __forceinline__ void gmlp_half(LAS unsigned char* wl, const bf16* PROJ, const bf16* wsg, const float* norm_v, const float* b_s, bf16* Y, int tok0, int g, int fr, int fq) {
;     ...
;         for (int nt = 0; nt < 4; ++nt)
; #pragma unroll
;             for (int mi = 0; mi < 4; ++mi) acc[mi][nt] = __builtin_amdgcn_mfma_f32_16x16x32_bf16(av[mi], bw[ki][nt], acc[mi][nt], 0, 0, 0);
;     }
;     asm volatile("" ::: "memory");
;     f32x4 nv[2][2];
; #pragma unroll
;     for (int p = 0; p < 2; ++p) { nv[p][0] = *(const f32x4*)(norm_v + g * 64 + 32 * p + 8 * fq); nv[p][1] = *(const f32x4*)(norm_v + g * 64 + 32 * p + 8 * fq + 4); }
; #pragma unroll
;     for (int nt = 0; nt < 4; ++nt) {
;         const int t = 64 * HF + 16 * nt + fr; const size_t tok = (size_t)(tok0 + t); const float bs = b_s[g * 128 + t];
;         u32x4 uu[2];
; #pragma unroll
;         for (int p = 0; p < 2; ++p) uu[p] = *(const u32x4*)(PROJ + tok * NPROJ + g * 64 + 32 * p + 8 * fq);
; #pragma unroll
;         for (int p = 0; p < 2; ++p) {
;             u32x4 w;
; #pragma unroll
;             for (int e2 = 0; e2 < 2; ++e2) {
;                 const f32x4 z = nv[p][e2] * acc[2 * p + e2][nt] + bs;
;                 const unsigned u0 = uu[p][2 * e2], u1 = uu[p][2 * e2 + 1];
;                 w[2 * e2] = pk2(bf_lo(u0) * z[0], bf_hi(u0) * z[1]); w[2 * e2 + 1] = pk2(bf_lo(u1) * z[2], bf_hi(u1) * z[3]);
;             }
;             *(u32x4*)(Y + tok * D + g * 64 + 32 * p + 8 * fq) = w;
	v_mfma_f32_16x16x32_bf16 v[156:159], v[0:3], v[156:159], v[168:171]
	s_waitcnt vmcnt(2)
	v_mfma_f32_16x16x32_bf16 v[168:171], v[48:51], v[206:209], v[172:175]
	v_mfma_f32_16x16x32_bf16 v[172:175], v[32:35], v[206:209], v[176:179]
	v_mfma_f32_16x16x32_bf16 v[176:179], v[8:11], v[206:209], v[180:183]
	v_mfma_f32_16x16x32_bf16 v[180:183], v[0:3], v[206:209], v[184:187]
	s_waitcnt vmcnt(1)
	v_mfma_f32_16x16x32_bf16 v[188:191], v[20:23], v[4:7], 0
	v_mfma_f32_16x16x32_bf16 v[192:195], v[28:31], v[4:7], 0
	v_mfma_f32_16x16x32_bf16 v[196:199], v[12:15], v[4:7], 0
	v_mfma_f32_16x16x32_bf16 v[52:55], v[16:19], v[4:7], 0
	global_load_dwordx4 v[60:63], v[78:79], off nt
	global_load_dwordx4 v[4:7], v[80:81], off nt
	s_waitcnt vmcnt(2)
	v_mfma_f32_16x16x32_bf16 v[56:59], v[20:23], v[24:27], 0
	v_mad_i64_i32 v[20:21], s[20:21], v222, s4, v[82:83]
	global_load_dwordx4 v[214:217], v[20:21], off nt
	global_load_dwordx4 v[44:47], v[118:119], off offset:2048 nt
	global_load_dword v224, v[120:121], off
	v_mfma_f32_16x16x32_bf16 v[40:43], v[28:31], v[24:27], 0
	global_load_dwordx4 v[36:39], v[118:119], off offset:2064 nt
	global_load_dwordx4 v[28:31], v[118:119], off offset:2176 nt
	global_load_dwordx4 v[218:221], v[20:21], off offset:64 nt
	v_lshlrev_b64 v[222:223], 11, v[222:223]
	global_load_dwordx4 v[20:23], v[118:119], off offset:2192 nt
	v_lshl_add_u64 v[222:223], v[84:85], 0, v[222:223]
	v_mfma_f32_16x16x32_bf16 v[12:15], v[12:15], v[24:27], 0
	s_waitcnt vmcnt(6)
	v_lshlrev_b32_e32 v227, 16, v215
	v_lshlrev_b32_e32 v226, 16, v214
	s_waitcnt vmcnt(4)
	v_pk_fma_f32 v[184:185], v[212:213], v[46:47], v[224:225] op_sel_hi:[1,1,0]
	v_pk_fma_f32 v[186:187], v[210:211], v[44:45], v[224:225] op_sel_hi:[1,1,0]
	s_waitcnt vmcnt(3)
	v_pk_fma_f32 v[162:163], v[162:163], v[38:39], v[224:225] op_sel_hi:[1,1,0]
	v_pk_fma_f32 v[160:161], v[160:161], v[36:37], v[224:225] op_sel_hi:[1,1,0]
	v_lshlrev_b32_e32 v229, 16, v217
	v_lshlrev_b32_e32 v228, 16, v216
	v_and_b32_e32 v217, 0xffff0000, v217
	v_and_b32_e32 v216, 0xffff0000, v216
	v_mov_b32_e32 v206, v186
	v_mov_b32_e32 v207, v184
	v_mov_b32_e32 v184, v187
	v_mov_b32_e32 v186, v160
	v_mov_b32_e32 v187, v162
	v_mov_b32_e32 v162, v161
	v_and_b32_e32 v215, 0xffff0000, v215
	v_and_b32_e32 v214, 0xffff0000, v214
	v_pk_mul_f32 v[160:161], v[206:207], v[226:227]
	v_pk_mul_f32 v[186:187], v[186:187], v[228:229]
	v_pk_mul_f32 v[162:163], v[162:163], v[216:217]
	v_pk_mul_f32 v[184:185], v[184:185], v[214:215]
	v_bfe_u32 v155, v163, 16, 1
	v_bfe_u32 v208, v160, 16, 1
	v_bfe_u32 v209, v161, 16, 1
	v_bfe_u32 v210, v186, 16, 1
	v_bfe_u32 v211, v187, 16, 1
	v_bfe_u32 v205, v162, 16, 1
	v_bfe_u32 v206, v185, 16, 1
	v_bfe_u32 v207, v184, 16, 1
	v_add3_u32 v155, v163, v155, s5
	v_add3_u32 v163, v187, v211, s5
	v_add3_u32 v186, v186, v210, s5
	v_add3_u32 v161, v161, v209, s5
	v_add3_u32 v160, v160, v208, s5
	v_add3_u32 v184, v184, v207, s5
	v_add3_u32 v185, v185, v206, s5
	v_add3_u32 v162, v162, v205, s5
	v_lshrrev_b32_e32 v160, 16, v160
	v_lshrrev_b32_e32 v161, 16, v161
	v_lshrrev_b32_e32 v186, 16, v186
	v_lshrrev_b32_e32 v163, 16, v163
	v_and_or_b32 v163, v155, s6, v163
	v_and_or_b32 v162, v162, s6, v186
	v_and_or_b32 v161, v185, s6, v161
	v_and_or_b32 v160, v184, s6, v160
	global_store_dwordx4 v[222:223], v[160:163], off
	s_waitcnt vmcnt(1)
	v_pk_fma_f32 v[158:159], v[158:159], v[22:23], v[224:225] op_sel_hi:[1,1,0]
	v_pk_fma_f32 v[156:157], v[156:157], v[20:21], v[224:225] op_sel_hi:[1,1,0]
	v_pk_fma_f32 v[160:161], v[166:167], v[30:31], v[224:225] op_sel_hi:[1,1,0]
	v_pk_fma_f32 v[162:163], v[164:165], v[28:29], v[224:225] op_sel_hi:[1,1,0]
	v_lshlrev_b32_e32 v165, 16, v219
	v_lshlrev_b32_e32 v164, 16, v218
	v_mov_b32_e32 v166, v162
	v_mov_b32_e32 v167, v160
	v_pk_mul_f32 v[164:165], v[166:167], v[164:165]
	v_and_b32_e32 v167, 0xffff0000, v219
	v_and_b32_e32 v166, 0xffff0000, v218
	v_mov_b32_e32 v160, v163
	v_pk_mul_f32 v[160:161], v[160:161], v[166:167]
	v_lshlrev_b32_e32 v163, 16, v221
	v_lshlrev_b32_e32 v162, 16, v220
	v_mov_b32_e32 v166, v156
	v_mov_b32_e32 v167, v158
	v_pk_mul_f32 v[162:163], v[166:167], v[162:163]
	v_and_b32_e32 v167, 0xffff0000, v221
	v_and_b32_e32 v166, 0xffff0000, v220
	v_mov_b32_e32 v158, v157
	v_pk_mul_f32 v[156:157], v[158:159], v[166:167]
	v_bfe_u32 v159, v161, 16, 1
	v_bfe_u32 v155, v157, 16, 1
	v_bfe_u32 v158, v156, 16, 1
	v_bfe_u32 v166, v160, 16, 1
	v_add3_u32 v160, v160, v166, s5
	v_add3_u32 v161, v161, v159, s5
	v_add3_u32 v156, v156, v158, s5
	v_add3_u32 v155, v157, v155, s5
	v_bfe_u32 v157, v164, 16, 1
	v_bfe_u32 v158, v165, 16, 1
	v_bfe_u32 v159, v162, 16, 1
	v_bfe_u32 v166, v163, 16, 1
	v_add3_u32 v163, v163, v166, s5
	v_add3_u32 v159, v162, v159, s5
	v_add3_u32 v158, v165, v158, s5
	v_add3_u32 v157, v164, v157, s5
	v_lshrrev_b32_e32 v162, 16, v157
	v_lshrrev_b32_e32 v157, 16, v158
	v_lshrrev_b32_e32 v158, 16, v159
	v_lshrrev_b32_e32 v159, 16, v163
	v_and_or_b32 v159, v155, s6, v159
	v_and_or_b32 v158, v156, s6, v158
	v_and_or_b32 v157, v161, s6, v157
	v_and_or_b32 v156, v160, s6, v162
	global_store_dwordx4 v[222:223], v[156:159], off offset:64
	v_or_b32_e32 v206, s12, v142
	global_load_dword v208, v[122:123], off
	v_mad_i64_i32 v[164:165], s[20:21], v206, s4, v[82:83]
	global_load_dwordx4 v[156:159], v[164:165], off nt
	v_ashrrev_i32_e32 v207, 31, v206
	global_load_dwordx4 v[164:167], v[164:165], off offset:64 nt
	v_mfma_f32_16x16x32_bf16 v[160:163], v[48:51], v[60:63], v[188:191]
	v_or_b32_e32 v218, s12, v145
	v_ashrrev_i32_e32 v219, 31, v218
	s_waitcnt vmcnt(2)
; __device__ __forceinline__ unsigned pk2(float lo, float hi) { return f2bf(lo) | (f2bf(hi) << 16); }
; template <int HF>
; __device__ __forceinline__ void gmlp_half(LAS unsigned char* wl, const bf16* PROJ, const bf16* wsg, const float* norm_v, const float* b_s, bf16* Y, int tok0, int g, int fr, int fq) {
;     ...
;     for (int nt = 0; nt < 4; ++nt) {
;         const int t = 64 * HF + 16 * nt + fr; const size_t tok = (size_t)(tok0 + t); const float bs = b_s[g * 128 + t];
;         u32x4 uu[2];
; #pragma unroll
;         for (int p = 0; p < 2; ++p) uu[p] = *(const u32x4*)(PROJ + tok * NPROJ + g * 64 + 32 * p + 8 * fq);
; #pragma unroll
;         for (int p = 0; p < 2; ++p) {
;             u32x4 w;
; #pragma unroll
;             for (int e2 = 0; e2 < 2; ++e2) {
;                 const f32x4 z = nv[p][e2] * acc[2 * p + e2][nt] + bs;
;                 const unsigned u0 = uu[p][2 * e2], u1 = uu[p][2 * e2 + 1];
;                 w[2 * e2] = pk2(bf_lo(u0) * z[0], bf_hi(u0) * z[1]); w[2 * e2 + 1] = pk2(bf_lo(u1) * z[2], bf_hi(u1) * z[3]);
;             }
;             *(u32x4*)(Y + tok * D + g * 64 + 32 * p + 8 * fq) = w;
	v_pk_fma_f32 v[170:171], v[170:171], v[46:47], v[208:209] op_sel_hi:[1,1,0]
	v_lshlrev_b64 v[188:189], 11, v[206:207]
	v_pk_fma_f32 v[168:169], v[168:169], v[44:45], v[208:209] op_sel_hi:[1,1,0]
	v_pk_fma_f32 v[174:175], v[174:175], v[38:39], v[208:209] op_sel_hi:[1,1,0]
	v_pk_fma_f32 v[172:173], v[172:173], v[36:37], v[208:209] op_sel_hi:[1,1,0]
	v_mfma_f32_16x16x32_bf16 v[184:187], v[32:35], v[60:63], v[192:195]
	s_nop 2
	v_lshl_add_u64 v[192:193], v[84:85], 0, v[188:189]
	v_mfma_f32_16x16x32_bf16 v[188:191], v[8:11], v[60:63], v[196:199]
	s_waitcnt vmcnt(1)
	v_lshlrev_b32_e32 v195, 16, v157
	v_lshlrev_b32_e32 v194, 16, v156
	v_and_b32_e32 v157, 0xffff0000, v157
	v_and_b32_e32 v156, 0xffff0000, v156
	v_lshlrev_b32_e32 v197, 16, v159
	v_lshlrev_b32_e32 v196, 16, v158
	v_and_b32_e32 v159, 0xffff0000, v159
	v_mov_b32_e32 v199, v170
	v_mov_b32_e32 v170, v169
	v_mov_b32_e32 v169, v174
	v_and_b32_e32 v158, 0xffff0000, v158
	v_mov_b32_e32 v174, v173
	v_mov_b32_e32 v198, v168
	v_mov_b32_e32 v168, v172
	v_pk_mul_f32 v[156:157], v[170:171], v[156:157]
	v_pk_mul_f32 v[158:159], v[174:175], v[158:159]
	v_pk_mul_f32 v[194:195], v[198:199], v[194:195]
	v_pk_mul_f32 v[168:169], v[168:169], v[196:197]
	v_bfe_u32 v155, v159, 16, 1
	v_bfe_u32 v170, v158, 16, 1
	v_bfe_u32 v171, v157, 16, 1
	v_bfe_u32 v172, v156, 16, 1
	v_add3_u32 v156, v156, v172, s5
	v_add3_u32 v157, v157, v171, s5
	v_add3_u32 v158, v158, v170, s5
	v_add3_u32 v155, v159, v155, s5
	v_bfe_u32 v159, v194, 16, 1
	v_bfe_u32 v170, v195, 16, 1
	v_bfe_u32 v171, v168, 16, 1
	v_bfe_u32 v172, v169, 16, 1
	v_add3_u32 v169, v169, v172, s5
	v_add3_u32 v168, v168, v171, s5
	v_add3_u32 v170, v195, v170, s5
	v_add3_u32 v159, v194, v159, s5
	v_lshrrev_b32_e32 v171, 16, v159
	v_lshrrev_b32_e32 v170, 16, v170
	v_lshrrev_b32_e32 v168, 16, v168
	v_lshrrev_b32_e32 v159, 16, v169
	v_and_or_b32 v159, v155, s6, v159
	v_and_or_b32 v158, v158, s6, v168
	v_and_or_b32 v157, v157, s6, v170
	v_and_or_b32 v156, v156, s6, v171
	global_store_dwordx4 v[192:193], v[156:159], off
	s_waitcnt vmcnt(1)
	v_lshlrev_b32_e32 v169, 16, v165
	v_lshlrev_b32_e32 v168, 16, v164
	v_pk_fma_f32 v[156:157], v[178:179], v[30:31], v[208:209] op_sel_hi:[1,1,0]
	v_pk_fma_f32 v[158:159], v[176:177], v[28:29], v[208:209] op_sel_hi:[1,1,0]
	v_mov_b32_e32 v171, v156
	v_and_b32_e32 v165, 0xffff0000, v165
	v_and_b32_e32 v164, 0xffff0000, v164
	v_mov_b32_e32 v156, v159
	v_mov_b32_e32 v170, v158
	v_pk_mul_f32 v[156:157], v[156:157], v[164:165]
	v_pk_fma_f32 v[158:159], v[182:183], v[22:23], v[208:209] op_sel_hi:[1,1,0]
	v_pk_fma_f32 v[164:165], v[180:181], v[20:21], v[208:209] op_sel_hi:[1,1,0]
	v_pk_mul_f32 v[168:169], v[170:171], v[168:169]
	v_lshlrev_b32_e32 v171, 16, v167
	v_lshlrev_b32_e32 v170, 16, v166
	v_mov_b32_e32 v173, v158
	v_and_b32_e32 v167, 0xffff0000, v167
	v_and_b32_e32 v166, 0xffff0000, v166
	v_mov_b32_e32 v158, v165
	v_mov_b32_e32 v172, v164
	v_pk_mul_f32 v[158:159], v[158:159], v[166:167]
	v_pk_mul_f32 v[170:171], v[172:173], v[170:171]
	v_bfe_u32 v155, v159, 16, 1
	v_bfe_u32 v164, v158, 16, 1
	v_bfe_u32 v165, v157, 16, 1
	v_bfe_u32 v166, v156, 16, 1
	v_add3_u32 v156, v156, v166, s5
	v_add3_u32 v157, v157, v165, s5
	v_add3_u32 v158, v158, v164, s5
	v_add3_u32 v155, v159, v155, s5
	v_bfe_u32 v159, v168, 16, 1
	v_bfe_u32 v164, v169, 16, 1
	v_bfe_u32 v165, v170, 16, 1
	v_bfe_u32 v166, v171, 16, 1
	v_add3_u32 v166, v171, v166, s5
	v_add3_u32 v165, v170, v165, s5
	v_add3_u32 v164, v169, v164, s5
	v_add3_u32 v159, v168, v159, s5
	v_lshrrev_b32_e32 v167, 16, v159
	v_lshrrev_b32_e32 v164, 16, v164
	v_lshrrev_b32_e32 v165, 16, v165
	v_lshrrev_b32_e32 v159, 16, v166
	v_and_or_b32 v159, v155, s6, v159
	v_and_or_b32 v158, v158, s6, v165
	v_and_or_b32 v157, v157, s6, v164
	v_and_or_b32 v156, v156, s6, v167
	global_store_dwordx4 v[192:193], v[156:159], off offset:64
	v_or_b32_e32 v164, s12, v143
	global_load_dword v166, v[124:125], off
	v_mad_i64_i32 v[168:169], s[20:21], v164, s4, v[82:83]
	global_load_dwordx4 v[156:159], v[168:169], off nt
	v_mfma_f32_16x16x32_bf16 v[52:55], v[0:3], v[60:63], v[52:55]
	global_load_dwordx4 v[60:63], v[168:169], off offset:64 nt
	v_ashrrev_i32_e32 v165, 31, v164
	v_mfma_f32_16x16x32_bf16 v[48:51], v[48:51], v[4:7], v[56:59]
	s_nop 2
	v_lshlrev_b64 v[56:57], 11, v[164:165]
	v_lshl_add_u64 v[164:165], v[84:85], 0, v[56:57]
	v_mfma_f32_16x16x32_bf16 v[32:35], v[32:35], v[4:7], v[40:43]
	s_waitcnt vmcnt(2)
	v_pk_fma_f32 v[56:57], v[162:163], v[46:47], v[166:167] op_sel_hi:[1,1,0]
	v_pk_fma_f32 v[58:59], v[160:161], v[44:45], v[166:167] op_sel_hi:[1,1,0]
	v_mov_b32_e32 v163, v56
	s_waitcnt vmcnt(1)
	v_lshlrev_b32_e32 v161, 16, v157
	v_lshlrev_b32_e32 v160, 16, v156
	v_and_b32_e32 v157, 0xffff0000, v157
	v_and_b32_e32 v156, 0xffff0000, v156
	v_mov_b32_e32 v56, v59
	v_mov_b32_e32 v162, v58
	v_pk_mul_f32 v[56:57], v[56:57], v[156:157]
	v_pk_fma_f32 v[58:59], v[186:187], v[38:39], v[166:167] op_sel_hi:[1,1,0]
	v_pk_fma_f32 v[156:157], v[184:185], v[36:37], v[166:167] op_sel_hi:[1,1,0]
	v_pk_mul_f32 v[160:161], v[162:163], v[160:161]
	v_lshlrev_b32_e32 v163, 16, v159
	v_lshlrev_b32_e32 v162, 16, v158
	v_mov_b32_e32 v169, v58
	v_and_b32_e32 v159, 0xffff0000, v159
	v_and_b32_e32 v158, 0xffff0000, v158
	v_mov_b32_e32 v58, v157
	v_mov_b32_e32 v168, v156
	v_pk_mul_f32 v[58:59], v[58:59], v[158:159]
	v_pk_mul_f32 v[162:163], v[168:169], v[162:163]
	v_bfe_u32 v155, v59, 16, 1
	v_bfe_u32 v156, v58, 16, 1
	v_bfe_u32 v157, v57, 16, 1
	v_bfe_u32 v158, v56, 16, 1
	v_add3_u32 v56, v56, v158, s5
	v_add3_u32 v57, v57, v157, s5
	v_add3_u32 v58, v58, v156, s5
	v_add3_u32 v59, v59, v155, s5
	v_bfe_u32 v155, v160, 16, 1
	v_bfe_u32 v156, v161, 16, 1
	v_bfe_u32 v157, v162, 16, 1
	v_bfe_u32 v158, v163, 16, 1
	v_add3_u32 v158, v163, v158, s5
	v_add3_u32 v157, v162, v157, s5
	v_add3_u32 v156, v161, v156, s5
	v_add3_u32 v155, v160, v155, s5
	v_lshrrev_b32_e32 v155, 16, v155
	v_lshrrev_b32_e32 v156, 16, v156
	v_lshrrev_b32_e32 v157, 16, v157
	v_lshrrev_b32_e32 v158, 16, v158
	v_and_or_b32 v59, v59, s6, v158
	v_and_or_b32 v58, v58, s6, v157
	v_and_or_b32 v57, v57, s6, v156
	v_and_or_b32 v56, v56, s6, v155
	global_store_dwordx4 v[164:165], v[56:59], off
	s_waitcnt vmcnt(1)
; #define LAS __attribute__((address_space(3)))
; __device__ __forceinline__ unsigned pk2(float lo, float hi) { return f2bf(lo) | (f2bf(hi) << 16); }
; template <int HF>
; __device__ __forceinline__ void gmlp_half(LAS unsigned char* wl, const bf16* PROJ, const bf16* wsg, const float* norm_v, const float* b_s, bf16* Y, int tok0, int g, int fr, int fq) {
;     ...
;         for (int nt = 0; nt < 4; ++nt) bw[ki][nt] = *(const bf16x8*)(wsg + (size_t)(64 * HF + 16 * nt + fr) * 128 + 32 * ki + 8 * fq);
;     f32x4 acc[4][4];
; #pragma unroll
;     for (int i = 0; i < 4; ++i)
; #pragma unroll
;         for (int j = 0; j < 4; ++j) acc[i][j] = (f32x4){0.f, 0.f, 0.f, 0.f};
; #pragma unroll
;     for (int ki = 0; ki < NK; ++ki) {
;         bf16x8 av[4];
; #pragma unroll
;         for (int mi = 0; mi < 4; ++mi) av[mi] = *(const LAS bf16x8*)(wl + ((32 * (mi >> 1) + 8 * (fr >> 2) + 4 * (mi & 1) + (fr & 3)) * VS + 32 * ki + 8 * fq) * 2);
; #pragma unroll
;         for (int nt = 0; nt < 4; ++nt)
; #pragma unroll
;             for (int mi = 0; mi < 4; ++mi) acc[mi][nt] = __builtin_amdgcn_mfma_f32_16x16x32_bf16(av[mi], bw[ki][nt], acc[mi][nt], 0, 0, 0);
;     ...
;     for (int nt = 0; nt < 4; ++nt) {
;         const int t = 64 * HF + 16 * nt + fr; const size_t tok = (size_t)(tok0 + t); const float bs = b_s[g * 128 + t];
;         u32x4 uu[2];
; #pragma unroll
;         for (int p = 0; p < 2; ++p) uu[p] = *(const u32x4*)(PROJ + tok * NPROJ + g * 64 + 32 * p + 8 * fq);
; #pragma unroll
;         for (int p = 0; p < 2; ++p) {
;             u32x4 w;
; #pragma unroll
;             for (int e2 = 0; e2 < 2; ++e2) {
;                 const f32x4 z = nv[p][e2] * acc[2 * p + e2][nt] + bs;
;                 const unsigned u0 = uu[p][2 * e2], u1 = uu[p][2 * e2 + 1];
;                 w[2 * e2] = pk2(bf_lo(u0) * z[0], bf_hi(u0) * z[1]); w[2 * e2 + 1] = pk2(bf_lo(u1) * z[2], bf_hi(u1) * z[3]);
;             }
;             *(u32x4*)(Y + tok * D + g * 64 + 32 * p + 8 * fq) = w;
	v_lshlrev_b32_e32 v157, 16, v61
	v_lshlrev_b32_e32 v156, 16, v60
	v_pk_fma_f32 v[56:57], v[190:191], v[30:31], v[166:167] op_sel_hi:[1,1,0]
	v_pk_fma_f32 v[58:59], v[188:189], v[28:29], v[166:167] op_sel_hi:[1,1,0]
	v_mov_b32_e32 v159, v56
	v_and_b32_e32 v61, 0xffff0000, v61
	v_and_b32_e32 v60, 0xffff0000, v60
	v_mov_b32_e32 v56, v59
	v_pk_fma_f32 v[54:55], v[54:55], v[22:23], v[166:167] op_sel_hi:[1,1,0]
	v_pk_fma_f32 v[52:53], v[52:53], v[20:21], v[166:167] op_sel_hi:[1,1,0]
	v_mov_b32_e32 v158, v58
	v_pk_mul_f32 v[56:57], v[56:57], v[60:61]
	v_lshlrev_b32_e32 v59, 16, v63
	v_lshlrev_b32_e32 v58, 16, v62
	v_mov_b32_e32 v60, v52
	v_mov_b32_e32 v61, v54
	v_pk_mul_f32 v[58:59], v[60:61], v[58:59]
	v_and_b32_e32 v61, 0xffff0000, v63
	v_and_b32_e32 v60, 0xffff0000, v62
	v_mov_b32_e32 v54, v53
	v_pk_mul_f32 v[52:53], v[54:55], v[60:61]
	v_pk_mul_f32 v[156:157], v[158:159], v[156:157]
	v_bfe_u32 v54, v53, 16, 1
	v_bfe_u32 v55, v52, 16, 1
	v_bfe_u32 v60, v57, 16, 1
	v_bfe_u32 v61, v56, 16, 1
	v_add3_u32 v56, v56, v61, s5
	v_add3_u32 v57, v57, v60, s5
	v_add3_u32 v52, v52, v55, s5
	v_add3_u32 v53, v53, v54, s5
	v_bfe_u32 v54, v156, 16, 1
	v_bfe_u32 v55, v157, 16, 1
	v_bfe_u32 v60, v58, 16, 1
	v_bfe_u32 v61, v59, 16, 1
	v_add3_u32 v59, v59, v61, s5
	v_add3_u32 v58, v58, v60, s5
	v_add3_u32 v55, v157, v55, s5
	v_add3_u32 v54, v156, v54, s5
	v_lshrrev_b32_e32 v60, 16, v54
	v_lshrrev_b32_e32 v61, 16, v55
	v_lshrrev_b32_e32 v54, 16, v58
	v_lshrrev_b32_e32 v55, 16, v59
	v_and_or_b32 v55, v53, s6, v55
	v_and_or_b32 v54, v52, s6, v54
	v_and_or_b32 v53, v57, s6, v61
	v_and_or_b32 v52, v56, s6, v60
	global_store_dwordx4 v[164:165], v[52:55], off offset:64
	v_or_b32_e32 v56, s12, v202
	global_load_dword v160, v[126:127], off
	v_mad_i64_i32 v[58:59], s[20:21], v56, s4, v[82:83]
	global_load_dwordx4 v[52:55], v[58:59], off nt
	global_load_dwordx4 v[40:43], v[58:59], off offset:64 nt
	v_ashrrev_i32_e32 v57, 31, v56
	v_lshlrev_b64 v[56:57], 11, v[56:57]
	v_lshl_add_u64 v[180:181], v[84:85], 0, v[56:57]
	v_mfma_f32_16x16x32_bf16 v[16:19], v[16:19], v[24:27], 0
	s_waitcnt vmcnt(2)
	v_pk_fma_f32 v[46:47], v[50:51], v[46:47], v[160:161] op_sel_hi:[1,1,0]
	v_pk_fma_f32 v[44:45], v[48:49], v[44:45], v[160:161] op_sel_hi:[1,1,0]
	v_pk_fma_f32 v[34:35], v[34:35], v[38:39], v[160:161] op_sel_hi:[1,1,0]
	v_pk_fma_f32 v[32:33], v[32:33], v[36:37], v[160:161] op_sel_hi:[1,1,0]
	s_waitcnt vmcnt(1)
	v_lshlrev_b32_e32 v49, 16, v53
	v_lshlrev_b32_e32 v48, 16, v52
	v_mov_b32_e32 v50, v44
	v_mov_b32_e32 v51, v46
	v_lshlrev_b32_e32 v37, 16, v55
	v_lshlrev_b32_e32 v36, 16, v54
	v_mov_b32_e32 v38, v32
	v_mov_b32_e32 v39, v34
	v_pk_mul_f32 v[48:49], v[50:51], v[48:49]
	v_and_b32_e32 v51, 0xffff0000, v53
	v_and_b32_e32 v50, 0xffff0000, v52
	v_mov_b32_e32 v46, v45
	v_pk_mul_f32 v[36:37], v[38:39], v[36:37]
	v_and_b32_e32 v39, 0xffff0000, v55
	v_and_b32_e32 v38, 0xffff0000, v54
	v_mov_b32_e32 v34, v33
	v_pk_mul_f32 v[44:45], v[46:47], v[50:51]
	v_pk_mul_f32 v[32:33], v[34:35], v[38:39]
	v_bfe_u32 v38, v45, 16, 1
	v_bfe_u32 v34, v33, 16, 1
	v_bfe_u32 v35, v32, 16, 1
	v_bfe_u32 v39, v44, 16, 1
	v_add3_u32 v39, v44, v39, s5
	v_add3_u32 v38, v45, v38, s5
	v_add3_u32 v32, v32, v35, s5
	v_add3_u32 v33, v33, v34, s5
	v_bfe_u32 v34, v48, 16, 1
	v_bfe_u32 v35, v49, 16, 1
	v_bfe_u32 v44, v36, 16, 1
	v_bfe_u32 v45, v37, 16, 1
	v_add3_u32 v37, v37, v45, s5
	v_add3_u32 v36, v36, v44, s5
	v_add3_u32 v35, v49, v35, s5
	v_add3_u32 v34, v48, v34, s5
	v_lshrrev_b32_e32 v44, 16, v34
	v_lshrrev_b32_e32 v45, 16, v35
	v_lshrrev_b32_e32 v34, 16, v36
	v_lshrrev_b32_e32 v35, 16, v37
	v_and_or_b32 v35, v33, s6, v35
	v_and_or_b32 v34, v32, s6, v34
	v_and_or_b32 v33, v38, s6, v45
	v_and_or_b32 v32, v39, s6, v44
	global_store_dwordx4 v[180:181], v[32:35], off
	global_load_dwordx4 v[32:35], v[86:87], off nt
	s_nop 0
	global_load_dwordx4 v[36:39], v[88:89], off nt
	global_load_dwordx4 v[44:47], v[90:91], off nt
	global_load_dwordx4 v[24:27], v[92:93], off nt
	v_mfma_f32_16x16x32_bf16 v[8:11], v[8:11], v[4:7], v[12:15]
	ds_read_b128 v[48:51], v154 offset:8704
	ds_read_b128 v[52:55], v154 offset:9792
	s_nop 0
	ds_read_b128 v[12:15], v154
	ds_read_b128 v[56:59], v154 offset:64
	ds_read_b128 v[60:63], v154 offset:1088
	ds_read_b128 v[156:159], v154 offset:1152
	s_nop 0
	v_pk_fma_f32 v[8:9], v[8:9], v[28:29], v[160:161] op_sel_hi:[1,1,0]
	v_mfma_f32_16x16x32_bf16 v[0:3], v[0:3], v[4:7], v[16:19]
	v_mov_b32_e32 v28, v8
	s_nop 1
	v_pk_fma_f32 v[16:17], v[10:11], v[30:31], v[160:161] op_sel_hi:[1,1,0]
	s_waitcnt vmcnt(5)
	v_lshlrev_b32_e32 v11, 16, v41
	s_nop 1
	v_pk_fma_f32 v[162:163], v[2:3], v[22:23], v[160:161] op_sel_hi:[1,1,0]
	v_pk_fma_f32 v[160:161], v[0:1], v[20:21], v[160:161] op_sel_hi:[1,1,0]
	v_lshlrev_b32_e32 v10, 16, v40
	v_and_b32_e32 v19, 0xffff0000, v41
	v_and_b32_e32 v18, 0xffff0000, v40
	v_mov_b32_e32 v29, v16
	v_lshlrev_b32_e32 v41, 16, v43
	v_lshlrev_b32_e32 v40, 16, v42
	v_mov_b32_e32 v166, v160
	v_mov_b32_e32 v167, v162
	v_mov_b32_e32 v16, v9
	v_pk_mul_f32 v[176:177], v[28:29], v[10:11]
	v_pk_mul_f32 v[178:179], v[166:167], v[40:41]
	v_and_b32_e32 v167, 0xffff0000, v43
	v_and_b32_e32 v166, 0xffff0000, v42
	v_mov_b32_e32 v162, v161
	v_pk_mul_f32 v[164:165], v[16:17], v[18:19]
	v_pk_mul_f32 v[168:169], v[162:163], v[166:167]
	v_bfe_u32 v185, v176, 16, 1
	v_bfe_u32 v186, v177, 16, 1
	v_bfe_u32 v187, v178, 16, 1
	v_bfe_u32 v172, v179, 16, 1
	v_bfe_u32 v155, v169, 16, 1
	v_bfe_u32 v166, v168, 16, 1
	v_bfe_u32 v167, v165, 16, 1
	v_bfe_u32 v170, v164, 16, 1
	v_add3_u32 v179, v179, v172, s5
	v_add3_u32 v178, v178, v187, s5
	v_add3_u32 v177, v177, v186, s5
	v_add3_u32 v176, v176, v185, s5
	v_add3_u32 v182, v164, v170, s5
	v_add3_u32 v183, v165, v167, s5
	v_add3_u32 v184, v168, v166, s5
	v_add3_u32 v155, v169, v155, s5
	v_lshrrev_b32_e32 v176, 16, v176
	v_lshrrev_b32_e32 v177, 16, v177
	v_lshrrev_b32_e32 v178, 16, v178
	v_lshrrev_b32_e32 v179, 16, v179
	v_and_or_b32 v179, v155, s6, v179
	v_and_or_b32 v178, v184, s6, v178
	v_and_or_b32 v177, v183, s6, v177
	v_and_or_b32 v176, v182, s6, v176
	global_store_dwordx4 v[180:181], v[176:179], off offset:64
	s_waitcnt vmcnt(4) lgkmcnt(3)
; #define LAS __attribute__((address_space(3)))
; template <int HF>
; __device__ __forceinline__ void gmlp_half(LAS unsigned char* wl, const bf16* PROJ, const bf16* wsg, const float* norm_v, const float* b_s, bf16* Y, int tok0, int g, int fr, int fq) {
;     ...
;         for (int nt = 0; nt < 4; ++nt) bw[ki][nt] = *(const bf16x8*)(wsg + (size_t)(64 * HF + 16 * nt + fr) * 128 + 32 * ki + 8 * fq);
;     f32x4 acc[4][4];
; #pragma unroll
;     for (int i = 0; i < 4; ++i)
; #pragma unroll
;         for (int j = 0; j < 4; ++j) acc[i][j] = (f32x4){0.f, 0.f, 0.f, 0.f};
; #pragma unroll
;     for (int ki = 0; ki < NK; ++ki) {
;         bf16x8 av[4];
; #pragma unroll
;         for (int mi = 0; mi < 4; ++mi) av[mi] = *(const LAS bf16x8*)(wl + ((32 * (mi >> 1) + 8 * (fr >> 2) + 4 * (mi & 1) + (fr & 3)) * VS + 32 * ki + 8 * fq) * 2);
; #pragma unroll
;         for (int nt = 0; nt < 4; ++nt)
; #pragma unroll
;             for (int mi = 0; mi < 4; ++mi) acc[mi][nt] = __builtin_amdgcn_mfma_f32_16x16x32_bf16(av[mi], bw[ki][nt], acc[mi][nt], 0, 0, 0);
;     }
;     asm volatile("" ::: "memory");
;     f32x4 nv[2][2];
; #pragma unroll
;     for (int p = 0; p < 2; ++p) { nv[p][0] = *(const f32x4*)(norm_v + g * 64 + 32 * p + 8 * fq); nv[p][1] = *(const f32x4*)(norm_v + g * 64 + 32 * p + 8 * fq + 4); }
; #pragma unroll
;     for (int nt = 0; nt < 4; ++nt) {
;         const int t = 64 * HF + 16 * nt + fr; const size_t tok = (size_t)(tok0 + t); const float bs = b_s[g * 128 + t];
;         u32x4 uu[2];
; #pragma unroll
;         for (int p = 0; p < 2; ++p) uu[p] = *(const u32x4*)(PROJ + tok * NPROJ + g * 64 + 32 * p + 8 * fq);
	v_mfma_f32_16x16x32_bf16 v[4:7], v[12:15], v[32:35], 0
	global_load_dwordx4 v[176:179], v[94:95], off nt
	ds_read_b128 v[16:19], v154 offset:8768
	ds_read_b128 v[0:3], v154 offset:9856
	s_waitcnt lgkmcnt(3)
	v_mfma_f32_16x16x32_bf16 v[8:11], v[60:63], v[32:35], 0
	v_mfma_f32_16x16x32_bf16 v[28:31], v[48:51], v[32:35], 0
	v_mfma_f32_16x16x32_bf16 v[20:23], v[52:55], v[32:35], 0
	s_waitcnt vmcnt(4)
	v_mfma_f32_16x16x32_bf16 v[32:35], v[12:15], v[36:39], 0
	v_mfma_f32_16x16x32_bf16 v[40:43], v[60:63], v[36:39], 0
	v_mfma_f32_16x16x32_bf16 v[160:163], v[48:51], v[36:39], 0
	v_mfma_f32_16x16x32_bf16 v[36:39], v[52:55], v[36:39], 0
	s_waitcnt vmcnt(3)
	v_mfma_f32_16x16x32_bf16 v[164:167], v[12:15], v[44:47], 0
	v_mfma_f32_16x16x32_bf16 v[168:171], v[60:63], v[44:47], 0
	v_mfma_f32_16x16x32_bf16 v[172:175], v[48:51], v[44:47], 0
	v_mfma_f32_16x16x32_bf16 v[44:47], v[52:55], v[44:47], 0
	s_waitcnt vmcnt(2)
	v_mfma_f32_16x16x32_bf16 v[12:15], v[12:15], v[24:27], 0
	v_mfma_f32_16x16x32_bf16 v[60:63], v[60:63], v[24:27], 0
	v_mfma_f32_16x16x32_bf16 v[48:51], v[48:51], v[24:27], 0
	v_mfma_f32_16x16x32_bf16 v[24:27], v[52:55], v[24:27], 0
	global_load_dwordx4 v[52:55], v[96:97], off nt
	s_waitcnt vmcnt(1)
	v_mfma_f32_16x16x32_bf16 v[4:7], v[56:59], v[176:179], v[4:7]
	s_waitcnt lgkmcnt(2)
	v_mfma_f32_16x16x32_bf16 v[8:11], v[156:159], v[176:179], v[8:11]
	s_waitcnt lgkmcnt(1)
	v_mfma_f32_16x16x32_bf16 v[28:31], v[16:19], v[176:179], v[28:31]
	s_waitcnt lgkmcnt(0)
	v_mfma_f32_16x16x32_bf16 v[20:23], v[0:3], v[176:179], v[20:23]
	s_waitcnt vmcnt(0)
	v_mfma_f32_16x16x32_bf16 v[32:35], v[56:59], v[52:55], v[32:35]
	v_mfma_f32_16x16x32_bf16 v[176:179], v[156:159], v[52:55], v[40:43]
	v_mfma_f32_16x16x32_bf16 v[160:163], v[16:19], v[52:55], v[160:163]
	s_nop 1
	global_load_dwordx4 v[40:43], v[98:99], off nt
	v_mfma_f32_16x16x32_bf16 v[52:55], v[0:3], v[52:55], v[36:39]
	s_nop 2
	global_load_dwordx4 v[36:39], v[100:101], off nt
	s_waitcnt vmcnt(1)
	v_mfma_f32_16x16x32_bf16 v[168:171], v[156:159], v[40:43], v[168:171]
	s_waitcnt vmcnt(0)
	v_mfma_f32_16x16x32_bf16 v[60:63], v[156:159], v[36:39], v[60:63]
	global_load_dwordx4 v[156:159], v[102:103], off nt
	v_mfma_f32_16x16x32_bf16 v[164:167], v[56:59], v[40:43], v[164:167]
	v_mfma_f32_16x16x32_bf16 v[172:175], v[16:19], v[40:43], v[172:175]
	v_mfma_f32_16x16x32_bf16 v[44:47], v[0:3], v[40:43], v[44:47]
	v_mfma_f32_16x16x32_bf16 v[56:59], v[56:59], v[36:39], v[12:15]
	v_mfma_f32_16x16x32_bf16 v[16:19], v[16:19], v[36:39], v[48:51]
	s_nop 2
	global_load_dwordx4 v[48:51], v[104:105], off nt
	v_mfma_f32_16x16x32_bf16 v[0:3], v[0:3], v[36:39], v[24:27]
	s_nop 2
	ds_read_b128 v[24:27], v154 offset:128
	ds_read_b128 v[36:39], v154 offset:192
	ds_read_b128 v[180:183], v154 offset:1216
	ds_read_b128 v[40:43], v154 offset:1280
	s_waitcnt vmcnt(1) lgkmcnt(1)
	v_mfma_f32_16x16x32_bf16 v[184:187], v[180:183], v[156:159], v[8:11]
	ds_read_b128 v[188:191], v154 offset:8832
	s_nop 1
	ds_read_b128 v[8:11], v154 offset:8896
	ds_read_b128 v[192:195], v154 offset:9920
	ds_read_b128 v[12:15], v154 offset:9984
	global_load_dwordx4 v[196:199], v[108:109], off nt
	v_mfma_f32_16x16x32_bf16 v[4:7], v[24:27], v[156:159], v[4:7]
	s_waitcnt lgkmcnt(3)
	v_mfma_f32_16x16x32_bf16 v[28:31], v[188:191], v[156:159], v[28:31]
	s_waitcnt lgkmcnt(1)
	v_mfma_f32_16x16x32_bf16 v[156:159], v[192:195], v[156:159], v[20:23]
	s_nop 2
	global_load_dwordx4 v[20:23], v[106:107], off nt
	s_waitcnt vmcnt(2)
	v_mfma_f32_16x16x32_bf16 v[32:35], v[24:27], v[48:51], v[32:35]
	v_mfma_f32_16x16x32_bf16 v[176:179], v[180:183], v[48:51], v[176:179]
	v_mfma_f32_16x16x32_bf16 v[160:163], v[188:191], v[48:51], v[160:163]
	v_mfma_f32_16x16x32_bf16 v[52:55], v[192:195], v[48:51], v[52:55]
	s_waitcnt vmcnt(0)
	v_mfma_f32_16x16x32_bf16 v[164:167], v[24:27], v[20:23], v[164:167]
	v_mfma_f32_16x16x32_bf16 v[48:51], v[24:27], v[196:199], v[56:59]
	global_load_dwordx4 v[24:27], v[110:111], off nt
	v_mfma_f32_16x16x32_bf16 v[168:171], v[180:183], v[20:23], v[168:171]
	s_nop 0
	v_mad_i64_i32 v[56:57], s[20:21], v218, s4, v[82:83]
	v_mfma_f32_16x16x32_bf16 v[172:175], v[188:191], v[20:23], v[172:175]
	v_mfma_f32_16x16x32_bf16 v[206:209], v[192:195], v[20:23], v[44:47]
	v_mfma_f32_16x16x32_bf16 v[20:23], v[192:195], v[196:199], v[0:3]
	s_nop 2
	global_load_dwordx4 v[0:3], v[112:113], off nt
	v_mfma_f32_16x16x32_bf16 v[44:47], v[180:183], v[196:199], v[60:63]
	v_mfma_f32_16x16x32_bf16 v[16:19], v[188:191], v[196:199], v[16:19]
	s_waitcnt vmcnt(1)
	v_mfma_f32_16x16x32_bf16 v[188:191], v[8:11], v[24:27], v[28:31]
	global_load_dwordx4 v[196:199], v[114:115], off nt
	s_nop 1
	global_load_dwordx4 v[28:31], v[116:117], off nt
	global_load_dword v220, v[128:129], off
	s_waitcnt vmcnt(3)
	v_mfma_f32_16x16x32_bf16 v[192:195], v[36:39], v[0:3], v[32:35]
	s_nop 2
	global_load_dwordx4 v[32:35], v[118:119], off offset:2048 nt
	global_load_dwordx4 v[210:213], v[56:57], off nt
	v_mfma_f32_16x16x32_bf16 v[180:183], v[36:39], v[24:27], v[4:7]
	v_mfma_f32_16x16x32_bf16 v[184:187], v[40:43], v[24:27], v[184:187]
	s_waitcnt lgkmcnt(0)
	v_mfma_f32_16x16x32_bf16 v[156:159], v[12:15], v[24:27], v[156:159]
	global_load_dwordx4 v[24:27], v[118:119], off offset:2064 nt
	global_load_dwordx4 v[4:7], v[118:119], off offset:2176 nt
	global_load_dwordx4 v[214:217], v[56:57], off offset:64 nt
	v_mfma_f32_16x16x32_bf16 v[176:179], v[40:43], v[0:3], v[176:179]
	v_mfma_f32_16x16x32_bf16 v[160:163], v[8:11], v[0:3], v[160:163]
	v_mfma_f32_16x16x32_bf16 v[60:63], v[12:15], v[0:3], v[52:55]
	global_load_dwordx4 v[0:3], v[118:119], off offset:2192 nt
	s_waitcnt vmcnt(0)
; __device__ __forceinline__ unsigned pk2(float lo, float hi) { return f2bf(lo) | (f2bf(hi) << 16); }
; template <int HF>
; __device__ __forceinline__ void gmlp_half(LAS unsigned char* wl, const bf16* PROJ, const bf16* wsg, const float* norm_v, const float* b_s, bf16* Y, int tok0, int g, int fr, int fq) {
;     ...
;     for (int nt = 0; nt < 4; ++nt) {
;         const int t = 64 * HF + 16 * nt + fr; const size_t tok = (size_t)(tok0 + t); const float bs = b_s[g * 128 + t];
;         u32x4 uu[2];
; #pragma unroll
;         for (int p = 0; p < 2; ++p) uu[p] = *(const u32x4*)(PROJ + tok * NPROJ + g * 64 + 32 * p + 8 * fq);
; #pragma unroll
;         for (int p = 0; p < 2; ++p) {
;             u32x4 w;
; #pragma unroll
;             for (int e2 = 0; e2 < 2; ++e2) {
;                 const f32x4 z = nv[p][e2] * acc[2 * p + e2][nt] + bs;
;                 const unsigned u0 = uu[p][2 * e2], u1 = uu[p][2 * e2 + 1];
;                 w[2 * e2] = pk2(bf_lo(u0) * z[0], bf_hi(u0) * z[1]); w[2 * e2 + 1] = pk2(bf_lo(u1) * z[2], bf_hi(u1) * z[3]);
;             }
;             *(u32x4*)(Y + tok * D + g * 64 + 32 * p + 8 * fq) = w;
	v_pk_fma_f32 v[158:159], v[158:159], v[2:3], v[220:221] op_sel_hi:[1,1,0]
	v_mfma_f32_16x16x32_bf16 v[56:59], v[36:39], v[196:199], v[164:167]
	v_fma_f32 v156, v156, v0, v220
	v_fma_f32 v157, v157, v1, v220
	s_nop 0
	v_lshlrev_b64 v[164:165], 11, v[218:219]
	v_mfma_f32_16x16x32_bf16 v[52:55], v[40:43], v[196:199], v[168:171]
	v_fma_f32 v166, v180, v32, v220
	v_fma_f32 v167, v181, v33, v220
	v_mov_b32_e32 v180, v166
	v_lshl_add_u64 v[168:169], v[84:85], 0, v[164:165]
	v_pk_fma_f32 v[164:165], v[182:183], v[34:35], v[220:221] op_sel_hi:[1,1,0]
	v_lshlrev_b32_e32 v171, 16, v211
	v_lshlrev_b32_e32 v170, 16, v210
	v_mov_b32_e32 v181, v164
	v_pk_mul_f32 v[170:171], v[180:181], v[170:171]
	v_and_b32_e32 v181, 0xffff0000, v211
	v_and_b32_e32 v180, 0xffff0000, v210
	v_mov_b32_e32 v164, v167
	v_pk_mul_f32 v[164:165], v[164:165], v[180:181]
	v_pk_fma_f32 v[166:167], v[186:187], v[26:27], v[220:221] op_sel_hi:[1,1,0]
	v_pk_fma_f32 v[180:181], v[184:185], v[24:25], v[220:221] op_sel_hi:[1,1,0]
	v_lshlrev_b32_e32 v183, 16, v213
	v_lshlrev_b32_e32 v182, 16, v212
	v_mov_b32_e32 v184, v180
	v_mov_b32_e32 v185, v166
	v_pk_mul_f32 v[182:183], v[184:185], v[182:183]
	v_and_b32_e32 v185, 0xffff0000, v213
	v_and_b32_e32 v184, 0xffff0000, v212
	v_mov_b32_e32 v166, v181
	v_pk_mul_f32 v[166:167], v[166:167], v[184:185]
	v_bfe_u32 v181, v165, 16, 1
	v_bfe_u32 v155, v167, 16, 1
	v_bfe_u32 v180, v166, 16, 1
	v_bfe_u32 v184, v164, 16, 1
	v_add3_u32 v164, v164, v184, s5
	v_add3_u32 v165, v165, v181, s5
	v_add3_u32 v166, v166, v180, s5
	v_add3_u32 v155, v167, v155, s5
	v_bfe_u32 v167, v170, 16, 1
	v_bfe_u32 v180, v171, 16, 1
	v_bfe_u32 v181, v182, 16, 1
	v_bfe_u32 v184, v183, 16, 1
	v_add3_u32 v183, v183, v184, s5
	v_add3_u32 v181, v182, v181, s5
	v_add3_u32 v171, v171, v180, s5
	v_add3_u32 v167, v170, v167, s5
	v_lshrrev_b32_e32 v170, 16, v167
	v_lshrrev_b32_e32 v171, 16, v171
	v_lshrrev_b32_e32 v180, 16, v181
	v_lshrrev_b32_e32 v167, 16, v183
	v_and_or_b32 v167, v155, s6, v167
	v_and_or_b32 v166, v166, s6, v180
	v_and_or_b32 v165, v165, s6, v171
	v_and_or_b32 v164, v164, s6, v170
	global_store_dwordx4 v[168:169], v[164:167], off
	v_lshlrev_b32_e32 v171, 16, v215
	v_lshlrev_b32_e32 v170, 16, v214
	v_pk_fma_f32 v[164:165], v[190:191], v[6:7], v[220:221] op_sel_hi:[1,1,0]
	v_pk_fma_f32 v[166:167], v[188:189], v[4:5], v[220:221] op_sel_hi:[1,1,0]
	v_mov_b32_e32 v181, v164
	v_mov_b32_e32 v180, v166
	v_pk_mul_f32 v[170:171], v[180:181], v[170:171]
	v_and_b32_e32 v181, 0xffff0000, v215
	v_and_b32_e32 v180, 0xffff0000, v214
	v_mov_b32_e32 v164, v167
	v_pk_mul_f32 v[164:165], v[164:165], v[180:181]
	v_lshlrev_b32_e32 v167, 16, v217
	v_lshlrev_b32_e32 v166, 16, v216
	v_mov_b32_e32 v180, v156
	v_mov_b32_e32 v181, v158
	v_pk_mul_f32 v[166:167], v[180:181], v[166:167]
	v_and_b32_e32 v181, 0xffff0000, v217
	v_and_b32_e32 v180, 0xffff0000, v216
	v_mov_b32_e32 v158, v157
	v_pk_mul_f32 v[156:157], v[158:159], v[180:181]
	v_bfe_u32 v159, v165, 16, 1
	v_bfe_u32 v155, v157, 16, 1
	v_bfe_u32 v158, v156, 16, 1
	v_bfe_u32 v180, v164, 16, 1
	v_add3_u32 v164, v164, v180, s5
	v_add3_u32 v165, v165, v159, s5
	v_add3_u32 v156, v156, v158, s5
	v_add3_u32 v155, v157, v155, s5
	v_bfe_u32 v157, v170, 16, 1
	v_bfe_u32 v158, v171, 16, 1
	v_bfe_u32 v159, v166, 16, 1
	v_bfe_u32 v180, v167, 16, 1
	v_add3_u32 v167, v167, v180, s5
	v_add3_u32 v159, v166, v159, s5
	v_add3_u32 v158, v171, v158, s5
	v_add3_u32 v157, v170, v157, s5
	v_lshrrev_b32_e32 v166, 16, v157
	v_lshrrev_b32_e32 v157, 16, v158
	v_lshrrev_b32_e32 v158, 16, v159
	v_lshrrev_b32_e32 v159, 16, v167
	v_and_or_b32 v159, v155, s6, v159
	v_and_or_b32 v158, v156, s6, v158
	v_and_or_b32 v157, v165, s6, v157
	v_and_or_b32 v156, v164, s6, v166
	global_store_dwordx4 v[168:169], v[156:159], off offset:64
	v_or_b32_e32 v180, s12, v146
	global_load_dword v182, v[130:131], off
	v_mad_i64_i32 v[168:169], s[20:21], v180, s4, v[82:83]
	global_load_dwordx4 v[156:159], v[168:169], off nt
	v_ashrrev_i32_e32 v181, 31, v180
	global_load_dwordx4 v[168:171], v[168:169], off offset:64 nt
	v_lshlrev_b64 v[180:181], 11, v[180:181]
	v_lshl_add_u64 v[180:181], v[84:85], 0, v[180:181]
	v_mfma_f32_16x16x32_bf16 v[36:39], v[36:39], v[28:31], v[48:51]
	s_waitcnt vmcnt(2)
	v_pk_fma_f32 v[184:185], v[194:195], v[34:35], v[182:183] op_sel_hi:[1,1,0]
	v_pk_fma_f32 v[186:187], v[192:193], v[32:33], v[182:183] op_sel_hi:[1,1,0]
	v_mov_b32_e32 v191, v184
	s_waitcnt vmcnt(1)
	v_lshlrev_b32_e32 v189, 16, v157
	v_lshlrev_b32_e32 v188, 16, v156
	v_and_b32_e32 v157, 0xffff0000, v157
	v_and_b32_e32 v156, 0xffff0000, v156
	v_mov_b32_e32 v184, v187
	v_pk_fma_f32 v[178:179], v[178:179], v[26:27], v[182:183] op_sel_hi:[1,1,0]
	v_pk_fma_f32 v[176:177], v[176:177], v[24:25], v[182:183] op_sel_hi:[1,1,0]
	v_pk_mul_f32 v[156:157], v[184:185], v[156:157]
	v_lshlrev_b32_e32 v185, 16, v159
	v_lshlrev_b32_e32 v184, 16, v158
	v_mov_b32_e32 v187, v178
	v_and_b32_e32 v159, 0xffff0000, v159
	v_and_b32_e32 v158, 0xffff0000, v158
	v_mov_b32_e32 v178, v177
	v_mov_b32_e32 v190, v186
	v_mov_b32_e32 v186, v176
	v_pk_mul_f32 v[158:159], v[178:179], v[158:159]
	v_pk_mul_f32 v[188:189], v[190:191], v[188:189]
	v_pk_mul_f32 v[184:185], v[186:187], v[184:185]
	v_bfe_u32 v155, v159, 16, 1
	v_bfe_u32 v176, v158, 16, 1
	v_bfe_u32 v177, v157, 16, 1
	v_bfe_u32 v178, v156, 16, 1
	v_add3_u32 v156, v156, v178, s5
	v_add3_u32 v157, v157, v177, s5
	v_add3_u32 v158, v158, v176, s5
	v_add3_u32 v155, v159, v155, s5
	v_bfe_u32 v159, v188, 16, 1
	v_bfe_u32 v176, v189, 16, 1
	v_bfe_u32 v177, v184, 16, 1
	v_bfe_u32 v178, v185, 16, 1
	v_add3_u32 v178, v185, v178, s5
	v_add3_u32 v177, v184, v177, s5
	v_add3_u32 v176, v189, v176, s5
	v_add3_u32 v159, v188, v159, s5
	v_lshrrev_b32_e32 v179, 16, v159
	v_lshrrev_b32_e32 v176, 16, v176
	v_lshrrev_b32_e32 v177, 16, v177
	v_lshrrev_b32_e32 v159, 16, v178
	v_and_or_b32 v159, v155, s6, v159
	v_and_or_b32 v158, v158, s6, v177
	v_and_or_b32 v157, v157, s6, v176
	v_and_or_b32 v156, v156, s6, v179
	global_store_dwordx4 v[180:181], v[156:159], off
	v_pk_fma_f32 v[62:63], v[62:63], v[2:3], v[182:183] op_sel_hi:[1,1,0]
	v_pk_fma_f32 v[60:61], v[60:61], v[0:1], v[182:183] op_sel_hi:[1,1,0]
	v_pk_fma_f32 v[156:157], v[162:163], v[6:7], v[182:183] op_sel_hi:[1,1,0]
	v_pk_fma_f32 v[158:159], v[160:161], v[4:5], v[182:183] op_sel_hi:[1,1,0]
	s_waitcnt vmcnt(1)
; __device__ __forceinline__ unsigned pk2(float lo, float hi) { return f2bf(lo) | (f2bf(hi) << 16); }
; template <int HF>
; __device__ __forceinline__ void gmlp_half(LAS unsigned char* wl, const bf16* PROJ, const bf16* wsg, const float* norm_v, const float* b_s, bf16* Y, int tok0, int g, int fr, int fq) {
;     ...
;     for (int nt = 0; nt < 4; ++nt) {
;         const int t = 64 * HF + 16 * nt + fr; const size_t tok = (size_t)(tok0 + t); const float bs = b_s[g * 128 + t];
;         u32x4 uu[2];
; #pragma unroll
;         for (int p = 0; p < 2; ++p) uu[p] = *(const u32x4*)(PROJ + tok * NPROJ + g * 64 + 32 * p + 8 * fq);
; #pragma unroll
;         for (int p = 0; p < 2; ++p) {
;             u32x4 w;
; #pragma unroll
;             for (int e2 = 0; e2 < 2; ++e2) {
;                 const f32x4 z = nv[p][e2] * acc[2 * p + e2][nt] + bs;
;                 const unsigned u0 = uu[p][2 * e2], u1 = uu[p][2 * e2 + 1];
;                 w[2 * e2] = pk2(bf_lo(u0) * z[0], bf_hi(u0) * z[1]); w[2 * e2 + 1] = pk2(bf_lo(u1) * z[2], bf_hi(u1) * z[3]);
;             }
;             *(u32x4*)(Y + tok * D + g * 64 + 32 * p + 8 * fq) = w;
	v_lshlrev_b32_e32 v161, 16, v169
	v_lshlrev_b32_e32 v160, 16, v168
	v_mov_b32_e32 v162, v158
	v_mov_b32_e32 v163, v156
	v_pk_mul_f32 v[160:161], v[162:163], v[160:161]
	v_and_b32_e32 v163, 0xffff0000, v169
	v_and_b32_e32 v162, 0xffff0000, v168
	v_mov_b32_e32 v156, v159
	v_pk_mul_f32 v[156:157], v[156:157], v[162:163]
	v_lshlrev_b32_e32 v159, 16, v171
	v_lshlrev_b32_e32 v158, 16, v170
	v_mov_b32_e32 v162, v60
	v_mov_b32_e32 v163, v62
	v_pk_mul_f32 v[158:159], v[162:163], v[158:159]
	v_and_b32_e32 v163, 0xffff0000, v171
	v_and_b32_e32 v162, 0xffff0000, v170
	v_mov_b32_e32 v62, v61
	v_pk_mul_f32 v[60:61], v[62:63], v[162:163]
	v_bfe_u32 v155, v157, 16, 1
	v_bfe_u32 v62, v61, 16, 1
	v_bfe_u32 v63, v60, 16, 1
	v_bfe_u32 v162, v156, 16, 1
	v_add3_u32 v156, v156, v162, s5
	v_add3_u32 v155, v157, v155, s5
	v_add3_u32 v60, v60, v63, s5
	v_add3_u32 v61, v61, v62, s5
	v_bfe_u32 v62, v160, 16, 1
	v_bfe_u32 v63, v161, 16, 1
	v_bfe_u32 v157, v158, 16, 1
	v_bfe_u32 v162, v159, 16, 1
	v_add3_u32 v159, v159, v162, s5
	v_add3_u32 v157, v158, v157, s5
	v_add3_u32 v63, v161, v63, s5
	v_add3_u32 v62, v160, v62, s5
	v_lshrrev_b32_e32 v158, 16, v62
	v_lshrrev_b32_e32 v160, 16, v63
	v_lshrrev_b32_e32 v62, 16, v157
	v_lshrrev_b32_e32 v63, 16, v159
	v_and_or_b32 v63, v61, s6, v63
	v_and_or_b32 v62, v60, s6, v62
	v_and_or_b32 v61, v155, s6, v160
	v_and_or_b32 v60, v156, s6, v158
	global_store_dwordx4 v[180:181], v[60:63], off offset:64
	v_or_b32_e32 v156, s12, v147
	global_load_dword v158, v[132:133], off
	v_mad_i64_i32 v[160:161], s[12:13], v156, s4, v[82:83]
	global_load_dwordx4 v[60:63], v[160:161], off nt
	global_load_dwordx4 v[48:51], v[160:161], off offset:64 nt
	v_ashrrev_i32_e32 v157, 31, v156
	v_mfma_f32_16x16x32_bf16 v[40:43], v[40:43], v[28:31], v[44:47]
	s_waitcnt vmcnt(2)
	v_pk_fma_f32 v[52:53], v[52:53], v[24:25], v[158:159] op_sel_hi:[1,1,0]
	s_nop 0
	v_lshlrev_b64 v[44:45], 11, v[156:157]
	v_lshl_add_u64 v[156:157], v[84:85], 0, v[44:45]
	v_pk_fma_f32 v[44:45], v[58:59], v[34:35], v[158:159] op_sel_hi:[1,1,0]
	v_pk_fma_f32 v[46:47], v[56:57], v[32:33], v[158:159] op_sel_hi:[1,1,0]
	s_waitcnt vmcnt(1)
	v_lshlrev_b32_e32 v57, 16, v61
	v_lshlrev_b32_e32 v56, 16, v60
	v_mov_b32_e32 v58, v46
	v_mov_b32_e32 v59, v44
	v_pk_mul_f32 v[56:57], v[58:59], v[56:57]
	v_and_b32_e32 v59, 0xffff0000, v61
	v_and_b32_e32 v58, 0xffff0000, v60
	v_mov_b32_e32 v44, v47
	v_pk_fma_f32 v[46:47], v[54:55], v[26:27], v[158:159] op_sel_hi:[1,1,0]
	v_pk_mul_f32 v[44:45], v[44:45], v[58:59]
	v_lshlrev_b32_e32 v55, 16, v63
	v_lshlrev_b32_e32 v54, 16, v62
	v_mov_b32_e32 v58, v52
	v_mov_b32_e32 v59, v46
	v_pk_mul_f32 v[54:55], v[58:59], v[54:55]
	v_and_b32_e32 v59, 0xffff0000, v63
	v_and_b32_e32 v58, 0xffff0000, v62
	v_mov_b32_e32 v46, v53
	v_pk_mul_f32 v[46:47], v[46:47], v[58:59]
	v_bfe_u32 v58, v45, 16, 1
	v_bfe_u32 v52, v47, 16, 1
	v_bfe_u32 v53, v46, 16, 1
	v_bfe_u32 v59, v44, 16, 1
	v_mfma_f32_16x16x32_bf16 v[164:167], v[8:11], v[196:199], v[172:175]
	v_add3_u32 v44, v44, v59, s5
	v_add3_u32 v45, v45, v58, s5
	v_add3_u32 v46, v46, v53, s5
	v_add3_u32 v47, v47, v52, s5
	v_bfe_u32 v52, v56, 16, 1
	v_bfe_u32 v53, v57, 16, 1
	v_bfe_u32 v58, v54, 16, 1
	v_bfe_u32 v59, v55, 16, 1
	v_add3_u32 v55, v55, v59, s5
	v_add3_u32 v54, v54, v58, s5
	v_add3_u32 v53, v57, v53, s5
	v_add3_u32 v52, v56, v52, s5
	v_mfma_f32_16x16x32_bf16 v[172:175], v[12:15], v[196:199], v[206:209]
	v_lshrrev_b32_e32 v52, 16, v52
	v_lshrrev_b32_e32 v53, 16, v53
	v_lshrrev_b32_e32 v54, 16, v54
	v_lshrrev_b32_e32 v55, 16, v55
	v_and_or_b32 v47, v47, s6, v55
	v_and_or_b32 v46, v46, s6, v54
	v_and_or_b32 v45, v45, s6, v53
	v_and_or_b32 v44, v44, s6, v52
	global_store_dwordx4 v[156:157], v[44:47], off
	s_waitcnt vmcnt(1)
	v_lshlrev_b32_e32 v53, 16, v49
	v_lshlrev_b32_e32 v52, 16, v48
	v_pk_fma_f32 v[44:45], v[166:167], v[6:7], v[158:159] op_sel_hi:[1,1,0]
	v_pk_fma_f32 v[46:47], v[164:165], v[4:5], v[158:159] op_sel_hi:[1,1,0]
	v_mov_b32_e32 v55, v44
	v_and_b32_e32 v49, 0xffff0000, v49
	v_and_b32_e32 v48, 0xffff0000, v48
	v_mov_b32_e32 v44, v47
	v_mov_b32_e32 v54, v46
	v_pk_mul_f32 v[44:45], v[44:45], v[48:49]
	v_pk_fma_f32 v[46:47], v[174:175], v[2:3], v[158:159] op_sel_hi:[1,1,0]
	v_pk_fma_f32 v[48:49], v[172:173], v[0:1], v[158:159] op_sel_hi:[1,1,0]
	v_pk_mul_f32 v[52:53], v[54:55], v[52:53]
	v_lshlrev_b32_e32 v55, 16, v51
	v_lshlrev_b32_e32 v54, 16, v50
	v_mov_b32_e32 v57, v46
	v_and_b32_e32 v51, 0xffff0000, v51
	v_and_b32_e32 v50, 0xffff0000, v50
	v_mov_b32_e32 v46, v49
	v_mov_b32_e32 v56, v48
	v_pk_mul_f32 v[46:47], v[46:47], v[50:51]
	v_pk_mul_f32 v[54:55], v[56:57], v[54:55]
	v_bfe_u32 v48, v47, 16, 1
	v_bfe_u32 v49, v46, 16, 1
	v_bfe_u32 v50, v45, 16, 1
	v_bfe_u32 v51, v44, 16, 1
	v_add3_u32 v44, v44, v51, s5
	v_add3_u32 v45, v45, v50, s5
	v_add3_u32 v46, v46, v49, s5
	v_add3_u32 v47, v47, v48, s5
	v_bfe_u32 v48, v52, 16, 1
	v_bfe_u32 v49, v53, 16, 1
	v_bfe_u32 v50, v54, 16, 1
	v_bfe_u32 v51, v55, 16, 1
	v_add3_u32 v51, v55, v51, s5
	v_add3_u32 v50, v54, v50, s5
	v_add3_u32 v49, v53, v49, s5
	v_add3_u32 v48, v52, v48, s5
	v_lshrrev_b32_e32 v48, 16, v48
	v_lshrrev_b32_e32 v49, 16, v49
	v_lshrrev_b32_e32 v50, 16, v50
	v_lshrrev_b32_e32 v51, 16, v51
	v_and_or_b32 v47, v47, s6, v51
	v_and_or_b32 v46, v46, s6, v50
	v_and_or_b32 v45, v45, s6, v49
	v_and_or_b32 v44, v44, s6, v48
	global_store_dwordx4 v[156:157], v[44:47], off offset:64
	v_or_b32_e32 v48, s11, v148
	global_load_dword v50, v[134:135], off
	v_mad_i64_i32 v[52:53], s[12:13], v48, s4, v[82:83]
	global_load_dwordx4 v[44:47], v[52:53], off nt
	v_mfma_f32_16x16x32_bf16 v[8:11], v[8:11], v[28:31], v[16:19]
	v_ashrrev_i32_e32 v49, 31, v48
	s_waitcnt vmcnt(1)
; #define LAS __attribute__((address_space(3)))
; __device__ __forceinline__ unsigned pk2(float lo, float hi) { return f2bf(lo) | (f2bf(hi) << 16); }
; template <int HF>
; __device__ __forceinline__ void gmlp_half(LAS unsigned char* wl, const bf16* PROJ, const bf16* wsg, const float* norm_v, const float* b_s, bf16* Y, int tok0, int g, int fr, int fq) {
;     ...
;                 const f32x4 z = nv[p][e2] * acc[2 * p + e2][nt] + bs;
;                 const unsigned u0 = uu[p][2 * e2], u1 = uu[p][2 * e2 + 1];
;                 w[2 * e2] = pk2(bf_lo(u0) * z[0], bf_hi(u0) * z[1]); w[2 * e2 + 1] = pk2(bf_lo(u1) * z[2], bf_hi(u1) * z[3]);
;             }
;             *(u32x4*)(Y + tok * D + g * 64 + 32 * p + 8 * fq) = w;
; __device__ __forceinline__ void gla_upd_unit(LAS unsigned char* wl, const bf16* PROJ, const float* R, const float* w_gk2, const float* b_gk, float* UPD, float* DEC, int unit, int lane) {
;     constexpr int KS = 72;
;     LAS unsigned* KD32 = (LAS unsigned*)wl; LAS unsigned* VB32 = (LAS unsigned*)(wl + 9216);
;     const int h = unit & 3, tok0 = (unit >> 2) * 64, kk = lane;
;     { const f32x4* rp = (const f32x4*)(R + (size_t)(tok0 + lane) * 16); LAS f32x4* rl = (LAS f32x4*)(wl + 9216) + lane * 4;
;       const f32x4 r0 = rp[0], r1 = rp[1], r2 = rp[2], r3 = rp[3]; rl[0] = r0; rl[1] = r1; rl[2] = r2; rl[3] = r3; }
;     const bf16* kp = PROJ + (size_t)tok0 * NPROJ + 1280 + h * 64 + kk;
;     unsigned short kv0[32], kv1[32];
; #pragma unroll
;     for (int t = 0; t < 32; ++t) kv0[t] = kp[(size_t)t * NPROJ];
;     float w[16];
; #pragma unroll
;     for (int j = 0; j < 16; ++j) w[j] = w_gk2[j * 256 + h * 64 + kk];
;     const float bias = b_gk[h * 64 + kk];
	v_pk_fma_f32 v[24:25], v[40:41], v[24:25], v[50:51] op_sel_hi:[1,1,0]
	global_load_dwordx4 v[16:19], v[52:53], off offset:64 nt
	v_mfma_f32_16x16x32_bf16 v[12:15], v[12:15], v[28:31], v[20:23]
	s_nop 2
	v_fma_f32 v6, v10, v6, v50
	v_fma_f32 v7, v11, v7, v50
	v_pk_fma_f32 v[4:5], v[8:9], v[4:5], v[50:51] op_sel_hi:[1,1,0]
	s_waitcnt vmcnt(1)
	v_lshlrev_b32_e32 v31, 16, v45
	v_lshlrev_b64 v[20:21], 11, v[48:49]
	v_lshl_add_u64 v[28:29], v[84:85], 0, v[20:21]
	v_pk_fma_f32 v[20:21], v[38:39], v[34:35], v[50:51] op_sel_hi:[1,1,0]
	v_pk_fma_f32 v[22:23], v[36:37], v[32:33], v[50:51] op_sel_hi:[1,1,0]
	v_lshlrev_b32_e32 v30, 16, v44
	v_mov_b32_e32 v32, v22
	v_mov_b32_e32 v33, v20
	v_mov_b32_e32 v10, v4
	v_mov_b32_e32 v11, v6
	v_pk_mul_f32 v[30:31], v[32:33], v[30:31]
	v_and_b32_e32 v33, 0xffff0000, v45
	v_and_b32_e32 v32, 0xffff0000, v44
	v_mov_b32_e32 v20, v23
	v_pk_fma_f32 v[22:23], v[42:43], v[26:27], v[50:51] op_sel_hi:[1,1,0]
	v_mov_b32_e32 v6, v5
	v_pk_fma_f32 v[2:3], v[14:15], v[2:3], v[50:51] op_sel_hi:[1,1,0]
	v_pk_fma_f32 v[0:1], v[12:13], v[0:1], v[50:51] op_sel_hi:[1,1,0]
	v_pk_mul_f32 v[20:21], v[20:21], v[32:33]
	v_lshlrev_b32_e32 v27, 16, v47
	v_lshlrev_b32_e32 v26, 16, v46
	v_mov_b32_e32 v32, v24
	v_mov_b32_e32 v33, v22
	v_pk_mul_f32 v[26:27], v[32:33], v[26:27]
	v_and_b32_e32 v33, 0xffff0000, v47
	v_and_b32_e32 v32, 0xffff0000, v46
	v_mov_b32_e32 v22, v25
	v_pk_mul_f32 v[22:23], v[22:23], v[32:33]
	v_bfe_u32 v32, v21, 16, 1
	v_bfe_u32 v24, v23, 16, 1
	v_bfe_u32 v25, v22, 16, 1
	v_bfe_u32 v33, v20, 16, 1
	v_add3_u32 v20, v20, v33, s5
	v_add3_u32 v21, v21, v32, s5
	v_add3_u32 v22, v22, v25, s5
	v_add3_u32 v23, v23, v24, s5
	v_bfe_u32 v24, v30, 16, 1
	v_bfe_u32 v25, v31, 16, 1
	v_bfe_u32 v32, v26, 16, 1
	v_bfe_u32 v33, v27, 16, 1
	v_add3_u32 v27, v27, v33, s5
	v_add3_u32 v26, v26, v32, s5
	v_add3_u32 v25, v31, v25, s5
	v_add3_u32 v24, v30, v24, s5
	v_lshrrev_b32_e32 v24, 16, v24
	v_lshrrev_b32_e32 v25, 16, v25
	v_lshrrev_b32_e32 v26, 16, v26
	v_lshrrev_b32_e32 v27, 16, v27
	v_and_or_b32 v23, v23, s6, v27
	v_and_or_b32 v22, v22, s6, v26
	v_and_or_b32 v21, v21, s6, v25
	v_and_or_b32 v20, v20, s6, v24
	global_store_dwordx4 v[28:29], v[20:23], off
	s_waitcnt vmcnt(1)
	v_lshlrev_b32_e32 v9, 16, v17
	v_lshlrev_b32_e32 v8, 16, v16
	v_pk_mul_f32 v[8:9], v[10:11], v[8:9]
	v_and_b32_e32 v11, 0xffff0000, v17
	v_and_b32_e32 v10, 0xffff0000, v16
	v_pk_mul_f32 v[4:5], v[6:7], v[10:11]
	v_lshlrev_b32_e32 v7, 16, v19
	v_lshlrev_b32_e32 v6, 16, v18
	v_mov_b32_e32 v10, v0
	v_mov_b32_e32 v11, v2
	v_pk_mul_f32 v[6:7], v[10:11], v[6:7]
	v_and_b32_e32 v11, 0xffff0000, v19
	v_and_b32_e32 v10, 0xffff0000, v18
	v_mov_b32_e32 v2, v1
	v_pk_mul_f32 v[0:1], v[2:3], v[10:11]
	v_bfe_u32 v10, v5, 16, 1
	v_bfe_u32 v2, v1, 16, 1
	v_bfe_u32 v3, v0, 16, 1
	v_bfe_u32 v11, v4, 16, 1
	v_add3_u32 v4, v4, v11, s5
	v_add3_u32 v5, v5, v10, s5
	v_add3_u32 v0, v0, v3, s5
	v_add3_u32 v1, v1, v2, s5
	v_bfe_u32 v2, v8, 16, 1
	v_bfe_u32 v3, v9, 16, 1
	v_bfe_u32 v10, v6, 16, 1
	v_bfe_u32 v11, v7, 16, 1
	v_add3_u32 v7, v7, v11, s5
	v_add3_u32 v6, v6, v10, s5
	v_add3_u32 v3, v9, v3, s5
	v_add3_u32 v2, v8, v2, s5
	v_lshrrev_b32_e32 v8, 16, v2
	v_lshrrev_b32_e32 v9, 16, v3
	v_lshrrev_b32_e32 v2, 16, v6
	v_lshrrev_b32_e32 v3, 16, v7
	v_and_or_b32 v3, v1, s6, v3
	v_and_or_b32 v2, v0, s6, v2
	v_and_or_b32 v1, v5, s6, v9
	v_and_or_b32 v0, v4, s6, v8
	global_store_dwordx4 v[28:29], v[0:3], off offset:64
	s_waitcnt lgkmcnt(0)
	s_cbranch_scc0 .LBB0_1050
	v_readlane_b32 s0, v230, 10
	v_lshlrev_b32_e32 v0, 2, v200
	v_mov_b32_e32 v1, 0
	v_readlane_b32 s1, v230, 11
	v_and_b32_e32 v2, 12, v140
	v_readlane_b32 s2, v230, 8
	v_lshl_add_u64 v[24:25], s[0:1], 0, v[0:1]
	s_movk_i32 s0, 0x90
	v_mov_b32_e32 v6, s37
	v_lshlrev_b32_e32 v2, 2, v2
	v_mov_b32_e32 v3, v1
	v_readlane_b32 s3, v230, 9
	v_mad_u32_u24 v6, v64, s0, v6
	v_readlane_b32 s0, v230, 4
	v_lshl_add_u64 v[2:3], s[2:3], 0, v[2:3]
	s_bfe_u32 s2, s0, 0x20006
	s_lshl_b32 s3, s2, 8
	v_lshl_add_u32 v81, v67, 2, v6
	v_mov_b32_e32 v67, v1
	v_or_b32_e32 v0, s3, v0
	v_lshl_add_u64 v[26:27], v[2:3], 0, v[66:67]
	v_lshl_add_u64 v[2:3], s[14:15], 0, v[0:1]
	s_mov_b64 s[0:1], 0x4000
	v_lshl_add_u64 v[28:29], v[2:3], 0, s[0:1]
	s_mov_b64 s[0:1], 0x5000
	v_lshl_add_u64 v[30:31], v[2:3], 0, s[0:1]
	s_mov_b64 s[0:1], 0x5400
	v_lshl_add_u64 v[32:33], v[2:3], 0, s[0:1]
	s_mov_b64 s[0:1], 0x5800
	v_lshl_add_u64 v[34:35], v[2:3], 0, s[0:1]
	s_mov_b64 s[0:1], 0x5c00
	v_lshl_add_u64 v[36:37], v[2:3], 0, s[0:1]
	s_mov_b64 s[0:1], 0x6000
	v_lshl_add_u64 v[38:39], v[2:3], 0, s[0:1]
	s_mov_b64 s[0:1], 0x6400
	v_lshl_add_u64 v[40:41], v[2:3], 0, s[0:1]
	s_mov_b64 s[0:1], 0x6800
	v_lshl_add_u64 v[42:43], v[2:3], 0, s[0:1]
	s_mov_b64 s[0:1], 0x6c00
	v_lshl_add_u64 v[44:45], v[2:3], 0, s[0:1]
	s_mov_b64 s[0:1], 0x7000
	v_lshl_add_u64 v[46:47], v[2:3], 0, s[0:1]
	s_mov_b64 s[0:1], 0x7400
	v_lshl_add_u64 v[48:49], v[2:3], 0, s[0:1]
	s_mov_b64 s[0:1], 0x7800
	v_lshl_add_u64 v[50:51], v[2:3], 0, s[0:1]
	s_mov_b64 s[0:1], 0x7c00
	v_lshl_add_u64 v[52:53], v[2:3], 0, s[0:1]
	s_lshl_b32 s0, s2, 7
	s_add_u32 s0, s24, s0
	v_lshl_add_u64 v[54:55], s[16:17], 0, v[0:1]
	s_addc_u32 s1, s25, 0
	v_lshlrev_b32_e32 v0, 1, v200
	v_or_b32_e32 v78, 16, v138
	v_or_b32_e32 v79, 32, v138
	v_or_b32_e32 v80, 48, v138
	v_lshl_add_u64 v[56:57], s[0:1], 0, v[0:1]
	s_add_u32 s0, s24, s3
	v_lshlrev_b32_e32 v4, 6, v200
	v_mul_u32_u24_e32 v5, 0x90, v200
	v_lshl_add_u32 v82, v78, 1, v6
	v_lshl_add_u32 v83, v79, 1, v6
	v_lshl_add_u32 v84, v80, 1, v6
	v_mul_u32_u24_e32 v6, 0x90, v139
	v_mul_u32_u24_e32 v7, 0x90, v202
	s_addc_u32 s1, s25, 0
	v_lshlrev_b32_e32 v0, 1, v64
	v_lshl_add_u64 v[58:59], s[0:1], 0, v[0:1]
	v_add_u32_e32 v85, s37, v4
	s_movk_i32 s39, 0x1600
	s_mov_b32 s48, 0xbfb8aa3b
	s_mov_b32 s49, 0x800000
	s_mov_b32 s56, 0x3f317217
	s_mov_b32 s57, 0x7f800000
	s_movk_i32 s58, 0x7fff
	s_mov_b32 s59, 0xffff0000
	v_add_u32_e32 v86, s37, v5
	s_mov_b32 s66, 0x2c000
	s_mov_b32 s67, 0x2f000
	s_mov_b32 s68, 0x2e000
	s_mov_b32 s69, 0x30000
	s_mov_b32 s70, 0x32000
	s_mov_b32 s71, 0x34000
	s_mov_b32 s72, 0x33000
	s_mov_b32 s20, 0x36000
	s_mov_b32 s21, 0x37000
	s_mov_b32 s28, 0x3a000
	s_mov_b32 s29, 0x39000
	s_mov_b32 s30, 0x3b000
	s_mov_b32 s31, 0x3d000
	s_mov_b32 s73, 0x3f000
	s_mov_b32 s74, 0x3e000
	s_mov_b32 s75, 0x41000
	s_mov_b32 s76, 0x42000
	s_mov_b32 s77, 0x45000
	s_mov_b32 s78, 0x44000
	s_mov_b32 s79, 0x46000
	s_mov_b32 s80, 0x48000
	s_mov_b32 s81, 0x4a000
	s_mov_b32 s82, 0x49000
	s_mov_b32 s83, 0x4c000
	s_mov_b32 s84, 0x4d000
	s_mov_b32 s85, 0x50000
	s_mov_b32 s86, 0x4f000
	v_add_u32_e32 v87, v65, v6
	v_add_u32_e32 v88, v65, v7
	v_mov_b32_e32 v89, 0x1600
	v_mov_b32_e32 v90, 0x41b17218
	v_mov_b32_e32 v91, 1
	s_mov_b32 s87, 0x51000
	s_mov_b32 s88, 0x53000
	s_mov_b32 s89, 0x55000
	s_mov_b32 s90, 0x54000
	s_mov_b32 s91, 0x57000
	s_mov_b32 s13, 0
	s_mov_b32 s14, s38
; #define LAS __attribute__((address_space(3)))
; __device__ __forceinline__ void gla_upd_unit(LAS unsigned char* wl, const bf16* PROJ, const float* R, const float* w_gk2, const float* b_gk, float* UPD, float* DEC, int unit, int lane) {
;     ...
;     const int h = unit & 3, tok0 = (unit >> 2) * 64, kk = lane;
;     { const f32x4* rp = (const f32x4*)(R + (size_t)(tok0 + lane) * 16); LAS f32x4* rl = (LAS f32x4*)(wl + 9216) + lane * 4;
;       const f32x4 r0 = rp[0], r1 = rp[1], r2 = rp[2], r3 = rp[3]; rl[0] = r0; rl[1] = r1; rl[2] = r2; rl[3] = r3; }
;     const bf16* kp = PROJ + (size_t)tok0 * NPROJ + 1280 + h * 64 + kk;
;     unsigned short kv0[32], kv1[32];
; #pragma unroll
;     for (int t = 0; t < 32; ++t) kv0[t] = kp[(size_t)t * NPROJ];
;     float w[16];
; #pragma unroll
;     for (int j = 0; j < 16; ++j) w[j] = w_gk2[j * 256 + h * 64 + kk];
;     const float bias = b_gk[h * 64 + kk];
.LBB0_1054:
	s_lshl_b32 s4, s14, 4
	s_and_b32 s5, s4, 0xffffffc0
	v_or_b32_e32 v0, s5, v200
	v_ashrrev_i32_e32 v1, 31, v0
	v_lshlrev_b64 v[0:1], 6, v[0:1]
	v_lshl_add_u64 v[12:13], s[46:47], 0, v[0:1]
	global_load_dwordx4 v[0:3], v[12:13], off offset:48 nt
	global_load_dwordx4 v[4:7], v[12:13], off offset:32 nt
	global_load_dwordx4 v[8:11], v[12:13], off offset:16 nt
	s_nop 0
	global_load_dwordx4 v[12:15], v[12:13], off nt
	s_ashr_i32 s15, s14, 31
	s_mov_b64 s[16:17], -1
	s_waitcnt vmcnt(0)
	ds_write_b128 v85, v[12:15] offset:9216
	ds_write_b128 v85, v[8:11] offset:9232
	ds_write_b128 v85, v[4:7] offset:9248
	ds_write_b128 v85, v[0:3] offset:9264
	global_load_dword v14, v[28:29], off
	global_load_dword v16, v[28:29], off offset:1024
	global_load_dword v12, v[28:29], off offset:2048
	global_load_dword v10, v[28:29], off offset:3072
	global_load_dword v15, v[30:31], off
	global_load_dword v17, v[32:33], off
	global_load_dword v13, v[34:35], off
	global_load_dword v11, v[36:37], off
	global_load_dword v6, v[38:39], off
	global_load_dword v8, v[40:41], off
	global_load_dword v2, v[42:43], off
	global_load_dword v0, v[44:45], off
	global_load_dword v7, v[46:47], off
	global_load_dword v9, v[48:49], off
	global_load_dword v3, v[50:51], off
	global_load_dword v1, v[52:53], off
	global_load_dword v100, v[54:55], off offset:1024
	v_mad_i64_i32 v[4:5], s[0:1], s5, v89, v[56:57]
	s_movk_i32 s0, 0x3000
	s_nop 0
	v_add_co_u32_e32 v18, vcc, s0, v4
	s_movk_i32 s0, 0x2000
	s_nop 0
	v_addc_co_u32_e32 v19, vcc, 0, v5, vcc
	global_load_ushort v92, v[18:19], off offset:1536 nt
	global_load_ushort v93, v[4:5], off offset:2560 nt
	v_add_co_u32_e32 v18, vcc, s0, v4
	s_movk_i32 s0, 0x4000
	s_nop 0
	v_addc_co_u32_e32 v19, vcc, 0, v5, vcc
	global_load_ushort v95, v[18:19], off nt
	v_add_co_u32_e32 v18, vcc, s0, v4
	s_movk_i32 s0, 0x6000
	s_nop 0
	v_addc_co_u32_e32 v19, vcc, 0, v5, vcc
	global_load_ushort v97, v[18:19], off offset:3072 nt
	v_add_co_u32_e32 v18, vcc, s0, v4
	s_mov_b32 s0, 0x8000
	s_nop 0
	v_addc_co_u32_e32 v19, vcc, 0, v5, vcc
	global_load_ushort v94, v[18:19], off offset:512 nt
	v_add_co_u32_e32 v18, vcc, s0, v4
	s_movk_i32 s0, 0x7000
	s_nop 0
	v_addc_co_u32_e32 v19, vcc, 0, v5, vcc
	global_load_ushort v96, v[18:19], off offset:3584 nt
	v_add_co_u32_e32 v18, vcc, s0, v4
	s_mov_b32 s0, 0xa000
	s_nop 0
	v_addc_co_u32_e32 v19, vcc, 0, v5, vcc
	global_load_ushort v98, v[18:19], off offset:2048 nt
	v_add_co_u32_e32 v18, vcc, s0, v4
	s_mov_b32 s0, 0xb000
	s_nop 0
	v_addc_co_u32_e32 v19, vcc, 0, v5, vcc
	global_load_ushort v99, v[18:19], off offset:1024 nt
	v_add_co_u32_e32 v18, vcc, s0, v4
	s_mov_b32 s0, 0xe000
	s_nop 0
	v_addc_co_u32_e32 v19, vcc, 0, v5, vcc
	v_add_co_u32_e32 v20, vcc, s0, v4
	s_mov_b32 s0, 0xd000
	s_nop 0
	v_addc_co_u32_e32 v21, vcc, 0, v5, vcc
	global_load_ushort v18, v[18:19], off offset:2560 nt
	s_waitcnt vmcnt(0)
	v_lshlrev_b32_e32 v18, 16, v18
	global_load_ushort v19, v[20:21], off offset:1536 nt
	v_add_co_u32_e32 v20, vcc, s0, v4
	s_mov_b32 s0, 0xf000
	s_nop 0
	v_addc_co_u32_e32 v21, vcc, 0, v5, vcc
	v_add_co_u32_e32 v22, vcc, s0, v4
	s_mov_b32 s0, 0x11000
	s_nop 0
	v_addc_co_u32_e32 v23, vcc, 0, v5, vcc
	global_load_ushort v20, v[20:21], off nt
	s_waitcnt vmcnt(1)
	v_lshlrev_b32_e32 v19, 16, v19
	global_load_ushort v21, v[22:23], off offset:3072 nt
	v_add_co_u32_e32 v22, vcc, s0, v4
	s_mov_b32 s0, 0x13000
	s_nop 0
	v_addc_co_u32_e32 v23, vcc, 0, v5, vcc
	v_add_co_u32_e32 v60, vcc, s0, v4
	s_mov_b32 s0, 0x12000
	s_nop 0
	v_addc_co_u32_e32 v61, vcc, 0, v5, vcc
	v_add_co_u32_e32 v62, vcc, s0, v4
	s_mov_b32 s0, 0x15000
	s_nop 0
	v_addc_co_u32_e32 v63, vcc, 0, v5, vcc
	global_load_ushort v22, v[22:23], off offset:512 nt
	s_nop 0
	global_load_ushort v60, v[60:61], off offset:3584 nt
	s_nop 0
	global_load_ushort v61, v[62:63], off offset:2048 nt
	v_add_co_u32_e32 v62, vcc, s0, v4
	s_mov_b32 s0, 0x16000
	s_nop 0
	v_addc_co_u32_e32 v63, vcc, 0, v5, vcc
	global_load_ushort v75, v[62:63], off offset:1024 nt
	v_add_co_u32_e32 v62, vcc, s0, v4
	s_mov_b32 s0, 0x19000
	s_nop 0
	v_addc_co_u32_e32 v63, vcc, 0, v5, vcc
	v_add_co_u32_e32 v64, vcc, s0, v4
	s_mov_b32 s0, 0x18000
	s_nop 0
	v_addc_co_u32_e32 v65, vcc, 0, v5, vcc
	global_load_ushort v67, v[64:65], off offset:1536 nt
	v_add_co_u32_e32 v64, vcc, s0, v4
	s_mov_b32 s0, 0x1a000
	s_nop 0
	v_addc_co_u32_e32 v65, vcc, 0, v5, vcc
	global_load_ushort v62, v[62:63], off offset:2560 nt
	s_nop 0
	global_load_ushort v68, v[64:65], off nt
	v_add_co_u32_e32 v64, vcc, s0, v4
	s_mov_b32 s0, 0x1c000
	s_nop 0
	v_addc_co_u32_e32 v65, vcc, 0, v5, vcc
	global_load_ushort v73, v[64:65], off offset:3072 nt
	v_add_co_u32_e32 v64, vcc, s0, v4
	s_mov_b32 s0, 0x1e000
	s_nop 0
	v_addc_co_u32_e32 v65, vcc, 0, v5, vcc
	global_load_ushort v23, v[64:65], off offset:512 nt
	v_add_co_u32_e32 v64, vcc, s0, v4
	s_mov_b32 s0, 0x1d000
	s_nop 0
	v_addc_co_u32_e32 v65, vcc, 0, v5, vcc
	v_add_co_u32_e32 v70, vcc, s0, v4
	s_mov_b32 s0, 0x20000
	s_nop 0
	v_addc_co_u32_e32 v71, vcc, 0, v5, vcc
	global_load_ushort v64, v[64:65], off offset:3584 nt
	s_nop 0
	global_load_ushort v65, v[70:71], off offset:2048 nt
	v_add_co_u32_e32 v70, vcc, s0, v4
	s_mov_b32 s0, 0x21000
	s_nop 0
	v_addc_co_u32_e32 v71, vcc, 0, v5, vcc
	global_load_ushort v76, v[70:71], off offset:1024 nt
	v_add_co_u32_e32 v70, vcc, s0, v4
	s_mov_b32 s0, 0x24000
	s_nop 0
	v_addc_co_u32_e32 v71, vcc, 0, v5, vcc
	global_load_ushort v66, v[70:71], off offset:2560 nt
	v_add_co_u32_e32 v70, vcc, s0, v4
	s_mov_b32 s0, 0x23000
	s_nop 0
	v_addc_co_u32_e32 v71, vcc, 0, v5, vcc
	v_add_co_u32_e32 v102, vcc, s0, v4
	s_mov_b32 s0, 0x25000
	s_nop 0
	v_addc_co_u32_e32 v103, vcc, 0, v5, vcc
	global_load_ushort v71, v[70:71], off offset:1536 nt
	s_nop 0
	global_load_ushort v72, v[102:103], off nt
	v_add_co_u32_e32 v102, vcc, s0, v4
	s_mov_b32 s0, 0x27000
	s_nop 0
	v_addc_co_u32_e32 v103, vcc, 0, v5, vcc
	global_load_ushort v74, v[102:103], off offset:3072 nt
	v_add_co_u32_e32 v102, vcc, s0, v4
	s_mov_b32 s0, 0x29000
	s_nop 0
	v_addc_co_u32_e32 v103, vcc, 0, v5, vcc
	global_load_ushort v63, v[102:103], off offset:512 nt
	v_add_co_u32_e32 v102, vcc, s0, v4
	s_mov_b32 s0, 0x28000
	s_nop 0
	v_addc_co_u32_e32 v103, vcc, 0, v5, vcc
	global_load_ushort v69, v[102:103], off offset:3584 nt
	v_add_co_u32_e32 v102, vcc, s0, v4
	s_mov_b32 s0, 0x2b000
	s_nop 0
	v_addc_co_u32_e32 v103, vcc, 0, v5, vcc
	global_load_ushort v70, v[102:103], off offset:2048 nt
	v_add_co_u32_e32 v102, vcc, s0, v4
	s_nop 1
	v_addc_co_u32_e32 v103, vcc, 0, v5, vcc
	global_load_ushort v77, v[102:103], off offset:1024 nt
	s_waitcnt lgkmcnt(0)
; #define LAS __attribute__((address_space(3)))
; __device__ __forceinline__ void gla_upd_unit(LAS unsigned char* wl, const bf16* PROJ, const float* R, const float* w_gk2, const float* b_gk, float* UPD, float* DEC, int unit, int lane) {
;     ...
;     for (int t = 0; t < 64; ++t) {
;         const LAS f32x4* rr = (const LAS f32x4*)(wl + 9216) + t * 4;
;         float z = bias;
; #pragma unroll
;         for (int q = 0; q < 4; ++q) { const f32x4 rv = rr[q]; z += rv[0] * w[4 * q] + rv[1] * w[4 * q + 1] + rv[2] * w[4 * q + 2] + rv[3] * w[4 * q + 3]; }
;         la[t] = (fminf(z, 0.f) - __logf(1.0f + __expf(-fabsf(z)))) * (1.0f / 16.0f);
;         tot += la[t];
;     }
	v_mov_b32_e32 v102, s37
	ds_read_b128 v[104:107], v102 offset:9216
	ds_read_b128 v[108:111], v102 offset:9232
	ds_read_b128 v[112:115], v102 offset:9248
	ds_read_b128 v[116:119], v102 offset:9264
	s_waitcnt lgkmcnt(3)
	v_mov_b32_e32 v120, v104
	s_waitcnt lgkmcnt(2)
	v_mov_b32_e32 v121, v108
	v_mov_b32_e32 v108, v105
	v_pk_mul_f32 v[104:105], v[16:17], v[108:109]
	v_mov_b32_e32 v108, v106
	v_pk_fma_f32 v[104:105], v[14:15], v[120:121], v[104:105]
	v_mov_b32_e32 v109, v110
	v_pk_fma_f32 v[104:105], v[12:13], v[108:109], v[104:105]
	v_mov_b32_e32 v110, v107
	v_pk_fma_f32 v[104:105], v[10:11], v[110:111], v[104:105]
	s_nop 0
	v_add_f32_e32 v101, v100, v104
	v_add_f32_e32 v101, v101, v105
	s_waitcnt lgkmcnt(0)
	v_mov_b32_e32 v105, v116
	v_mov_b32_e32 v116, v113
	v_mov_b32_e32 v104, v112
	v_pk_mul_f32 v[106:107], v[8:9], v[116:117]
	s_nop 0
	v_pk_fma_f32 v[104:105], v[6:7], v[104:105], v[106:107]
	v_mov_b32_e32 v106, v114
	v_mov_b32_e32 v107, v118
	v_pk_fma_f32 v[104:105], v[2:3], v[106:107], v[104:105]
	v_mov_b32_e32 v118, v115
	v_pk_fma_f32 v[104:105], v[0:1], v[118:119], v[104:105]
	s_nop 0
	v_add_f32_e32 v101, v101, v104
	v_add_f32_e32 v101, v101, v105
	v_min_f32_e32 v103, 0, v101
	v_mul_f32_e64 v101, |v101|, s48
	v_exp_f32_e32 v101, v101
	s_nop 0
	v_add_f32_e32 v101, 1.0, v101
	v_cmp_gt_f32_e32 vcc, s49, v101
	s_nop 1
	v_cndmask_b32_e64 v104, 0, 32, vcc
	v_ldexp_f32 v101, v101, v104
	v_log_f32_e32 v101, v101
	s_nop 0
	v_mul_f32_e32 v104, 0x3f317217, v101
	v_fma_f32 v104, v101, s56, -v104
	v_fmac_f32_e32 v104, 0x3377d1cf, v101
	v_fmac_f32_e32 v104, 0x3f317217, v101
	v_cmp_lt_f32_e64 s[0:1], |v101|, s57
	s_nop 1
	v_cndmask_b32_e64 v101, v101, v104, s[0:1]
	v_cndmask_b32_e32 v104, 0, v90, vcc
	v_sub_f32_e32 v101, v101, v104
	ds_read_b128 v[104:107], v102 offset:9280
	ds_read_b128 v[108:111], v102 offset:9296
	v_sub_f32_e32 v101, v103, v101
	s_mov_b32 s0, 0x3d800000
	v_fma_f32 v101, v101, s0, 0
	s_waitcnt lgkmcnt(1)
	v_mov_b32_e32 v112, v104
	s_waitcnt lgkmcnt(0)
	v_mov_b32_e32 v113, v108
	v_mov_b32_e32 v108, v105
	v_pk_mul_f32 v[104:105], v[16:17], v[108:109]
	v_mov_b32_e32 v108, v106
	v_pk_fma_f32 v[104:105], v[14:15], v[112:113], v[104:105]
	v_mov_b32_e32 v109, v110
	v_pk_fma_f32 v[104:105], v[12:13], v[108:109], v[104:105]
	v_mov_b32_e32 v110, v107
	v_pk_fma_f32 v[104:105], v[10:11], v[110:111], v[104:105]
	s_nop 0
	v_add_f32_e32 v103, v100, v104
	v_add_f32_e32 v103, v103, v105
	ds_read_b128 v[104:107], v102 offset:9312
	ds_read_b128 v[108:111], v102 offset:9328
	s_waitcnt lgkmcnt(1)
	v_mov_b32_e32 v112, v104
	s_waitcnt lgkmcnt(0)
	v_mov_b32_e32 v113, v108
	v_mov_b32_e32 v108, v105
	v_pk_mul_f32 v[104:105], v[8:9], v[108:109]
	v_mov_b32_e32 v108, v106
	v_pk_fma_f32 v[104:105], v[6:7], v[112:113], v[104:105]
	v_mov_b32_e32 v109, v110
	v_pk_fma_f32 v[104:105], v[2:3], v[108:109], v[104:105]
	v_mov_b32_e32 v110, v107
	v_pk_fma_f32 v[104:105], v[0:1], v[110:111], v[104:105]
	s_nop 0
	v_add_f32_e32 v103, v103, v104
	v_add_f32_e32 v103, v103, v105
	v_min_f32_e32 v104, 0, v103
	v_mul_f32_e64 v103, |v103|, s48
	v_exp_f32_e32 v103, v103
	s_nop 0
	v_add_f32_e32 v103, 1.0, v103
	v_cmp_gt_f32_e32 vcc, s49, v103
	s_nop 1
	v_cndmask_b32_e64 v105, 0, 32, vcc
	v_ldexp_f32 v103, v103, v105
	v_log_f32_e32 v103, v103
	s_nop 0
	v_mul_f32_e32 v105, 0x3f317217, v103
	v_fma_f32 v105, v103, s56, -v105
	v_fmac_f32_e32 v105, 0x3377d1cf, v103
	v_fmac_f32_e32 v105, 0x3f317217, v103
	v_cmp_lt_f32_e64 s[0:1], |v103|, s57
	s_nop 1
	v_cndmask_b32_e64 v103, v103, v105, s[0:1]
	v_cndmask_b32_e32 v105, 0, v90, vcc
	v_sub_f32_e32 v103, v103, v105
	v_sub_f32_e32 v103, v104, v103
	ds_read_b128 v[104:107], v102 offset:9344
	ds_read_b128 v[108:111], v102 offset:9360
	v_fmamk_f32 v103, v103, 0x3d800000, v101
	s_waitcnt lgkmcnt(1)
	v_mov_b32_e32 v112, v104
	s_waitcnt lgkmcnt(0)
	v_mov_b32_e32 v113, v108
	v_mov_b32_e32 v108, v105
	v_pk_mul_f32 v[104:105], v[16:17], v[108:109]
	v_mov_b32_e32 v108, v106
	v_pk_fma_f32 v[104:105], v[14:15], v[112:113], v[104:105]
	v_mov_b32_e32 v109, v110
	v_pk_fma_f32 v[104:105], v[12:13], v[108:109], v[104:105]
	v_mov_b32_e32 v110, v107
	v_pk_fma_f32 v[104:105], v[10:11], v[110:111], v[104:105]
	s_nop 0
	v_add_f32_e32 v104, v100, v104
	v_add_f32_e32 v114, v104, v105
	ds_read_b128 v[104:107], v102 offset:9376
	ds_read_b128 v[108:111], v102 offset:9392
	s_waitcnt lgkmcnt(1)
	v_mov_b32_e32 v112, v104
	s_waitcnt lgkmcnt(0)
	v_mov_b32_e32 v113, v108
	v_mov_b32_e32 v108, v105
	v_pk_mul_f32 v[104:105], v[8:9], v[108:109]
	v_mov_b32_e32 v108, v106
	v_pk_fma_f32 v[104:105], v[6:7], v[112:113], v[104:105]
	v_mov_b32_e32 v109, v110
	v_pk_fma_f32 v[104:105], v[2:3], v[108:109], v[104:105]
	v_mov_b32_e32 v110, v107
	v_pk_fma_f32 v[104:105], v[0:1], v[110:111], v[104:105]
	s_nop 0
	v_add_f32_e32 v104, v114, v104
	v_add_f32_e32 v104, v104, v105
	v_min_f32_e32 v105, 0, v104
	v_mul_f32_e64 v104, |v104|, s48
	v_exp_f32_e32 v104, v104
	s_nop 0
	v_add_f32_e32 v104, 1.0, v104
	v_cmp_gt_f32_e32 vcc, s49, v104
	s_nop 1
	v_cndmask_b32_e64 v106, 0, 32, vcc
	v_ldexp_f32 v104, v104, v106
	v_log_f32_e32 v104, v104
	s_nop 0
	v_mul_f32_e32 v106, 0x3f317217, v104
	v_fma_f32 v106, v104, s56, -v106
	v_fmac_f32_e32 v106, 0x3377d1cf, v104
	v_fmac_f32_e32 v106, 0x3f317217, v104
	v_cmp_lt_f32_e64 s[0:1], |v104|, s57
	s_nop 1
	v_cndmask_b32_e64 v104, v104, v106, s[0:1]
	v_cndmask_b32_e32 v106, 0, v90, vcc
	v_sub_f32_e32 v104, v104, v106
	ds_read_b128 v[106:109], v102 offset:9408
	ds_read_b128 v[110:113], v102 offset:9424
	v_sub_f32_e32 v104, v105, v104
	v_fmamk_f32 v104, v104, 0x3d800000, v103
	s_waitcnt lgkmcnt(1)
	v_mov_b32_e32 v114, v106
	s_waitcnt lgkmcnt(0)
; #define LAS __attribute__((address_space(3)))
; __device__ __forceinline__ void gla_upd_unit(LAS unsigned char* wl, const bf16* PROJ, const float* R, const float* w_gk2, const float* b_gk, float* UPD, float* DEC, int unit, int lane) {
;     ...
;     for (int t = 0; t < 64; ++t) {
;         const LAS f32x4* rr = (const LAS f32x4*)(wl + 9216) + t * 4;
;         float z = bias;
; #pragma unroll
;         for (int q = 0; q < 4; ++q) { const f32x4 rv = rr[q]; z += rv[0] * w[4 * q] + rv[1] * w[4 * q + 1] + rv[2] * w[4 * q + 2] + rv[3] * w[4 * q + 3]; }
;         la[t] = (fminf(z, 0.f) - __logf(1.0f + __expf(-fabsf(z)))) * (1.0f / 16.0f);
;         tot += la[t];
;     }
	v_mov_b32_e32 v115, v110
	v_mov_b32_e32 v110, v107
	v_pk_mul_f32 v[106:107], v[16:17], v[110:111]
	v_mov_b32_e32 v110, v108
	v_pk_fma_f32 v[106:107], v[14:15], v[114:115], v[106:107]
	v_mov_b32_e32 v111, v112
	v_pk_fma_f32 v[106:107], v[12:13], v[110:111], v[106:107]
	v_mov_b32_e32 v112, v109
	v_pk_fma_f32 v[106:107], v[10:11], v[112:113], v[106:107]
	s_nop 0
	v_add_f32_e32 v105, v100, v106
	v_add_f32_e32 v105, v105, v107
	ds_read_b128 v[106:109], v102 offset:9440
	ds_read_b128 v[110:113], v102 offset:9456
	s_waitcnt lgkmcnt(1)
	v_mov_b32_e32 v114, v106
	s_waitcnt lgkmcnt(0)
	v_mov_b32_e32 v115, v110
	v_mov_b32_e32 v110, v107
	v_pk_mul_f32 v[106:107], v[8:9], v[110:111]
	v_mov_b32_e32 v110, v108
	v_pk_fma_f32 v[106:107], v[6:7], v[114:115], v[106:107]
	v_mov_b32_e32 v111, v112
	v_pk_fma_f32 v[106:107], v[2:3], v[110:111], v[106:107]
	v_mov_b32_e32 v112, v109
	v_pk_fma_f32 v[106:107], v[0:1], v[112:113], v[106:107]
	s_nop 0
	v_add_f32_e32 v105, v105, v106
	v_add_f32_e32 v105, v105, v107
	v_min_f32_e32 v106, 0, v105
	v_mul_f32_e64 v105, |v105|, s48
	v_exp_f32_e32 v105, v105
	s_nop 0
	v_add_f32_e32 v105, 1.0, v105
	v_cmp_gt_f32_e32 vcc, s49, v105
	s_nop 1
	v_cndmask_b32_e64 v107, 0, 32, vcc
	v_ldexp_f32 v105, v105, v107
	v_log_f32_e32 v105, v105
	s_nop 0
	v_mul_f32_e32 v107, 0x3f317217, v105
	v_fma_f32 v107, v105, s56, -v107
	v_fmac_f32_e32 v107, 0x3377d1cf, v105
	v_fmac_f32_e32 v107, 0x3f317217, v105
	v_cmp_lt_f32_e64 s[0:1], |v105|, s57
	s_nop 1
	v_cndmask_b32_e64 v105, v105, v107, s[0:1]
	v_cndmask_b32_e32 v107, 0, v90, vcc
	v_sub_f32_e32 v105, v105, v107
	v_sub_f32_e32 v105, v106, v105
	ds_read_b128 v[106:109], v102 offset:9472
	ds_read_b128 v[110:113], v102 offset:9488
	v_fmamk_f32 v105, v105, 0x3d800000, v104
	s_waitcnt lgkmcnt(1)
	v_mov_b32_e32 v114, v106
	s_waitcnt lgkmcnt(0)
	v_mov_b32_e32 v115, v110
	v_mov_b32_e32 v110, v107
	v_pk_mul_f32 v[106:107], v[16:17], v[110:111]
	v_mov_b32_e32 v110, v108
	v_pk_fma_f32 v[106:107], v[14:15], v[114:115], v[106:107]
	v_mov_b32_e32 v111, v112
	v_pk_fma_f32 v[106:107], v[12:13], v[110:111], v[106:107]
	v_mov_b32_e32 v112, v109
	v_pk_fma_f32 v[106:107], v[10:11], v[112:113], v[106:107]
	s_nop 0
	v_add_f32_e32 v106, v100, v106
	v_add_f32_e32 v116, v106, v107
	ds_read_b128 v[106:109], v102 offset:9504
	ds_read_b128 v[110:113], v102 offset:9520
	s_waitcnt lgkmcnt(1)
	v_mov_b32_e32 v114, v106
	s_waitcnt lgkmcnt(0)
	v_mov_b32_e32 v115, v110
	v_mov_b32_e32 v110, v107
	v_pk_mul_f32 v[106:107], v[8:9], v[110:111]
	v_mov_b32_e32 v110, v108
	v_pk_fma_f32 v[106:107], v[6:7], v[114:115], v[106:107]
	v_mov_b32_e32 v111, v112
	v_pk_fma_f32 v[106:107], v[2:3], v[110:111], v[106:107]
	v_mov_b32_e32 v112, v109
	v_pk_fma_f32 v[106:107], v[0:1], v[112:113], v[106:107]
	s_nop 0
	v_add_f32_e32 v106, v116, v106
	v_add_f32_e32 v106, v106, v107
	v_min_f32_e32 v107, 0, v106
	v_mul_f32_e64 v106, |v106|, s48
	v_exp_f32_e32 v106, v106
	s_nop 0
	v_add_f32_e32 v106, 1.0, v106
	v_cmp_gt_f32_e32 vcc, s49, v106
	s_nop 1
	v_cndmask_b32_e64 v108, 0, 32, vcc
	v_ldexp_f32 v106, v106, v108
	v_log_f32_e32 v106, v106
	s_nop 0
	v_mul_f32_e32 v108, 0x3f317217, v106
	v_fma_f32 v108, v106, s56, -v108
	v_fmac_f32_e32 v108, 0x3377d1cf, v106
	v_fmac_f32_e32 v108, 0x3f317217, v106
	v_cmp_lt_f32_e64 s[0:1], |v106|, s57
	s_nop 1
	v_cndmask_b32_e64 v106, v106, v108, s[0:1]
	v_cndmask_b32_e32 v108, 0, v90, vcc
	v_sub_f32_e32 v106, v106, v108
	ds_read_b128 v[108:111], v102 offset:9536
	ds_read_b128 v[112:115], v102 offset:9552
	v_sub_f32_e32 v106, v107, v106
	v_fmamk_f32 v106, v106, 0x3d800000, v105
	s_waitcnt lgkmcnt(1)
	v_mov_b32_e32 v116, v108
	s_waitcnt lgkmcnt(0)
	v_mov_b32_e32 v117, v112
	v_mov_b32_e32 v112, v109
	v_pk_mul_f32 v[108:109], v[16:17], v[112:113]
	v_mov_b32_e32 v112, v110
	v_pk_fma_f32 v[108:109], v[14:15], v[116:117], v[108:109]
	v_mov_b32_e32 v113, v114
	v_pk_fma_f32 v[108:109], v[12:13], v[112:113], v[108:109]
	v_mov_b32_e32 v114, v111
	v_pk_fma_f32 v[108:109], v[10:11], v[114:115], v[108:109]
	s_nop 0
	v_add_f32_e32 v107, v100, v108
	v_add_f32_e32 v107, v107, v109
	ds_read_b128 v[108:111], v102 offset:9568
	ds_read_b128 v[112:115], v102 offset:9584
	s_waitcnt lgkmcnt(1)
	v_mov_b32_e32 v116, v108
	s_waitcnt lgkmcnt(0)
	v_mov_b32_e32 v117, v112
	v_mov_b32_e32 v112, v109
	v_pk_mul_f32 v[108:109], v[8:9], v[112:113]
	v_mov_b32_e32 v112, v110
	v_pk_fma_f32 v[108:109], v[6:7], v[116:117], v[108:109]
	v_mov_b32_e32 v113, v114
	v_pk_fma_f32 v[108:109], v[2:3], v[112:113], v[108:109]
	v_mov_b32_e32 v114, v111
	v_pk_fma_f32 v[108:109], v[0:1], v[114:115], v[108:109]
	s_nop 0
	v_add_f32_e32 v107, v107, v108
	v_add_f32_e32 v107, v107, v109
	v_min_f32_e32 v108, 0, v107
	v_mul_f32_e64 v107, |v107|, s48
	v_exp_f32_e32 v107, v107
	s_nop 0
	v_add_f32_e32 v107, 1.0, v107
	v_cmp_gt_f32_e32 vcc, s49, v107
	s_nop 1
	v_cndmask_b32_e64 v109, 0, 32, vcc
	v_ldexp_f32 v107, v107, v109
	v_log_f32_e32 v107, v107
	s_nop 0
	v_mul_f32_e32 v109, 0x3f317217, v107
	v_fma_f32 v109, v107, s56, -v109
	v_fmac_f32_e32 v109, 0x3377d1cf, v107
	v_fmac_f32_e32 v109, 0x3f317217, v107
	v_cmp_lt_f32_e64 s[0:1], |v107|, s57
	s_nop 1
	v_cndmask_b32_e64 v107, v107, v109, s[0:1]
	v_cndmask_b32_e32 v109, 0, v90, vcc
	v_sub_f32_e32 v107, v107, v109
	v_sub_f32_e32 v107, v108, v107
	ds_read_b128 v[108:111], v102 offset:9600
	ds_read_b128 v[112:115], v102 offset:9616
	v_fmamk_f32 v107, v107, 0x3d800000, v106
	s_waitcnt lgkmcnt(1)
	v_mov_b32_e32 v116, v108
	s_waitcnt lgkmcnt(0)
; #define LAS __attribute__((address_space(3)))
; __device__ __forceinline__ void gla_upd_unit(LAS unsigned char* wl, const bf16* PROJ, const float* R, const float* w_gk2, const float* b_gk, float* UPD, float* DEC, int unit, int lane) {
;     ...
;     for (int t = 0; t < 64; ++t) {
;         const LAS f32x4* rr = (const LAS f32x4*)(wl + 9216) + t * 4;
;         float z = bias;
; #pragma unroll
;         for (int q = 0; q < 4; ++q) { const f32x4 rv = rr[q]; z += rv[0] * w[4 * q] + rv[1] * w[4 * q + 1] + rv[2] * w[4 * q + 2] + rv[3] * w[4 * q + 3]; }
;         la[t] = (fminf(z, 0.f) - __logf(1.0f + __expf(-fabsf(z)))) * (1.0f / 16.0f);
;         tot += la[t];
;     }
	v_mov_b32_e32 v117, v112
	v_mov_b32_e32 v112, v109
	v_pk_mul_f32 v[108:109], v[16:17], v[112:113]
	v_mov_b32_e32 v112, v110
	v_pk_fma_f32 v[108:109], v[14:15], v[116:117], v[108:109]
	v_mov_b32_e32 v113, v114
	v_pk_fma_f32 v[108:109], v[12:13], v[112:113], v[108:109]
	v_mov_b32_e32 v114, v111
	v_pk_fma_f32 v[108:109], v[10:11], v[114:115], v[108:109]
	s_nop 0
	v_add_f32_e32 v108, v100, v108
	v_add_f32_e32 v118, v108, v109
	ds_read_b128 v[108:111], v102 offset:9632
	ds_read_b128 v[112:115], v102 offset:9648
	s_waitcnt lgkmcnt(1)
	v_mov_b32_e32 v116, v108
	s_waitcnt lgkmcnt(0)
	v_mov_b32_e32 v117, v112
	v_mov_b32_e32 v112, v109
	v_pk_mul_f32 v[108:109], v[8:9], v[112:113]
	v_mov_b32_e32 v112, v110
	v_pk_fma_f32 v[108:109], v[6:7], v[116:117], v[108:109]
	v_mov_b32_e32 v113, v114
	v_pk_fma_f32 v[108:109], v[2:3], v[112:113], v[108:109]
	v_mov_b32_e32 v114, v111
	v_pk_fma_f32 v[108:109], v[0:1], v[114:115], v[108:109]
	s_nop 0
	v_add_f32_e32 v108, v118, v108
	v_add_f32_e32 v108, v108, v109
	v_min_f32_e32 v109, 0, v108
	v_mul_f32_e64 v108, |v108|, s48
	v_exp_f32_e32 v108, v108
	s_nop 0
	v_add_f32_e32 v108, 1.0, v108
	v_cmp_gt_f32_e32 vcc, s49, v108
	s_nop 1
	v_cndmask_b32_e64 v110, 0, 32, vcc
	v_ldexp_f32 v108, v108, v110
	v_log_f32_e32 v108, v108
	s_nop 0
	v_mul_f32_e32 v110, 0x3f317217, v108
	v_fma_f32 v110, v108, s56, -v110
	v_fmac_f32_e32 v110, 0x3377d1cf, v108
	v_fmac_f32_e32 v110, 0x3f317217, v108
	v_cmp_lt_f32_e64 s[0:1], |v108|, s57
	s_nop 1
	v_cndmask_b32_e64 v108, v108, v110, s[0:1]
	v_cndmask_b32_e32 v110, 0, v90, vcc
	v_sub_f32_e32 v108, v108, v110
	ds_read_b128 v[110:113], v102 offset:9664
	ds_read_b128 v[114:117], v102 offset:9680
	v_sub_f32_e32 v108, v109, v108
	v_fmamk_f32 v109, v108, 0x3d800000, v107
	s_waitcnt lgkmcnt(1)
	v_mov_b32_e32 v118, v110
	s_waitcnt lgkmcnt(0)
	v_mov_b32_e32 v119, v114
	v_mov_b32_e32 v114, v111
	v_pk_mul_f32 v[110:111], v[16:17], v[114:115]
	v_mov_b32_e32 v114, v112
	v_pk_fma_f32 v[110:111], v[14:15], v[118:119], v[110:111]
	v_mov_b32_e32 v115, v116
	v_pk_fma_f32 v[110:111], v[12:13], v[114:115], v[110:111]
	v_mov_b32_e32 v116, v113
	v_pk_fma_f32 v[110:111], v[10:11], v[116:117], v[110:111]
	s_nop 0
	v_add_f32_e32 v108, v100, v110
	v_add_f32_e32 v108, v108, v111
	ds_read_b128 v[110:113], v102 offset:9696
	ds_read_b128 v[114:117], v102 offset:9712
	s_waitcnt lgkmcnt(1)
	v_mov_b32_e32 v118, v110
	s_waitcnt lgkmcnt(0)
	v_mov_b32_e32 v119, v114
	v_mov_b32_e32 v114, v111
	v_pk_mul_f32 v[110:111], v[8:9], v[114:115]
	v_mov_b32_e32 v114, v112
	v_pk_fma_f32 v[110:111], v[6:7], v[118:119], v[110:111]
	v_mov_b32_e32 v115, v116
	v_pk_fma_f32 v[110:111], v[2:3], v[114:115], v[110:111]
	v_mov_b32_e32 v116, v113
	v_pk_fma_f32 v[110:111], v[0:1], v[116:117], v[110:111]
	ds_read_b128 v[112:115], v102 offset:9728
	ds_read_b128 v[116:119], v102 offset:9744
	v_add_f32_e32 v108, v108, v110
	v_add_f32_e32 v108, v108, v111
	v_min_f32_e32 v110, 0, v108
	v_mul_f32_e64 v108, |v108|, s48
	v_exp_f32_e32 v108, v108
	s_waitcnt lgkmcnt(0)
	v_mov_b32_e32 v121, v116
	v_mov_b32_e32 v116, v113
	v_mov_b32_e32 v120, v112
	v_add_f32_e32 v108, 1.0, v108
	v_cmp_gt_f32_e32 vcc, s49, v108
	v_pk_mul_f32 v[112:113], v[16:17], v[116:117]
	v_mov_b32_e32 v116, v114
	v_cndmask_b32_e64 v111, 0, 32, vcc
	v_ldexp_f32 v108, v108, v111
	v_log_f32_e32 v108, v108
	v_pk_fma_f32 v[112:113], v[14:15], v[120:121], v[112:113]
	v_mov_b32_e32 v117, v118
	v_pk_fma_f32 v[112:113], v[12:13], v[116:117], v[112:113]
	v_mul_f32_e32 v111, 0x3f317217, v108
	v_fma_f32 v111, v108, s56, -v111
	v_fmac_f32_e32 v111, 0x3377d1cf, v108
	v_fmac_f32_e32 v111, 0x3f317217, v108
	v_cmp_lt_f32_e64 s[0:1], |v108|, s57
	v_mov_b32_e32 v118, v115
	v_pk_fma_f32 v[112:113], v[10:11], v[118:119], v[112:113]
	v_cndmask_b32_e64 v108, v108, v111, s[0:1]
	v_cndmask_b32_e32 v111, 0, v90, vcc
	v_sub_f32_e32 v108, v108, v111
	v_sub_f32_e32 v108, v110, v108
	v_fmamk_f32 v111, v108, 0x3d800000, v109
	v_add_f32_e32 v108, v100, v112
	v_add_f32_e32 v108, v108, v113
	ds_read_b128 v[112:115], v102 offset:9760
	ds_read_b128 v[116:119], v102 offset:9776
	s_waitcnt lgkmcnt(1)
	v_mov_b32_e32 v120, v112
	s_waitcnt lgkmcnt(0)
	v_mov_b32_e32 v121, v116
	v_mov_b32_e32 v116, v113
	v_pk_mul_f32 v[112:113], v[8:9], v[116:117]
	v_mov_b32_e32 v116, v114
	v_pk_fma_f32 v[112:113], v[6:7], v[120:121], v[112:113]
	v_mov_b32_e32 v117, v118
	v_pk_fma_f32 v[112:113], v[2:3], v[116:117], v[112:113]
	v_mov_b32_e32 v118, v115
	v_pk_fma_f32 v[112:113], v[0:1], v[118:119], v[112:113]
	s_nop 0
	v_add_f32_e32 v108, v108, v112
	v_add_f32_e32 v108, v108, v113
	v_min_f32_e32 v110, 0, v108
	v_mul_f32_e64 v108, |v108|, s48
	v_exp_f32_e32 v108, v108
	s_nop 0
	v_add_f32_e32 v108, 1.0, v108
	v_cmp_gt_f32_e32 vcc, s49, v108
	s_nop 1
	v_cndmask_b32_e64 v112, 0, 32, vcc
	v_ldexp_f32 v108, v108, v112
	v_log_f32_e32 v108, v108
	s_nop 0
	v_mul_f32_e32 v112, 0x3f317217, v108
	v_fma_f32 v112, v108, s56, -v112
	v_fmac_f32_e32 v112, 0x3377d1cf, v108
	v_fmac_f32_e32 v112, 0x3f317217, v108
	v_cmp_lt_f32_e64 s[0:1], |v108|, s57
	s_nop 1
	v_cndmask_b32_e64 v108, v108, v112, s[0:1]
	v_cndmask_b32_e32 v112, 0, v90, vcc
	v_sub_f32_e32 v108, v108, v112
	ds_read_b128 v[112:115], v102 offset:9792
	ds_read_b128 v[116:119], v102 offset:9808
	v_sub_f32_e32 v108, v110, v108
	v_fmamk_f32 v108, v108, 0x3d800000, v111
	s_waitcnt lgkmcnt(1)
	v_mov_b32_e32 v120, v112
	s_waitcnt lgkmcnt(0)
	v_mov_b32_e32 v121, v116
	v_mov_b32_e32 v116, v113
	v_pk_mul_f32 v[112:113], v[16:17], v[116:117]
	v_mov_b32_e32 v116, v114
	v_pk_fma_f32 v[112:113], v[14:15], v[120:121], v[112:113]
	v_mov_b32_e32 v117, v118
	v_pk_fma_f32 v[112:113], v[12:13], v[116:117], v[112:113]
	v_mov_b32_e32 v118, v115
	v_pk_fma_f32 v[112:113], v[10:11], v[118:119], v[112:113]
	s_nop 0
	v_add_f32_e32 v110, v100, v112
	v_add_f32_e32 v110, v110, v113
	ds_read_b128 v[112:115], v102 offset:9824
	ds_read_b128 v[116:119], v102 offset:9840
	s_waitcnt lgkmcnt(1)
; #define LAS __attribute__((address_space(3)))
; __device__ __forceinline__ void gla_upd_unit(LAS unsigned char* wl, const bf16* PROJ, const float* R, const float* w_gk2, const float* b_gk, float* UPD, float* DEC, int unit, int lane) {
;     ...
;     for (int t = 0; t < 64; ++t) {
;         const LAS f32x4* rr = (const LAS f32x4*)(wl + 9216) + t * 4;
;         float z = bias;
; #pragma unroll
;         for (int q = 0; q < 4; ++q) { const f32x4 rv = rr[q]; z += rv[0] * w[4 * q] + rv[1] * w[4 * q + 1] + rv[2] * w[4 * q + 2] + rv[3] * w[4 * q + 3]; }
;         la[t] = (fminf(z, 0.f) - __logf(1.0f + __expf(-fabsf(z)))) * (1.0f / 16.0f);
;         tot += la[t];
;     }
	v_mov_b32_e32 v120, v112
	s_waitcnt lgkmcnt(0)
	v_mov_b32_e32 v121, v116
	v_mov_b32_e32 v116, v113
	v_pk_mul_f32 v[112:113], v[8:9], v[116:117]
	v_mov_b32_e32 v116, v114
	v_pk_fma_f32 v[112:113], v[6:7], v[120:121], v[112:113]
	v_mov_b32_e32 v117, v118
	v_pk_fma_f32 v[112:113], v[2:3], v[116:117], v[112:113]
	v_mov_b32_e32 v118, v115
	v_pk_fma_f32 v[112:113], v[0:1], v[118:119], v[112:113]
	s_nop 0
	v_add_f32_e32 v110, v110, v112
	v_add_f32_e32 v110, v110, v113
	v_min_f32_e32 v112, 0, v110
	v_mul_f32_e64 v110, |v110|, s48
	v_exp_f32_e32 v110, v110
	s_nop 0
	v_add_f32_e32 v110, 1.0, v110
	v_cmp_gt_f32_e32 vcc, s49, v110
	s_nop 1
	v_cndmask_b32_e64 v113, 0, 32, vcc
	v_ldexp_f32 v110, v110, v113
	v_log_f32_e32 v110, v110
	s_nop 0
	v_mul_f32_e32 v113, 0x3f317217, v110
	v_fma_f32 v113, v110, s56, -v113
	v_fmac_f32_e32 v113, 0x3377d1cf, v110
	v_fmac_f32_e32 v113, 0x3f317217, v110
	v_cmp_lt_f32_e64 s[0:1], |v110|, s57
	s_nop 1
	v_cndmask_b32_e64 v110, v110, v113, s[0:1]
	v_cndmask_b32_e32 v113, 0, v90, vcc
	v_sub_f32_e32 v110, v110, v113
	v_sub_f32_e32 v110, v112, v110
	ds_read_b128 v[112:115], v102 offset:9856
	ds_read_b128 v[116:119], v102 offset:9872
	v_fmamk_f32 v110, v110, 0x3d800000, v108
	s_waitcnt lgkmcnt(1)
	v_mov_b32_e32 v120, v112
	s_waitcnt lgkmcnt(0)
	v_mov_b32_e32 v121, v116
	v_mov_b32_e32 v116, v113
	v_pk_mul_f32 v[112:113], v[16:17], v[116:117]
	v_mov_b32_e32 v116, v114
	v_pk_fma_f32 v[112:113], v[14:15], v[120:121], v[112:113]
	v_mov_b32_e32 v117, v118
	v_pk_fma_f32 v[112:113], v[12:13], v[116:117], v[112:113]
	v_mov_b32_e32 v118, v115
	v_pk_fma_f32 v[112:113], v[10:11], v[118:119], v[112:113]
	s_nop 0
	v_add_f32_e32 v112, v100, v112
	v_add_f32_e32 v122, v112, v113
	ds_read_b128 v[112:115], v102 offset:9888
	ds_read_b128 v[116:119], v102 offset:9904
	s_waitcnt lgkmcnt(1)
	v_mov_b32_e32 v120, v112
	s_waitcnt lgkmcnt(0)
	v_mov_b32_e32 v121, v116
	v_mov_b32_e32 v116, v113
	v_pk_mul_f32 v[112:113], v[8:9], v[116:117]
	v_mov_b32_e32 v116, v114
	v_pk_fma_f32 v[112:113], v[6:7], v[120:121], v[112:113]
	v_mov_b32_e32 v117, v118
	v_pk_fma_f32 v[112:113], v[2:3], v[116:117], v[112:113]
	v_mov_b32_e32 v118, v115
	v_pk_fma_f32 v[112:113], v[0:1], v[118:119], v[112:113]
	s_nop 0
	v_add_f32_e32 v112, v122, v112
	v_add_f32_e32 v112, v112, v113
	v_min_f32_e32 v113, 0, v112
	v_mul_f32_e64 v112, |v112|, s48
	v_exp_f32_e32 v112, v112
	s_nop 0
	v_add_f32_e32 v112, 1.0, v112
	v_cmp_gt_f32_e32 vcc, s49, v112
	s_nop 1
	v_cndmask_b32_e64 v114, 0, 32, vcc
	v_ldexp_f32 v112, v112, v114
	v_log_f32_e32 v112, v112
	s_nop 0
	v_mul_f32_e32 v114, 0x3f317217, v112
	v_fma_f32 v114, v112, s56, -v114
	v_fmac_f32_e32 v114, 0x3377d1cf, v112
	v_fmac_f32_e32 v114, 0x3f317217, v112
	v_cmp_lt_f32_e64 s[0:1], |v112|, s57
	s_nop 1
	v_cndmask_b32_e64 v112, v112, v114, s[0:1]
	v_cndmask_b32_e32 v114, 0, v90, vcc
	v_sub_f32_e32 v112, v112, v114
	ds_read_b128 v[114:117], v102 offset:9920
	ds_read_b128 v[118:121], v102 offset:9936
	v_sub_f32_e32 v112, v113, v112
	v_fmamk_f32 v112, v112, 0x3d800000, v110
	s_waitcnt lgkmcnt(1)
	v_mov_b32_e32 v122, v114
	s_waitcnt lgkmcnt(0)
	v_mov_b32_e32 v123, v118
	v_mov_b32_e32 v118, v115
	v_pk_mul_f32 v[114:115], v[16:17], v[118:119]
	v_mov_b32_e32 v118, v116
	v_pk_fma_f32 v[114:115], v[14:15], v[122:123], v[114:115]
	v_mov_b32_e32 v119, v120
	v_pk_fma_f32 v[114:115], v[12:13], v[118:119], v[114:115]
	v_mov_b32_e32 v120, v117
	v_pk_fma_f32 v[114:115], v[10:11], v[120:121], v[114:115]
	s_nop 0
	v_add_f32_e32 v113, v100, v114
	v_add_f32_e32 v113, v113, v115
	ds_read_b128 v[114:117], v102 offset:9952
	ds_read_b128 v[118:121], v102 offset:9968
	s_waitcnt lgkmcnt(1)
	v_mov_b32_e32 v122, v114
	s_waitcnt lgkmcnt(0)
	v_mov_b32_e32 v123, v118
	v_mov_b32_e32 v118, v115
	v_pk_mul_f32 v[114:115], v[8:9], v[118:119]
	v_mov_b32_e32 v118, v116
	v_pk_fma_f32 v[114:115], v[6:7], v[122:123], v[114:115]
	v_mov_b32_e32 v119, v120
	v_pk_fma_f32 v[114:115], v[2:3], v[118:119], v[114:115]
	v_mov_b32_e32 v120, v117
	v_pk_fma_f32 v[114:115], v[0:1], v[120:121], v[114:115]
	s_nop 0
	v_add_f32_e32 v113, v113, v114
	v_add_f32_e32 v113, v113, v115
	v_min_f32_e32 v114, 0, v113
	v_mul_f32_e64 v113, |v113|, s48
	v_exp_f32_e32 v113, v113
	s_nop 0
	v_add_f32_e32 v113, 1.0, v113
	v_cmp_gt_f32_e32 vcc, s49, v113
	s_nop 1
	v_cndmask_b32_e64 v115, 0, 32, vcc
	v_ldexp_f32 v113, v113, v115
	v_log_f32_e32 v113, v113
	s_nop 0
	v_mul_f32_e32 v115, 0x3f317217, v113
	v_fma_f32 v115, v113, s56, -v115
	v_fmac_f32_e32 v115, 0x3377d1cf, v113
	v_fmac_f32_e32 v115, 0x3f317217, v113
	v_cmp_lt_f32_e64 s[0:1], |v113|, s57
	s_nop 1
	v_cndmask_b32_e64 v113, v113, v115, s[0:1]
	v_cndmask_b32_e32 v115, 0, v90, vcc
	v_sub_f32_e32 v113, v113, v115
	v_sub_f32_e32 v113, v114, v113
	ds_read_b128 v[114:117], v102 offset:9984
	ds_read_b128 v[118:121], v102 offset:10000
	v_fmamk_f32 v113, v113, 0x3d800000, v112
	s_waitcnt lgkmcnt(1)
	v_mov_b32_e32 v122, v114
	s_waitcnt lgkmcnt(0)
	v_mov_b32_e32 v123, v118
	v_mov_b32_e32 v118, v115
	v_pk_mul_f32 v[114:115], v[16:17], v[118:119]
	v_mov_b32_e32 v118, v116
	v_pk_fma_f32 v[114:115], v[14:15], v[122:123], v[114:115]
	v_mov_b32_e32 v119, v120
	v_pk_fma_f32 v[114:115], v[12:13], v[118:119], v[114:115]
	v_mov_b32_e32 v120, v117
	v_pk_fma_f32 v[114:115], v[10:11], v[120:121], v[114:115]
	s_nop 0
	v_add_f32_e32 v114, v100, v114
	v_add_f32_e32 v124, v114, v115
	ds_read_b128 v[114:117], v102 offset:10016
	ds_read_b128 v[118:121], v102 offset:10032
	s_waitcnt lgkmcnt(1)
	v_mov_b32_e32 v122, v114
	s_waitcnt lgkmcnt(0)
; #define LAS __attribute__((address_space(3)))
; __device__ __forceinline__ void gla_upd_unit(LAS unsigned char* wl, const bf16* PROJ, const float* R, const float* w_gk2, const float* b_gk, float* UPD, float* DEC, int unit, int lane) {
;     ...
;     for (int t = 0; t < 64; ++t) {
;         const LAS f32x4* rr = (const LAS f32x4*)(wl + 9216) + t * 4;
;         float z = bias;
; #pragma unroll
;         for (int q = 0; q < 4; ++q) { const f32x4 rv = rr[q]; z += rv[0] * w[4 * q] + rv[1] * w[4 * q + 1] + rv[2] * w[4 * q + 2] + rv[3] * w[4 * q + 3]; }
;         la[t] = (fminf(z, 0.f) - __logf(1.0f + __expf(-fabsf(z)))) * (1.0f / 16.0f);
;         tot += la[t];
;     }
	v_mov_b32_e32 v123, v118
	v_mov_b32_e32 v118, v115
	v_pk_mul_f32 v[114:115], v[8:9], v[118:119]
	v_mov_b32_e32 v118, v116
	v_pk_fma_f32 v[114:115], v[6:7], v[122:123], v[114:115]
	v_mov_b32_e32 v119, v120
	v_pk_fma_f32 v[114:115], v[2:3], v[118:119], v[114:115]
	v_mov_b32_e32 v120, v117
	v_pk_fma_f32 v[114:115], v[0:1], v[120:121], v[114:115]
	s_nop 0
	v_add_f32_e32 v114, v124, v114
	v_add_f32_e32 v114, v114, v115
	v_min_f32_e32 v115, 0, v114
	v_mul_f32_e64 v114, |v114|, s48
	v_exp_f32_e32 v114, v114
	s_nop 0
	v_add_f32_e32 v114, 1.0, v114
	v_cmp_gt_f32_e32 vcc, s49, v114
	s_nop 1
	v_cndmask_b32_e64 v116, 0, 32, vcc
	v_ldexp_f32 v114, v114, v116
	v_log_f32_e32 v114, v114
	s_nop 0
	v_mul_f32_e32 v116, 0x3f317217, v114
	v_fma_f32 v116, v114, s56, -v116
	v_fmac_f32_e32 v116, 0x3377d1cf, v114
	v_fmac_f32_e32 v116, 0x3f317217, v114
	v_cmp_lt_f32_e64 s[0:1], |v114|, s57
	s_nop 1
	v_cndmask_b32_e64 v114, v114, v116, s[0:1]
	v_cndmask_b32_e32 v116, 0, v90, vcc
	v_sub_f32_e32 v114, v114, v116
	ds_read_b128 v[116:119], v102 offset:10048
	ds_read_b128 v[120:123], v102 offset:10064
	v_sub_f32_e32 v114, v115, v114
	v_fmamk_f32 v114, v114, 0x3d800000, v113
	s_waitcnt lgkmcnt(1)
	v_mov_b32_e32 v124, v116
	s_waitcnt lgkmcnt(0)
	v_mov_b32_e32 v125, v120
	v_mov_b32_e32 v120, v117
	v_pk_mul_f32 v[116:117], v[16:17], v[120:121]
	v_mov_b32_e32 v120, v118
	v_pk_fma_f32 v[116:117], v[14:15], v[124:125], v[116:117]
	v_mov_b32_e32 v121, v122
	v_pk_fma_f32 v[116:117], v[12:13], v[120:121], v[116:117]
	v_mov_b32_e32 v122, v119
	v_pk_fma_f32 v[116:117], v[10:11], v[122:123], v[116:117]
	s_nop 0
	v_add_f32_e32 v115, v100, v116
	v_add_f32_e32 v115, v115, v117
	ds_read_b128 v[116:119], v102 offset:10080
	ds_read_b128 v[120:123], v102 offset:10096
	s_waitcnt lgkmcnt(1)
	v_mov_b32_e32 v124, v116
	s_waitcnt lgkmcnt(0)
	v_mov_b32_e32 v125, v120
	v_mov_b32_e32 v120, v117
	v_pk_mul_f32 v[116:117], v[8:9], v[120:121]
	v_mov_b32_e32 v120, v118
	v_pk_fma_f32 v[116:117], v[6:7], v[124:125], v[116:117]
	v_mov_b32_e32 v121, v122
	v_pk_fma_f32 v[116:117], v[2:3], v[120:121], v[116:117]
	v_mov_b32_e32 v122, v119
	v_pk_fma_f32 v[116:117], v[0:1], v[122:123], v[116:117]
	s_nop 0
	v_add_f32_e32 v115, v115, v116
	v_add_f32_e32 v115, v115, v117
	v_min_f32_e32 v116, 0, v115
	v_mul_f32_e64 v115, |v115|, s48
	v_exp_f32_e32 v115, v115
	s_nop 0
	v_add_f32_e32 v115, 1.0, v115
	v_cmp_gt_f32_e32 vcc, s49, v115
	s_nop 1
	v_cndmask_b32_e64 v117, 0, 32, vcc
	v_ldexp_f32 v115, v115, v117
	v_log_f32_e32 v115, v115
	s_nop 0
	v_mul_f32_e32 v117, 0x3f317217, v115
	v_fma_f32 v117, v115, s56, -v117
	v_fmac_f32_e32 v117, 0x3377d1cf, v115
	v_fmac_f32_e32 v117, 0x3f317217, v115
	v_cmp_lt_f32_e64 s[0:1], |v115|, s57
	s_nop 1
	v_cndmask_b32_e64 v115, v115, v117, s[0:1]
	v_cndmask_b32_e32 v117, 0, v90, vcc
	v_sub_f32_e32 v115, v115, v117
	v_sub_f32_e32 v115, v116, v115
	ds_read_b128 v[116:119], v102 offset:10112
	ds_read_b128 v[120:123], v102 offset:10128
	v_fmamk_f32 v115, v115, 0x3d800000, v114
	s_waitcnt lgkmcnt(1)
	v_mov_b32_e32 v124, v116
	s_waitcnt lgkmcnt(0)
	v_mov_b32_e32 v125, v120
	v_mov_b32_e32 v120, v117
	v_pk_mul_f32 v[116:117], v[16:17], v[120:121]
	v_mov_b32_e32 v120, v118
	v_pk_fma_f32 v[116:117], v[14:15], v[124:125], v[116:117]
	v_mov_b32_e32 v121, v122
	v_pk_fma_f32 v[116:117], v[12:13], v[120:121], v[116:117]
	v_mov_b32_e32 v122, v119
	v_pk_fma_f32 v[116:117], v[10:11], v[122:123], v[116:117]
	s_nop 0
	v_add_f32_e32 v116, v100, v116
	v_add_f32_e32 v126, v116, v117
	ds_read_b128 v[116:119], v102 offset:10144
	ds_read_b128 v[120:123], v102 offset:10160
	s_waitcnt lgkmcnt(1)
	v_mov_b32_e32 v124, v116
	s_waitcnt lgkmcnt(0)
	v_mov_b32_e32 v125, v120
	v_mov_b32_e32 v120, v117
	v_pk_mul_f32 v[116:117], v[8:9], v[120:121]
	v_mov_b32_e32 v120, v118
	v_pk_fma_f32 v[116:117], v[6:7], v[124:125], v[116:117]
	v_mov_b32_e32 v121, v122
	v_pk_fma_f32 v[116:117], v[2:3], v[120:121], v[116:117]
	v_mov_b32_e32 v122, v119
	v_pk_fma_f32 v[116:117], v[0:1], v[122:123], v[116:117]
	s_nop 0
	v_add_f32_e32 v116, v126, v116
	v_add_f32_e32 v116, v116, v117
	v_min_f32_e32 v117, 0, v116
	v_mul_f32_e64 v116, |v116|, s48
	v_exp_f32_e32 v116, v116
	s_nop 0
	v_add_f32_e32 v116, 1.0, v116
	v_cmp_gt_f32_e32 vcc, s49, v116
	s_nop 1
	v_cndmask_b32_e64 v118, 0, 32, vcc
	v_ldexp_f32 v116, v116, v118
	v_log_f32_e32 v116, v116
	s_nop 0
	v_mul_f32_e32 v118, 0x3f317217, v116
	v_fma_f32 v118, v116, s56, -v118
	v_fmac_f32_e32 v118, 0x3377d1cf, v116
	v_fmac_f32_e32 v118, 0x3f317217, v116
	v_cmp_lt_f32_e64 s[0:1], |v116|, s57
	s_nop 1
	v_cndmask_b32_e64 v116, v116, v118, s[0:1]
	v_cndmask_b32_e32 v118, 0, v90, vcc
	v_sub_f32_e32 v116, v116, v118
	ds_read_b128 v[118:121], v102 offset:10176
	ds_read_b128 v[122:125], v102 offset:10192
	v_sub_f32_e32 v116, v117, v116
	v_fmamk_f32 v116, v116, 0x3d800000, v115
	s_waitcnt lgkmcnt(1)
	v_mov_b32_e32 v126, v118
	s_waitcnt lgkmcnt(0)
	v_mov_b32_e32 v127, v122
	v_mov_b32_e32 v122, v119
	v_pk_mul_f32 v[118:119], v[16:17], v[122:123]
	v_mov_b32_e32 v122, v120
	v_pk_fma_f32 v[118:119], v[14:15], v[126:127], v[118:119]
	v_mov_b32_e32 v123, v124
	v_pk_fma_f32 v[118:119], v[12:13], v[122:123], v[118:119]
	v_mov_b32_e32 v124, v121
	v_pk_fma_f32 v[118:119], v[10:11], v[124:125], v[118:119]
	s_nop 0
	v_add_f32_e32 v117, v100, v118
	v_add_f32_e32 v117, v117, v119
	ds_read_b128 v[118:121], v102 offset:10208
	ds_read_b128 v[122:125], v102 offset:10224
	s_waitcnt lgkmcnt(1)
	v_mov_b32_e32 v126, v118
	s_waitcnt lgkmcnt(0)
; #define LAS __attribute__((address_space(3)))
; __device__ __forceinline__ void gla_upd_unit(LAS unsigned char* wl, const bf16* PROJ, const float* R, const float* w_gk2, const float* b_gk, float* UPD, float* DEC, int unit, int lane) {
;     ...
;     for (int t = 0; t < 64; ++t) {
;         const LAS f32x4* rr = (const LAS f32x4*)(wl + 9216) + t * 4;
;         float z = bias;
; #pragma unroll
;         for (int q = 0; q < 4; ++q) { const f32x4 rv = rr[q]; z += rv[0] * w[4 * q] + rv[1] * w[4 * q + 1] + rv[2] * w[4 * q + 2] + rv[3] * w[4 * q + 3]; }
;         la[t] = (fminf(z, 0.f) - __logf(1.0f + __expf(-fabsf(z)))) * (1.0f / 16.0f);
;         tot += la[t];
;     }
	v_mov_b32_e32 v127, v122
	v_mov_b32_e32 v122, v119
	v_pk_mul_f32 v[118:119], v[8:9], v[122:123]
	v_mov_b32_e32 v122, v120
	v_pk_fma_f32 v[118:119], v[6:7], v[126:127], v[118:119]
	v_mov_b32_e32 v123, v124
	v_pk_fma_f32 v[118:119], v[2:3], v[122:123], v[118:119]
	v_mov_b32_e32 v124, v121
	v_pk_fma_f32 v[118:119], v[0:1], v[124:125], v[118:119]
	s_nop 0
	v_add_f32_e32 v117, v117, v118
	v_add_f32_e32 v117, v117, v119
	v_min_f32_e32 v118, 0, v117
	v_mul_f32_e64 v117, |v117|, s48
	v_exp_f32_e32 v117, v117
	s_nop 0
	v_add_f32_e32 v117, 1.0, v117
	v_cmp_gt_f32_e32 vcc, s49, v117
	s_nop 1
	v_cndmask_b32_e64 v119, 0, 32, vcc
	v_ldexp_f32 v117, v117, v119
	v_log_f32_e32 v117, v117
	s_nop 0
	v_mul_f32_e32 v119, 0x3f317217, v117
	v_fma_f32 v119, v117, s56, -v119
	v_fmac_f32_e32 v119, 0x3377d1cf, v117
	v_fmac_f32_e32 v119, 0x3f317217, v117
	v_cmp_lt_f32_e64 s[0:1], |v117|, s57
	s_nop 1
	v_cndmask_b32_e64 v117, v117, v119, s[0:1]
	v_cndmask_b32_e32 v119, 0, v90, vcc
	v_sub_f32_e32 v117, v117, v119
	v_sub_f32_e32 v117, v118, v117
	ds_read_b128 v[118:121], v102 offset:10240
	ds_read_b128 v[122:125], v102 offset:10256
	v_fmamk_f32 v117, v117, 0x3d800000, v116
	s_waitcnt lgkmcnt(1)
	v_mov_b32_e32 v126, v118
	s_waitcnt lgkmcnt(0)
	v_mov_b32_e32 v127, v122
	v_mov_b32_e32 v122, v119
	v_pk_mul_f32 v[118:119], v[16:17], v[122:123]
	v_mov_b32_e32 v122, v120
	v_pk_fma_f32 v[118:119], v[14:15], v[126:127], v[118:119]
	v_mov_b32_e32 v123, v124
	v_pk_fma_f32 v[118:119], v[12:13], v[122:123], v[118:119]
	v_mov_b32_e32 v124, v121
	v_pk_fma_f32 v[118:119], v[10:11], v[124:125], v[118:119]
	s_nop 0
	v_add_f32_e32 v118, v100, v118
	v_add_f32_e32 v128, v118, v119
	ds_read_b128 v[118:121], v102 offset:10272
	ds_read_b128 v[122:125], v102 offset:10288
	s_waitcnt lgkmcnt(1)
	v_mov_b32_e32 v126, v118
	s_waitcnt lgkmcnt(0)
	v_mov_b32_e32 v127, v122
	v_mov_b32_e32 v122, v119
	v_pk_mul_f32 v[118:119], v[8:9], v[122:123]
	v_mov_b32_e32 v122, v120
	v_pk_fma_f32 v[118:119], v[6:7], v[126:127], v[118:119]
	v_mov_b32_e32 v123, v124
	v_pk_fma_f32 v[118:119], v[2:3], v[122:123], v[118:119]
	v_mov_b32_e32 v124, v121
	v_pk_fma_f32 v[118:119], v[0:1], v[124:125], v[118:119]
	s_nop 0
	v_add_f32_e32 v118, v128, v118
	v_add_f32_e32 v118, v118, v119
	v_min_f32_e32 v119, 0, v118
	v_mul_f32_e64 v118, |v118|, s48
	v_exp_f32_e32 v118, v118
	s_nop 0
	v_add_f32_e32 v118, 1.0, v118
	v_cmp_gt_f32_e32 vcc, s49, v118
	s_nop 1
	v_cndmask_b32_e64 v120, 0, 32, vcc
	v_ldexp_f32 v118, v118, v120
	v_log_f32_e32 v118, v118
	s_nop 0
	v_mul_f32_e32 v120, 0x3f317217, v118
	v_fma_f32 v120, v118, s56, -v120
	v_fmac_f32_e32 v120, 0x3377d1cf, v118
	v_fmac_f32_e32 v120, 0x3f317217, v118
	v_cmp_lt_f32_e64 s[0:1], |v118|, s57
	s_nop 1
	v_cndmask_b32_e64 v118, v118, v120, s[0:1]
	v_cndmask_b32_e32 v120, 0, v90, vcc
	v_sub_f32_e32 v118, v118, v120
	ds_read_b128 v[120:123], v102 offset:10304
	ds_read_b128 v[124:127], v102 offset:10320
	v_sub_f32_e32 v118, v119, v118
	v_fmamk_f32 v118, v118, 0x3d800000, v117
	s_waitcnt lgkmcnt(1)
	v_mov_b32_e32 v128, v120
	s_waitcnt lgkmcnt(0)
	v_mov_b32_e32 v129, v124
	v_mov_b32_e32 v124, v121
	v_pk_mul_f32 v[120:121], v[16:17], v[124:125]
	v_mov_b32_e32 v124, v122
	v_pk_fma_f32 v[120:121], v[14:15], v[128:129], v[120:121]
	v_mov_b32_e32 v125, v126
	v_pk_fma_f32 v[120:121], v[12:13], v[124:125], v[120:121]
	v_mov_b32_e32 v126, v123
	v_pk_fma_f32 v[120:121], v[10:11], v[126:127], v[120:121]
	s_nop 0
	v_add_f32_e32 v119, v100, v120
	v_add_f32_e32 v119, v119, v121
	ds_read_b128 v[120:123], v102 offset:10336
	ds_read_b128 v[124:127], v102 offset:10352
	s_waitcnt lgkmcnt(1)
	v_mov_b32_e32 v128, v120
	s_waitcnt lgkmcnt(0)
	v_mov_b32_e32 v129, v124
	v_mov_b32_e32 v124, v121
	v_pk_mul_f32 v[120:121], v[8:9], v[124:125]
	v_mov_b32_e32 v124, v122
	v_pk_fma_f32 v[120:121], v[6:7], v[128:129], v[120:121]
	v_mov_b32_e32 v125, v126
	v_pk_fma_f32 v[120:121], v[2:3], v[124:125], v[120:121]
	v_mov_b32_e32 v126, v123
	v_pk_fma_f32 v[120:121], v[0:1], v[126:127], v[120:121]
	s_nop 0
	v_add_f32_e32 v119, v119, v120
	v_add_f32_e32 v119, v119, v121
	v_min_f32_e32 v120, 0, v119
	v_mul_f32_e64 v119, |v119|, s48
	v_exp_f32_e32 v119, v119
	s_nop 0
	v_add_f32_e32 v119, 1.0, v119
	v_cmp_gt_f32_e32 vcc, s49, v119
	s_nop 1
	v_cndmask_b32_e64 v121, 0, 32, vcc
	v_ldexp_f32 v119, v119, v121
	v_log_f32_e32 v119, v119
	s_nop 0
	v_mul_f32_e32 v121, 0x3f317217, v119
	v_fma_f32 v121, v119, s56, -v121
	v_fmac_f32_e32 v121, 0x3377d1cf, v119
	v_fmac_f32_e32 v121, 0x3f317217, v119
	v_cmp_lt_f32_e64 s[0:1], |v119|, s57
	s_nop 1
	v_cndmask_b32_e64 v119, v119, v121, s[0:1]
	v_cndmask_b32_e32 v121, 0, v90, vcc
	v_sub_f32_e32 v119, v119, v121
	v_sub_f32_e32 v119, v120, v119
	ds_read_b128 v[120:123], v102 offset:10368
	ds_read_b128 v[124:127], v102 offset:10384
	v_fmamk_f32 v119, v119, 0x3d800000, v118
	s_waitcnt lgkmcnt(1)
	v_mov_b32_e32 v128, v120
	s_waitcnt lgkmcnt(0)
	v_mov_b32_e32 v129, v124
	v_mov_b32_e32 v124, v121
	v_pk_mul_f32 v[120:121], v[16:17], v[124:125]
	v_mov_b32_e32 v124, v122
	v_pk_fma_f32 v[120:121], v[14:15], v[128:129], v[120:121]
	v_mov_b32_e32 v125, v126
	v_pk_fma_f32 v[120:121], v[12:13], v[124:125], v[120:121]
	v_mov_b32_e32 v126, v123
	v_pk_fma_f32 v[120:121], v[10:11], v[126:127], v[120:121]
	s_nop 0
	v_add_f32_e32 v120, v100, v120
	v_add_f32_e32 v130, v120, v121
	ds_read_b128 v[120:123], v102 offset:10400
	ds_read_b128 v[124:127], v102 offset:10416
	s_waitcnt lgkmcnt(1)
	v_mov_b32_e32 v128, v120
	s_waitcnt lgkmcnt(0)
; #define LAS __attribute__((address_space(3)))
; __device__ __forceinline__ void gla_upd_unit(LAS unsigned char* wl, const bf16* PROJ, const float* R, const float* w_gk2, const float* b_gk, float* UPD, float* DEC, int unit, int lane) {
;     ...
;     for (int t = 0; t < 64; ++t) {
;         const LAS f32x4* rr = (const LAS f32x4*)(wl + 9216) + t * 4;
;         float z = bias;
; #pragma unroll
;         for (int q = 0; q < 4; ++q) { const f32x4 rv = rr[q]; z += rv[0] * w[4 * q] + rv[1] * w[4 * q + 1] + rv[2] * w[4 * q + 2] + rv[3] * w[4 * q + 3]; }
;         la[t] = (fminf(z, 0.f) - __logf(1.0f + __expf(-fabsf(z)))) * (1.0f / 16.0f);
;         tot += la[t];
;     }
	v_mov_b32_e32 v129, v124
	v_mov_b32_e32 v124, v121
	v_pk_mul_f32 v[120:121], v[8:9], v[124:125]
	v_mov_b32_e32 v124, v122
	v_pk_fma_f32 v[120:121], v[6:7], v[128:129], v[120:121]
	v_mov_b32_e32 v125, v126
	v_pk_fma_f32 v[120:121], v[2:3], v[124:125], v[120:121]
	v_mov_b32_e32 v126, v123
	v_pk_fma_f32 v[120:121], v[0:1], v[126:127], v[120:121]
	s_nop 0
	v_add_f32_e32 v120, v130, v120
	v_add_f32_e32 v120, v120, v121
	v_min_f32_e32 v121, 0, v120
	v_mul_f32_e64 v120, |v120|, s48
	v_exp_f32_e32 v120, v120
	s_nop 0
	v_add_f32_e32 v120, 1.0, v120
	v_cmp_gt_f32_e32 vcc, s49, v120
	s_nop 1
	v_cndmask_b32_e64 v122, 0, 32, vcc
	v_ldexp_f32 v120, v120, v122
	v_log_f32_e32 v120, v120
	s_nop 0
	v_mul_f32_e32 v122, 0x3f317217, v120
	v_fma_f32 v122, v120, s56, -v122
	v_fmac_f32_e32 v122, 0x3377d1cf, v120
	v_fmac_f32_e32 v122, 0x3f317217, v120
	v_cmp_lt_f32_e64 s[0:1], |v120|, s57
	s_nop 1
	v_cndmask_b32_e64 v120, v120, v122, s[0:1]
	v_cndmask_b32_e32 v122, 0, v90, vcc
	v_sub_f32_e32 v120, v120, v122
	ds_read_b128 v[122:125], v102 offset:10432
	ds_read_b128 v[126:129], v102 offset:10448
	v_sub_f32_e32 v120, v121, v120
	v_fmamk_f32 v120, v120, 0x3d800000, v119
	s_waitcnt lgkmcnt(1)
	v_mov_b32_e32 v130, v122
	s_waitcnt lgkmcnt(0)
	v_mov_b32_e32 v131, v126
	v_mov_b32_e32 v126, v123
	v_pk_mul_f32 v[122:123], v[16:17], v[126:127]
	v_mov_b32_e32 v126, v124
	v_pk_fma_f32 v[122:123], v[14:15], v[130:131], v[122:123]
	v_mov_b32_e32 v127, v128
	v_pk_fma_f32 v[122:123], v[12:13], v[126:127], v[122:123]
	v_mov_b32_e32 v128, v125
	v_pk_fma_f32 v[122:123], v[10:11], v[128:129], v[122:123]
	s_nop 0
	v_add_f32_e32 v121, v100, v122
	v_add_f32_e32 v121, v121, v123
	ds_read_b128 v[122:125], v102 offset:10464
	ds_read_b128 v[126:129], v102 offset:10480
	s_waitcnt lgkmcnt(1)
	v_mov_b32_e32 v130, v122
	s_waitcnt lgkmcnt(0)
	v_mov_b32_e32 v131, v126
	v_mov_b32_e32 v126, v123
	v_pk_mul_f32 v[122:123], v[8:9], v[126:127]
	v_mov_b32_e32 v126, v124
	v_pk_fma_f32 v[122:123], v[6:7], v[130:131], v[122:123]
	v_mov_b32_e32 v127, v128
	v_pk_fma_f32 v[122:123], v[2:3], v[126:127], v[122:123]
	v_mov_b32_e32 v128, v125
	v_pk_fma_f32 v[122:123], v[0:1], v[128:129], v[122:123]
	s_nop 0
	v_add_f32_e32 v121, v121, v122
	v_add_f32_e32 v121, v121, v123
	v_min_f32_e32 v122, 0, v121
	v_mul_f32_e64 v121, |v121|, s48
	v_exp_f32_e32 v121, v121
	s_nop 0
	v_add_f32_e32 v121, 1.0, v121
	v_cmp_gt_f32_e32 vcc, s49, v121
	s_nop 1
	v_cndmask_b32_e64 v123, 0, 32, vcc
	v_ldexp_f32 v121, v121, v123
	v_log_f32_e32 v121, v121
	s_nop 0
	v_mul_f32_e32 v123, 0x3f317217, v121
	v_fma_f32 v123, v121, s56, -v123
	v_fmac_f32_e32 v123, 0x3377d1cf, v121
	v_fmac_f32_e32 v123, 0x3f317217, v121
	v_cmp_lt_f32_e64 s[0:1], |v121|, s57
	s_nop 1
	v_cndmask_b32_e64 v121, v121, v123, s[0:1]
	v_cndmask_b32_e32 v123, 0, v90, vcc
	v_sub_f32_e32 v121, v121, v123
	v_sub_f32_e32 v121, v122, v121
	ds_read_b128 v[122:125], v102 offset:10496
	ds_read_b128 v[126:129], v102 offset:10512
	v_fmamk_f32 v121, v121, 0x3d800000, v120
	s_waitcnt lgkmcnt(1)
	v_mov_b32_e32 v130, v122
	s_waitcnt lgkmcnt(0)
	v_mov_b32_e32 v131, v126
	v_mov_b32_e32 v126, v123
	v_pk_mul_f32 v[122:123], v[16:17], v[126:127]
	v_mov_b32_e32 v126, v124
	v_pk_fma_f32 v[122:123], v[14:15], v[130:131], v[122:123]
	v_mov_b32_e32 v127, v128
	v_pk_fma_f32 v[122:123], v[12:13], v[126:127], v[122:123]
	v_mov_b32_e32 v128, v125
	v_pk_fma_f32 v[122:123], v[10:11], v[128:129], v[122:123]
	s_nop 0
	v_add_f32_e32 v122, v100, v122
	v_add_f32_e32 v132, v122, v123
	ds_read_b128 v[122:125], v102 offset:10528
	ds_read_b128 v[126:129], v102 offset:10544
	s_waitcnt lgkmcnt(1)
	v_mov_b32_e32 v130, v122
	s_waitcnt lgkmcnt(0)
	v_mov_b32_e32 v131, v126
	v_mov_b32_e32 v126, v123
	v_pk_mul_f32 v[122:123], v[8:9], v[126:127]
	v_mov_b32_e32 v126, v124
	v_pk_fma_f32 v[122:123], v[6:7], v[130:131], v[122:123]
	v_mov_b32_e32 v127, v128
	v_pk_fma_f32 v[122:123], v[2:3], v[126:127], v[122:123]
	v_mov_b32_e32 v128, v125
	v_pk_fma_f32 v[122:123], v[0:1], v[128:129], v[122:123]
	s_nop 0
	v_add_f32_e32 v122, v132, v122
	v_add_f32_e32 v122, v122, v123
	v_min_f32_e32 v123, 0, v122
	v_mul_f32_e64 v122, |v122|, s48
	v_exp_f32_e32 v122, v122
	s_nop 0
	v_add_f32_e32 v122, 1.0, v122
	v_cmp_gt_f32_e32 vcc, s49, v122
	s_nop 1
	v_cndmask_b32_e64 v124, 0, 32, vcc
	v_ldexp_f32 v122, v122, v124
	v_log_f32_e32 v122, v122
	s_nop 0
	v_mul_f32_e32 v124, 0x3f317217, v122
	v_fma_f32 v124, v122, s56, -v124
	v_fmac_f32_e32 v124, 0x3377d1cf, v122
	v_fmac_f32_e32 v124, 0x3f317217, v122
	v_cmp_lt_f32_e64 s[0:1], |v122|, s57
	s_nop 1
	v_cndmask_b32_e64 v122, v122, v124, s[0:1]
	v_cndmask_b32_e32 v124, 0, v90, vcc
	v_sub_f32_e32 v122, v122, v124
	ds_read_b128 v[124:127], v102 offset:10560
	ds_read_b128 v[128:131], v102 offset:10576
	v_sub_f32_e32 v122, v123, v122
	v_fmamk_f32 v122, v122, 0x3d800000, v121
	s_waitcnt lgkmcnt(1)
	v_mov_b32_e32 v132, v124
	s_waitcnt lgkmcnt(0)
	v_mov_b32_e32 v133, v128
	v_mov_b32_e32 v128, v125
	v_pk_mul_f32 v[124:125], v[16:17], v[128:129]
	v_mov_b32_e32 v128, v126
	v_pk_fma_f32 v[124:125], v[14:15], v[132:133], v[124:125]
	v_mov_b32_e32 v129, v130
	v_pk_fma_f32 v[124:125], v[12:13], v[128:129], v[124:125]
	v_mov_b32_e32 v130, v127
	v_pk_fma_f32 v[124:125], v[10:11], v[130:131], v[124:125]
	s_nop 0
	v_add_f32_e32 v123, v100, v124
	v_add_f32_e32 v123, v123, v125
	ds_read_b128 v[124:127], v102 offset:10592
	ds_read_b128 v[128:131], v102 offset:10608
	s_waitcnt lgkmcnt(1)
	v_mov_b32_e32 v132, v124
	s_waitcnt lgkmcnt(0)
; #define LAS __attribute__((address_space(3)))
; __device__ __forceinline__ void gla_upd_unit(LAS unsigned char* wl, const bf16* PROJ, const float* R, const float* w_gk2, const float* b_gk, float* UPD, float* DEC, int unit, int lane) {
;     ...
;     for (int t = 0; t < 64; ++t) {
;         const LAS f32x4* rr = (const LAS f32x4*)(wl + 9216) + t * 4;
;         float z = bias;
; #pragma unroll
;         for (int q = 0; q < 4; ++q) { const f32x4 rv = rr[q]; z += rv[0] * w[4 * q] + rv[1] * w[4 * q + 1] + rv[2] * w[4 * q + 2] + rv[3] * w[4 * q + 3]; }
;         la[t] = (fminf(z, 0.f) - __logf(1.0f + __expf(-fabsf(z)))) * (1.0f / 16.0f);
;         tot += la[t];
;     }
	v_mov_b32_e32 v133, v128
	v_mov_b32_e32 v128, v125
	v_pk_mul_f32 v[124:125], v[8:9], v[128:129]
	v_mov_b32_e32 v128, v126
	v_pk_fma_f32 v[124:125], v[6:7], v[132:133], v[124:125]
	v_mov_b32_e32 v129, v130
	v_pk_fma_f32 v[124:125], v[2:3], v[128:129], v[124:125]
	v_mov_b32_e32 v130, v127
	v_pk_fma_f32 v[124:125], v[0:1], v[130:131], v[124:125]
	s_nop 0
	v_add_f32_e32 v123, v123, v124
	v_add_f32_e32 v123, v123, v125
	v_min_f32_e32 v124, 0, v123
	v_mul_f32_e64 v123, |v123|, s48
	v_exp_f32_e32 v123, v123
	s_nop 0
	v_add_f32_e32 v123, 1.0, v123
	v_cmp_gt_f32_e32 vcc, s49, v123
	s_nop 1
	v_cndmask_b32_e64 v125, 0, 32, vcc
	v_ldexp_f32 v123, v123, v125
	v_log_f32_e32 v123, v123
	s_nop 0
	v_mul_f32_e32 v125, 0x3f317217, v123
	v_fma_f32 v125, v123, s56, -v125
	v_fmac_f32_e32 v125, 0x3377d1cf, v123
	v_fmac_f32_e32 v125, 0x3f317217, v123
	v_cmp_lt_f32_e64 s[0:1], |v123|, s57
	s_nop 1
	v_cndmask_b32_e64 v123, v123, v125, s[0:1]
	v_cndmask_b32_e32 v125, 0, v90, vcc
	v_sub_f32_e32 v123, v123, v125
	v_sub_f32_e32 v123, v124, v123
	ds_read_b128 v[124:127], v102 offset:10624
	ds_read_b128 v[128:131], v102 offset:10640
	v_fmamk_f32 v123, v123, 0x3d800000, v122
	s_waitcnt lgkmcnt(1)
	v_mov_b32_e32 v132, v124
	s_waitcnt lgkmcnt(0)
	v_mov_b32_e32 v133, v128
	v_mov_b32_e32 v128, v125
	v_pk_mul_f32 v[124:125], v[16:17], v[128:129]
	v_mov_b32_e32 v128, v126
	v_pk_fma_f32 v[124:125], v[14:15], v[132:133], v[124:125]
	v_mov_b32_e32 v129, v130
	v_pk_fma_f32 v[124:125], v[12:13], v[128:129], v[124:125]
	v_mov_b32_e32 v130, v127
	v_pk_fma_f32 v[124:125], v[10:11], v[130:131], v[124:125]
	s_nop 0
	v_add_f32_e32 v124, v100, v124
	v_add_f32_e32 v134, v124, v125
	ds_read_b128 v[124:127], v102 offset:10656
	ds_read_b128 v[128:131], v102 offset:10672
	s_waitcnt lgkmcnt(1)
	v_mov_b32_e32 v132, v124
	s_waitcnt lgkmcnt(0)
	v_mov_b32_e32 v133, v128
	v_mov_b32_e32 v128, v125
	v_pk_mul_f32 v[124:125], v[8:9], v[128:129]
	v_mov_b32_e32 v128, v126
	v_pk_fma_f32 v[124:125], v[6:7], v[132:133], v[124:125]
	v_mov_b32_e32 v129, v130
	v_pk_fma_f32 v[124:125], v[2:3], v[128:129], v[124:125]
	v_mov_b32_e32 v130, v127
	v_pk_fma_f32 v[124:125], v[0:1], v[130:131], v[124:125]
	s_nop 0
	v_add_f32_e32 v124, v134, v124
	v_add_f32_e32 v124, v124, v125
	v_min_f32_e32 v125, 0, v124
	v_mul_f32_e64 v124, |v124|, s48
	v_exp_f32_e32 v124, v124
	s_nop 0
	v_add_f32_e32 v124, 1.0, v124
	v_cmp_gt_f32_e32 vcc, s49, v124
	s_nop 1
	v_cndmask_b32_e64 v126, 0, 32, vcc
	v_ldexp_f32 v124, v124, v126
	v_log_f32_e32 v124, v124
	s_nop 0
	v_mul_f32_e32 v126, 0x3f317217, v124
	v_fma_f32 v126, v124, s56, -v126
	v_fmac_f32_e32 v126, 0x3377d1cf, v124
	v_fmac_f32_e32 v126, 0x3f317217, v124
	v_cmp_lt_f32_e64 s[0:1], |v124|, s57
	s_nop 1
	v_cndmask_b32_e64 v124, v124, v126, s[0:1]
	v_cndmask_b32_e32 v126, 0, v90, vcc
	v_sub_f32_e32 v124, v124, v126
	ds_read_b128 v[126:129], v102 offset:10688
	ds_read_b128 v[130:133], v102 offset:10704
	v_sub_f32_e32 v124, v125, v124
	v_fmamk_f32 v124, v124, 0x3d800000, v123
	s_waitcnt lgkmcnt(1)
	v_mov_b32_e32 v134, v126
	s_waitcnt lgkmcnt(0)
	v_mov_b32_e32 v135, v130
	v_mov_b32_e32 v130, v127
	v_pk_mul_f32 v[126:127], v[16:17], v[130:131]
	v_mov_b32_e32 v130, v128
	v_pk_fma_f32 v[126:127], v[14:15], v[134:135], v[126:127]
	v_mov_b32_e32 v131, v132
	v_pk_fma_f32 v[126:127], v[12:13], v[130:131], v[126:127]
	v_mov_b32_e32 v132, v129
	v_pk_fma_f32 v[126:127], v[10:11], v[132:133], v[126:127]
	s_nop 0
	v_add_f32_e32 v125, v100, v126
	v_add_f32_e32 v125, v125, v127
	ds_read_b128 v[126:129], v102 offset:10720
	ds_read_b128 v[130:133], v102 offset:10736
	s_waitcnt lgkmcnt(1)
	v_mov_b32_e32 v134, v126
	s_waitcnt lgkmcnt(0)
	v_mov_b32_e32 v135, v130
	v_mov_b32_e32 v130, v127
	v_pk_mul_f32 v[126:127], v[8:9], v[130:131]
	v_mov_b32_e32 v130, v128
	v_pk_fma_f32 v[126:127], v[6:7], v[134:135], v[126:127]
	v_mov_b32_e32 v131, v132
	v_pk_fma_f32 v[126:127], v[2:3], v[130:131], v[126:127]
	v_mov_b32_e32 v132, v129
	v_pk_fma_f32 v[126:127], v[0:1], v[132:133], v[126:127]
	s_nop 0
	v_add_f32_e32 v125, v125, v126
	v_add_f32_e32 v125, v125, v127
	v_min_f32_e32 v126, 0, v125
	v_mul_f32_e64 v125, |v125|, s48
	v_exp_f32_e32 v125, v125
	s_nop 0
	v_add_f32_e32 v125, 1.0, v125
	v_cmp_gt_f32_e32 vcc, s49, v125
	s_nop 1
	v_cndmask_b32_e64 v127, 0, 32, vcc
	v_ldexp_f32 v125, v125, v127
	v_log_f32_e32 v125, v125
	s_nop 0
	v_mul_f32_e32 v127, 0x3f317217, v125
	v_fma_f32 v127, v125, s56, -v127
	v_fmac_f32_e32 v127, 0x3377d1cf, v125
	v_fmac_f32_e32 v127, 0x3f317217, v125
	v_cmp_lt_f32_e64 s[0:1], |v125|, s57
	s_nop 1
	v_cndmask_b32_e64 v125, v125, v127, s[0:1]
	v_cndmask_b32_e32 v127, 0, v90, vcc
	v_sub_f32_e32 v125, v125, v127
	v_sub_f32_e32 v125, v126, v125
	ds_read_b128 v[126:129], v102 offset:10752
	ds_read_b128 v[130:133], v102 offset:10768
	v_fmamk_f32 v125, v125, 0x3d800000, v124
	s_waitcnt lgkmcnt(1)
	v_mov_b32_e32 v134, v126
	s_waitcnt lgkmcnt(0)
	v_mov_b32_e32 v135, v130
	v_mov_b32_e32 v130, v127
	v_pk_mul_f32 v[126:127], v[16:17], v[130:131]
	v_mov_b32_e32 v130, v128
	v_pk_fma_f32 v[126:127], v[14:15], v[134:135], v[126:127]
	v_mov_b32_e32 v131, v132
	v_pk_fma_f32 v[126:127], v[12:13], v[130:131], v[126:127]
	v_mov_b32_e32 v132, v129
	v_pk_fma_f32 v[126:127], v[10:11], v[132:133], v[126:127]
	s_nop 0
	v_add_f32_e32 v126, v100, v126
	v_add_f32_e32 v136, v126, v127
	ds_read_b128 v[126:129], v102 offset:10784
	ds_read_b128 v[130:133], v102 offset:10800
	s_waitcnt lgkmcnt(1)
	v_mov_b32_e32 v134, v126
	s_waitcnt lgkmcnt(0)
; #define LAS __attribute__((address_space(3)))
; __device__ __forceinline__ void gla_upd_unit(LAS unsigned char* wl, const bf16* PROJ, const float* R, const float* w_gk2, const float* b_gk, float* UPD, float* DEC, int unit, int lane) {
;     ...
;     for (int t = 0; t < 64; ++t) {
;         const LAS f32x4* rr = (const LAS f32x4*)(wl + 9216) + t * 4;
;         float z = bias;
; #pragma unroll
;         for (int q = 0; q < 4; ++q) { const f32x4 rv = rr[q]; z += rv[0] * w[4 * q] + rv[1] * w[4 * q + 1] + rv[2] * w[4 * q + 2] + rv[3] * w[4 * q + 3]; }
;         la[t] = (fminf(z, 0.f) - __logf(1.0f + __expf(-fabsf(z)))) * (1.0f / 16.0f);
;         tot += la[t];
;     }
	v_mov_b32_e32 v135, v130
	v_mov_b32_e32 v130, v127
	v_pk_mul_f32 v[126:127], v[8:9], v[130:131]
	v_mov_b32_e32 v130, v128
	v_pk_fma_f32 v[126:127], v[6:7], v[134:135], v[126:127]
	v_mov_b32_e32 v131, v132
	v_pk_fma_f32 v[126:127], v[2:3], v[130:131], v[126:127]
	v_mov_b32_e32 v132, v129
	v_pk_fma_f32 v[126:127], v[0:1], v[132:133], v[126:127]
	s_nop 0
	v_add_f32_e32 v126, v136, v126
	v_add_f32_e32 v126, v126, v127
	v_min_f32_e32 v127, 0, v126
	v_mul_f32_e64 v126, |v126|, s48
	v_exp_f32_e32 v126, v126
	s_nop 0
	v_add_f32_e32 v126, 1.0, v126
	v_cmp_gt_f32_e32 vcc, s49, v126
	s_nop 1
	v_cndmask_b32_e64 v128, 0, 32, vcc
	v_ldexp_f32 v126, v126, v128
	v_log_f32_e32 v126, v126
	s_nop 0
	v_mul_f32_e32 v128, 0x3f317217, v126
	v_fma_f32 v128, v126, s56, -v128
	v_fmac_f32_e32 v128, 0x3377d1cf, v126
	v_fmac_f32_e32 v128, 0x3f317217, v126
	v_cmp_lt_f32_e64 s[0:1], |v126|, s57
	s_nop 1
	v_cndmask_b32_e64 v126, v126, v128, s[0:1]
	v_cndmask_b32_e32 v128, 0, v90, vcc
	v_sub_f32_e32 v126, v126, v128
	ds_read_b128 v[128:131], v102 offset:10816
	ds_read_b128 v[132:135], v102 offset:10832
	v_sub_f32_e32 v126, v127, v126
	v_fmamk_f32 v126, v126, 0x3d800000, v125
	s_waitcnt lgkmcnt(1)
	v_mov_b32_e32 v136, v128
	s_waitcnt lgkmcnt(0)
	v_mov_b32_e32 v137, v132
	v_mov_b32_e32 v132, v129
	v_pk_mul_f32 v[128:129], v[16:17], v[132:133]
	v_mov_b32_e32 v132, v130
	v_pk_fma_f32 v[128:129], v[14:15], v[136:137], v[128:129]
	v_mov_b32_e32 v133, v134
	v_pk_fma_f32 v[128:129], v[12:13], v[132:133], v[128:129]
	v_mov_b32_e32 v134, v131
	v_pk_fma_f32 v[128:129], v[10:11], v[134:135], v[128:129]
	s_nop 0
	v_add_f32_e32 v127, v100, v128
	v_add_f32_e32 v127, v127, v129
	ds_read_b128 v[128:131], v102 offset:10848
	ds_read_b128 v[132:135], v102 offset:10864
	s_waitcnt lgkmcnt(1)
	v_mov_b32_e32 v136, v128
	s_waitcnt lgkmcnt(0)
	v_mov_b32_e32 v137, v132
	v_mov_b32_e32 v132, v129
	v_pk_mul_f32 v[128:129], v[8:9], v[132:133]
	v_mov_b32_e32 v132, v130
	v_pk_fma_f32 v[128:129], v[6:7], v[136:137], v[128:129]
	v_mov_b32_e32 v133, v134
	v_pk_fma_f32 v[128:129], v[2:3], v[132:133], v[128:129]
	v_mov_b32_e32 v134, v131
	v_pk_fma_f32 v[128:129], v[0:1], v[134:135], v[128:129]
	s_nop 0
	v_add_f32_e32 v127, v127, v128
	v_add_f32_e32 v127, v127, v129
	v_min_f32_e32 v128, 0, v127
	v_mul_f32_e64 v127, |v127|, s48
	v_exp_f32_e32 v127, v127
	s_nop 0
	v_add_f32_e32 v127, 1.0, v127
	v_cmp_gt_f32_e32 vcc, s49, v127
	s_nop 1
	v_cndmask_b32_e64 v129, 0, 32, vcc
	v_ldexp_f32 v127, v127, v129
	v_log_f32_e32 v127, v127
	s_nop 0
	v_mul_f32_e32 v129, 0x3f317217, v127
	v_fma_f32 v129, v127, s56, -v129
	v_fmac_f32_e32 v129, 0x3377d1cf, v127
	v_fmac_f32_e32 v129, 0x3f317217, v127
	v_cmp_lt_f32_e64 s[0:1], |v127|, s57
	s_nop 1
	v_cndmask_b32_e64 v127, v127, v129, s[0:1]
	v_cndmask_b32_e32 v129, 0, v90, vcc
	v_sub_f32_e32 v127, v127, v129
	v_sub_f32_e32 v127, v128, v127
	ds_read_b128 v[128:131], v102 offset:10880
	ds_read_b128 v[132:135], v102 offset:10896
	v_fmamk_f32 v127, v127, 0x3d800000, v126
	s_waitcnt lgkmcnt(1)
	v_mov_b32_e32 v136, v128
	s_waitcnt lgkmcnt(0)
	v_mov_b32_e32 v137, v132
	v_mov_b32_e32 v132, v129
	v_pk_mul_f32 v[128:129], v[16:17], v[132:133]
	v_mov_b32_e32 v132, v130
	v_pk_fma_f32 v[128:129], v[14:15], v[136:137], v[128:129]
	v_mov_b32_e32 v133, v134
	v_pk_fma_f32 v[128:129], v[12:13], v[132:133], v[128:129]
	v_mov_b32_e32 v134, v131
	v_pk_fma_f32 v[128:129], v[10:11], v[134:135], v[128:129]
	s_nop 0
	v_add_f32_e32 v128, v100, v128
	v_add_f32_e32 v139, v128, v129
	ds_read_b128 v[128:131], v102 offset:10912
	ds_read_b128 v[132:135], v102 offset:10928
	s_waitcnt lgkmcnt(1)
	v_mov_b32_e32 v136, v128
	s_waitcnt lgkmcnt(0)
	v_mov_b32_e32 v137, v132
	v_mov_b32_e32 v132, v129
	v_pk_mul_f32 v[128:129], v[8:9], v[132:133]
	v_mov_b32_e32 v132, v130
	v_pk_fma_f32 v[128:129], v[6:7], v[136:137], v[128:129]
	v_mov_b32_e32 v133, v134
	v_pk_fma_f32 v[128:129], v[2:3], v[132:133], v[128:129]
	v_mov_b32_e32 v134, v131
	v_pk_fma_f32 v[128:129], v[0:1], v[134:135], v[128:129]
	s_nop 0
	v_add_f32_e32 v128, v139, v128
	v_add_f32_e32 v128, v128, v129
	v_min_f32_e32 v129, 0, v128
	v_mul_f32_e64 v128, |v128|, s48
	v_exp_f32_e32 v128, v128
	s_nop 0
	v_add_f32_e32 v128, 1.0, v128
	v_cmp_gt_f32_e32 vcc, s49, v128
	s_nop 1
	v_cndmask_b32_e64 v130, 0, 32, vcc
	v_ldexp_f32 v128, v128, v130
	v_log_f32_e32 v128, v128
	s_nop 0
	v_mul_f32_e32 v130, 0x3f317217, v128
	v_fma_f32 v130, v128, s56, -v130
	v_fmac_f32_e32 v130, 0x3377d1cf, v128
	v_fmac_f32_e32 v130, 0x3f317217, v128
	v_cmp_lt_f32_e64 s[0:1], |v128|, s57
	s_nop 1
	v_cndmask_b32_e64 v128, v128, v130, s[0:1]
	v_cndmask_b32_e32 v130, 0, v90, vcc
	v_sub_f32_e32 v128, v128, v130
	ds_read_b128 v[130:133], v102 offset:10944
	ds_read_b128 v[134:137], v102 offset:10960
	v_sub_f32_e32 v128, v129, v128
	v_fmamk_f32 v128, v128, 0x3d800000, v127
	s_waitcnt lgkmcnt(1)
	v_mov_b32_e32 v140, v130
	s_waitcnt lgkmcnt(0)
	v_mov_b32_e32 v141, v134
	v_mov_b32_e32 v134, v131
	v_pk_mul_f32 v[130:131], v[16:17], v[134:135]
	v_mov_b32_e32 v134, v132
	v_pk_fma_f32 v[130:131], v[14:15], v[140:141], v[130:131]
	v_mov_b32_e32 v135, v136
	v_pk_fma_f32 v[130:131], v[12:13], v[134:135], v[130:131]
	v_mov_b32_e32 v136, v133
	v_pk_fma_f32 v[130:131], v[10:11], v[136:137], v[130:131]
	s_nop 0
	v_add_f32_e32 v129, v100, v130
	v_add_f32_e32 v129, v129, v131
	ds_read_b128 v[130:133], v102 offset:10976
	ds_read_b128 v[134:137], v102 offset:10992
	s_waitcnt lgkmcnt(1)
	v_mov_b32_e32 v140, v130
	s_waitcnt lgkmcnt(0)
; #define LAS __attribute__((address_space(3)))
; __device__ __forceinline__ void gla_upd_unit(LAS unsigned char* wl, const bf16* PROJ, const float* R, const float* w_gk2, const float* b_gk, float* UPD, float* DEC, int unit, int lane) {
;     ...
;     for (int t = 0; t < 64; ++t) {
;         const LAS f32x4* rr = (const LAS f32x4*)(wl + 9216) + t * 4;
;         float z = bias;
; #pragma unroll
;         for (int q = 0; q < 4; ++q) { const f32x4 rv = rr[q]; z += rv[0] * w[4 * q] + rv[1] * w[4 * q + 1] + rv[2] * w[4 * q + 2] + rv[3] * w[4 * q + 3]; }
;         la[t] = (fminf(z, 0.f) - __logf(1.0f + __expf(-fabsf(z)))) * (1.0f / 16.0f);
;         tot += la[t];
;     }
	v_mov_b32_e32 v141, v134
	v_mov_b32_e32 v134, v131
	v_pk_mul_f32 v[130:131], v[8:9], v[134:135]
	v_mov_b32_e32 v134, v132
	v_pk_fma_f32 v[130:131], v[6:7], v[140:141], v[130:131]
	v_mov_b32_e32 v135, v136
	v_pk_fma_f32 v[130:131], v[2:3], v[134:135], v[130:131]
	v_mov_b32_e32 v136, v133
	v_pk_fma_f32 v[130:131], v[0:1], v[136:137], v[130:131]
	s_nop 0
	v_add_f32_e32 v129, v129, v130
	v_add_f32_e32 v129, v129, v131
	v_min_f32_e32 v130, 0, v129
	v_mul_f32_e64 v129, |v129|, s48
	v_exp_f32_e32 v129, v129
	s_nop 0
	v_add_f32_e32 v129, 1.0, v129
	v_cmp_gt_f32_e32 vcc, s49, v129
	s_nop 1
	v_cndmask_b32_e64 v131, 0, 32, vcc
	v_ldexp_f32 v129, v129, v131
	v_log_f32_e32 v129, v129
	s_nop 0
	v_mul_f32_e32 v131, 0x3f317217, v129
	v_fma_f32 v131, v129, s56, -v131
	v_fmac_f32_e32 v131, 0x3377d1cf, v129
	v_fmac_f32_e32 v131, 0x3f317217, v129
	v_cmp_lt_f32_e64 s[0:1], |v129|, s57
	s_nop 1
	v_cndmask_b32_e64 v129, v129, v131, s[0:1]
	v_cndmask_b32_e32 v131, 0, v90, vcc
	v_sub_f32_e32 v129, v129, v131
	v_sub_f32_e32 v129, v130, v129
	ds_read_b128 v[130:133], v102 offset:11008
	ds_read_b128 v[134:137], v102 offset:11024
	v_fmamk_f32 v129, v129, 0x3d800000, v128
	s_waitcnt lgkmcnt(1)
	v_mov_b32_e32 v140, v130
	s_waitcnt lgkmcnt(0)
	v_mov_b32_e32 v141, v134
	v_mov_b32_e32 v134, v131
	v_pk_mul_f32 v[130:131], v[16:17], v[134:135]
	v_mov_b32_e32 v134, v132
	v_pk_fma_f32 v[130:131], v[14:15], v[140:141], v[130:131]
	v_mov_b32_e32 v135, v136
	v_pk_fma_f32 v[130:131], v[12:13], v[134:135], v[130:131]
	v_mov_b32_e32 v136, v133
	v_pk_fma_f32 v[130:131], v[10:11], v[136:137], v[130:131]
	s_nop 0
	v_add_f32_e32 v130, v100, v130
	v_add_f32_e32 v139, v130, v131
	ds_read_b128 v[130:133], v102 offset:11040
	ds_read_b128 v[134:137], v102 offset:11056
	s_waitcnt lgkmcnt(1)
	v_mov_b32_e32 v140, v130
	s_waitcnt lgkmcnt(0)
	v_mov_b32_e32 v141, v134
	v_mov_b32_e32 v134, v131
	v_pk_mul_f32 v[130:131], v[8:9], v[134:135]
	v_mov_b32_e32 v134, v132
	v_pk_fma_f32 v[130:131], v[6:7], v[140:141], v[130:131]
	v_mov_b32_e32 v135, v136
	v_pk_fma_f32 v[130:131], v[2:3], v[134:135], v[130:131]
	v_mov_b32_e32 v136, v133
	v_pk_fma_f32 v[130:131], v[0:1], v[136:137], v[130:131]
	s_nop 0
	v_add_f32_e32 v130, v139, v130
	v_add_f32_e32 v130, v130, v131
	v_min_f32_e32 v131, 0, v130
	v_mul_f32_e64 v130, |v130|, s48
	v_exp_f32_e32 v130, v130
	s_nop 0
	v_add_f32_e32 v130, 1.0, v130
	v_cmp_gt_f32_e32 vcc, s49, v130
	s_nop 1
	v_cndmask_b32_e64 v132, 0, 32, vcc
	v_ldexp_f32 v130, v130, v132
	v_log_f32_e32 v130, v130
	s_nop 0
	v_mul_f32_e32 v132, 0x3f317217, v130
	v_fma_f32 v132, v130, s56, -v132
	v_fmac_f32_e32 v132, 0x3377d1cf, v130
	v_fmac_f32_e32 v132, 0x3f317217, v130
	v_cmp_lt_f32_e64 s[0:1], |v130|, s57
	s_nop 1
	v_cndmask_b32_e64 v130, v130, v132, s[0:1]
	v_cndmask_b32_e32 v132, 0, v90, vcc
	v_sub_f32_e32 v130, v130, v132
	ds_read_b128 v[132:135], v102 offset:11072
	ds_read_b128 v[140:143], v102 offset:11088
	v_sub_f32_e32 v130, v131, v130
	v_fmamk_f32 v130, v130, 0x3d800000, v129
	s_waitcnt lgkmcnt(1)
	v_mov_b32_e32 v136, v132
	s_waitcnt lgkmcnt(0)
	v_mov_b32_e32 v137, v140
	v_mov_b32_e32 v140, v133
	v_pk_mul_f32 v[132:133], v[16:17], v[140:141]
	s_nop 0
	v_pk_fma_f32 v[132:133], v[14:15], v[136:137], v[132:133]
	v_mov_b32_e32 v136, v134
	v_mov_b32_e32 v137, v142
	v_pk_fma_f32 v[132:133], v[12:13], v[136:137], v[132:133]
	v_mov_b32_e32 v142, v135
	v_pk_fma_f32 v[132:133], v[10:11], v[142:143], v[132:133]
	s_nop 0
	v_add_f32_e32 v131, v100, v132
	v_add_f32_e32 v131, v131, v133
	ds_read_b128 v[132:135], v102 offset:11104
	ds_read_b128 v[140:143], v102 offset:11120
	s_waitcnt lgkmcnt(1)
	v_mov_b32_e32 v136, v132
	s_waitcnt lgkmcnt(0)
	v_mov_b32_e32 v137, v140
	v_mov_b32_e32 v140, v133
	v_pk_mul_f32 v[132:133], v[8:9], v[140:141]
	s_nop 0
	v_pk_fma_f32 v[132:133], v[6:7], v[136:137], v[132:133]
	v_mov_b32_e32 v136, v134
	v_mov_b32_e32 v137, v142
	v_pk_fma_f32 v[132:133], v[2:3], v[136:137], v[132:133]
	v_mov_b32_e32 v142, v135
	v_pk_fma_f32 v[132:133], v[0:1], v[142:143], v[132:133]
	s_nop 0
	v_add_f32_e32 v131, v131, v132
	v_add_f32_e32 v131, v131, v133
	v_min_f32_e32 v132, 0, v131
	v_mul_f32_e64 v131, |v131|, s48
	v_exp_f32_e32 v131, v131
	s_nop 0
	v_add_f32_e32 v131, 1.0, v131
	v_cmp_gt_f32_e32 vcc, s49, v131
	s_nop 1
	v_cndmask_b32_e64 v133, 0, 32, vcc
	v_ldexp_f32 v131, v131, v133
	v_log_f32_e32 v131, v131
	s_nop 0
	v_mul_f32_e32 v133, 0x3f317217, v131
	v_fma_f32 v133, v131, s56, -v133
	v_fmac_f32_e32 v133, 0x3377d1cf, v131
	v_fmac_f32_e32 v133, 0x3f317217, v131
	v_cmp_lt_f32_e64 s[0:1], |v131|, s57
	s_nop 1
	v_cndmask_b32_e64 v131, v131, v133, s[0:1]
	v_cndmask_b32_e32 v133, 0, v90, vcc
	v_sub_f32_e32 v131, v131, v133
	v_sub_f32_e32 v131, v132, v131
	ds_read_b128 v[132:135], v102 offset:11136
	ds_read_b128 v[140:143], v102 offset:11152
	v_fmamk_f32 v131, v131, 0x3d800000, v130
	s_waitcnt lgkmcnt(1)
	v_mov_b32_e32 v136, v132
	s_waitcnt lgkmcnt(0)
	v_mov_b32_e32 v137, v140
	v_mov_b32_e32 v140, v133
	v_pk_mul_f32 v[132:133], v[16:17], v[140:141]
	s_nop 0
	v_pk_fma_f32 v[132:133], v[14:15], v[136:137], v[132:133]
	v_mov_b32_e32 v136, v134
	v_mov_b32_e32 v137, v142
	v_pk_fma_f32 v[132:133], v[12:13], v[136:137], v[132:133]
	v_mov_b32_e32 v142, v135
	v_pk_fma_f32 v[132:133], v[10:11], v[142:143], v[132:133]
	s_nop 0
	v_add_f32_e32 v132, v100, v132
	v_add_f32_e32 v139, v132, v133
	ds_read_b128 v[132:135], v102 offset:11168
	ds_read_b128 v[140:143], v102 offset:11184
	s_waitcnt lgkmcnt(1)
	v_mov_b32_e32 v136, v132
	s_waitcnt lgkmcnt(0)
; #define LAS __attribute__((address_space(3)))
; __device__ __forceinline__ void gla_upd_unit(LAS unsigned char* wl, const bf16* PROJ, const float* R, const float* w_gk2, const float* b_gk, float* UPD, float* DEC, int unit, int lane) {
;     ...
;     for (int t = 0; t < 64; ++t) {
;         const LAS f32x4* rr = (const LAS f32x4*)(wl + 9216) + t * 4;
;         float z = bias;
; #pragma unroll
;         for (int q = 0; q < 4; ++q) { const f32x4 rv = rr[q]; z += rv[0] * w[4 * q] + rv[1] * w[4 * q + 1] + rv[2] * w[4 * q + 2] + rv[3] * w[4 * q + 3]; }
;         la[t] = (fminf(z, 0.f) - __logf(1.0f + __expf(-fabsf(z)))) * (1.0f / 16.0f);
;         tot += la[t];
;     }
	v_mov_b32_e32 v137, v140
	v_mov_b32_e32 v140, v133
	v_pk_mul_f32 v[132:133], v[8:9], v[140:141]
	s_nop 0
	v_pk_fma_f32 v[132:133], v[6:7], v[136:137], v[132:133]
	v_mov_b32_e32 v136, v134
	v_mov_b32_e32 v137, v142
	v_pk_fma_f32 v[132:133], v[2:3], v[136:137], v[132:133]
	v_mov_b32_e32 v142, v135
	v_pk_fma_f32 v[132:133], v[0:1], v[142:143], v[132:133]
	s_nop 0
	v_add_f32_e32 v132, v139, v132
	v_add_f32_e32 v132, v132, v133
	v_min_f32_e32 v133, 0, v132
	v_mul_f32_e64 v132, |v132|, s48
	v_exp_f32_e32 v132, v132
	s_nop 0
	v_add_f32_e32 v132, 1.0, v132
	v_cmp_gt_f32_e32 vcc, s49, v132
	s_nop 1
	v_cndmask_b32_e64 v134, 0, 32, vcc
	v_ldexp_f32 v132, v132, v134
	v_log_f32_e32 v132, v132
	s_nop 0
	v_mul_f32_e32 v134, 0x3f317217, v132
	v_fma_f32 v134, v132, s56, -v134
	v_fmac_f32_e32 v134, 0x3377d1cf, v132
	v_fmac_f32_e32 v134, 0x3f317217, v132
	v_cmp_lt_f32_e64 s[0:1], |v132|, s57
	s_nop 1
	v_cndmask_b32_e64 v132, v132, v134, s[0:1]
	v_cndmask_b32_e32 v134, 0, v90, vcc
	v_sub_f32_e32 v132, v132, v134
	ds_read_b128 v[134:137], v102 offset:11200
	ds_read_b128 v[140:143], v102 offset:11216
	v_sub_f32_e32 v132, v133, v132
	v_fmamk_f32 v132, v132, 0x3d800000, v131
	s_waitcnt lgkmcnt(1)
	v_mov_b32_e32 v146, v134
	s_waitcnt lgkmcnt(0)
	v_mov_b32_e32 v147, v140
	v_mov_b32_e32 v140, v135
	v_pk_mul_f32 v[134:135], v[16:17], v[140:141]
	v_mov_b32_e32 v140, v136
	v_pk_fma_f32 v[134:135], v[14:15], v[146:147], v[134:135]
	v_mov_b32_e32 v141, v142
	v_pk_fma_f32 v[134:135], v[12:13], v[140:141], v[134:135]
	v_mov_b32_e32 v142, v137
	v_pk_fma_f32 v[134:135], v[10:11], v[142:143], v[134:135]
	s_nop 0
	v_add_f32_e32 v133, v100, v134
	v_add_f32_e32 v133, v133, v135
	ds_read_b128 v[134:137], v102 offset:11232
	ds_read_b128 v[140:143], v102 offset:11248
	s_waitcnt lgkmcnt(1)
	v_mov_b32_e32 v146, v134
	s_waitcnt lgkmcnt(0)
	v_mov_b32_e32 v147, v140
	v_mov_b32_e32 v140, v135
	v_pk_mul_f32 v[134:135], v[8:9], v[140:141]
	v_mov_b32_e32 v140, v136
	v_pk_fma_f32 v[134:135], v[6:7], v[146:147], v[134:135]
	v_mov_b32_e32 v141, v142
	v_pk_fma_f32 v[134:135], v[2:3], v[140:141], v[134:135]
	v_mov_b32_e32 v142, v137
	v_pk_fma_f32 v[134:135], v[0:1], v[142:143], v[134:135]
	s_nop 0
	v_add_f32_e32 v133, v133, v134
	v_add_f32_e32 v133, v133, v135
	v_min_f32_e32 v134, 0, v133
	v_mul_f32_e64 v133, |v133|, s48
	v_exp_f32_e32 v133, v133
	s_nop 0
	v_add_f32_e32 v133, 1.0, v133
	v_cmp_gt_f32_e32 vcc, s49, v133
	s_nop 1
	v_cndmask_b32_e64 v135, 0, 32, vcc
	v_ldexp_f32 v133, v133, v135
	v_log_f32_e32 v133, v133
	s_nop 0
	v_mul_f32_e32 v135, 0x3f317217, v133
	v_fma_f32 v135, v133, s56, -v135
	v_fmac_f32_e32 v135, 0x3377d1cf, v133
	v_fmac_f32_e32 v135, 0x3f317217, v133
	v_cmp_lt_f32_e64 s[0:1], |v133|, s57
	s_nop 1
	v_cndmask_b32_e64 v133, v133, v135, s[0:1]
	v_cndmask_b32_e32 v135, 0, v90, vcc
	v_sub_f32_e32 v133, v133, v135
	v_sub_f32_e32 v133, v134, v133
	ds_read_b128 v[134:137], v102 offset:11264
	ds_read_b128 v[140:143], v102 offset:11280
	v_fmamk_f32 v133, v133, 0x3d800000, v132
	s_waitcnt lgkmcnt(1)
	v_mov_b32_e32 v146, v134
	s_waitcnt lgkmcnt(0)
	v_mov_b32_e32 v147, v140
	v_mov_b32_e32 v140, v135
	v_pk_mul_f32 v[134:135], v[16:17], v[140:141]
	v_mov_b32_e32 v140, v136
	v_pk_fma_f32 v[134:135], v[14:15], v[146:147], v[134:135]
	v_mov_b32_e32 v141, v142
	v_pk_fma_f32 v[134:135], v[12:13], v[140:141], v[134:135]
	v_mov_b32_e32 v142, v137
	v_pk_fma_f32 v[134:135], v[10:11], v[142:143], v[134:135]
	s_nop 0
	v_add_f32_e32 v134, v100, v134
	v_add_f32_e32 v139, v134, v135
	ds_read_b128 v[134:137], v102 offset:11296
	ds_read_b128 v[140:143], v102 offset:11312
	s_waitcnt lgkmcnt(1)
	v_mov_b32_e32 v146, v134
	s_waitcnt lgkmcnt(0)
	v_mov_b32_e32 v147, v140
	v_mov_b32_e32 v140, v135
	v_pk_mul_f32 v[134:135], v[8:9], v[140:141]
	v_mov_b32_e32 v140, v136
	v_pk_fma_f32 v[134:135], v[6:7], v[146:147], v[134:135]
	v_mov_b32_e32 v141, v142
	v_pk_fma_f32 v[134:135], v[2:3], v[140:141], v[134:135]
	v_mov_b32_e32 v142, v137
	v_pk_fma_f32 v[134:135], v[0:1], v[142:143], v[134:135]
	ds_read_b128 v[140:143], v102 offset:11328
	ds_read_b128 v[146:149], v102 offset:11344
	v_add_f32_e32 v134, v139, v134
	v_add_f32_e32 v134, v134, v135
	v_min_f32_e32 v135, 0, v134
	v_mul_f32_e64 v134, |v134|, s48
	v_exp_f32_e32 v134, v134
	s_waitcnt lgkmcnt(0)
	v_mov_b32_e32 v137, v146
	v_mov_b32_e32 v146, v141
	v_add_f32_e32 v134, 1.0, v134
	v_cmp_gt_f32_e32 vcc, s49, v134
	s_nop 1
	v_cndmask_b32_e64 v136, 0, 32, vcc
	v_ldexp_f32 v134, v134, v136
	v_log_f32_e32 v134, v134
	s_nop 0
	v_mul_f32_e32 v136, 0x3f317217, v134
	v_fma_f32 v136, v134, s56, -v136
	v_fmac_f32_e32 v136, 0x3377d1cf, v134
	v_fmac_f32_e32 v136, 0x3f317217, v134
	v_cmp_lt_f32_e64 s[0:1], |v134|, s57
	s_nop 1
	v_cndmask_b32_e64 v134, v134, v136, s[0:1]
	v_cndmask_b32_e32 v136, 0, v90, vcc
	v_sub_f32_e32 v134, v134, v136
	v_mov_b32_e32 v136, v140
	v_pk_mul_f32 v[140:141], v[16:17], v[146:147]
	v_sub_f32_e32 v134, v135, v134
	v_pk_fma_f32 v[136:137], v[14:15], v[136:137], v[140:141]
	v_mov_b32_e32 v140, v142
	v_mov_b32_e32 v141, v148
	v_pk_fma_f32 v[136:137], v[12:13], v[140:141], v[136:137]
	v_mov_b32_e32 v148, v143
	v_pk_fma_f32 v[136:137], v[10:11], v[148:149], v[136:137]
	ds_read_b128 v[140:143], v102 offset:11360
	ds_read_b128 v[146:149], v102 offset:11376
	v_add_f32_e32 v135, v100, v136
	v_add_f32_e32 v135, v135, v137
	v_fmamk_f32 v134, v134, 0x3d800000, v133
	s_waitcnt lgkmcnt(1)
	v_mov_b32_e32 v136, v140
	s_waitcnt lgkmcnt(0)
; #define LAS __attribute__((address_space(3)))
; __device__ __forceinline__ void gla_upd_unit(LAS unsigned char* wl, const bf16* PROJ, const float* R, const float* w_gk2, const float* b_gk, float* UPD, float* DEC, int unit, int lane) {
;     ...
;     for (int t = 0; t < 64; ++t) {
;         const LAS f32x4* rr = (const LAS f32x4*)(wl + 9216) + t * 4;
;         float z = bias;
; #pragma unroll
;         for (int q = 0; q < 4; ++q) { const f32x4 rv = rr[q]; z += rv[0] * w[4 * q] + rv[1] * w[4 * q + 1] + rv[2] * w[4 * q + 2] + rv[3] * w[4 * q + 3]; }
;         la[t] = (fminf(z, 0.f) - __logf(1.0f + __expf(-fabsf(z)))) * (1.0f / 16.0f);
;         tot += la[t];
;     }
	v_mov_b32_e32 v137, v146
	v_mov_b32_e32 v146, v141
	v_pk_mul_f32 v[140:141], v[8:9], v[146:147]
	s_nop 0
	v_pk_fma_f32 v[136:137], v[6:7], v[136:137], v[140:141]
	v_mov_b32_e32 v140, v142
	v_mov_b32_e32 v141, v148
	v_pk_fma_f32 v[136:137], v[2:3], v[140:141], v[136:137]
	v_mov_b32_e32 v148, v143
	v_pk_fma_f32 v[136:137], v[0:1], v[148:149], v[136:137]
	ds_read_b128 v[140:143], v102 offset:11392
	ds_read_b128 v[146:149], v102 offset:11408
	v_add_f32_e32 v135, v135, v136
	v_add_f32_e32 v135, v135, v137
	v_min_f32_e32 v136, 0, v135
	v_mul_f32_e64 v135, |v135|, s48
	v_exp_f32_e32 v135, v135
	s_nop 0
	v_add_f32_e32 v135, 1.0, v135
	v_cmp_gt_f32_e32 vcc, s49, v135
	s_nop 1
	v_cndmask_b32_e64 v137, 0, 32, vcc
	v_ldexp_f32 v135, v135, v137
	v_log_f32_e32 v135, v135
	s_nop 0
	v_mul_f32_e32 v137, 0x3f317217, v135
	v_fma_f32 v137, v135, s56, -v137
	v_fmac_f32_e32 v137, 0x3377d1cf, v135
	v_fmac_f32_e32 v137, 0x3f317217, v135
	v_cmp_lt_f32_e64 s[0:1], |v135|, s57
	s_nop 1
	v_cndmask_b32_e64 v135, v135, v137, s[0:1]
	v_cndmask_b32_e32 v137, 0, v90, vcc
	v_sub_f32_e32 v135, v135, v137
	s_waitcnt lgkmcnt(0)
	v_mov_b32_e32 v137, v146
	v_mov_b32_e32 v146, v141
	v_sub_f32_e32 v135, v136, v135
	v_mov_b32_e32 v136, v140
	v_pk_mul_f32 v[140:141], v[16:17], v[146:147]
	v_fmamk_f32 v135, v135, 0x3d800000, v134
	v_pk_fma_f32 v[136:137], v[14:15], v[136:137], v[140:141]
	v_mov_b32_e32 v140, v142
	v_mov_b32_e32 v141, v148
	v_pk_fma_f32 v[136:137], v[12:13], v[140:141], v[136:137]
	v_mov_b32_e32 v148, v143
	v_pk_fma_f32 v[136:137], v[10:11], v[148:149], v[136:137]
	ds_read_b128 v[140:143], v102 offset:11424
	ds_read_b128 v[146:149], v102 offset:11440
	v_add_f32_e32 v136, v100, v136
	v_add_f32_e32 v139, v136, v137
	s_waitcnt lgkmcnt(1)
	v_mov_b32_e32 v136, v140
	s_waitcnt lgkmcnt(0)
	v_mov_b32_e32 v137, v146
	v_mov_b32_e32 v146, v141
	v_pk_mul_f32 v[140:141], v[8:9], v[146:147]
	s_nop 0
	v_pk_fma_f32 v[136:137], v[6:7], v[136:137], v[140:141]
	v_mov_b32_e32 v140, v142
	v_mov_b32_e32 v141, v148
	v_pk_fma_f32 v[136:137], v[2:3], v[140:141], v[136:137]
	v_mov_b32_e32 v148, v143
	v_pk_fma_f32 v[136:137], v[0:1], v[148:149], v[136:137]
	ds_read_b128 v[140:143], v102 offset:11456
	ds_read_b128 v[146:149], v102 offset:11472
	v_add_f32_e32 v136, v139, v136
	v_add_f32_e32 v136, v136, v137
	v_min_f32_e32 v137, 0, v136
	v_mul_f32_e64 v136, |v136|, s48
	v_exp_f32_e32 v136, v136
	s_waitcnt lgkmcnt(0)
	v_mov_b32_e32 v151, v146
	v_mov_b32_e32 v146, v141
	v_mov_b32_e32 v150, v140
	v_add_f32_e32 v136, 1.0, v136
	v_cmp_gt_f32_e32 vcc, s49, v136
	v_pk_mul_f32 v[140:141], v[16:17], v[146:147]
	v_mov_b32_e32 v146, v142
	v_cndmask_b32_e64 v139, 0, 32, vcc
	v_ldexp_f32 v136, v136, v139
	v_log_f32_e32 v136, v136
	v_pk_fma_f32 v[140:141], v[14:15], v[150:151], v[140:141]
	v_mov_b32_e32 v147, v148
	v_pk_fma_f32 v[140:141], v[12:13], v[146:147], v[140:141]
	v_mul_f32_e32 v139, 0x3f317217, v136
	v_fma_f32 v139, v136, s56, -v139
	v_fmac_f32_e32 v139, 0x3377d1cf, v136
	v_fmac_f32_e32 v139, 0x3f317217, v136
	v_cmp_lt_f32_e64 s[0:1], |v136|, s57
	v_mov_b32_e32 v148, v143
	v_pk_fma_f32 v[140:141], v[10:11], v[148:149], v[140:141]
	v_cndmask_b32_e64 v136, v136, v139, s[0:1]
	v_cndmask_b32_e32 v139, 0, v90, vcc
	v_sub_f32_e32 v136, v136, v139
	v_sub_f32_e32 v136, v137, v136
	v_add_f32_e32 v137, v100, v140
	v_add_f32_e32 v137, v137, v141
	ds_read_b128 v[140:143], v102 offset:11488
	ds_read_b128 v[146:149], v102 offset:11504
	v_fmamk_f32 v136, v136, 0x3d800000, v135
	s_waitcnt lgkmcnt(1)
	v_mov_b32_e32 v150, v140
	s_waitcnt lgkmcnt(0)
	v_mov_b32_e32 v151, v146
	v_mov_b32_e32 v146, v141
	v_pk_mul_f32 v[140:141], v[8:9], v[146:147]
	v_mov_b32_e32 v146, v142
	v_pk_fma_f32 v[140:141], v[6:7], v[150:151], v[140:141]
	v_mov_b32_e32 v147, v148
	v_pk_fma_f32 v[140:141], v[2:3], v[146:147], v[140:141]
	v_mov_b32_e32 v148, v143
	v_pk_fma_f32 v[140:141], v[0:1], v[148:149], v[140:141]
	s_nop 0
	v_add_f32_e32 v137, v137, v140
	v_add_f32_e32 v137, v137, v141
	v_min_f32_e32 v139, 0, v137
	v_mul_f32_e64 v137, |v137|, s48
	v_exp_f32_e32 v137, v137
	s_nop 0
	v_add_f32_e32 v137, 1.0, v137
	v_cmp_gt_f32_e32 vcc, s49, v137
	s_nop 1
	v_cndmask_b32_e64 v140, 0, 32, vcc
	v_ldexp_f32 v137, v137, v140
	v_log_f32_e32 v137, v137
	s_nop 0
	v_mul_f32_e32 v140, 0x3f317217, v137
	v_fma_f32 v140, v137, s56, -v140
	v_fmac_f32_e32 v140, 0x3377d1cf, v137
	v_fmac_f32_e32 v140, 0x3f317217, v137
	v_cmp_lt_f32_e64 s[0:1], |v137|, s57
	s_nop 1
	v_cndmask_b32_e64 v137, v137, v140, s[0:1]
	v_cndmask_b32_e32 v140, 0, v90, vcc
	v_sub_f32_e32 v137, v137, v140
	ds_read_b128 v[140:143], v102 offset:11520
	ds_read_b128 v[146:149], v102 offset:11536
	v_sub_f32_e32 v137, v139, v137
	v_fmamk_f32 v137, v137, 0x3d800000, v136
	s_waitcnt lgkmcnt(1)
	v_mov_b32_e32 v150, v140
	s_waitcnt lgkmcnt(0)
	v_mov_b32_e32 v151, v146
	v_mov_b32_e32 v146, v141
	v_pk_mul_f32 v[140:141], v[16:17], v[146:147]
	v_mov_b32_e32 v146, v142
	v_pk_fma_f32 v[140:141], v[14:15], v[150:151], v[140:141]
	v_mov_b32_e32 v147, v148
	v_pk_fma_f32 v[140:141], v[12:13], v[146:147], v[140:141]
	v_mov_b32_e32 v148, v143
	v_pk_fma_f32 v[140:141], v[10:11], v[148:149], v[140:141]
	s_nop 0
	v_add_f32_e32 v139, v100, v140
	v_add_f32_e32 v139, v139, v141
	ds_read_b128 v[140:143], v102 offset:11552
	ds_read_b128 v[146:149], v102 offset:11568
	s_waitcnt lgkmcnt(1)
	v_mov_b32_e32 v150, v140
	s_waitcnt lgkmcnt(0)
; #define LAS __attribute__((address_space(3)))
; __device__ __forceinline__ void gla_upd_unit(LAS unsigned char* wl, const bf16* PROJ, const float* R, const float* w_gk2, const float* b_gk, float* UPD, float* DEC, int unit, int lane) {
;     ...
;     for (int t = 0; t < 64; ++t) {
;         const LAS f32x4* rr = (const LAS f32x4*)(wl + 9216) + t * 4;
;         float z = bias;
; #pragma unroll
;         for (int q = 0; q < 4; ++q) { const f32x4 rv = rr[q]; z += rv[0] * w[4 * q] + rv[1] * w[4 * q + 1] + rv[2] * w[4 * q + 2] + rv[3] * w[4 * q + 3]; }
;         la[t] = (fminf(z, 0.f) - __logf(1.0f + __expf(-fabsf(z)))) * (1.0f / 16.0f);
;         tot += la[t];
;     }
	v_mov_b32_e32 v151, v146
	v_mov_b32_e32 v146, v141
	v_pk_mul_f32 v[140:141], v[8:9], v[146:147]
	v_mov_b32_e32 v146, v142
	v_pk_fma_f32 v[140:141], v[6:7], v[150:151], v[140:141]
	v_mov_b32_e32 v147, v148
	v_pk_fma_f32 v[140:141], v[2:3], v[146:147], v[140:141]
	v_mov_b32_e32 v148, v143
	v_pk_fma_f32 v[140:141], v[0:1], v[148:149], v[140:141]
	s_nop 0
	v_add_f32_e32 v139, v139, v140
	v_add_f32_e32 v139, v139, v141
	v_min_f32_e32 v140, 0, v139
	v_mul_f32_e64 v139, |v139|, s48
	v_exp_f32_e32 v139, v139
	s_nop 0
	v_add_f32_e32 v139, 1.0, v139
	v_cmp_gt_f32_e32 vcc, s49, v139
	s_nop 1
	v_cndmask_b32_e64 v141, 0, 32, vcc
	v_ldexp_f32 v139, v139, v141
	v_log_f32_e32 v139, v139
	s_nop 0
	v_mul_f32_e32 v141, 0x3f317217, v139
	v_fma_f32 v141, v139, s56, -v141
	v_fmac_f32_e32 v141, 0x3377d1cf, v139
	v_fmac_f32_e32 v141, 0x3f317217, v139
	v_cmp_lt_f32_e64 s[0:1], |v139|, s57
	s_nop 1
	v_cndmask_b32_e64 v139, v139, v141, s[0:1]
	v_cndmask_b32_e32 v141, 0, v90, vcc
	v_sub_f32_e32 v139, v139, v141
	v_sub_f32_e32 v139, v140, v139
	ds_read_b128 v[140:143], v102 offset:11584
	ds_read_b128 v[146:149], v102 offset:11600
	v_fmamk_f32 v139, v139, 0x3d800000, v137
	s_waitcnt lgkmcnt(1)
	v_mov_b32_e32 v150, v140
	s_waitcnt lgkmcnt(0)
	v_mov_b32_e32 v151, v146
	v_mov_b32_e32 v146, v141
	v_pk_mul_f32 v[140:141], v[16:17], v[146:147]
	v_mov_b32_e32 v146, v142
	v_pk_fma_f32 v[140:141], v[14:15], v[150:151], v[140:141]
	v_mov_b32_e32 v147, v148
	v_pk_fma_f32 v[140:141], v[12:13], v[146:147], v[140:141]
	v_mov_b32_e32 v148, v143
	v_pk_fma_f32 v[140:141], v[10:11], v[148:149], v[140:141]
	s_nop 0
	v_add_f32_e32 v140, v100, v140
	v_add_f32_e32 v145, v140, v141
	ds_read_b128 v[140:143], v102 offset:11616
	ds_read_b128 v[146:149], v102 offset:11632
	s_waitcnt lgkmcnt(1)
	v_mov_b32_e32 v150, v140
	s_waitcnt lgkmcnt(0)
	v_mov_b32_e32 v151, v146
	v_mov_b32_e32 v146, v141
	v_pk_mul_f32 v[140:141], v[8:9], v[146:147]
	v_mov_b32_e32 v146, v142
	v_pk_fma_f32 v[140:141], v[6:7], v[150:151], v[140:141]
	v_mov_b32_e32 v147, v148
	v_pk_fma_f32 v[140:141], v[2:3], v[146:147], v[140:141]
	v_mov_b32_e32 v148, v143
	v_pk_fma_f32 v[140:141], v[0:1], v[148:149], v[140:141]
	ds_read_b128 v[146:149], v102 offset:11648
	ds_read_b128 v[150:153], v102 offset:11664
	v_add_f32_e32 v140, v145, v140
	v_add_f32_e32 v140, v140, v141
	v_min_f32_e32 v141, 0, v140
	v_mul_f32_e64 v140, |v140|, s48
	v_exp_f32_e32 v140, v140
	s_waitcnt lgkmcnt(0)
	v_mov_b32_e32 v143, v150
	v_mov_b32_e32 v150, v147
	v_add_f32_e32 v140, 1.0, v140
	v_cmp_gt_f32_e32 vcc, s49, v140
	s_nop 1
	v_cndmask_b32_e64 v142, 0, 32, vcc
	v_ldexp_f32 v140, v140, v142
	v_log_f32_e32 v140, v140
	s_nop 0
	v_mul_f32_e32 v142, 0x3f317217, v140
	v_fma_f32 v142, v140, s56, -v142
	v_fmac_f32_e32 v142, 0x3377d1cf, v140
	v_fmac_f32_e32 v142, 0x3f317217, v140
	v_cmp_lt_f32_e64 s[0:1], |v140|, s57
	s_nop 1
	v_cndmask_b32_e64 v140, v140, v142, s[0:1]
	v_cndmask_b32_e32 v142, 0, v90, vcc
	v_sub_f32_e32 v140, v140, v142
	v_mov_b32_e32 v142, v146
	v_pk_mul_f32 v[146:147], v[16:17], v[150:151]
	v_sub_f32_e32 v140, v141, v140
	v_pk_fma_f32 v[142:143], v[14:15], v[142:143], v[146:147]
	v_mov_b32_e32 v146, v148
	v_mov_b32_e32 v147, v152
	v_pk_fma_f32 v[142:143], v[12:13], v[146:147], v[142:143]
	v_mov_b32_e32 v152, v149
	v_pk_fma_f32 v[142:143], v[10:11], v[152:153], v[142:143]
	ds_read_b128 v[146:149], v102 offset:11680
	ds_read_b128 v[150:153], v102 offset:11696
	v_add_f32_e32 v141, v100, v142
	v_add_f32_e32 v141, v141, v143
	v_fmamk_f32 v140, v140, 0x3d800000, v139
	s_waitcnt lgkmcnt(1)
	v_mov_b32_e32 v142, v146
	s_waitcnt lgkmcnt(0)
	v_mov_b32_e32 v143, v150
	v_mov_b32_e32 v150, v147
	v_pk_mul_f32 v[146:147], v[8:9], v[150:151]
	s_nop 0
	v_pk_fma_f32 v[142:143], v[6:7], v[142:143], v[146:147]
	v_mov_b32_e32 v146, v148
	v_mov_b32_e32 v147, v152
	v_pk_fma_f32 v[142:143], v[2:3], v[146:147], v[142:143]
	v_mov_b32_e32 v152, v149
	v_pk_fma_f32 v[142:143], v[0:1], v[152:153], v[142:143]
	ds_read_b128 v[146:149], v102 offset:11712
	ds_read_b128 v[150:153], v102 offset:11728
	v_add_f32_e32 v141, v141, v142
	v_add_f32_e32 v141, v141, v143
	v_min_f32_e32 v142, 0, v141
	v_mul_f32_e64 v141, |v141|, s48
	v_exp_f32_e32 v141, v141
	s_nop 0
	v_add_f32_e32 v141, 1.0, v141
	v_cmp_gt_f32_e32 vcc, s49, v141
	s_nop 1
	v_cndmask_b32_e64 v143, 0, 32, vcc
	v_ldexp_f32 v141, v141, v143
	v_log_f32_e32 v141, v141
	s_nop 0
	v_mul_f32_e32 v143, 0x3f317217, v141
	v_fma_f32 v143, v141, s56, -v143
	v_fmac_f32_e32 v143, 0x3377d1cf, v141
	v_fmac_f32_e32 v143, 0x3f317217, v141
	v_cmp_lt_f32_e64 s[0:1], |v141|, s57
	s_nop 1
	v_cndmask_b32_e64 v141, v141, v143, s[0:1]
	v_cndmask_b32_e32 v143, 0, v90, vcc
	v_sub_f32_e32 v141, v141, v143
	s_waitcnt lgkmcnt(0)
	v_mov_b32_e32 v143, v150
	v_mov_b32_e32 v150, v147
	v_sub_f32_e32 v141, v142, v141
	v_mov_b32_e32 v142, v146
	v_pk_mul_f32 v[146:147], v[16:17], v[150:151]
	v_fmamk_f32 v141, v141, 0x3d800000, v140
	v_pk_fma_f32 v[142:143], v[14:15], v[142:143], v[146:147]
	v_mov_b32_e32 v146, v148
	v_mov_b32_e32 v147, v152
	v_pk_fma_f32 v[142:143], v[12:13], v[146:147], v[142:143]
	v_mov_b32_e32 v152, v149
	v_pk_fma_f32 v[142:143], v[10:11], v[152:153], v[142:143]
	ds_read_b128 v[146:149], v102 offset:11744
	ds_read_b128 v[150:153], v102 offset:11760
	v_add_f32_e32 v142, v100, v142
	v_add_f32_e32 v145, v142, v143
	s_waitcnt lgkmcnt(1)
	v_mov_b32_e32 v142, v146
	s_waitcnt lgkmcnt(0)
; #define LAS __attribute__((address_space(3)))
; __device__ __forceinline__ void gla_upd_unit(LAS unsigned char* wl, const bf16* PROJ, const float* R, const float* w_gk2, const float* b_gk, float* UPD, float* DEC, int unit, int lane) {
;     ...
;     for (int t = 0; t < 64; ++t) {
;         const LAS f32x4* rr = (const LAS f32x4*)(wl + 9216) + t * 4;
;         float z = bias;
; #pragma unroll
;         for (int q = 0; q < 4; ++q) { const f32x4 rv = rr[q]; z += rv[0] * w[4 * q] + rv[1] * w[4 * q + 1] + rv[2] * w[4 * q + 2] + rv[3] * w[4 * q + 3]; }
;         la[t] = (fminf(z, 0.f) - __logf(1.0f + __expf(-fabsf(z)))) * (1.0f / 16.0f);
;         tot += la[t];
;     }
	v_mov_b32_e32 v143, v150
	v_mov_b32_e32 v150, v147
	v_pk_mul_f32 v[146:147], v[8:9], v[150:151]
	s_nop 0
	v_pk_fma_f32 v[142:143], v[6:7], v[142:143], v[146:147]
	v_mov_b32_e32 v146, v148
	v_mov_b32_e32 v147, v152
	v_pk_fma_f32 v[142:143], v[2:3], v[146:147], v[142:143]
	v_mov_b32_e32 v152, v149
	v_pk_fma_f32 v[142:143], v[0:1], v[152:153], v[142:143]
	ds_read_b128 v[146:149], v102 offset:11776
	ds_read_b128 v[150:153], v102 offset:11792
	v_add_f32_e32 v142, v145, v142
	v_add_f32_e32 v142, v142, v143
	v_min_f32_e32 v143, 0, v142
	v_mul_f32_e64 v142, |v142|, s48
	v_exp_f32_e32 v142, v142
	s_waitcnt lgkmcnt(0)
	v_mov_b32_e32 v155, v150
	v_mov_b32_e32 v150, v147
	v_mov_b32_e32 v154, v146
	v_add_f32_e32 v142, 1.0, v142
	v_cmp_gt_f32_e32 vcc, s49, v142
	v_pk_mul_f32 v[146:147], v[16:17], v[150:151]
	v_mov_b32_e32 v150, v148
	v_cndmask_b32_e64 v145, 0, 32, vcc
	v_ldexp_f32 v142, v142, v145
	v_log_f32_e32 v142, v142
	v_pk_fma_f32 v[146:147], v[14:15], v[154:155], v[146:147]
	v_mov_b32_e32 v151, v152
	v_pk_fma_f32 v[146:147], v[12:13], v[150:151], v[146:147]
	v_mul_f32_e32 v145, 0x3f317217, v142
	v_fma_f32 v145, v142, s56, -v145
	v_fmac_f32_e32 v145, 0x3377d1cf, v142
	v_fmac_f32_e32 v145, 0x3f317217, v142
	v_cmp_lt_f32_e64 s[0:1], |v142|, s57
	v_mov_b32_e32 v152, v149
	v_pk_fma_f32 v[146:147], v[10:11], v[152:153], v[146:147]
	v_cndmask_b32_e64 v142, v142, v145, s[0:1]
	v_cndmask_b32_e32 v145, 0, v90, vcc
	v_sub_f32_e32 v142, v142, v145
	v_sub_f32_e32 v142, v143, v142
	v_add_f32_e32 v143, v100, v146
	v_add_f32_e32 v143, v143, v147
	ds_read_b128 v[146:149], v102 offset:11808
	ds_read_b128 v[150:153], v102 offset:11824
	v_fmamk_f32 v142, v142, 0x3d800000, v141
	s_waitcnt lgkmcnt(1)
	v_mov_b32_e32 v154, v146
	s_waitcnt lgkmcnt(0)
	v_mov_b32_e32 v155, v150
	v_mov_b32_e32 v150, v147
	v_pk_mul_f32 v[146:147], v[8:9], v[150:151]
	v_mov_b32_e32 v150, v148
	v_pk_fma_f32 v[146:147], v[6:7], v[154:155], v[146:147]
	v_mov_b32_e32 v151, v152
	v_pk_fma_f32 v[146:147], v[2:3], v[150:151], v[146:147]
	v_mov_b32_e32 v152, v149
	v_pk_fma_f32 v[146:147], v[0:1], v[152:153], v[146:147]
	s_nop 0
	v_add_f32_e32 v143, v143, v146
	v_add_f32_e32 v143, v143, v147
	v_min_f32_e32 v145, 0, v143
	v_mul_f32_e64 v143, |v143|, s48
	v_exp_f32_e32 v143, v143
	s_nop 0
	v_add_f32_e32 v143, 1.0, v143
	v_cmp_gt_f32_e32 vcc, s49, v143
	s_nop 1
	v_cndmask_b32_e64 v146, 0, 32, vcc
	v_ldexp_f32 v143, v143, v146
	v_log_f32_e32 v143, v143
	s_nop 0
	v_mul_f32_e32 v146, 0x3f317217, v143
	v_fma_f32 v146, v143, s56, -v146
	v_fmac_f32_e32 v146, 0x3377d1cf, v143
	v_fmac_f32_e32 v146, 0x3f317217, v143
	v_cmp_lt_f32_e64 s[0:1], |v143|, s57
	s_nop 1
	v_cndmask_b32_e64 v143, v143, v146, s[0:1]
	v_cndmask_b32_e32 v146, 0, v90, vcc
	v_sub_f32_e32 v143, v143, v146
	ds_read_b128 v[146:149], v102 offset:11840
	ds_read_b128 v[150:153], v102 offset:11856
	v_sub_f32_e32 v143, v145, v143
	v_fmamk_f32 v143, v143, 0x3d800000, v142
	s_waitcnt lgkmcnt(1)
	v_mov_b32_e32 v154, v146
	s_waitcnt lgkmcnt(0)
	v_mov_b32_e32 v155, v150
	v_mov_b32_e32 v150, v147
	v_pk_mul_f32 v[146:147], v[16:17], v[150:151]
	v_mov_b32_e32 v150, v148
	v_pk_fma_f32 v[146:147], v[14:15], v[154:155], v[146:147]
	v_mov_b32_e32 v151, v152
	v_pk_fma_f32 v[146:147], v[12:13], v[150:151], v[146:147]
	v_mov_b32_e32 v152, v149
	v_pk_fma_f32 v[146:147], v[10:11], v[152:153], v[146:147]
	s_nop 0
	v_add_f32_e32 v145, v100, v146
	v_add_f32_e32 v145, v145, v147
	ds_read_b128 v[146:149], v102 offset:11872
	ds_read_b128 v[150:153], v102 offset:11888
	s_waitcnt lgkmcnt(1)
	v_mov_b32_e32 v154, v146
	s_waitcnt lgkmcnt(0)
	v_mov_b32_e32 v155, v150
	v_mov_b32_e32 v150, v147
	v_pk_mul_f32 v[146:147], v[8:9], v[150:151]
	v_mov_b32_e32 v150, v148
	v_pk_fma_f32 v[146:147], v[6:7], v[154:155], v[146:147]
	v_mov_b32_e32 v151, v152
	v_pk_fma_f32 v[146:147], v[2:3], v[150:151], v[146:147]
	v_mov_b32_e32 v152, v149
	v_pk_fma_f32 v[146:147], v[0:1], v[152:153], v[146:147]
	s_nop 0
	v_add_f32_e32 v145, v145, v146
	v_add_f32_e32 v145, v145, v147
	v_min_f32_e32 v146, 0, v145
	v_mul_f32_e64 v145, |v145|, s48
	v_exp_f32_e32 v145, v145
	s_nop 0
	v_add_f32_e32 v145, 1.0, v145
	v_cmp_gt_f32_e32 vcc, s49, v145
	s_nop 1
	v_cndmask_b32_e64 v147, 0, 32, vcc
	v_ldexp_f32 v145, v145, v147
	v_log_f32_e32 v145, v145
	s_nop 0
	v_mul_f32_e32 v147, 0x3f317217, v145
	v_fma_f32 v147, v145, s56, -v147
	v_fmac_f32_e32 v147, 0x3377d1cf, v145
	v_fmac_f32_e32 v147, 0x3f317217, v145
	v_cmp_lt_f32_e64 s[0:1], |v145|, s57
	s_nop 1
	v_cndmask_b32_e64 v145, v145, v147, s[0:1]
	v_cndmask_b32_e32 v147, 0, v90, vcc
	v_sub_f32_e32 v145, v145, v147
	v_sub_f32_e32 v145, v146, v145
	ds_read_b128 v[146:149], v102 offset:11904
	ds_read_b128 v[150:153], v102 offset:11920
	v_fmamk_f32 v145, v145, 0x3d800000, v143
	s_waitcnt lgkmcnt(1)
	v_mov_b32_e32 v154, v146
	s_waitcnt lgkmcnt(0)
	v_mov_b32_e32 v155, v150
	v_mov_b32_e32 v150, v147
	v_pk_mul_f32 v[146:147], v[16:17], v[150:151]
	v_mov_b32_e32 v150, v148
	v_pk_fma_f32 v[146:147], v[14:15], v[154:155], v[146:147]
	v_mov_b32_e32 v151, v152
	v_pk_fma_f32 v[146:147], v[12:13], v[150:151], v[146:147]
	v_mov_b32_e32 v152, v149
	v_pk_fma_f32 v[146:147], v[10:11], v[152:153], v[146:147]
	s_nop 0
	v_add_f32_e32 v146, v100, v146
	v_add_f32_e32 v156, v146, v147
	ds_read_b128 v[146:149], v102 offset:11936
	ds_read_b128 v[150:153], v102 offset:11952
	s_waitcnt lgkmcnt(1)
	v_mov_b32_e32 v154, v146
	s_waitcnt lgkmcnt(0)
; #define LAS __attribute__((address_space(3)))
; __device__ __forceinline__ void gla_upd_unit(LAS unsigned char* wl, const bf16* PROJ, const float* R, const float* w_gk2, const float* b_gk, float* UPD, float* DEC, int unit, int lane) {
;     ...
;     for (int t = 0; t < 64; ++t) {
;         const LAS f32x4* rr = (const LAS f32x4*)(wl + 9216) + t * 4;
;         float z = bias;
; #pragma unroll
;         for (int q = 0; q < 4; ++q) { const f32x4 rv = rr[q]; z += rv[0] * w[4 * q] + rv[1] * w[4 * q + 1] + rv[2] * w[4 * q + 2] + rv[3] * w[4 * q + 3]; }
;         la[t] = (fminf(z, 0.f) - __logf(1.0f + __expf(-fabsf(z)))) * (1.0f / 16.0f);
;         tot += la[t];
;     }
	v_mov_b32_e32 v155, v150
	v_mov_b32_e32 v150, v147
	v_pk_mul_f32 v[146:147], v[8:9], v[150:151]
	v_mov_b32_e32 v150, v148
	v_pk_fma_f32 v[146:147], v[6:7], v[154:155], v[146:147]
	v_mov_b32_e32 v151, v152
	v_pk_fma_f32 v[146:147], v[2:3], v[150:151], v[146:147]
	v_mov_b32_e32 v152, v149
	v_pk_fma_f32 v[146:147], v[0:1], v[152:153], v[146:147]
	s_nop 0
	v_add_f32_e32 v146, v156, v146
	v_add_f32_e32 v146, v146, v147
	v_min_f32_e32 v147, 0, v146
	v_mul_f32_e64 v146, |v146|, s48
	v_exp_f32_e32 v146, v146
	s_nop 0
	v_add_f32_e32 v146, 1.0, v146
	v_cmp_gt_f32_e32 vcc, s49, v146
	s_nop 1
	v_cndmask_b32_e64 v148, 0, 32, vcc
	v_ldexp_f32 v146, v146, v148
	v_log_f32_e32 v146, v146
	s_nop 0
	v_mul_f32_e32 v148, 0x3f317217, v146
	v_fma_f32 v148, v146, s56, -v148
	v_fmac_f32_e32 v148, 0x3377d1cf, v146
	v_fmac_f32_e32 v148, 0x3f317217, v146
	v_cmp_lt_f32_e64 s[0:1], |v146|, s57
	s_nop 1
	v_cndmask_b32_e64 v146, v146, v148, s[0:1]
	v_cndmask_b32_e32 v148, 0, v90, vcc
	v_sub_f32_e32 v146, v146, v148
	ds_read_b128 v[148:151], v102 offset:11968
	ds_read_b128 v[152:155], v102 offset:11984
	v_sub_f32_e32 v146, v147, v146
	v_fmamk_f32 v146, v146, 0x3d800000, v145
	s_waitcnt lgkmcnt(1)
	v_mov_b32_e32 v156, v148
	s_waitcnt lgkmcnt(0)
	v_mov_b32_e32 v157, v152
	v_mov_b32_e32 v152, v149
	v_pk_mul_f32 v[148:149], v[16:17], v[152:153]
	v_mov_b32_e32 v152, v150
	v_pk_fma_f32 v[148:149], v[14:15], v[156:157], v[148:149]
	v_mov_b32_e32 v153, v154
	v_pk_fma_f32 v[148:149], v[12:13], v[152:153], v[148:149]
	v_mov_b32_e32 v154, v151
	v_pk_fma_f32 v[148:149], v[10:11], v[154:155], v[148:149]
	s_nop 0
	v_add_f32_e32 v147, v100, v148
	v_add_f32_e32 v147, v147, v149
	ds_read_b128 v[148:151], v102 offset:12000
	ds_read_b128 v[152:155], v102 offset:12016
	s_waitcnt lgkmcnt(1)
	v_mov_b32_e32 v156, v148
	s_waitcnt lgkmcnt(0)
	v_mov_b32_e32 v157, v152
	v_mov_b32_e32 v152, v149
	v_pk_mul_f32 v[148:149], v[8:9], v[152:153]
	v_mov_b32_e32 v152, v150
	v_pk_fma_f32 v[148:149], v[6:7], v[156:157], v[148:149]
	v_mov_b32_e32 v153, v154
	v_pk_fma_f32 v[148:149], v[2:3], v[152:153], v[148:149]
	v_mov_b32_e32 v154, v151
	v_pk_fma_f32 v[148:149], v[0:1], v[154:155], v[148:149]
	s_nop 0
	v_add_f32_e32 v147, v147, v148
	v_add_f32_e32 v147, v147, v149
	v_min_f32_e32 v148, 0, v147
	v_mul_f32_e64 v147, |v147|, s48
	v_exp_f32_e32 v147, v147
	s_nop 0
	v_add_f32_e32 v147, 1.0, v147
	v_cmp_gt_f32_e32 vcc, s49, v147
	s_nop 1
	v_cndmask_b32_e64 v149, 0, 32, vcc
	v_ldexp_f32 v147, v147, v149
	v_log_f32_e32 v147, v147
	s_nop 0
	v_mul_f32_e32 v149, 0x3f317217, v147
	v_fma_f32 v149, v147, s56, -v149
	v_fmac_f32_e32 v149, 0x3377d1cf, v147
	v_fmac_f32_e32 v149, 0x3f317217, v147
	v_cmp_lt_f32_e64 s[0:1], |v147|, s57
	s_nop 1
	v_cndmask_b32_e64 v147, v147, v149, s[0:1]
	v_cndmask_b32_e32 v149, 0, v90, vcc
	v_sub_f32_e32 v147, v147, v149
	v_sub_f32_e32 v147, v148, v147
	ds_read_b128 v[148:151], v102 offset:12032
	ds_read_b128 v[152:155], v102 offset:12048
	v_fmamk_f32 v147, v147, 0x3d800000, v146
	s_waitcnt lgkmcnt(1)
	v_mov_b32_e32 v156, v148
	s_waitcnt lgkmcnt(0)
	v_mov_b32_e32 v157, v152
	v_mov_b32_e32 v152, v149
	v_pk_mul_f32 v[148:149], v[16:17], v[152:153]
	v_mov_b32_e32 v152, v150
	v_pk_fma_f32 v[148:149], v[14:15], v[156:157], v[148:149]
	v_mov_b32_e32 v153, v154
	v_pk_fma_f32 v[148:149], v[12:13], v[152:153], v[148:149]
	v_mov_b32_e32 v154, v151
	v_pk_fma_f32 v[148:149], v[10:11], v[154:155], v[148:149]
	s_nop 0
	v_add_f32_e32 v148, v100, v148
	v_add_f32_e32 v158, v148, v149
	ds_read_b128 v[148:151], v102 offset:12064
	ds_read_b128 v[152:155], v102 offset:12080
	s_waitcnt lgkmcnt(1)
	v_mov_b32_e32 v156, v148
	s_waitcnt lgkmcnt(0)
	v_mov_b32_e32 v157, v152
	v_mov_b32_e32 v152, v149
	v_pk_mul_f32 v[148:149], v[8:9], v[152:153]
	v_mov_b32_e32 v152, v150
	v_pk_fma_f32 v[148:149], v[6:7], v[156:157], v[148:149]
	v_mov_b32_e32 v153, v154
	v_pk_fma_f32 v[148:149], v[2:3], v[152:153], v[148:149]
	v_mov_b32_e32 v154, v151
	v_pk_fma_f32 v[148:149], v[0:1], v[154:155], v[148:149]
	s_nop 0
	v_add_f32_e32 v148, v158, v148
	v_add_f32_e32 v148, v148, v149
	v_min_f32_e32 v149, 0, v148
	v_mul_f32_e64 v148, |v148|, s48
	v_exp_f32_e32 v148, v148
	s_nop 0
	v_add_f32_e32 v148, 1.0, v148
	v_cmp_gt_f32_e32 vcc, s49, v148
	s_nop 1
	v_cndmask_b32_e64 v150, 0, 32, vcc
	v_ldexp_f32 v148, v148, v150
	v_log_f32_e32 v148, v148
	s_nop 0
	v_mul_f32_e32 v150, 0x3f317217, v148
	v_fma_f32 v150, v148, s56, -v150
	v_fmac_f32_e32 v150, 0x3377d1cf, v148
	v_fmac_f32_e32 v150, 0x3f317217, v148
	v_cmp_lt_f32_e64 s[0:1], |v148|, s57
	s_nop 1
	v_cndmask_b32_e64 v148, v148, v150, s[0:1]
	v_cndmask_b32_e32 v150, 0, v90, vcc
	v_sub_f32_e32 v148, v148, v150
	ds_read_b128 v[150:153], v102 offset:12096
	ds_read_b128 v[154:157], v102 offset:12112
	v_sub_f32_e32 v148, v149, v148
	v_fmamk_f32 v148, v148, 0x3d800000, v147
	s_waitcnt lgkmcnt(1)
	v_mov_b32_e32 v158, v150
	s_waitcnt lgkmcnt(0)
	v_mov_b32_e32 v159, v154
	v_mov_b32_e32 v154, v151
	v_pk_mul_f32 v[150:151], v[16:17], v[154:155]
	v_mov_b32_e32 v154, v152
	v_pk_fma_f32 v[150:151], v[14:15], v[158:159], v[150:151]
	v_mov_b32_e32 v155, v156
	v_pk_fma_f32 v[150:151], v[12:13], v[154:155], v[150:151]
	v_mov_b32_e32 v156, v153
	v_pk_fma_f32 v[150:151], v[10:11], v[156:157], v[150:151]
	s_nop 0
	v_add_f32_e32 v149, v100, v150
	v_add_f32_e32 v149, v149, v151
	ds_read_b128 v[150:153], v102 offset:12128
	ds_read_b128 v[154:157], v102 offset:12144
	s_waitcnt lgkmcnt(1)
	v_mov_b32_e32 v158, v150
	s_waitcnt lgkmcnt(0)
; #define LAS __attribute__((address_space(3)))
; __device__ __forceinline__ void gla_upd_unit(LAS unsigned char* wl, const bf16* PROJ, const float* R, const float* w_gk2, const float* b_gk, float* UPD, float* DEC, int unit, int lane) {
;     ...
;     for (int t = 0; t < 64; ++t) {
;         const LAS f32x4* rr = (const LAS f32x4*)(wl + 9216) + t * 4;
;         float z = bias;
; #pragma unroll
;         for (int q = 0; q < 4; ++q) { const f32x4 rv = rr[q]; z += rv[0] * w[4 * q] + rv[1] * w[4 * q + 1] + rv[2] * w[4 * q + 2] + rv[3] * w[4 * q + 3]; }
;         la[t] = (fminf(z, 0.f) - __logf(1.0f + __expf(-fabsf(z)))) * (1.0f / 16.0f);
;         tot += la[t];
;     }
	v_mov_b32_e32 v159, v154
	v_mov_b32_e32 v154, v151
	v_pk_mul_f32 v[150:151], v[8:9], v[154:155]
	v_mov_b32_e32 v154, v152
	v_pk_fma_f32 v[150:151], v[6:7], v[158:159], v[150:151]
	v_mov_b32_e32 v155, v156
	v_pk_fma_f32 v[150:151], v[2:3], v[154:155], v[150:151]
	v_mov_b32_e32 v156, v153
	v_pk_fma_f32 v[150:151], v[0:1], v[156:157], v[150:151]
	s_nop 0
	v_add_f32_e32 v149, v149, v150
	v_add_f32_e32 v149, v149, v151
	v_min_f32_e32 v150, 0, v149
	v_mul_f32_e64 v149, |v149|, s48
	v_exp_f32_e32 v149, v149
	s_nop 0
	v_add_f32_e32 v149, 1.0, v149
	v_cmp_gt_f32_e32 vcc, s49, v149
	s_nop 1
	v_cndmask_b32_e64 v151, 0, 32, vcc
	v_ldexp_f32 v149, v149, v151
	v_log_f32_e32 v149, v149
	s_nop 0
	v_mul_f32_e32 v151, 0x3f317217, v149
	v_fma_f32 v151, v149, s56, -v151
	v_fmac_f32_e32 v151, 0x3377d1cf, v149
	v_fmac_f32_e32 v151, 0x3f317217, v149
	v_cmp_lt_f32_e64 s[0:1], |v149|, s57
	s_nop 1
	v_cndmask_b32_e64 v149, v149, v151, s[0:1]
	v_cndmask_b32_e32 v151, 0, v90, vcc
	v_sub_f32_e32 v149, v149, v151
	v_sub_f32_e32 v149, v150, v149
	ds_read_b128 v[150:153], v102 offset:12160
	ds_read_b128 v[154:157], v102 offset:12176
	v_fmamk_f32 v149, v149, 0x3d800000, v148
	s_waitcnt lgkmcnt(1)
	v_mov_b32_e32 v158, v150
	s_waitcnt lgkmcnt(0)
	v_mov_b32_e32 v159, v154
	v_mov_b32_e32 v154, v151
	v_pk_mul_f32 v[150:151], v[16:17], v[154:155]
	v_mov_b32_e32 v154, v152
	v_pk_fma_f32 v[150:151], v[14:15], v[158:159], v[150:151]
	v_mov_b32_e32 v155, v156
	v_pk_fma_f32 v[150:151], v[12:13], v[154:155], v[150:151]
	v_mov_b32_e32 v156, v153
	v_pk_fma_f32 v[150:151], v[10:11], v[156:157], v[150:151]
	s_nop 0
	v_add_f32_e32 v150, v100, v150
	v_add_f32_e32 v160, v150, v151
	ds_read_b128 v[150:153], v102 offset:12192
	ds_read_b128 v[154:157], v102 offset:12208
	s_waitcnt lgkmcnt(1)
	v_mov_b32_e32 v158, v150
	s_waitcnt lgkmcnt(0)
	v_mov_b32_e32 v159, v154
	v_mov_b32_e32 v154, v151
	v_pk_mul_f32 v[150:151], v[8:9], v[154:155]
	v_mov_b32_e32 v154, v152
	v_pk_fma_f32 v[150:151], v[6:7], v[158:159], v[150:151]
	v_mov_b32_e32 v155, v156
	v_pk_fma_f32 v[150:151], v[2:3], v[154:155], v[150:151]
	v_mov_b32_e32 v156, v153
	v_pk_fma_f32 v[150:151], v[0:1], v[156:157], v[150:151]
	s_nop 0
	v_add_f32_e32 v150, v160, v150
	v_add_f32_e32 v150, v150, v151
	v_min_f32_e32 v151, 0, v150
	v_mul_f32_e64 v150, |v150|, s48
	v_exp_f32_e32 v150, v150
	s_nop 0
	v_add_f32_e32 v150, 1.0, v150
	v_cmp_gt_f32_e32 vcc, s49, v150
	s_nop 1
	v_cndmask_b32_e64 v152, 0, 32, vcc
	v_ldexp_f32 v150, v150, v152
	v_log_f32_e32 v150, v150
	s_nop 0
	v_mul_f32_e32 v152, 0x3f317217, v150
	v_fma_f32 v152, v150, s56, -v152
	v_fmac_f32_e32 v152, 0x3377d1cf, v150
	v_fmac_f32_e32 v152, 0x3f317217, v150
	v_cmp_lt_f32_e64 s[0:1], |v150|, s57
	s_nop 1
	v_cndmask_b32_e64 v150, v150, v152, s[0:1]
	v_cndmask_b32_e32 v152, 0, v90, vcc
	v_sub_f32_e32 v150, v150, v152
	ds_read_b128 v[152:155], v102 offset:12224
	ds_read_b128 v[156:159], v102 offset:12240
	v_sub_f32_e32 v150, v151, v150
	v_fmamk_f32 v150, v150, 0x3d800000, v149
	s_waitcnt lgkmcnt(1)
	v_mov_b32_e32 v160, v152
	s_waitcnt lgkmcnt(0)
	v_mov_b32_e32 v161, v156
	v_mov_b32_e32 v156, v153
	v_pk_mul_f32 v[152:153], v[16:17], v[156:157]
	v_mov_b32_e32 v156, v154
	v_pk_fma_f32 v[152:153], v[14:15], v[160:161], v[152:153]
	v_mov_b32_e32 v157, v158
	v_pk_fma_f32 v[152:153], v[12:13], v[156:157], v[152:153]
	v_mov_b32_e32 v158, v155
	v_pk_fma_f32 v[152:153], v[10:11], v[158:159], v[152:153]
	s_nop 0
	v_add_f32_e32 v151, v100, v152
	v_add_f32_e32 v151, v151, v153
	ds_read_b128 v[152:155], v102 offset:12256
	ds_read_b128 v[156:159], v102 offset:12272
	s_waitcnt lgkmcnt(1)
	v_mov_b32_e32 v160, v152
	s_waitcnt lgkmcnt(0)
	v_mov_b32_e32 v161, v156
	v_mov_b32_e32 v156, v153
	v_pk_mul_f32 v[152:153], v[8:9], v[156:157]
	v_mov_b32_e32 v156, v154
	v_pk_fma_f32 v[152:153], v[6:7], v[160:161], v[152:153]
	v_mov_b32_e32 v157, v158
	v_pk_fma_f32 v[152:153], v[2:3], v[156:157], v[152:153]
	v_mov_b32_e32 v158, v155
	v_pk_fma_f32 v[152:153], v[0:1], v[158:159], v[152:153]
	s_nop 0
	v_add_f32_e32 v151, v151, v152
	v_add_f32_e32 v151, v151, v153
	v_min_f32_e32 v152, 0, v151
	v_mul_f32_e64 v151, |v151|, s48
	v_exp_f32_e32 v151, v151
	s_nop 0
	v_add_f32_e32 v151, 1.0, v151
	v_cmp_gt_f32_e32 vcc, s49, v151
	s_nop 1
	v_cndmask_b32_e64 v153, 0, 32, vcc
	v_ldexp_f32 v151, v151, v153
	v_log_f32_e32 v151, v151
	s_nop 0
	v_mul_f32_e32 v153, 0x3f317217, v151
	v_fma_f32 v153, v151, s56, -v153
	v_fmac_f32_e32 v153, 0x3377d1cf, v151
	v_fmac_f32_e32 v153, 0x3f317217, v151
	v_cmp_lt_f32_e64 s[0:1], |v151|, s57
	s_nop 1
	v_cndmask_b32_e64 v151, v151, v153, s[0:1]
	v_cndmask_b32_e32 v153, 0, v90, vcc
	v_sub_f32_e32 v151, v151, v153
	v_sub_f32_e32 v151, v152, v151
	ds_read_b128 v[152:155], v102 offset:12288
	ds_read_b128 v[156:159], v102 offset:12304
	v_fmamk_f32 v151, v151, 0x3d800000, v150
	s_waitcnt lgkmcnt(1)
	v_mov_b32_e32 v160, v152
	s_waitcnt lgkmcnt(0)
	v_mov_b32_e32 v161, v156
	v_mov_b32_e32 v156, v153
	v_pk_mul_f32 v[152:153], v[16:17], v[156:157]
	v_mov_b32_e32 v156, v154
	v_pk_fma_f32 v[152:153], v[14:15], v[160:161], v[152:153]
	v_mov_b32_e32 v157, v158
	v_pk_fma_f32 v[152:153], v[12:13], v[156:157], v[152:153]
	v_mov_b32_e32 v158, v155
	v_pk_fma_f32 v[152:153], v[10:11], v[158:159], v[152:153]
	s_nop 0
	v_add_f32_e32 v152, v100, v152
	v_add_f32_e32 v162, v152, v153
	ds_read_b128 v[152:155], v102 offset:12320
	ds_read_b128 v[156:159], v102 offset:12336
	s_waitcnt lgkmcnt(1)
	v_mov_b32_e32 v160, v152
	s_waitcnt lgkmcnt(0)
; #define LAS __attribute__((address_space(3)))
; __device__ __forceinline__ void gla_upd_unit(LAS unsigned char* wl, const bf16* PROJ, const float* R, const float* w_gk2, const float* b_gk, float* UPD, float* DEC, int unit, int lane) {
;     ...
;     for (int t = 0; t < 64; ++t) {
;         const LAS f32x4* rr = (const LAS f32x4*)(wl + 9216) + t * 4;
;         float z = bias;
; #pragma unroll
;         for (int q = 0; q < 4; ++q) { const f32x4 rv = rr[q]; z += rv[0] * w[4 * q] + rv[1] * w[4 * q + 1] + rv[2] * w[4 * q + 2] + rv[3] * w[4 * q + 3]; }
;         la[t] = (fminf(z, 0.f) - __logf(1.0f + __expf(-fabsf(z)))) * (1.0f / 16.0f);
;         tot += la[t];
;     }
	v_mov_b32_e32 v161, v156
	v_mov_b32_e32 v156, v153
	v_pk_mul_f32 v[152:153], v[8:9], v[156:157]
	v_mov_b32_e32 v156, v154
	v_pk_fma_f32 v[152:153], v[6:7], v[160:161], v[152:153]
	v_mov_b32_e32 v157, v158
	v_pk_fma_f32 v[152:153], v[2:3], v[156:157], v[152:153]
	v_mov_b32_e32 v158, v155
	v_pk_fma_f32 v[152:153], v[0:1], v[158:159], v[152:153]
	s_nop 0
	v_add_f32_e32 v152, v162, v152
	v_add_f32_e32 v152, v152, v153
	v_min_f32_e32 v153, 0, v152
	v_mul_f32_e64 v152, |v152|, s48
	v_exp_f32_e32 v152, v152
	s_nop 0
	v_add_f32_e32 v152, 1.0, v152
	v_cmp_gt_f32_e32 vcc, s49, v152
	s_nop 1
	v_cndmask_b32_e64 v154, 0, 32, vcc
	v_ldexp_f32 v152, v152, v154
	v_log_f32_e32 v152, v152
	s_nop 0
	v_mul_f32_e32 v154, 0x3f317217, v152
	v_fma_f32 v154, v152, s56, -v154
	v_fmac_f32_e32 v154, 0x3377d1cf, v152
	v_fmac_f32_e32 v154, 0x3f317217, v152
	v_cmp_lt_f32_e64 s[0:1], |v152|, s57
	s_nop 1
	v_cndmask_b32_e64 v152, v152, v154, s[0:1]
	v_cndmask_b32_e32 v154, 0, v90, vcc
	v_sub_f32_e32 v152, v152, v154
	ds_read_b128 v[154:157], v102 offset:12352
	ds_read_b128 v[158:161], v102 offset:12368
	v_sub_f32_e32 v152, v153, v152
	v_fmamk_f32 v152, v152, 0x3d800000, v151
	s_waitcnt lgkmcnt(1)
	v_mov_b32_e32 v162, v154
	s_waitcnt lgkmcnt(0)
	v_mov_b32_e32 v163, v158
	v_mov_b32_e32 v158, v155
	v_pk_mul_f32 v[154:155], v[16:17], v[158:159]
	v_mov_b32_e32 v158, v156
	v_pk_fma_f32 v[154:155], v[14:15], v[162:163], v[154:155]
	v_mov_b32_e32 v159, v160
	v_pk_fma_f32 v[154:155], v[12:13], v[158:159], v[154:155]
	v_mov_b32_e32 v160, v157
	v_pk_fma_f32 v[154:155], v[10:11], v[160:161], v[154:155]
	s_nop 0
	v_add_f32_e32 v153, v100, v154
	v_add_f32_e32 v153, v153, v155
	ds_read_b128 v[154:157], v102 offset:12384
	ds_read_b128 v[158:161], v102 offset:12400
	s_waitcnt lgkmcnt(1)
	v_mov_b32_e32 v162, v154
	s_waitcnt lgkmcnt(0)
	v_mov_b32_e32 v163, v158
	v_mov_b32_e32 v158, v155
	v_pk_mul_f32 v[154:155], v[8:9], v[158:159]
	v_mov_b32_e32 v158, v156
	v_pk_fma_f32 v[154:155], v[6:7], v[162:163], v[154:155]
	v_mov_b32_e32 v159, v160
	v_pk_fma_f32 v[154:155], v[2:3], v[158:159], v[154:155]
	v_mov_b32_e32 v160, v157
	v_pk_fma_f32 v[154:155], v[0:1], v[160:161], v[154:155]
	s_nop 0
	v_add_f32_e32 v153, v153, v154
	v_add_f32_e32 v153, v153, v155
	v_min_f32_e32 v154, 0, v153
	v_mul_f32_e64 v153, |v153|, s48
	v_exp_f32_e32 v153, v153
	s_nop 0
	v_add_f32_e32 v153, 1.0, v153
	v_cmp_gt_f32_e32 vcc, s49, v153
	s_nop 1
	v_cndmask_b32_e64 v155, 0, 32, vcc
	v_ldexp_f32 v153, v153, v155
	v_log_f32_e32 v153, v153
	s_nop 0
	v_mul_f32_e32 v155, 0x3f317217, v153
	v_fma_f32 v155, v153, s56, -v155
	v_fmac_f32_e32 v155, 0x3377d1cf, v153
	v_fmac_f32_e32 v155, 0x3f317217, v153
	v_cmp_lt_f32_e64 s[0:1], |v153|, s57
	s_nop 1
	v_cndmask_b32_e64 v153, v153, v155, s[0:1]
	v_cndmask_b32_e32 v155, 0, v90, vcc
	v_sub_f32_e32 v153, v153, v155
	v_sub_f32_e32 v153, v154, v153
	ds_read_b128 v[154:157], v102 offset:12416
	ds_read_b128 v[158:161], v102 offset:12432
	v_fmamk_f32 v153, v153, 0x3d800000, v152
	s_waitcnt lgkmcnt(1)
	v_mov_b32_e32 v162, v154
	s_waitcnt lgkmcnt(0)
	v_mov_b32_e32 v163, v158
	v_mov_b32_e32 v158, v155
	v_pk_mul_f32 v[154:155], v[16:17], v[158:159]
	v_mov_b32_e32 v158, v156
	v_pk_fma_f32 v[154:155], v[14:15], v[162:163], v[154:155]
	v_mov_b32_e32 v159, v160
	v_pk_fma_f32 v[154:155], v[12:13], v[158:159], v[154:155]
	v_mov_b32_e32 v160, v157
	v_pk_fma_f32 v[154:155], v[10:11], v[160:161], v[154:155]
	s_nop 0
	v_add_f32_e32 v154, v100, v154
	v_add_f32_e32 v164, v154, v155
	ds_read_b128 v[154:157], v102 offset:12448
	ds_read_b128 v[158:161], v102 offset:12464
	s_waitcnt lgkmcnt(1)
	v_mov_b32_e32 v162, v154
	s_waitcnt lgkmcnt(0)
	v_mov_b32_e32 v163, v158
	v_mov_b32_e32 v158, v155
	v_pk_mul_f32 v[154:155], v[8:9], v[158:159]
	v_mov_b32_e32 v158, v156
	v_pk_fma_f32 v[154:155], v[6:7], v[162:163], v[154:155]
	v_mov_b32_e32 v159, v160
	v_pk_fma_f32 v[154:155], v[2:3], v[158:159], v[154:155]
	v_mov_b32_e32 v160, v157
	v_pk_fma_f32 v[154:155], v[0:1], v[160:161], v[154:155]
	s_nop 0
	v_add_f32_e32 v154, v164, v154
	v_add_f32_e32 v154, v154, v155
	v_min_f32_e32 v155, 0, v154
	v_mul_f32_e64 v154, |v154|, s48
	v_exp_f32_e32 v154, v154
	s_nop 0
	v_add_f32_e32 v154, 1.0, v154
	v_cmp_gt_f32_e32 vcc, s49, v154
	s_nop 1
	v_cndmask_b32_e64 v156, 0, 32, vcc
	v_ldexp_f32 v154, v154, v156
	v_log_f32_e32 v154, v154
	s_nop 0
	v_mul_f32_e32 v156, 0x3f317217, v154
	v_fma_f32 v156, v154, s56, -v156
	v_fmac_f32_e32 v156, 0x3377d1cf, v154
	v_fmac_f32_e32 v156, 0x3f317217, v154
	v_cmp_lt_f32_e64 s[0:1], |v154|, s57
	s_nop 1
	v_cndmask_b32_e64 v154, v154, v156, s[0:1]
	v_cndmask_b32_e32 v156, 0, v90, vcc
	v_sub_f32_e32 v154, v154, v156
	ds_read_b128 v[156:159], v102 offset:12480
	ds_read_b128 v[160:163], v102 offset:12496
	v_sub_f32_e32 v154, v155, v154
	v_fmamk_f32 v154, v154, 0x3d800000, v153
	s_waitcnt lgkmcnt(1)
	v_mov_b32_e32 v164, v156
	s_waitcnt lgkmcnt(0)
	v_mov_b32_e32 v165, v160
	v_mov_b32_e32 v160, v157
	v_pk_mul_f32 v[156:157], v[16:17], v[160:161]
	v_mov_b32_e32 v160, v158
	v_pk_fma_f32 v[156:157], v[14:15], v[164:165], v[156:157]
	v_mov_b32_e32 v161, v162
	v_pk_fma_f32 v[156:157], v[12:13], v[160:161], v[156:157]
	v_mov_b32_e32 v162, v159
	v_pk_fma_f32 v[156:157], v[10:11], v[162:163], v[156:157]
	s_nop 0
	v_add_f32_e32 v155, v100, v156
	v_add_f32_e32 v155, v155, v157
	ds_read_b128 v[156:159], v102 offset:12512
	ds_read_b128 v[160:163], v102 offset:12528
	s_waitcnt lgkmcnt(1)
	v_mov_b32_e32 v164, v156
	s_waitcnt lgkmcnt(0)
; #define LAS __attribute__((address_space(3)))
; __device__ __forceinline__ void gla_upd_unit(LAS unsigned char* wl, const bf16* PROJ, const float* R, const float* w_gk2, const float* b_gk, float* UPD, float* DEC, int unit, int lane) {
;     ...
;     for (int t = 0; t < 64; ++t) {
;         const LAS f32x4* rr = (const LAS f32x4*)(wl + 9216) + t * 4;
;         float z = bias;
; #pragma unroll
;         for (int q = 0; q < 4; ++q) { const f32x4 rv = rr[q]; z += rv[0] * w[4 * q] + rv[1] * w[4 * q + 1] + rv[2] * w[4 * q + 2] + rv[3] * w[4 * q + 3]; }
;         la[t] = (fminf(z, 0.f) - __logf(1.0f + __expf(-fabsf(z)))) * (1.0f / 16.0f);
;         tot += la[t];
;     }
	v_mov_b32_e32 v165, v160
	v_mov_b32_e32 v160, v157
	v_pk_mul_f32 v[156:157], v[8:9], v[160:161]
	v_mov_b32_e32 v160, v158
	v_pk_fma_f32 v[156:157], v[6:7], v[164:165], v[156:157]
	v_mov_b32_e32 v161, v162
	v_pk_fma_f32 v[156:157], v[2:3], v[160:161], v[156:157]
	v_mov_b32_e32 v162, v159
	v_pk_fma_f32 v[156:157], v[0:1], v[162:163], v[156:157]
	s_nop 0
	v_add_f32_e32 v155, v155, v156
	v_add_f32_e32 v155, v155, v157
	v_min_f32_e32 v156, 0, v155
	v_mul_f32_e64 v155, |v155|, s48
	v_exp_f32_e32 v155, v155
	s_nop 0
	v_add_f32_e32 v155, 1.0, v155
	v_cmp_gt_f32_e32 vcc, s49, v155
	s_nop 1
	v_cndmask_b32_e64 v157, 0, 32, vcc
	v_ldexp_f32 v155, v155, v157
	v_log_f32_e32 v155, v155
	s_nop 0
	v_mul_f32_e32 v157, 0x3f317217, v155
	v_fma_f32 v157, v155, s56, -v157
	v_fmac_f32_e32 v157, 0x3377d1cf, v155
	v_fmac_f32_e32 v157, 0x3f317217, v155
	v_cmp_lt_f32_e64 s[0:1], |v155|, s57
	s_nop 1
	v_cndmask_b32_e64 v155, v155, v157, s[0:1]
	v_cndmask_b32_e32 v157, 0, v90, vcc
	v_sub_f32_e32 v155, v155, v157
	v_sub_f32_e32 v155, v156, v155
	ds_read_b128 v[156:159], v102 offset:12544
	ds_read_b128 v[160:163], v102 offset:12560
	v_fmamk_f32 v155, v155, 0x3d800000, v154
	s_waitcnt lgkmcnt(1)
	v_mov_b32_e32 v164, v156
	s_waitcnt lgkmcnt(0)
	v_mov_b32_e32 v165, v160
	v_mov_b32_e32 v160, v157
	v_pk_mul_f32 v[156:157], v[16:17], v[160:161]
	v_mov_b32_e32 v160, v158
	v_pk_fma_f32 v[156:157], v[14:15], v[164:165], v[156:157]
	v_mov_b32_e32 v161, v162
	v_pk_fma_f32 v[156:157], v[12:13], v[160:161], v[156:157]
	v_mov_b32_e32 v162, v159
	v_pk_fma_f32 v[156:157], v[10:11], v[162:163], v[156:157]
	s_nop 0
	v_add_f32_e32 v156, v100, v156
	v_add_f32_e32 v166, v156, v157
	ds_read_b128 v[156:159], v102 offset:12576
	ds_read_b128 v[160:163], v102 offset:12592
	s_waitcnt lgkmcnt(1)
	v_mov_b32_e32 v164, v156
	s_waitcnt lgkmcnt(0)
	v_mov_b32_e32 v165, v160
	v_mov_b32_e32 v160, v157
	v_pk_mul_f32 v[156:157], v[8:9], v[160:161]
	v_mov_b32_e32 v160, v158
	v_pk_fma_f32 v[156:157], v[6:7], v[164:165], v[156:157]
	v_mov_b32_e32 v161, v162
	v_pk_fma_f32 v[156:157], v[2:3], v[160:161], v[156:157]
	v_mov_b32_e32 v162, v159
	v_pk_fma_f32 v[156:157], v[0:1], v[162:163], v[156:157]
	s_nop 0
	v_add_f32_e32 v156, v166, v156
	v_add_f32_e32 v156, v156, v157
	v_min_f32_e32 v157, 0, v156
	v_mul_f32_e64 v156, |v156|, s48
	v_exp_f32_e32 v156, v156
	s_nop 0
	v_add_f32_e32 v156, 1.0, v156
	v_cmp_gt_f32_e32 vcc, s49, v156
	s_nop 1
	v_cndmask_b32_e64 v158, 0, 32, vcc
	v_ldexp_f32 v156, v156, v158
	v_log_f32_e32 v156, v156
	s_nop 0
	v_mul_f32_e32 v158, 0x3f317217, v156
	v_fma_f32 v158, v156, s56, -v158
	v_fmac_f32_e32 v158, 0x3377d1cf, v156
	v_fmac_f32_e32 v158, 0x3f317217, v156
	v_cmp_lt_f32_e64 s[0:1], |v156|, s57
	s_nop 1
	v_cndmask_b32_e64 v156, v156, v158, s[0:1]
	v_cndmask_b32_e32 v158, 0, v90, vcc
	v_sub_f32_e32 v156, v156, v158
	ds_read_b128 v[158:161], v102 offset:12608
	ds_read_b128 v[162:165], v102 offset:12624
	v_sub_f32_e32 v156, v157, v156
	v_fmamk_f32 v156, v156, 0x3d800000, v155
	s_waitcnt lgkmcnt(1)
	v_mov_b32_e32 v166, v158
	s_waitcnt lgkmcnt(0)
	v_mov_b32_e32 v167, v162
	v_mov_b32_e32 v162, v159
	v_pk_mul_f32 v[158:159], v[16:17], v[162:163]
	v_mov_b32_e32 v162, v160
	v_pk_fma_f32 v[158:159], v[14:15], v[166:167], v[158:159]
	v_mov_b32_e32 v163, v164
	v_pk_fma_f32 v[158:159], v[12:13], v[162:163], v[158:159]
	v_mov_b32_e32 v164, v161
	v_pk_fma_f32 v[158:159], v[10:11], v[164:165], v[158:159]
	s_nop 0
	v_add_f32_e32 v157, v100, v158
	v_add_f32_e32 v157, v157, v159
	ds_read_b128 v[158:161], v102 offset:12640
	ds_read_b128 v[162:165], v102 offset:12656
	s_waitcnt lgkmcnt(1)
	v_mov_b32_e32 v166, v158
	s_waitcnt lgkmcnt(0)
	v_mov_b32_e32 v167, v162
	v_mov_b32_e32 v162, v159
	v_pk_mul_f32 v[158:159], v[8:9], v[162:163]
	v_mov_b32_e32 v162, v160
	v_pk_fma_f32 v[158:159], v[6:7], v[166:167], v[158:159]
	v_mov_b32_e32 v163, v164
	v_pk_fma_f32 v[158:159], v[2:3], v[162:163], v[158:159]
	v_mov_b32_e32 v164, v161
	v_pk_fma_f32 v[158:159], v[0:1], v[164:165], v[158:159]
	s_nop 0
	v_add_f32_e32 v157, v157, v158
	v_add_f32_e32 v157, v157, v159
	v_min_f32_e32 v158, 0, v157
	v_mul_f32_e64 v157, |v157|, s48
	v_exp_f32_e32 v157, v157
	s_nop 0
	v_add_f32_e32 v157, 1.0, v157
	v_cmp_gt_f32_e32 vcc, s49, v157
	s_nop 1
	v_cndmask_b32_e64 v159, 0, 32, vcc
	v_ldexp_f32 v157, v157, v159
	v_log_f32_e32 v157, v157
	s_nop 0
	v_mul_f32_e32 v159, 0x3f317217, v157
	v_fma_f32 v159, v157, s56, -v159
	v_fmac_f32_e32 v159, 0x3377d1cf, v157
	v_fmac_f32_e32 v159, 0x3f317217, v157
	v_cmp_lt_f32_e64 s[0:1], |v157|, s57
	s_nop 1
	v_cndmask_b32_e64 v157, v157, v159, s[0:1]
	v_cndmask_b32_e32 v159, 0, v90, vcc
	v_sub_f32_e32 v157, v157, v159
	v_sub_f32_e32 v157, v158, v157
	ds_read_b128 v[158:161], v102 offset:12672
	ds_read_b128 v[162:165], v102 offset:12688
	v_fmamk_f32 v157, v157, 0x3d800000, v156
	s_waitcnt lgkmcnt(1)
	v_mov_b32_e32 v166, v158
	s_waitcnt lgkmcnt(0)
	v_mov_b32_e32 v167, v162
	v_mov_b32_e32 v162, v159
	v_pk_mul_f32 v[158:159], v[16:17], v[162:163]
	v_mov_b32_e32 v162, v160
	v_pk_fma_f32 v[158:159], v[14:15], v[166:167], v[158:159]
	v_mov_b32_e32 v163, v164
	v_pk_fma_f32 v[158:159], v[12:13], v[162:163], v[158:159]
	v_mov_b32_e32 v164, v161
	v_pk_fma_f32 v[158:159], v[10:11], v[164:165], v[158:159]
	s_nop 0
	v_add_f32_e32 v158, v100, v158
	v_add_f32_e32 v168, v158, v159
	ds_read_b128 v[158:161], v102 offset:12704
	ds_read_b128 v[162:165], v102 offset:12720
	s_waitcnt lgkmcnt(1)
	v_mov_b32_e32 v166, v158
	s_waitcnt lgkmcnt(0)
; #define LAS __attribute__((address_space(3)))
; __device__ __forceinline__ void gla_upd_unit(LAS unsigned char* wl, const bf16* PROJ, const float* R, const float* w_gk2, const float* b_gk, float* UPD, float* DEC, int unit, int lane) {
;     ...
;     for (int t = 0; t < 64; ++t) {
;         const LAS f32x4* rr = (const LAS f32x4*)(wl + 9216) + t * 4;
;         float z = bias;
; #pragma unroll
;         for (int q = 0; q < 4; ++q) { const f32x4 rv = rr[q]; z += rv[0] * w[4 * q] + rv[1] * w[4 * q + 1] + rv[2] * w[4 * q + 2] + rv[3] * w[4 * q + 3]; }
;         la[t] = (fminf(z, 0.f) - __logf(1.0f + __expf(-fabsf(z)))) * (1.0f / 16.0f);
;         tot += la[t];
;     }
	v_mov_b32_e32 v167, v162
	v_mov_b32_e32 v162, v159
	v_pk_mul_f32 v[158:159], v[8:9], v[162:163]
	v_mov_b32_e32 v162, v160
	v_pk_fma_f32 v[158:159], v[6:7], v[166:167], v[158:159]
	v_mov_b32_e32 v163, v164
	v_pk_fma_f32 v[158:159], v[2:3], v[162:163], v[158:159]
	v_mov_b32_e32 v164, v161
	v_pk_fma_f32 v[158:159], v[0:1], v[164:165], v[158:159]
	s_nop 0
	v_add_f32_e32 v158, v168, v158
	v_add_f32_e32 v158, v158, v159
	v_min_f32_e32 v159, 0, v158
	v_mul_f32_e64 v158, |v158|, s48
	v_exp_f32_e32 v158, v158
	s_nop 0
	v_add_f32_e32 v158, 1.0, v158
	v_cmp_gt_f32_e32 vcc, s49, v158
	s_nop 1
	v_cndmask_b32_e64 v160, 0, 32, vcc
	v_ldexp_f32 v158, v158, v160
	v_log_f32_e32 v158, v158
	s_nop 0
	v_mul_f32_e32 v160, 0x3f317217, v158
	v_fma_f32 v160, v158, s56, -v160
	v_fmac_f32_e32 v160, 0x3377d1cf, v158
	v_fmac_f32_e32 v160, 0x3f317217, v158
	v_cmp_lt_f32_e64 s[0:1], |v158|, s57
	s_nop 1
	v_cndmask_b32_e64 v158, v158, v160, s[0:1]
	v_cndmask_b32_e32 v160, 0, v90, vcc
	v_sub_f32_e32 v158, v158, v160
	ds_read_b128 v[160:163], v102 offset:12736
	ds_read_b128 v[164:167], v102 offset:12752
	v_sub_f32_e32 v158, v159, v158
	v_fmamk_f32 v158, v158, 0x3d800000, v157
	s_waitcnt lgkmcnt(1)
	v_mov_b32_e32 v168, v160
	s_waitcnt lgkmcnt(0)
	v_mov_b32_e32 v169, v164
	v_mov_b32_e32 v164, v161
	v_pk_mul_f32 v[160:161], v[16:17], v[164:165]
	v_mov_b32_e32 v164, v162
	v_pk_fma_f32 v[160:161], v[14:15], v[168:169], v[160:161]
	v_mov_b32_e32 v165, v166
	v_pk_fma_f32 v[160:161], v[12:13], v[164:165], v[160:161]
	v_mov_b32_e32 v166, v163
	v_pk_fma_f32 v[160:161], v[10:11], v[166:167], v[160:161]
	s_nop 0
	v_add_f32_e32 v159, v100, v160
	v_add_f32_e32 v159, v159, v161
	ds_read_b128 v[160:163], v102 offset:12768
	ds_read_b128 v[164:167], v102 offset:12784
	s_waitcnt lgkmcnt(1)
	v_mov_b32_e32 v168, v160
	s_waitcnt lgkmcnt(0)
	v_mov_b32_e32 v169, v164
	v_mov_b32_e32 v164, v161
	v_pk_mul_f32 v[160:161], v[8:9], v[164:165]
	v_mov_b32_e32 v164, v162
	v_pk_fma_f32 v[160:161], v[6:7], v[168:169], v[160:161]
	v_mov_b32_e32 v165, v166
	v_pk_fma_f32 v[160:161], v[2:3], v[164:165], v[160:161]
	v_mov_b32_e32 v166, v163
	v_pk_fma_f32 v[160:161], v[0:1], v[166:167], v[160:161]
	s_nop 0
	v_add_f32_e32 v159, v159, v160
	v_add_f32_e32 v159, v159, v161
	v_min_f32_e32 v160, 0, v159
	v_mul_f32_e64 v159, |v159|, s48
	v_exp_f32_e32 v159, v159
	s_nop 0
	v_add_f32_e32 v159, 1.0, v159
	v_cmp_gt_f32_e32 vcc, s49, v159
	s_nop 1
	v_cndmask_b32_e64 v161, 0, 32, vcc
	v_ldexp_f32 v159, v159, v161
	v_log_f32_e32 v159, v159
	s_nop 0
	v_mul_f32_e32 v161, 0x3f317217, v159
	v_fma_f32 v161, v159, s56, -v161
	v_fmac_f32_e32 v161, 0x3377d1cf, v159
	v_fmac_f32_e32 v161, 0x3f317217, v159
	v_cmp_lt_f32_e64 s[0:1], |v159|, s57
	s_nop 1
	v_cndmask_b32_e64 v159, v159, v161, s[0:1]
	v_cndmask_b32_e32 v161, 0, v90, vcc
	v_sub_f32_e32 v159, v159, v161
	v_sub_f32_e32 v159, v160, v159
	ds_read_b128 v[160:163], v102 offset:12800
	ds_read_b128 v[164:167], v102 offset:12816
	v_fmamk_f32 v159, v159, 0x3d800000, v158
	s_waitcnt lgkmcnt(1)
	v_mov_b32_e32 v168, v160
	s_waitcnt lgkmcnt(0)
	v_mov_b32_e32 v169, v164
	v_mov_b32_e32 v164, v161
	v_pk_mul_f32 v[160:161], v[16:17], v[164:165]
	v_mov_b32_e32 v164, v162
	v_pk_fma_f32 v[160:161], v[14:15], v[168:169], v[160:161]
	v_mov_b32_e32 v165, v166
	v_pk_fma_f32 v[160:161], v[12:13], v[164:165], v[160:161]
	v_mov_b32_e32 v166, v163
	v_pk_fma_f32 v[160:161], v[10:11], v[166:167], v[160:161]
	s_nop 0
	v_add_f32_e32 v160, v100, v160
	v_add_f32_e32 v170, v160, v161
	ds_read_b128 v[160:163], v102 offset:12832
	ds_read_b128 v[164:167], v102 offset:12848
	s_waitcnt lgkmcnt(1)
	v_mov_b32_e32 v168, v160
	s_waitcnt lgkmcnt(0)
	v_mov_b32_e32 v169, v164
	v_mov_b32_e32 v164, v161
	v_pk_mul_f32 v[160:161], v[8:9], v[164:165]
	v_mov_b32_e32 v164, v162
	v_pk_fma_f32 v[160:161], v[6:7], v[168:169], v[160:161]
	v_mov_b32_e32 v165, v166
	v_pk_fma_f32 v[160:161], v[2:3], v[164:165], v[160:161]
	v_mov_b32_e32 v166, v163
	v_pk_fma_f32 v[160:161], v[0:1], v[166:167], v[160:161]
	s_nop 0
	v_add_f32_e32 v160, v170, v160
	v_add_f32_e32 v160, v160, v161
	v_min_f32_e32 v161, 0, v160
	v_mul_f32_e64 v160, |v160|, s48
	v_exp_f32_e32 v160, v160
	s_nop 0
	v_add_f32_e32 v160, 1.0, v160
	v_cmp_gt_f32_e32 vcc, s49, v160
	s_nop 1
	v_cndmask_b32_e64 v162, 0, 32, vcc
	v_ldexp_f32 v160, v160, v162
	v_log_f32_e32 v160, v160
	s_nop 0
	v_mul_f32_e32 v162, 0x3f317217, v160
	v_fma_f32 v162, v160, s56, -v162
	v_fmac_f32_e32 v162, 0x3377d1cf, v160
	v_fmac_f32_e32 v162, 0x3f317217, v160
	v_cmp_lt_f32_e64 s[0:1], |v160|, s57
	s_nop 1
	v_cndmask_b32_e64 v160, v160, v162, s[0:1]
	v_cndmask_b32_e32 v162, 0, v90, vcc
	v_sub_f32_e32 v160, v160, v162
	ds_read_b128 v[162:165], v102 offset:12864
	ds_read_b128 v[166:169], v102 offset:12880
	v_sub_f32_e32 v160, v161, v160
	v_fmamk_f32 v160, v160, 0x3d800000, v159
	s_waitcnt lgkmcnt(1)
	v_mov_b32_e32 v170, v162
	s_waitcnt lgkmcnt(0)
	v_mov_b32_e32 v171, v166
	v_mov_b32_e32 v166, v163
	v_pk_mul_f32 v[162:163], v[16:17], v[166:167]
	v_mov_b32_e32 v166, v164
	v_pk_fma_f32 v[162:163], v[14:15], v[170:171], v[162:163]
	v_mov_b32_e32 v167, v168
	v_pk_fma_f32 v[162:163], v[12:13], v[166:167], v[162:163]
	v_mov_b32_e32 v168, v165
	v_pk_fma_f32 v[162:163], v[10:11], v[168:169], v[162:163]
	s_nop 0
	v_add_f32_e32 v161, v100, v162
	v_add_f32_e32 v161, v161, v163
	ds_read_b128 v[162:165], v102 offset:12896
	ds_read_b128 v[166:169], v102 offset:12912
	s_waitcnt lgkmcnt(1)
	v_mov_b32_e32 v170, v162
	s_waitcnt lgkmcnt(0)
; #define LAS __attribute__((address_space(3)))
; __device__ __forceinline__ void gla_upd_unit(LAS unsigned char* wl, const bf16* PROJ, const float* R, const float* w_gk2, const float* b_gk, float* UPD, float* DEC, int unit, int lane) {
;     ...
;     for (int t = 0; t < 64; ++t) {
;         const LAS f32x4* rr = (const LAS f32x4*)(wl + 9216) + t * 4;
;         float z = bias;
; #pragma unroll
;         for (int q = 0; q < 4; ++q) { const f32x4 rv = rr[q]; z += rv[0] * w[4 * q] + rv[1] * w[4 * q + 1] + rv[2] * w[4 * q + 2] + rv[3] * w[4 * q + 3]; }
;         la[t] = (fminf(z, 0.f) - __logf(1.0f + __expf(-fabsf(z)))) * (1.0f / 16.0f);
;         tot += la[t];
;     }
	v_mov_b32_e32 v171, v166
	v_mov_b32_e32 v166, v163
	v_pk_mul_f32 v[162:163], v[8:9], v[166:167]
	v_mov_b32_e32 v166, v164
	v_pk_fma_f32 v[162:163], v[6:7], v[170:171], v[162:163]
	v_mov_b32_e32 v167, v168
	v_pk_fma_f32 v[162:163], v[2:3], v[166:167], v[162:163]
	v_mov_b32_e32 v168, v165
	v_pk_fma_f32 v[162:163], v[0:1], v[168:169], v[162:163]
	s_nop 0
	v_add_f32_e32 v161, v161, v162
	v_add_f32_e32 v161, v161, v163
	v_min_f32_e32 v162, 0, v161
	v_mul_f32_e64 v161, |v161|, s48
	v_exp_f32_e32 v161, v161
	s_nop 0
	v_add_f32_e32 v161, 1.0, v161
	v_cmp_gt_f32_e32 vcc, s49, v161
	s_nop 1
	v_cndmask_b32_e64 v163, 0, 32, vcc
	v_ldexp_f32 v161, v161, v163
	v_log_f32_e32 v161, v161
	s_nop 0
	v_mul_f32_e32 v163, 0x3f317217, v161
	v_fma_f32 v163, v161, s56, -v163
	v_fmac_f32_e32 v163, 0x3377d1cf, v161
	v_fmac_f32_e32 v163, 0x3f317217, v161
	v_cmp_lt_f32_e64 s[0:1], |v161|, s57
	s_nop 1
	v_cndmask_b32_e64 v161, v161, v163, s[0:1]
	v_cndmask_b32_e32 v163, 0, v90, vcc
	v_sub_f32_e32 v161, v161, v163
	v_sub_f32_e32 v161, v162, v161
	ds_read_b128 v[162:165], v102 offset:12928
	ds_read_b128 v[166:169], v102 offset:12944
	v_fmamk_f32 v161, v161, 0x3d800000, v160
	s_waitcnt lgkmcnt(1)
	v_mov_b32_e32 v170, v162
	s_waitcnt lgkmcnt(0)
	v_mov_b32_e32 v171, v166
	v_mov_b32_e32 v166, v163
	v_pk_mul_f32 v[162:163], v[16:17], v[166:167]
	v_mov_b32_e32 v166, v164
	v_pk_fma_f32 v[162:163], v[14:15], v[170:171], v[162:163]
	v_mov_b32_e32 v167, v168
	v_pk_fma_f32 v[162:163], v[12:13], v[166:167], v[162:163]
	v_mov_b32_e32 v168, v165
	v_pk_fma_f32 v[162:163], v[10:11], v[168:169], v[162:163]
	s_nop 0
	v_add_f32_e32 v162, v100, v162
	v_add_f32_e32 v172, v162, v163
	ds_read_b128 v[162:165], v102 offset:12960
	ds_read_b128 v[166:169], v102 offset:12976
	s_waitcnt lgkmcnt(1)
	v_mov_b32_e32 v170, v162
	s_waitcnt lgkmcnt(0)
	v_mov_b32_e32 v171, v166
	v_mov_b32_e32 v166, v163
	v_pk_mul_f32 v[162:163], v[8:9], v[166:167]
	v_mov_b32_e32 v166, v164
	v_pk_fma_f32 v[162:163], v[6:7], v[170:171], v[162:163]
	v_mov_b32_e32 v167, v168
	v_pk_fma_f32 v[162:163], v[2:3], v[166:167], v[162:163]
	v_mov_b32_e32 v168, v165
	v_pk_fma_f32 v[162:163], v[0:1], v[168:169], v[162:163]
	s_nop 0
	v_add_f32_e32 v162, v172, v162
	v_add_f32_e32 v162, v162, v163
	v_min_f32_e32 v163, 0, v162
	v_mul_f32_e64 v162, |v162|, s48
	v_exp_f32_e32 v162, v162
	s_nop 0
	v_add_f32_e32 v162, 1.0, v162
	v_cmp_gt_f32_e32 vcc, s49, v162
	s_nop 1
	v_cndmask_b32_e64 v164, 0, 32, vcc
	v_ldexp_f32 v162, v162, v164
	v_log_f32_e32 v162, v162
	s_nop 0
	v_mul_f32_e32 v164, 0x3f317217, v162
	v_fma_f32 v164, v162, s56, -v164
	v_fmac_f32_e32 v164, 0x3377d1cf, v162
	v_fmac_f32_e32 v164, 0x3f317217, v162
	v_cmp_lt_f32_e64 s[0:1], |v162|, s57
	s_nop 1
	v_cndmask_b32_e64 v162, v162, v164, s[0:1]
	v_cndmask_b32_e32 v164, 0, v90, vcc
	v_sub_f32_e32 v162, v162, v164
	ds_read_b128 v[164:167], v102 offset:12992
	ds_read_b128 v[168:171], v102 offset:13008
	v_sub_f32_e32 v162, v163, v162
	v_fmamk_f32 v162, v162, 0x3d800000, v161
	s_waitcnt lgkmcnt(1)
	v_mov_b32_e32 v172, v164
	s_waitcnt lgkmcnt(0)
	v_mov_b32_e32 v173, v168
	v_mov_b32_e32 v168, v165
	v_pk_mul_f32 v[164:165], v[16:17], v[168:169]
	v_mov_b32_e32 v168, v166
	v_pk_fma_f32 v[164:165], v[14:15], v[172:173], v[164:165]
	v_mov_b32_e32 v169, v170
	v_pk_fma_f32 v[164:165], v[12:13], v[168:169], v[164:165]
	v_mov_b32_e32 v170, v167
	v_pk_fma_f32 v[164:165], v[10:11], v[170:171], v[164:165]
	s_nop 0
	v_add_f32_e32 v163, v100, v164
	v_add_f32_e32 v163, v163, v165
	ds_read_b128 v[164:167], v102 offset:13024
	ds_read_b128 v[168:171], v102 offset:13040
	s_waitcnt lgkmcnt(1)
	v_mov_b32_e32 v172, v164
	s_waitcnt lgkmcnt(0)
	v_mov_b32_e32 v173, v168
	v_mov_b32_e32 v168, v165
	v_pk_mul_f32 v[164:165], v[8:9], v[168:169]
	v_mov_b32_e32 v168, v166
	v_pk_fma_f32 v[164:165], v[6:7], v[172:173], v[164:165]
	v_mov_b32_e32 v169, v170
	v_pk_fma_f32 v[164:165], v[2:3], v[168:169], v[164:165]
	v_mov_b32_e32 v170, v167
	v_pk_fma_f32 v[164:165], v[0:1], v[170:171], v[164:165]
	s_nop 0
	v_add_f32_e32 v163, v163, v164
	v_add_f32_e32 v163, v163, v165
	v_min_f32_e32 v164, 0, v163
	v_mul_f32_e64 v163, |v163|, s48
	v_exp_f32_e32 v163, v163
	s_nop 0
	v_add_f32_e32 v163, 1.0, v163
	v_cmp_gt_f32_e32 vcc, s49, v163
	s_nop 1
	v_cndmask_b32_e64 v165, 0, 32, vcc
	v_ldexp_f32 v163, v163, v165
	v_log_f32_e32 v163, v163
	s_nop 0
	v_mul_f32_e32 v165, 0x3f317217, v163
	v_fma_f32 v165, v163, s56, -v165
	v_fmac_f32_e32 v165, 0x3377d1cf, v163
	v_fmac_f32_e32 v165, 0x3f317217, v163
	v_cmp_lt_f32_e64 s[0:1], |v163|, s57
	s_nop 1
	v_cndmask_b32_e64 v163, v163, v165, s[0:1]
	v_cndmask_b32_e32 v165, 0, v90, vcc
	v_sub_f32_e32 v163, v163, v165
	v_sub_f32_e32 v163, v164, v163
	ds_read_b128 v[164:167], v102 offset:13056
	ds_read_b128 v[168:171], v102 offset:13072
	v_fmamk_f32 v163, v163, 0x3d800000, v162
	s_waitcnt lgkmcnt(1)
	v_mov_b32_e32 v172, v164
	s_waitcnt lgkmcnt(0)
	v_mov_b32_e32 v173, v168
	v_mov_b32_e32 v168, v165
	v_pk_mul_f32 v[164:165], v[16:17], v[168:169]
	v_mov_b32_e32 v168, v166
	v_pk_fma_f32 v[164:165], v[14:15], v[172:173], v[164:165]
	v_mov_b32_e32 v169, v170
	v_pk_fma_f32 v[164:165], v[12:13], v[168:169], v[164:165]
	v_mov_b32_e32 v170, v167
	v_pk_fma_f32 v[164:165], v[10:11], v[170:171], v[164:165]
	s_nop 0
	v_add_f32_e32 v164, v100, v164
	v_add_f32_e32 v174, v164, v165
	ds_read_b128 v[164:167], v102 offset:13088
	ds_read_b128 v[168:171], v102 offset:13104
	s_waitcnt lgkmcnt(1)
	v_mov_b32_e32 v172, v164
	s_waitcnt lgkmcnt(0)
; #define LAS __attribute__((address_space(3)))
; __device__ __forceinline__ void gla_upd_unit(LAS unsigned char* wl, const bf16* PROJ, const float* R, const float* w_gk2, const float* b_gk, float* UPD, float* DEC, int unit, int lane) {
;     ...
;     for (int t = 0; t < 64; ++t) {
;         const LAS f32x4* rr = (const LAS f32x4*)(wl + 9216) + t * 4;
;         float z = bias;
; #pragma unroll
;         for (int q = 0; q < 4; ++q) { const f32x4 rv = rr[q]; z += rv[0] * w[4 * q] + rv[1] * w[4 * q + 1] + rv[2] * w[4 * q + 2] + rv[3] * w[4 * q + 3]; }
;         la[t] = (fminf(z, 0.f) - __logf(1.0f + __expf(-fabsf(z)))) * (1.0f / 16.0f);
;         tot += la[t];
;     }
	v_mov_b32_e32 v173, v168
	v_mov_b32_e32 v168, v165
	v_pk_mul_f32 v[164:165], v[8:9], v[168:169]
	v_mov_b32_e32 v168, v166
	v_pk_fma_f32 v[164:165], v[6:7], v[172:173], v[164:165]
	v_mov_b32_e32 v169, v170
	v_pk_fma_f32 v[164:165], v[2:3], v[168:169], v[164:165]
	v_mov_b32_e32 v170, v167
	v_pk_fma_f32 v[164:165], v[0:1], v[170:171], v[164:165]
	s_nop 0
	v_add_f32_e32 v164, v174, v164
	v_add_f32_e32 v164, v164, v165
	v_min_f32_e32 v165, 0, v164
	v_mul_f32_e64 v164, |v164|, s48
	v_exp_f32_e32 v164, v164
	s_nop 0
	v_add_f32_e32 v164, 1.0, v164
	v_cmp_gt_f32_e32 vcc, s49, v164
	s_nop 1
	v_cndmask_b32_e64 v166, 0, 32, vcc
	v_ldexp_f32 v164, v164, v166
	v_log_f32_e32 v164, v164
	s_nop 0
	v_mul_f32_e32 v166, 0x3f317217, v164
	v_fma_f32 v166, v164, s56, -v166
	v_fmac_f32_e32 v166, 0x3377d1cf, v164
	v_fmac_f32_e32 v166, 0x3f317217, v164
	v_cmp_lt_f32_e64 s[0:1], |v164|, s57
	s_nop 1
	v_cndmask_b32_e64 v164, v164, v166, s[0:1]
	v_cndmask_b32_e32 v166, 0, v90, vcc
	v_sub_f32_e32 v164, v164, v166
	ds_read_b128 v[166:169], v102 offset:13120
	ds_read_b128 v[170:173], v102 offset:13136
	v_sub_f32_e32 v164, v165, v164
	v_fmamk_f32 v164, v164, 0x3d800000, v163
	s_waitcnt lgkmcnt(1)
	v_mov_b32_e32 v174, v166
	s_waitcnt lgkmcnt(0)
	v_mov_b32_e32 v175, v170
	v_mov_b32_e32 v170, v167
	v_pk_mul_f32 v[166:167], v[16:17], v[170:171]
	v_mov_b32_e32 v170, v168
	v_pk_fma_f32 v[166:167], v[14:15], v[174:175], v[166:167]
	v_mov_b32_e32 v171, v172
	v_pk_fma_f32 v[166:167], v[12:13], v[170:171], v[166:167]
	v_mov_b32_e32 v172, v169
	v_pk_fma_f32 v[166:167], v[10:11], v[172:173], v[166:167]
	s_nop 0
	v_add_f32_e32 v165, v100, v166
	v_add_f32_e32 v165, v165, v167
	ds_read_b128 v[166:169], v102 offset:13152
	ds_read_b128 v[170:173], v102 offset:13168
	s_waitcnt lgkmcnt(1)
	v_mov_b32_e32 v174, v166
	s_waitcnt lgkmcnt(0)
	v_mov_b32_e32 v175, v170
	v_mov_b32_e32 v170, v167
	v_pk_mul_f32 v[166:167], v[8:9], v[170:171]
	v_mov_b32_e32 v170, v168
	v_pk_fma_f32 v[166:167], v[6:7], v[174:175], v[166:167]
	v_mov_b32_e32 v171, v172
	v_pk_fma_f32 v[166:167], v[2:3], v[170:171], v[166:167]
	v_mov_b32_e32 v172, v169
	v_pk_fma_f32 v[166:167], v[0:1], v[172:173], v[166:167]
	s_nop 0
	v_add_f32_e32 v165, v165, v166
	v_add_f32_e32 v165, v165, v167
	v_min_f32_e32 v166, 0, v165
	v_mul_f32_e64 v165, |v165|, s48
	v_exp_f32_e32 v165, v165
	s_nop 0
	v_add_f32_e32 v165, 1.0, v165
	v_cmp_gt_f32_e32 vcc, s49, v165
	s_nop 1
	v_cndmask_b32_e64 v167, 0, 32, vcc
	v_ldexp_f32 v165, v165, v167
	v_log_f32_e32 v165, v165
	s_nop 0
	v_mul_f32_e32 v167, 0x3f317217, v165
	v_fma_f32 v167, v165, s56, -v167
	v_fmac_f32_e32 v167, 0x3377d1cf, v165
	v_fmac_f32_e32 v167, 0x3f317217, v165
	v_cmp_lt_f32_e64 s[0:1], |v165|, s57
	s_nop 1
	v_cndmask_b32_e64 v165, v165, v167, s[0:1]
	v_cndmask_b32_e32 v167, 0, v90, vcc
	v_sub_f32_e32 v165, v165, v167
	v_sub_f32_e32 v165, v166, v165
	ds_read_b128 v[166:169], v102 offset:13184
	ds_read_b128 v[170:173], v102 offset:13200
	v_fmamk_f32 v165, v165, 0x3d800000, v164
	s_waitcnt lgkmcnt(1)
	v_mov_b32_e32 v174, v166
	s_waitcnt lgkmcnt(0)
	v_mov_b32_e32 v175, v170
	v_mov_b32_e32 v170, v167
	v_pk_mul_f32 v[166:167], v[16:17], v[170:171]
	v_mov_b32_e32 v170, v168
	v_pk_fma_f32 v[166:167], v[14:15], v[174:175], v[166:167]
	v_mov_b32_e32 v171, v172
	v_pk_fma_f32 v[166:167], v[12:13], v[170:171], v[166:167]
	v_mov_b32_e32 v172, v169
	v_pk_fma_f32 v[166:167], v[10:11], v[172:173], v[166:167]
	s_nop 0
	v_add_f32_e32 v166, v100, v166
	v_add_f32_e32 v176, v166, v167
	ds_read_b128 v[166:169], v102 offset:13216
	ds_read_b128 v[170:173], v102 offset:13232
	s_waitcnt lgkmcnt(1)
	v_mov_b32_e32 v174, v166
	s_waitcnt lgkmcnt(0)
	v_mov_b32_e32 v175, v170
	v_mov_b32_e32 v170, v167
	v_pk_mul_f32 v[166:167], v[8:9], v[170:171]
	v_mov_b32_e32 v170, v168
	v_pk_fma_f32 v[166:167], v[6:7], v[174:175], v[166:167]
	v_mov_b32_e32 v171, v172
	v_pk_fma_f32 v[166:167], v[2:3], v[170:171], v[166:167]
	v_mov_b32_e32 v172, v169
	v_pk_fma_f32 v[166:167], v[0:1], v[172:173], v[166:167]
	s_nop 0
	v_add_f32_e32 v166, v176, v166
	v_add_f32_e32 v166, v166, v167
	v_min_f32_e32 v167, 0, v166
	v_mul_f32_e64 v166, |v166|, s48
	v_exp_f32_e32 v166, v166
	s_nop 0
	v_add_f32_e32 v166, 1.0, v166
	v_cmp_gt_f32_e32 vcc, s49, v166
	s_nop 1
	v_cndmask_b32_e64 v168, 0, 32, vcc
	v_ldexp_f32 v166, v166, v168
	v_log_f32_e32 v166, v166
	s_nop 0
	v_mul_f32_e32 v168, 0x3f317217, v166
	v_fma_f32 v168, v166, s56, -v168
	v_fmac_f32_e32 v168, 0x3377d1cf, v166
	v_fmac_f32_e32 v168, 0x3f317217, v166
	v_cmp_lt_f32_e64 s[0:1], |v166|, s57
	s_nop 1
	v_cndmask_b32_e64 v166, v166, v168, s[0:1]
	v_cndmask_b32_e32 v168, 0, v90, vcc
	v_sub_f32_e32 v166, v166, v168
	ds_read_b128 v[168:171], v102 offset:13248
	ds_read_b128 v[172:175], v102 offset:13264
	v_sub_f32_e32 v166, v167, v166
	v_fmamk_f32 v166, v166, 0x3d800000, v165
	s_waitcnt lgkmcnt(1)
	v_mov_b32_e32 v176, v168
	s_waitcnt lgkmcnt(0)
	v_mov_b32_e32 v177, v172
	v_mov_b32_e32 v172, v169
	v_pk_mul_f32 v[16:17], v[16:17], v[172:173]
	s_nop 0
	v_pk_fma_f32 v[14:15], v[14:15], v[176:177], v[16:17]
	v_mov_b32_e32 v16, v170
	v_mov_b32_e32 v17, v174
	v_pk_fma_f32 v[12:13], v[12:13], v[16:17], v[14:15]
	v_mov_b32_e32 v174, v171
	v_pk_fma_f32 v[10:11], v[10:11], v[174:175], v[12:13]
	s_nop 0
	v_add_f32_e32 v10, v100, v10
	v_add_f32_e32 v100, v10, v11
	ds_read_b128 v[10:13], v102 offset:13280
	ds_read_b128 v[14:17], v102 offset:13296
	s_waitcnt lgkmcnt(1)
	v_mov_b32_e32 v168, v10
	s_waitcnt lgkmcnt(0)
; #define LAS __attribute__((address_space(3)))
; __device__ __forceinline__ unsigned pk2(float lo, float hi) { return f2bf(lo) | (f2bf(hi) << 16); }
; __device__ __forceinline__ void gla_upd_unit(LAS unsigned char* wl, const bf16* PROJ, const float* R, const float* w_gk2, const float* b_gk, float* UPD, float* DEC, int unit, int lane) {
;     ...
;     for (int t = 0; t < 64; ++t) {
;         const LAS f32x4* rr = (const LAS f32x4*)(wl + 9216) + t * 4;
;         float z = bias;
; #pragma unroll
;         for (int q = 0; q < 4; ++q) { const f32x4 rv = rr[q]; z += rv[0] * w[4 * q] + rv[1] * w[4 * q + 1] + rv[2] * w[4 * q + 2] + rv[3] * w[4 * q + 3]; }
;         la[t] = (fminf(z, 0.f) - __logf(1.0f + __expf(-fabsf(z)))) * (1.0f / 16.0f);
;         tot += la[t];
;     }
;     DEC[(size_t)unit * 64 + kk] = __expf(tot);
; #pragma unroll
;     for (int t = 0; t < 32; ++t) kv1[t] = kp[(size_t)(t + 32) * NPROJ];
;     float run = 0.f;
; #pragma unroll
;     for (int t = 0; t < 32; t += 2) {
;         run += la[t]; const float d0 = bf2f(kv0[t]) * __expf(tot - run);
;         run += la[t + 1]; const float d1 = bf2f(kv0[t + 1]) * __expf(tot - run);
;         KD32[kk * (KS / 2) + (t >> 1)] = pk2(d0, d1);
;     }
; #pragma unroll
;     for (int t = 0; t < 32; t += 2) {
;         run += la[32 + t]; const float d0 = bf2f(kv1[t]) * __expf(tot - run);
;         run += la[33 + t]; const float d1 = bf2f(kv1[t + 1]) * __expf(tot - run);
;         KD32[kk * (KS / 2) + 16 + (t >> 1)] = pk2(d0, d1);
;     }
	v_mov_b32_e32 v169, v14
	v_mov_b32_e32 v14, v11
	v_pk_mul_f32 v[8:9], v[8:9], v[14:15]
	v_lshlrev_b32_e32 v11, 16, v96
	v_pk_fma_f32 v[6:7], v[6:7], v[168:169], v[8:9]
	v_mov_b32_e32 v8, v12
	v_mov_b32_e32 v9, v16
	v_pk_fma_f32 v[2:3], v[2:3], v[8:9], v[6:7]
	v_mov_b32_e32 v16, v13
	v_pk_fma_f32 v[0:1], v[0:1], v[16:17], v[2:3]
	v_lshlrev_b32_e32 v9, 16, v92
	v_add_f32_e32 v0, v100, v0
	v_add_f32_e32 v0, v0, v1
	v_min_f32_e32 v1, 0, v0
	v_mul_f32_e64 v0, |v0|, s48
	v_exp_f32_e32 v0, v0
	v_lshlrev_b32_e32 v8, 16, v93
	v_lshlrev_b32_e32 v10, 16, v94
	v_add_f32_e32 v0, 1.0, v0
	v_cmp_gt_f32_e32 vcc, s49, v0
	s_nop 1
	v_cndmask_b32_e64 v2, 0, 32, vcc
	v_ldexp_f32 v0, v0, v2
	v_log_f32_e32 v0, v0
	s_nop 0
	v_mul_f32_e32 v2, 0x3f317217, v0
	v_fma_f32 v2, v0, s56, -v2
	v_fmac_f32_e32 v2, 0x3377d1cf, v0
	v_fmac_f32_e32 v2, 0x3f317217, v0
	v_cmp_lt_f32_e64 s[0:1], |v0|, s57
	s_nop 1
	v_cndmask_b32_e64 v0, v0, v2, s[0:1]
	v_cndmask_b32_e32 v2, 0, v90, vcc
	v_sub_f32_e32 v0, v0, v2
	v_sub_f32_e32 v0, v1, v0
	v_fmamk_f32 v6, v0, 0x3d800000, v166
	v_mul_f32_e32 v0, 0x3fb8aa3b, v6
	v_exp_f32_e32 v2, v0
	s_lshl_b64 s[0:1], s[14:15], 8
	v_lshl_add_u64 v[0:1], v[24:25], 0, s[0:1]
	v_sub_f32_e32 v3, v6, v105
	global_store_dword v[0:1], v2, off
	v_sub_f32_e32 v1, v6, v103
	v_mul_f32_e32 v1, 0x3fb8aa3b, v1
	v_sub_f32_e32 v0, v6, v101
	v_exp_f32_e32 v2, v1
	v_sub_f32_e32 v1, v6, v104
	v_mul_f32_e32 v0, 0x3fb8aa3b, v0
	v_mul_f32_e32 v1, 0x3fb8aa3b, v1
	v_exp_f32_e32 v0, v0
	v_exp_f32_e32 v1, v1
	v_mul_f32_e32 v3, 0x3fb8aa3b, v3
	v_exp_f32_e32 v3, v3
	s_lshl_b64 s[0:1], s[14:15], 15
	v_pk_mul_f32 v[0:1], v[0:1], v[8:9]
	v_lshlrev_b32_e32 v9, 16, v97
	v_lshlrev_b32_e32 v8, 16, v95
	v_pk_mul_f32 v[2:3], v[2:3], v[8:9]
	v_and_b32_sdwa v7, v1, v91 dst_sel:DWORD dst_unused:UNUSED_PAD src0_sel:WORD_1 src1_sel:DWORD
	v_add3_u32 v1, v1, v7, s58
	v_and_b32_sdwa v7, v3, v91 dst_sel:DWORD dst_unused:UNUSED_PAD src0_sel:WORD_1 src1_sel:DWORD
	v_and_b32_sdwa v8, v0, v91 dst_sel:DWORD dst_unused:UNUSED_PAD src0_sel:WORD_1 src1_sel:DWORD
	v_add3_u32 v3, v3, v7, s58
	v_add3_u32 v0, v0, v8, s58
	v_and_b32_sdwa v8, v2, v91 dst_sel:DWORD dst_unused:UNUSED_PAD src0_sel:WORD_1 src1_sel:DWORD
	v_and_b32_e32 v3, 0xffff0000, v3
	v_add3_u32 v2, v2, v8, s58
	v_or_b32_sdwa v1, v3, v1 dst_sel:DWORD dst_unused:UNUSED_PAD src0_sel:DWORD src1_sel:WORD_1
	v_sub_f32_e32 v3, v6, v107
	v_and_b32_e32 v2, 0xffff0000, v2
	v_mul_f32_e32 v3, 0x3fb8aa3b, v3
	v_or_b32_sdwa v0, v2, v0 dst_sel:DWORD dst_unused:UNUSED_PAD src0_sel:DWORD src1_sel:WORD_1
	v_sub_f32_e32 v2, v6, v106
	v_exp_f32_e32 v8, v3
	v_sub_f32_e32 v3, v6, v109
	v_mul_f32_e32 v2, 0x3fb8aa3b, v2
	v_mul_f32_e32 v3, 0x3fb8aa3b, v3
	v_sub_f32_e32 v7, v6, v111
	v_exp_f32_e32 v2, v2
	v_exp_f32_e32 v3, v3
	v_mul_f32_e32 v7, 0x3fb8aa3b, v7
	v_exp_f32_e32 v9, v7
	v_pk_mul_f32 v[2:3], v[2:3], v[10:11]
	v_lshlrev_b32_e32 v11, 16, v99
	v_lshlrev_b32_e32 v10, 16, v98
	v_pk_mul_f32 v[8:9], v[8:9], v[10:11]
	v_and_b32_sdwa v10, v2, v91 dst_sel:DWORD dst_unused:UNUSED_PAD src0_sel:WORD_1 src1_sel:DWORD
	v_add3_u32 v2, v2, v10, s58
	v_and_b32_sdwa v10, v8, v91 dst_sel:DWORD dst_unused:UNUSED_PAD src0_sel:WORD_1 src1_sel:DWORD
	v_add3_u32 v8, v8, v10, s58
	v_and_b32_sdwa v7, v3, v91 dst_sel:DWORD dst_unused:UNUSED_PAD src0_sel:WORD_1 src1_sel:DWORD
	v_and_b32_e32 v8, 0xffff0000, v8
	v_add3_u32 v3, v3, v7, s58
	v_and_b32_sdwa v7, v9, v91 dst_sel:DWORD dst_unused:UNUSED_PAD src0_sel:WORD_1 src1_sel:DWORD
	v_or_b32_sdwa v2, v8, v2 dst_sel:DWORD dst_unused:UNUSED_PAD src0_sel:DWORD src1_sel:WORD_1
	v_add_co_u32_e32 v8, vcc, s66, v4
	v_add3_u32 v7, v9, v7, s58
	s_nop 0
	v_addc_co_u32_e32 v9, vcc, 0, v5, vcc
	global_load_ushort v11, v[8:9], off offset:2560 nt
	v_add_co_u32_e32 v8, vcc, s67, v4
	v_and_b32_e32 v7, 0xffff0000, v7
	s_nop 0
	v_addc_co_u32_e32 v9, vcc, 0, v5, vcc
	global_load_ushort v97, v[8:9], off offset:1536 nt
	v_add_co_u32_e32 v8, vcc, s68, v4
	v_or_b32_sdwa v3, v7, v3 dst_sel:DWORD dst_unused:UNUSED_PAD src0_sel:DWORD src1_sel:WORD_1
	s_nop 0
	v_addc_co_u32_e32 v9, vcc, 0, v5, vcc
	global_load_ushort v98, v[8:9], off nt
	v_add_co_u32_e32 v8, vcc, s69, v4
	ds_write_b128 v86, v[0:3]
	s_nop 0
	v_addc_co_u32_e32 v9, vcc, 0, v5, vcc
	global_load_ushort v105, v[8:9], off offset:3072 nt
	v_add_co_u32_e32 v8, vcc, s70, v4
	v_sub_f32_e32 v1, v6, v110
	s_nop 0
	v_addc_co_u32_e32 v9, vcc, 0, v5, vcc
	global_load_ushort v7, v[8:9], off offset:512 nt
	v_add_co_u32_e32 v8, vcc, s71, v4
	v_mul_f32_e32 v1, 0x3fb8aa3b, v1
	s_nop 0
	v_addc_co_u32_e32 v9, vcc, 0, v5, vcc
	global_load_ushort v14, v[8:9], off offset:3584 nt
	v_add_co_u32_e32 v8, vcc, s72, v4
	v_sub_f32_e32 v0, v6, v108
	s_nop 0
	v_addc_co_u32_e32 v9, vcc, 0, v5, vcc
	global_load_ushort v15, v[8:9], off offset:2048 nt
	v_add_co_u32_e32 v8, vcc, s20, v4
	v_exp_f32_e32 v2, v1
	s_nop 0
	v_addc_co_u32_e32 v9, vcc, 0, v5, vcc
	global_load_ushort v111, v[8:9], off offset:1024 nt
	v_add_co_u32_e32 v8, vcc, s21, v4
	v_sub_f32_e32 v1, v6, v112
	s_nop 0
	v_addc_co_u32_e32 v9, vcc, 0, v5, vcc
	global_load_ushort v12, v[8:9], off offset:2560 nt
	v_add_co_u32_e32 v8, vcc, s28, v4
	v_mul_f32_e32 v0, 0x3fb8aa3b, v0
	s_nop 0
	v_addc_co_u32_e32 v9, vcc, 0, v5, vcc
	global_load_ushort v99, v[8:9], off offset:1536 nt
	v_add_co_u32_e32 v8, vcc, s29, v4
	v_mul_f32_e32 v1, 0x3fb8aa3b, v1
	s_nop 0
	v_addc_co_u32_e32 v9, vcc, 0, v5, vcc
	global_load_ushort v100, v[8:9], off nt
	v_add_co_u32_e32 v8, vcc, s30, v4
	v_sub_f32_e32 v3, v6, v113
	s_nop 0
	v_addc_co_u32_e32 v9, vcc, 0, v5, vcc
	global_load_ushort v106, v[8:9], off offset:3072 nt
	v_add_co_u32_e32 v8, vcc, s31, v4
	v_exp_f32_e32 v0, v0
	s_nop 0
	v_addc_co_u32_e32 v9, vcc, 0, v5, vcc
	v_add_co_u32_e32 v16, vcc, s73, v4
	global_load_ushort v8, v[8:9], off offset:512 nt
	s_nop 0
	v_addc_co_u32_e32 v17, vcc, 0, v5, vcc
	v_add_co_u32_e32 v92, vcc, s74, v4
	global_load_ushort v17, v[16:17], off offset:3584 nt
	s_nop 0
	v_addc_co_u32_e32 v93, vcc, 0, v5, vcc
	v_add_co_u32_e32 v94, vcc, s75, v4
	global_load_ushort v92, v[92:93], off offset:2048 nt
	s_nop 0
	v_addc_co_u32_e32 v95, vcc, 0, v5, vcc
	global_load_ushort v167, v[94:95], off offset:1024 nt
	v_add_co_u32_e32 v94, vcc, s76, v4
	v_exp_f32_e32 v1, v1
	s_nop 0
	v_addc_co_u32_e32 v95, vcc, 0, v5, vcc
	global_load_ushort v13, v[94:95], off offset:2560 nt
	v_add_co_u32_e32 v94, vcc, s77, v4
	v_mul_f32_e32 v3, 0x3fb8aa3b, v3
	s_nop 0
	v_addc_co_u32_e32 v95, vcc, 0, v5, vcc
	global_load_ushort v101, v[94:95], off offset:1536 nt
	v_add_co_u32_e32 v94, vcc, s78, v4
	v_exp_f32_e32 v3, v3
	s_nop 0
	v_addc_co_u32_e32 v95, vcc, 0, v5, vcc
	global_load_ushort v102, v[94:95], off nt
	v_add_co_u32_e32 v94, vcc, s79, v4
	v_pk_mul_f32 v[0:1], v[0:1], v[18:19]
	s_nop 0
	v_addc_co_u32_e32 v95, vcc, 0, v5, vcc
	global_load_ushort v107, v[94:95], off offset:3072 nt
	v_add_co_u32_e32 v94, vcc, s80, v4
	s_waitcnt vmcnt(41)
; __device__ __forceinline__ unsigned pk2(float lo, float hi) { return f2bf(lo) | (f2bf(hi) << 16); }
; __device__ __forceinline__ void gla_upd_unit(LAS unsigned char* wl, const bf16* PROJ, const float* R, const float* w_gk2, const float* b_gk, float* UPD, float* DEC, int unit, int lane) {
;     ...
;     for (int t = 0; t < 32; ++t) kv1[t] = kp[(size_t)(t + 32) * NPROJ];
;     float run = 0.f;
; #pragma unroll
;     for (int t = 0; t < 32; t += 2) {
;         run += la[t]; const float d0 = bf2f(kv0[t]) * __expf(tot - run);
;         run += la[t + 1]; const float d1 = bf2f(kv0[t + 1]) * __expf(tot - run);
;         KD32[kk * (KS / 2) + (t >> 1)] = pk2(d0, d1);
;     }
	v_lshlrev_b32_e32 v19, 16, v21
	v_addc_co_u32_e32 v95, vcc, 0, v5, vcc
	global_load_ushort v9, v[94:95], off offset:512 nt
	v_add_co_u32_e32 v94, vcc, s81, v4
	v_lshlrev_b32_e32 v18, 16, v20
	s_nop 0
	v_addc_co_u32_e32 v95, vcc, 0, v5, vcc
	global_load_ushort v93, v[94:95], off offset:3584 nt
	v_add_co_u32_e32 v94, vcc, s82, v4
	v_pk_mul_f32 v[2:3], v[2:3], v[18:19]
	s_nop 0
	v_addc_co_u32_e32 v95, vcc, 0, v5, vcc
	v_add_co_u32_e32 v168, vcc, s83, v4
	global_load_ushort v94, v[94:95], off offset:2048 nt
	s_nop 0
	v_addc_co_u32_e32 v169, vcc, 0, v5, vcc
	v_add_co_u32_e32 v170, vcc, s84, v4
	global_load_ushort v168, v[168:169], off offset:1024 nt
	s_nop 0
	v_addc_co_u32_e32 v171, vcc, 0, v5, vcc
	global_load_ushort v16, v[170:171], off offset:2560 nt
	v_add_co_u32_e32 v170, vcc, s85, v4
	v_and_b32_sdwa v18, v0, v91 dst_sel:DWORD dst_unused:UNUSED_PAD src0_sel:WORD_1 src1_sel:DWORD
	s_nop 0
	v_addc_co_u32_e32 v171, vcc, 0, v5, vcc
	global_load_ushort v103, v[170:171], off offset:1536 nt
	v_add_co_u32_e32 v170, vcc, s86, v4
	v_add3_u32 v0, v0, v18, s58
	s_nop 0
	v_addc_co_u32_e32 v171, vcc, 0, v5, vcc
	global_load_ushort v104, v[170:171], off nt
	v_add_co_u32_e32 v170, vcc, s87, v4
	v_and_b32_sdwa v18, v2, v91 dst_sel:DWORD dst_unused:UNUSED_PAD src0_sel:WORD_1 src1_sel:DWORD
	s_nop 0
	v_addc_co_u32_e32 v171, vcc, 0, v5, vcc
	global_load_ushort v109, v[170:171], off offset:3072 nt
	v_add_co_u32_e32 v170, vcc, s88, v4
	v_add3_u32 v2, v2, v18, s58
	s_nop 0
	v_addc_co_u32_e32 v171, vcc, 0, v5, vcc
	global_load_ushort v10, v[170:171], off offset:512 nt
	v_add_co_u32_e32 v170, vcc, s89, v4
	v_and_b32_e32 v2, 0xffff0000, v2
	s_nop 0
	v_addc_co_u32_e32 v171, vcc, 0, v5, vcc
	global_load_ushort v95, v[170:171], off offset:3584 nt
	v_add_co_u32_e32 v170, vcc, s90, v4
	v_or_b32_sdwa v0, v2, v0 dst_sel:DWORD dst_unused:UNUSED_PAD src0_sel:DWORD src1_sel:WORD_1
	s_nop 0
	v_addc_co_u32_e32 v171, vcc, 0, v5, vcc
	v_add_co_u32_e32 v4, vcc, s91, v4
	v_sub_f32_e32 v2, v6, v114
	s_nop 0
	v_addc_co_u32_e32 v5, vcc, 0, v5, vcc
	global_load_ushort v4, v[4:5], off offset:1024 nt
	v_and_b32_sdwa v5, v1, v91 dst_sel:DWORD dst_unused:UNUSED_PAD src0_sel:WORD_1 src1_sel:DWORD
	v_add3_u32 v1, v1, v5, s58
	v_and_b32_sdwa v5, v3, v91 dst_sel:DWORD dst_unused:UNUSED_PAD src0_sel:WORD_1 src1_sel:DWORD
	v_add3_u32 v3, v3, v5, s58
	v_and_b32_e32 v3, 0xffff0000, v3
	v_or_b32_sdwa v1, v3, v1 dst_sel:DWORD dst_unused:UNUSED_PAD src0_sel:DWORD src1_sel:WORD_1
	v_sub_f32_e32 v3, v6, v115
	v_mul_f32_e32 v3, 0x3fb8aa3b, v3
	v_exp_f32_e32 v18, v3
	v_sub_f32_e32 v3, v6, v116
	v_mul_f32_e32 v2, 0x3fb8aa3b, v2
	v_mul_f32_e32 v3, 0x3fb8aa3b, v3
	v_sub_f32_e32 v5, v6, v117
	v_exp_f32_e32 v2, v2
	v_exp_f32_e32 v3, v3
	v_mul_f32_e32 v5, 0x3fb8aa3b, v5
	v_exp_f32_e32 v19, v5
	s_waitcnt vmcnt(50)
	v_lshlrev_b32_e32 v21, 16, v60
	v_lshlrev_b32_e32 v20, 16, v22
	v_pk_mul_f32 v[2:3], v[2:3], v[20:21]
	s_waitcnt vmcnt(48)
	v_lshlrev_b32_e32 v21, 16, v75
	v_lshlrev_b32_e32 v20, 16, v61
	v_pk_mul_f32 v[18:19], v[18:19], v[20:21]
	v_and_b32_sdwa v5, v3, v91 dst_sel:DWORD dst_unused:UNUSED_PAD src0_sel:WORD_1 src1_sel:DWORD
	v_and_b32_sdwa v20, v2, v91 dst_sel:DWORD dst_unused:UNUSED_PAD src0_sel:WORD_1 src1_sel:DWORD
	v_add3_u32 v2, v2, v20, s58
	v_add3_u32 v3, v3, v5, s58
	v_and_b32_sdwa v5, v19, v91 dst_sel:DWORD dst_unused:UNUSED_PAD src0_sel:WORD_1 src1_sel:DWORD
	v_and_b32_sdwa v20, v18, v91 dst_sel:DWORD dst_unused:UNUSED_PAD src0_sel:WORD_1 src1_sel:DWORD
	v_add3_u32 v5, v19, v5, s58
	v_add3_u32 v18, v18, v20, s58
	v_and_b32_e32 v5, 0xffff0000, v5
	v_and_b32_e32 v18, 0xffff0000, v18
	v_or_b32_sdwa v3, v5, v3 dst_sel:DWORD dst_unused:UNUSED_PAD src0_sel:DWORD src1_sel:WORD_1
	v_or_b32_sdwa v2, v18, v2 dst_sel:DWORD dst_unused:UNUSED_PAD src0_sel:DWORD src1_sel:WORD_1
	ds_write_b128 v86, v[0:3] offset:16
	v_sub_f32_e32 v1, v6, v119
	v_mul_f32_e32 v1, 0x3fb8aa3b, v1
	v_sub_f32_e32 v0, v6, v118
	v_exp_f32_e32 v2, v1
	v_sub_f32_e32 v1, v6, v120
	v_mul_f32_e32 v0, 0x3fb8aa3b, v0
	v_mul_f32_e32 v1, 0x3fb8aa3b, v1
	v_sub_f32_e32 v3, v6, v121
	v_exp_f32_e32 v0, v0
	v_exp_f32_e32 v1, v1
	v_mul_f32_e32 v3, 0x3fb8aa3b, v3
	v_exp_f32_e32 v3, v3
	s_waitcnt vmcnt(47)
	v_lshlrev_b32_e32 v19, 16, v67
	s_waitcnt vmcnt(46)
	v_lshlrev_b32_e32 v18, 16, v62
	v_pk_mul_f32 v[0:1], v[0:1], v[18:19]
	s_waitcnt vmcnt(44)
	v_lshlrev_b32_e32 v19, 16, v73
	v_lshlrev_b32_e32 v18, 16, v68
	v_pk_mul_f32 v[2:3], v[2:3], v[18:19]
	v_and_b32_sdwa v5, v1, v91 dst_sel:DWORD dst_unused:UNUSED_PAD src0_sel:WORD_1 src1_sel:DWORD
	v_add3_u32 v1, v1, v5, s58
	v_and_b32_sdwa v5, v3, v91 dst_sel:DWORD dst_unused:UNUSED_PAD src0_sel:WORD_1 src1_sel:DWORD
	v_and_b32_sdwa v18, v0, v91 dst_sel:DWORD dst_unused:UNUSED_PAD src0_sel:WORD_1 src1_sel:DWORD
	v_add3_u32 v3, v3, v5, s58
	v_add3_u32 v0, v0, v18, s58
	v_and_b32_sdwa v18, v2, v91 dst_sel:DWORD dst_unused:UNUSED_PAD src0_sel:WORD_1 src1_sel:DWORD
	v_and_b32_e32 v3, 0xffff0000, v3
	v_add3_u32 v2, v2, v18, s58
	v_or_b32_sdwa v1, v3, v1 dst_sel:DWORD dst_unused:UNUSED_PAD src0_sel:DWORD src1_sel:WORD_1
	v_sub_f32_e32 v3, v6, v123
	v_and_b32_e32 v2, 0xffff0000, v2
	v_mul_f32_e32 v3, 0x3fb8aa3b, v3
	v_or_b32_sdwa v0, v2, v0 dst_sel:DWORD dst_unused:UNUSED_PAD src0_sel:DWORD src1_sel:WORD_1
	v_sub_f32_e32 v2, v6, v122
	v_exp_f32_e32 v18, v3
	v_sub_f32_e32 v3, v6, v124
	v_mul_f32_e32 v2, 0x3fb8aa3b, v2
	v_mul_f32_e32 v3, 0x3fb8aa3b, v3
	v_sub_f32_e32 v5, v6, v125
	v_exp_f32_e32 v2, v2
	v_exp_f32_e32 v3, v3
	v_mul_f32_e32 v5, 0x3fb8aa3b, v5
	v_exp_f32_e32 v19, v5
	s_waitcnt vmcnt(42)
	v_lshlrev_b32_e32 v21, 16, v64
	v_lshlrev_b32_e32 v20, 16, v23
	v_pk_mul_f32 v[2:3], v[2:3], v[20:21]
	s_waitcnt vmcnt(40)
; __device__ __forceinline__ unsigned pk2(float lo, float hi) { return f2bf(lo) | (f2bf(hi) << 16); }
; __device__ __forceinline__ void gla_upd_unit(LAS unsigned char* wl, const bf16* PROJ, const float* R, const float* w_gk2, const float* b_gk, float* UPD, float* DEC, int unit, int lane) {
;     ...
;     for (int t = 0; t < 32; t += 2) {
;         run += la[t]; const float d0 = bf2f(kv0[t]) * __expf(tot - run);
;         run += la[t + 1]; const float d1 = bf2f(kv0[t + 1]) * __expf(tot - run);
;         KD32[kk * (KS / 2) + (t >> 1)] = pk2(d0, d1);
;     }
; #pragma unroll
;     for (int t = 0; t < 32; t += 2) {
;         run += la[32 + t]; const float d0 = bf2f(kv1[t]) * __expf(tot - run);
;         run += la[33 + t]; const float d1 = bf2f(kv1[t + 1]) * __expf(tot - run);
;         KD32[kk * (KS / 2) + 16 + (t >> 1)] = pk2(d0, d1);
;     }
	v_lshlrev_b32_e32 v21, 16, v76
	v_lshlrev_b32_e32 v20, 16, v65
	v_pk_mul_f32 v[18:19], v[18:19], v[20:21]
	v_and_b32_sdwa v5, v3, v91 dst_sel:DWORD dst_unused:UNUSED_PAD src0_sel:WORD_1 src1_sel:DWORD
	v_and_b32_sdwa v20, v2, v91 dst_sel:DWORD dst_unused:UNUSED_PAD src0_sel:WORD_1 src1_sel:DWORD
	v_add3_u32 v2, v2, v20, s58
	v_add3_u32 v3, v3, v5, s58
	v_and_b32_sdwa v5, v19, v91 dst_sel:DWORD dst_unused:UNUSED_PAD src0_sel:WORD_1 src1_sel:DWORD
	v_and_b32_sdwa v20, v18, v91 dst_sel:DWORD dst_unused:UNUSED_PAD src0_sel:WORD_1 src1_sel:DWORD
	v_add3_u32 v5, v19, v5, s58
	v_add3_u32 v18, v18, v20, s58
	v_and_b32_e32 v5, 0xffff0000, v5
	v_and_b32_e32 v18, 0xffff0000, v18
	v_or_b32_sdwa v3, v5, v3 dst_sel:DWORD dst_unused:UNUSED_PAD src0_sel:DWORD src1_sel:WORD_1
	v_or_b32_sdwa v2, v18, v2 dst_sel:DWORD dst_unused:UNUSED_PAD src0_sel:DWORD src1_sel:WORD_1
	ds_write_b128 v86, v[0:3] offset:32
	v_sub_f32_e32 v1, v6, v127
	v_mul_f32_e32 v1, 0x3fb8aa3b, v1
	v_sub_f32_e32 v0, v6, v126
	v_exp_f32_e32 v2, v1
	v_sub_f32_e32 v1, v6, v128
	v_mul_f32_e32 v0, 0x3fb8aa3b, v0
	v_mul_f32_e32 v1, 0x3fb8aa3b, v1
	v_sub_f32_e32 v3, v6, v129
	v_exp_f32_e32 v0, v0
	v_exp_f32_e32 v1, v1
	v_mul_f32_e32 v3, 0x3fb8aa3b, v3
	v_exp_f32_e32 v3, v3
	s_waitcnt vmcnt(38)
	v_lshlrev_b32_e32 v19, 16, v71
	v_lshlrev_b32_e32 v18, 16, v66
	v_pk_mul_f32 v[0:1], v[0:1], v[18:19]
	s_waitcnt vmcnt(36)
	v_lshlrev_b32_e32 v19, 16, v74
	v_lshlrev_b32_e32 v18, 16, v72
	v_pk_mul_f32 v[2:3], v[2:3], v[18:19]
	v_and_b32_sdwa v5, v1, v91 dst_sel:DWORD dst_unused:UNUSED_PAD src0_sel:WORD_1 src1_sel:DWORD
	v_add3_u32 v1, v1, v5, s58
	v_and_b32_sdwa v5, v3, v91 dst_sel:DWORD dst_unused:UNUSED_PAD src0_sel:WORD_1 src1_sel:DWORD
	v_and_b32_sdwa v18, v0, v91 dst_sel:DWORD dst_unused:UNUSED_PAD src0_sel:WORD_1 src1_sel:DWORD
	v_add3_u32 v3, v3, v5, s58
	v_add3_u32 v0, v0, v18, s58
	v_and_b32_sdwa v18, v2, v91 dst_sel:DWORD dst_unused:UNUSED_PAD src0_sel:WORD_1 src1_sel:DWORD
	v_and_b32_e32 v3, 0xffff0000, v3
	v_add3_u32 v2, v2, v18, s58
	v_or_b32_sdwa v1, v3, v1 dst_sel:DWORD dst_unused:UNUSED_PAD src0_sel:DWORD src1_sel:WORD_1
	v_sub_f32_e32 v3, v6, v131
	v_and_b32_e32 v2, 0xffff0000, v2
	v_mul_f32_e32 v3, 0x3fb8aa3b, v3
	v_or_b32_sdwa v0, v2, v0 dst_sel:DWORD dst_unused:UNUSED_PAD src0_sel:DWORD src1_sel:WORD_1
	v_sub_f32_e32 v2, v6, v130
	v_exp_f32_e32 v18, v3
	v_sub_f32_e32 v3, v6, v132
	v_mul_f32_e32 v2, 0x3fb8aa3b, v2
	v_mul_f32_e32 v3, 0x3fb8aa3b, v3
	v_sub_f32_e32 v5, v6, v133
	v_exp_f32_e32 v2, v2
	v_exp_f32_e32 v3, v3
	v_mul_f32_e32 v5, 0x3fb8aa3b, v5
	v_exp_f32_e32 v19, v5
	s_waitcnt vmcnt(34)
	v_lshlrev_b32_e32 v21, 16, v69
	v_lshlrev_b32_e32 v20, 16, v63
	v_pk_mul_f32 v[2:3], v[2:3], v[20:21]
	s_waitcnt vmcnt(32)
	v_lshlrev_b32_e32 v21, 16, v77
	v_lshlrev_b32_e32 v20, 16, v70
	v_pk_mul_f32 v[18:19], v[18:19], v[20:21]
	v_and_b32_sdwa v5, v3, v91 dst_sel:DWORD dst_unused:UNUSED_PAD src0_sel:WORD_1 src1_sel:DWORD
	v_and_b32_sdwa v20, v2, v91 dst_sel:DWORD dst_unused:UNUSED_PAD src0_sel:WORD_1 src1_sel:DWORD
	v_add3_u32 v2, v2, v20, s58
	v_add3_u32 v3, v3, v5, s58
	v_and_b32_sdwa v5, v19, v91 dst_sel:DWORD dst_unused:UNUSED_PAD src0_sel:WORD_1 src1_sel:DWORD
	v_and_b32_sdwa v20, v18, v91 dst_sel:DWORD dst_unused:UNUSED_PAD src0_sel:WORD_1 src1_sel:DWORD
	v_add3_u32 v5, v19, v5, s58
	v_add3_u32 v18, v18, v20, s58
	v_and_b32_e32 v5, 0xffff0000, v5
	v_and_b32_e32 v18, 0xffff0000, v18
	v_or_b32_sdwa v3, v5, v3 dst_sel:DWORD dst_unused:UNUSED_PAD src0_sel:DWORD src1_sel:WORD_1
	v_or_b32_sdwa v2, v18, v2 dst_sel:DWORD dst_unused:UNUSED_PAD src0_sel:DWORD src1_sel:WORD_1
	ds_write_b128 v86, v[0:3] offset:48
	v_sub_f32_e32 v1, v6, v135
	v_mul_f32_e32 v1, 0x3fb8aa3b, v1
	v_sub_f32_e32 v0, v6, v134
	v_exp_f32_e32 v2, v1
	v_sub_f32_e32 v1, v6, v136
	v_mul_f32_e32 v0, 0x3fb8aa3b, v0
	v_mul_f32_e32 v1, 0x3fb8aa3b, v1
	v_sub_f32_e32 v3, v6, v137
	v_exp_f32_e32 v0, v0
	v_exp_f32_e32 v1, v1
	v_mul_f32_e32 v3, 0x3fb8aa3b, v3
	v_exp_f32_e32 v3, v3
	s_waitcnt vmcnt(29)
	v_lshlrev_b32_e32 v19, 16, v97
	v_lshlrev_b32_e32 v18, 16, v11
	v_pk_mul_f32 v[0:1], v[0:1], v[18:19]
	s_waitcnt vmcnt(27)
	v_lshlrev_b32_e32 v19, 16, v105
	v_lshlrev_b32_e32 v18, 16, v98
	v_pk_mul_f32 v[2:3], v[2:3], v[18:19]
	v_and_b32_sdwa v5, v1, v91 dst_sel:DWORD dst_unused:UNUSED_PAD src0_sel:WORD_1 src1_sel:DWORD
	v_add3_u32 v1, v1, v5, s58
	v_and_b32_sdwa v5, v3, v91 dst_sel:DWORD dst_unused:UNUSED_PAD src0_sel:WORD_1 src1_sel:DWORD
	v_and_b32_sdwa v11, v0, v91 dst_sel:DWORD dst_unused:UNUSED_PAD src0_sel:WORD_1 src1_sel:DWORD
	v_add3_u32 v3, v3, v5, s58
	v_add3_u32 v0, v0, v11, s58
	v_and_b32_sdwa v11, v2, v91 dst_sel:DWORD dst_unused:UNUSED_PAD src0_sel:WORD_1 src1_sel:DWORD
	v_and_b32_e32 v3, 0xffff0000, v3
	v_add3_u32 v2, v2, v11, s58
	v_or_b32_sdwa v1, v3, v1 dst_sel:DWORD dst_unused:UNUSED_PAD src0_sel:DWORD src1_sel:WORD_1
	v_sub_f32_e32 v3, v6, v140
	v_and_b32_e32 v2, 0xffff0000, v2
	v_mul_f32_e32 v3, 0x3fb8aa3b, v3
	v_or_b32_sdwa v0, v2, v0 dst_sel:DWORD dst_unused:UNUSED_PAD src0_sel:DWORD src1_sel:WORD_1
	v_sub_f32_e32 v2, v6, v139
	v_exp_f32_e32 v18, v3
	v_sub_f32_e32 v3, v6, v141
	v_mul_f32_e32 v2, 0x3fb8aa3b, v2
	v_mul_f32_e32 v3, 0x3fb8aa3b, v3
	v_sub_f32_e32 v5, v6, v142
	v_exp_f32_e32 v2, v2
	v_exp_f32_e32 v3, v3
	v_mul_f32_e32 v5, 0x3fb8aa3b, v5
	v_exp_f32_e32 v19, v5
	s_waitcnt vmcnt(25)
	v_lshlrev_b32_e32 v21, 16, v14
	v_lshlrev_b32_e32 v20, 16, v7
	v_pk_mul_f32 v[2:3], v[2:3], v[20:21]
	s_waitcnt vmcnt(23)
; __device__ __forceinline__ unsigned pk2(float lo, float hi) { return f2bf(lo) | (f2bf(hi) << 16); }
; __device__ __forceinline__ void gla_upd_unit(LAS unsigned char* wl, const bf16* PROJ, const float* R, const float* w_gk2, const float* b_gk, float* UPD, float* DEC, int unit, int lane) {
;     ...
;     for (int t = 0; t < 32; ++t) kv1[t] = kp[(size_t)(t + 32) * NPROJ];
;     float run = 0.f;
; #pragma unroll
;     for (int t = 0; t < 32; t += 2) {
;         run += la[t]; const float d0 = bf2f(kv0[t]) * __expf(tot - run);
;         run += la[t + 1]; const float d1 = bf2f(kv0[t + 1]) * __expf(tot - run);
;         KD32[kk * (KS / 2) + (t >> 1)] = pk2(d0, d1);
;     }
; #pragma unroll
;     for (int t = 0; t < 32; t += 2) {
;         run += la[32 + t]; const float d0 = bf2f(kv1[t]) * __expf(tot - run);
;         run += la[33 + t]; const float d1 = bf2f(kv1[t + 1]) * __expf(tot - run);
;         KD32[kk * (KS / 2) + 16 + (t >> 1)] = pk2(d0, d1);
;     }
	v_lshlrev_b32_e32 v21, 16, v111
	v_lshlrev_b32_e32 v20, 16, v15
	global_load_ushort v96, v[170:171], off offset:2048 nt
	v_pk_mul_f32 v[14:15], v[18:19], v[20:21]
	v_and_b32_sdwa v5, v3, v91 dst_sel:DWORD dst_unused:UNUSED_PAD src0_sel:WORD_1 src1_sel:DWORD
	v_and_b32_sdwa v7, v2, v91 dst_sel:DWORD dst_unused:UNUSED_PAD src0_sel:WORD_1 src1_sel:DWORD
	v_add3_u32 v2, v2, v7, s58
	v_add3_u32 v3, v3, v5, s58
	v_and_b32_sdwa v5, v15, v91 dst_sel:DWORD dst_unused:UNUSED_PAD src0_sel:WORD_1 src1_sel:DWORD
	v_and_b32_sdwa v7, v14, v91 dst_sel:DWORD dst_unused:UNUSED_PAD src0_sel:WORD_1 src1_sel:DWORD
	v_add3_u32 v5, v15, v5, s58
	v_add3_u32 v7, v14, v7, s58
	v_and_b32_e32 v5, 0xffff0000, v5
	v_and_b32_e32 v7, 0xffff0000, v7
	v_or_b32_sdwa v3, v5, v3 dst_sel:DWORD dst_unused:UNUSED_PAD src0_sel:DWORD src1_sel:WORD_1
	v_or_b32_sdwa v2, v7, v2 dst_sel:DWORD dst_unused:UNUSED_PAD src0_sel:DWORD src1_sel:WORD_1
	ds_write_b128 v86, v[0:3] offset:64
	v_sub_f32_e32 v1, v6, v145
	v_mul_f32_e32 v1, 0x3fb8aa3b, v1
	v_sub_f32_e32 v0, v6, v143
	v_exp_f32_e32 v2, v1
	v_sub_f32_e32 v1, v6, v146
	v_mul_f32_e32 v0, 0x3fb8aa3b, v0
	v_mul_f32_e32 v1, 0x3fb8aa3b, v1
	v_sub_f32_e32 v3, v6, v147
	v_exp_f32_e32 v0, v0
	v_exp_f32_e32 v1, v1
	v_mul_f32_e32 v3, 0x3fb8aa3b, v3
	v_exp_f32_e32 v3, v3
	s_waitcnt vmcnt(22)
	v_lshlrev_b32_e32 v15, 16, v99
	v_lshlrev_b32_e32 v14, 16, v12
	v_pk_mul_f32 v[0:1], v[0:1], v[14:15]
	s_waitcnt vmcnt(20)
	v_lshlrev_b32_e32 v15, 16, v106
	v_lshlrev_b32_e32 v14, 16, v100
	v_pk_mul_f32 v[2:3], v[2:3], v[14:15]
	v_and_b32_sdwa v5, v1, v91 dst_sel:DWORD dst_unused:UNUSED_PAD src0_sel:WORD_1 src1_sel:DWORD
	v_add3_u32 v1, v1, v5, s58
	v_and_b32_sdwa v5, v3, v91 dst_sel:DWORD dst_unused:UNUSED_PAD src0_sel:WORD_1 src1_sel:DWORD
	v_and_b32_sdwa v7, v0, v91 dst_sel:DWORD dst_unused:UNUSED_PAD src0_sel:WORD_1 src1_sel:DWORD
	v_add3_u32 v3, v3, v5, s58
	v_add3_u32 v0, v0, v7, s58
	v_and_b32_sdwa v7, v2, v91 dst_sel:DWORD dst_unused:UNUSED_PAD src0_sel:WORD_1 src1_sel:DWORD
	v_and_b32_e32 v3, 0xffff0000, v3
	v_add3_u32 v2, v2, v7, s58
	v_or_b32_sdwa v1, v3, v1 dst_sel:DWORD dst_unused:UNUSED_PAD src0_sel:DWORD src1_sel:WORD_1
	v_sub_f32_e32 v3, v6, v149
	v_and_b32_e32 v2, 0xffff0000, v2
	v_mul_f32_e32 v3, 0x3fb8aa3b, v3
	v_or_b32_sdwa v0, v2, v0 dst_sel:DWORD dst_unused:UNUSED_PAD src0_sel:DWORD src1_sel:WORD_1
	v_sub_f32_e32 v2, v6, v148
	v_exp_f32_e32 v14, v3
	v_sub_f32_e32 v3, v6, v150
	v_mul_f32_e32 v2, 0x3fb8aa3b, v2
	v_mul_f32_e32 v3, 0x3fb8aa3b, v3
	v_sub_f32_e32 v5, v6, v151
	v_exp_f32_e32 v2, v2
	v_exp_f32_e32 v3, v3
	v_mul_f32_e32 v5, 0x3fb8aa3b, v5
	v_exp_f32_e32 v15, v5
	s_waitcnt vmcnt(18)
	v_lshlrev_b32_e32 v19, 16, v17
	v_lshlrev_b32_e32 v18, 16, v8
	v_pk_mul_f32 v[2:3], v[2:3], v[18:19]
	s_waitcnt vmcnt(16)
	v_lshlrev_b32_e32 v19, 16, v167
	v_lshlrev_b32_e32 v18, 16, v92
	v_pk_mul_f32 v[14:15], v[14:15], v[18:19]
	v_and_b32_sdwa v5, v3, v91 dst_sel:DWORD dst_unused:UNUSED_PAD src0_sel:WORD_1 src1_sel:DWORD
	v_and_b32_sdwa v7, v2, v91 dst_sel:DWORD dst_unused:UNUSED_PAD src0_sel:WORD_1 src1_sel:DWORD
	v_add3_u32 v2, v2, v7, s58
	v_add3_u32 v3, v3, v5, s58
	v_and_b32_sdwa v5, v15, v91 dst_sel:DWORD dst_unused:UNUSED_PAD src0_sel:WORD_1 src1_sel:DWORD
	v_and_b32_sdwa v7, v14, v91 dst_sel:DWORD dst_unused:UNUSED_PAD src0_sel:WORD_1 src1_sel:DWORD
	v_add3_u32 v5, v15, v5, s58
	v_add3_u32 v7, v14, v7, s58
	v_and_b32_e32 v5, 0xffff0000, v5
	v_and_b32_e32 v7, 0xffff0000, v7
	v_or_b32_sdwa v3, v5, v3 dst_sel:DWORD dst_unused:UNUSED_PAD src0_sel:DWORD src1_sel:WORD_1
	v_or_b32_sdwa v2, v7, v2 dst_sel:DWORD dst_unused:UNUSED_PAD src0_sel:DWORD src1_sel:WORD_1
	ds_write_b128 v86, v[0:3] offset:80
	v_sub_f32_e32 v1, v6, v153
	v_mul_f32_e32 v1, 0x3fb8aa3b, v1
	v_sub_f32_e32 v0, v6, v152
	v_exp_f32_e32 v2, v1
	v_sub_f32_e32 v1, v6, v154
	v_mul_f32_e32 v0, 0x3fb8aa3b, v0
	v_mul_f32_e32 v1, 0x3fb8aa3b, v1
	v_sub_f32_e32 v3, v6, v155
	v_exp_f32_e32 v0, v0
	v_exp_f32_e32 v1, v1
	v_mul_f32_e32 v3, 0x3fb8aa3b, v3
	v_exp_f32_e32 v3, v3
	s_waitcnt vmcnt(14)
	v_lshlrev_b32_e32 v15, 16, v101
	v_lshlrev_b32_e32 v14, 16, v13
	v_pk_mul_f32 v[0:1], v[0:1], v[14:15]
	s_waitcnt vmcnt(12)
	v_lshlrev_b32_e32 v13, 16, v107
	v_lshlrev_b32_e32 v12, 16, v102
	v_pk_mul_f32 v[2:3], v[2:3], v[12:13]
	v_and_b32_sdwa v5, v1, v91 dst_sel:DWORD dst_unused:UNUSED_PAD src0_sel:WORD_1 src1_sel:DWORD
	v_add3_u32 v1, v1, v5, s58
	v_and_b32_sdwa v5, v3, v91 dst_sel:DWORD dst_unused:UNUSED_PAD src0_sel:WORD_1 src1_sel:DWORD
	v_and_b32_sdwa v7, v0, v91 dst_sel:DWORD dst_unused:UNUSED_PAD src0_sel:WORD_1 src1_sel:DWORD
	v_add3_u32 v3, v3, v5, s58
	v_add3_u32 v0, v0, v7, s58
	v_and_b32_sdwa v7, v2, v91 dst_sel:DWORD dst_unused:UNUSED_PAD src0_sel:WORD_1 src1_sel:DWORD
	v_and_b32_e32 v3, 0xffff0000, v3
	v_add3_u32 v2, v2, v7, s58
	v_or_b32_sdwa v1, v3, v1 dst_sel:DWORD dst_unused:UNUSED_PAD src0_sel:DWORD src1_sel:WORD_1
	v_sub_f32_e32 v3, v6, v157
	v_and_b32_e32 v2, 0xffff0000, v2
	v_mul_f32_e32 v3, 0x3fb8aa3b, v3
	v_or_b32_sdwa v0, v2, v0 dst_sel:DWORD dst_unused:UNUSED_PAD src0_sel:DWORD src1_sel:WORD_1
	v_sub_f32_e32 v2, v6, v156
	v_exp_f32_e32 v12, v3
	v_sub_f32_e32 v3, v6, v158
	v_mul_f32_e32 v2, 0x3fb8aa3b, v2
	v_mul_f32_e32 v3, 0x3fb8aa3b, v3
	v_sub_f32_e32 v5, v6, v159
	v_exp_f32_e32 v2, v2
	v_exp_f32_e32 v3, v3
	v_mul_f32_e32 v5, 0x3fb8aa3b, v5
	v_exp_f32_e32 v13, v5
	s_waitcnt vmcnt(10)
	v_lshlrev_b32_e32 v15, 16, v93
	v_lshlrev_b32_e32 v14, 16, v9
	v_pk_mul_f32 v[2:3], v[2:3], v[14:15]
	s_waitcnt vmcnt(8)
; #define LDS_WAIT() asm volatile("s_waitcnt lgkmcnt(0)" ::: "memory")
; __device__ __forceinline__ unsigned pk2(float lo, float hi) { return f2bf(lo) | (f2bf(hi) << 16); }
; __device__ __forceinline__ void gla_upd_unit(LAS unsigned char* wl, const bf16* PROJ, const float* R, const float* w_gk2, const float* b_gk, float* UPD, float* DEC, int unit, int lane) {
;     ...
;     for (int t = 0; t < 32; t += 2) {
;         run += la[t]; const float d0 = bf2f(kv0[t]) * __expf(tot - run);
;         run += la[t + 1]; const float d1 = bf2f(kv0[t + 1]) * __expf(tot - run);
;         KD32[kk * (KS / 2) + (t >> 1)] = pk2(d0, d1);
;     }
; #pragma unroll
;     for (int t = 0; t < 32; t += 2) {
;         run += la[32 + t]; const float d0 = bf2f(kv1[t]) * __expf(tot - run);
;         run += la[33 + t]; const float d1 = bf2f(kv1[t + 1]) * __expf(tot - run);
;         KD32[kk * (KS / 2) + 16 + (t >> 1)] = pk2(d0, d1);
;     }
;     LDS_WAIT(); asm volatile("" ::: "memory");
;     const int fr = lane & 15, fq = lane >> 4, sp = lane >> 3, cc = lane & 7;
; #pragma unroll 1
;     for (int vh = 0; vh < 2; ++vh) {
; #pragma unroll
;         for (int it = 0; it < 4; ++it) {
;             const int t0 = it * 16 + 2 * sp;
;             const u32x4 va = *(const u32x4*)(PROJ + (size_t)(tok0 + t0) * NPROJ + 1536 + h * 128 + vh * 64 + 8 * cc);
;             const u32x4 vb = *(const u32x4*)(PROJ + (size_t)(tok0 + t0 + 1) * NPROJ + 1536 + h * 128 + vh * 64 + 8 * cc);
	v_lshlrev_b32_e32 v9, 16, v168
	v_lshlrev_b32_e32 v8, 16, v94
	v_pk_mul_f32 v[8:9], v[12:13], v[8:9]
	v_and_b32_sdwa v5, v3, v91 dst_sel:DWORD dst_unused:UNUSED_PAD src0_sel:WORD_1 src1_sel:DWORD
	v_and_b32_sdwa v7, v2, v91 dst_sel:DWORD dst_unused:UNUSED_PAD src0_sel:WORD_1 src1_sel:DWORD
	v_add3_u32 v2, v2, v7, s58
	v_add3_u32 v3, v3, v5, s58
	v_and_b32_sdwa v5, v9, v91 dst_sel:DWORD dst_unused:UNUSED_PAD src0_sel:WORD_1 src1_sel:DWORD
	v_and_b32_sdwa v7, v8, v91 dst_sel:DWORD dst_unused:UNUSED_PAD src0_sel:WORD_1 src1_sel:DWORD
	v_add3_u32 v5, v9, v5, s58
	v_add3_u32 v7, v8, v7, s58
	v_and_b32_e32 v5, 0xffff0000, v5
	v_and_b32_e32 v7, 0xffff0000, v7
	v_or_b32_sdwa v3, v5, v3 dst_sel:DWORD dst_unused:UNUSED_PAD src0_sel:DWORD src1_sel:WORD_1
	v_or_b32_sdwa v2, v7, v2 dst_sel:DWORD dst_unused:UNUSED_PAD src0_sel:DWORD src1_sel:WORD_1
	ds_write_b128 v86, v[0:3] offset:96
	v_sub_f32_e32 v1, v6, v161
	v_mul_f32_e32 v1, 0x3fb8aa3b, v1
	v_sub_f32_e32 v0, v6, v160
	v_exp_f32_e32 v2, v1
	v_sub_f32_e32 v1, v6, v162
	v_mul_f32_e32 v0, 0x3fb8aa3b, v0
	v_mul_f32_e32 v1, 0x3fb8aa3b, v1
	v_sub_f32_e32 v3, v6, v163
	v_exp_f32_e32 v0, v0
	v_exp_f32_e32 v1, v1
	v_mul_f32_e32 v3, 0x3fb8aa3b, v3
	v_exp_f32_e32 v3, v3
	s_waitcnt vmcnt(6)
	v_lshlrev_b32_e32 v9, 16, v103
	v_lshlrev_b32_e32 v8, 16, v16
	v_pk_mul_f32 v[0:1], v[0:1], v[8:9]
	s_waitcnt vmcnt(4)
	v_lshlrev_b32_e32 v9, 16, v109
	v_lshlrev_b32_e32 v8, 16, v104
	v_pk_mul_f32 v[2:3], v[2:3], v[8:9]
	v_and_b32_sdwa v5, v1, v91 dst_sel:DWORD dst_unused:UNUSED_PAD src0_sel:WORD_1 src1_sel:DWORD
	v_add3_u32 v1, v1, v5, s58
	v_and_b32_sdwa v5, v3, v91 dst_sel:DWORD dst_unused:UNUSED_PAD src0_sel:WORD_1 src1_sel:DWORD
	v_and_b32_sdwa v7, v0, v91 dst_sel:DWORD dst_unused:UNUSED_PAD src0_sel:WORD_1 src1_sel:DWORD
	v_add3_u32 v3, v3, v5, s58
	v_add3_u32 v0, v0, v7, s58
	v_and_b32_sdwa v7, v2, v91 dst_sel:DWORD dst_unused:UNUSED_PAD src0_sel:WORD_1 src1_sel:DWORD
	v_and_b32_e32 v3, 0xffff0000, v3
	v_add3_u32 v2, v2, v7, s58
	v_or_b32_sdwa v1, v3, v1 dst_sel:DWORD dst_unused:UNUSED_PAD src0_sel:DWORD src1_sel:WORD_1
	v_sub_f32_e32 v3, v6, v165
	v_and_b32_e32 v2, 0xffff0000, v2
	v_mul_f32_e32 v3, 0x3fb8aa3b, v3
	v_or_b32_sdwa v0, v2, v0 dst_sel:DWORD dst_unused:UNUSED_PAD src0_sel:DWORD src1_sel:WORD_1
	v_sub_f32_e32 v2, v6, v164
	v_exp_f32_e32 v8, v3
	v_sub_f32_e32 v3, v6, v166
	v_mul_f32_e32 v2, 0x3fb8aa3b, v2
	v_mul_f32_e32 v3, 0x3fb8aa3b, v3
	v_sub_f32_e32 v5, v6, v6
	v_exp_f32_e32 v2, v2
	v_exp_f32_e32 v3, v3
	v_mul_f32_e32 v5, 0x3fb8aa3b, v5
	v_exp_f32_e32 v9, v5
	s_waitcnt vmcnt(2)
	v_lshlrev_b32_e32 v7, 16, v95
	v_lshlrev_b32_e32 v6, 16, v10
	v_pk_mul_f32 v[2:3], v[2:3], v[6:7]
	s_waitcnt vmcnt(1)
	v_lshlrev_b32_e32 v5, 16, v4
	s_waitcnt vmcnt(0)
	v_lshlrev_b32_e32 v4, 16, v96
	v_pk_mul_f32 v[4:5], v[8:9], v[4:5]
	v_and_b32_sdwa v6, v3, v91 dst_sel:DWORD dst_unused:UNUSED_PAD src0_sel:WORD_1 src1_sel:DWORD
	v_and_b32_sdwa v7, v2, v91 dst_sel:DWORD dst_unused:UNUSED_PAD src0_sel:WORD_1 src1_sel:DWORD
	v_add3_u32 v2, v2, v7, s58
	v_add3_u32 v3, v3, v6, s58
	v_and_b32_sdwa v6, v5, v91 dst_sel:DWORD dst_unused:UNUSED_PAD src0_sel:WORD_1 src1_sel:DWORD
	v_and_b32_sdwa v7, v4, v91 dst_sel:DWORD dst_unused:UNUSED_PAD src0_sel:WORD_1 src1_sel:DWORD
	v_add3_u32 v5, v5, v6, s58
	v_add3_u32 v4, v4, v7, s58
	v_and_b32_e32 v5, 0xffff0000, v5
	v_and_b32_e32 v4, 0xffff0000, v4
	v_or_b32_sdwa v3, v5, v3 dst_sel:DWORD dst_unused:UNUSED_PAD src0_sel:DWORD src1_sel:WORD_1
	v_or_b32_sdwa v2, v4, v2 dst_sel:DWORD dst_unused:UNUSED_PAD src0_sel:DWORD src1_sel:WORD_1
	ds_write_b128 v86, v[0:3] offset:112
	v_or_b32_e32 v0, s5, v138
	v_mad_i64_i32 v[60:61], s[2:3], v0, s39, v[58:59]
	v_or_b32_e32 v0, 1, v0
	v_mad_i64_i32 v[62:63], s[2:3], v0, s39, v[58:59]
	v_or_b32_e32 v0, s5, v78
	v_mad_i64_i32 v[64:65], s[2:3], v0, s39, v[58:59]
	v_or_b32_e32 v0, 1, v0
	v_mad_i64_i32 v[66:67], s[2:3], v0, s39, v[58:59]
	v_or_b32_e32 v0, s5, v79
	s_waitcnt lgkmcnt(0)
	v_mad_i64_i32 v[68:69], s[2:3], v0, s39, v[58:59]
	v_or_b32_e32 v0, 1, v0
	v_mad_i64_i32 v[70:71], s[2:3], v0, s39, v[58:59]
	v_or_b32_e32 v0, s4, v80
	v_mad_i64_i32 v[72:73], s[2:3], v0, s39, v[58:59]
	v_or_b32_e32 v0, 1, v0
	v_mad_i64_i32 v[74:75], s[2:3], v0, s39, v[58:59]
	v_lshl_add_u64 v[76:77], v[26:27], 0, s[0:1]
	s_mov_b32 s0, s13
; #define LDS_WAIT() asm volatile("s_waitcnt lgkmcnt(0)" ::: "memory")
; __device__ __forceinline__ void gla_upd_unit(LAS unsigned char* wl, const bf16* PROJ, const float* R, const float* w_gk2, const float* b_gk, float* UPD, float* DEC, int unit, int lane) {
;     ...
;     for (int vh = 0; vh < 2; ++vh) {
; #pragma unroll
;         for (int it = 0; it < 4; ++it) {
;             const int t0 = it * 16 + 2 * sp;
;             const u32x4 va = *(const u32x4*)(PROJ + (size_t)(tok0 + t0) * NPROJ + 1536 + h * 128 + vh * 64 + 8 * cc);
;             const u32x4 vb = *(const u32x4*)(PROJ + (size_t)(tok0 + t0 + 1) * NPROJ + 1536 + h * 128 + vh * 64 + 8 * cc);
; #pragma unroll
;             for (int i = 0; i < 4; ++i) {
;                 VB32[(8 * cc + 2 * i) * (KS / 2) + (t0 >> 1)] = (va[i] & 0xffffu) | (vb[i] << 16);
;                 VB32[(8 * cc + 2 * i + 1) * (KS / 2) + (t0 >> 1)] = (va[i] >> 16) | (vb[i] & 0xffff0000u);
;             }
;         }
;         LDS_WAIT(); asm volatile("" ::: "memory");
.LBB0_1055:
	s_lshl_b32 s12, s0, 7
	v_lshl_add_u64 v[0:1], v[60:61], 0, s[12:13]
	v_lshl_add_u64 v[16:17], v[62:63], 0, s[12:13]
	v_lshl_add_u64 v[4:5], v[64:65], 0, s[12:13]
	v_lshl_add_u64 v[20:21], v[66:67], 0, s[12:13]
	v_lshl_add_u64 v[8:9], v[68:69], 0, s[12:13]
	v_lshl_add_u64 v[92:93], v[70:71], 0, s[12:13]
	v_lshl_add_u64 v[12:13], v[72:73], 0, s[12:13]
	v_lshl_add_u64 v[96:97], v[74:75], 0, s[12:13]
	global_load_dwordx4 v[0:3], v[0:1], off offset:3072 nt
	s_nop 0
	global_load_dwordx4 v[4:7], v[4:5], off offset:3072 nt
	s_nop 0
	global_load_dwordx4 v[8:11], v[8:9], off offset:3072 nt
	s_nop 0
	global_load_dwordx4 v[12:15], v[12:13], off offset:3072 nt
	s_nop 0
	global_load_dwordx4 v[16:19], v[16:17], off offset:3072 nt
	s_nop 0
	global_load_dwordx4 v[20:23], v[20:21], off offset:3072 nt
	s_nop 0
	global_load_dwordx4 v[92:95], v[92:93], off offset:3072 nt
	s_nop 0
	global_load_dwordx4 v[96:99], v[96:97], off offset:3072 nt
	v_add_u32_e32 v100, 0x2400, v81
	v_add_u32_e32 v101, 0x2400, v82
	v_add_u32_e32 v102, 0x2400, v83
	v_add_u32_e32 v103, 0x2400, v84
	s_lshl_b32 s12, s0, 12
	v_lshl_add_u64 v[136:137], s[12:13], 2, v[76:77]
	v_add_co_u32_e32 v158, vcc, 0x1000, v136
	s_mov_b64 s[6:7], vcc
	s_and_b64 s[4:5], exec, s[16:17]
	s_mov_b64 s[16:17], 0
	s_waitcnt vmcnt(7)
	v_and_b32_e32 v104, 0xffff, v0
	v_lshrrev_b32_e32 v0, 16, v0
	v_and_b32_e32 v105, 0xffff, v1
	v_lshrrev_b32_e32 v1, 16, v1
	v_and_b32_e32 v106, 0xffff, v2
	v_lshrrev_b32_e32 v2, 16, v2
	v_and_b32_e32 v107, 0xffff, v3
	v_lshrrev_b32_e32 v3, 16, v3
	s_waitcnt vmcnt(6)
	v_and_b32_e32 v108, 0xffff, v4
	v_lshrrev_b32_e32 v4, 16, v4
	v_and_b32_e32 v109, 0xffff, v5
	v_lshrrev_b32_e32 v5, 16, v5
	v_and_b32_e32 v110, 0xffff, v6
	v_lshrrev_b32_e32 v6, 16, v6
	v_and_b32_e32 v111, 0xffff, v7
	v_lshrrev_b32_e32 v7, 16, v7
	s_waitcnt vmcnt(5)
	v_and_b32_e32 v112, 0xffff, v8
	v_lshrrev_b32_e32 v8, 16, v8
	v_and_b32_e32 v113, 0xffff, v9
	v_lshrrev_b32_e32 v9, 16, v9
	v_and_b32_e32 v114, 0xffff, v10
	v_lshrrev_b32_e32 v10, 16, v10
	v_and_b32_e32 v115, 0xffff, v11
	v_lshrrev_b32_e32 v11, 16, v11
	s_waitcnt vmcnt(4)
	v_and_b32_e32 v116, 0xffff, v12
	v_lshrrev_b32_e32 v12, 16, v12
	v_and_b32_e32 v117, 0xffff, v13
	v_lshrrev_b32_e32 v13, 16, v13
	v_and_b32_e32 v118, 0xffff, v14
	v_lshrrev_b32_e32 v14, 16, v14
	v_and_b32_e32 v119, 0xffff, v15
	v_lshrrev_b32_e32 v15, 16, v15
	s_waitcnt vmcnt(3)
	v_lshl_or_b32 v104, v16, 16, v104
	v_and_or_b32 v0, v16, s59, v0
	v_lshl_or_b32 v16, v17, 16, v105
	v_and_or_b32 v1, v17, s59, v1
	v_lshl_or_b32 v17, v18, 16, v106
	v_and_or_b32 v2, v18, s59, v2
	v_lshl_or_b32 v18, v19, 16, v107
	v_and_or_b32 v3, v19, s59, v3
	s_waitcnt vmcnt(2)
	v_lshl_or_b32 v19, v20, 16, v108
	v_and_or_b32 v4, v20, s59, v4
	v_lshl_or_b32 v20, v21, 16, v109
	v_and_or_b32 v5, v21, s59, v5
	v_lshl_or_b32 v21, v22, 16, v110
	v_and_or_b32 v6, v22, s59, v6
	v_lshl_or_b32 v22, v23, 16, v111
	v_and_or_b32 v7, v23, s59, v7
	s_waitcnt vmcnt(1)
	v_lshl_or_b32 v23, v92, 16, v112
	v_and_or_b32 v8, v92, s59, v8
	v_lshl_or_b32 v92, v93, 16, v113
	v_and_or_b32 v9, v93, s59, v9
	v_lshl_or_b32 v93, v94, 16, v114
	v_and_or_b32 v10, v94, s59, v10
	v_lshl_or_b32 v94, v95, 16, v115
	v_and_or_b32 v11, v95, s59, v11
	s_waitcnt vmcnt(0)
	v_lshl_or_b32 v95, v96, 16, v116
	v_and_or_b32 v12, v96, s59, v12
	v_lshl_or_b32 v96, v97, 16, v117
	v_and_or_b32 v13, v97, s59, v13
	v_lshl_or_b32 v97, v98, 16, v118
	v_and_or_b32 v14, v98, s59, v14
	v_lshl_or_b32 v98, v99, 16, v119
	v_and_or_b32 v15, v99, s59, v15
	ds_write2_b32 v100, v104, v0 offset1:36
	ds_write2_b32 v100, v16, v1 offset0:72 offset1:108
	ds_write2_b32 v100, v17, v2 offset0:144 offset1:180
	ds_write2_b32 v100, v18, v3 offset0:216 offset1:252
	ds_write2_b32 v101, v19, v4 offset1:36
	ds_write2_b32 v101, v20, v5 offset0:72 offset1:108
	ds_write2_b32 v101, v21, v6 offset0:144 offset1:180
	ds_write2_b32 v101, v22, v7 offset0:216 offset1:252
	ds_write2_b32 v102, v23, v8 offset1:36
	ds_write2_b32 v102, v92, v9 offset0:72 offset1:108
	ds_write2_b32 v102, v93, v10 offset0:144 offset1:180
	ds_write2_b32 v102, v94, v11 offset0:216 offset1:252
	ds_write2_b32 v103, v95, v12 offset1:36
	ds_write2_b32 v103, v96, v13 offset0:72 offset1:108
	ds_write2_b32 v103, v97, v14 offset0:144 offset1:180
	ds_write2_b32 v103, v98, v15 offset0:216 offset1:252
	s_waitcnt lgkmcnt(0)
; #define LAS __attribute__((address_space(3)))
; #define LDS_WAIT() asm volatile("s_waitcnt lgkmcnt(0)" ::: "memory")
; __device__ __forceinline__ void gla_upd_unit(LAS unsigned char* wl, const bf16* PROJ, const float* R, const float* w_gk2, const float* b_gk, float* UPD, float* DEC, int unit, int lane) {
;     ...
;         f32x4 acc[4][4];
; #pragma unroll
;         for (int i = 0; i < 4; ++i)
; #pragma unroll
;             for (int j = 0; j < 4; ++j) acc[i][j] = (f32x4){0.f, 0.f, 0.f, 0.f};
; #pragma unroll
;         for (int ki = 0; ki < 2; ++ki) {
;             bf16x8 av[4], bk[4];
; #pragma unroll
;             for (int mi = 0; mi < 4; ++mi) av[mi] = *(const LAS bf16x8*)(wl + 9216 + ((16 * mi + fr) * KS + 32 * ki + 8 * fq) * 2);
; #pragma unroll
;             for (int ni = 0; ni < 4; ++ni) bk[ni] = *(const LAS bf16x8*)(wl + ((16 * ni + fr) * KS + 32 * ki + 8 * fq) * 2);
; #pragma unroll
;             for (int mi = 0; mi < 4; ++mi)
; #pragma unroll
;                 for (int ni = 0; ni < 4; ++ni) acc[mi][ni] = __builtin_amdgcn_mfma_f32_16x16x32_bf16(bk[ni], av[mi], acc[mi][ni], 0, 0, 0);
;         }
;         float* up = UPD + (size_t)unit * 8192 + (size_t)(vh * 64) * 64;
; #pragma unroll
;         for (int mi = 0; mi < 4; ++mi)
; #pragma unroll
;             for (int ni = 0; ni < 4; ++ni) *(f32x4*)(up + (16 * mi + fr) * 64 + 16 * ni + 4 * fq) = acc[mi][ni];
;         LDS_WAIT(); asm volatile("" ::: "memory");
;     }
	ds_read_b128 v[0:3], v87
	ds_read_b128 v[4:7], v87 offset:9216
	ds_read_b128 v[12:15], v87 offset:2304
	ds_read_b128 v[20:23], v87 offset:4608
	ds_read_b128 v[100:103], v88
	s_waitcnt lgkmcnt(3)
	v_mfma_f32_16x16x32_bf16 v[16:19], v[0:3], v[4:7], 0
	ds_read_b128 v[146:149], v88 offset:9216
	ds_read_b128 v[154:157], v88 offset:64
	ds_read_b128 v[150:153], v87 offset:4672
	s_waitcnt lgkmcnt(5)
	v_mfma_f32_16x16x32_bf16 v[92:95], v[12:15], v[4:7], 0
	s_waitcnt lgkmcnt(4)
	v_mfma_f32_16x16x32_bf16 v[96:99], v[20:23], v[4:7], 0
	s_waitcnt lgkmcnt(3)
	v_mfma_f32_16x16x32_bf16 v[104:107], v[100:103], v[4:7], 0
	ds_read_b128 v[4:7], v87 offset:11520
	s_waitcnt lgkmcnt(0)
	v_mfma_f32_16x16x32_bf16 v[108:111], v[0:3], v[4:7], 0
	v_mfma_f32_16x16x32_bf16 v[112:115], v[12:15], v[4:7], 0
	v_mfma_f32_16x16x32_bf16 v[116:119], v[20:23], v[4:7], 0
	v_mfma_f32_16x16x32_bf16 v[120:123], v[100:103], v[4:7], 0
	ds_read_b128 v[4:7], v87 offset:13824
	s_waitcnt lgkmcnt(0)
	v_mfma_f32_16x16x32_bf16 v[124:127], v[0:3], v[4:7], 0
	v_mfma_f32_16x16x32_bf16 v[128:131], v[12:15], v[4:7], 0
	v_mfma_f32_16x16x32_bf16 v[132:135], v[20:23], v[4:7], 0
	v_mfma_f32_16x16x32_bf16 v[140:143], v[100:103], v[4:7], 0
	v_mfma_f32_16x16x32_bf16 v[8:11], v[0:3], v[146:149], 0
	v_mfma_f32_16x16x32_bf16 v[4:7], v[12:15], v[146:149], 0
	v_mfma_f32_16x16x32_bf16 v[0:3], v[20:23], v[146:149], 0
	ds_read_b128 v[20:23], v87 offset:64
	v_mfma_f32_16x16x32_bf16 v[12:15], v[100:103], v[146:149], 0
	ds_read_b128 v[100:103], v87 offset:9280
	ds_read_b128 v[146:149], v87 offset:2368
	s_waitcnt lgkmcnt(1)
	v_mfma_f32_16x16x32_bf16 v[16:19], v[20:23], v[100:103], v[16:19]
	s_waitcnt lgkmcnt(0)
	v_mfma_f32_16x16x32_bf16 v[92:95], v[146:149], v[100:103], v[92:95]
	v_mfma_f32_16x16x32_bf16 v[96:99], v[150:153], v[100:103], v[96:99]
	v_mfma_f32_16x16x32_bf16 v[100:103], v[154:157], v[100:103], v[104:107]
	s_nop 2
	ds_read_b128 v[104:107], v87 offset:11584
	s_waitcnt lgkmcnt(0)
	v_mfma_f32_16x16x32_bf16 v[108:111], v[20:23], v[104:107], v[108:111]
	v_mfma_f32_16x16x32_bf16 v[112:115], v[146:149], v[104:107], v[112:115]
	v_mfma_f32_16x16x32_bf16 v[116:119], v[150:153], v[104:107], v[116:119]
	v_mfma_f32_16x16x32_bf16 v[104:107], v[154:157], v[104:107], v[120:123]
	s_nop 2
	ds_read_b128 v[120:123], v87 offset:13888
	s_waitcnt lgkmcnt(0)
	v_mfma_f32_16x16x32_bf16 v[124:127], v[20:23], v[120:123], v[124:127]
	v_mfma_f32_16x16x32_bf16 v[128:131], v[146:149], v[120:123], v[128:131]
	v_mfma_f32_16x16x32_bf16 v[132:135], v[150:153], v[120:123], v[132:135]
	v_mfma_f32_16x16x32_bf16 v[120:123], v[154:157], v[120:123], v[140:143]
	s_nop 2
	ds_read_b128 v[140:143], v88 offset:9280
	s_waitcnt lgkmcnt(0)
	v_mfma_f32_16x16x32_bf16 v[8:11], v[20:23], v[140:143], v[8:11]
	v_add_co_u32_e32 v20, vcc, 0x2000, v136
	s_mov_b64 s[0:1], vcc
	v_addc_co_u32_e64 v159, vcc, 0, v137, s[6:7]
	v_add_co_u32_e32 v22, vcc, 0x3000, v136
	v_mfma_f32_16x16x32_bf16 v[4:7], v[146:149], v[140:143], v[4:7]
	v_addc_co_u32_e64 v21, s[0:1], 0, v137, s[0:1]
	v_addc_co_u32_e32 v23, vcc, 0, v137, vcc
	v_mfma_f32_16x16x32_bf16 v[0:3], v[150:153], v[140:143], v[0:3]
	s_mov_b32 s0, 1
	s_mov_b64 vcc, s[4:5]
	v_mfma_f32_16x16x32_bf16 v[12:15], v[154:157], v[140:143], v[12:15]
	global_store_dwordx4 v[136:137], v[16:19], off
	global_store_dwordx4 v[136:137], v[92:95], off offset:64
	global_store_dwordx4 v[136:137], v[96:99], off offset:128
	global_store_dwordx4 v[136:137], v[100:103], off offset:192
	global_store_dwordx4 v[158:159], v[108:111], off
	global_store_dwordx4 v[158:159], v[112:115], off offset:64
	global_store_dwordx4 v[158:159], v[116:119], off offset:128
	global_store_dwordx4 v[158:159], v[104:107], off offset:192
	global_store_dwordx4 v[20:21], v[124:127], off
	global_store_dwordx4 v[20:21], v[128:131], off offset:64
	global_store_dwordx4 v[20:21], v[132:135], off offset:128
	global_store_dwordx4 v[20:21], v[120:123], off offset:192
	global_store_dwordx4 v[22:23], v[8:11], off
	global_store_dwordx4 v[22:23], v[4:7], off offset:64
	global_store_dwordx4 v[22:23], v[0:3], off offset:128
	global_store_dwordx4 v[22:23], v[12:15], off offset:192
	s_waitcnt lgkmcnt(0)
	s_cbranch_vccnz .LBB0_1055
	s_add_i32 s14, s14, s36
	s_cmpk_lt_i32 s14, 0x100
	s_cbranch_scc1 .LBB0_1054
